# same prefetch restructuring for merge (P6), w_in norm (P1) and FF1 epilogues: all epilogue loads hoisted into a VGPR pool with counted vmcnt
# speedup vs baseline: 1.0647x; 1.0430x over previous
; #define PG8_STAGE(bufoff, gbase, voff) do { _Pragma("unroll") for (int _i = 0; _i < 2; ++_i) \
;         __builtin_amdgcn_global_load_lds((const unsigned*)((const char*)(gbase) + (voff)[_i]), (LAS unsigned*)(lds + (bufoff) + ldsw + _i * 8192), 16, 0, 0); } while (0)
; #define PG8_LDA(dst, b, h) do { _Pragma("unroll") for (int m = 0; m < 4; ++m) _Pragma("unroll") for (int k = 0; k < 2; ++k) dst[m][k] = *(const LAS bf16x8*)(lds + PG8_SA(b, h) + aoff + m * 2048 + k * 1024); } while (0)
; #define PG8_LDB(dst, b, h) do { _Pragma("unroll") for (int n = 0; n < 2; ++n) _Pragma("unroll") for (int k = 0; k < 2; ++k) dst[n][k] = *(const LAS bf16x8*)(lds + PG8_SB(b, h) + boff + n * 2048 + k * 1024); } while (0)
; #define PG8_MMA(ai, bj, At, Bt) do { __builtin_amdgcn_s_setprio(1); _Pragma("unroll") for (int m = 0; m < 4; ++m) _Pragma("unroll") for (int n = 0; n < 2; ++n) _Pragma("unroll") for (int k = 0; k < 2; ++k) \
;         acc[ai][bj][m][n] = __builtin_amdgcn_mfma_f32_16x16x32_bf16(Bt[n][k], At[m][k], acc[ai][bj][m][n], 0, 0, 0); __builtin_amdgcn_s_setprio(0); } while (0)
; #define PG8_WAIT_L(n) asm volatile("s_waitcnt lgkmcnt(" #n ")" ::: "memory")
; #define PG8_BAR __builtin_amdgcn_s_barrier()
; #define PG8_SCHED __builtin_amdgcn_sched_barrier(0)
;     ...
;             PG8_LDB(B0, 0, 0); PG8_SCHED; PG8_LDA(At, 0, 0); PG8_STAGE(PG8_SA(1, 1), a1 + hA, voffA);
;             PG8_WAIT_L(8); PG8_BAR; PG8_WAIT_L(0); PG8_MMA(0, 0, At, B0); PG8_BAR; PG8_SCHED;
;             PG8_LDB(B1, 0, 1); PG8_STAGE(PG8_SB(0, 0), b2, voffB);
;             PG8_BAR; PG8_WAIT_L(0); PG8_MMA(0, 1, At, B1); PG8_BAR;
;             PG8_LDA(At, 0, 1); PG8_STAGE(PG8_SA(0, 0), a2, voffA);
;             PG8_BAR; PG8_WAIT_L(0); PG8_MMA(1, 0, At, B0); PG8_BAR; PG8_SCHED;
.LBB0_125:
	ds_read_b128 v[146:149], v155
	ds_read_b128 v[160:163], v155 offset:1024
	ds_read_b128 v[170:173], v155 offset:2048
	ds_read_b128 v[174:177], v155 offset:3072
	s_add_u32 s34, s30, 0xfffc0080
	s_addc_u32 s35, s31, -1
	s_cmp_eq_u32 s44, 12
	s_cselect_b32 s37, s7, s35
	s_cselect_b32 s36, s23, s34
	s_cselect_b32 s35, s21, s43
	s_cselect_b32 s34, s33, s42
	v_lshl_add_u64 v[150:151], s[30:31], 0, v[138:139]
	s_add_i32 m0, s29, 0xc000
	ds_read_b128 v[178:181], v156
	ds_read_b128 v[182:185], v156 offset:1024
	ds_read_b128 v[186:189], v156 offset:2048
	ds_read_b128 v[190:193], v156 offset:3072
	ds_read_b128 v[194:197], v156 offset:4096
	ds_read_b128 v[198:201], v156 offset:5120
	ds_read_b128 v[202:205], v156 offset:6144
	ds_read_b128 v[206:209], v156 offset:7168
	global_load_lds_dwordx4 v[150:151], off
	v_lshl_add_u64 v[150:151], s[30:31], 0, v[136:137]
	s_add_i32 m0, s29, 0xe000
	s_nop 0
	global_load_lds_dwordx4 v[150:151], off
	s_waitcnt lgkmcnt(8)
	s_barrier
	s_waitcnt lgkmcnt(0)
	s_setprio 1
	s_waitcnt lgkmcnt(0)
	v_mfma_f32_16x16x32_bf16 v[124:127], v[146:149], v[178:181], v[124:127]
	v_mfma_f32_16x16x32_bf16 v[120:123], v[170:173], v[178:181], v[120:123]
	v_mfma_f32_16x16x32_bf16 v[108:111], v[146:149], v[186:189], v[108:111]
	v_mfma_f32_16x16x32_bf16 v[104:107], v[170:173], v[186:189], v[104:107]
	v_mfma_f32_16x16x32_bf16 v[92:95], v[146:149], v[194:197], v[92:95]
	v_mfma_f32_16x16x32_bf16 v[88:91], v[170:173], v[194:197], v[88:91]
	v_mfma_f32_16x16x32_bf16 v[76:79], v[146:149], v[202:205], v[76:79]
	v_mfma_f32_16x16x32_bf16 v[72:75], v[170:173], v[202:205], v[72:75]
	v_mfma_f32_16x16x32_bf16 v[124:127], v[160:163], v[182:185], v[124:127]
	v_mfma_f32_16x16x32_bf16 v[120:123], v[174:177], v[182:185], v[120:123]
	v_mfma_f32_16x16x32_bf16 v[108:111], v[160:163], v[190:193], v[108:111]
	v_mfma_f32_16x16x32_bf16 v[104:107], v[174:177], v[190:193], v[104:107]
	v_mfma_f32_16x16x32_bf16 v[92:95], v[160:163], v[198:201], v[92:95]
	v_mfma_f32_16x16x32_bf16 v[88:91], v[174:177], v[198:201], v[88:91]
	v_mfma_f32_16x16x32_bf16 v[76:79], v[160:163], v[206:209], v[76:79]
	v_mfma_f32_16x16x32_bf16 v[72:75], v[174:177], v[206:209], v[72:75]
	s_setprio 0
	s_barrier
	s_add_i32 s45, s59, s51
	v_lshl_add_u64 v[150:151], s[34:35], 0, v[130:131]
	s_mov_b32 m0, s45
	ds_read_b128 v[210:213], v157
	ds_read_b128 v[214:217], v157 offset:1024
	ds_read_b128 v[218:221], v157 offset:2048
	ds_read_b128 v[222:225], v157 offset:3072
	global_load_lds_dwordx4 v[150:151], off
	v_lshl_add_u64 v[164:165], s[34:35], 0, v[134:135]
	s_add_i32 m0, s45, 0x2000
	s_nop 0
	global_load_lds_dwordx4 v[164:165], off
	s_barrier
	s_waitcnt lgkmcnt(0)
	s_setprio 1
	s_waitcnt lgkmcnt(0)
	v_mfma_f32_16x16x32_bf16 v[116:119], v[210:213], v[178:181], v[116:119]
	v_mfma_f32_16x16x32_bf16 v[112:115], v[218:221], v[178:181], v[112:115]
	v_mfma_f32_16x16x32_bf16 v[100:103], v[210:213], v[186:189], v[100:103]
	v_mfma_f32_16x16x32_bf16 v[96:99], v[218:221], v[186:189], v[96:99]
	v_mfma_f32_16x16x32_bf16 v[84:87], v[210:213], v[194:197], v[84:87]
	v_mfma_f32_16x16x32_bf16 v[80:83], v[218:221], v[194:197], v[80:83]
	v_mfma_f32_16x16x32_bf16 v[68:71], v[210:213], v[202:205], v[68:71]
	v_mfma_f32_16x16x32_bf16 v[64:67], v[218:221], v[202:205], v[64:67]
	v_mfma_f32_16x16x32_bf16 v[116:119], v[214:217], v[182:185], v[116:119]
	v_mfma_f32_16x16x32_bf16 v[112:115], v[222:225], v[182:185], v[112:115]
	v_mfma_f32_16x16x32_bf16 v[100:103], v[214:217], v[190:193], v[100:103]
	v_mfma_f32_16x16x32_bf16 v[96:99], v[222:225], v[190:193], v[96:99]
	v_mfma_f32_16x16x32_bf16 v[84:87], v[214:217], v[198:201], v[84:87]
	v_mfma_f32_16x16x32_bf16 v[80:83], v[222:225], v[198:201], v[80:83]
	v_mfma_f32_16x16x32_bf16 v[68:71], v[214:217], v[206:209], v[68:71]
	v_mfma_f32_16x16x32_bf16 v[64:67], v[222:225], v[206:209], v[64:67]
	s_setprio 0
	s_mov_b32 m0, s29
	v_lshl_add_u64 v[226:227], s[36:37], 0, v[128:129]
	s_barrier
	ds_read_b128 v[178:181], v156 offset:16384
	ds_read_b128 v[182:185], v156 offset:17408
	ds_read_b128 v[186:189], v156 offset:18432
	ds_read_b128 v[190:193], v156 offset:19456
	ds_read_b128 v[194:197], v156 offset:20480
	ds_read_b128 v[198:201], v156 offset:21504
	ds_read_b128 v[202:205], v156 offset:22528
	ds_read_b128 v[206:209], v156 offset:23552
	global_load_lds_dwordx4 v[226:227], off
	v_lshl_add_u64 v[228:229], s[36:37], 0, v[132:133]
	s_mov_b32 m0, s52
	s_nop 0
	global_load_lds_dwordx4 v[228:229], off
	s_barrier
	s_waitcnt lgkmcnt(0)
	s_setprio 1
	s_waitcnt lgkmcnt(0)
	v_mfma_f32_16x16x32_bf16 v[60:63], v[146:149], v[178:181], v[60:63]
	v_mfma_f32_16x16x32_bf16 v[56:59], v[170:173], v[178:181], v[56:59]
	v_mfma_f32_16x16x32_bf16 v[44:47], v[146:149], v[186:189], v[44:47]
	v_mfma_f32_16x16x32_bf16 v[40:43], v[170:173], v[186:189], v[40:43]
	v_mfma_f32_16x16x32_bf16 v[28:31], v[146:149], v[194:197], v[28:31]
	v_mfma_f32_16x16x32_bf16 v[24:27], v[170:173], v[194:197], v[24:27]
	v_mfma_f32_16x16x32_bf16 v[12:15], v[146:149], v[202:205], v[12:15]
	v_mfma_f32_16x16x32_bf16 v[8:11], v[170:173], v[202:205], v[8:11]
	v_mfma_f32_16x16x32_bf16 v[60:63], v[160:163], v[182:185], v[60:63]
	v_mfma_f32_16x16x32_bf16 v[56:59], v[174:177], v[182:185], v[56:59]
	v_mfma_f32_16x16x32_bf16 v[44:47], v[160:163], v[190:193], v[44:47]
	v_mfma_f32_16x16x32_bf16 v[40:43], v[174:177], v[190:193], v[40:43]
	v_mfma_f32_16x16x32_bf16 v[28:31], v[160:163], v[198:201], v[28:31]
	v_mfma_f32_16x16x32_bf16 v[24:27], v[174:177], v[198:201], v[24:27]
	v_mfma_f32_16x16x32_bf16 v[12:15], v[160:163], v[206:209], v[12:15]
	v_mfma_f32_16x16x32_bf16 v[8:11], v[174:177], v[206:209], v[8:11]
	s_setprio 0
	s_barrier
; #define PG8_STAGE(bufoff, gbase, voff) do { _Pragma("unroll") for (int _i = 0; _i < 2; ++_i) \
;         __builtin_amdgcn_global_load_lds((const unsigned*)((const char*)(gbase) + (voff)[_i]), (LAS unsigned*)(lds + (bufoff) + ldsw + _i * 8192), 16, 0, 0); } while (0)
; #define PG8_LDA(dst, b, h) do { _Pragma("unroll") for (int m = 0; m < 4; ++m) _Pragma("unroll") for (int k = 0; k < 2; ++k) dst[m][k] = *(const LAS bf16x8*)(lds + PG8_SA(b, h) + aoff + m * 2048 + k * 1024); } while (0)
; #define PG8_LDB(dst, b, h) do { _Pragma("unroll") for (int n = 0; n < 2; ++n) _Pragma("unroll") for (int k = 0; k < 2; ++k) dst[n][k] = *(const LAS bf16x8*)(lds + PG8_SB(b, h) + boff + n * 2048 + k * 1024); } while (0)
; #define PG8_MMA(ai, bj, At, Bt) do { __builtin_amdgcn_s_setprio(1); _Pragma("unroll") for (int m = 0; m < 4; ++m) _Pragma("unroll") for (int n = 0; n < 2; ++n) _Pragma("unroll") for (int k = 0; k < 2; ++k) \
;         acc[ai][bj][m][n] = __builtin_amdgcn_mfma_f32_16x16x32_bf16(Bt[n][k], At[m][k], acc[ai][bj][m][n], 0, 0, 0); __builtin_amdgcn_s_setprio(0); } while (0)
; #define PG8_WAIT_V(n) asm volatile("s_waitcnt vmcnt(" #n ")" ::: "memory")
; #define PG8_WAIT_L(n) asm volatile("s_waitcnt lgkmcnt(" #n ")" ::: "memory")
; #define PG8_BAR __builtin_amdgcn_s_barrier()
; #define PG8_SCHED __builtin_amdgcn_sched_barrier(0)
;     ...
;             PG8_STAGE(PG8_SB(0, 1), b2 + hB, voffB);
;             PG8_WAIT_V(6); PG8_BAR; PG8_MMA(1, 1, At, B1); PG8_BAR;
;             PG8_LDB(B0, 1, 0); PG8_SCHED; PG8_LDA(At, 1, 0); PG8_STAGE(PG8_SA(0, 1), a2 + hA, voffA);
;             PG8_WAIT_L(8); PG8_BAR; PG8_WAIT_L(0); PG8_MMA(0, 0, At, B0); PG8_BAR; PG8_SCHED;
;             PG8_LDB(B1, 1, 1); PG8_STAGE(PG8_SB(1, 0), b3, voffB);
;             PG8_BAR; PG8_WAIT_L(0); PG8_MMA(0, 1, At, B1); PG8_BAR;
;             PG8_LDA(At, 1, 1); PG8_STAGE(PG8_SA(1, 0), a3, voffA);
	s_add_u32 s64, s34, 0x40000
	s_addc_u32 s65, s35, 0
	s_add_i32 s45, s60, s51
	v_lshl_add_u64 v[146:147], s[64:65], 0, v[130:131]
	s_mov_b32 m0, s45
	s_nop 0
	global_load_lds_dwordx4 v[146:147], off
	v_lshl_add_u64 v[146:147], s[64:65], 0, v[134:135]
	s_add_i32 m0, s45, 0x2000
	s_nop 0
	global_load_lds_dwordx4 v[146:147], off
	s_waitcnt vmcnt(6)
	s_barrier
	s_setprio 1
	v_mfma_f32_16x16x32_bf16 v[52:55], v[210:213], v[178:181], v[52:55]
	v_mfma_f32_16x16x32_bf16 v[48:51], v[218:221], v[178:181], v[48:51]
	v_mfma_f32_16x16x32_bf16 v[36:39], v[210:213], v[186:189], v[36:39]
	v_mfma_f32_16x16x32_bf16 v[32:35], v[218:221], v[186:189], v[32:35]
	v_mfma_f32_16x16x32_bf16 v[20:23], v[210:213], v[194:197], v[20:23]
	v_mfma_f32_16x16x32_bf16 v[16:19], v[218:221], v[194:197], v[16:19]
	v_mfma_f32_16x16x32_bf16 v[4:7], v[210:213], v[202:205], v[4:7]
	v_mfma_f32_16x16x32_bf16 v[0:3], v[218:221], v[202:205], v[0:3]
	v_mfma_f32_16x16x32_bf16 v[52:55], v[214:217], v[182:185], v[52:55]
	v_mfma_f32_16x16x32_bf16 v[48:51], v[222:225], v[182:185], v[48:51]
	v_mfma_f32_16x16x32_bf16 v[36:39], v[214:217], v[190:193], v[36:39]
	v_mfma_f32_16x16x32_bf16 v[32:35], v[222:225], v[190:193], v[32:35]
	v_mfma_f32_16x16x32_bf16 v[20:23], v[214:217], v[198:201], v[20:23]
	v_mfma_f32_16x16x32_bf16 v[16:19], v[222:225], v[198:201], v[16:19]
	v_mfma_f32_16x16x32_bf16 v[4:7], v[214:217], v[206:209], v[4:7]
	v_mfma_f32_16x16x32_bf16 v[0:3], v[222:225], v[206:209], v[0:3]
	s_setprio 0
	s_add_i32 s45, 0, 0x18000
	v_add_u32_e32 v159, s45, v153
	s_barrier
	ds_read_b128 v[146:149], v159
	ds_read_b128 v[160:163], v159 offset:1024
	ds_read_b128 v[170:173], v159 offset:2048
	ds_read_b128 v[174:177], v159 offset:3072
	s_add_u32 s36, s36, 0x40000
	s_addc_u32 s37, s37, 0
	s_mov_b32 m0, s53
	v_lshl_add_u64 v[210:211], s[36:37], 0, v[128:129]
	ds_read_b128 v[178:181], v156 offset:32768
	ds_read_b128 v[182:185], v156 offset:33792
	ds_read_b128 v[186:189], v156 offset:34816
	ds_read_b128 v[190:193], v156 offset:35840
	ds_read_b128 v[194:197], v156 offset:36864
	ds_read_b128 v[198:201], v156 offset:37888
	ds_read_b128 v[202:205], v156 offset:38912
	ds_read_b128 v[206:209], v156 offset:39936
	global_load_lds_dwordx4 v[210:211], off
	v_lshl_add_u64 v[210:211], s[36:37], 0, v[132:133]
	s_mov_b32 m0, s54
	s_nop 0
	global_load_lds_dwordx4 v[210:211], off
	s_waitcnt lgkmcnt(8)
	s_barrier
	s_waitcnt lgkmcnt(0)
	s_setprio 1
	s_waitcnt lgkmcnt(0)
	v_mfma_f32_16x16x32_bf16 v[124:127], v[146:149], v[178:181], v[124:127]
	v_mfma_f32_16x16x32_bf16 v[120:123], v[170:173], v[178:181], v[120:123]
	v_mfma_f32_16x16x32_bf16 v[108:111], v[146:149], v[186:189], v[108:111]
	v_mfma_f32_16x16x32_bf16 v[104:107], v[170:173], v[186:189], v[104:107]
	v_mfma_f32_16x16x32_bf16 v[92:95], v[146:149], v[194:197], v[92:95]
	v_mfma_f32_16x16x32_bf16 v[88:91], v[170:173], v[194:197], v[88:91]
	v_mfma_f32_16x16x32_bf16 v[76:79], v[146:149], v[202:205], v[76:79]
	v_mfma_f32_16x16x32_bf16 v[72:75], v[170:173], v[202:205], v[72:75]
	v_mfma_f32_16x16x32_bf16 v[124:127], v[160:163], v[182:185], v[124:127]
	v_mfma_f32_16x16x32_bf16 v[120:123], v[174:177], v[182:185], v[120:123]
	v_mfma_f32_16x16x32_bf16 v[108:111], v[160:163], v[190:193], v[108:111]
	v_mfma_f32_16x16x32_bf16 v[104:107], v[174:177], v[190:193], v[104:107]
	v_mfma_f32_16x16x32_bf16 v[92:95], v[160:163], v[198:201], v[92:95]
	v_mfma_f32_16x16x32_bf16 v[88:91], v[174:177], v[198:201], v[88:91]
	v_mfma_f32_16x16x32_bf16 v[76:79], v[160:163], v[206:209], v[76:79]
	v_mfma_f32_16x16x32_bf16 v[72:75], v[174:177], v[206:209], v[72:75]
	s_setprio 0
	s_barrier
	s_add_i32 s36, 0, 0x1c000
	s_add_i32 s37, s45, s51
	v_add_u32_e32 v159, s36, v153
	v_lshl_add_u64 v[150:151], v[150:151], 0, s[18:19]
	s_mov_b32 m0, s37
	ds_read_b128 v[210:213], v159
	ds_read_b128 v[214:217], v159 offset:1024
	ds_read_b128 v[218:221], v159 offset:2048
	ds_read_b128 v[222:225], v159 offset:3072
	global_load_lds_dwordx4 v[150:151], off
	v_lshl_add_u64 v[150:151], v[164:165], 0, s[18:19]
	s_add_i32 m0, s37, 0x2000
	s_nop 0
	global_load_lds_dwordx4 v[150:151], off
	s_barrier
	s_waitcnt lgkmcnt(0)
	s_setprio 1
	s_waitcnt lgkmcnt(0)
	v_mfma_f32_16x16x32_bf16 v[116:119], v[210:213], v[178:181], v[116:119]
	v_mfma_f32_16x16x32_bf16 v[112:115], v[218:221], v[178:181], v[112:115]
	v_mfma_f32_16x16x32_bf16 v[100:103], v[210:213], v[186:189], v[100:103]
	v_mfma_f32_16x16x32_bf16 v[96:99], v[218:221], v[186:189], v[96:99]
	v_mfma_f32_16x16x32_bf16 v[84:87], v[210:213], v[194:197], v[84:87]
	v_mfma_f32_16x16x32_bf16 v[80:83], v[218:221], v[194:197], v[80:83]
	v_mfma_f32_16x16x32_bf16 v[68:71], v[210:213], v[202:205], v[68:71]
	v_mfma_f32_16x16x32_bf16 v[64:67], v[218:221], v[202:205], v[64:67]
	v_mfma_f32_16x16x32_bf16 v[116:119], v[214:217], v[182:185], v[116:119]
	v_mfma_f32_16x16x32_bf16 v[112:115], v[222:225], v[182:185], v[112:115]
	v_mfma_f32_16x16x32_bf16 v[100:103], v[214:217], v[190:193], v[100:103]
	v_mfma_f32_16x16x32_bf16 v[96:99], v[222:225], v[190:193], v[96:99]
	v_mfma_f32_16x16x32_bf16 v[84:87], v[214:217], v[198:201], v[84:87]
	v_mfma_f32_16x16x32_bf16 v[80:83], v[222:225], v[198:201], v[80:83]
	v_mfma_f32_16x16x32_bf16 v[68:71], v[214:217], v[206:209], v[68:71]
	v_mfma_f32_16x16x32_bf16 v[64:67], v[222:225], v[206:209], v[64:67]
	s_setprio 0
	s_mov_b32 m0, s56
	v_lshl_add_u64 v[150:151], v[226:227], 0, s[18:19]
	s_barrier
	ds_read_b128 v[178:181], v156 offset:49152
	ds_read_b128 v[182:185], v156 offset:50176
	ds_read_b128 v[186:189], v156 offset:51200
	ds_read_b128 v[190:193], v156 offset:52224
	ds_read_b128 v[194:197], v156 offset:53248
	ds_read_b128 v[198:201], v156 offset:54272
	ds_read_b128 v[202:205], v156 offset:55296
	ds_read_b128 v[206:209], v156 offset:56320
	global_load_lds_dwordx4 v[150:151], off
	v_lshl_add_u64 v[150:151], v[228:229], 0, s[18:19]
	s_mov_b32 m0, s57
	s_nop 0
	global_load_lds_dwordx4 v[150:151], off
	s_barrier
; #define PG8_STAGE(bufoff, gbase, voff) do { _Pragma("unroll") for (int _i = 0; _i < 2; ++_i) \
;         __builtin_amdgcn_global_load_lds((const unsigned*)((const char*)(gbase) + (voff)[_i]), (LAS unsigned*)(lds + (bufoff) + ldsw + _i * 8192), 16, 0, 0); } while (0)
; #define PG8_MMA(ai, bj, At, Bt) do { __builtin_amdgcn_s_setprio(1); _Pragma("unroll") for (int m = 0; m < 4; ++m) _Pragma("unroll") for (int n = 0; n < 2; ++n) _Pragma("unroll") for (int k = 0; k < 2; ++k) \
;         acc[ai][bj][m][n] = __builtin_amdgcn_mfma_f32_16x16x32_bf16(Bt[n][k], At[m][k], acc[ai][bj][m][n], 0, 0, 0); __builtin_amdgcn_s_setprio(0); } while (0)
; #define PG8_WAIT_V(n) asm volatile("s_waitcnt vmcnt(" #n ")" ::: "memory")
; #define PG8_WAIT_L(n) asm volatile("s_waitcnt lgkmcnt(" #n ")" ::: "memory")
; #define PG8_BAR __builtin_amdgcn_s_barrier()
; #define PG8_SCHED __builtin_amdgcn_sched_barrier(0)
;     ...
;             PG8_BAR; PG8_WAIT_L(0); PG8_MMA(1, 0, At, B0); PG8_BAR; PG8_SCHED;
;             PG8_STAGE(PG8_SB(1, 1), b3 + hB, voffB);
;             PG8_WAIT_V(6); PG8_BAR; PG8_MMA(1, 1, At, B1); PG8_BAR;
; __device__ __forceinline__ float row_rstd(const float* ssq, int row) {
;     const f32x4* p = (const f32x4*)(ssq + (size_t)row * 16);
;     const f32x4 a = p[0], b = p[1], c = p[2], d = p[3];
;     const float s = ((a[0] + a[1]) + (a[2] + a[3])) + ((b[0] + b[1]) + (b[2] + b[3])) + ((c[0] + c[1]) + (c[2] + c[3])) + ((d[0] + d[1]) + (d[2] + d[3]));
;     return rsqrtf(s * (1.0f / 1024.0f) + 1e-6f);
	s_waitcnt lgkmcnt(0)
	s_setprio 1
	s_waitcnt lgkmcnt(0)
	v_mfma_f32_16x16x32_bf16 v[60:63], v[146:149], v[178:181], v[60:63]
	v_mfma_f32_16x16x32_bf16 v[56:59], v[170:173], v[178:181], v[56:59]
	v_mfma_f32_16x16x32_bf16 v[44:47], v[146:149], v[186:189], v[44:47]
	v_mfma_f32_16x16x32_bf16 v[40:43], v[170:173], v[186:189], v[40:43]
	v_mfma_f32_16x16x32_bf16 v[28:31], v[146:149], v[194:197], v[28:31]
	v_mfma_f32_16x16x32_bf16 v[24:27], v[170:173], v[194:197], v[24:27]
	v_mfma_f32_16x16x32_bf16 v[12:15], v[146:149], v[202:205], v[12:15]
	v_mfma_f32_16x16x32_bf16 v[8:11], v[170:173], v[202:205], v[8:11]
	v_mfma_f32_16x16x32_bf16 v[60:63], v[160:163], v[182:185], v[60:63]
	v_mfma_f32_16x16x32_bf16 v[56:59], v[174:177], v[182:185], v[56:59]
	v_mfma_f32_16x16x32_bf16 v[44:47], v[160:163], v[190:193], v[44:47]
	v_mfma_f32_16x16x32_bf16 v[40:43], v[174:177], v[190:193], v[40:43]
	v_mfma_f32_16x16x32_bf16 v[28:31], v[160:163], v[198:201], v[28:31]
	v_mfma_f32_16x16x32_bf16 v[24:27], v[174:177], v[198:201], v[24:27]
	v_mfma_f32_16x16x32_bf16 v[12:15], v[160:163], v[206:209], v[12:15]
	v_mfma_f32_16x16x32_bf16 v[8:11], v[174:177], v[206:209], v[8:11]
	s_setprio 0
	s_barrier
	s_add_u32 s34, s34, 0x40080
	s_addc_u32 s35, s35, 0
	s_add_i32 s36, s36, s51
	v_lshl_add_u64 v[146:147], s[34:35], 0, v[130:131]
	s_mov_b32 m0, s36
	s_nop 0
	global_load_lds_dwordx4 v[146:147], off
	v_lshl_add_u64 v[146:147], s[34:35], 0, v[134:135]
	s_add_i32 m0, s36, 0x2000
	s_nop 0
	global_load_lds_dwordx4 v[146:147], off
	s_waitcnt vmcnt(6)
	s_barrier
	s_setprio 1
	v_mfma_f32_16x16x32_bf16 v[52:55], v[210:213], v[178:181], v[52:55]
	v_mfma_f32_16x16x32_bf16 v[48:51], v[218:221], v[178:181], v[48:51]
	v_mfma_f32_16x16x32_bf16 v[36:39], v[210:213], v[186:189], v[36:39]
	v_mfma_f32_16x16x32_bf16 v[32:35], v[218:221], v[186:189], v[32:35]
	v_mfma_f32_16x16x32_bf16 v[20:23], v[210:213], v[194:197], v[20:23]
	v_mfma_f32_16x16x32_bf16 v[16:19], v[218:221], v[194:197], v[16:19]
	v_mfma_f32_16x16x32_bf16 v[4:7], v[210:213], v[202:205], v[4:7]
	v_mfma_f32_16x16x32_bf16 v[0:3], v[218:221], v[202:205], v[0:3]
	v_mfma_f32_16x16x32_bf16 v[52:55], v[214:217], v[182:185], v[52:55]
	v_mfma_f32_16x16x32_bf16 v[48:51], v[222:225], v[182:185], v[48:51]
	v_mfma_f32_16x16x32_bf16 v[36:39], v[214:217], v[190:193], v[36:39]
	v_mfma_f32_16x16x32_bf16 v[32:35], v[222:225], v[190:193], v[32:35]
	v_mfma_f32_16x16x32_bf16 v[20:23], v[214:217], v[198:201], v[20:23]
	v_mfma_f32_16x16x32_bf16 v[16:19], v[222:225], v[198:201], v[16:19]
	v_mfma_f32_16x16x32_bf16 v[4:7], v[214:217], v[206:209], v[4:7]
	v_mfma_f32_16x16x32_bf16 v[0:3], v[222:225], v[206:209], v[0:3]
	s_setprio 0
	s_add_i32 s44, s44, 2
	s_add_u32 s42, s42, 0x100
	s_addc_u32 s43, s43, 0
	s_add_u32 s30, s30, 0x100
	s_addc_u32 s31, s31, 0
	s_cmp_gt_u32 s44, 13
	s_barrier
	s_cbranch_scc0 .LBB0_125
	v_lshl_add_u32 v150, s28, 8, v152
	v_ashrrev_i32_e32 v151, 31, v150
	v_lshlrev_b64 v[146:147], 6, v[150:151]
	v_lshl_add_u64 v[146:147], s[16:17], 0, v[146:147]
	v_subrev_u32_e32 v186, s16, v146
	v_add_u32_e32 v187, 0x0, v186
	global_load_dwordx4 v[188:191], v187, s[16:17]
	v_add_u32_e32 v187, 0x20, v186
	global_load_dwordx4 v[192:195], v187, s[16:17]
	v_add_u32_e32 v187, 0x10, v186
	global_load_dwordx4 v[196:199], v187, s[16:17]
	v_add_u32_e32 v187, 0x30, v186
	global_load_dwordx4 v[200:203], v187, s[16:17]
	v_add_u32_e32 v187, 0x400, v186
	global_load_dwordx4 v[204:207], v187, s[16:17]
	v_add_u32_e32 v187, 0x410, v186
	global_load_dwordx4 v[208:211], v187, s[16:17]
	v_add_u32_e32 v187, 0x420, v186
	global_load_dwordx4 v[212:215], v187, s[16:17]
	v_add_u32_e32 v187, 0x430, v186
	global_load_dwordx4 v[216:219], v187, s[16:17]
	v_add_u32_e32 v187, 0x800, v186
	global_load_dwordx4 v[220:223], v187, s[16:17]
	v_add_u32_e32 v187, 0x810, v186
	global_load_dwordx4 v[232:235], v187, s[16:17]
	v_add_u32_e32 v187, 0x820, v186
	global_load_dwordx4 v[236:239], v187, s[16:17]
	v_add_u32_e32 v187, 0x830, v186
	global_load_dwordx4 v[240:243], v187, s[16:17]
	v_lshl_or_b32 v148, s6, 8, v154
	v_mov_b64_e32 v[146:147], s[14:15]
	v_ashrrev_i32_e32 v149, 31, v148
	v_mad_i64_i32 v[164:165], s[6:7], v150, s62, v[146:147]
	v_or_b32_e32 v182, 16, v150
	v_lshlrev_b64 v[148:149], 1, v[148:149]
	v_ashrrev_i32_e32 v183, 31, v182
	s_mov_b64 s[34:35], s[24:25]
	s_mov_b32 s28, s22
	s_mov_b64 s[30:31], s[26:27]
	s_waitcnt vmcnt(8)
; __device__ __forceinline__ u32x4 pack8(const f32x4 v0, const f32x4 v1) { u32x4 w; w.x = pk2(v0[0], v0[1]); w.y = pk2(v0[2], v0[3]); w.z = pk2(v1[0], v1[1]); w.w = pk2(v1[2], v1[3]); return w; }
; __device__ __forceinline__ float row_rstd(const float* ssq, int row) {
;     const f32x4* p = (const f32x4*)(ssq + (size_t)row * 16);
;     const f32x4 a = p[0], b = p[1], c = p[2], d = p[3];
;     const float s = ((a[0] + a[1]) + (a[2] + a[3])) + ((b[0] + b[1]) + (b[2] + b[3])) + ((c[0] + c[1]) + (c[2] + c[3])) + ((d[0] + d[1]) + (d[2] + d[3]));
;     return rsqrtf(s * (1.0f / 1024.0f) + 1e-6f);
;     __device__ __forceinline__ void operator()(const f32x4 (&acc)[2][2][4][2], const Unit& u, int wr, int wc, int fr, int fq) const {
;         const int row0 = u.pm * 256 + wr * 64 + fr, col0 = u.pn * 256 + wc * 32 + 8 * fq;
; #pragma unroll
;         for (int ai = 0; ai < 2; ++ai)
; #pragma unroll
;             for (int m = 0; m < 4; ++m) {
;                 const int row = row0 + ai * 128 + m * 16; const float rs = row_rstd(ssq, row);
;                 bf16_t* rowp = O + (size_t)row * ldc + col0;
; #pragma unroll
;                 for (int bj = 0; bj < 2; ++bj) { f32x4 v0 = acc[ai][bj][m][0] * rs, v1 = acc[ai][bj][m][1] * rs;
;                     if (ACT == 1) {
; #pragma unroll
;                         for (int j = 0; j < 4; ++j) { const float a = fmaxf(v0[j], 0.f), b = fmaxf(v1[j], 0.f); v0[j] = a * a; v1[j] = b * b; } }
;                     *(u32x4*)(rowp + bj * 128) = pack8(v0, v1); }
	v_mov_b32_e32 v160, v188
	v_mov_b32_e32 v161, v189
	v_mov_b32_e32 v162, v190
	v_mov_b32_e32 v163, v191
	v_mov_b32_e32 v170, v192
	v_mov_b32_e32 v171, v193
	v_mov_b32_e32 v172, v194
	v_mov_b32_e32 v173, v195
	v_mov_b32_e32 v174, v196
	v_mov_b32_e32 v175, v197
	v_mov_b32_e32 v176, v198
	v_mov_b32_e32 v177, v199
	v_mov_b32_e32 v178, v200
	v_mov_b32_e32 v179, v201
	v_mov_b32_e32 v180, v202
	v_mov_b32_e32 v181, v203
	v_add_u32_e32 v187, 0xc00, v186
	global_load_dwordx4 v[188:191], v187, s[16:17]
	v_add_u32_e32 v187, 0xc10, v186
	global_load_dwordx4 v[192:195], v187, s[16:17]
	v_add_u32_e32 v187, 0xc20, v186
	global_load_dwordx4 v[196:199], v187, s[16:17]
	v_add_u32_e32 v187, 0xc30, v186
	global_load_dwordx4 v[200:203], v187, s[16:17]
	v_mov_b32_e32 v184, v161
	v_mov_b32_e32 v185, v162
	v_mov_b32_e32 v161, v163
	v_add_f32_e32 v162, v170, v171
	v_add_f32_e32 v170, v172, v173
	v_mov_b32_e32 v172, v175
	v_mov_b32_e32 v173, v176
	v_mov_b32_e32 v175, v177
	v_mov_b32_e32 v163, v180
	v_mov_b32_e32 v171, v181
	v_pk_add_f32 v[160:161], v[184:185], v[160:161]
	v_pk_add_f32 v[172:173], v[172:173], v[174:175]
	v_pk_add_f32 v[162:163], v[162:163], v[170:171]
	v_pk_add_f32 v[160:161], v[160:161], v[160:161] op_sel:[0,1] op_sel_hi:[1,0]
	v_pk_add_f32 v[170:171], v[172:173], v[172:173] op_sel:[0,1] op_sel_hi:[1,0]
	v_mov_b32_e32 v161, v178
	v_mov_b32_e32 v171, v179
	v_pk_add_f32 v[160:161], v[160:161], v[170:171]
	s_nop 0
	v_pk_add_f32 v[160:161], v[160:161], v[162:163]
	v_lshlrev_b64 v[162:163], 6, v[182:183]
	v_add_f32_e32 v151, v160, v161
	v_fmamk_f32 v151, v151, 0x3a800000, v158
	v_mul_f32_e32 v159, 0x4b800000, v151
	v_cmp_gt_f32_e32 vcc, s61, v151
	v_lshl_add_u64 v[160:161], v[164:165], 0, v[148:149]
	v_lshl_add_u64 v[162:163], s[16:17], 0, v[162:163]
	v_cndmask_b32_e32 v151, v151, v159, vcc
	v_rsq_f32_e32 v151, v151
	s_nop 0
	v_mul_f32_e32 v159, 0x45800000, v151
	v_cndmask_b32_e32 v164, v151, v159, vcc
	v_pk_mul_f32 v[126:127], v[126:127], v[164:165] op_sel_hi:[1,0]
	v_pk_mul_f32 v[124:125], v[124:125], v[164:165] op_sel_hi:[1,0]
	v_pk_mul_f32 v[122:123], v[122:123], v[164:165] op_sel_hi:[1,0]
	v_pk_mul_f32 v[120:121], v[120:121], v[164:165] op_sel_hi:[1,0]
	v_pk_mul_f32 v[118:119], v[118:119], v[164:165] op_sel_hi:[1,0]
	v_pk_mul_f32 v[116:117], v[116:117], v[164:165] op_sel_hi:[1,0]
	v_pk_mul_f32 v[170:171], v[114:115], v[164:165] op_sel_hi:[1,0]
	v_pk_mul_f32 v[164:165], v[112:113], v[164:165] op_sel_hi:[1,0]
	v_cvt_pk_bf16_f32 v112, v124, v125
	v_cvt_pk_bf16_f32 v113, v126, v127
	v_cvt_pk_bf16_f32 v114, v120, v121
	v_cvt_pk_bf16_f32 v115, v122, v123
	global_store_dwordx4 v[160:161], v[112:115], off
	s_nop 1
	v_cvt_pk_bf16_f32 v112, v116, v117
	v_cvt_pk_bf16_f32 v113, v118, v119
	v_cvt_pk_bf16_f32 v114, v164, v165
	v_cvt_pk_bf16_f32 v115, v170, v171
	global_store_dwordx4 v[160:161], v[112:115], off offset:256
	s_nop 0
	v_or_b32_e32 v160, 32, v150
	v_mad_i64_i32 v[162:163], s[6:7], v182, s62, v[146:147]
	v_ashrrev_i32_e32 v161, 31, v160
	s_waitcnt vmcnt(10)
	v_mov_b32_e32 v112, v204
	v_mov_b32_e32 v113, v205
	v_mov_b32_e32 v114, v206
	v_mov_b32_e32 v115, v207
	v_mov_b32_e32 v116, v208
	v_mov_b32_e32 v117, v209
	v_mov_b32_e32 v118, v210
	v_mov_b32_e32 v119, v211
	v_mov_b32_e32 v120, v212
	v_mov_b32_e32 v121, v213
	v_mov_b32_e32 v122, v214
	v_mov_b32_e32 v123, v215
	v_mov_b32_e32 v124, v216
	v_mov_b32_e32 v125, v217
	v_mov_b32_e32 v126, v218
	v_mov_b32_e32 v127, v219
	v_add_u32_e32 v187, 0x2000, v186
	global_load_dwordx4 v[204:207], v187, s[16:17]
	v_add_u32_e32 v187, 0x2010, v186
	global_load_dwordx4 v[208:211], v187, s[16:17]
	v_add_u32_e32 v187, 0x2020, v186
	global_load_dwordx4 v[212:215], v187, s[16:17]
	v_add_u32_e32 v187, 0x2030, v186
	global_load_dwordx4 v[216:219], v187, s[16:17]
	v_mov_b32_e32 v164, v113
	v_mov_b32_e32 v165, v114
	v_mov_b32_e32 v113, v115
	v_mov_b32_e32 v114, v117
	v_mov_b32_e32 v115, v118
	v_mov_b32_e32 v117, v119
	v_pk_add_f32 v[112:113], v[164:165], v[112:113]
	v_pk_add_f32 v[114:115], v[114:115], v[116:117]
	v_pk_add_f32 v[112:113], v[112:113], v[112:113] op_sel:[0,1] op_sel_hi:[1,0]
	v_pk_add_f32 v[114:115], v[114:115], v[114:115] op_sel:[0,1] op_sel_hi:[1,0]
	v_add_f32_e32 v118, v120, v121
	v_add_f32_e32 v120, v122, v123
	v_mov_b32_e32 v119, v126
	v_mov_b32_e32 v121, v127
	v_mov_b32_e32 v113, v124
	v_mov_b32_e32 v115, v125
	v_pk_add_f32 v[116:117], v[118:119], v[120:121]
	v_pk_add_f32 v[112:113], v[112:113], v[114:115]
	v_lshlrev_b64 v[114:115], 6, v[160:161]
	v_pk_add_f32 v[112:113], v[112:113], v[116:117]
	v_lshl_add_u64 v[114:115], s[16:17], 0, v[114:115]
	v_add_f32_e32 v112, v112, v113
	v_fmamk_f32 v112, v112, 0x3a800000, v158
	v_mul_f32_e32 v113, 0x4b800000, v112
	v_cmp_gt_f32_e32 vcc, s61, v112
	s_nop 1
	v_cndmask_b32_e32 v112, v112, v113, vcc
	v_rsq_f32_e32 v116, v112
	v_lshl_add_u64 v[112:113], v[162:163], 0, v[148:149]
	v_mul_f32_e32 v117, 0x45800000, v116
	v_cndmask_b32_e32 v116, v116, v117, vcc
	v_pk_mul_f32 v[110:111], v[110:111], v[116:117] op_sel_hi:[1,0]
	v_pk_mul_f32 v[108:109], v[108:109], v[116:117] op_sel_hi:[1,0]
	v_pk_mul_f32 v[106:107], v[106:107], v[116:117] op_sel_hi:[1,0]
	v_pk_mul_f32 v[104:105], v[104:105], v[116:117] op_sel_hi:[1,0]
	v_pk_mul_f32 v[102:103], v[102:103], v[116:117] op_sel_hi:[1,0]
	v_pk_mul_f32 v[100:101], v[100:101], v[116:117] op_sel_hi:[1,0]
	v_pk_mul_f32 v[118:119], v[98:99], v[116:117] op_sel_hi:[1,0]
	v_pk_mul_f32 v[116:117], v[96:97], v[116:117] op_sel_hi:[1,0]
	v_cvt_pk_bf16_f32 v96, v108, v109
	v_cvt_pk_bf16_f32 v97, v110, v111
	v_cvt_pk_bf16_f32 v98, v104, v105
	v_cvt_pk_bf16_f32 v99, v106, v107
	global_store_dwordx4 v[112:113], v[96:99], off
	s_nop 1
	v_cvt_pk_bf16_f32 v96, v100, v101
	v_cvt_pk_bf16_f32 v97, v102, v103
	v_cvt_pk_bf16_f32 v98, v116, v117
	v_cvt_pk_bf16_f32 v99, v118, v119
	global_store_dwordx4 v[112:113], v[96:99], off offset:256
	s_nop 0
	v_or_b32_e32 v112, 48, v150
	v_mad_i64_i32 v[114:115], s[6:7], v160, s62, v[146:147]
	v_ashrrev_i32_e32 v113, 31, v112
	s_waitcnt vmcnt(12)
; __device__ __forceinline__ u32x4 pack8(const f32x4 v0, const f32x4 v1) { u32x4 w; w.x = pk2(v0[0], v0[1]); w.y = pk2(v0[2], v0[3]); w.z = pk2(v1[0], v1[1]); w.w = pk2(v1[2], v1[3]); return w; }
; __device__ __forceinline__ float row_rstd(const float* ssq, int row) {
;     const f32x4* p = (const f32x4*)(ssq + (size_t)row * 16);
;     const f32x4 a = p[0], b = p[1], c = p[2], d = p[3];
;     const float s = ((a[0] + a[1]) + (a[2] + a[3])) + ((b[0] + b[1]) + (b[2] + b[3])) + ((c[0] + c[1]) + (c[2] + c[3])) + ((d[0] + d[1]) + (d[2] + d[3]));
;     return rsqrtf(s * (1.0f / 1024.0f) + 1e-6f);
;     __device__ __forceinline__ void operator()(const f32x4 (&acc)[2][2][4][2], const Unit& u, int wr, int wc, int fr, int fq) const {
;         const int row0 = u.pm * 256 + wr * 64 + fr, col0 = u.pn * 256 + wc * 32 + 8 * fq;
; #pragma unroll
;         for (int ai = 0; ai < 2; ++ai)
; #pragma unroll
;             for (int m = 0; m < 4; ++m) {
;                 const int row = row0 + ai * 128 + m * 16; const float rs = row_rstd(ssq, row);
;                 bf16_t* rowp = O + (size_t)row * ldc + col0;
; #pragma unroll
;                 for (int bj = 0; bj < 2; ++bj) { f32x4 v0 = acc[ai][bj][m][0] * rs, v1 = acc[ai][bj][m][1] * rs;
;                     if (ACT == 1) {
; #pragma unroll
;                         for (int j = 0; j < 4; ++j) { const float a = fmaxf(v0[j], 0.f), b = fmaxf(v1[j], 0.f); v0[j] = a * a; v1[j] = b * b; } }
;                     *(u32x4*)(rowp + bj * 128) = pack8(v0, v1); }
	v_mov_b32_e32 v96, v220
	v_mov_b32_e32 v97, v221
	v_mov_b32_e32 v98, v222
	v_mov_b32_e32 v99, v223
	v_mov_b32_e32 v100, v232
	v_mov_b32_e32 v101, v233
	v_mov_b32_e32 v102, v234
	v_mov_b32_e32 v103, v235
	v_mov_b32_e32 v104, v236
	v_mov_b32_e32 v105, v237
	v_mov_b32_e32 v106, v238
	v_mov_b32_e32 v107, v239
	v_mov_b32_e32 v108, v240
	v_mov_b32_e32 v109, v241
	v_mov_b32_e32 v110, v242
	v_mov_b32_e32 v111, v243
	v_add_u32_e32 v187, 0x2400, v186
	global_load_dwordx4 v[220:223], v187, s[16:17]
	v_add_u32_e32 v187, 0x2410, v186
	global_load_dwordx4 v[232:235], v187, s[16:17]
	v_add_u32_e32 v187, 0x2420, v186
	global_load_dwordx4 v[236:239], v187, s[16:17]
	v_add_u32_e32 v187, 0x2430, v186
	global_load_dwordx4 v[240:243], v187, s[16:17]
	v_mov_b32_e32 v116, v97
	v_mov_b32_e32 v117, v98
	v_mov_b32_e32 v97, v99
	v_mov_b32_e32 v98, v101
	v_mov_b32_e32 v99, v102
	v_mov_b32_e32 v101, v103
	v_pk_add_f32 v[96:97], v[116:117], v[96:97]
	v_pk_add_f32 v[98:99], v[98:99], v[100:101]
	v_pk_add_f32 v[96:97], v[96:97], v[96:97] op_sel:[0,1] op_sel_hi:[1,0]
	v_pk_add_f32 v[98:99], v[98:99], v[98:99] op_sel:[0,1] op_sel_hi:[1,0]
	v_add_f32_e32 v102, v104, v105
	v_add_f32_e32 v104, v106, v107
	v_mov_b32_e32 v103, v110
	v_mov_b32_e32 v105, v111
	v_mov_b32_e32 v97, v108
	v_mov_b32_e32 v99, v109
	v_pk_add_f32 v[100:101], v[102:103], v[104:105]
	v_pk_add_f32 v[96:97], v[96:97], v[98:99]
	v_lshlrev_b64 v[98:99], 6, v[112:113]
	v_pk_add_f32 v[96:97], v[96:97], v[100:101]
	v_lshl_add_u64 v[98:99], s[16:17], 0, v[98:99]
	v_add_f32_e32 v96, v96, v97
	v_fmamk_f32 v96, v96, 0x3a800000, v158
	v_mul_f32_e32 v97, 0x4b800000, v96
	v_cmp_gt_f32_e32 vcc, s61, v96
	s_nop 1
	v_cndmask_b32_e32 v96, v96, v97, vcc
	v_rsq_f32_e32 v100, v96
	v_lshl_add_u64 v[96:97], v[114:115], 0, v[148:149]
	v_mul_f32_e32 v101, 0x45800000, v100
	v_cndmask_b32_e32 v100, v100, v101, vcc
	v_pk_mul_f32 v[94:95], v[94:95], v[100:101] op_sel_hi:[1,0]
	v_pk_mul_f32 v[92:93], v[92:93], v[100:101] op_sel_hi:[1,0]
	v_pk_mul_f32 v[90:91], v[90:91], v[100:101] op_sel_hi:[1,0]
	v_pk_mul_f32 v[88:89], v[88:89], v[100:101] op_sel_hi:[1,0]
	v_pk_mul_f32 v[86:87], v[86:87], v[100:101] op_sel_hi:[1,0]
	v_pk_mul_f32 v[84:85], v[84:85], v[100:101] op_sel_hi:[1,0]
	v_pk_mul_f32 v[102:103], v[82:83], v[100:101] op_sel_hi:[1,0]
	v_pk_mul_f32 v[100:101], v[80:81], v[100:101] op_sel_hi:[1,0]
	v_cvt_pk_bf16_f32 v80, v92, v93
	v_cvt_pk_bf16_f32 v81, v94, v95
	v_cvt_pk_bf16_f32 v82, v88, v89
	v_cvt_pk_bf16_f32 v83, v90, v91
	global_store_dwordx4 v[96:97], v[80:83], off
	s_nop 1
	v_cvt_pk_bf16_f32 v80, v84, v85
	v_cvt_pk_bf16_f32 v81, v86, v87
	v_cvt_pk_bf16_f32 v82, v100, v101
	v_cvt_pk_bf16_f32 v83, v102, v103
	global_store_dwordx4 v[96:97], v[80:83], off offset:256
	s_nop 0
	v_add_u32_e32 v96, 0x80, v150
	v_mad_i64_i32 v[98:99], s[6:7], v112, s62, v[146:147]
	v_ashrrev_i32_e32 v97, 31, v96
	s_waitcnt vmcnt(14)
	v_mov_b32_e32 v80, v188
	v_mov_b32_e32 v81, v189
	v_mov_b32_e32 v82, v190
	v_mov_b32_e32 v83, v191
	v_mov_b32_e32 v84, v192
	v_mov_b32_e32 v85, v193
	v_mov_b32_e32 v86, v194
	v_mov_b32_e32 v87, v195
	v_mov_b32_e32 v88, v196
	v_mov_b32_e32 v89, v197
	v_mov_b32_e32 v90, v198
	v_mov_b32_e32 v91, v199
	v_mov_b32_e32 v92, v200
	v_mov_b32_e32 v93, v201
	v_mov_b32_e32 v94, v202
	v_mov_b32_e32 v95, v203
	v_add_u32_e32 v187, 0x2800, v186
	global_load_dwordx4 v[188:191], v187, s[16:17]
	v_add_u32_e32 v187, 0x2810, v186
	global_load_dwordx4 v[192:195], v187, s[16:17]
	v_add_u32_e32 v187, 0x2820, v186
	global_load_dwordx4 v[196:199], v187, s[16:17]
	v_add_u32_e32 v187, 0x2830, v186
	global_load_dwordx4 v[200:203], v187, s[16:17]
	v_mov_b32_e32 v100, v81
	v_mov_b32_e32 v101, v82
	v_mov_b32_e32 v81, v83
	v_mov_b32_e32 v82, v85
	v_mov_b32_e32 v83, v86
	v_mov_b32_e32 v85, v87
	v_pk_add_f32 v[80:81], v[100:101], v[80:81]
	v_pk_add_f32 v[82:83], v[82:83], v[84:85]
	v_pk_add_f32 v[80:81], v[80:81], v[80:81] op_sel:[0,1] op_sel_hi:[1,0]
	v_pk_add_f32 v[82:83], v[82:83], v[82:83] op_sel:[0,1] op_sel_hi:[1,0]
	v_add_f32_e32 v86, v88, v89
	v_add_f32_e32 v88, v90, v91
	v_mov_b32_e32 v87, v94
	v_mov_b32_e32 v89, v95
	v_mov_b32_e32 v81, v92
	v_mov_b32_e32 v83, v93
	v_pk_add_f32 v[84:85], v[86:87], v[88:89]
	v_pk_add_f32 v[80:81], v[80:81], v[82:83]
	v_lshlrev_b64 v[82:83], 6, v[96:97]
	v_pk_add_f32 v[80:81], v[80:81], v[84:85]
	v_lshl_add_u64 v[82:83], s[16:17], 0, v[82:83]
	v_add_f32_e32 v80, v80, v81
	v_fmamk_f32 v80, v80, 0x3a800000, v158
	v_mul_f32_e32 v81, 0x4b800000, v80
	v_cmp_gt_f32_e32 vcc, s61, v80
	s_nop 1
	v_cndmask_b32_e32 v80, v80, v81, vcc
	v_rsq_f32_e32 v84, v80
	v_lshl_add_u64 v[80:81], v[98:99], 0, v[148:149]
	v_mul_f32_e32 v85, 0x45800000, v84
	v_cndmask_b32_e32 v84, v84, v85, vcc
	v_pk_mul_f32 v[78:79], v[78:79], v[84:85] op_sel_hi:[1,0]
	v_pk_mul_f32 v[76:77], v[76:77], v[84:85] op_sel_hi:[1,0]
	v_pk_mul_f32 v[74:75], v[74:75], v[84:85] op_sel_hi:[1,0]
	v_pk_mul_f32 v[72:73], v[72:73], v[84:85] op_sel_hi:[1,0]
	v_pk_mul_f32 v[70:71], v[70:71], v[84:85] op_sel_hi:[1,0]
	v_pk_mul_f32 v[68:69], v[68:69], v[84:85] op_sel_hi:[1,0]
	v_pk_mul_f32 v[86:87], v[66:67], v[84:85] op_sel_hi:[1,0]
	v_pk_mul_f32 v[84:85], v[64:65], v[84:85] op_sel_hi:[1,0]
	v_cvt_pk_bf16_f32 v64, v76, v77
	v_cvt_pk_bf16_f32 v65, v78, v79
	v_cvt_pk_bf16_f32 v66, v72, v73
	v_cvt_pk_bf16_f32 v67, v74, v75
	global_store_dwordx4 v[80:81], v[64:67], off
	s_nop 1
	v_cvt_pk_bf16_f32 v64, v68, v69
	v_cvt_pk_bf16_f32 v65, v70, v71
	v_cvt_pk_bf16_f32 v66, v84, v85
	v_cvt_pk_bf16_f32 v67, v86, v87
	global_store_dwordx4 v[80:81], v[64:67], off offset:256
	s_nop 0
	v_add_u32_e32 v80, 0x90, v150
	v_mad_i64_i32 v[82:83], s[6:7], v96, s62, v[146:147]
	v_ashrrev_i32_e32 v81, 31, v80
	s_waitcnt vmcnt(14)
; __device__ __forceinline__ u32x4 pack8(const f32x4 v0, const f32x4 v1) { u32x4 w; w.x = pk2(v0[0], v0[1]); w.y = pk2(v0[2], v0[3]); w.z = pk2(v1[0], v1[1]); w.w = pk2(v1[2], v1[3]); return w; }
; __device__ __forceinline__ float row_rstd(const float* ssq, int row) {
;     const f32x4* p = (const f32x4*)(ssq + (size_t)row * 16);
;     const f32x4 a = p[0], b = p[1], c = p[2], d = p[3];
;     const float s = ((a[0] + a[1]) + (a[2] + a[3])) + ((b[0] + b[1]) + (b[2] + b[3])) + ((c[0] + c[1]) + (c[2] + c[3])) + ((d[0] + d[1]) + (d[2] + d[3]));
;     return rsqrtf(s * (1.0f / 1024.0f) + 1e-6f);
;     __device__ __forceinline__ void operator()(const f32x4 (&acc)[2][2][4][2], const Unit& u, int wr, int wc, int fr, int fq) const {
;         const int row0 = u.pm * 256 + wr * 64 + fr, col0 = u.pn * 256 + wc * 32 + 8 * fq;
; #pragma unroll
;         for (int ai = 0; ai < 2; ++ai)
; #pragma unroll
;             for (int m = 0; m < 4; ++m) {
;                 const int row = row0 + ai * 128 + m * 16; const float rs = row_rstd(ssq, row);
;                 bf16_t* rowp = O + (size_t)row * ldc + col0;
; #pragma unroll
;                 for (int bj = 0; bj < 2; ++bj) { f32x4 v0 = acc[ai][bj][m][0] * rs, v1 = acc[ai][bj][m][1] * rs;
;                     if (ACT == 1) {
; #pragma unroll
;                         for (int j = 0; j < 4; ++j) { const float a = fmaxf(v0[j], 0.f), b = fmaxf(v1[j], 0.f); v0[j] = a * a; v1[j] = b * b; } }
;                     *(u32x4*)(rowp + bj * 128) = pack8(v0, v1); }
	v_mov_b32_e32 v64, v204
	v_mov_b32_e32 v65, v205
	v_mov_b32_e32 v66, v206
	v_mov_b32_e32 v67, v207
	v_mov_b32_e32 v68, v208
	v_mov_b32_e32 v69, v209
	v_mov_b32_e32 v70, v210
	v_mov_b32_e32 v71, v211
	v_mov_b32_e32 v72, v212
	v_mov_b32_e32 v73, v213
	v_mov_b32_e32 v74, v214
	v_mov_b32_e32 v75, v215
	v_mov_b32_e32 v76, v216
	v_mov_b32_e32 v77, v217
	v_mov_b32_e32 v78, v218
	v_mov_b32_e32 v79, v219
	v_add_u32_e32 v187, 0x2c00, v186
	global_load_dwordx4 v[204:207], v187, s[16:17]
	v_add_u32_e32 v187, 0x2c10, v186
	global_load_dwordx4 v[208:211], v187, s[16:17]
	v_add_u32_e32 v187, 0x2c20, v186
	global_load_dwordx4 v[212:215], v187, s[16:17]
	v_add_u32_e32 v187, 0x2c30, v186
	global_load_dwordx4 v[216:219], v187, s[16:17]
	v_mov_b32_e32 v84, v65
	v_mov_b32_e32 v85, v66
	v_mov_b32_e32 v65, v67
	v_mov_b32_e32 v66, v69
	v_mov_b32_e32 v67, v70
	v_mov_b32_e32 v69, v71
	v_pk_add_f32 v[64:65], v[84:85], v[64:65]
	v_pk_add_f32 v[66:67], v[66:67], v[68:69]
	v_pk_add_f32 v[64:65], v[64:65], v[64:65] op_sel:[0,1] op_sel_hi:[1,0]
	v_pk_add_f32 v[66:67], v[66:67], v[66:67] op_sel:[0,1] op_sel_hi:[1,0]
	v_add_f32_e32 v70, v72, v73
	v_add_f32_e32 v72, v74, v75
	v_mov_b32_e32 v71, v78
	v_mov_b32_e32 v73, v79
	v_mov_b32_e32 v65, v76
	v_mov_b32_e32 v67, v77
	v_pk_add_f32 v[68:69], v[70:71], v[72:73]
	v_pk_add_f32 v[64:65], v[64:65], v[66:67]
	v_lshlrev_b64 v[66:67], 6, v[80:81]
	v_pk_add_f32 v[64:65], v[64:65], v[68:69]
	v_lshl_add_u64 v[66:67], s[16:17], 0, v[66:67]
	v_add_f32_e32 v64, v64, v65
	v_fmamk_f32 v64, v64, 0x3a800000, v158
	v_mul_f32_e32 v65, 0x4b800000, v64
	v_cmp_gt_f32_e32 vcc, s61, v64
	s_nop 1
	v_cndmask_b32_e32 v64, v64, v65, vcc
	v_rsq_f32_e32 v68, v64
	v_lshl_add_u64 v[64:65], v[82:83], 0, v[148:149]
	v_mul_f32_e32 v69, 0x45800000, v68
	v_cndmask_b32_e32 v68, v68, v69, vcc
	v_pk_mul_f32 v[62:63], v[62:63], v[68:69] op_sel_hi:[1,0]
	v_pk_mul_f32 v[60:61], v[60:61], v[68:69] op_sel_hi:[1,0]
	v_pk_mul_f32 v[58:59], v[58:59], v[68:69] op_sel_hi:[1,0]
	v_pk_mul_f32 v[56:57], v[56:57], v[68:69] op_sel_hi:[1,0]
	v_pk_mul_f32 v[54:55], v[54:55], v[68:69] op_sel_hi:[1,0]
	v_pk_mul_f32 v[52:53], v[52:53], v[68:69] op_sel_hi:[1,0]
	v_pk_mul_f32 v[70:71], v[50:51], v[68:69] op_sel_hi:[1,0]
	v_pk_mul_f32 v[68:69], v[48:49], v[68:69] op_sel_hi:[1,0]
	v_cvt_pk_bf16_f32 v48, v60, v61
	v_cvt_pk_bf16_f32 v49, v62, v63
	v_cvt_pk_bf16_f32 v50, v56, v57
	v_cvt_pk_bf16_f32 v51, v58, v59
	global_store_dwordx4 v[64:65], v[48:51], off
	s_nop 1
	v_cvt_pk_bf16_f32 v48, v52, v53
	v_cvt_pk_bf16_f32 v49, v54, v55
	v_cvt_pk_bf16_f32 v50, v68, v69
	v_cvt_pk_bf16_f32 v51, v70, v71
	global_store_dwordx4 v[64:65], v[48:51], off offset:256
	s_nop 0
	v_add_u32_e32 v64, 0xa0, v150
	v_mad_i64_i32 v[66:67], s[6:7], v80, s62, v[146:147]
	v_ashrrev_i32_e32 v65, 31, v64
	s_waitcnt vmcnt(14)
	v_mov_b32_e32 v48, v220
	v_mov_b32_e32 v49, v221
	v_mov_b32_e32 v50, v222
	v_mov_b32_e32 v51, v223
	v_mov_b32_e32 v52, v232
	v_mov_b32_e32 v53, v233
	v_mov_b32_e32 v54, v234
	v_mov_b32_e32 v55, v235
	v_mov_b32_e32 v56, v236
	v_mov_b32_e32 v57, v237
	v_mov_b32_e32 v58, v238
	v_mov_b32_e32 v59, v239
	v_mov_b32_e32 v60, v240
	v_mov_b32_e32 v61, v241
	v_mov_b32_e32 v62, v242
	v_mov_b32_e32 v63, v243
	v_mov_b32_e32 v68, v49
	v_mov_b32_e32 v69, v50
	v_mov_b32_e32 v49, v51
	v_mov_b32_e32 v50, v53
	v_mov_b32_e32 v51, v54
	v_mov_b32_e32 v53, v55
	v_pk_add_f32 v[48:49], v[68:69], v[48:49]
	v_pk_add_f32 v[50:51], v[50:51], v[52:53]
	v_pk_add_f32 v[48:49], v[48:49], v[48:49] op_sel:[0,1] op_sel_hi:[1,0]
	v_pk_add_f32 v[50:51], v[50:51], v[50:51] op_sel:[0,1] op_sel_hi:[1,0]
	v_add_f32_e32 v54, v56, v57
	v_add_f32_e32 v56, v58, v59
	v_mov_b32_e32 v55, v62
	v_mov_b32_e32 v57, v63
	v_mov_b32_e32 v49, v60
	v_mov_b32_e32 v51, v61
	v_pk_add_f32 v[52:53], v[54:55], v[56:57]
	v_pk_add_f32 v[48:49], v[48:49], v[50:51]
	v_lshlrev_b64 v[50:51], 6, v[64:65]
	v_pk_add_f32 v[48:49], v[48:49], v[52:53]
	v_lshl_add_u64 v[50:51], s[16:17], 0, v[50:51]
	v_add_f32_e32 v48, v48, v49
	v_fmamk_f32 v48, v48, 0x3a800000, v158
	v_mul_f32_e32 v49, 0x4b800000, v48
	v_cmp_gt_f32_e32 vcc, s61, v48
	s_nop 1
	v_cndmask_b32_e32 v48, v48, v49, vcc
	v_rsq_f32_e32 v52, v48
	v_lshl_add_u64 v[48:49], v[66:67], 0, v[148:149]
	v_mul_f32_e32 v53, 0x45800000, v52
	v_cndmask_b32_e32 v52, v52, v53, vcc
	v_pk_mul_f32 v[46:47], v[46:47], v[52:53] op_sel_hi:[1,0]
	v_pk_mul_f32 v[44:45], v[44:45], v[52:53] op_sel_hi:[1,0]
	v_pk_mul_f32 v[42:43], v[42:43], v[52:53] op_sel_hi:[1,0]
	v_pk_mul_f32 v[40:41], v[40:41], v[52:53] op_sel_hi:[1,0]
	v_pk_mul_f32 v[38:39], v[38:39], v[52:53] op_sel_hi:[1,0]
	v_pk_mul_f32 v[36:37], v[36:37], v[52:53] op_sel_hi:[1,0]
	v_pk_mul_f32 v[54:55], v[34:35], v[52:53] op_sel_hi:[1,0]
	v_pk_mul_f32 v[52:53], v[32:33], v[52:53] op_sel_hi:[1,0]
	v_cvt_pk_bf16_f32 v32, v44, v45
	v_cvt_pk_bf16_f32 v33, v46, v47
	v_cvt_pk_bf16_f32 v34, v40, v41
	v_cvt_pk_bf16_f32 v35, v42, v43
	global_store_dwordx4 v[48:49], v[32:35], off
	s_nop 1
	v_cvt_pk_bf16_f32 v32, v36, v37
	v_cvt_pk_bf16_f32 v33, v38, v39
	v_cvt_pk_bf16_f32 v34, v52, v53
	v_cvt_pk_bf16_f32 v35, v54, v55
	global_store_dwordx4 v[48:49], v[32:35], off offset:256
	s_nop 0
	v_add_u32_e32 v48, 0xb0, v150
	v_mad_i64_i32 v[50:51], s[6:7], v64, s62, v[146:147]
	v_ashrrev_i32_e32 v49, 31, v48
	s_mov_b32 s6, s20
	s_waitcnt vmcnt(10)
; __device__ __forceinline__ u32x4 pack8(const f32x4 v0, const f32x4 v1) { u32x4 w; w.x = pk2(v0[0], v0[1]); w.y = pk2(v0[2], v0[3]); w.z = pk2(v1[0], v1[1]); w.w = pk2(v1[2], v1[3]); return w; }
;     ...
;         if (!has_next) break;
; __device__ __forceinline__ float row_rstd(const float* ssq, int row) {
;     const f32x4* p = (const f32x4*)(ssq + (size_t)row * 16);
;     const f32x4 a = p[0], b = p[1], c = p[2], d = p[3];
;     const float s = ((a[0] + a[1]) + (a[2] + a[3])) + ((b[0] + b[1]) + (b[2] + b[3])) + ((c[0] + c[1]) + (c[2] + c[3])) + ((d[0] + d[1]) + (d[2] + d[3]));
;     return rsqrtf(s * (1.0f / 1024.0f) + 1e-6f);
;     __device__ __forceinline__ void operator()(const f32x4 (&acc)[2][2][4][2], const Unit& u, int wr, int wc, int fr, int fq) const {
;         const int row0 = u.pm * 256 + wr * 64 + fr, col0 = u.pn * 256 + wc * 32 + 8 * fq;
; #pragma unroll
;         for (int ai = 0; ai < 2; ++ai)
; #pragma unroll
;             for (int m = 0; m < 4; ++m) {
;                 const int row = row0 + ai * 128 + m * 16; const float rs = row_rstd(ssq, row);
;                 bf16_t* rowp = O + (size_t)row * ldc + col0;
; #pragma unroll
;                 for (int bj = 0; bj < 2; ++bj) { f32x4 v0 = acc[ai][bj][m][0] * rs, v1 = acc[ai][bj][m][1] * rs;
;                     if (ACT == 1) {
; #pragma unroll
;                         for (int j = 0; j < 4; ++j) { const float a = fmaxf(v0[j], 0.f), b = fmaxf(v1[j], 0.f); v0[j] = a * a; v1[j] = b * b; } }
;                     *(u32x4*)(rowp + bj * 128) = pack8(v0, v1); }
	v_mov_b32_e32 v32, v188
	v_mov_b32_e32 v33, v189
	v_mov_b32_e32 v34, v190
	v_mov_b32_e32 v35, v191
	v_mov_b32_e32 v36, v192
	v_mov_b32_e32 v37, v193
	v_mov_b32_e32 v38, v194
	v_mov_b32_e32 v39, v195
	v_mov_b32_e32 v40, v196
	v_mov_b32_e32 v41, v197
	v_mov_b32_e32 v42, v198
	v_mov_b32_e32 v43, v199
	v_mov_b32_e32 v44, v200
	v_mov_b32_e32 v45, v201
	v_mov_b32_e32 v46, v202
	v_mov_b32_e32 v47, v203
	v_mov_b32_e32 v52, v33
	v_mov_b32_e32 v53, v34
	v_mov_b32_e32 v33, v35
	v_mov_b32_e32 v34, v37
	v_mov_b32_e32 v35, v38
	v_mov_b32_e32 v37, v39
	v_pk_add_f32 v[32:33], v[52:53], v[32:33]
	v_pk_add_f32 v[34:35], v[34:35], v[36:37]
	v_pk_add_f32 v[32:33], v[32:33], v[32:33] op_sel:[0,1] op_sel_hi:[1,0]
	v_pk_add_f32 v[34:35], v[34:35], v[34:35] op_sel:[0,1] op_sel_hi:[1,0]
	v_add_f32_e32 v38, v40, v41
	v_add_f32_e32 v40, v42, v43
	v_mov_b32_e32 v39, v46
	v_mov_b32_e32 v41, v47
	v_mov_b32_e32 v33, v44
	v_mov_b32_e32 v35, v45
	v_pk_add_f32 v[36:37], v[38:39], v[40:41]
	v_pk_add_f32 v[32:33], v[32:33], v[34:35]
	v_lshlrev_b64 v[34:35], 6, v[48:49]
	v_pk_add_f32 v[32:33], v[32:33], v[36:37]
	v_lshl_add_u64 v[34:35], s[16:17], 0, v[34:35]
	v_add_f32_e32 v32, v32, v33
	v_fmamk_f32 v32, v32, 0x3a800000, v158
	v_mul_f32_e32 v33, 0x4b800000, v32
	v_cmp_gt_f32_e32 vcc, s61, v32
	s_nop 1
	v_cndmask_b32_e32 v32, v32, v33, vcc
	v_rsq_f32_e32 v36, v32
	v_lshl_add_u64 v[32:33], v[50:51], 0, v[148:149]
	v_mul_f32_e32 v37, 0x45800000, v36
	v_cndmask_b32_e32 v36, v36, v37, vcc
	v_pk_mul_f32 v[30:31], v[30:31], v[36:37] op_sel_hi:[1,0]
	v_pk_mul_f32 v[28:29], v[28:29], v[36:37] op_sel_hi:[1,0]
	v_pk_mul_f32 v[26:27], v[26:27], v[36:37] op_sel_hi:[1,0]
	v_pk_mul_f32 v[24:25], v[24:25], v[36:37] op_sel_hi:[1,0]
	v_pk_mul_f32 v[22:23], v[22:23], v[36:37] op_sel_hi:[1,0]
	v_pk_mul_f32 v[20:21], v[20:21], v[36:37] op_sel_hi:[1,0]
	v_pk_mul_f32 v[38:39], v[18:19], v[36:37] op_sel_hi:[1,0]
	v_pk_mul_f32 v[36:37], v[16:17], v[36:37] op_sel_hi:[1,0]
	v_cvt_pk_bf16_f32 v16, v28, v29
	v_cvt_pk_bf16_f32 v17, v30, v31
	v_cvt_pk_bf16_f32 v18, v24, v25
	v_cvt_pk_bf16_f32 v19, v26, v27
	global_store_dwordx4 v[32:33], v[16:19], off
	s_and_b64 vcc, exec, s[8:9]
	s_nop 0
	v_cvt_pk_bf16_f32 v16, v20, v21
	v_cvt_pk_bf16_f32 v17, v22, v23
	v_cvt_pk_bf16_f32 v18, v36, v37
	v_cvt_pk_bf16_f32 v19, v38, v39
	global_store_dwordx4 v[32:33], v[16:19], off offset:256
	s_nop 0
	s_waitcnt vmcnt(6)
	v_mov_b32_e32 v16, v204
	v_mov_b32_e32 v17, v205
	v_mov_b32_e32 v18, v206
	v_mov_b32_e32 v19, v207
	v_mov_b32_e32 v20, v208
	v_mov_b32_e32 v21, v209
	v_mov_b32_e32 v22, v210
	v_mov_b32_e32 v23, v211
	v_mov_b32_e32 v24, v212
	v_mov_b32_e32 v25, v213
	v_mov_b32_e32 v26, v214
	v_mov_b32_e32 v27, v215
	v_mov_b32_e32 v28, v216
	v_mov_b32_e32 v29, v217
	v_mov_b32_e32 v30, v218
	v_mov_b32_e32 v31, v219
	v_mov_b32_e32 v32, v17
	v_mov_b32_e32 v33, v18
	v_mov_b32_e32 v17, v19
	v_mov_b32_e32 v18, v21
	v_mov_b32_e32 v19, v22
	v_mov_b32_e32 v21, v23
	v_pk_add_f32 v[16:17], v[32:33], v[16:17]
	v_pk_add_f32 v[18:19], v[18:19], v[20:21]
	v_pk_add_f32 v[16:17], v[16:17], v[16:17] op_sel:[0,1] op_sel_hi:[1,0]
	v_pk_add_f32 v[18:19], v[18:19], v[18:19] op_sel:[0,1] op_sel_hi:[1,0]
	v_add_f32_e32 v22, v24, v25
	v_add_f32_e32 v24, v26, v27
	v_mov_b32_e32 v23, v30
	v_mov_b32_e32 v25, v31
	v_mov_b32_e32 v17, v28
	v_mov_b32_e32 v19, v29
	v_pk_add_f32 v[20:21], v[22:23], v[24:25]
	v_pk_add_f32 v[16:17], v[16:17], v[18:19]
	s_nop 0
	v_pk_add_f32 v[16:17], v[16:17], v[20:21]
	s_nop 0
	v_add_f32_e32 v16, v16, v17
	v_fmamk_f32 v16, v16, 0x3a800000, v158
	v_mul_f32_e32 v17, 0x4b800000, v16
	v_cmp_gt_f32_e64 s[8:9], s61, v16
	s_nop 1
	v_cndmask_b32_e64 v16, v16, v17, s[8:9]
	v_rsq_f32_e32 v18, v16
	v_mad_i64_i32 v[16:17], s[24:25], v48, s62, v[146:147]
	v_lshl_add_u64 v[16:17], v[16:17], 0, v[148:149]
	v_mul_f32_e32 v19, 0x45800000, v18
	v_cndmask_b32_e64 v18, v18, v19, s[8:9]
	v_pk_mul_f32 v[14:15], v[14:15], v[18:19] op_sel_hi:[1,0]
	v_pk_mul_f32 v[12:13], v[12:13], v[18:19] op_sel_hi:[1,0]
	v_pk_mul_f32 v[10:11], v[10:11], v[18:19] op_sel_hi:[1,0]
	v_pk_mul_f32 v[8:9], v[8:9], v[18:19] op_sel_hi:[1,0]
	v_pk_mul_f32 v[6:7], v[6:7], v[18:19] op_sel_hi:[1,0]
	v_pk_mul_f32 v[4:5], v[4:5], v[18:19] op_sel_hi:[1,0]
	v_pk_mul_f32 v[20:21], v[2:3], v[18:19] op_sel_hi:[1,0]
	v_pk_mul_f32 v[18:19], v[0:1], v[18:19] op_sel_hi:[1,0]
	v_cvt_pk_bf16_f32 v0, v12, v13
	v_cvt_pk_bf16_f32 v1, v14, v15
	v_cvt_pk_bf16_f32 v2, v8, v9
	v_cvt_pk_bf16_f32 v3, v10, v11
	global_store_dwordx4 v[16:17], v[0:3], off
	s_nop 1
	v_cvt_pk_bf16_f32 v0, v4, v5
	v_cvt_pk_bf16_f32 v1, v6, v7
	v_cvt_pk_bf16_f32 v2, v18, v19
	v_cvt_pk_bf16_f32 v3, v20, v21
	global_store_dwordx4 v[16:17], v[0:3], off offset:256
	s_cbranch_vccz .LBB0_118
	s_waitcnt vmcnt(0)
	s_cmpk_gt_u32 s40, 0xff
	s_cbranch_scc1 .LBB0_129
	s_barrier

; #define PG8_STAGE(bufoff, gbase, voff) do { _Pragma("unroll") for (int _i = 0; _i < 2; ++_i) \
;         __builtin_amdgcn_global_load_lds((const unsigned*)((const char*)(gbase) + (voff)[_i]), (LAS unsigned*)(lds + (bufoff) + ldsw + _i * 8192), 16, 0, 0); } while (0)
; #define PG8_LDA(dst, b, h) do { _Pragma("unroll") for (int m = 0; m < 4; ++m) _Pragma("unroll") for (int k = 0; k < 2; ++k) dst[m][k] = *(const LAS bf16x8*)(lds + PG8_SA(b, h) + aoff + m * 2048 + k * 1024); } while (0)
; #define PG8_LDB(dst, b, h) do { _Pragma("unroll") for (int n = 0; n < 2; ++n) _Pragma("unroll") for (int k = 0; k < 2; ++k) dst[n][k] = *(const LAS bf16x8*)(lds + PG8_SB(b, h) + boff + n * 2048 + k * 1024); } while (0)
; #define PG8_MMA(ai, bj, At, Bt) do { __builtin_amdgcn_s_setprio(1); _Pragma("unroll") for (int m = 0; m < 4; ++m) _Pragma("unroll") for (int n = 0; n < 2; ++n) _Pragma("unroll") for (int k = 0; k < 2; ++k) \
;         acc[ai][bj][m][n] = __builtin_amdgcn_mfma_f32_16x16x32_bf16(Bt[n][k], At[m][k], acc[ai][bj][m][n], 0, 0, 0); __builtin_amdgcn_s_setprio(0); } while (0)
; #define PG8_WAIT_L(n) asm volatile("s_waitcnt lgkmcnt(" #n ")" ::: "memory")
; #define PG8_BAR __builtin_amdgcn_s_barrier()
; #define PG8_SCHED __builtin_amdgcn_sched_barrier(0)
;     ...
;             PG8_LDB(B0, 0, 0); PG8_SCHED; PG8_LDA(At, 0, 0); PG8_STAGE(PG8_SA(1, 1), a1 + hA, voffA);
;             PG8_WAIT_L(8); PG8_BAR; PG8_WAIT_L(0); PG8_MMA(0, 0, At, B0); PG8_BAR; PG8_SCHED;
;             PG8_LDB(B1, 0, 1); PG8_STAGE(PG8_SB(0, 0), b2, voffB);
;             PG8_BAR; PG8_WAIT_L(0); PG8_MMA(0, 1, At, B1); PG8_BAR;
;             PG8_LDA(At, 0, 1); PG8_STAGE(PG8_SA(0, 0), a2, voffA);
;             PG8_BAR; PG8_WAIT_L(0); PG8_MMA(1, 0, At, B0); PG8_BAR; PG8_SCHED;
.LBB0_700:
	ds_read_b128 v[146:149], v159
	ds_read_b128 v[150:153], v159 offset:1024
	ds_read_b128 v[162:165], v159 offset:2048
	ds_read_b128 v[170:173], v159 offset:3072
	s_add_u32 s16, s14, 0xfffe0080
	s_addc_u32 s17, s15, -1
	s_cmp_eq_u32 s41, 4
	s_cselect_b32 s19, s7, s17
	s_cselect_b32 s18, s8, s16
	s_cselect_b32 s17, s9, s33
	s_cselect_b32 s16, s20, s21
	v_lshl_add_u64 v[154:155], s[14:15], 0, v[138:139]
	s_add_i32 m0, s67, 0xc000
	ds_read_b128 v[174:177], v160
	ds_read_b128 v[178:181], v160 offset:1024
	ds_read_b128 v[182:185], v160 offset:2048
	ds_read_b128 v[186:189], v160 offset:3072
	ds_read_b128 v[190:193], v160 offset:4096
	ds_read_b128 v[194:197], v160 offset:5120
	ds_read_b128 v[198:201], v160 offset:6144
	ds_read_b128 v[202:205], v160 offset:7168
	global_load_lds_dwordx4 v[154:155], off
	v_lshl_add_u64 v[154:155], s[14:15], 0, v[136:137]
	s_add_i32 m0, s67, 0xe000
	s_nop 0
	global_load_lds_dwordx4 v[154:155], off
	s_waitcnt lgkmcnt(8)
	s_barrier
	s_waitcnt lgkmcnt(0)
	s_setprio 1
	s_waitcnt lgkmcnt(0)
	v_mfma_f32_16x16x32_bf16 v[124:127], v[146:149], v[174:177], v[124:127]
	v_mfma_f32_16x16x32_bf16 v[120:123], v[162:165], v[174:177], v[120:123]
	v_mfma_f32_16x16x32_bf16 v[108:111], v[146:149], v[182:185], v[108:111]
	v_mfma_f32_16x16x32_bf16 v[104:107], v[162:165], v[182:185], v[104:107]
	v_mfma_f32_16x16x32_bf16 v[92:95], v[146:149], v[190:193], v[92:95]
	v_mfma_f32_16x16x32_bf16 v[88:91], v[162:165], v[190:193], v[88:91]
	v_mfma_f32_16x16x32_bf16 v[76:79], v[146:149], v[198:201], v[76:79]
	v_mfma_f32_16x16x32_bf16 v[72:75], v[162:165], v[198:201], v[72:75]
	v_mfma_f32_16x16x32_bf16 v[124:127], v[150:153], v[178:181], v[124:127]
	v_mfma_f32_16x16x32_bf16 v[120:123], v[170:173], v[178:181], v[120:123]
	v_mfma_f32_16x16x32_bf16 v[108:111], v[150:153], v[186:189], v[108:111]
	v_mfma_f32_16x16x32_bf16 v[104:107], v[170:173], v[186:189], v[104:107]
	v_mfma_f32_16x16x32_bf16 v[92:95], v[150:153], v[194:197], v[92:95]
	v_mfma_f32_16x16x32_bf16 v[88:91], v[170:173], v[194:197], v[88:91]
	v_mfma_f32_16x16x32_bf16 v[76:79], v[150:153], v[202:205], v[76:79]
	v_mfma_f32_16x16x32_bf16 v[72:75], v[170:173], v[202:205], v[72:75]
	s_setprio 0
	s_barrier
	s_add_i32 s42, s75, s66
	v_lshl_add_u64 v[154:155], s[16:17], 0, v[130:131]
	s_mov_b32 m0, s42
	ds_read_b128 v[206:209], v161
	ds_read_b128 v[210:213], v161 offset:1024
	ds_read_b128 v[214:217], v161 offset:2048
	ds_read_b128 v[218:221], v161 offset:3072
	global_load_lds_dwordx4 v[154:155], off
	v_lshl_add_u64 v[222:223], s[16:17], 0, v[134:135]
	s_add_i32 m0, s42, 0x2000
	s_nop 0
	global_load_lds_dwordx4 v[222:223], off
	s_barrier
	s_waitcnt lgkmcnt(0)
	s_setprio 1
	s_waitcnt lgkmcnt(0)
	v_mfma_f32_16x16x32_bf16 v[116:119], v[206:209], v[174:177], v[116:119]
	v_mfma_f32_16x16x32_bf16 v[112:115], v[214:217], v[174:177], v[112:115]
	v_mfma_f32_16x16x32_bf16 v[100:103], v[206:209], v[182:185], v[100:103]
	v_mfma_f32_16x16x32_bf16 v[96:99], v[214:217], v[182:185], v[96:99]
	v_mfma_f32_16x16x32_bf16 v[84:87], v[206:209], v[190:193], v[84:87]
	v_mfma_f32_16x16x32_bf16 v[80:83], v[214:217], v[190:193], v[80:83]
	v_mfma_f32_16x16x32_bf16 v[68:71], v[206:209], v[198:201], v[68:71]
	v_mfma_f32_16x16x32_bf16 v[64:67], v[214:217], v[198:201], v[64:67]
	v_mfma_f32_16x16x32_bf16 v[116:119], v[210:213], v[178:181], v[116:119]
	v_mfma_f32_16x16x32_bf16 v[112:115], v[218:221], v[178:181], v[112:115]
	v_mfma_f32_16x16x32_bf16 v[100:103], v[210:213], v[186:189], v[100:103]
	v_mfma_f32_16x16x32_bf16 v[96:99], v[218:221], v[186:189], v[96:99]
	v_mfma_f32_16x16x32_bf16 v[84:87], v[210:213], v[194:197], v[84:87]
	v_mfma_f32_16x16x32_bf16 v[80:83], v[218:221], v[194:197], v[80:83]
	v_mfma_f32_16x16x32_bf16 v[68:71], v[210:213], v[202:205], v[68:71]
	v_mfma_f32_16x16x32_bf16 v[64:67], v[218:221], v[202:205], v[64:67]
	s_setprio 0
	s_mov_b32 m0, s67
	v_lshl_add_u64 v[224:225], s[18:19], 0, v[128:129]
	s_barrier
	ds_read_b128 v[174:177], v160 offset:16384
	ds_read_b128 v[178:181], v160 offset:17408
	ds_read_b128 v[182:185], v160 offset:18432
	ds_read_b128 v[186:189], v160 offset:19456
	ds_read_b128 v[190:193], v160 offset:20480
	ds_read_b128 v[194:197], v160 offset:21504
	ds_read_b128 v[198:201], v160 offset:22528
	ds_read_b128 v[202:205], v160 offset:23552
	global_load_lds_dwordx4 v[224:225], off
	v_lshl_add_u64 v[226:227], s[18:19], 0, v[132:133]
	s_mov_b32 m0, s68
	s_nop 0
	global_load_lds_dwordx4 v[226:227], off
	s_barrier
	s_waitcnt lgkmcnt(0)
	s_setprio 1
	s_waitcnt lgkmcnt(0)
	v_mfma_f32_16x16x32_bf16 v[60:63], v[146:149], v[174:177], v[60:63]
	v_mfma_f32_16x16x32_bf16 v[56:59], v[162:165], v[174:177], v[56:59]
	v_mfma_f32_16x16x32_bf16 v[44:47], v[146:149], v[182:185], v[44:47]
	v_mfma_f32_16x16x32_bf16 v[40:43], v[162:165], v[182:185], v[40:43]
	v_mfma_f32_16x16x32_bf16 v[28:31], v[146:149], v[190:193], v[28:31]
	v_mfma_f32_16x16x32_bf16 v[24:27], v[162:165], v[190:193], v[24:27]
	v_mfma_f32_16x16x32_bf16 v[12:15], v[146:149], v[198:201], v[12:15]
	v_mfma_f32_16x16x32_bf16 v[8:11], v[162:165], v[198:201], v[8:11]
	v_mfma_f32_16x16x32_bf16 v[60:63], v[150:153], v[178:181], v[60:63]
	v_mfma_f32_16x16x32_bf16 v[56:59], v[170:173], v[178:181], v[56:59]
	v_mfma_f32_16x16x32_bf16 v[44:47], v[150:153], v[186:189], v[44:47]
	v_mfma_f32_16x16x32_bf16 v[40:43], v[170:173], v[186:189], v[40:43]
	v_mfma_f32_16x16x32_bf16 v[28:31], v[150:153], v[194:197], v[28:31]
	v_mfma_f32_16x16x32_bf16 v[24:27], v[170:173], v[194:197], v[24:27]
	v_mfma_f32_16x16x32_bf16 v[12:15], v[150:153], v[202:205], v[12:15]
	v_mfma_f32_16x16x32_bf16 v[8:11], v[170:173], v[202:205], v[8:11]
	s_setprio 0
	s_barrier
; #define PG8_STAGE(bufoff, gbase, voff) do { _Pragma("unroll") for (int _i = 0; _i < 2; ++_i) \
;         __builtin_amdgcn_global_load_lds((const unsigned*)((const char*)(gbase) + (voff)[_i]), (LAS unsigned*)(lds + (bufoff) + ldsw + _i * 8192), 16, 0, 0); } while (0)
; #define PG8_LDA(dst, b, h) do { _Pragma("unroll") for (int m = 0; m < 4; ++m) _Pragma("unroll") for (int k = 0; k < 2; ++k) dst[m][k] = *(const LAS bf16x8*)(lds + PG8_SA(b, h) + aoff + m * 2048 + k * 1024); } while (0)
; #define PG8_LDB(dst, b, h) do { _Pragma("unroll") for (int n = 0; n < 2; ++n) _Pragma("unroll") for (int k = 0; k < 2; ++k) dst[n][k] = *(const LAS bf16x8*)(lds + PG8_SB(b, h) + boff + n * 2048 + k * 1024); } while (0)
; #define PG8_MMA(ai, bj, At, Bt) do { __builtin_amdgcn_s_setprio(1); _Pragma("unroll") for (int m = 0; m < 4; ++m) _Pragma("unroll") for (int n = 0; n < 2; ++n) _Pragma("unroll") for (int k = 0; k < 2; ++k) \
;         acc[ai][bj][m][n] = __builtin_amdgcn_mfma_f32_16x16x32_bf16(Bt[n][k], At[m][k], acc[ai][bj][m][n], 0, 0, 0); __builtin_amdgcn_s_setprio(0); } while (0)
; #define PG8_WAIT_V(n) asm volatile("s_waitcnt vmcnt(" #n ")" ::: "memory")
; #define PG8_WAIT_L(n) asm volatile("s_waitcnt lgkmcnt(" #n ")" ::: "memory")
; #define PG8_BAR __builtin_amdgcn_s_barrier()
; #define PG8_SCHED __builtin_amdgcn_sched_barrier(0)
;     ...
;             PG8_STAGE(PG8_SB(0, 1), b2 + hB, voffB);
;             PG8_WAIT_V(6); PG8_BAR; PG8_MMA(1, 1, At, B1); PG8_BAR;
;             PG8_LDB(B0, 1, 0); PG8_SCHED; PG8_LDA(At, 1, 0); PG8_STAGE(PG8_SA(0, 1), a2 + hA, voffA);
;             PG8_WAIT_L(8); PG8_BAR; PG8_WAIT_L(0); PG8_MMA(0, 0, At, B0); PG8_BAR; PG8_SCHED;
;             PG8_LDB(B1, 1, 1); PG8_STAGE(PG8_SB(1, 0), b3, voffB);
;             PG8_BAR; PG8_WAIT_L(0); PG8_MMA(0, 1, At, B1); PG8_BAR;
;             PG8_LDA(At, 1, 1); PG8_STAGE(PG8_SA(1, 0), a3, voffA);
	s_add_u32 s42, s16, 0x20000
	s_addc_u32 s43, s17, 0
	s_add_i32 s44, s76, s66
	v_lshl_add_u64 v[146:147], s[42:43], 0, v[130:131]
	s_mov_b32 m0, s44
	s_nop 0
	global_load_lds_dwordx4 v[146:147], off
	v_lshl_add_u64 v[146:147], s[42:43], 0, v[134:135]
	s_add_i32 m0, s44, 0x2000
	s_nop 0
	global_load_lds_dwordx4 v[146:147], off
	s_waitcnt vmcnt(6)
	s_barrier
	s_setprio 1
	v_mfma_f32_16x16x32_bf16 v[52:55], v[206:209], v[174:177], v[52:55]
	v_mfma_f32_16x16x32_bf16 v[48:51], v[214:217], v[174:177], v[48:51]
	v_mfma_f32_16x16x32_bf16 v[36:39], v[206:209], v[182:185], v[36:39]
	v_mfma_f32_16x16x32_bf16 v[32:35], v[214:217], v[182:185], v[32:35]
	v_mfma_f32_16x16x32_bf16 v[20:23], v[206:209], v[190:193], v[20:23]
	v_mfma_f32_16x16x32_bf16 v[16:19], v[214:217], v[190:193], v[16:19]
	v_mfma_f32_16x16x32_bf16 v[4:7], v[206:209], v[198:201], v[4:7]
	v_mfma_f32_16x16x32_bf16 v[0:3], v[214:217], v[198:201], v[0:3]
	v_mfma_f32_16x16x32_bf16 v[52:55], v[210:213], v[178:181], v[52:55]
	v_mfma_f32_16x16x32_bf16 v[48:51], v[218:221], v[178:181], v[48:51]
	v_mfma_f32_16x16x32_bf16 v[36:39], v[210:213], v[186:189], v[36:39]
	v_mfma_f32_16x16x32_bf16 v[32:35], v[218:221], v[186:189], v[32:35]
	v_mfma_f32_16x16x32_bf16 v[20:23], v[210:213], v[194:197], v[20:23]
	v_mfma_f32_16x16x32_bf16 v[16:19], v[218:221], v[194:197], v[16:19]
	v_mfma_f32_16x16x32_bf16 v[4:7], v[210:213], v[202:205], v[4:7]
	v_mfma_f32_16x16x32_bf16 v[0:3], v[218:221], v[202:205], v[0:3]
	s_setprio 0
	s_add_i32 s42, 0, 0x18000
	v_add_u32_e32 v170, s42, v157
	s_barrier
	ds_read_b128 v[146:149], v170
	ds_read_b128 v[150:153], v170 offset:1024
	ds_read_b128 v[162:165], v170 offset:2048
	ds_read_b128 v[170:173], v170 offset:3072
	s_add_u32 s18, s18, 0x20000
	s_addc_u32 s19, s19, 0
	s_mov_b32 m0, s69
	v_lshl_add_u64 v[206:207], s[18:19], 0, v[128:129]
	ds_read_b128 v[174:177], v160 offset:32768
	ds_read_b128 v[178:181], v160 offset:33792
	ds_read_b128 v[182:185], v160 offset:34816
	ds_read_b128 v[186:189], v160 offset:35840
	ds_read_b128 v[190:193], v160 offset:36864
	ds_read_b128 v[194:197], v160 offset:37888
	ds_read_b128 v[198:201], v160 offset:38912
	ds_read_b128 v[202:205], v160 offset:39936
	global_load_lds_dwordx4 v[206:207], off
	v_lshl_add_u64 v[206:207], s[18:19], 0, v[132:133]
	s_mov_b32 m0, s70
	s_nop 0
	global_load_lds_dwordx4 v[206:207], off
	s_waitcnt lgkmcnt(8)
	s_barrier
	s_waitcnt lgkmcnt(0)
	s_setprio 1
	s_waitcnt lgkmcnt(0)
	v_mfma_f32_16x16x32_bf16 v[124:127], v[146:149], v[174:177], v[124:127]
	v_mfma_f32_16x16x32_bf16 v[120:123], v[162:165], v[174:177], v[120:123]
	v_mfma_f32_16x16x32_bf16 v[108:111], v[146:149], v[182:185], v[108:111]
	v_mfma_f32_16x16x32_bf16 v[104:107], v[162:165], v[182:185], v[104:107]
	v_mfma_f32_16x16x32_bf16 v[92:95], v[146:149], v[190:193], v[92:95]
	v_mfma_f32_16x16x32_bf16 v[88:91], v[162:165], v[190:193], v[88:91]
	v_mfma_f32_16x16x32_bf16 v[76:79], v[146:149], v[198:201], v[76:79]
	v_mfma_f32_16x16x32_bf16 v[72:75], v[162:165], v[198:201], v[72:75]
	v_mfma_f32_16x16x32_bf16 v[124:127], v[150:153], v[178:181], v[124:127]
	v_mfma_f32_16x16x32_bf16 v[120:123], v[170:173], v[178:181], v[120:123]
	v_mfma_f32_16x16x32_bf16 v[108:111], v[150:153], v[186:189], v[108:111]
	v_mfma_f32_16x16x32_bf16 v[104:107], v[170:173], v[186:189], v[104:107]
	v_mfma_f32_16x16x32_bf16 v[92:95], v[150:153], v[194:197], v[92:95]
	v_mfma_f32_16x16x32_bf16 v[88:91], v[170:173], v[194:197], v[88:91]
	v_mfma_f32_16x16x32_bf16 v[76:79], v[150:153], v[202:205], v[76:79]
	v_mfma_f32_16x16x32_bf16 v[72:75], v[170:173], v[202:205], v[72:75]
	s_setprio 0
	s_barrier
	s_add_i32 s18, 0, 0x1c000
	s_add_i32 s19, s42, s66
	v_add_u32_e32 v218, s18, v157
	v_lshl_add_u64 v[154:155], v[154:155], 0, s[54:55]
	s_mov_b32 m0, s19
	ds_read_b128 v[206:209], v218
	ds_read_b128 v[210:213], v218 offset:1024
	ds_read_b128 v[214:217], v218 offset:2048
	ds_read_b128 v[218:221], v218 offset:3072
	global_load_lds_dwordx4 v[154:155], off
	v_lshl_add_u64 v[154:155], v[222:223], 0, s[54:55]
	s_add_i32 m0, s19, 0x2000
	s_nop 0
	global_load_lds_dwordx4 v[154:155], off
	s_barrier
	s_waitcnt lgkmcnt(0)
	s_setprio 1
	s_waitcnt lgkmcnt(0)
	v_mfma_f32_16x16x32_bf16 v[116:119], v[206:209], v[174:177], v[116:119]
	v_mfma_f32_16x16x32_bf16 v[112:115], v[214:217], v[174:177], v[112:115]
	v_mfma_f32_16x16x32_bf16 v[100:103], v[206:209], v[182:185], v[100:103]
	v_mfma_f32_16x16x32_bf16 v[96:99], v[214:217], v[182:185], v[96:99]
	v_mfma_f32_16x16x32_bf16 v[84:87], v[206:209], v[190:193], v[84:87]
	v_mfma_f32_16x16x32_bf16 v[80:83], v[214:217], v[190:193], v[80:83]
	v_mfma_f32_16x16x32_bf16 v[68:71], v[206:209], v[198:201], v[68:71]
	v_mfma_f32_16x16x32_bf16 v[64:67], v[214:217], v[198:201], v[64:67]
	v_mfma_f32_16x16x32_bf16 v[116:119], v[210:213], v[178:181], v[116:119]
	v_mfma_f32_16x16x32_bf16 v[112:115], v[218:221], v[178:181], v[112:115]
	v_mfma_f32_16x16x32_bf16 v[100:103], v[210:213], v[186:189], v[100:103]
	v_mfma_f32_16x16x32_bf16 v[96:99], v[218:221], v[186:189], v[96:99]
	v_mfma_f32_16x16x32_bf16 v[84:87], v[210:213], v[194:197], v[84:87]
	v_mfma_f32_16x16x32_bf16 v[80:83], v[218:221], v[194:197], v[80:83]
	v_mfma_f32_16x16x32_bf16 v[68:71], v[210:213], v[202:205], v[68:71]
	v_mfma_f32_16x16x32_bf16 v[64:67], v[218:221], v[202:205], v[64:67]
	s_setprio 0
	s_mov_b32 m0, s72
	v_lshl_add_u64 v[154:155], v[224:225], 0, s[54:55]
	s_barrier
	ds_read_b128 v[174:177], v160 offset:49152
	ds_read_b128 v[178:181], v160 offset:50176
	ds_read_b128 v[182:185], v160 offset:51200
	ds_read_b128 v[186:189], v160 offset:52224
	ds_read_b128 v[190:193], v160 offset:53248
	ds_read_b128 v[194:197], v160 offset:54272
	ds_read_b128 v[198:201], v160 offset:55296
	ds_read_b128 v[202:205], v160 offset:56320
	global_load_lds_dwordx4 v[154:155], off
	v_lshl_add_u64 v[154:155], v[226:227], 0, s[54:55]
	s_mov_b32 m0, s73
	s_nop 0
	global_load_lds_dwordx4 v[154:155], off
	s_barrier
; __device__ __forceinline__ float sigmoidf_(float x) { return 1.0f / (1.0f + __expf(-x)); }
; #define PG8_STAGE(bufoff, gbase, voff) do { _Pragma("unroll") for (int _i = 0; _i < 2; ++_i) \
;         __builtin_amdgcn_global_load_lds((const unsigned*)((const char*)(gbase) + (voff)[_i]), (LAS unsigned*)(lds + (bufoff) + ldsw + _i * 8192), 16, 0, 0); } while (0)
; #define PG8_MMA(ai, bj, At, Bt) do { __builtin_amdgcn_s_setprio(1); _Pragma("unroll") for (int m = 0; m < 4; ++m) _Pragma("unroll") for (int n = 0; n < 2; ++n) _Pragma("unroll") for (int k = 0; k < 2; ++k) \
;         acc[ai][bj][m][n] = __builtin_amdgcn_mfma_f32_16x16x32_bf16(Bt[n][k], At[m][k], acc[ai][bj][m][n], 0, 0, 0); __builtin_amdgcn_s_setprio(0); } while (0)
; #define PG8_WAIT_V(n) asm volatile("s_waitcnt vmcnt(" #n ")" ::: "memory")
; #define PG8_WAIT_L(n) asm volatile("s_waitcnt lgkmcnt(" #n ")" ::: "memory")
; #define PG8_BAR __builtin_amdgcn_s_barrier()
; #define PG8_SCHED __builtin_amdgcn_sched_barrier(0)
;     ...
;             PG8_BAR; PG8_WAIT_L(0); PG8_MMA(1, 0, At, B0); PG8_BAR; PG8_SCHED;
;             PG8_STAGE(PG8_SB(1, 1), b3 + hB, voffB);
;             PG8_WAIT_V(6); PG8_BAR; PG8_MMA(1, 1, At, B1); PG8_BAR;
;     __device__ __forceinline__ void operator()(const f32x4 (&acc)[2][2][4][2], const Unit& u, int wr, int wc, int fr, int fq) const {
;     ...
;         const int row0 = row_off + u.pm * 256 + wr * 64 + fr, col0 = u.pn * 256 + wc * 32 + 8 * fq;
; #pragma unroll
;         for (int ai = 0; ai < 2; ++ai)
; #pragma unroll
;             for (int m = 0; m < 4; ++m) {
;                 const int row = row0 + ai * 128 + m * 16;
;                 const bf16_t* rowp = z + (size_t)row * DIN + col0;
; #pragma unroll
;                 for (int bj = 0; bj < 2; ++bj) {
;                     const u32x4 gw = *(const u32x4*)(rowp + O_GA + bj * 128);
;                     f32x4 g0, g1; unpack8(gw, g0, g1);
;                     f32x4 v0, v1;
; #pragma unroll
;                     for (int j = 0; j < 4; ++j) { v0[j] = sigmoidf_(g0[j]) * acc[ai][bj][m][0][j]; v1[j] = sigmoidf_(g1[j]) * acc[ai][bj][m][1][j]; }
;                     const u32x4 mw = *(const u32x4*)(rowp + bj * 128); f32x4 m0, m1; unpack8(mw, m0, m1); v0 += m0; v1 += m1;
	s_waitcnt lgkmcnt(0)
	s_setprio 1
	s_waitcnt lgkmcnt(0)
	v_mfma_f32_16x16x32_bf16 v[60:63], v[146:149], v[174:177], v[60:63]
	v_mfma_f32_16x16x32_bf16 v[56:59], v[162:165], v[174:177], v[56:59]
	v_mfma_f32_16x16x32_bf16 v[44:47], v[146:149], v[182:185], v[44:47]
	v_mfma_f32_16x16x32_bf16 v[40:43], v[162:165], v[182:185], v[40:43]
	v_mfma_f32_16x16x32_bf16 v[28:31], v[146:149], v[190:193], v[28:31]
	v_mfma_f32_16x16x32_bf16 v[24:27], v[162:165], v[190:193], v[24:27]
	v_mfma_f32_16x16x32_bf16 v[12:15], v[146:149], v[198:201], v[12:15]
	v_mfma_f32_16x16x32_bf16 v[8:11], v[162:165], v[198:201], v[8:11]
	v_mfma_f32_16x16x32_bf16 v[60:63], v[150:153], v[178:181], v[60:63]
	v_mfma_f32_16x16x32_bf16 v[56:59], v[170:173], v[178:181], v[56:59]
	v_mfma_f32_16x16x32_bf16 v[44:47], v[150:153], v[186:189], v[44:47]
	v_mfma_f32_16x16x32_bf16 v[40:43], v[170:173], v[186:189], v[40:43]
	v_mfma_f32_16x16x32_bf16 v[28:31], v[150:153], v[194:197], v[28:31]
	v_mfma_f32_16x16x32_bf16 v[24:27], v[170:173], v[194:197], v[24:27]
	v_mfma_f32_16x16x32_bf16 v[12:15], v[150:153], v[202:205], v[12:15]
	v_mfma_f32_16x16x32_bf16 v[8:11], v[170:173], v[202:205], v[8:11]
	s_setprio 0
	s_barrier
	s_add_u32 s16, s16, 0x20080
	s_addc_u32 s17, s17, 0
	s_add_i32 s18, s18, s66
	v_lshl_add_u64 v[146:147], s[16:17], 0, v[130:131]
	s_mov_b32 m0, s18
	s_nop 0
	global_load_lds_dwordx4 v[146:147], off
	v_lshl_add_u64 v[146:147], s[16:17], 0, v[134:135]
	s_add_i32 m0, s18, 0x2000
	s_nop 0
	global_load_lds_dwordx4 v[146:147], off
	s_waitcnt vmcnt(6)
	s_barrier
	s_setprio 1
	v_mfma_f32_16x16x32_bf16 v[52:55], v[206:209], v[174:177], v[52:55]
	v_mfma_f32_16x16x32_bf16 v[48:51], v[214:217], v[174:177], v[48:51]
	v_mfma_f32_16x16x32_bf16 v[36:39], v[206:209], v[182:185], v[36:39]
	v_mfma_f32_16x16x32_bf16 v[32:35], v[214:217], v[182:185], v[32:35]
	v_mfma_f32_16x16x32_bf16 v[20:23], v[206:209], v[190:193], v[20:23]
	v_mfma_f32_16x16x32_bf16 v[16:19], v[214:217], v[190:193], v[16:19]
	v_mfma_f32_16x16x32_bf16 v[4:7], v[206:209], v[198:201], v[4:7]
	v_mfma_f32_16x16x32_bf16 v[0:3], v[214:217], v[198:201], v[0:3]
	v_mfma_f32_16x16x32_bf16 v[52:55], v[210:213], v[178:181], v[52:55]
	v_mfma_f32_16x16x32_bf16 v[48:51], v[218:221], v[178:181], v[48:51]
	v_mfma_f32_16x16x32_bf16 v[36:39], v[210:213], v[186:189], v[36:39]
	v_mfma_f32_16x16x32_bf16 v[32:35], v[218:221], v[186:189], v[32:35]
	v_mfma_f32_16x16x32_bf16 v[20:23], v[210:213], v[194:197], v[20:23]
	v_mfma_f32_16x16x32_bf16 v[16:19], v[218:221], v[194:197], v[16:19]
	v_mfma_f32_16x16x32_bf16 v[4:7], v[210:213], v[202:205], v[4:7]
	v_mfma_f32_16x16x32_bf16 v[0:3], v[218:221], v[202:205], v[0:3]
	s_setprio 0
	s_add_i32 s41, s41, 2
	s_add_u32 s21, s21, 0x100
	s_addc_u32 s33, s33, 0
	s_add_u32 s14, s14, 0x100
	s_addc_u32 s15, s15, 0
	s_cmp_gt_u32 s41, 5
	s_barrier
	s_cbranch_scc0 .LBB0_700
	v_lshl_or_b32 v146, s6, 8, v158
	v_lshl_add_u32 v162, s79, 8, v156
	v_ashrrev_i32_e32 v147, 31, v146
	v_mad_i64_i32 v[154:155], s[6:7], v162, s77, 0
	v_lshl_add_u64 v[150:151], v[154:155], 1, s[38:39]
	v_lshlrev_b64 v[148:149], 1, v[146:147]
	v_lshl_add_u64 v[150:151], v[150:151], 0, v[148:149]
	v_add_co_u32_e32 v152, vcc, 0x1000, v150
	s_nop 1
	v_addc_co_u32_e32 v153, vcc, 0, v151, vcc
	v_subrev_u32_e32 v202, s38, v150
	v_add_u32_e32 v203, 0x1200, v202
	global_load_dwordx4 v[204:207], v203, s[38:39]
	v_add_u32_e32 v203, 0x0, v202
	global_load_dwordx4 v[208:211], v203, s[38:39]
	v_add_u32_e32 v203, 0x1300, v202
	global_load_dwordx4 v[212:215], v203, s[38:39]
	v_add_u32_e32 v203, 0x100, v202
	global_load_dwordx4 v[216:219], v203, s[38:39]
	v_add_u32_e32 v203, 0x23200, v202
	global_load_dwordx4 v[232:235], v203, s[38:39]
	v_add_u32_e32 v203, 0x22000, v202
	global_load_dwordx4 v[236:239], v203, s[38:39]
	v_add_u32_e32 v203, 0x23300, v202
	global_load_dwordx4 v[240:243], v203, s[38:39]
	v_add_u32_e32 v203, 0x22100, v202
	global_load_dwordx4 v[244:247], v203, s[38:39]
	v_add_u32_e32 v203, 0x45200, v202
	global_load_dwordx4 v[248:251], v203, s[38:39]
	v_add_u32_e32 v203, 0x44000, v202
	global_load_dwordx4 v[252:255], v203, s[38:39]
	s_waitcnt vmcnt(8)
	v_mov_b32_e32 v170, v204
	v_mov_b32_e32 v171, v205
	v_mov_b32_e32 v172, v206
	v_mov_b32_e32 v173, v207
	v_mov_b32_e32 v174, v208
	v_mov_b32_e32 v175, v209
	v_mov_b32_e32 v176, v210
	v_mov_b32_e32 v177, v211
	v_add_u32_e32 v203, 0x45300, v202
	global_load_dwordx4 v[204:207], v203, s[38:39]
	v_add_u32_e32 v203, 0x44100, v202
	global_load_dwordx4 v[208:211], v203, s[38:39]
	v_lshlrev_b32_e32 v147, 16, v170
	v_and_b32_e32 v155, 0xffff0000, v170
	v_lshlrev_b32_e32 v165, 16, v172
	v_and_b32_e32 v164, 0xffff0000, v171
	v_and_b32_e32 v170, 0xffff0000, v172
	v_mul_f32_e32 v147, 0xbfb8aa3b, v147
	v_mul_f32_e32 v165, 0xbfb8aa3b, v165
	v_mul_f32_e32 v155, 0xbfb8aa3b, v155
	v_lshlrev_b32_e32 v163, 16, v171
	v_lshlrev_b32_e32 v171, 16, v173
	v_and_b32_e32 v172, 0xffff0000, v173
	v_mul_f32_e32 v180, 0xbfb8aa3b, v170
	v_mul_f32_e32 v173, 0xbfb8aa3b, v164
	v_exp_f32_e32 v164, v147
	v_exp_f32_e32 v170, v165
	v_exp_f32_e32 v165, v155
	v_mul_f32_e32 v163, 0xbfb8aa3b, v163
	v_mul_f32_e32 v179, 0xbfb8aa3b, v172
	v_exp_f32_e32 v172, v163
	v_exp_f32_e32 v173, v173
	v_mul_f32_e32 v171, 0xbfb8aa3b, v171
	v_pk_add_f32 v[164:165], v[164:165], 1.0 op_sel_hi:[1,0]
	v_exp_f32_e32 v178, v171
	v_exp_f32_e32 v171, v180
	v_div_scale_f32 v147, s[6:7], v165, v165, 1.0
	v_pk_add_f32 v[172:173], v[172:173], 1.0 op_sel_hi:[1,0]
	v_div_scale_f32 v163, s[6:7], v164, v164, 1.0
	v_rcp_f32_e32 v187, v147
	v_div_scale_f32 v181, s[6:7], v173, v173, 1.0
	v_rcp_f32_e32 v188, v163
	v_div_scale_f32 v183, s[6:7], v172, v172, 1.0
	v_rcp_f32_e32 v189, v181
; __device__ __forceinline__ float sigmoidf_(float x) { return 1.0f / (1.0f + __expf(-x)); }
; __device__ __forceinline__ u32x4 pack8(const f32x4 v0, const f32x4 v1) { u32x4 w; w.x = pk2(v0[0], v0[1]); w.y = pk2(v0[2], v0[3]); w.z = pk2(v1[0], v1[1]); w.w = pk2(v1[2], v1[3]); return w; }
; __device__ __forceinline__ void unpack8(const u32x4 w, f32x4& v0, f32x4& v1) { v0 = (f32x4){bflo(w.x), bfhi(w.x), bflo(w.y), bfhi(w.y)}; v1 = (f32x4){bflo(w.z), bfhi(w.z), bflo(w.w), bfhi(w.w)}; }
;     __device__ __forceinline__ void operator()(const f32x4 (&acc)[2][2][4][2], const Unit& u, int wr, int wc, int fr, int fq) const {
;     ...
;                 for (int bj = 0; bj < 2; ++bj) {
;                     const u32x4 gw = *(const u32x4*)(rowp + O_GA + bj * 128);
;                     f32x4 g0, g1; unpack8(gw, g0, g1);
;                     f32x4 v0, v1;
; #pragma unroll
;                     for (int j = 0; j < 4; ++j) { v0[j] = sigmoidf_(g0[j]) * acc[ai][bj][m][0][j]; v1[j] = sigmoidf_(g1[j]) * acc[ai][bj][m][1][j]; }
;                     const u32x4 mw = *(const u32x4*)(rowp + bj * 128); f32x4 m0, m1; unpack8(mw, m0, m1); v0 += m0; v1 += m1;
;                     __builtin_amdgcn_raw_buffer_store_b128(pack8(v0, v1), rsrc, (unsigned)(((size_t)row * DIN + col0 + bj * 128) * 2), 0, 16  ); }
	v_pk_add_f32 v[170:171], v[170:171], 1.0 op_sel_hi:[1,0]
	v_rcp_f32_e32 v190, v183
	v_div_scale_f32 v185, s[6:7], v171, v171, 1.0
	v_fma_f32 v192, -v147, v187, 1.0
	v_div_scale_f32 v155, vcc, 1.0, v165, 1.0
	v_rcp_f32_e32 v191, v185
	v_fma_f32 v193, -v163, v188, 1.0
	v_fmac_f32_e32 v187, v192, v187
	v_div_scale_f32 v180, s[14:15], 1.0, v164, 1.0
	v_fma_f32 v194, -v181, v189, 1.0
	v_fmac_f32_e32 v188, v193, v188
	v_mul_f32_e32 v192, v155, v187
	v_div_scale_f32 v182, s[16:17], 1.0, v173, 1.0
	v_fma_f32 v195, -v183, v190, 1.0
	v_fmac_f32_e32 v189, v194, v189
	v_mul_f32_e32 v193, v180, v188
	v_fma_f32 v197, -v147, v192, v155
	v_div_scale_f32 v184, s[18:19], 1.0, v172, 1.0
	v_fmac_f32_e32 v190, v195, v190
	v_mul_f32_e32 v194, v182, v189
	v_fma_f32 v198, -v163, v193, v180
	v_fmac_f32_e32 v192, v197, v187
	v_fma_f32 v196, -v185, v191, 1.0
	v_mul_f32_e32 v195, v184, v190
	v_fma_f32 v199, -v181, v194, v182
	v_fmac_f32_e32 v193, v198, v188
	v_fma_f32 v147, -v147, v192, v155
	v_div_scale_f32 v186, s[20:21], 1.0, v171, 1.0
	v_fmac_f32_e32 v191, v196, v191
	v_fma_f32 v200, -v183, v195, v184
	v_fmac_f32_e32 v194, v199, v189
	v_fma_f32 v155, -v163, v193, v180
	v_div_fmas_f32 v147, v147, v187, v192
	s_mov_b64 vcc, s[14:15]
	v_mul_f32_e32 v196, v186, v191
	v_fmac_f32_e32 v195, v200, v190
	v_fma_f32 v163, -v181, v194, v182
	v_div_fixup_f32 v165, v147, v165, 1.0
	v_div_fmas_f32 v147, v155, v188, v193
	s_mov_b64 vcc, s[16:17]
	v_div_scale_f32 v155, s[6:7], v170, v170, 1.0
	v_fma_f32 v201, -v185, v196, v186
	v_fma_f32 v180, -v183, v195, v184
	v_div_fixup_f32 v164, v147, v164, 1.0
	v_div_fmas_f32 v147, v163, v189, v194
	s_mov_b64 vcc, s[18:19]
	v_rcp_f32_e32 v163, v155
	v_fmac_f32_e32 v196, v201, v191
	v_div_fixup_f32 v173, v147, v173, 1.0
	v_div_fmas_f32 v147, v180, v190, v195
	v_div_fixup_f32 v172, v147, v172, 1.0
	v_fma_f32 v147, -v185, v196, v186
	s_mov_b64 vcc, s[20:21]
	v_div_fmas_f32 v147, v147, v191, v196
	v_exp_f32_e32 v179, v179
	v_div_fixup_f32 v171, v147, v171, 1.0
	v_fma_f32 v147, -v155, v163, 1.0
	v_fmac_f32_e32 v163, v147, v163
	v_div_scale_f32 v147, vcc, 1.0, v170, 1.0
	v_mul_f32_e32 v180, v147, v163
	v_fma_f32 v181, -v155, v180, v147
	v_pk_add_f32 v[178:179], v[178:179], 1.0 op_sel_hi:[1,0]
	v_fmac_f32_e32 v180, v181, v163
	v_fma_f32 v147, -v155, v180, v147
	v_div_scale_f32 v155, s[6:7], v179, v179, 1.0
	v_rcp_f32_e32 v181, v155
	v_div_fmas_f32 v147, v147, v163, v180
	v_div_fixup_f32 v170, v147, v170, 1.0
	v_lshlrev_b32_e32 v182, 16, v176
	v_fma_f32 v147, -v155, v181, 1.0
	v_fmac_f32_e32 v181, v147, v181
	v_div_scale_f32 v147, vcc, 1.0, v179, 1.0
	v_mul_f32_e32 v163, v147, v181
	v_fma_f32 v180, -v155, v163, v147
	v_fmac_f32_e32 v163, v180, v181
	v_fma_f32 v147, -v155, v163, v147
	v_div_scale_f32 v155, s[6:7], v178, v178, 1.0
	v_rcp_f32_e32 v180, v155
	v_div_fmas_f32 v147, v147, v181, v163
	v_div_fixup_f32 v179, v147, v179, 1.0
	v_and_b32_e32 v183, 0xffff0000, v176
	v_fma_f32 v147, -v155, v180, 1.0
	v_fmac_f32_e32 v180, v147, v180
	v_div_scale_f32 v147, vcc, 1.0, v178, 1.0
	v_mul_f32_e32 v163, v147, v180
	v_fma_f32 v181, -v155, v163, v147
	v_fmac_f32_e32 v163, v181, v180
	v_fma_f32 v147, -v155, v163, v147
	v_div_fmas_f32 v147, v147, v180, v163
	v_div_fixup_f32 v178, v147, v178, 1.0
	v_lshlrev_b32_e32 v180, 16, v174
	v_and_b32_e32 v181, 0xffff0000, v174
	v_lshlrev_b32_e32 v176, 16, v177
	v_and_b32_e32 v177, 0xffff0000, v177
	v_lshlrev_b32_e32 v174, 16, v175
	v_and_b32_e32 v175, 0xffff0000, v175
	v_pk_fma_f32 v[124:125], v[124:125], v[164:165], v[180:181]
	v_pk_fma_f32 v[164:165], v[122:123], v[178:179], v[176:177]
	v_pk_fma_f32 v[122:123], v[120:121], v[170:171], v[182:183]
	v_add_lshl_u32 v147, v146, v154, 1
	v_pk_fma_f32 v[126:127], v[126:127], v[172:173], v[174:175]
	v_cvt_pk_bf16_f32 v120, v124, v125
	s_nop 0
	v_cvt_pk_bf16_f32 v121, v126, v127
	v_cvt_pk_bf16_f32 v122, v122, v123
	v_cvt_pk_bf16_f32 v123, v164, v165
	buffer_store_dwordx4 v[120:123], v147, s[24:27], 0 offen sc1
	s_nop 0
	s_waitcnt vmcnt(9)
	v_mov_b32_e32 v120, v212
	v_mov_b32_e32 v121, v213
	v_mov_b32_e32 v122, v214
	v_mov_b32_e32 v123, v215
	v_mov_b32_e32 v124, v216
	v_mov_b32_e32 v125, v217
	v_mov_b32_e32 v126, v218
	v_mov_b32_e32 v127, v219
	v_add_u32_e32 v203, 0x67200, v202
	global_load_dwordx4 v[212:215], v203, s[38:39]
	v_add_u32_e32 v203, 0x66000, v202
	global_load_dwordx4 v[216:219], v203, s[38:39]
	v_lshlrev_b32_e32 v150, 16, v120
	v_and_b32_e32 v120, 0xffff0000, v120
	v_lshlrev_b32_e32 v151, 16, v121
	v_and_b32_e32 v121, 0xffff0000, v121
	v_lshlrev_b32_e32 v152, 16, v122
	v_and_b32_e32 v122, 0xffff0000, v122
	v_lshlrev_b32_e32 v153, 16, v123
	v_and_b32_e32 v154, 0xffff0000, v123
	v_mul_f32_e32 v123, 0xbfb8aa3b, v150
	v_mul_f32_e32 v150, 0xbfb8aa3b, v152
	v_mul_f32_e32 v152, 0xbfb8aa3b, v120
	v_mul_f32_e32 v151, 0xbfb8aa3b, v151
	v_mul_f32_e32 v121, 0xbfb8aa3b, v121
	v_mul_f32_e32 v155, 0xbfb8aa3b, v122
	v_exp_f32_e32 v120, v123
	v_exp_f32_e32 v122, v150
	v_exp_f32_e32 v150, v151
	v_exp_f32_e32 v151, v121
	v_exp_f32_e32 v121, v152
	v_mul_f32_e32 v153, 0xbfb8aa3b, v153
	v_exp_f32_e32 v152, v153
	v_exp_f32_e32 v123, v155
	v_pk_add_f32 v[120:121], v[120:121], 1.0 op_sel_hi:[1,0]
	v_pk_add_f32 v[150:151], v[150:151], 1.0 op_sel_hi:[1,0]
	v_div_scale_f32 v153, s[6:7], v121, v121, 1.0
	v_rcp_f32_e32 v163, v153
	v_div_scale_f32 v155, vcc, 1.0, v121, 1.0
	v_div_scale_f32 v164, s[6:7], v120, v120, 1.0
	v_fma_f32 v170, -v153, v163, 1.0
	v_fmac_f32_e32 v163, v170, v163
	v_mul_f32_e32 v170, v155, v163
	v_rcp_f32_e32 v165, v164
	v_fma_f32 v171, -v153, v170, v155
	v_fmac_f32_e32 v170, v171, v163
	v_fma_f32 v153, -v153, v170, v155
	v_div_fmas_f32 v153, v153, v163, v170
; __device__ __forceinline__ float sigmoidf_(float x) { return 1.0f / (1.0f + __expf(-x)); }
; __device__ __forceinline__ u32x4 pack8(const f32x4 v0, const f32x4 v1) { u32x4 w; w.x = pk2(v0[0], v0[1]); w.y = pk2(v0[2], v0[3]); w.z = pk2(v1[0], v1[1]); w.w = pk2(v1[2], v1[3]); return w; }
; __device__ __forceinline__ void unpack8(const u32x4 w, f32x4& v0, f32x4& v1) { v0 = (f32x4){bflo(w.x), bfhi(w.x), bflo(w.y), bfhi(w.y)}; v1 = (f32x4){bflo(w.z), bfhi(w.z), bflo(w.w), bfhi(w.w)}; }
;     __device__ __forceinline__ void operator()(const f32x4 (&acc)[2][2][4][2], const Unit& u, int wr, int wc, int fr, int fq) const {
;     ...
;                 for (int bj = 0; bj < 2; ++bj) {
;                     const u32x4 gw = *(const u32x4*)(rowp + O_GA + bj * 128);
;                     f32x4 g0, g1; unpack8(gw, g0, g1);
;                     f32x4 v0, v1;
; #pragma unroll
;                     for (int j = 0; j < 4; ++j) { v0[j] = sigmoidf_(g0[j]) * acc[ai][bj][m][0][j]; v1[j] = sigmoidf_(g1[j]) * acc[ai][bj][m][1][j]; }
;                     const u32x4 mw = *(const u32x4*)(rowp + bj * 128); f32x4 m0, m1; unpack8(mw, m0, m1); v0 += m0; v1 += m1;
;                     __builtin_amdgcn_raw_buffer_store_b128(pack8(v0, v1), rsrc, (unsigned)(((size_t)row * DIN + col0 + bj * 128) * 2), 0, 16  ); }
	v_div_fixup_f32 v121, v153, v121, 1.0
	v_fma_f32 v153, -v164, v165, 1.0
	v_fmac_f32_e32 v165, v153, v165
	v_div_scale_f32 v153, vcc, 1.0, v120, 1.0
	v_mul_f32_e32 v155, v153, v165
	v_fma_f32 v163, -v164, v155, v153
	v_fmac_f32_e32 v155, v163, v165
	v_div_scale_f32 v163, s[6:7], v151, v151, 1.0
	v_fma_f32 v153, -v164, v155, v153
	v_rcp_f32_e32 v164, v163
	v_div_fmas_f32 v153, v153, v165, v155
	v_div_fixup_f32 v120, v153, v120, 1.0
	v_pk_add_f32 v[122:123], v[122:123], 1.0 op_sel_hi:[1,0]
	v_fma_f32 v153, -v163, v164, 1.0
	v_fmac_f32_e32 v164, v153, v164
	v_div_scale_f32 v153, vcc, 1.0, v151, 1.0
	v_mul_f32_e32 v155, v153, v164
	v_fma_f32 v165, -v163, v155, v153
	v_fmac_f32_e32 v155, v165, v164
	v_fma_f32 v153, -v163, v155, v153
	v_div_scale_f32 v163, s[6:7], v150, v150, 1.0
	v_rcp_f32_e32 v165, v163
	v_div_fmas_f32 v153, v153, v164, v155
	v_div_fixup_f32 v151, v153, v151, 1.0
	v_fma_f32 v153, -v163, v165, 1.0
	v_fmac_f32_e32 v165, v153, v165
	v_div_scale_f32 v153, vcc, 1.0, v150, 1.0
	v_mul_f32_e32 v155, v153, v165
	v_fma_f32 v164, -v163, v155, v153
	v_fmac_f32_e32 v155, v164, v165
	v_fma_f32 v163, -v163, v155, v153
	v_mul_f32_e32 v153, 0xbfb8aa3b, v154
	v_div_scale_f32 v154, s[6:7], v123, v123, 1.0
	v_rcp_f32_e32 v164, v154
	v_div_fmas_f32 v155, v163, v165, v155
	v_div_fixup_f32 v150, v155, v150, 1.0
	v_exp_f32_e32 v153, v153
	v_fma_f32 v155, -v154, v164, 1.0
	v_fmac_f32_e32 v164, v155, v164
	v_div_scale_f32 v155, vcc, 1.0, v123, 1.0
	v_mul_f32_e32 v163, v155, v164
	v_fma_f32 v165, -v154, v163, v155
	v_fmac_f32_e32 v163, v165, v164
	v_fma_f32 v154, -v154, v163, v155
	v_div_scale_f32 v155, s[6:7], v122, v122, 1.0
	v_rcp_f32_e32 v165, v155
	v_div_fmas_f32 v154, v154, v164, v163
	v_div_fixup_f32 v123, v154, v123, 1.0
	v_pk_add_f32 v[152:153], v[152:153], 1.0 op_sel_hi:[1,0]
	v_fma_f32 v154, -v155, v165, 1.0
	v_fmac_f32_e32 v165, v154, v165
	v_div_scale_f32 v154, vcc, 1.0, v122, 1.0
	v_mul_f32_e32 v163, v154, v165
	v_fma_f32 v164, -v155, v163, v154
	v_fmac_f32_e32 v163, v164, v165
	v_fma_f32 v154, -v155, v163, v154
	v_div_scale_f32 v155, s[6:7], v153, v153, 1.0
	v_rcp_f32_e32 v164, v155
	v_div_fmas_f32 v154, v154, v165, v163
	v_div_fixup_f32 v122, v154, v122, 1.0
	v_fma_f32 v154, -v155, v164, 1.0
	v_fmac_f32_e32 v164, v154, v164
	v_div_scale_f32 v154, vcc, 1.0, v153, 1.0
	v_mul_f32_e32 v163, v154, v164
	v_fma_f32 v165, -v155, v163, v154
	v_fmac_f32_e32 v163, v165, v164
	v_fma_f32 v154, -v155, v163, v154
	v_div_scale_f32 v155, s[6:7], v152, v152, 1.0
	v_rcp_f32_e32 v165, v155
	v_div_fmas_f32 v154, v154, v164, v163
	v_div_fixup_f32 v153, v154, v153, 1.0
	v_fma_f32 v154, -v155, v165, 1.0
	v_fmac_f32_e32 v165, v154, v165
	v_div_scale_f32 v154, vcc, 1.0, v152, 1.0
	v_mul_f32_e32 v163, v154, v165
	v_fma_f32 v164, -v155, v163, v154
	v_fmac_f32_e32 v163, v164, v165
	v_fma_f32 v154, -v155, v163, v154
	v_div_fmas_f32 v154, v154, v165, v163
	v_div_fixup_f32 v152, v154, v152, 1.0
	v_lshlrev_b32_e32 v154, 16, v124
	v_and_b32_e32 v155, 0xffff0000, v124
	v_lshlrev_b32_e32 v164, 16, v126
	v_and_b32_e32 v165, 0xffff0000, v126
	v_lshlrev_b32_e32 v126, 16, v127
	v_and_b32_e32 v127, 0xffff0000, v127
	v_lshlrev_b32_e32 v124, 16, v125
	v_and_b32_e32 v125, 0xffff0000, v125
	v_pk_fma_f32 v[116:117], v[116:117], v[120:121], v[154:155]
	v_pk_fma_f32 v[120:121], v[114:115], v[152:153], v[126:127]
	v_pk_fma_f32 v[114:115], v[112:113], v[122:123], v[164:165]
	v_cvt_pk_bf16_f32 v112, v116, v117
	v_pk_fma_f32 v[118:119], v[118:119], v[150:151], v[124:125]
	s_nop 0
	v_cvt_pk_bf16_f32 v113, v118, v119
	v_cvt_pk_bf16_f32 v114, v114, v115
	v_cvt_pk_bf16_f32 v115, v120, v121
	buffer_store_dwordx4 v[112:115], v147, s[24:27], 0 offen offset:256 sc1
	s_nop 1
	v_or_b32_e32 v112, 16, v162
	v_mad_i64_i32 v[114:115], s[6:7], v112, s77, 0
	v_lshl_add_u64 v[112:113], v[114:115], 1, s[38:39]
	v_lshl_add_u64 v[112:113], v[112:113], 0, v[148:149]
	v_add_co_u32_e32 v116, vcc, s78, v112
	s_nop 1
	v_addc_co_u32_e32 v117, vcc, 0, v113, vcc
	s_waitcnt vmcnt(10)
	v_mov_b32_e32 v118, v232
	v_mov_b32_e32 v119, v233
	v_mov_b32_e32 v120, v234
	v_mov_b32_e32 v121, v235
	v_mov_b32_e32 v122, v236
	v_mov_b32_e32 v123, v237
	v_mov_b32_e32 v124, v238
	v_mov_b32_e32 v125, v239
	v_add_u32_e32 v203, 0x67300, v202
	global_load_dwordx4 v[232:235], v203, s[38:39]
	v_add_u32_e32 v203, 0x66100, v202
	global_load_dwordx4 v[236:239], v203, s[38:39]
	v_lshlrev_b32_e32 v115, 16, v118
	v_lshlrev_b32_e32 v127, 16, v119
	v_and_b32_e32 v147, 0xffff0000, v119
	v_lshlrev_b32_e32 v119, 16, v120
	v_mul_f32_e32 v115, 0xbfb8aa3b, v115
	v_and_b32_e32 v126, 0xffff0000, v118
	v_exp_f32_e32 v118, v115
	v_mul_f32_e32 v115, 0xbfb8aa3b, v119
	v_and_b32_e32 v150, 0xffff0000, v120
	v_exp_f32_e32 v120, v115
	v_mul_f32_e32 v115, 0xbfb8aa3b, v126
	v_exp_f32_e32 v119, v115
	v_mul_f32_e32 v115, 0xbfb8aa3b, v150
	v_lshlrev_b32_e32 v151, 16, v121
	v_and_b32_e32 v152, 0xffff0000, v121
	v_exp_f32_e32 v121, v115
	v_mul_f32_e32 v115, 0xbfb8aa3b, v127
	v_exp_f32_e32 v126, v115
	v_mul_f32_e32 v115, 0xbfb8aa3b, v147
	v_pk_add_f32 v[118:119], v[118:119], 1.0 op_sel_hi:[1,0]
	v_exp_f32_e32 v127, v115
	v_div_scale_f32 v115, s[6:7], v119, v119, 1.0
	v_rcp_f32_e32 v147, v115
	v_mul_f32_e32 v150, 0xbfb8aa3b, v151
	v_pk_add_f32 v[126:127], v[126:127], 1.0 op_sel_hi:[1,0]
	v_pk_add_f32 v[120:121], v[120:121], 1.0 op_sel_hi:[1,0]
	v_fma_f32 v151, -v115, v147, 1.0
	v_fmac_f32_e32 v147, v151, v147
	v_div_scale_f32 v151, vcc, 1.0, v119, 1.0
	v_mul_f32_e32 v153, v151, v147
	v_fma_f32 v154, -v115, v153, v151
	v_fmac_f32_e32 v153, v154, v147
	v_fma_f32 v115, -v115, v153, v151
	v_div_scale_f32 v151, s[6:7], v118, v118, 1.0
	v_rcp_f32_e32 v154, v151
; __device__ __forceinline__ float sigmoidf_(float x) { return 1.0f / (1.0f + __expf(-x)); }
; __device__ __forceinline__ u32x4 pack8(const f32x4 v0, const f32x4 v1) { u32x4 w; w.x = pk2(v0[0], v0[1]); w.y = pk2(v0[2], v0[3]); w.z = pk2(v1[0], v1[1]); w.w = pk2(v1[2], v1[3]); return w; }
; __device__ __forceinline__ void unpack8(const u32x4 w, f32x4& v0, f32x4& v1) { v0 = (f32x4){bflo(w.x), bfhi(w.x), bflo(w.y), bfhi(w.y)}; v1 = (f32x4){bflo(w.z), bfhi(w.z), bflo(w.w), bfhi(w.w)}; }
;     __device__ __forceinline__ void operator()(const f32x4 (&acc)[2][2][4][2], const Unit& u, int wr, int wc, int fr, int fq) const {
;     ...
;                 for (int bj = 0; bj < 2; ++bj) {
;                     const u32x4 gw = *(const u32x4*)(rowp + O_GA + bj * 128);
;                     f32x4 g0, g1; unpack8(gw, g0, g1);
;                     f32x4 v0, v1;
; #pragma unroll
;                     for (int j = 0; j < 4; ++j) { v0[j] = sigmoidf_(g0[j]) * acc[ai][bj][m][0][j]; v1[j] = sigmoidf_(g1[j]) * acc[ai][bj][m][1][j]; }
;                     const u32x4 mw = *(const u32x4*)(rowp + bj * 128); f32x4 m0, m1; unpack8(mw, m0, m1); v0 += m0; v1 += m1;
;                     __builtin_amdgcn_raw_buffer_store_b128(pack8(v0, v1), rsrc, (unsigned)(((size_t)row * DIN + col0 + bj * 128) * 2), 0, 16  ); }
	v_div_fmas_f32 v115, v115, v147, v153
	v_div_fixup_f32 v119, v115, v119, 1.0
	v_exp_f32_e32 v150, v150
	v_fma_f32 v115, -v151, v154, 1.0
	v_fmac_f32_e32 v154, v115, v154
	v_div_scale_f32 v115, vcc, 1.0, v118, 1.0
	v_mul_f32_e32 v147, v115, v154
	v_fma_f32 v153, -v151, v147, v115
	v_fmac_f32_e32 v147, v153, v154
	v_fma_f32 v115, -v151, v147, v115
	v_div_scale_f32 v151, s[6:7], v127, v127, 1.0
	v_rcp_f32_e32 v153, v151
	v_div_fmas_f32 v115, v115, v154, v147
	v_div_fixup_f32 v118, v115, v118, 1.0
	v_and_b32_e32 v155, 0xffff0000, v124
	v_fma_f32 v115, -v151, v153, 1.0
	v_fmac_f32_e32 v153, v115, v153
	v_div_scale_f32 v115, vcc, 1.0, v127, 1.0
	v_mul_f32_e32 v147, v115, v153
	v_fma_f32 v154, -v151, v147, v115
	v_fmac_f32_e32 v147, v154, v153
	v_fma_f32 v115, -v151, v147, v115
	v_div_scale_f32 v151, s[6:7], v126, v126, 1.0
	v_rcp_f32_e32 v154, v151
	v_div_fmas_f32 v115, v115, v153, v147
	v_div_fixup_f32 v127, v115, v127, 1.0
	v_fma_f32 v115, -v151, v154, 1.0
	v_fmac_f32_e32 v154, v115, v154
	v_div_scale_f32 v115, vcc, 1.0, v126, 1.0
	v_mul_f32_e32 v147, v115, v154
	v_fma_f32 v153, -v151, v147, v115
	v_fmac_f32_e32 v147, v153, v154
	v_fma_f32 v115, -v151, v147, v115
	v_mul_f32_e32 v151, 0xbfb8aa3b, v152
	v_div_scale_f32 v152, s[6:7], v121, v121, 1.0
	v_rcp_f32_e32 v153, v152
	v_div_fmas_f32 v115, v115, v154, v147
	v_div_fixup_f32 v126, v115, v126, 1.0
	v_exp_f32_e32 v151, v151
	v_fma_f32 v115, -v152, v153, 1.0
	v_fmac_f32_e32 v153, v115, v153
	v_div_scale_f32 v115, vcc, 1.0, v121, 1.0
	v_mul_f32_e32 v147, v115, v153
	v_fma_f32 v154, -v152, v147, v115
	v_fmac_f32_e32 v147, v154, v153
	v_fma_f32 v115, -v152, v147, v115
	v_div_scale_f32 v152, s[6:7], v120, v120, 1.0
	v_rcp_f32_e32 v154, v152
	v_div_fmas_f32 v115, v115, v153, v147
	v_div_fixup_f32 v121, v115, v121, 1.0
	v_pk_add_f32 v[150:151], v[150:151], 1.0 op_sel_hi:[1,0]
	v_fma_f32 v115, -v152, v154, 1.0
	v_fmac_f32_e32 v154, v115, v154
	v_div_scale_f32 v115, vcc, 1.0, v120, 1.0
	v_mul_f32_e32 v147, v115, v154
	v_fma_f32 v153, -v152, v147, v115
	v_fmac_f32_e32 v147, v153, v154
	v_fma_f32 v115, -v152, v147, v115
	v_div_scale_f32 v152, s[6:7], v151, v151, 1.0
	v_rcp_f32_e32 v153, v152
	v_div_fmas_f32 v115, v115, v154, v147
	v_div_fixup_f32 v120, v115, v120, 1.0
	v_fma_f32 v115, -v152, v153, 1.0
	v_fmac_f32_e32 v153, v115, v153
	v_div_scale_f32 v115, vcc, 1.0, v151, 1.0
	v_mul_f32_e32 v147, v115, v153
	v_fma_f32 v154, -v152, v147, v115
	v_fmac_f32_e32 v147, v154, v153
	v_fma_f32 v115, -v152, v147, v115
	v_div_scale_f32 v152, s[6:7], v150, v150, 1.0
	v_rcp_f32_e32 v154, v152
	v_div_fmas_f32 v115, v115, v153, v147
	v_div_fixup_f32 v151, v115, v151, 1.0
	v_fma_f32 v115, -v152, v154, 1.0
	v_fmac_f32_e32 v154, v115, v154
	v_div_scale_f32 v115, vcc, 1.0, v150, 1.0
	v_mul_f32_e32 v147, v115, v154
	v_fma_f32 v153, -v152, v147, v115
	v_fmac_f32_e32 v147, v153, v154
	v_fma_f32 v115, -v152, v147, v115
	v_div_fmas_f32 v115, v115, v154, v147
	v_div_fixup_f32 v150, v115, v150, 1.0
	v_lshlrev_b32_e32 v152, 16, v122
	v_and_b32_e32 v153, 0xffff0000, v122
	v_lshlrev_b32_e32 v154, 16, v124
	v_lshlrev_b32_e32 v124, 16, v125
	v_and_b32_e32 v125, 0xffff0000, v125
	v_lshlrev_b32_e32 v122, 16, v123
	v_and_b32_e32 v123, 0xffff0000, v123
	v_pk_fma_f32 v[108:109], v[108:109], v[118:119], v[152:153]
	v_pk_fma_f32 v[118:119], v[106:107], v[150:151], v[124:125]
	v_pk_fma_f32 v[106:107], v[104:105], v[120:121], v[154:155]
	v_add_lshl_u32 v120, v146, v114, 1
	v_pk_fma_f32 v[110:111], v[110:111], v[126:127], v[122:123]
	v_cvt_pk_bf16_f32 v104, v108, v109
	s_nop 0
	v_cvt_pk_bf16_f32 v105, v110, v111
	v_cvt_pk_bf16_f32 v106, v106, v107
	v_cvt_pk_bf16_f32 v107, v118, v119
	buffer_store_dwordx4 v[104:107], v120, s[24:27], 0 offen sc1
	s_nop 0
	s_waitcnt vmcnt(11)
	v_mov_b32_e32 v104, v240
	v_mov_b32_e32 v105, v241
	v_mov_b32_e32 v106, v242
	v_mov_b32_e32 v107, v243
	v_mov_b32_e32 v108, v244
	v_mov_b32_e32 v109, v245
	v_mov_b32_e32 v110, v246
	v_mov_b32_e32 v111, v247
	v_add_u32_e32 v203, 0x111200, v202
	global_load_dwordx4 v[240:243], v203, s[38:39]
	v_add_u32_e32 v203, 0x110000, v202
	global_load_dwordx4 v[244:247], v203, s[38:39]
	v_lshlrev_b32_e32 v114, 16, v105
	v_and_b32_e32 v115, 0xffff0000, v105
	v_lshlrev_b32_e32 v105, 16, v106
	v_lshlrev_b32_e32 v112, 16, v104
	v_and_b32_e32 v113, 0xffff0000, v104
	v_mul_f32_e32 v105, 0xbfb8aa3b, v105
	v_and_b32_e32 v116, 0xffff0000, v106
	v_mul_f32_e32 v104, 0xbfb8aa3b, v112
	v_exp_f32_e32 v106, v105
	v_mul_f32_e32 v105, 0xbfb8aa3b, v113
	v_exp_f32_e32 v104, v104
	v_exp_f32_e32 v105, v105
	v_mul_f32_e32 v113, 0xbfb8aa3b, v115
	v_lshlrev_b32_e32 v117, 16, v107
	v_and_b32_e32 v118, 0xffff0000, v107
	v_pk_add_f32 v[104:105], v[104:105], 1.0 op_sel_hi:[1,0]
	v_mul_f32_e32 v107, 0xbfb8aa3b, v116
	v_div_scale_f32 v115, s[6:7], v105, v105, 1.0
	v_rcp_f32_e32 v116, v115
	v_mul_f32_e32 v112, 0xbfb8aa3b, v114
	v_mul_f32_e32 v114, 0xbfb8aa3b, v117
	v_exp_f32_e32 v112, v112
	v_fma_f32 v117, -v115, v116, 1.0
	v_fmac_f32_e32 v116, v117, v116
	v_div_scale_f32 v117, vcc, 1.0, v105, 1.0
	v_mul_f32_e32 v119, v117, v116
	v_fma_f32 v121, -v115, v119, v117
	v_fmac_f32_e32 v119, v121, v116
	v_fma_f32 v115, -v115, v119, v117
	v_div_scale_f32 v117, s[6:7], v104, v104, 1.0
	v_rcp_f32_e32 v121, v117
	v_div_fmas_f32 v115, v115, v116, v119
	v_exp_f32_e32 v113, v113
	v_div_fixup_f32 v105, v115, v105, 1.0
	v_fma_f32 v115, -v117, v121, 1.0
	v_fmac_f32_e32 v121, v115, v121
	v_div_scale_f32 v115, vcc, 1.0, v104, 1.0
	v_mul_f32_e32 v116, v115, v121
	v_fma_f32 v119, -v117, v116, v115
	v_pk_add_f32 v[112:113], v[112:113], 1.0 op_sel_hi:[1,0]
	v_fmac_f32_e32 v116, v119, v121
	v_fma_f32 v115, -v117, v116, v115
; __device__ __forceinline__ float sigmoidf_(float x) { return 1.0f / (1.0f + __expf(-x)); }
; __device__ __forceinline__ u32x4 pack8(const f32x4 v0, const f32x4 v1) { u32x4 w; w.x = pk2(v0[0], v0[1]); w.y = pk2(v0[2], v0[3]); w.z = pk2(v1[0], v1[1]); w.w = pk2(v1[2], v1[3]); return w; }
; __device__ __forceinline__ void unpack8(const u32x4 w, f32x4& v0, f32x4& v1) { v0 = (f32x4){bflo(w.x), bfhi(w.x), bflo(w.y), bfhi(w.y)}; v1 = (f32x4){bflo(w.z), bfhi(w.z), bflo(w.w), bfhi(w.w)}; }
;     __device__ __forceinline__ void operator()(const f32x4 (&acc)[2][2][4][2], const Unit& u, int wr, int wc, int fr, int fq) const {
;     ...
;                 for (int bj = 0; bj < 2; ++bj) {
;                     const u32x4 gw = *(const u32x4*)(rowp + O_GA + bj * 128);
;                     f32x4 g0, g1; unpack8(gw, g0, g1);
;                     f32x4 v0, v1;
; #pragma unroll
;                     for (int j = 0; j < 4; ++j) { v0[j] = sigmoidf_(g0[j]) * acc[ai][bj][m][0][j]; v1[j] = sigmoidf_(g1[j]) * acc[ai][bj][m][1][j]; }
;                     const u32x4 mw = *(const u32x4*)(rowp + bj * 128); f32x4 m0, m1; unpack8(mw, m0, m1); v0 += m0; v1 += m1;
;                     __builtin_amdgcn_raw_buffer_store_b128(pack8(v0, v1), rsrc, (unsigned)(((size_t)row * DIN + col0 + bj * 128) * 2), 0, 16  ); }
	v_div_scale_f32 v117, s[6:7], v113, v113, 1.0
	v_rcp_f32_e32 v119, v117
	v_div_fmas_f32 v115, v115, v121, v116
	v_div_fixup_f32 v104, v115, v104, 1.0
	v_exp_f32_e32 v107, v107
	v_fma_f32 v115, -v117, v119, 1.0
	v_fmac_f32_e32 v119, v115, v119
	v_div_scale_f32 v115, vcc, 1.0, v113, 1.0
	v_mul_f32_e32 v116, v115, v119
	v_fma_f32 v121, -v117, v116, v115
	v_fmac_f32_e32 v116, v121, v119
	v_fma_f32 v115, -v117, v116, v115
	v_div_scale_f32 v117, s[6:7], v112, v112, 1.0
	v_rcp_f32_e32 v121, v117
	v_div_fmas_f32 v115, v115, v119, v116
	v_div_fixup_f32 v113, v115, v113, 1.0
	v_pk_add_f32 v[106:107], v[106:107], 1.0 op_sel_hi:[1,0]
	v_fma_f32 v115, -v117, v121, 1.0
	v_fmac_f32_e32 v121, v115, v121
	v_div_scale_f32 v115, vcc, 1.0, v112, 1.0
	v_mul_f32_e32 v116, v115, v121
	v_fma_f32 v119, -v117, v116, v115
	v_fmac_f32_e32 v116, v119, v121
	v_fma_f32 v117, -v117, v116, v115
	v_mul_f32_e32 v115, 0xbfb8aa3b, v118
	v_div_scale_f32 v118, s[6:7], v107, v107, 1.0
	v_rcp_f32_e32 v119, v118
	v_div_fmas_f32 v116, v117, v121, v116
	v_div_fixup_f32 v112, v116, v112, 1.0
	v_exp_f32_e32 v114, v114
	v_fma_f32 v116, -v118, v119, 1.0
	v_fmac_f32_e32 v119, v116, v119
	v_div_scale_f32 v116, vcc, 1.0, v107, 1.0
	v_mul_f32_e32 v117, v116, v119
	v_fma_f32 v121, -v118, v117, v116
	v_fmac_f32_e32 v117, v121, v119
	v_fma_f32 v116, -v118, v117, v116
	v_div_scale_f32 v118, s[6:7], v106, v106, 1.0
	v_rcp_f32_e32 v121, v118
	v_div_fmas_f32 v116, v116, v119, v117
	v_exp_f32_e32 v115, v115
	v_div_fixup_f32 v107, v116, v107, 1.0
	v_fma_f32 v116, -v118, v121, 1.0
	v_fmac_f32_e32 v121, v116, v121
	v_div_scale_f32 v116, vcc, 1.0, v106, 1.0
	v_mul_f32_e32 v117, v116, v121
	v_fma_f32 v119, -v118, v117, v116
	v_pk_add_f32 v[114:115], v[114:115], 1.0 op_sel_hi:[1,0]
	v_fmac_f32_e32 v117, v119, v121
	v_fma_f32 v116, -v118, v117, v116
	v_div_scale_f32 v118, s[6:7], v115, v115, 1.0
	v_rcp_f32_e32 v119, v118
	v_div_fmas_f32 v116, v116, v121, v117
	v_div_fixup_f32 v106, v116, v106, 1.0
	v_fma_f32 v116, -v118, v119, 1.0
	v_fmac_f32_e32 v119, v116, v119
	v_div_scale_f32 v116, vcc, 1.0, v115, 1.0
	v_mul_f32_e32 v117, v116, v119
	v_fma_f32 v121, -v118, v117, v116
	v_fmac_f32_e32 v117, v121, v119
	v_fma_f32 v116, -v118, v117, v116
	v_div_scale_f32 v118, s[6:7], v114, v114, 1.0
	v_rcp_f32_e32 v121, v118
	v_div_fmas_f32 v116, v116, v119, v117
	v_div_fixup_f32 v115, v116, v115, 1.0
	v_fma_f32 v116, -v118, v121, 1.0
	v_fmac_f32_e32 v121, v116, v121
	v_div_scale_f32 v116, vcc, 1.0, v114, 1.0
	v_mul_f32_e32 v117, v116, v121
	v_fma_f32 v119, -v118, v117, v116
	v_fmac_f32_e32 v117, v119, v121
	v_fma_f32 v116, -v118, v117, v116
	v_div_fmas_f32 v116, v116, v121, v117
	v_div_fixup_f32 v114, v116, v114, 1.0
	v_lshlrev_b32_e32 v116, 16, v108
	v_and_b32_e32 v117, 0xffff0000, v108
	v_lshlrev_b32_e32 v118, 16, v110
	v_and_b32_e32 v119, 0xffff0000, v110
	v_lshlrev_b32_e32 v110, 16, v111
	v_and_b32_e32 v111, 0xffff0000, v111
	v_lshlrev_b32_e32 v108, 16, v109
	v_and_b32_e32 v109, 0xffff0000, v109
	v_pk_fma_f32 v[100:101], v[100:101], v[104:105], v[116:117]
	v_pk_fma_f32 v[104:105], v[98:99], v[114:115], v[110:111]
	v_pk_fma_f32 v[98:99], v[96:97], v[106:107], v[118:119]
	v_cvt_pk_bf16_f32 v96, v100, v101
	v_pk_fma_f32 v[102:103], v[102:103], v[112:113], v[108:109]
	s_nop 0
	v_cvt_pk_bf16_f32 v97, v102, v103
	v_cvt_pk_bf16_f32 v98, v98, v99
	v_cvt_pk_bf16_f32 v99, v104, v105
	buffer_store_dwordx4 v[96:99], v120, s[24:27], 0 offen offset:256 sc1
	s_nop 1
	v_or_b32_e32 v96, 32, v162
	v_mad_i64_i32 v[98:99], s[6:7], v96, s77, 0
	v_lshl_add_u64 v[96:97], v[98:99], 1, s[38:39]
	v_lshl_add_u64 v[96:97], v[96:97], 0, v[148:149]
	v_add_co_u32_e32 v100, vcc, s78, v96
	s_nop 1
	v_addc_co_u32_e32 v101, vcc, 0, v97, vcc
	s_waitcnt vmcnt(12)
	v_mov_b32_e32 v102, v248
	v_mov_b32_e32 v103, v249
	v_mov_b32_e32 v104, v250
	v_mov_b32_e32 v105, v251
	v_mov_b32_e32 v106, v252
	v_mov_b32_e32 v107, v253
	v_mov_b32_e32 v108, v254
	v_mov_b32_e32 v109, v255
	v_add_u32_e32 v203, 0x111300, v202
	global_load_dwordx4 v[248:251], v203, s[38:39]
	v_add_u32_e32 v203, 0x110100, v202
	global_load_dwordx4 v[252:255], v203, s[38:39]
	v_lshlrev_b32_e32 v99, 16, v102
	v_lshlrev_b32_e32 v111, 16, v103
	v_and_b32_e32 v112, 0xffff0000, v103
	v_lshlrev_b32_e32 v103, 16, v104
	v_mul_f32_e32 v99, 0xbfb8aa3b, v99
	v_and_b32_e32 v110, 0xffff0000, v102
	v_exp_f32_e32 v102, v99
	v_mul_f32_e32 v99, 0xbfb8aa3b, v103
	v_and_b32_e32 v113, 0xffff0000, v104
	v_exp_f32_e32 v104, v99
	v_mul_f32_e32 v99, 0xbfb8aa3b, v110
	v_exp_f32_e32 v103, v99
	v_mul_f32_e32 v99, 0xbfb8aa3b, v113
	v_lshlrev_b32_e32 v114, 16, v105
	v_and_b32_e32 v115, 0xffff0000, v105
	v_exp_f32_e32 v105, v99
	v_mul_f32_e32 v99, 0xbfb8aa3b, v111
	v_exp_f32_e32 v110, v99
	v_mul_f32_e32 v99, 0xbfb8aa3b, v112
	v_pk_add_f32 v[102:103], v[102:103], 1.0 op_sel_hi:[1,0]
	v_exp_f32_e32 v111, v99
	v_div_scale_f32 v99, s[6:7], v103, v103, 1.0
	v_rcp_f32_e32 v113, v99
	v_mul_f32_e32 v112, 0xbfb8aa3b, v114
	v_pk_add_f32 v[110:111], v[110:111], 1.0 op_sel_hi:[1,0]
	v_pk_add_f32 v[104:105], v[104:105], 1.0 op_sel_hi:[1,0]
	v_fma_f32 v114, -v99, v113, 1.0
	v_fmac_f32_e32 v113, v114, v113
	v_div_scale_f32 v114, vcc, 1.0, v103, 1.0
	v_mul_f32_e32 v116, v114, v113
	v_fma_f32 v117, -v99, v116, v114
	v_fmac_f32_e32 v116, v117, v113
	v_fma_f32 v99, -v99, v116, v114
	v_div_scale_f32 v114, s[6:7], v102, v102, 1.0
	v_rcp_f32_e32 v117, v114
	v_div_fmas_f32 v99, v99, v113, v116
	v_div_fixup_f32 v103, v99, v103, 1.0
	v_exp_f32_e32 v112, v112
	v_fma_f32 v99, -v114, v117, 1.0
	v_fmac_f32_e32 v117, v99, v117
	v_div_scale_f32 v99, vcc, 1.0, v102, 1.0
	v_mul_f32_e32 v113, v99, v117
	v_fma_f32 v116, -v114, v113, v99
; __device__ __forceinline__ float sigmoidf_(float x) { return 1.0f / (1.0f + __expf(-x)); }
; __device__ __forceinline__ u32x4 pack8(const f32x4 v0, const f32x4 v1) { u32x4 w; w.x = pk2(v0[0], v0[1]); w.y = pk2(v0[2], v0[3]); w.z = pk2(v1[0], v1[1]); w.w = pk2(v1[2], v1[3]); return w; }
; __device__ __forceinline__ void unpack8(const u32x4 w, f32x4& v0, f32x4& v1) { v0 = (f32x4){bflo(w.x), bfhi(w.x), bflo(w.y), bfhi(w.y)}; v1 = (f32x4){bflo(w.z), bfhi(w.z), bflo(w.w), bfhi(w.w)}; }
;     __device__ __forceinline__ void operator()(const f32x4 (&acc)[2][2][4][2], const Unit& u, int wr, int wc, int fr, int fq) const {
;     ...
;                 for (int bj = 0; bj < 2; ++bj) {
;                     const u32x4 gw = *(const u32x4*)(rowp + O_GA + bj * 128);
;                     f32x4 g0, g1; unpack8(gw, g0, g1);
;                     f32x4 v0, v1;
; #pragma unroll
;                     for (int j = 0; j < 4; ++j) { v0[j] = sigmoidf_(g0[j]) * acc[ai][bj][m][0][j]; v1[j] = sigmoidf_(g1[j]) * acc[ai][bj][m][1][j]; }
;                     const u32x4 mw = *(const u32x4*)(rowp + bj * 128); f32x4 m0, m1; unpack8(mw, m0, m1); v0 += m0; v1 += m1;
;                     __builtin_amdgcn_raw_buffer_store_b128(pack8(v0, v1), rsrc, (unsigned)(((size_t)row * DIN + col0 + bj * 128) * 2), 0, 16  ); }
	v_fmac_f32_e32 v113, v116, v117
	v_fma_f32 v99, -v114, v113, v99
	v_div_scale_f32 v114, s[6:7], v111, v111, 1.0
	v_rcp_f32_e32 v116, v114
	v_div_fmas_f32 v99, v99, v117, v113
	v_div_fixup_f32 v102, v99, v102, 1.0
	v_fma_f32 v99, -v114, v116, 1.0
	v_fmac_f32_e32 v116, v99, v116
	v_div_scale_f32 v99, vcc, 1.0, v111, 1.0
	v_mul_f32_e32 v113, v99, v116
	v_fma_f32 v117, -v114, v113, v99
	v_fmac_f32_e32 v113, v117, v116
	v_fma_f32 v99, -v114, v113, v99
	v_div_scale_f32 v114, s[6:7], v110, v110, 1.0
	v_rcp_f32_e32 v117, v114
	v_div_fmas_f32 v99, v99, v116, v113
	v_div_fixup_f32 v111, v99, v111, 1.0
	v_fma_f32 v99, -v114, v117, 1.0
	v_fmac_f32_e32 v117, v99, v117
	v_div_scale_f32 v99, vcc, 1.0, v110, 1.0
	v_mul_f32_e32 v116, v99, v117
	v_fma_f32 v113, -v114, v116, v99
	v_fmac_f32_e32 v116, v113, v117
	v_fma_f32 v99, -v114, v116, v99
	v_div_scale_f32 v114, s[6:7], v105, v105, 1.0
	v_mul_f32_e32 v113, 0xbfb8aa3b, v115
	v_rcp_f32_e32 v115, v114
	v_div_fmas_f32 v99, v99, v117, v116
	v_div_fixup_f32 v110, v99, v110, 1.0
	v_exp_f32_e32 v113, v113
	v_fma_f32 v99, -v114, v115, 1.0
	v_fmac_f32_e32 v115, v99, v115
	v_div_scale_f32 v99, vcc, 1.0, v105, 1.0
	v_mul_f32_e32 v116, v99, v115
	v_fma_f32 v117, -v114, v116, v99
	v_fmac_f32_e32 v116, v117, v115
	v_fma_f32 v99, -v114, v116, v99
	v_div_scale_f32 v114, s[6:7], v104, v104, 1.0
	v_rcp_f32_e32 v117, v114
	v_div_fmas_f32 v99, v99, v115, v116
	v_div_fixup_f32 v105, v99, v105, 1.0
	v_pk_add_f32 v[112:113], v[112:113], 1.0 op_sel_hi:[1,0]
	v_fma_f32 v99, -v114, v117, 1.0
	v_fmac_f32_e32 v117, v99, v117
	v_div_scale_f32 v99, vcc, 1.0, v104, 1.0
	v_mul_f32_e32 v115, v99, v117
	v_fma_f32 v116, -v114, v115, v99
	v_fmac_f32_e32 v115, v116, v117
	v_fma_f32 v99, -v114, v115, v99
	v_div_scale_f32 v114, s[6:7], v113, v113, 1.0
	v_rcp_f32_e32 v116, v114
	v_div_fmas_f32 v99, v99, v117, v115
	v_div_fixup_f32 v104, v99, v104, 1.0
	v_fma_f32 v99, -v114, v116, 1.0
	v_fmac_f32_e32 v116, v99, v116
	v_div_scale_f32 v99, vcc, 1.0, v113, 1.0
	v_mul_f32_e32 v115, v99, v116
	v_fma_f32 v117, -v114, v115, v99
	v_fmac_f32_e32 v115, v117, v116
	v_fma_f32 v99, -v114, v115, v99
	v_div_scale_f32 v114, s[6:7], v112, v112, 1.0
	v_rcp_f32_e32 v117, v114
	v_div_fmas_f32 v99, v99, v116, v115
	v_div_fixup_f32 v113, v99, v113, 1.0
	v_fma_f32 v99, -v114, v117, 1.0
	v_fmac_f32_e32 v117, v99, v117
	v_div_scale_f32 v99, vcc, 1.0, v112, 1.0
	v_mul_f32_e32 v115, v99, v117
	v_fma_f32 v116, -v114, v115, v99
	v_fmac_f32_e32 v115, v116, v117
	v_fma_f32 v99, -v114, v115, v99
	v_div_fmas_f32 v99, v99, v117, v115
	v_div_fixup_f32 v112, v99, v112, 1.0
	v_lshlrev_b32_e32 v114, 16, v106
	v_and_b32_e32 v115, 0xffff0000, v106
	v_lshlrev_b32_e32 v116, 16, v108
	v_and_b32_e32 v117, 0xffff0000, v108
	v_lshlrev_b32_e32 v108, 16, v109
	v_and_b32_e32 v109, 0xffff0000, v109
	v_lshlrev_b32_e32 v106, 16, v107
	v_and_b32_e32 v107, 0xffff0000, v107
	v_pk_fma_f32 v[92:93], v[92:93], v[102:103], v[114:115]
	v_pk_fma_f32 v[102:103], v[90:91], v[112:113], v[108:109]
	v_pk_fma_f32 v[90:91], v[88:89], v[104:105], v[116:117]
	v_add_lshl_u32 v104, v146, v98, 1
	v_pk_fma_f32 v[94:95], v[94:95], v[110:111], v[106:107]
	v_cvt_pk_bf16_f32 v88, v92, v93
	s_nop 0
	v_cvt_pk_bf16_f32 v89, v94, v95
	v_cvt_pk_bf16_f32 v90, v90, v91
	v_cvt_pk_bf16_f32 v91, v102, v103
	buffer_store_dwordx4 v[88:91], v104, s[24:27], 0 offen sc1
	s_nop 0
	s_waitcnt vmcnt(13)
	v_mov_b32_e32 v88, v204
	v_mov_b32_e32 v89, v205
	v_mov_b32_e32 v90, v206
	v_mov_b32_e32 v91, v207
	v_mov_b32_e32 v92, v208
	v_mov_b32_e32 v93, v209
	v_mov_b32_e32 v94, v210
	v_mov_b32_e32 v95, v211
	v_add_u32_e32 v203, 0x133200, v202
	global_load_dwordx4 v[204:207], v203, s[38:39]
	v_add_u32_e32 v203, 0x132000, v202
	global_load_dwordx4 v[208:211], v203, s[38:39]
	v_lshlrev_b32_e32 v98, 16, v89
	v_and_b32_e32 v99, 0xffff0000, v89
	v_lshlrev_b32_e32 v89, 16, v90
	v_lshlrev_b32_e32 v96, 16, v88
	v_and_b32_e32 v97, 0xffff0000, v88
	v_mul_f32_e32 v89, 0xbfb8aa3b, v89
	v_and_b32_e32 v100, 0xffff0000, v90
	v_mul_f32_e32 v88, 0xbfb8aa3b, v96
	v_exp_f32_e32 v90, v89
	v_mul_f32_e32 v89, 0xbfb8aa3b, v97
	v_exp_f32_e32 v88, v88
	v_exp_f32_e32 v89, v89
	v_mul_f32_e32 v97, 0xbfb8aa3b, v99
	v_lshlrev_b32_e32 v101, 16, v91
	v_and_b32_e32 v102, 0xffff0000, v91
	v_pk_add_f32 v[88:89], v[88:89], 1.0 op_sel_hi:[1,0]
	v_mul_f32_e32 v91, 0xbfb8aa3b, v100
	v_div_scale_f32 v99, s[6:7], v89, v89, 1.0
	v_rcp_f32_e32 v100, v99
	v_mul_f32_e32 v96, 0xbfb8aa3b, v98
	v_mul_f32_e32 v98, 0xbfb8aa3b, v101
	v_exp_f32_e32 v96, v96
	v_fma_f32 v101, -v99, v100, 1.0
	v_fmac_f32_e32 v100, v101, v100
	v_div_scale_f32 v101, vcc, 1.0, v89, 1.0
	v_mul_f32_e32 v103, v101, v100
	v_fma_f32 v105, -v99, v103, v101
	v_fmac_f32_e32 v103, v105, v100
	v_fma_f32 v99, -v99, v103, v101
	v_div_scale_f32 v101, s[6:7], v88, v88, 1.0
	v_rcp_f32_e32 v105, v101
	v_div_fmas_f32 v99, v99, v100, v103
	v_exp_f32_e32 v97, v97
	v_div_fixup_f32 v89, v99, v89, 1.0
	v_fma_f32 v99, -v101, v105, 1.0
	v_fmac_f32_e32 v105, v99, v105
	v_div_scale_f32 v99, vcc, 1.0, v88, 1.0
	v_mul_f32_e32 v100, v99, v105
	v_fma_f32 v103, -v101, v100, v99
	v_pk_add_f32 v[96:97], v[96:97], 1.0 op_sel_hi:[1,0]
	v_fmac_f32_e32 v100, v103, v105
	v_fma_f32 v99, -v101, v100, v99
	v_div_scale_f32 v101, s[6:7], v97, v97, 1.0
	v_rcp_f32_e32 v103, v101
	v_div_fmas_f32 v99, v99, v105, v100
	v_div_fixup_f32 v88, v99, v88, 1.0
	v_exp_f32_e32 v91, v91
	v_fma_f32 v99, -v101, v103, 1.0
	v_fmac_f32_e32 v103, v99, v103
	v_div_scale_f32 v99, vcc, 1.0, v97, 1.0
	v_mul_f32_e32 v100, v99, v103
	v_fma_f32 v105, -v101, v100, v99
	v_fmac_f32_e32 v100, v105, v103
	v_fma_f32 v99, -v101, v100, v99
	v_div_scale_f32 v101, s[6:7], v96, v96, 1.0
; __device__ __forceinline__ float sigmoidf_(float x) { return 1.0f / (1.0f + __expf(-x)); }
; __device__ __forceinline__ u32x4 pack8(const f32x4 v0, const f32x4 v1) { u32x4 w; w.x = pk2(v0[0], v0[1]); w.y = pk2(v0[2], v0[3]); w.z = pk2(v1[0], v1[1]); w.w = pk2(v1[2], v1[3]); return w; }
; __device__ __forceinline__ void unpack8(const u32x4 w, f32x4& v0, f32x4& v1) { v0 = (f32x4){bflo(w.x), bfhi(w.x), bflo(w.y), bfhi(w.y)}; v1 = (f32x4){bflo(w.z), bfhi(w.z), bflo(w.w), bfhi(w.w)}; }
;     __device__ __forceinline__ void operator()(const f32x4 (&acc)[2][2][4][2], const Unit& u, int wr, int wc, int fr, int fq) const {
;     ...
;                 for (int bj = 0; bj < 2; ++bj) {
;                     const u32x4 gw = *(const u32x4*)(rowp + O_GA + bj * 128);
;                     f32x4 g0, g1; unpack8(gw, g0, g1);
;                     f32x4 v0, v1;
; #pragma unroll
;                     for (int j = 0; j < 4; ++j) { v0[j] = sigmoidf_(g0[j]) * acc[ai][bj][m][0][j]; v1[j] = sigmoidf_(g1[j]) * acc[ai][bj][m][1][j]; }
;                     const u32x4 mw = *(const u32x4*)(rowp + bj * 128); f32x4 m0, m1; unpack8(mw, m0, m1); v0 += m0; v1 += m1;
;                     __builtin_amdgcn_raw_buffer_store_b128(pack8(v0, v1), rsrc, (unsigned)(((size_t)row * DIN + col0 + bj * 128) * 2), 0, 16  ); }
	v_rcp_f32_e32 v105, v101
	v_div_fmas_f32 v99, v99, v103, v100
	v_div_fixup_f32 v97, v99, v97, 1.0
	v_pk_add_f32 v[90:91], v[90:91], 1.0 op_sel_hi:[1,0]
	v_fma_f32 v99, -v101, v105, 1.0
	v_fmac_f32_e32 v105, v99, v105
	v_div_scale_f32 v99, vcc, 1.0, v96, 1.0
	v_mul_f32_e32 v100, v99, v105
	v_fma_f32 v103, -v101, v100, v99
	v_fmac_f32_e32 v100, v103, v105
	v_fma_f32 v101, -v101, v100, v99
	v_mul_f32_e32 v99, 0xbfb8aa3b, v102
	v_div_scale_f32 v102, s[6:7], v91, v91, 1.0
	v_rcp_f32_e32 v103, v102
	v_div_fmas_f32 v100, v101, v105, v100
	v_div_fixup_f32 v96, v100, v96, 1.0
	v_exp_f32_e32 v98, v98
	v_fma_f32 v100, -v102, v103, 1.0
	v_fmac_f32_e32 v103, v100, v103
	v_div_scale_f32 v100, vcc, 1.0, v91, 1.0
	v_mul_f32_e32 v101, v100, v103
	v_fma_f32 v105, -v102, v101, v100
	v_fmac_f32_e32 v101, v105, v103
	v_fma_f32 v100, -v102, v101, v100
	v_div_scale_f32 v102, s[6:7], v90, v90, 1.0
	v_rcp_f32_e32 v105, v102
	v_div_fmas_f32 v100, v100, v103, v101
	v_exp_f32_e32 v99, v99
	v_div_fixup_f32 v91, v100, v91, 1.0
	v_fma_f32 v100, -v102, v105, 1.0
	v_fmac_f32_e32 v105, v100, v105
	v_div_scale_f32 v100, vcc, 1.0, v90, 1.0
	v_mul_f32_e32 v101, v100, v105
	v_fma_f32 v103, -v102, v101, v100
	v_pk_add_f32 v[98:99], v[98:99], 1.0 op_sel_hi:[1,0]
	v_fmac_f32_e32 v101, v103, v105
	v_fma_f32 v100, -v102, v101, v100
	v_div_scale_f32 v102, s[6:7], v99, v99, 1.0
	v_rcp_f32_e32 v103, v102
	v_div_fmas_f32 v100, v100, v105, v101
	v_div_fixup_f32 v90, v100, v90, 1.0
	v_fma_f32 v100, -v102, v103, 1.0
	v_fmac_f32_e32 v103, v100, v103
	v_div_scale_f32 v100, vcc, 1.0, v99, 1.0
	v_mul_f32_e32 v101, v100, v103
	v_fma_f32 v105, -v102, v101, v100
	v_fmac_f32_e32 v101, v105, v103
	v_fma_f32 v100, -v102, v101, v100
	v_div_scale_f32 v102, s[6:7], v98, v98, 1.0
	v_rcp_f32_e32 v105, v102
	v_div_fmas_f32 v100, v100, v103, v101
	v_div_fixup_f32 v99, v100, v99, 1.0
	v_fma_f32 v100, -v102, v105, 1.0
	v_fmac_f32_e32 v105, v100, v105
	v_div_scale_f32 v100, vcc, 1.0, v98, 1.0
	v_mul_f32_e32 v101, v100, v105
	v_fma_f32 v103, -v102, v101, v100
	v_fmac_f32_e32 v101, v103, v105
	v_fma_f32 v100, -v102, v101, v100
	v_div_fmas_f32 v100, v100, v105, v101
	v_div_fixup_f32 v98, v100, v98, 1.0
	v_lshlrev_b32_e32 v100, 16, v92
	v_and_b32_e32 v101, 0xffff0000, v92
	v_lshlrev_b32_e32 v102, 16, v94
	v_and_b32_e32 v103, 0xffff0000, v94
	v_lshlrev_b32_e32 v94, 16, v95
	v_and_b32_e32 v95, 0xffff0000, v95
	v_lshlrev_b32_e32 v92, 16, v93
	v_and_b32_e32 v93, 0xffff0000, v93
	v_pk_fma_f32 v[84:85], v[84:85], v[88:89], v[100:101]
	v_pk_fma_f32 v[88:89], v[82:83], v[98:99], v[94:95]
	v_pk_fma_f32 v[82:83], v[80:81], v[90:91], v[102:103]
	v_cvt_pk_bf16_f32 v80, v84, v85
	v_pk_fma_f32 v[86:87], v[86:87], v[96:97], v[92:93]
	s_nop 0
	v_cvt_pk_bf16_f32 v81, v86, v87
	v_cvt_pk_bf16_f32 v82, v82, v83
	v_cvt_pk_bf16_f32 v83, v88, v89
	buffer_store_dwordx4 v[80:83], v104, s[24:27], 0 offen offset:256 sc1
	s_nop 1
	v_or_b32_e32 v80, 48, v162
	v_mad_i64_i32 v[82:83], s[6:7], v80, s77, 0
	v_lshl_add_u64 v[80:81], v[82:83], 1, s[38:39]
	v_lshl_add_u64 v[80:81], v[80:81], 0, v[148:149]
	v_add_co_u32_e32 v84, vcc, s78, v80
	s_nop 1
	v_addc_co_u32_e32 v85, vcc, 0, v81, vcc
	s_waitcnt vmcnt(13)
	v_mov_b32_e32 v86, v212
	v_mov_b32_e32 v87, v213
	v_mov_b32_e32 v88, v214
	v_mov_b32_e32 v89, v215
	v_mov_b32_e32 v90, v216
	v_mov_b32_e32 v91, v217
	v_mov_b32_e32 v92, v218
	v_mov_b32_e32 v93, v219
	v_add_u32_e32 v203, 0x133300, v202
	global_load_dwordx4 v[212:215], v203, s[38:39]
	v_add_u32_e32 v203, 0x132100, v202
	global_load_dwordx4 v[216:219], v203, s[38:39]
	v_lshlrev_b32_e32 v83, 16, v86
	v_lshlrev_b32_e32 v95, 16, v87
	v_and_b32_e32 v96, 0xffff0000, v87
	v_lshlrev_b32_e32 v87, 16, v88
	v_mul_f32_e32 v83, 0xbfb8aa3b, v83
	v_and_b32_e32 v94, 0xffff0000, v86
	v_exp_f32_e32 v86, v83
	v_mul_f32_e32 v83, 0xbfb8aa3b, v87
	v_and_b32_e32 v97, 0xffff0000, v88
	v_exp_f32_e32 v88, v83
	v_mul_f32_e32 v83, 0xbfb8aa3b, v94
	v_exp_f32_e32 v87, v83
	v_mul_f32_e32 v83, 0xbfb8aa3b, v97
	v_lshlrev_b32_e32 v98, 16, v89
	v_and_b32_e32 v99, 0xffff0000, v89
	v_exp_f32_e32 v89, v83
	v_mul_f32_e32 v83, 0xbfb8aa3b, v95
	v_exp_f32_e32 v94, v83
	v_mul_f32_e32 v83, 0xbfb8aa3b, v96
	v_pk_add_f32 v[86:87], v[86:87], 1.0 op_sel_hi:[1,0]
	v_exp_f32_e32 v95, v83
	v_div_scale_f32 v83, s[6:7], v87, v87, 1.0
	v_rcp_f32_e32 v97, v83
	v_mul_f32_e32 v96, 0xbfb8aa3b, v98
	v_pk_add_f32 v[94:95], v[94:95], 1.0 op_sel_hi:[1,0]
	v_pk_add_f32 v[88:89], v[88:89], 1.0 op_sel_hi:[1,0]
	v_fma_f32 v98, -v83, v97, 1.0
	v_fmac_f32_e32 v97, v98, v97
	v_div_scale_f32 v98, vcc, 1.0, v87, 1.0
	v_mul_f32_e32 v100, v98, v97
	v_fma_f32 v101, -v83, v100, v98
	v_fmac_f32_e32 v100, v101, v97
	v_fma_f32 v83, -v83, v100, v98
	v_div_scale_f32 v98, s[6:7], v86, v86, 1.0
	v_rcp_f32_e32 v101, v98
	v_div_fmas_f32 v83, v83, v97, v100
	v_div_fixup_f32 v87, v83, v87, 1.0
	v_exp_f32_e32 v96, v96
	v_fma_f32 v83, -v98, v101, 1.0
	v_fmac_f32_e32 v101, v83, v101
	v_div_scale_f32 v83, vcc, 1.0, v86, 1.0
	v_mul_f32_e32 v97, v83, v101
	v_fma_f32 v100, -v98, v97, v83
	v_fmac_f32_e32 v97, v100, v101
	v_fma_f32 v83, -v98, v97, v83
	v_div_scale_f32 v98, s[6:7], v95, v95, 1.0
	v_rcp_f32_e32 v100, v98
	v_div_fmas_f32 v83, v83, v101, v97
	v_div_fixup_f32 v86, v83, v86, 1.0
	v_fma_f32 v83, -v98, v100, 1.0
	v_fmac_f32_e32 v100, v83, v100
	v_div_scale_f32 v83, vcc, 1.0, v95, 1.0
	v_mul_f32_e32 v97, v83, v100
	v_fma_f32 v101, -v98, v97, v83
	v_fmac_f32_e32 v97, v101, v100
	v_fma_f32 v83, -v98, v97, v83
	v_div_scale_f32 v98, s[6:7], v94, v94, 1.0
	v_rcp_f32_e32 v101, v98
	v_div_fmas_f32 v83, v83, v100, v97
	v_div_fixup_f32 v95, v83, v95, 1.0
	v_fma_f32 v83, -v98, v101, 1.0
	v_fmac_f32_e32 v101, v83, v101
; __device__ __forceinline__ float sigmoidf_(float x) { return 1.0f / (1.0f + __expf(-x)); }
; __device__ __forceinline__ u32x4 pack8(const f32x4 v0, const f32x4 v1) { u32x4 w; w.x = pk2(v0[0], v0[1]); w.y = pk2(v0[2], v0[3]); w.z = pk2(v1[0], v1[1]); w.w = pk2(v1[2], v1[3]); return w; }
; __device__ __forceinline__ void unpack8(const u32x4 w, f32x4& v0, f32x4& v1) { v0 = (f32x4){bflo(w.x), bfhi(w.x), bflo(w.y), bfhi(w.y)}; v1 = (f32x4){bflo(w.z), bfhi(w.z), bflo(w.w), bfhi(w.w)}; }
;     __device__ __forceinline__ void operator()(const f32x4 (&acc)[2][2][4][2], const Unit& u, int wr, int wc, int fr, int fq) const {
;     ...
;                 for (int bj = 0; bj < 2; ++bj) {
;                     const u32x4 gw = *(const u32x4*)(rowp + O_GA + bj * 128);
;                     f32x4 g0, g1; unpack8(gw, g0, g1);
;                     f32x4 v0, v1;
; #pragma unroll
;                     for (int j = 0; j < 4; ++j) { v0[j] = sigmoidf_(g0[j]) * acc[ai][bj][m][0][j]; v1[j] = sigmoidf_(g1[j]) * acc[ai][bj][m][1][j]; }
;                     const u32x4 mw = *(const u32x4*)(rowp + bj * 128); f32x4 m0, m1; unpack8(mw, m0, m1); v0 += m0; v1 += m1;
;                     __builtin_amdgcn_raw_buffer_store_b128(pack8(v0, v1), rsrc, (unsigned)(((size_t)row * DIN + col0 + bj * 128) * 2), 0, 16  ); }
	v_div_scale_f32 v83, vcc, 1.0, v94, 1.0
	v_mul_f32_e32 v100, v83, v101
	v_fma_f32 v97, -v98, v100, v83
	v_fmac_f32_e32 v100, v97, v101
	v_fma_f32 v83, -v98, v100, v83
	v_div_scale_f32 v98, s[6:7], v89, v89, 1.0
	v_mul_f32_e32 v97, 0xbfb8aa3b, v99
	v_rcp_f32_e32 v99, v98
	v_div_fmas_f32 v83, v83, v101, v100
	v_div_fixup_f32 v94, v83, v94, 1.0
	v_exp_f32_e32 v97, v97
	v_fma_f32 v83, -v98, v99, 1.0
	v_fmac_f32_e32 v99, v83, v99
	v_div_scale_f32 v83, vcc, 1.0, v89, 1.0
	v_mul_f32_e32 v100, v83, v99
	v_fma_f32 v101, -v98, v100, v83
	v_fmac_f32_e32 v100, v101, v99
	v_fma_f32 v83, -v98, v100, v83
	v_div_scale_f32 v98, s[6:7], v88, v88, 1.0
	v_rcp_f32_e32 v101, v98
	v_div_fmas_f32 v83, v83, v99, v100
	v_div_fixup_f32 v89, v83, v89, 1.0
	v_pk_add_f32 v[96:97], v[96:97], 1.0 op_sel_hi:[1,0]
	v_fma_f32 v83, -v98, v101, 1.0
	v_fmac_f32_e32 v101, v83, v101
	v_div_scale_f32 v83, vcc, 1.0, v88, 1.0
	v_mul_f32_e32 v99, v83, v101
	v_fma_f32 v100, -v98, v99, v83
	v_fmac_f32_e32 v99, v100, v101
	v_fma_f32 v83, -v98, v99, v83
	v_div_scale_f32 v98, s[6:7], v97, v97, 1.0
	v_rcp_f32_e32 v100, v98
	v_div_fmas_f32 v83, v83, v101, v99
	v_div_fixup_f32 v88, v83, v88, 1.0
	v_fma_f32 v83, -v98, v100, 1.0
	v_fmac_f32_e32 v100, v83, v100
	v_div_scale_f32 v83, vcc, 1.0, v97, 1.0
	v_mul_f32_e32 v99, v83, v100
	v_fma_f32 v101, -v98, v99, v83
	v_fmac_f32_e32 v99, v101, v100
	v_fma_f32 v83, -v98, v99, v83
	v_div_scale_f32 v98, s[6:7], v96, v96, 1.0
	v_rcp_f32_e32 v101, v98
	v_div_fmas_f32 v83, v83, v100, v99
	v_div_fixup_f32 v97, v83, v97, 1.0
	v_fma_f32 v83, -v98, v101, 1.0
	v_fmac_f32_e32 v101, v83, v101
	v_div_scale_f32 v83, vcc, 1.0, v96, 1.0
	v_mul_f32_e32 v99, v83, v101
	v_fma_f32 v100, -v98, v99, v83
	v_fmac_f32_e32 v99, v100, v101
	v_fma_f32 v83, -v98, v99, v83
	v_div_fmas_f32 v83, v83, v101, v99
	v_div_fixup_f32 v96, v83, v96, 1.0
	v_lshlrev_b32_e32 v98, 16, v90
	v_and_b32_e32 v99, 0xffff0000, v90
	v_lshlrev_b32_e32 v100, 16, v92
	v_and_b32_e32 v101, 0xffff0000, v92
	v_lshlrev_b32_e32 v92, 16, v93
	v_and_b32_e32 v93, 0xffff0000, v93
	v_lshlrev_b32_e32 v90, 16, v91
	v_and_b32_e32 v91, 0xffff0000, v91
	v_pk_fma_f32 v[76:77], v[76:77], v[86:87], v[98:99]
	v_pk_fma_f32 v[86:87], v[74:75], v[96:97], v[92:93]
	v_pk_fma_f32 v[74:75], v[72:73], v[88:89], v[100:101]
	v_add_lshl_u32 v88, v146, v82, 1
	v_pk_fma_f32 v[78:79], v[78:79], v[94:95], v[90:91]
	v_cvt_pk_bf16_f32 v72, v76, v77
	s_nop 0
	v_cvt_pk_bf16_f32 v73, v78, v79
	v_cvt_pk_bf16_f32 v74, v74, v75
	v_cvt_pk_bf16_f32 v75, v86, v87
	buffer_store_dwordx4 v[72:75], v88, s[24:27], 0 offen sc1
	s_nop 0
	s_waitcnt vmcnt(13)
	v_mov_b32_e32 v72, v232
	v_mov_b32_e32 v73, v233
	v_mov_b32_e32 v74, v234
	v_mov_b32_e32 v75, v235
	v_mov_b32_e32 v76, v236
	v_mov_b32_e32 v77, v237
	v_mov_b32_e32 v78, v238
	v_mov_b32_e32 v79, v239
	v_add_u32_e32 v203, 0x155200, v202
	global_load_dwordx4 v[232:235], v203, s[38:39]
	v_add_u32_e32 v203, 0x154000, v202
	global_load_dwordx4 v[236:239], v203, s[38:39]
	v_lshlrev_b32_e32 v82, 16, v73
	v_and_b32_e32 v83, 0xffff0000, v73
	v_lshlrev_b32_e32 v73, 16, v74
	v_lshlrev_b32_e32 v80, 16, v72
	v_and_b32_e32 v81, 0xffff0000, v72
	v_mul_f32_e32 v73, 0xbfb8aa3b, v73
	v_and_b32_e32 v84, 0xffff0000, v74
	v_mul_f32_e32 v72, 0xbfb8aa3b, v80
	v_exp_f32_e32 v74, v73
	v_mul_f32_e32 v73, 0xbfb8aa3b, v81
	v_exp_f32_e32 v72, v72
	v_exp_f32_e32 v73, v73
	v_mul_f32_e32 v81, 0xbfb8aa3b, v83
	v_lshlrev_b32_e32 v85, 16, v75
	v_and_b32_e32 v86, 0xffff0000, v75
	v_pk_add_f32 v[72:73], v[72:73], 1.0 op_sel_hi:[1,0]
	v_mul_f32_e32 v75, 0xbfb8aa3b, v84
	v_div_scale_f32 v83, s[6:7], v73, v73, 1.0
	v_rcp_f32_e32 v84, v83
	v_mul_f32_e32 v80, 0xbfb8aa3b, v82
	v_mul_f32_e32 v82, 0xbfb8aa3b, v85
	v_exp_f32_e32 v80, v80
	v_fma_f32 v85, -v83, v84, 1.0
	v_fmac_f32_e32 v84, v85, v84
	v_div_scale_f32 v85, vcc, 1.0, v73, 1.0
	v_mul_f32_e32 v87, v85, v84
	v_fma_f32 v89, -v83, v87, v85
	v_fmac_f32_e32 v87, v89, v84
	v_fma_f32 v83, -v83, v87, v85
	v_div_scale_f32 v85, s[6:7], v72, v72, 1.0
	v_rcp_f32_e32 v89, v85
	v_div_fmas_f32 v83, v83, v84, v87
	v_exp_f32_e32 v81, v81
	v_div_fixup_f32 v73, v83, v73, 1.0
	v_fma_f32 v83, -v85, v89, 1.0
	v_fmac_f32_e32 v89, v83, v89
	v_div_scale_f32 v83, vcc, 1.0, v72, 1.0
	v_mul_f32_e32 v84, v83, v89
	v_fma_f32 v87, -v85, v84, v83
	v_pk_add_f32 v[80:81], v[80:81], 1.0 op_sel_hi:[1,0]
	v_fmac_f32_e32 v84, v87, v89
	v_fma_f32 v83, -v85, v84, v83
	v_div_scale_f32 v85, s[6:7], v81, v81, 1.0
	v_rcp_f32_e32 v87, v85
	v_div_fmas_f32 v83, v83, v89, v84
	v_div_fixup_f32 v72, v83, v72, 1.0
	v_exp_f32_e32 v75, v75
	v_fma_f32 v83, -v85, v87, 1.0
	v_fmac_f32_e32 v87, v83, v87
	v_div_scale_f32 v83, vcc, 1.0, v81, 1.0
	v_mul_f32_e32 v84, v83, v87
	v_fma_f32 v89, -v85, v84, v83
	v_fmac_f32_e32 v84, v89, v87
	v_fma_f32 v83, -v85, v84, v83
	v_div_scale_f32 v85, s[6:7], v80, v80, 1.0
	v_rcp_f32_e32 v89, v85
	v_div_fmas_f32 v83, v83, v87, v84
	v_div_fixup_f32 v81, v83, v81, 1.0
	v_pk_add_f32 v[74:75], v[74:75], 1.0 op_sel_hi:[1,0]
	v_fma_f32 v83, -v85, v89, 1.0
	v_fmac_f32_e32 v89, v83, v89
	v_div_scale_f32 v83, vcc, 1.0, v80, 1.0
	v_mul_f32_e32 v84, v83, v89
	v_fma_f32 v87, -v85, v84, v83
	v_fmac_f32_e32 v84, v87, v89
	v_fma_f32 v85, -v85, v84, v83
	v_mul_f32_e32 v83, 0xbfb8aa3b, v86
	v_div_scale_f32 v86, s[6:7], v75, v75, 1.0
	v_rcp_f32_e32 v87, v86
	v_div_fmas_f32 v84, v85, v89, v84
	v_div_fixup_f32 v80, v84, v80, 1.0
	v_exp_f32_e32 v82, v82
	v_fma_f32 v84, -v86, v87, 1.0
	v_fmac_f32_e32 v87, v84, v87
	v_div_scale_f32 v84, vcc, 1.0, v75, 1.0
	v_mul_f32_e32 v85, v84, v87
	v_fma_f32 v89, -v86, v85, v84
	v_fmac_f32_e32 v85, v89, v87
	v_fma_f32 v84, -v86, v85, v84
	v_div_scale_f32 v86, s[6:7], v74, v74, 1.0
; __device__ __forceinline__ float sigmoidf_(float x) { return 1.0f / (1.0f + __expf(-x)); }
; __device__ __forceinline__ u32x4 pack8(const f32x4 v0, const f32x4 v1) { u32x4 w; w.x = pk2(v0[0], v0[1]); w.y = pk2(v0[2], v0[3]); w.z = pk2(v1[0], v1[1]); w.w = pk2(v1[2], v1[3]); return w; }
; __device__ __forceinline__ void unpack8(const u32x4 w, f32x4& v0, f32x4& v1) { v0 = (f32x4){bflo(w.x), bfhi(w.x), bflo(w.y), bfhi(w.y)}; v1 = (f32x4){bflo(w.z), bfhi(w.z), bflo(w.w), bfhi(w.w)}; }
;     __device__ __forceinline__ void operator()(const f32x4 (&acc)[2][2][4][2], const Unit& u, int wr, int wc, int fr, int fq) const {
;     ...
;                 for (int bj = 0; bj < 2; ++bj) {
;                     const u32x4 gw = *(const u32x4*)(rowp + O_GA + bj * 128);
;                     f32x4 g0, g1; unpack8(gw, g0, g1);
;                     f32x4 v0, v1;
; #pragma unroll
;                     for (int j = 0; j < 4; ++j) { v0[j] = sigmoidf_(g0[j]) * acc[ai][bj][m][0][j]; v1[j] = sigmoidf_(g1[j]) * acc[ai][bj][m][1][j]; }
;                     const u32x4 mw = *(const u32x4*)(rowp + bj * 128); f32x4 m0, m1; unpack8(mw, m0, m1); v0 += m0; v1 += m1;
;                     __builtin_amdgcn_raw_buffer_store_b128(pack8(v0, v1), rsrc, (unsigned)(((size_t)row * DIN + col0 + bj * 128) * 2), 0, 16  ); }
	v_rcp_f32_e32 v89, v86
	v_div_fmas_f32 v84, v84, v87, v85
	v_exp_f32_e32 v83, v83
	v_div_fixup_f32 v75, v84, v75, 1.0
	v_fma_f32 v84, -v86, v89, 1.0
	v_fmac_f32_e32 v89, v84, v89
	v_div_scale_f32 v84, vcc, 1.0, v74, 1.0
	v_mul_f32_e32 v85, v84, v89
	v_fma_f32 v87, -v86, v85, v84
	v_pk_add_f32 v[82:83], v[82:83], 1.0 op_sel_hi:[1,0]
	v_fmac_f32_e32 v85, v87, v89
	v_fma_f32 v84, -v86, v85, v84
	v_div_scale_f32 v86, s[6:7], v83, v83, 1.0
	v_rcp_f32_e32 v87, v86
	v_div_fmas_f32 v84, v84, v89, v85
	v_div_fixup_f32 v74, v84, v74, 1.0
	v_fma_f32 v84, -v86, v87, 1.0
	v_fmac_f32_e32 v87, v84, v87
	v_div_scale_f32 v84, vcc, 1.0, v83, 1.0
	v_mul_f32_e32 v85, v84, v87
	v_fma_f32 v89, -v86, v85, v84
	v_fmac_f32_e32 v85, v89, v87
	v_fma_f32 v84, -v86, v85, v84
	v_div_scale_f32 v86, s[6:7], v82, v82, 1.0
	v_rcp_f32_e32 v89, v86
	v_div_fmas_f32 v84, v84, v87, v85
	v_div_fixup_f32 v83, v84, v83, 1.0
	v_fma_f32 v84, -v86, v89, 1.0
	v_fmac_f32_e32 v89, v84, v89
	v_div_scale_f32 v84, vcc, 1.0, v82, 1.0
	v_mul_f32_e32 v85, v84, v89
	v_fma_f32 v87, -v86, v85, v84
	v_fmac_f32_e32 v85, v87, v89
	v_fma_f32 v84, -v86, v85, v84
	v_div_fmas_f32 v84, v84, v89, v85
	v_div_fixup_f32 v82, v84, v82, 1.0
	v_lshlrev_b32_e32 v84, 16, v76
	v_and_b32_e32 v85, 0xffff0000, v76
	v_lshlrev_b32_e32 v86, 16, v78
	v_and_b32_e32 v87, 0xffff0000, v78
	v_lshlrev_b32_e32 v78, 16, v79
	v_and_b32_e32 v79, 0xffff0000, v79
	v_lshlrev_b32_e32 v76, 16, v77
	v_and_b32_e32 v77, 0xffff0000, v77
	v_pk_fma_f32 v[68:69], v[68:69], v[72:73], v[84:85]
	v_pk_fma_f32 v[72:73], v[66:67], v[82:83], v[78:79]
	v_pk_fma_f32 v[66:67], v[64:65], v[74:75], v[86:87]
	v_cvt_pk_bf16_f32 v64, v68, v69
	v_pk_fma_f32 v[70:71], v[70:71], v[80:81], v[76:77]
	s_nop 0
	v_cvt_pk_bf16_f32 v65, v70, v71
	v_cvt_pk_bf16_f32 v66, v66, v67
	v_cvt_pk_bf16_f32 v67, v72, v73
	buffer_store_dwordx4 v[64:67], v88, s[24:27], 0 offen offset:256 sc1
	s_nop 1
	v_add_u32_e32 v64, 0x80, v162
	v_mad_i64_i32 v[66:67], s[6:7], v64, s77, 0
	v_lshl_add_u64 v[64:65], v[66:67], 1, s[38:39]
	v_lshl_add_u64 v[64:65], v[64:65], 0, v[148:149]
	v_add_co_u32_e32 v68, vcc, s78, v64
	s_nop 1
	v_addc_co_u32_e32 v69, vcc, 0, v65, vcc
	s_waitcnt vmcnt(13)
	v_mov_b32_e32 v70, v240
	v_mov_b32_e32 v71, v241
	v_mov_b32_e32 v72, v242
	v_mov_b32_e32 v73, v243
	v_mov_b32_e32 v74, v244
	v_mov_b32_e32 v75, v245
	v_mov_b32_e32 v76, v246
	v_mov_b32_e32 v77, v247
	v_add_u32_e32 v203, 0x155300, v202
	global_load_dwordx4 v[240:243], v203, s[38:39]
	v_add_u32_e32 v203, 0x154100, v202
	global_load_dwordx4 v[244:247], v203, s[38:39]
	v_lshlrev_b32_e32 v67, 16, v70
	v_lshlrev_b32_e32 v79, 16, v71
	v_and_b32_e32 v80, 0xffff0000, v71
	v_lshlrev_b32_e32 v71, 16, v72
	v_mul_f32_e32 v67, 0xbfb8aa3b, v67
	v_and_b32_e32 v78, 0xffff0000, v70
	v_exp_f32_e32 v70, v67
	v_mul_f32_e32 v67, 0xbfb8aa3b, v71
	v_and_b32_e32 v81, 0xffff0000, v72
	v_exp_f32_e32 v72, v67
	v_mul_f32_e32 v67, 0xbfb8aa3b, v78
	v_exp_f32_e32 v71, v67
	v_mul_f32_e32 v67, 0xbfb8aa3b, v81
	v_lshlrev_b32_e32 v82, 16, v73
	v_and_b32_e32 v83, 0xffff0000, v73
	v_exp_f32_e32 v73, v67
	v_mul_f32_e32 v67, 0xbfb8aa3b, v79
	v_exp_f32_e32 v78, v67
	v_mul_f32_e32 v67, 0xbfb8aa3b, v80
	v_pk_add_f32 v[70:71], v[70:71], 1.0 op_sel_hi:[1,0]
	v_exp_f32_e32 v79, v67
	v_div_scale_f32 v67, s[6:7], v71, v71, 1.0
	v_rcp_f32_e32 v81, v67
	v_mul_f32_e32 v80, 0xbfb8aa3b, v82
	v_pk_add_f32 v[78:79], v[78:79], 1.0 op_sel_hi:[1,0]
	v_pk_add_f32 v[72:73], v[72:73], 1.0 op_sel_hi:[1,0]
	v_fma_f32 v82, -v67, v81, 1.0
	v_fmac_f32_e32 v81, v82, v81
	v_div_scale_f32 v82, vcc, 1.0, v71, 1.0
	v_mul_f32_e32 v84, v82, v81
	v_fma_f32 v85, -v67, v84, v82
	v_fmac_f32_e32 v84, v85, v81
	v_fma_f32 v67, -v67, v84, v82
	v_div_scale_f32 v82, s[6:7], v70, v70, 1.0
	v_rcp_f32_e32 v85, v82
	v_div_fmas_f32 v67, v67, v81, v84
	v_div_fixup_f32 v71, v67, v71, 1.0
	v_exp_f32_e32 v80, v80
	v_fma_f32 v67, -v82, v85, 1.0
	v_fmac_f32_e32 v85, v67, v85
	v_div_scale_f32 v67, vcc, 1.0, v70, 1.0
	v_mul_f32_e32 v81, v67, v85
	v_fma_f32 v84, -v82, v81, v67
	v_fmac_f32_e32 v81, v84, v85
	v_fma_f32 v67, -v82, v81, v67
	v_div_scale_f32 v82, s[6:7], v79, v79, 1.0
	v_rcp_f32_e32 v84, v82
	v_div_fmas_f32 v67, v67, v85, v81
	v_div_fixup_f32 v70, v67, v70, 1.0
	v_fma_f32 v67, -v82, v84, 1.0
	v_fmac_f32_e32 v84, v67, v84
	v_div_scale_f32 v67, vcc, 1.0, v79, 1.0
	v_mul_f32_e32 v81, v67, v84
	v_fma_f32 v85, -v82, v81, v67
	v_fmac_f32_e32 v81, v85, v84
	v_fma_f32 v67, -v82, v81, v67
	v_div_scale_f32 v82, s[6:7], v78, v78, 1.0
	v_rcp_f32_e32 v85, v82
	v_div_fmas_f32 v67, v67, v84, v81
	v_div_fixup_f32 v79, v67, v79, 1.0
	v_fma_f32 v67, -v82, v85, 1.0
	v_fmac_f32_e32 v85, v67, v85
	v_div_scale_f32 v67, vcc, 1.0, v78, 1.0
	v_mul_f32_e32 v84, v67, v85
	v_fma_f32 v81, -v82, v84, v67
	v_fmac_f32_e32 v84, v81, v85
	v_fma_f32 v67, -v82, v84, v67
	v_div_scale_f32 v82, s[6:7], v73, v73, 1.0
	v_mul_f32_e32 v81, 0xbfb8aa3b, v83
	v_rcp_f32_e32 v83, v82
	v_div_fmas_f32 v67, v67, v85, v84
	v_div_fixup_f32 v78, v67, v78, 1.0
	v_exp_f32_e32 v81, v81
	v_fma_f32 v67, -v82, v83, 1.0
	v_fmac_f32_e32 v83, v67, v83
	v_div_scale_f32 v67, vcc, 1.0, v73, 1.0
	v_mul_f32_e32 v84, v67, v83
	v_fma_f32 v85, -v82, v84, v67
	v_fmac_f32_e32 v84, v85, v83
	v_fma_f32 v67, -v82, v84, v67
	v_div_scale_f32 v82, s[6:7], v72, v72, 1.0
	v_rcp_f32_e32 v85, v82
	v_div_fmas_f32 v67, v67, v83, v84
	v_div_fixup_f32 v73, v67, v73, 1.0
	v_pk_add_f32 v[80:81], v[80:81], 1.0 op_sel_hi:[1,0]
	v_fma_f32 v67, -v82, v85, 1.0
	v_fmac_f32_e32 v85, v67, v85
	v_div_scale_f32 v67, vcc, 1.0, v72, 1.0
	v_mul_f32_e32 v83, v67, v85
	v_fma_f32 v84, -v82, v83, v67
	v_fmac_f32_e32 v83, v84, v85
	v_fma_f32 v67, -v82, v83, v67
	v_div_scale_f32 v82, s[6:7], v81, v81, 1.0
; __device__ __forceinline__ float sigmoidf_(float x) { return 1.0f / (1.0f + __expf(-x)); }
; __device__ __forceinline__ u32x4 pack8(const f32x4 v0, const f32x4 v1) { u32x4 w; w.x = pk2(v0[0], v0[1]); w.y = pk2(v0[2], v0[3]); w.z = pk2(v1[0], v1[1]); w.w = pk2(v1[2], v1[3]); return w; }
; __device__ __forceinline__ void unpack8(const u32x4 w, f32x4& v0, f32x4& v1) { v0 = (f32x4){bflo(w.x), bfhi(w.x), bflo(w.y), bfhi(w.y)}; v1 = (f32x4){bflo(w.z), bfhi(w.z), bflo(w.w), bfhi(w.w)}; }
;     __device__ __forceinline__ void operator()(const f32x4 (&acc)[2][2][4][2], const Unit& u, int wr, int wc, int fr, int fq) const {
;     ...
;                 for (int bj = 0; bj < 2; ++bj) {
;                     const u32x4 gw = *(const u32x4*)(rowp + O_GA + bj * 128);
;                     f32x4 g0, g1; unpack8(gw, g0, g1);
;                     f32x4 v0, v1;
; #pragma unroll
;                     for (int j = 0; j < 4; ++j) { v0[j] = sigmoidf_(g0[j]) * acc[ai][bj][m][0][j]; v1[j] = sigmoidf_(g1[j]) * acc[ai][bj][m][1][j]; }
;                     const u32x4 mw = *(const u32x4*)(rowp + bj * 128); f32x4 m0, m1; unpack8(mw, m0, m1); v0 += m0; v1 += m1;
;                     __builtin_amdgcn_raw_buffer_store_b128(pack8(v0, v1), rsrc, (unsigned)(((size_t)row * DIN + col0 + bj * 128) * 2), 0, 16  ); }
	v_rcp_f32_e32 v84, v82
	v_div_fmas_f32 v67, v67, v85, v83
	v_div_fixup_f32 v72, v67, v72, 1.0
	v_fma_f32 v67, -v82, v84, 1.0
	v_fmac_f32_e32 v84, v67, v84
	v_div_scale_f32 v67, vcc, 1.0, v81, 1.0
	v_mul_f32_e32 v83, v67, v84
	v_fma_f32 v85, -v82, v83, v67
	v_fmac_f32_e32 v83, v85, v84
	v_fma_f32 v67, -v82, v83, v67
	v_div_scale_f32 v82, s[6:7], v80, v80, 1.0
	v_rcp_f32_e32 v85, v82
	v_div_fmas_f32 v67, v67, v84, v83
	v_div_fixup_f32 v81, v67, v81, 1.0
	v_fma_f32 v67, -v82, v85, 1.0
	v_fmac_f32_e32 v85, v67, v85
	v_div_scale_f32 v67, vcc, 1.0, v80, 1.0
	v_mul_f32_e32 v83, v67, v85
	v_fma_f32 v84, -v82, v83, v67
	v_fmac_f32_e32 v83, v84, v85
	v_fma_f32 v67, -v82, v83, v67
	v_div_fmas_f32 v67, v67, v85, v83
	v_div_fixup_f32 v80, v67, v80, 1.0
	v_lshlrev_b32_e32 v82, 16, v74
	v_and_b32_e32 v83, 0xffff0000, v74
	v_lshlrev_b32_e32 v84, 16, v76
	v_and_b32_e32 v85, 0xffff0000, v76
	v_lshlrev_b32_e32 v76, 16, v77
	v_and_b32_e32 v77, 0xffff0000, v77
	v_lshlrev_b32_e32 v74, 16, v75
	v_and_b32_e32 v75, 0xffff0000, v75
	v_pk_fma_f32 v[60:61], v[60:61], v[70:71], v[82:83]
	v_pk_fma_f32 v[70:71], v[58:59], v[80:81], v[76:77]
	v_pk_fma_f32 v[58:59], v[56:57], v[72:73], v[84:85]
	v_add_lshl_u32 v72, v146, v66, 1
	v_pk_fma_f32 v[62:63], v[62:63], v[78:79], v[74:75]
	v_cvt_pk_bf16_f32 v56, v60, v61
	s_nop 0
	v_cvt_pk_bf16_f32 v57, v62, v63
	v_cvt_pk_bf16_f32 v58, v58, v59
	v_cvt_pk_bf16_f32 v59, v70, v71
	buffer_store_dwordx4 v[56:59], v72, s[24:27], 0 offen sc1
	s_nop 0
	s_waitcnt vmcnt(13)
	v_mov_b32_e32 v56, v248
	v_mov_b32_e32 v57, v249
	v_mov_b32_e32 v58, v250
	v_mov_b32_e32 v59, v251
	v_mov_b32_e32 v60, v252
	v_mov_b32_e32 v61, v253
	v_mov_b32_e32 v62, v254
	v_mov_b32_e32 v63, v255
	v_add_u32_e32 v203, 0x177200, v202
	global_load_dwordx4 v[248:251], v203, s[38:39]
	v_add_u32_e32 v203, 0x176000, v202
	global_load_dwordx4 v[252:255], v203, s[38:39]
	v_lshlrev_b32_e32 v66, 16, v57
	v_and_b32_e32 v67, 0xffff0000, v57
	v_lshlrev_b32_e32 v57, 16, v58
	v_lshlrev_b32_e32 v64, 16, v56
	v_and_b32_e32 v65, 0xffff0000, v56
	v_mul_f32_e32 v57, 0xbfb8aa3b, v57
	v_and_b32_e32 v68, 0xffff0000, v58
	v_mul_f32_e32 v56, 0xbfb8aa3b, v64
	v_exp_f32_e32 v58, v57
	v_mul_f32_e32 v57, 0xbfb8aa3b, v65
	v_exp_f32_e32 v56, v56
	v_exp_f32_e32 v57, v57
	v_mul_f32_e32 v65, 0xbfb8aa3b, v67
	v_lshlrev_b32_e32 v69, 16, v59
	v_and_b32_e32 v70, 0xffff0000, v59
	v_pk_add_f32 v[56:57], v[56:57], 1.0 op_sel_hi:[1,0]
	v_mul_f32_e32 v59, 0xbfb8aa3b, v68
	v_div_scale_f32 v67, s[6:7], v57, v57, 1.0
	v_rcp_f32_e32 v68, v67
	v_mul_f32_e32 v64, 0xbfb8aa3b, v66
	v_mul_f32_e32 v66, 0xbfb8aa3b, v69
	v_exp_f32_e32 v64, v64
	v_fma_f32 v69, -v67, v68, 1.0
	v_fmac_f32_e32 v68, v69, v68
	v_div_scale_f32 v69, vcc, 1.0, v57, 1.0
	v_mul_f32_e32 v71, v69, v68
	v_fma_f32 v73, -v67, v71, v69
	v_fmac_f32_e32 v71, v73, v68
	v_fma_f32 v67, -v67, v71, v69
	v_div_scale_f32 v69, s[6:7], v56, v56, 1.0
	v_rcp_f32_e32 v73, v69
	v_div_fmas_f32 v67, v67, v68, v71
	v_exp_f32_e32 v65, v65
	v_div_fixup_f32 v57, v67, v57, 1.0
	v_fma_f32 v67, -v69, v73, 1.0
	v_fmac_f32_e32 v73, v67, v73
	v_div_scale_f32 v67, vcc, 1.0, v56, 1.0
	v_mul_f32_e32 v68, v67, v73
	v_fma_f32 v71, -v69, v68, v67
	v_pk_add_f32 v[64:65], v[64:65], 1.0 op_sel_hi:[1,0]
	v_fmac_f32_e32 v68, v71, v73
	v_fma_f32 v67, -v69, v68, v67
	v_div_scale_f32 v69, s[6:7], v65, v65, 1.0
	v_rcp_f32_e32 v71, v69
	v_div_fmas_f32 v67, v67, v73, v68
	v_div_fixup_f32 v56, v67, v56, 1.0
	v_exp_f32_e32 v59, v59
	v_fma_f32 v67, -v69, v71, 1.0
	v_fmac_f32_e32 v71, v67, v71
	v_div_scale_f32 v67, vcc, 1.0, v65, 1.0
	v_mul_f32_e32 v68, v67, v71
	v_fma_f32 v73, -v69, v68, v67
	v_fmac_f32_e32 v68, v73, v71
	v_fma_f32 v67, -v69, v68, v67
	v_div_scale_f32 v69, s[6:7], v64, v64, 1.0
	v_rcp_f32_e32 v73, v69
	v_div_fmas_f32 v67, v67, v71, v68
	v_div_fixup_f32 v65, v67, v65, 1.0
	v_pk_add_f32 v[58:59], v[58:59], 1.0 op_sel_hi:[1,0]
	v_fma_f32 v67, -v69, v73, 1.0
	v_fmac_f32_e32 v73, v67, v73
	v_div_scale_f32 v67, vcc, 1.0, v64, 1.0
	v_mul_f32_e32 v68, v67, v73
	v_fma_f32 v71, -v69, v68, v67
	v_fmac_f32_e32 v68, v71, v73
	v_fma_f32 v69, -v69, v68, v67
	v_mul_f32_e32 v67, 0xbfb8aa3b, v70
	v_div_scale_f32 v70, s[6:7], v59, v59, 1.0
	v_rcp_f32_e32 v71, v70
	v_div_fmas_f32 v68, v69, v73, v68
	v_div_fixup_f32 v64, v68, v64, 1.0
	v_exp_f32_e32 v66, v66
	v_fma_f32 v68, -v70, v71, 1.0
	v_fmac_f32_e32 v71, v68, v71
	v_div_scale_f32 v68, vcc, 1.0, v59, 1.0
	v_mul_f32_e32 v69, v68, v71
	v_fma_f32 v73, -v70, v69, v68
	v_fmac_f32_e32 v69, v73, v71
	v_fma_f32 v68, -v70, v69, v68
	v_div_scale_f32 v70, s[6:7], v58, v58, 1.0
	v_rcp_f32_e32 v73, v70
	v_div_fmas_f32 v68, v68, v71, v69
	v_exp_f32_e32 v67, v67
	v_div_fixup_f32 v59, v68, v59, 1.0
	v_fma_f32 v68, -v70, v73, 1.0
	v_fmac_f32_e32 v73, v68, v73
	v_div_scale_f32 v68, vcc, 1.0, v58, 1.0
	v_mul_f32_e32 v69, v68, v73
	v_fma_f32 v71, -v70, v69, v68
	v_pk_add_f32 v[66:67], v[66:67], 1.0 op_sel_hi:[1,0]
	v_fmac_f32_e32 v69, v71, v73
	v_fma_f32 v68, -v70, v69, v68
	v_div_scale_f32 v70, s[6:7], v67, v67, 1.0
	v_rcp_f32_e32 v71, v70
	v_div_fmas_f32 v68, v68, v73, v69
	v_div_fixup_f32 v58, v68, v58, 1.0
	v_fma_f32 v68, -v70, v71, 1.0
	v_fmac_f32_e32 v71, v68, v71
	v_div_scale_f32 v68, vcc, 1.0, v67, 1.0
	v_mul_f32_e32 v69, v68, v71
	v_fma_f32 v73, -v70, v69, v68
	v_fmac_f32_e32 v69, v73, v71
	v_fma_f32 v68, -v70, v69, v68
	v_div_scale_f32 v70, s[6:7], v66, v66, 1.0
	v_rcp_f32_e32 v73, v70
	v_div_fmas_f32 v68, v68, v71, v69
	v_div_fixup_f32 v67, v68, v67, 1.0
	v_fma_f32 v68, -v70, v73, 1.0
	v_fmac_f32_e32 v73, v68, v73
	v_div_scale_f32 v68, vcc, 1.0, v66, 1.0
	v_mul_f32_e32 v69, v68, v73
	v_fma_f32 v71, -v70, v69, v68
	v_fmac_f32_e32 v69, v71, v73
	v_fma_f32 v68, -v70, v69, v68
	v_div_fmas_f32 v68, v68, v73, v69
	v_div_fixup_f32 v66, v68, v66, 1.0
	v_lshlrev_b32_e32 v68, 16, v60
	v_and_b32_e32 v69, 0xffff0000, v60
	v_lshlrev_b32_e32 v70, 16, v62
	v_and_b32_e32 v71, 0xffff0000, v62
	v_lshlrev_b32_e32 v62, 16, v63
	v_and_b32_e32 v63, 0xffff0000, v63
	v_lshlrev_b32_e32 v60, 16, v61
	v_and_b32_e32 v61, 0xffff0000, v61
	v_pk_fma_f32 v[52:53], v[52:53], v[56:57], v[68:69]
	v_pk_fma_f32 v[56:57], v[50:51], v[66:67], v[62:63]
	v_pk_fma_f32 v[50:51], v[48:49], v[58:59], v[70:71]
	v_cvt_pk_bf16_f32 v48, v52, v53
	v_pk_fma_f32 v[54:55], v[54:55], v[64:65], v[60:61]
	s_nop 0
	v_cvt_pk_bf16_f32 v49, v54, v55
	v_cvt_pk_bf16_f32 v50, v50, v51
	v_cvt_pk_bf16_f32 v51, v56, v57
	buffer_store_dwordx4 v[48:51], v72, s[24:27], 0 offen offset:256 sc1
	s_nop 1
	v_add_u32_e32 v48, 0x90, v162
	v_mad_i64_i32 v[50:51], s[6:7], v48, s77, 0
	v_lshl_add_u64 v[48:49], v[50:51], 1, s[38:39]
	v_lshl_add_u64 v[48:49], v[48:49], 0, v[148:149]
	v_add_co_u32_e32 v52, vcc, s78, v48
	s_nop 1
	v_addc_co_u32_e32 v53, vcc, 0, v49, vcc
	s_waitcnt vmcnt(13)
; __device__ __forceinline__ float sigmoidf_(float x) { return 1.0f / (1.0f + __expf(-x)); }
; __device__ __forceinline__ u32x4 pack8(const f32x4 v0, const f32x4 v1) { u32x4 w; w.x = pk2(v0[0], v0[1]); w.y = pk2(v0[2], v0[3]); w.z = pk2(v1[0], v1[1]); w.w = pk2(v1[2], v1[3]); return w; }
; __device__ __forceinline__ void unpack8(const u32x4 w, f32x4& v0, f32x4& v1) { v0 = (f32x4){bflo(w.x), bfhi(w.x), bflo(w.y), bfhi(w.y)}; v1 = (f32x4){bflo(w.z), bfhi(w.z), bflo(w.w), bfhi(w.w)}; }
;     __device__ __forceinline__ void operator()(const f32x4 (&acc)[2][2][4][2], const Unit& u, int wr, int wc, int fr, int fq) const {
;     ...
;                 for (int bj = 0; bj < 2; ++bj) {
;                     const u32x4 gw = *(const u32x4*)(rowp + O_GA + bj * 128);
;                     f32x4 g0, g1; unpack8(gw, g0, g1);
;                     f32x4 v0, v1;
; #pragma unroll
;                     for (int j = 0; j < 4; ++j) { v0[j] = sigmoidf_(g0[j]) * acc[ai][bj][m][0][j]; v1[j] = sigmoidf_(g1[j]) * acc[ai][bj][m][1][j]; }
;                     const u32x4 mw = *(const u32x4*)(rowp + bj * 128); f32x4 m0, m1; unpack8(mw, m0, m1); v0 += m0; v1 += m1;
;                     __builtin_amdgcn_raw_buffer_store_b128(pack8(v0, v1), rsrc, (unsigned)(((size_t)row * DIN + col0 + bj * 128) * 2), 0, 16  ); }
	v_mov_b32_e32 v54, v204
	v_mov_b32_e32 v55, v205
	v_mov_b32_e32 v56, v206
	v_mov_b32_e32 v57, v207
	v_mov_b32_e32 v58, v208
	v_mov_b32_e32 v59, v209
	v_mov_b32_e32 v60, v210
	v_mov_b32_e32 v61, v211
	v_add_u32_e32 v203, 0x177300, v202
	global_load_dwordx4 v[204:207], v203, s[38:39]
	v_add_u32_e32 v203, 0x176100, v202
	global_load_dwordx4 v[208:211], v203, s[38:39]
	v_lshlrev_b32_e32 v51, 16, v54
	v_lshlrev_b32_e32 v63, 16, v55
	v_and_b32_e32 v64, 0xffff0000, v55
	v_lshlrev_b32_e32 v55, 16, v56
	v_mul_f32_e32 v51, 0xbfb8aa3b, v51
	v_and_b32_e32 v62, 0xffff0000, v54
	v_exp_f32_e32 v54, v51
	v_mul_f32_e32 v51, 0xbfb8aa3b, v55
	v_and_b32_e32 v65, 0xffff0000, v56
	v_exp_f32_e32 v56, v51
	v_mul_f32_e32 v51, 0xbfb8aa3b, v62
	v_exp_f32_e32 v55, v51
	v_mul_f32_e32 v51, 0xbfb8aa3b, v65
	v_lshlrev_b32_e32 v66, 16, v57
	v_and_b32_e32 v67, 0xffff0000, v57
	v_exp_f32_e32 v57, v51
	v_mul_f32_e32 v51, 0xbfb8aa3b, v63
	v_exp_f32_e32 v62, v51
	v_mul_f32_e32 v51, 0xbfb8aa3b, v64
	v_pk_add_f32 v[54:55], v[54:55], 1.0 op_sel_hi:[1,0]
	v_exp_f32_e32 v63, v51
	v_div_scale_f32 v51, s[6:7], v55, v55, 1.0
	v_rcp_f32_e32 v65, v51
	v_mul_f32_e32 v64, 0xbfb8aa3b, v66
	v_pk_add_f32 v[62:63], v[62:63], 1.0 op_sel_hi:[1,0]
	v_pk_add_f32 v[56:57], v[56:57], 1.0 op_sel_hi:[1,0]
	v_fma_f32 v66, -v51, v65, 1.0
	v_fmac_f32_e32 v65, v66, v65
	v_div_scale_f32 v66, vcc, 1.0, v55, 1.0
	v_mul_f32_e32 v68, v66, v65
	v_fma_f32 v69, -v51, v68, v66
	v_fmac_f32_e32 v68, v69, v65
	v_fma_f32 v51, -v51, v68, v66
	v_div_scale_f32 v66, s[6:7], v54, v54, 1.0
	v_rcp_f32_e32 v69, v66
	v_div_fmas_f32 v51, v51, v65, v68
	v_div_fixup_f32 v55, v51, v55, 1.0
	v_exp_f32_e32 v64, v64
	v_fma_f32 v51, -v66, v69, 1.0
	v_fmac_f32_e32 v69, v51, v69
	v_div_scale_f32 v51, vcc, 1.0, v54, 1.0
	v_mul_f32_e32 v65, v51, v69
	v_fma_f32 v68, -v66, v65, v51
	v_fmac_f32_e32 v65, v68, v69
	v_fma_f32 v51, -v66, v65, v51
	v_div_scale_f32 v66, s[6:7], v63, v63, 1.0
	v_rcp_f32_e32 v68, v66
	v_div_fmas_f32 v51, v51, v69, v65
	v_div_fixup_f32 v54, v51, v54, 1.0
	v_fma_f32 v51, -v66, v68, 1.0
	v_fmac_f32_e32 v68, v51, v68
	v_div_scale_f32 v51, vcc, 1.0, v63, 1.0
	v_mul_f32_e32 v65, v51, v68
	v_fma_f32 v69, -v66, v65, v51
	v_fmac_f32_e32 v65, v69, v68
	v_fma_f32 v51, -v66, v65, v51
	v_div_scale_f32 v66, s[6:7], v62, v62, 1.0
	v_rcp_f32_e32 v69, v66
	v_div_fmas_f32 v51, v51, v68, v65
	v_div_fixup_f32 v63, v51, v63, 1.0
	v_fma_f32 v51, -v66, v69, 1.0
	v_fmac_f32_e32 v69, v51, v69
	v_div_scale_f32 v51, vcc, 1.0, v62, 1.0
	v_mul_f32_e32 v68, v51, v69
	v_fma_f32 v65, -v66, v68, v51
	v_fmac_f32_e32 v68, v65, v69
	v_fma_f32 v51, -v66, v68, v51
	v_div_scale_f32 v66, s[6:7], v57, v57, 1.0
	v_mul_f32_e32 v65, 0xbfb8aa3b, v67
	v_rcp_f32_e32 v67, v66
	v_div_fmas_f32 v51, v51, v69, v68
	v_div_fixup_f32 v62, v51, v62, 1.0
	v_exp_f32_e32 v65, v65
	v_fma_f32 v51, -v66, v67, 1.0
	v_fmac_f32_e32 v67, v51, v67
	v_div_scale_f32 v51, vcc, 1.0, v57, 1.0
	v_mul_f32_e32 v68, v51, v67
	v_fma_f32 v69, -v66, v68, v51
	v_fmac_f32_e32 v68, v69, v67
	v_fma_f32 v51, -v66, v68, v51
	v_div_scale_f32 v66, s[6:7], v56, v56, 1.0
	v_rcp_f32_e32 v69, v66
	v_div_fmas_f32 v51, v51, v67, v68
	v_div_fixup_f32 v57, v51, v57, 1.0
	v_pk_add_f32 v[64:65], v[64:65], 1.0 op_sel_hi:[1,0]
	v_fma_f32 v51, -v66, v69, 1.0
	v_fmac_f32_e32 v69, v51, v69
	v_div_scale_f32 v51, vcc, 1.0, v56, 1.0
	v_mul_f32_e32 v67, v51, v69
	v_fma_f32 v68, -v66, v67, v51
	v_fmac_f32_e32 v67, v68, v69
	v_fma_f32 v51, -v66, v67, v51
	v_div_scale_f32 v66, s[6:7], v65, v65, 1.0
	v_rcp_f32_e32 v68, v66
	v_div_fmas_f32 v51, v51, v69, v67
	v_div_fixup_f32 v56, v51, v56, 1.0
	v_fma_f32 v51, -v66, v68, 1.0
	v_fmac_f32_e32 v68, v51, v68
	v_div_scale_f32 v51, vcc, 1.0, v65, 1.0
	v_mul_f32_e32 v67, v51, v68
	v_fma_f32 v69, -v66, v67, v51
	v_fmac_f32_e32 v67, v69, v68
	v_fma_f32 v51, -v66, v67, v51
	v_div_scale_f32 v66, s[6:7], v64, v64, 1.0
	v_rcp_f32_e32 v69, v66
	v_div_fmas_f32 v51, v51, v68, v67
	v_div_fixup_f32 v65, v51, v65, 1.0
	v_fma_f32 v51, -v66, v69, 1.0
	v_fmac_f32_e32 v69, v51, v69
	v_div_scale_f32 v51, vcc, 1.0, v64, 1.0
	v_mul_f32_e32 v67, v51, v69
	v_fma_f32 v68, -v66, v67, v51
	v_fmac_f32_e32 v67, v68, v69
	v_fma_f32 v51, -v66, v67, v51
	v_div_fmas_f32 v51, v51, v69, v67
	v_div_fixup_f32 v64, v51, v64, 1.0
	v_lshlrev_b32_e32 v66, 16, v58
	v_and_b32_e32 v67, 0xffff0000, v58
	v_lshlrev_b32_e32 v68, 16, v60
	v_and_b32_e32 v69, 0xffff0000, v60
	v_lshlrev_b32_e32 v60, 16, v61
	v_and_b32_e32 v61, 0xffff0000, v61
	v_lshlrev_b32_e32 v58, 16, v59
	v_and_b32_e32 v59, 0xffff0000, v59
	v_pk_fma_f32 v[44:45], v[44:45], v[54:55], v[66:67]
	v_pk_fma_f32 v[54:55], v[42:43], v[64:65], v[60:61]
	v_pk_fma_f32 v[42:43], v[40:41], v[56:57], v[68:69]
	v_add_lshl_u32 v56, v146, v50, 1
	v_pk_fma_f32 v[46:47], v[46:47], v[62:63], v[58:59]
	v_cvt_pk_bf16_f32 v40, v44, v45
	s_nop 0
	v_cvt_pk_bf16_f32 v41, v46, v47
	v_cvt_pk_bf16_f32 v42, v42, v43
	v_cvt_pk_bf16_f32 v43, v54, v55
	buffer_store_dwordx4 v[40:43], v56, s[24:27], 0 offen sc1
	s_nop 0
	s_waitcnt vmcnt(13)
; __device__ __forceinline__ float sigmoidf_(float x) { return 1.0f / (1.0f + __expf(-x)); }
; __device__ __forceinline__ u32x4 pack8(const f32x4 v0, const f32x4 v1) { u32x4 w; w.x = pk2(v0[0], v0[1]); w.y = pk2(v0[2], v0[3]); w.z = pk2(v1[0], v1[1]); w.w = pk2(v1[2], v1[3]); return w; }
; __device__ __forceinline__ void unpack8(const u32x4 w, f32x4& v0, f32x4& v1) { v0 = (f32x4){bflo(w.x), bfhi(w.x), bflo(w.y), bfhi(w.y)}; v1 = (f32x4){bflo(w.z), bfhi(w.z), bflo(w.w), bfhi(w.w)}; }
;     __device__ __forceinline__ void operator()(const f32x4 (&acc)[2][2][4][2], const Unit& u, int wr, int wc, int fr, int fq) const {
;     ...
;                 for (int bj = 0; bj < 2; ++bj) {
;                     const u32x4 gw = *(const u32x4*)(rowp + O_GA + bj * 128);
;                     f32x4 g0, g1; unpack8(gw, g0, g1);
;                     f32x4 v0, v1;
; #pragma unroll
;                     for (int j = 0; j < 4; ++j) { v0[j] = sigmoidf_(g0[j]) * acc[ai][bj][m][0][j]; v1[j] = sigmoidf_(g1[j]) * acc[ai][bj][m][1][j]; }
;                     const u32x4 mw = *(const u32x4*)(rowp + bj * 128); f32x4 m0, m1; unpack8(mw, m0, m1); v0 += m0; v1 += m1;
;                     __builtin_amdgcn_raw_buffer_store_b128(pack8(v0, v1), rsrc, (unsigned)(((size_t)row * DIN + col0 + bj * 128) * 2), 0, 16  ); }
	v_mov_b32_e32 v40, v212
	v_mov_b32_e32 v41, v213
	v_mov_b32_e32 v42, v214
	v_mov_b32_e32 v43, v215
	v_mov_b32_e32 v44, v216
	v_mov_b32_e32 v45, v217
	v_mov_b32_e32 v46, v218
	v_mov_b32_e32 v47, v219
	v_lshlrev_b32_e32 v50, 16, v41
	v_and_b32_e32 v51, 0xffff0000, v41
	v_lshlrev_b32_e32 v41, 16, v42
	v_lshlrev_b32_e32 v48, 16, v40
	v_and_b32_e32 v49, 0xffff0000, v40
	v_mul_f32_e32 v41, 0xbfb8aa3b, v41
	v_and_b32_e32 v52, 0xffff0000, v42
	v_mul_f32_e32 v40, 0xbfb8aa3b, v48
	v_exp_f32_e32 v42, v41
	v_mul_f32_e32 v41, 0xbfb8aa3b, v49
	v_exp_f32_e32 v40, v40
	v_exp_f32_e32 v41, v41
	v_mul_f32_e32 v49, 0xbfb8aa3b, v51
	v_lshlrev_b32_e32 v53, 16, v43
	v_and_b32_e32 v54, 0xffff0000, v43
	v_pk_add_f32 v[40:41], v[40:41], 1.0 op_sel_hi:[1,0]
	v_mul_f32_e32 v43, 0xbfb8aa3b, v52
	v_div_scale_f32 v51, s[6:7], v41, v41, 1.0
	v_rcp_f32_e32 v52, v51
	v_mul_f32_e32 v48, 0xbfb8aa3b, v50
	v_mul_f32_e32 v50, 0xbfb8aa3b, v53
	v_exp_f32_e32 v48, v48
	v_fma_f32 v53, -v51, v52, 1.0
	v_fmac_f32_e32 v52, v53, v52
	v_div_scale_f32 v53, vcc, 1.0, v41, 1.0
	v_mul_f32_e32 v55, v53, v52
	v_fma_f32 v57, -v51, v55, v53
	v_fmac_f32_e32 v55, v57, v52
	v_fma_f32 v51, -v51, v55, v53
	v_div_scale_f32 v53, s[6:7], v40, v40, 1.0
	v_rcp_f32_e32 v57, v53
	v_div_fmas_f32 v51, v51, v52, v55
	v_exp_f32_e32 v49, v49
	v_div_fixup_f32 v41, v51, v41, 1.0
	v_fma_f32 v51, -v53, v57, 1.0
	v_fmac_f32_e32 v57, v51, v57
	v_div_scale_f32 v51, vcc, 1.0, v40, 1.0
	v_mul_f32_e32 v52, v51, v57
	v_fma_f32 v55, -v53, v52, v51
	v_pk_add_f32 v[48:49], v[48:49], 1.0 op_sel_hi:[1,0]
	v_fmac_f32_e32 v52, v55, v57
	v_fma_f32 v51, -v53, v52, v51
	v_div_scale_f32 v53, s[6:7], v49, v49, 1.0
	v_rcp_f32_e32 v55, v53
	v_div_fmas_f32 v51, v51, v57, v52
	v_div_fixup_f32 v40, v51, v40, 1.0
	v_exp_f32_e32 v43, v43
	v_fma_f32 v51, -v53, v55, 1.0
	v_fmac_f32_e32 v55, v51, v55
	v_div_scale_f32 v51, vcc, 1.0, v49, 1.0
	v_mul_f32_e32 v52, v51, v55
	v_fma_f32 v57, -v53, v52, v51
	v_fmac_f32_e32 v52, v57, v55
	v_fma_f32 v51, -v53, v52, v51
	v_div_scale_f32 v53, s[6:7], v48, v48, 1.0
	v_rcp_f32_e32 v57, v53
	v_div_fmas_f32 v51, v51, v55, v52
	v_div_fixup_f32 v49, v51, v49, 1.0
	v_pk_add_f32 v[42:43], v[42:43], 1.0 op_sel_hi:[1,0]
	v_fma_f32 v51, -v53, v57, 1.0
	v_fmac_f32_e32 v57, v51, v57
	v_div_scale_f32 v51, vcc, 1.0, v48, 1.0
	v_mul_f32_e32 v52, v51, v57
	v_fma_f32 v55, -v53, v52, v51
	v_fmac_f32_e32 v52, v55, v57
	v_fma_f32 v53, -v53, v52, v51
	v_mul_f32_e32 v51, 0xbfb8aa3b, v54
	v_div_scale_f32 v54, s[6:7], v43, v43, 1.0
	v_rcp_f32_e32 v55, v54
	v_div_fmas_f32 v52, v53, v57, v52
	v_div_fixup_f32 v48, v52, v48, 1.0
	v_exp_f32_e32 v50, v50
	v_fma_f32 v52, -v54, v55, 1.0
	v_fmac_f32_e32 v55, v52, v55
	v_div_scale_f32 v52, vcc, 1.0, v43, 1.0
	v_mul_f32_e32 v53, v52, v55
	v_fma_f32 v57, -v54, v53, v52
	v_fmac_f32_e32 v53, v57, v55
	v_fma_f32 v52, -v54, v53, v52
	v_div_scale_f32 v54, s[6:7], v42, v42, 1.0
	v_rcp_f32_e32 v57, v54
	v_div_fmas_f32 v52, v52, v55, v53
	v_exp_f32_e32 v51, v51
	v_div_fixup_f32 v43, v52, v43, 1.0
	v_fma_f32 v52, -v54, v57, 1.0
	v_fmac_f32_e32 v57, v52, v57
	v_div_scale_f32 v52, vcc, 1.0, v42, 1.0
	v_mul_f32_e32 v53, v52, v57
	v_fma_f32 v55, -v54, v53, v52
	v_pk_add_f32 v[50:51], v[50:51], 1.0 op_sel_hi:[1,0]
	v_fmac_f32_e32 v53, v55, v57
	v_fma_f32 v52, -v54, v53, v52
	v_div_scale_f32 v54, s[6:7], v51, v51, 1.0
	v_rcp_f32_e32 v55, v54
	v_div_fmas_f32 v52, v52, v57, v53
	v_div_fixup_f32 v42, v52, v42, 1.0
	v_fma_f32 v52, -v54, v55, 1.0
	v_fmac_f32_e32 v55, v52, v55
	v_div_scale_f32 v52, vcc, 1.0, v51, 1.0
	v_mul_f32_e32 v53, v52, v55
	v_fma_f32 v57, -v54, v53, v52
	v_fmac_f32_e32 v53, v57, v55
	v_fma_f32 v52, -v54, v53, v52
	v_div_scale_f32 v54, s[6:7], v50, v50, 1.0
	v_rcp_f32_e32 v57, v54
	v_div_fmas_f32 v52, v52, v55, v53
	v_div_fixup_f32 v51, v52, v51, 1.0
	v_fma_f32 v52, -v54, v57, 1.0
	v_fmac_f32_e32 v57, v52, v57
	v_div_scale_f32 v52, vcc, 1.0, v50, 1.0
	v_mul_f32_e32 v53, v52, v57
	v_fma_f32 v55, -v54, v53, v52
	v_fmac_f32_e32 v53, v55, v57
	v_fma_f32 v52, -v54, v53, v52
	v_div_fmas_f32 v52, v52, v57, v53
	v_div_fixup_f32 v50, v52, v50, 1.0
	v_lshlrev_b32_e32 v52, 16, v44
	v_and_b32_e32 v53, 0xffff0000, v44
	v_lshlrev_b32_e32 v54, 16, v46
	v_and_b32_e32 v55, 0xffff0000, v46
	v_lshlrev_b32_e32 v46, 16, v47
	v_and_b32_e32 v47, 0xffff0000, v47
	v_lshlrev_b32_e32 v44, 16, v45
	v_and_b32_e32 v45, 0xffff0000, v45
	v_pk_fma_f32 v[36:37], v[36:37], v[40:41], v[52:53]
	v_pk_fma_f32 v[40:41], v[34:35], v[50:51], v[46:47]
	v_pk_fma_f32 v[34:35], v[32:33], v[42:43], v[54:55]
	v_cvt_pk_bf16_f32 v32, v36, v37
	v_pk_fma_f32 v[38:39], v[38:39], v[48:49], v[44:45]
	s_nop 0
	v_cvt_pk_bf16_f32 v33, v38, v39
	v_cvt_pk_bf16_f32 v34, v34, v35
	v_cvt_pk_bf16_f32 v35, v40, v41
	buffer_store_dwordx4 v[32:35], v56, s[24:27], 0 offen offset:256 sc1
	s_nop 1
	v_add_u32_e32 v32, 0xa0, v162
	v_mad_i64_i32 v[34:35], s[6:7], v32, s77, 0
	v_lshl_add_u64 v[32:33], v[34:35], 1, s[38:39]
	v_lshl_add_u64 v[32:33], v[32:33], 0, v[148:149]
	v_add_co_u32_e32 v36, vcc, s78, v32
	s_nop 1
	v_addc_co_u32_e32 v37, vcc, 0, v33, vcc
	s_waitcnt vmcnt(11)
; __device__ __forceinline__ float sigmoidf_(float x) { return 1.0f / (1.0f + __expf(-x)); }
; __device__ __forceinline__ u32x4 pack8(const f32x4 v0, const f32x4 v1) { u32x4 w; w.x = pk2(v0[0], v0[1]); w.y = pk2(v0[2], v0[3]); w.z = pk2(v1[0], v1[1]); w.w = pk2(v1[2], v1[3]); return w; }
; __device__ __forceinline__ void unpack8(const u32x4 w, f32x4& v0, f32x4& v1) { v0 = (f32x4){bflo(w.x), bfhi(w.x), bflo(w.y), bfhi(w.y)}; v1 = (f32x4){bflo(w.z), bfhi(w.z), bflo(w.w), bfhi(w.w)}; }
;     __device__ __forceinline__ void operator()(const f32x4 (&acc)[2][2][4][2], const Unit& u, int wr, int wc, int fr, int fq) const {
;     ...
;                 for (int bj = 0; bj < 2; ++bj) {
;                     const u32x4 gw = *(const u32x4*)(rowp + O_GA + bj * 128);
;                     f32x4 g0, g1; unpack8(gw, g0, g1);
;                     f32x4 v0, v1;
; #pragma unroll
;                     for (int j = 0; j < 4; ++j) { v0[j] = sigmoidf_(g0[j]) * acc[ai][bj][m][0][j]; v1[j] = sigmoidf_(g1[j]) * acc[ai][bj][m][1][j]; }
;                     const u32x4 mw = *(const u32x4*)(rowp + bj * 128); f32x4 m0, m1; unpack8(mw, m0, m1); v0 += m0; v1 += m1;
;                     __builtin_amdgcn_raw_buffer_store_b128(pack8(v0, v1), rsrc, (unsigned)(((size_t)row * DIN + col0 + bj * 128) * 2), 0, 16  ); }
	v_mov_b32_e32 v38, v232
	v_mov_b32_e32 v39, v233
	v_mov_b32_e32 v40, v234
	v_mov_b32_e32 v41, v235
	v_mov_b32_e32 v42, v236
	v_mov_b32_e32 v43, v237
	v_mov_b32_e32 v44, v238
	v_mov_b32_e32 v45, v239
	v_lshlrev_b32_e32 v35, 16, v38
	v_lshlrev_b32_e32 v47, 16, v39
	v_and_b32_e32 v48, 0xffff0000, v39
	v_lshlrev_b32_e32 v39, 16, v40
	v_mul_f32_e32 v35, 0xbfb8aa3b, v35
	v_and_b32_e32 v46, 0xffff0000, v38
	v_exp_f32_e32 v38, v35
	v_mul_f32_e32 v35, 0xbfb8aa3b, v39
	v_and_b32_e32 v49, 0xffff0000, v40
	v_exp_f32_e32 v40, v35
	v_mul_f32_e32 v35, 0xbfb8aa3b, v46
	v_exp_f32_e32 v39, v35
	v_mul_f32_e32 v35, 0xbfb8aa3b, v49
	v_lshlrev_b32_e32 v50, 16, v41
	v_and_b32_e32 v51, 0xffff0000, v41
	v_exp_f32_e32 v41, v35
	v_mul_f32_e32 v35, 0xbfb8aa3b, v47
	v_exp_f32_e32 v46, v35
	v_mul_f32_e32 v35, 0xbfb8aa3b, v48
	v_pk_add_f32 v[38:39], v[38:39], 1.0 op_sel_hi:[1,0]
	v_exp_f32_e32 v47, v35
	v_div_scale_f32 v35, s[6:7], v39, v39, 1.0
	v_rcp_f32_e32 v49, v35
	v_mul_f32_e32 v48, 0xbfb8aa3b, v50
	v_pk_add_f32 v[46:47], v[46:47], 1.0 op_sel_hi:[1,0]
	v_pk_add_f32 v[40:41], v[40:41], 1.0 op_sel_hi:[1,0]
	v_fma_f32 v50, -v35, v49, 1.0
	v_fmac_f32_e32 v49, v50, v49
	v_div_scale_f32 v50, vcc, 1.0, v39, 1.0
	v_mul_f32_e32 v52, v50, v49
	v_fma_f32 v53, -v35, v52, v50
	v_fmac_f32_e32 v52, v53, v49
	v_fma_f32 v35, -v35, v52, v50
	v_div_scale_f32 v50, s[6:7], v38, v38, 1.0
	v_rcp_f32_e32 v53, v50
	v_div_fmas_f32 v35, v35, v49, v52
	v_div_fixup_f32 v39, v35, v39, 1.0
	v_exp_f32_e32 v48, v48
	v_fma_f32 v35, -v50, v53, 1.0
	v_fmac_f32_e32 v53, v35, v53
	v_div_scale_f32 v35, vcc, 1.0, v38, 1.0
	v_mul_f32_e32 v49, v35, v53
	v_fma_f32 v52, -v50, v49, v35
	v_fmac_f32_e32 v49, v52, v53
	v_fma_f32 v35, -v50, v49, v35
	v_div_scale_f32 v50, s[6:7], v47, v47, 1.0
	v_rcp_f32_e32 v52, v50
	v_div_fmas_f32 v35, v35, v53, v49
	v_div_fixup_f32 v38, v35, v38, 1.0
	v_fma_f32 v35, -v50, v52, 1.0
	v_fmac_f32_e32 v52, v35, v52
	v_div_scale_f32 v35, vcc, 1.0, v47, 1.0
	v_mul_f32_e32 v49, v35, v52
	v_fma_f32 v53, -v50, v49, v35
	v_fmac_f32_e32 v49, v53, v52
	v_fma_f32 v35, -v50, v49, v35
	v_div_scale_f32 v50, s[6:7], v46, v46, 1.0
	v_rcp_f32_e32 v53, v50
	v_div_fmas_f32 v35, v35, v52, v49
	v_div_fixup_f32 v47, v35, v47, 1.0
	v_fma_f32 v35, -v50, v53, 1.0
	v_fmac_f32_e32 v53, v35, v53
	v_div_scale_f32 v35, vcc, 1.0, v46, 1.0
	v_mul_f32_e32 v52, v35, v53
	v_fma_f32 v49, -v50, v52, v35
	v_fmac_f32_e32 v52, v49, v53
	v_fma_f32 v35, -v50, v52, v35
	v_div_scale_f32 v50, s[6:7], v41, v41, 1.0
	v_mul_f32_e32 v49, 0xbfb8aa3b, v51
	v_rcp_f32_e32 v51, v50
	v_div_fmas_f32 v35, v35, v53, v52
	v_div_fixup_f32 v46, v35, v46, 1.0
	v_exp_f32_e32 v49, v49
	v_fma_f32 v35, -v50, v51, 1.0
	v_fmac_f32_e32 v51, v35, v51
	v_div_scale_f32 v35, vcc, 1.0, v41, 1.0
	v_mul_f32_e32 v52, v35, v51
	v_fma_f32 v53, -v50, v52, v35
	v_fmac_f32_e32 v52, v53, v51
	v_fma_f32 v35, -v50, v52, v35
	v_div_scale_f32 v50, s[6:7], v40, v40, 1.0
	v_rcp_f32_e32 v53, v50
	v_div_fmas_f32 v35, v35, v51, v52
	v_div_fixup_f32 v41, v35, v41, 1.0
	v_pk_add_f32 v[48:49], v[48:49], 1.0 op_sel_hi:[1,0]
	v_fma_f32 v35, -v50, v53, 1.0
	v_fmac_f32_e32 v53, v35, v53
	v_div_scale_f32 v35, vcc, 1.0, v40, 1.0
	v_mul_f32_e32 v51, v35, v53
	v_fma_f32 v52, -v50, v51, v35
	v_fmac_f32_e32 v51, v52, v53
	v_fma_f32 v35, -v50, v51, v35
	v_div_scale_f32 v50, s[6:7], v49, v49, 1.0
	v_rcp_f32_e32 v52, v50
	v_div_fmas_f32 v35, v35, v53, v51
	v_div_fixup_f32 v40, v35, v40, 1.0
	v_fma_f32 v35, -v50, v52, 1.0
	v_fmac_f32_e32 v52, v35, v52
	v_div_scale_f32 v35, vcc, 1.0, v49, 1.0
	v_mul_f32_e32 v51, v35, v52
	v_fma_f32 v53, -v50, v51, v35
	v_fmac_f32_e32 v51, v53, v52
	v_fma_f32 v35, -v50, v51, v35
	v_div_scale_f32 v50, s[6:7], v48, v48, 1.0
	v_rcp_f32_e32 v53, v50
	v_div_fmas_f32 v35, v35, v52, v51
	v_div_fixup_f32 v49, v35, v49, 1.0
	v_fma_f32 v35, -v50, v53, 1.0
	v_fmac_f32_e32 v53, v35, v53
	v_div_scale_f32 v35, vcc, 1.0, v48, 1.0
	v_mul_f32_e32 v51, v35, v53
	v_fma_f32 v52, -v50, v51, v35
	v_fmac_f32_e32 v51, v52, v53
	v_fma_f32 v35, -v50, v51, v35
	v_div_fmas_f32 v35, v35, v53, v51
	v_div_fixup_f32 v48, v35, v48, 1.0
	v_lshlrev_b32_e32 v50, 16, v42
	v_and_b32_e32 v51, 0xffff0000, v42
	v_lshlrev_b32_e32 v52, 16, v44
	v_and_b32_e32 v53, 0xffff0000, v44
	v_lshlrev_b32_e32 v44, 16, v45
	v_and_b32_e32 v45, 0xffff0000, v45
	v_lshlrev_b32_e32 v42, 16, v43
	v_and_b32_e32 v43, 0xffff0000, v43
	v_pk_fma_f32 v[28:29], v[28:29], v[38:39], v[50:51]
	v_pk_fma_f32 v[38:39], v[26:27], v[48:49], v[44:45]
	v_pk_fma_f32 v[26:27], v[24:25], v[40:41], v[52:53]
	v_add_lshl_u32 v40, v146, v34, 1
	v_pk_fma_f32 v[30:31], v[30:31], v[46:47], v[42:43]
	v_cvt_pk_bf16_f32 v24, v28, v29
	s_nop 0
	v_cvt_pk_bf16_f32 v25, v30, v31
	v_cvt_pk_bf16_f32 v26, v26, v27
	v_cvt_pk_bf16_f32 v27, v38, v39
	buffer_store_dwordx4 v[24:27], v40, s[24:27], 0 offen sc1
	s_nop 0
	s_waitcnt vmcnt(9)
; __device__ __forceinline__ float sigmoidf_(float x) { return 1.0f / (1.0f + __expf(-x)); }
; __device__ __forceinline__ u32x4 pack8(const f32x4 v0, const f32x4 v1) { u32x4 w; w.x = pk2(v0[0], v0[1]); w.y = pk2(v0[2], v0[3]); w.z = pk2(v1[0], v1[1]); w.w = pk2(v1[2], v1[3]); return w; }
; __device__ __forceinline__ void unpack8(const u32x4 w, f32x4& v0, f32x4& v1) { v0 = (f32x4){bflo(w.x), bfhi(w.x), bflo(w.y), bfhi(w.y)}; v1 = (f32x4){bflo(w.z), bfhi(w.z), bflo(w.w), bfhi(w.w)}; }
;     __device__ __forceinline__ void operator()(const f32x4 (&acc)[2][2][4][2], const Unit& u, int wr, int wc, int fr, int fq) const {
;     ...
;                 for (int bj = 0; bj < 2; ++bj) {
;                     const u32x4 gw = *(const u32x4*)(rowp + O_GA + bj * 128);
;                     f32x4 g0, g1; unpack8(gw, g0, g1);
;                     f32x4 v0, v1;
; #pragma unroll
;                     for (int j = 0; j < 4; ++j) { v0[j] = sigmoidf_(g0[j]) * acc[ai][bj][m][0][j]; v1[j] = sigmoidf_(g1[j]) * acc[ai][bj][m][1][j]; }
;                     const u32x4 mw = *(const u32x4*)(rowp + bj * 128); f32x4 m0, m1; unpack8(mw, m0, m1); v0 += m0; v1 += m1;
;                     __builtin_amdgcn_raw_buffer_store_b128(pack8(v0, v1), rsrc, (unsigned)(((size_t)row * DIN + col0 + bj * 128) * 2), 0, 16  ); }
	v_mov_b32_e32 v24, v240
	v_mov_b32_e32 v25, v241
	v_mov_b32_e32 v26, v242
	v_mov_b32_e32 v27, v243
	v_mov_b32_e32 v28, v244
	v_mov_b32_e32 v29, v245
	v_mov_b32_e32 v30, v246
	v_mov_b32_e32 v31, v247
	v_lshlrev_b32_e32 v34, 16, v25
	v_and_b32_e32 v35, 0xffff0000, v25
	v_lshlrev_b32_e32 v25, 16, v26
	v_lshlrev_b32_e32 v32, 16, v24
	v_and_b32_e32 v33, 0xffff0000, v24
	v_mul_f32_e32 v25, 0xbfb8aa3b, v25
	v_and_b32_e32 v36, 0xffff0000, v26
	v_mul_f32_e32 v24, 0xbfb8aa3b, v32
	v_exp_f32_e32 v26, v25
	v_mul_f32_e32 v25, 0xbfb8aa3b, v33
	v_exp_f32_e32 v24, v24
	v_exp_f32_e32 v25, v25
	v_mul_f32_e32 v33, 0xbfb8aa3b, v35
	v_lshlrev_b32_e32 v37, 16, v27
	v_and_b32_e32 v38, 0xffff0000, v27
	v_pk_add_f32 v[24:25], v[24:25], 1.0 op_sel_hi:[1,0]
	v_mul_f32_e32 v27, 0xbfb8aa3b, v36
	v_div_scale_f32 v35, s[6:7], v25, v25, 1.0
	v_rcp_f32_e32 v36, v35
	v_mul_f32_e32 v32, 0xbfb8aa3b, v34
	v_mul_f32_e32 v34, 0xbfb8aa3b, v37
	v_exp_f32_e32 v32, v32
	v_fma_f32 v37, -v35, v36, 1.0
	v_fmac_f32_e32 v36, v37, v36
	v_div_scale_f32 v37, vcc, 1.0, v25, 1.0
	v_mul_f32_e32 v39, v37, v36
	v_fma_f32 v41, -v35, v39, v37
	v_fmac_f32_e32 v39, v41, v36
	v_fma_f32 v35, -v35, v39, v37
	v_div_scale_f32 v37, s[6:7], v24, v24, 1.0
	v_rcp_f32_e32 v41, v37
	v_div_fmas_f32 v35, v35, v36, v39
	v_exp_f32_e32 v33, v33
	v_div_fixup_f32 v25, v35, v25, 1.0
	v_fma_f32 v35, -v37, v41, 1.0
	v_fmac_f32_e32 v41, v35, v41
	v_div_scale_f32 v35, vcc, 1.0, v24, 1.0
	v_mul_f32_e32 v36, v35, v41
	v_fma_f32 v39, -v37, v36, v35
	v_pk_add_f32 v[32:33], v[32:33], 1.0 op_sel_hi:[1,0]
	v_fmac_f32_e32 v36, v39, v41
	v_fma_f32 v35, -v37, v36, v35
	v_div_scale_f32 v37, s[6:7], v33, v33, 1.0
	v_rcp_f32_e32 v39, v37
	v_div_fmas_f32 v35, v35, v41, v36
	v_div_fixup_f32 v24, v35, v24, 1.0
	v_exp_f32_e32 v27, v27
	v_fma_f32 v35, -v37, v39, 1.0
	v_fmac_f32_e32 v39, v35, v39
	v_div_scale_f32 v35, vcc, 1.0, v33, 1.0
	v_mul_f32_e32 v36, v35, v39
	v_fma_f32 v41, -v37, v36, v35
	v_fmac_f32_e32 v36, v41, v39
	v_fma_f32 v35, -v37, v36, v35
	v_div_scale_f32 v37, s[6:7], v32, v32, 1.0
	v_rcp_f32_e32 v41, v37
	v_div_fmas_f32 v35, v35, v39, v36
	v_div_fixup_f32 v33, v35, v33, 1.0
	v_pk_add_f32 v[26:27], v[26:27], 1.0 op_sel_hi:[1,0]
	v_fma_f32 v35, -v37, v41, 1.0
	v_fmac_f32_e32 v41, v35, v41
	v_div_scale_f32 v35, vcc, 1.0, v32, 1.0
	v_mul_f32_e32 v36, v35, v41
	v_fma_f32 v39, -v37, v36, v35
	v_fmac_f32_e32 v36, v39, v41
	v_fma_f32 v37, -v37, v36, v35
	v_mul_f32_e32 v35, 0xbfb8aa3b, v38
	v_div_scale_f32 v38, s[6:7], v27, v27, 1.0
	v_rcp_f32_e32 v39, v38
	v_div_fmas_f32 v36, v37, v41, v36
	v_div_fixup_f32 v32, v36, v32, 1.0
	v_exp_f32_e32 v34, v34
	v_fma_f32 v36, -v38, v39, 1.0
	v_fmac_f32_e32 v39, v36, v39
	v_div_scale_f32 v36, vcc, 1.0, v27, 1.0
	v_mul_f32_e32 v37, v36, v39
	v_fma_f32 v41, -v38, v37, v36
	v_fmac_f32_e32 v37, v41, v39
	v_fma_f32 v36, -v38, v37, v36
	v_div_scale_f32 v38, s[6:7], v26, v26, 1.0
	v_rcp_f32_e32 v41, v38
	v_div_fmas_f32 v36, v36, v39, v37
	v_exp_f32_e32 v35, v35
	v_div_fixup_f32 v27, v36, v27, 1.0
	v_fma_f32 v36, -v38, v41, 1.0
	v_fmac_f32_e32 v41, v36, v41
	v_div_scale_f32 v36, vcc, 1.0, v26, 1.0
	v_mul_f32_e32 v37, v36, v41
	v_fma_f32 v39, -v38, v37, v36
	v_pk_add_f32 v[34:35], v[34:35], 1.0 op_sel_hi:[1,0]
	v_fmac_f32_e32 v37, v39, v41
	v_fma_f32 v36, -v38, v37, v36
	v_div_scale_f32 v38, s[6:7], v35, v35, 1.0
	v_rcp_f32_e32 v39, v38
	v_div_fmas_f32 v36, v36, v41, v37
	v_div_fixup_f32 v26, v36, v26, 1.0
	v_fma_f32 v36, -v38, v39, 1.0
	v_fmac_f32_e32 v39, v36, v39
	v_div_scale_f32 v36, vcc, 1.0, v35, 1.0
	v_mul_f32_e32 v37, v36, v39
	v_fma_f32 v41, -v38, v37, v36
	v_fmac_f32_e32 v37, v41, v39
	v_fma_f32 v36, -v38, v37, v36
	v_div_scale_f32 v38, s[6:7], v34, v34, 1.0
	v_rcp_f32_e32 v41, v38
	v_div_fmas_f32 v36, v36, v39, v37
	v_div_fixup_f32 v35, v36, v35, 1.0
	v_fma_f32 v36, -v38, v41, 1.0
	v_fmac_f32_e32 v41, v36, v41
	v_div_scale_f32 v36, vcc, 1.0, v34, 1.0
	v_mul_f32_e32 v37, v36, v41
	v_fma_f32 v39, -v38, v37, v36
	v_fmac_f32_e32 v37, v39, v41
	v_fma_f32 v36, -v38, v37, v36
	v_div_fmas_f32 v36, v36, v41, v37
	v_div_fixup_f32 v34, v36, v34, 1.0
	v_lshlrev_b32_e32 v36, 16, v28
	v_and_b32_e32 v37, 0xffff0000, v28
	v_lshlrev_b32_e32 v38, 16, v30
	v_and_b32_e32 v39, 0xffff0000, v30
	v_lshlrev_b32_e32 v30, 16, v31
	v_and_b32_e32 v31, 0xffff0000, v31
	v_lshlrev_b32_e32 v28, 16, v29
	v_and_b32_e32 v29, 0xffff0000, v29
	v_pk_fma_f32 v[20:21], v[20:21], v[24:25], v[36:37]
	v_pk_fma_f32 v[24:25], v[18:19], v[34:35], v[30:31]
	v_pk_fma_f32 v[18:19], v[16:17], v[26:27], v[38:39]
	v_cvt_pk_bf16_f32 v16, v20, v21
	v_pk_fma_f32 v[22:23], v[22:23], v[32:33], v[28:29]
	s_nop 0
	v_cvt_pk_bf16_f32 v17, v22, v23
	v_cvt_pk_bf16_f32 v18, v18, v19
	v_cvt_pk_bf16_f32 v19, v24, v25
	buffer_store_dwordx4 v[16:19], v40, s[24:27], 0 offen offset:256 sc1
	s_nop 1
	v_add_u32_e32 v16, 0xb0, v162
	v_mad_i64_i32 v[18:19], s[6:7], v16, s77, 0
	v_lshl_add_u64 v[16:17], v[18:19], 1, s[38:39]
	v_lshl_add_u64 v[16:17], v[16:17], 0, v[148:149]
	v_add_co_u32_e32 v20, vcc, s78, v16
	s_nop 1
	v_addc_co_u32_e32 v21, vcc, 0, v17, vcc
	s_waitcnt vmcnt(7)
; __device__ __forceinline__ float sigmoidf_(float x) { return 1.0f / (1.0f + __expf(-x)); }
; __device__ __forceinline__ u32x4 pack8(const f32x4 v0, const f32x4 v1) { u32x4 w; w.x = pk2(v0[0], v0[1]); w.y = pk2(v0[2], v0[3]); w.z = pk2(v1[0], v1[1]); w.w = pk2(v1[2], v1[3]); return w; }
; __device__ __forceinline__ void unpack8(const u32x4 w, f32x4& v0, f32x4& v1) { v0 = (f32x4){bflo(w.x), bfhi(w.x), bflo(w.y), bfhi(w.y)}; v1 = (f32x4){bflo(w.z), bfhi(w.z), bflo(w.w), bfhi(w.w)}; }
;     __device__ __forceinline__ void operator()(const f32x4 (&acc)[2][2][4][2], const Unit& u, int wr, int wc, int fr, int fq) const {
;     ...
;                 for (int bj = 0; bj < 2; ++bj) {
;                     const u32x4 gw = *(const u32x4*)(rowp + O_GA + bj * 128);
;                     f32x4 g0, g1; unpack8(gw, g0, g1);
;                     f32x4 v0, v1;
; #pragma unroll
;                     for (int j = 0; j < 4; ++j) { v0[j] = sigmoidf_(g0[j]) * acc[ai][bj][m][0][j]; v1[j] = sigmoidf_(g1[j]) * acc[ai][bj][m][1][j]; }
;                     const u32x4 mw = *(const u32x4*)(rowp + bj * 128); f32x4 m0, m1; unpack8(mw, m0, m1); v0 += m0; v1 += m1;
;                     __builtin_amdgcn_raw_buffer_store_b128(pack8(v0, v1), rsrc, (unsigned)(((size_t)row * DIN + col0 + bj * 128) * 2), 0, 16  ); }
	v_mov_b32_e32 v22, v248
	v_mov_b32_e32 v23, v249
	v_mov_b32_e32 v24, v250
	v_mov_b32_e32 v25, v251
	v_mov_b32_e32 v26, v252
	v_mov_b32_e32 v27, v253
	v_mov_b32_e32 v28, v254
	v_mov_b32_e32 v29, v255
	v_lshlrev_b32_e32 v19, 16, v22
	v_lshlrev_b32_e32 v31, 16, v23
	v_and_b32_e32 v32, 0xffff0000, v23
	v_lshlrev_b32_e32 v23, 16, v24
	v_mul_f32_e32 v19, 0xbfb8aa3b, v19
	v_and_b32_e32 v30, 0xffff0000, v22
	v_exp_f32_e32 v22, v19
	v_mul_f32_e32 v19, 0xbfb8aa3b, v23
	v_and_b32_e32 v33, 0xffff0000, v24
	v_exp_f32_e32 v24, v19
	v_mul_f32_e32 v19, 0xbfb8aa3b, v30
	v_exp_f32_e32 v23, v19
	v_mul_f32_e32 v19, 0xbfb8aa3b, v33
	v_lshlrev_b32_e32 v34, 16, v25
	v_and_b32_e32 v35, 0xffff0000, v25
	v_exp_f32_e32 v25, v19
	v_mul_f32_e32 v19, 0xbfb8aa3b, v31
	v_exp_f32_e32 v30, v19
	v_mul_f32_e32 v19, 0xbfb8aa3b, v32
	v_pk_add_f32 v[22:23], v[22:23], 1.0 op_sel_hi:[1,0]
	v_exp_f32_e32 v31, v19
	v_div_scale_f32 v19, s[6:7], v23, v23, 1.0
	v_rcp_f32_e32 v33, v19
	v_mul_f32_e32 v32, 0xbfb8aa3b, v34
	v_pk_add_f32 v[30:31], v[30:31], 1.0 op_sel_hi:[1,0]
	v_pk_add_f32 v[24:25], v[24:25], 1.0 op_sel_hi:[1,0]
	v_fma_f32 v34, -v19, v33, 1.0
	v_fmac_f32_e32 v33, v34, v33
	v_div_scale_f32 v34, vcc, 1.0, v23, 1.0
	v_mul_f32_e32 v36, v34, v33
	v_fma_f32 v37, -v19, v36, v34
	v_fmac_f32_e32 v36, v37, v33
	v_fma_f32 v19, -v19, v36, v34
	v_div_scale_f32 v34, s[6:7], v22, v22, 1.0
	v_rcp_f32_e32 v37, v34
	v_div_fmas_f32 v19, v19, v33, v36
	v_div_fixup_f32 v23, v19, v23, 1.0
	v_exp_f32_e32 v32, v32
	v_fma_f32 v19, -v34, v37, 1.0
	v_fmac_f32_e32 v37, v19, v37
	v_div_scale_f32 v19, vcc, 1.0, v22, 1.0
	v_mul_f32_e32 v33, v19, v37
	v_fma_f32 v36, -v34, v33, v19
	v_fmac_f32_e32 v33, v36, v37
	v_fma_f32 v19, -v34, v33, v19
	v_div_scale_f32 v34, s[6:7], v31, v31, 1.0
	v_rcp_f32_e32 v36, v34
	v_div_fmas_f32 v19, v19, v37, v33
	v_div_fixup_f32 v22, v19, v22, 1.0
	v_fma_f32 v19, -v34, v36, 1.0
	v_fmac_f32_e32 v36, v19, v36
	v_div_scale_f32 v19, vcc, 1.0, v31, 1.0
	v_mul_f32_e32 v33, v19, v36
	v_fma_f32 v37, -v34, v33, v19
	v_fmac_f32_e32 v33, v37, v36
	v_fma_f32 v19, -v34, v33, v19
	v_div_scale_f32 v34, s[6:7], v30, v30, 1.0
	v_rcp_f32_e32 v37, v34
	v_div_fmas_f32 v19, v19, v36, v33
	v_div_fixup_f32 v31, v19, v31, 1.0
	v_fma_f32 v19, -v34, v37, 1.0
	v_fmac_f32_e32 v37, v19, v37
	v_div_scale_f32 v19, vcc, 1.0, v30, 1.0
	v_mul_f32_e32 v36, v19, v37
	v_fma_f32 v33, -v34, v36, v19
	v_fmac_f32_e32 v36, v33, v37
	v_fma_f32 v19, -v34, v36, v19
	v_div_scale_f32 v34, s[6:7], v25, v25, 1.0
	v_mul_f32_e32 v33, 0xbfb8aa3b, v35
	v_rcp_f32_e32 v35, v34
	v_div_fmas_f32 v19, v19, v37, v36
	v_div_fixup_f32 v30, v19, v30, 1.0
	v_exp_f32_e32 v33, v33
	v_fma_f32 v19, -v34, v35, 1.0
	v_fmac_f32_e32 v35, v19, v35
	v_div_scale_f32 v19, vcc, 1.0, v25, 1.0
	v_mul_f32_e32 v36, v19, v35
	v_fma_f32 v37, -v34, v36, v19
	v_fmac_f32_e32 v36, v37, v35
	v_fma_f32 v19, -v34, v36, v19
	v_div_scale_f32 v34, s[6:7], v24, v24, 1.0
	v_rcp_f32_e32 v37, v34
	v_div_fmas_f32 v19, v19, v35, v36
	v_div_fixup_f32 v25, v19, v25, 1.0
	v_pk_add_f32 v[32:33], v[32:33], 1.0 op_sel_hi:[1,0]
	v_fma_f32 v19, -v34, v37, 1.0
	v_fmac_f32_e32 v37, v19, v37
	v_div_scale_f32 v19, vcc, 1.0, v24, 1.0
	v_mul_f32_e32 v35, v19, v37
	v_fma_f32 v36, -v34, v35, v19
	v_fmac_f32_e32 v35, v36, v37
	v_fma_f32 v19, -v34, v35, v19
	v_div_scale_f32 v34, s[6:7], v33, v33, 1.0
	v_rcp_f32_e32 v36, v34
	v_div_fmas_f32 v19, v19, v37, v35
	v_div_fixup_f32 v24, v19, v24, 1.0
	v_fma_f32 v19, -v34, v36, 1.0
	v_fmac_f32_e32 v36, v19, v36
	v_div_scale_f32 v19, vcc, 1.0, v33, 1.0
	v_mul_f32_e32 v35, v19, v36
	v_fma_f32 v37, -v34, v35, v19
	v_fmac_f32_e32 v35, v37, v36
	v_fma_f32 v19, -v34, v35, v19
	v_div_scale_f32 v34, s[6:7], v32, v32, 1.0
	v_rcp_f32_e32 v37, v34
	v_div_fmas_f32 v19, v19, v36, v35
	v_div_fixup_f32 v33, v19, v33, 1.0
	v_fma_f32 v19, -v34, v37, 1.0
	v_fmac_f32_e32 v37, v19, v37
	v_div_scale_f32 v19, vcc, 1.0, v32, 1.0
	v_mul_f32_e32 v35, v19, v37
	v_fma_f32 v36, -v34, v35, v19
	v_fmac_f32_e32 v35, v36, v37
	v_fma_f32 v19, -v34, v35, v19
	v_div_fmas_f32 v19, v19, v37, v35
	v_div_fixup_f32 v32, v19, v32, 1.0
	v_lshlrev_b32_e32 v34, 16, v26
	v_and_b32_e32 v35, 0xffff0000, v26
	v_lshlrev_b32_e32 v36, 16, v28
	v_and_b32_e32 v37, 0xffff0000, v28
	v_lshlrev_b32_e32 v28, 16, v29
	v_and_b32_e32 v29, 0xffff0000, v29
	v_lshlrev_b32_e32 v26, 16, v27
	v_and_b32_e32 v27, 0xffff0000, v27
	v_pk_fma_f32 v[12:13], v[12:13], v[22:23], v[34:35]
	v_pk_fma_f32 v[22:23], v[10:11], v[32:33], v[28:29]
	v_pk_fma_f32 v[10:11], v[8:9], v[24:25], v[36:37]
	v_add_lshl_u32 v24, v146, v18, 1
	v_pk_fma_f32 v[14:15], v[14:15], v[30:31], v[26:27]
	v_cvt_pk_bf16_f32 v8, v12, v13
	s_nop 0
	v_cvt_pk_bf16_f32 v9, v14, v15
	v_cvt_pk_bf16_f32 v10, v10, v11
	v_cvt_pk_bf16_f32 v11, v22, v23
	buffer_store_dwordx4 v[8:11], v24, s[24:27], 0 offen sc1
	s_nop 0
	s_waitcnt vmcnt(5)
; __device__ __forceinline__ float sigmoidf_(float x) { return 1.0f / (1.0f + __expf(-x)); }
; __device__ __forceinline__ u32x4 pack8(const f32x4 v0, const f32x4 v1) { u32x4 w; w.x = pk2(v0[0], v0[1]); w.y = pk2(v0[2], v0[3]); w.z = pk2(v1[0], v1[1]); w.w = pk2(v1[2], v1[3]); return w; }
; __device__ __forceinline__ void unpack8(const u32x4 w, f32x4& v0, f32x4& v1) { v0 = (f32x4){bflo(w.x), bfhi(w.x), bflo(w.y), bfhi(w.y)}; v1 = (f32x4){bflo(w.z), bfhi(w.z), bflo(w.w), bfhi(w.w)}; }
;     __device__ __forceinline__ void operator()(const f32x4 (&acc)[2][2][4][2], const Unit& u, int wr, int wc, int fr, int fq) const {
;     ...
;                 for (int bj = 0; bj < 2; ++bj) {
;                     const u32x4 gw = *(const u32x4*)(rowp + O_GA + bj * 128);
;                     f32x4 g0, g1; unpack8(gw, g0, g1);
;                     f32x4 v0, v1;
; #pragma unroll
;                     for (int j = 0; j < 4; ++j) { v0[j] = sigmoidf_(g0[j]) * acc[ai][bj][m][0][j]; v1[j] = sigmoidf_(g1[j]) * acc[ai][bj][m][1][j]; }
;                     const u32x4 mw = *(const u32x4*)(rowp + bj * 128); f32x4 m0, m1; unpack8(mw, m0, m1); v0 += m0; v1 += m1;
;                     __builtin_amdgcn_raw_buffer_store_b128(pack8(v0, v1), rsrc, (unsigned)(((size_t)row * DIN + col0 + bj * 128) * 2), 0, 16  ); }
;             }
;         asm volatile("s_waitcnt vmcnt(0)" ::: "memory");
;         if (fr == 0 && fq == 0) (void)__hip_atomic_fetch_add(ready + 64 * (pm_off + u.pm), 1u, __ATOMIC_RELAXED, __HIP_MEMORY_SCOPE_AGENT);
	v_mov_b32_e32 v8, v204
	v_mov_b32_e32 v9, v205
	v_mov_b32_e32 v10, v206
	v_mov_b32_e32 v11, v207
	v_mov_b32_e32 v12, v208
	v_mov_b32_e32 v13, v209
	v_mov_b32_e32 v14, v210
	v_mov_b32_e32 v15, v211
	v_lshlrev_b32_e32 v18, 16, v9
	v_and_b32_e32 v19, 0xffff0000, v9
	v_lshlrev_b32_e32 v9, 16, v10
	v_lshlrev_b32_e32 v16, 16, v8
	v_and_b32_e32 v17, 0xffff0000, v8
	v_mul_f32_e32 v9, 0xbfb8aa3b, v9
	v_and_b32_e32 v20, 0xffff0000, v10
	v_mul_f32_e32 v8, 0xbfb8aa3b, v16
	v_exp_f32_e32 v10, v9
	v_mul_f32_e32 v9, 0xbfb8aa3b, v17
	v_exp_f32_e32 v8, v8
	v_exp_f32_e32 v9, v9
	v_mul_f32_e32 v17, 0xbfb8aa3b, v19
	v_lshlrev_b32_e32 v21, 16, v11
	v_and_b32_e32 v22, 0xffff0000, v11
	v_pk_add_f32 v[8:9], v[8:9], 1.0 op_sel_hi:[1,0]
	v_mul_f32_e32 v11, 0xbfb8aa3b, v20
	v_div_scale_f32 v19, s[6:7], v9, v9, 1.0
	v_rcp_f32_e32 v20, v19
	v_mul_f32_e32 v16, 0xbfb8aa3b, v18
	v_mul_f32_e32 v18, 0xbfb8aa3b, v21
	v_exp_f32_e32 v16, v16
	v_fma_f32 v21, -v19, v20, 1.0
	v_fmac_f32_e32 v20, v21, v20
	v_div_scale_f32 v21, vcc, 1.0, v9, 1.0
	v_mul_f32_e32 v23, v21, v20
	v_fma_f32 v25, -v19, v23, v21
	v_fmac_f32_e32 v23, v25, v20
	v_fma_f32 v19, -v19, v23, v21
	v_div_scale_f32 v21, s[6:7], v8, v8, 1.0
	v_rcp_f32_e32 v25, v21
	v_div_fmas_f32 v19, v19, v20, v23
	v_exp_f32_e32 v17, v17
	v_div_fixup_f32 v9, v19, v9, 1.0
	v_fma_f32 v19, -v21, v25, 1.0
	v_fmac_f32_e32 v25, v19, v25
	v_div_scale_f32 v19, vcc, 1.0, v8, 1.0
	v_mul_f32_e32 v20, v19, v25
	v_fma_f32 v23, -v21, v20, v19
	v_pk_add_f32 v[16:17], v[16:17], 1.0 op_sel_hi:[1,0]
	v_fmac_f32_e32 v20, v23, v25
	v_fma_f32 v19, -v21, v20, v19
	v_div_scale_f32 v21, s[6:7], v17, v17, 1.0
	v_rcp_f32_e32 v23, v21
	v_div_fmas_f32 v19, v19, v25, v20
	v_div_fixup_f32 v8, v19, v8, 1.0
	v_exp_f32_e32 v11, v11
	v_fma_f32 v19, -v21, v23, 1.0
	v_fmac_f32_e32 v23, v19, v23
	v_div_scale_f32 v19, vcc, 1.0, v17, 1.0
	v_mul_f32_e32 v20, v19, v23
	v_fma_f32 v25, -v21, v20, v19
	v_fmac_f32_e32 v20, v25, v23
	v_fma_f32 v19, -v21, v20, v19
	v_div_scale_f32 v21, s[6:7], v16, v16, 1.0
	v_rcp_f32_e32 v25, v21
	v_div_fmas_f32 v19, v19, v23, v20
	v_div_fixup_f32 v17, v19, v17, 1.0
	v_pk_add_f32 v[10:11], v[10:11], 1.0 op_sel_hi:[1,0]
	v_fma_f32 v19, -v21, v25, 1.0
	v_fmac_f32_e32 v25, v19, v25
	v_div_scale_f32 v19, vcc, 1.0, v16, 1.0
	v_mul_f32_e32 v20, v19, v25
	v_fma_f32 v23, -v21, v20, v19
	v_fmac_f32_e32 v20, v23, v25
	v_fma_f32 v21, -v21, v20, v19
	v_mul_f32_e32 v19, 0xbfb8aa3b, v22
	v_div_scale_f32 v22, s[6:7], v11, v11, 1.0
	v_rcp_f32_e32 v23, v22
	v_div_fmas_f32 v20, v21, v25, v20
	v_div_fixup_f32 v16, v20, v16, 1.0
	v_exp_f32_e32 v18, v18
	v_fma_f32 v20, -v22, v23, 1.0
	v_fmac_f32_e32 v23, v20, v23
	v_div_scale_f32 v20, vcc, 1.0, v11, 1.0
	v_mul_f32_e32 v21, v20, v23
	v_fma_f32 v25, -v22, v21, v20
	v_fmac_f32_e32 v21, v25, v23
	v_fma_f32 v20, -v22, v21, v20
	v_div_scale_f32 v22, s[6:7], v10, v10, 1.0
	v_rcp_f32_e32 v25, v22
	v_div_fmas_f32 v20, v20, v23, v21
	v_exp_f32_e32 v19, v19
	v_div_fixup_f32 v11, v20, v11, 1.0
	v_fma_f32 v20, -v22, v25, 1.0
	v_fmac_f32_e32 v25, v20, v25
	v_div_scale_f32 v20, vcc, 1.0, v10, 1.0
	v_mul_f32_e32 v21, v20, v25
	v_fma_f32 v23, -v22, v21, v20
	v_pk_add_f32 v[18:19], v[18:19], 1.0 op_sel_hi:[1,0]
	v_fmac_f32_e32 v21, v23, v25
	v_fma_f32 v20, -v22, v21, v20
	v_div_scale_f32 v22, s[6:7], v19, v19, 1.0
	v_rcp_f32_e32 v23, v22
	v_div_fmas_f32 v20, v20, v25, v21
	v_div_fixup_f32 v10, v20, v10, 1.0
	v_fma_f32 v20, -v22, v23, 1.0
	v_fmac_f32_e32 v23, v20, v23
	v_div_scale_f32 v20, vcc, 1.0, v19, 1.0
	v_mul_f32_e32 v21, v20, v23
	v_fma_f32 v25, -v22, v21, v20
	v_fmac_f32_e32 v21, v25, v23
	v_fma_f32 v20, -v22, v21, v20
	v_div_scale_f32 v22, s[6:7], v18, v18, 1.0
	v_rcp_f32_e32 v25, v22
	v_div_fmas_f32 v20, v20, v23, v21
	v_div_fixup_f32 v19, v20, v19, 1.0
	v_fma_f32 v20, -v22, v25, 1.0
	v_fmac_f32_e32 v25, v20, v25
	v_div_scale_f32 v20, vcc, 1.0, v18, 1.0
	v_mul_f32_e32 v21, v20, v25
	v_fma_f32 v23, -v22, v21, v20
	v_fmac_f32_e32 v21, v23, v25
	v_fma_f32 v20, -v22, v21, v20
	v_div_fmas_f32 v20, v20, v25, v21
	v_div_fixup_f32 v18, v20, v18, 1.0
	v_lshlrev_b32_e32 v20, 16, v12
	v_and_b32_e32 v21, 0xffff0000, v12
	v_lshlrev_b32_e32 v22, 16, v14
	v_and_b32_e32 v23, 0xffff0000, v14
	v_lshlrev_b32_e32 v14, 16, v15
	v_and_b32_e32 v15, 0xffff0000, v15
	v_lshlrev_b32_e32 v12, 16, v13
	v_and_b32_e32 v13, 0xffff0000, v13
	v_pk_fma_f32 v[4:5], v[4:5], v[8:9], v[20:21]
	v_pk_fma_f32 v[8:9], v[2:3], v[18:19], v[14:15]
	v_pk_fma_f32 v[2:3], v[0:1], v[10:11], v[22:23]
	v_pk_fma_f32 v[6:7], v[6:7], v[16:17], v[12:13]
	v_cvt_pk_bf16_f32 v0, v4, v5
	s_nop 0
	v_cvt_pk_bf16_f32 v1, v6, v7
	v_cvt_pk_bf16_f32 v2, v2, v3
	v_cvt_pk_bf16_f32 v3, v8, v9
	buffer_store_dwordx4 v[0:3], v24, s[24:27], 0 offen offset:256 sc1
	s_waitcnt vmcnt(0)
	s_and_saveexec_b64 s[14:15], s[10:11]
	s_cbranch_execz .LBB0_692
	s_mov_b64 s[16:17], exec
	v_mbcnt_lo_u32_b32 v0, s16, 0
	v_mbcnt_hi_u32_b32 v0, s17, v0
	v_cmp_eq_u32_e32 vcc, 0, v0
	s_and_b64 s[6:7], exec, vcc
	s_mov_b64 exec, s[6:7]
	s_cbranch_execz .LBB0_692
	s_lshl_b32 s6, s79, 6
	s_ashr_i32 s7, s6, 31
	s_lshl_b64 s[6:7], s[6:7], 2
	s_add_u32 s6, s34, s6
	s_addc_u32 s7, s35, s7
	s_bcnt1_i32_b64 s8, s[16:17]
	v_mov_b32_e32 v0, s8
	global_atomic_add v131, v0, s[6:7]
	s_branch .LBB0_692

; #define PG8_STAGE(bufoff, gbase, voff) do { _Pragma("unroll") for (int _i = 0; _i < 2; ++_i) \
;         __builtin_amdgcn_global_load_lds((const unsigned*)((const char*)(gbase) + (voff)[_i]), (LAS unsigned*)(lds + (bufoff) + ldsw + _i * 8192), 16, 0, 0); } while (0)
; #define PG8_LDA(dst, b, h) do { _Pragma("unroll") for (int m = 0; m < 4; ++m) _Pragma("unroll") for (int k = 0; k < 2; ++k) dst[m][k] = *(const LAS bf16x8*)(lds + PG8_SA(b, h) + aoff + m * 2048 + k * 1024); } while (0)
; #define PG8_LDB(dst, b, h) do { _Pragma("unroll") for (int n = 0; n < 2; ++n) _Pragma("unroll") for (int k = 0; k < 2; ++k) dst[n][k] = *(const LAS bf16x8*)(lds + PG8_SB(b, h) + boff + n * 2048 + k * 1024); } while (0)
; #define PG8_MMA(ai, bj, At, Bt) do { __builtin_amdgcn_s_setprio(1); _Pragma("unroll") for (int m = 0; m < 4; ++m) _Pragma("unroll") for (int n = 0; n < 2; ++n) _Pragma("unroll") for (int k = 0; k < 2; ++k) \
;         acc[ai][bj][m][n] = __builtin_amdgcn_mfma_f32_16x16x32_bf16(Bt[n][k], At[m][k], acc[ai][bj][m][n], 0, 0, 0); __builtin_amdgcn_s_setprio(0); } while (0)
; #define PG8_WAIT_V(n) asm volatile("s_waitcnt vmcnt(" #n ")" ::: "memory")
; #define PG8_WAIT_L(n) asm volatile("s_waitcnt lgkmcnt(" #n ")" ::: "memory")
; #define PG8_BAR __builtin_amdgcn_s_barrier()
; #define PG8_SCHED __builtin_amdgcn_sched_barrier(0)
;     ...
;             PG8_LDB(B0, 0, 0); PG8_SCHED; PG8_LDA(At, 0, 0); PG8_STAGE(PG8_SA(1, 1), a1 + hA, voffA);
;             PG8_WAIT_L(8); PG8_BAR; PG8_WAIT_L(0); PG8_MMA(0, 0, At, B0); PG8_BAR; PG8_SCHED;
;             PG8_LDB(B1, 0, 1); PG8_STAGE(PG8_SB(0, 0), b2, voffB);
;             PG8_BAR; PG8_WAIT_L(0); PG8_MMA(0, 1, At, B1); PG8_BAR;
;             PG8_LDA(At, 0, 1); PG8_STAGE(PG8_SA(0, 0), a2, voffA);
;             PG8_BAR; PG8_WAIT_L(0); PG8_MMA(1, 0, At, B0); PG8_BAR; PG8_SCHED;
;             PG8_STAGE(PG8_SB(0, 1), b2 + hB, voffB);
;             PG8_WAIT_V(6); PG8_BAR; PG8_MMA(1, 1, At, B1); PG8_BAR;
;             PG8_LDB(B0, 1, 0); PG8_SCHED; PG8_LDA(At, 1, 0); PG8_STAGE(PG8_SA(0, 1), a2 + hA, voffA);
;             PG8_WAIT_L(8); PG8_BAR; PG8_WAIT_L(0); PG8_MMA(0, 0, At, B0); PG8_BAR; PG8_SCHED;
.LBB0_723:
	ds_read_b128 v[140:143], v155
	ds_read_b128 v[146:149], v155 offset:1024
	ds_read_b128 v[158:161], v155 offset:2048
	ds_read_b128 v[162:165], v155 offset:3072
	s_add_u32 s14, s12, 0xfffe0080
	s_addc_u32 s15, s13, -1
	s_cmp_eq_u32 s39, 4
	s_cselect_b32 s17, s7, s15
	s_cselect_b32 s16, s8, s14
	s_cselect_b32 s15, s9, s33
	s_cselect_b32 s14, s18, s19
	v_lshl_add_u64 v[150:151], s[12:13], 0, v[138:139]
	s_add_i32 m0, s67, 0xc000
	ds_read_b128 v[170:173], v156
	ds_read_b128 v[174:177], v156 offset:1024
	ds_read_b128 v[178:181], v156 offset:2048
	ds_read_b128 v[182:185], v156 offset:3072
	ds_read_b128 v[186:189], v156 offset:4096
	ds_read_b128 v[190:193], v156 offset:5120
	ds_read_b128 v[194:197], v156 offset:6144
	ds_read_b128 v[198:201], v156 offset:7168
	global_load_lds_dwordx4 v[150:151], off
	v_lshl_add_u64 v[150:151], s[12:13], 0, v[136:137]
	s_add_i32 m0, s67, 0xe000
	s_nop 0
	global_load_lds_dwordx4 v[150:151], off
	s_waitcnt lgkmcnt(8)
	s_barrier
	s_waitcnt lgkmcnt(0)
	s_setprio 1
	s_waitcnt lgkmcnt(0)
	v_mfma_f32_16x16x32_bf16 v[124:127], v[140:143], v[170:173], v[124:127]
	v_mfma_f32_16x16x32_bf16 v[120:123], v[158:161], v[170:173], v[120:123]
	v_mfma_f32_16x16x32_bf16 v[108:111], v[140:143], v[178:181], v[108:111]
	v_mfma_f32_16x16x32_bf16 v[104:107], v[158:161], v[178:181], v[104:107]
	v_mfma_f32_16x16x32_bf16 v[92:95], v[140:143], v[186:189], v[92:95]
	v_mfma_f32_16x16x32_bf16 v[88:91], v[158:161], v[186:189], v[88:91]
	v_mfma_f32_16x16x32_bf16 v[76:79], v[140:143], v[194:197], v[76:79]
	v_mfma_f32_16x16x32_bf16 v[72:75], v[158:161], v[194:197], v[72:75]
	v_mfma_f32_16x16x32_bf16 v[124:127], v[146:149], v[174:177], v[124:127]
	v_mfma_f32_16x16x32_bf16 v[120:123], v[162:165], v[174:177], v[120:123]
	v_mfma_f32_16x16x32_bf16 v[108:111], v[146:149], v[182:185], v[108:111]
	v_mfma_f32_16x16x32_bf16 v[104:107], v[162:165], v[182:185], v[104:107]
	v_mfma_f32_16x16x32_bf16 v[92:95], v[146:149], v[190:193], v[92:95]
	v_mfma_f32_16x16x32_bf16 v[88:91], v[162:165], v[190:193], v[88:91]
	v_mfma_f32_16x16x32_bf16 v[76:79], v[146:149], v[198:201], v[76:79]
	v_mfma_f32_16x16x32_bf16 v[72:75], v[162:165], v[198:201], v[72:75]
	s_setprio 0
	s_barrier
	s_add_i32 s42, s75, s66
	v_lshl_add_u64 v[150:151], s[14:15], 0, v[130:131]
	s_mov_b32 m0, s42
	ds_read_b128 v[202:205], v157
	ds_read_b128 v[206:209], v157 offset:1024
	ds_read_b128 v[210:213], v157 offset:2048
	ds_read_b128 v[214:217], v157 offset:3072
	global_load_lds_dwordx4 v[150:151], off
	v_lshl_add_u64 v[218:219], s[14:15], 0, v[134:135]
	s_add_i32 m0, s42, 0x2000
	s_nop 0
	global_load_lds_dwordx4 v[218:219], off
	s_barrier
	s_waitcnt lgkmcnt(0)
	s_setprio 1
	s_waitcnt lgkmcnt(0)
	v_mfma_f32_16x16x32_bf16 v[116:119], v[202:205], v[170:173], v[116:119]
	v_mfma_f32_16x16x32_bf16 v[112:115], v[210:213], v[170:173], v[112:115]
	v_mfma_f32_16x16x32_bf16 v[100:103], v[202:205], v[178:181], v[100:103]
	v_mfma_f32_16x16x32_bf16 v[96:99], v[210:213], v[178:181], v[96:99]
	v_mfma_f32_16x16x32_bf16 v[84:87], v[202:205], v[186:189], v[84:87]
	v_mfma_f32_16x16x32_bf16 v[80:83], v[210:213], v[186:189], v[80:83]
	v_mfma_f32_16x16x32_bf16 v[68:71], v[202:205], v[194:197], v[68:71]
	v_mfma_f32_16x16x32_bf16 v[64:67], v[210:213], v[194:197], v[64:67]
	v_mfma_f32_16x16x32_bf16 v[116:119], v[206:209], v[174:177], v[116:119]
	v_mfma_f32_16x16x32_bf16 v[112:115], v[214:217], v[174:177], v[112:115]
	v_mfma_f32_16x16x32_bf16 v[100:103], v[206:209], v[182:185], v[100:103]
	v_mfma_f32_16x16x32_bf16 v[96:99], v[214:217], v[182:185], v[96:99]
	v_mfma_f32_16x16x32_bf16 v[84:87], v[206:209], v[190:193], v[84:87]
	v_mfma_f32_16x16x32_bf16 v[80:83], v[214:217], v[190:193], v[80:83]
	v_mfma_f32_16x16x32_bf16 v[68:71], v[206:209], v[198:201], v[68:71]
	v_mfma_f32_16x16x32_bf16 v[64:67], v[214:217], v[198:201], v[64:67]
	s_setprio 0
	s_mov_b32 m0, s67
	v_lshl_add_u64 v[220:221], s[16:17], 0, v[128:129]
	s_barrier
	ds_read_b128 v[170:173], v156 offset:16384
	ds_read_b128 v[174:177], v156 offset:17408
	ds_read_b128 v[178:181], v156 offset:18432
	ds_read_b128 v[182:185], v156 offset:19456
	ds_read_b128 v[186:189], v156 offset:20480
	ds_read_b128 v[190:193], v156 offset:21504
	ds_read_b128 v[194:197], v156 offset:22528
	ds_read_b128 v[198:201], v156 offset:23552
	global_load_lds_dwordx4 v[220:221], off
	v_lshl_add_u64 v[222:223], s[16:17], 0, v[132:133]
	s_mov_b32 m0, s68
	s_nop 0
	global_load_lds_dwordx4 v[222:223], off
	s_barrier
	s_waitcnt lgkmcnt(0)
	s_setprio 1
	s_waitcnt lgkmcnt(0)
	v_mfma_f32_16x16x32_bf16 v[60:63], v[140:143], v[170:173], v[60:63]
	v_mfma_f32_16x16x32_bf16 v[56:59], v[158:161], v[170:173], v[56:59]
	v_mfma_f32_16x16x32_bf16 v[44:47], v[140:143], v[178:181], v[44:47]
	v_mfma_f32_16x16x32_bf16 v[40:43], v[158:161], v[178:181], v[40:43]
	v_mfma_f32_16x16x32_bf16 v[28:31], v[140:143], v[186:189], v[28:31]
	v_mfma_f32_16x16x32_bf16 v[24:27], v[158:161], v[186:189], v[24:27]
	v_mfma_f32_16x16x32_bf16 v[12:15], v[140:143], v[194:197], v[12:15]
	v_mfma_f32_16x16x32_bf16 v[8:11], v[158:161], v[194:197], v[8:11]
	v_mfma_f32_16x16x32_bf16 v[60:63], v[146:149], v[174:177], v[60:63]
	v_mfma_f32_16x16x32_bf16 v[56:59], v[162:165], v[174:177], v[56:59]
	v_mfma_f32_16x16x32_bf16 v[44:47], v[146:149], v[182:185], v[44:47]
	v_mfma_f32_16x16x32_bf16 v[40:43], v[162:165], v[182:185], v[40:43]
	v_mfma_f32_16x16x32_bf16 v[28:31], v[146:149], v[190:193], v[28:31]
	v_mfma_f32_16x16x32_bf16 v[24:27], v[162:165], v[190:193], v[24:27]
	v_mfma_f32_16x16x32_bf16 v[12:15], v[146:149], v[198:201], v[12:15]
	v_mfma_f32_16x16x32_bf16 v[8:11], v[162:165], v[198:201], v[8:11]
	s_setprio 0
	s_barrier
; #define PG8_STAGE(bufoff, gbase, voff) do { _Pragma("unroll") for (int _i = 0; _i < 2; ++_i) \
;         __builtin_amdgcn_global_load_lds((const unsigned*)((const char*)(gbase) + (voff)[_i]), (LAS unsigned*)(lds + (bufoff) + ldsw + _i * 8192), 16, 0, 0); } while (0)
; #define PG8_LDA(dst, b, h) do { _Pragma("unroll") for (int m = 0; m < 4; ++m) _Pragma("unroll") for (int k = 0; k < 2; ++k) dst[m][k] = *(const LAS bf16x8*)(lds + PG8_SA(b, h) + aoff + m * 2048 + k * 1024); } while (0)
; #define PG8_LDB(dst, b, h) do { _Pragma("unroll") for (int n = 0; n < 2; ++n) _Pragma("unroll") for (int k = 0; k < 2; ++k) dst[n][k] = *(const LAS bf16x8*)(lds + PG8_SB(b, h) + boff + n * 2048 + k * 1024); } while (0)
; #define PG8_MMA(ai, bj, At, Bt) do { __builtin_amdgcn_s_setprio(1); _Pragma("unroll") for (int m = 0; m < 4; ++m) _Pragma("unroll") for (int n = 0; n < 2; ++n) _Pragma("unroll") for (int k = 0; k < 2; ++k) \
;         acc[ai][bj][m][n] = __builtin_amdgcn_mfma_f32_16x16x32_bf16(Bt[n][k], At[m][k], acc[ai][bj][m][n], 0, 0, 0); __builtin_amdgcn_s_setprio(0); } while (0)
; #define PG8_WAIT_V(n) asm volatile("s_waitcnt vmcnt(" #n ")" ::: "memory")
; #define PG8_WAIT_L(n) asm volatile("s_waitcnt lgkmcnt(" #n ")" ::: "memory")
; #define PG8_BAR __builtin_amdgcn_s_barrier()
; #define PG8_SCHED __builtin_amdgcn_sched_barrier(0)
;     ...
;             PG8_WAIT_V(6); PG8_BAR; PG8_MMA(1, 1, At, B1); PG8_BAR;
;             PG8_LDB(B0, 1, 0); PG8_SCHED; PG8_LDA(At, 1, 0); PG8_STAGE(PG8_SA(0, 1), a2 + hA, voffA);
;             PG8_WAIT_L(8); PG8_BAR; PG8_WAIT_L(0); PG8_MMA(0, 0, At, B0); PG8_BAR; PG8_SCHED;
;             PG8_LDB(B1, 1, 1); PG8_STAGE(PG8_SB(1, 0), b3, voffB);
;             PG8_BAR; PG8_WAIT_L(0); PG8_MMA(0, 1, At, B1); PG8_BAR;
;             PG8_LDA(At, 1, 1); PG8_STAGE(PG8_SA(1, 0), a3, voffA);
;             PG8_BAR; PG8_WAIT_L(0); PG8_MMA(1, 0, At, B0); PG8_BAR; PG8_SCHED;
;             PG8_STAGE(PG8_SB(1, 1), b3 + hB, voffB);
;             PG8_WAIT_V(6); PG8_BAR; PG8_MMA(1, 1, At, B1); PG8_BAR;
	s_add_u32 s42, s14, 0x20000
	s_addc_u32 s43, s15, 0
	s_add_i32 s44, s76, s66
	v_lshl_add_u64 v[140:141], s[42:43], 0, v[130:131]
	s_mov_b32 m0, s44
	s_nop 0
	global_load_lds_dwordx4 v[140:141], off
	v_lshl_add_u64 v[140:141], s[42:43], 0, v[134:135]
	s_add_i32 m0, s44, 0x2000
	s_nop 0
	global_load_lds_dwordx4 v[140:141], off
	s_waitcnt vmcnt(6)
	s_barrier
	s_setprio 1
	v_mfma_f32_16x16x32_bf16 v[52:55], v[202:205], v[170:173], v[52:55]
	v_mfma_f32_16x16x32_bf16 v[48:51], v[210:213], v[170:173], v[48:51]
	v_mfma_f32_16x16x32_bf16 v[36:39], v[202:205], v[178:181], v[36:39]
	v_mfma_f32_16x16x32_bf16 v[32:35], v[210:213], v[178:181], v[32:35]
	v_mfma_f32_16x16x32_bf16 v[20:23], v[202:205], v[186:189], v[20:23]
	v_mfma_f32_16x16x32_bf16 v[16:19], v[210:213], v[186:189], v[16:19]
	v_mfma_f32_16x16x32_bf16 v[4:7], v[202:205], v[194:197], v[4:7]
	v_mfma_f32_16x16x32_bf16 v[0:3], v[210:213], v[194:197], v[0:3]
	v_mfma_f32_16x16x32_bf16 v[52:55], v[206:209], v[174:177], v[52:55]
	v_mfma_f32_16x16x32_bf16 v[48:51], v[214:217], v[174:177], v[48:51]
	v_mfma_f32_16x16x32_bf16 v[36:39], v[206:209], v[182:185], v[36:39]
	v_mfma_f32_16x16x32_bf16 v[32:35], v[214:217], v[182:185], v[32:35]
	v_mfma_f32_16x16x32_bf16 v[20:23], v[206:209], v[190:193], v[20:23]
	v_mfma_f32_16x16x32_bf16 v[16:19], v[214:217], v[190:193], v[16:19]
	v_mfma_f32_16x16x32_bf16 v[4:7], v[206:209], v[198:201], v[4:7]
	v_mfma_f32_16x16x32_bf16 v[0:3], v[214:217], v[198:201], v[0:3]
	s_setprio 0
	s_add_i32 s42, 0, 0x18000
	v_add_u32_e32 v162, s42, v153
	s_barrier
	ds_read_b128 v[140:143], v162
	ds_read_b128 v[146:149], v162 offset:1024
	ds_read_b128 v[158:161], v162 offset:2048
	ds_read_b128 v[162:165], v162 offset:3072
	s_add_u32 s16, s16, 0x20000
	s_addc_u32 s17, s17, 0
	s_mov_b32 m0, s69
	v_lshl_add_u64 v[202:203], s[16:17], 0, v[128:129]
	ds_read_b128 v[170:173], v156 offset:32768
	ds_read_b128 v[174:177], v156 offset:33792
	ds_read_b128 v[178:181], v156 offset:34816
	ds_read_b128 v[182:185], v156 offset:35840
	ds_read_b128 v[186:189], v156 offset:36864
	ds_read_b128 v[190:193], v156 offset:37888
	ds_read_b128 v[194:197], v156 offset:38912
	ds_read_b128 v[198:201], v156 offset:39936
	global_load_lds_dwordx4 v[202:203], off
	v_lshl_add_u64 v[202:203], s[16:17], 0, v[132:133]
	s_mov_b32 m0, s70
	s_nop 0
	global_load_lds_dwordx4 v[202:203], off
	s_waitcnt lgkmcnt(8)
	s_barrier
	s_waitcnt lgkmcnt(0)
	s_setprio 1
	s_waitcnt lgkmcnt(0)
	v_mfma_f32_16x16x32_bf16 v[124:127], v[140:143], v[170:173], v[124:127]
	v_mfma_f32_16x16x32_bf16 v[120:123], v[158:161], v[170:173], v[120:123]
	v_mfma_f32_16x16x32_bf16 v[108:111], v[140:143], v[178:181], v[108:111]
	v_mfma_f32_16x16x32_bf16 v[104:107], v[158:161], v[178:181], v[104:107]
	v_mfma_f32_16x16x32_bf16 v[92:95], v[140:143], v[186:189], v[92:95]
	v_mfma_f32_16x16x32_bf16 v[88:91], v[158:161], v[186:189], v[88:91]
	v_mfma_f32_16x16x32_bf16 v[76:79], v[140:143], v[194:197], v[76:79]
	v_mfma_f32_16x16x32_bf16 v[72:75], v[158:161], v[194:197], v[72:75]
	v_mfma_f32_16x16x32_bf16 v[124:127], v[146:149], v[174:177], v[124:127]
	v_mfma_f32_16x16x32_bf16 v[120:123], v[162:165], v[174:177], v[120:123]
	v_mfma_f32_16x16x32_bf16 v[108:111], v[146:149], v[182:185], v[108:111]
	v_mfma_f32_16x16x32_bf16 v[104:107], v[162:165], v[182:185], v[104:107]
	v_mfma_f32_16x16x32_bf16 v[92:95], v[146:149], v[190:193], v[92:95]
	v_mfma_f32_16x16x32_bf16 v[88:91], v[162:165], v[190:193], v[88:91]
	v_mfma_f32_16x16x32_bf16 v[76:79], v[146:149], v[198:201], v[76:79]
	v_mfma_f32_16x16x32_bf16 v[72:75], v[162:165], v[198:201], v[72:75]
	s_setprio 0
	s_barrier
	s_add_i32 s16, 0, 0x1c000
	s_add_i32 s17, s42, s66
	v_add_u32_e32 v214, s16, v153
	v_lshl_add_u64 v[150:151], v[150:151], 0, s[40:41]
	s_mov_b32 m0, s17
	ds_read_b128 v[202:205], v214
	ds_read_b128 v[206:209], v214 offset:1024
	ds_read_b128 v[210:213], v214 offset:2048
	ds_read_b128 v[214:217], v214 offset:3072
	global_load_lds_dwordx4 v[150:151], off
	v_lshl_add_u64 v[150:151], v[218:219], 0, s[40:41]
	s_add_i32 m0, s17, 0x2000
	s_nop 0
	global_load_lds_dwordx4 v[150:151], off
	s_barrier
	s_waitcnt lgkmcnt(0)
	s_setprio 1
	s_waitcnt lgkmcnt(0)
	v_mfma_f32_16x16x32_bf16 v[116:119], v[202:205], v[170:173], v[116:119]
	v_mfma_f32_16x16x32_bf16 v[112:115], v[210:213], v[170:173], v[112:115]
	v_mfma_f32_16x16x32_bf16 v[100:103], v[202:205], v[178:181], v[100:103]
	v_mfma_f32_16x16x32_bf16 v[96:99], v[210:213], v[178:181], v[96:99]
	v_mfma_f32_16x16x32_bf16 v[84:87], v[202:205], v[186:189], v[84:87]
	v_mfma_f32_16x16x32_bf16 v[80:83], v[210:213], v[186:189], v[80:83]
	v_mfma_f32_16x16x32_bf16 v[68:71], v[202:205], v[194:197], v[68:71]
	v_mfma_f32_16x16x32_bf16 v[64:67], v[210:213], v[194:197], v[64:67]
	v_mfma_f32_16x16x32_bf16 v[116:119], v[206:209], v[174:177], v[116:119]
	v_mfma_f32_16x16x32_bf16 v[112:115], v[214:217], v[174:177], v[112:115]
	v_mfma_f32_16x16x32_bf16 v[100:103], v[206:209], v[182:185], v[100:103]
	v_mfma_f32_16x16x32_bf16 v[96:99], v[214:217], v[182:185], v[96:99]
	v_mfma_f32_16x16x32_bf16 v[84:87], v[206:209], v[190:193], v[84:87]
	v_mfma_f32_16x16x32_bf16 v[80:83], v[214:217], v[190:193], v[80:83]
	v_mfma_f32_16x16x32_bf16 v[68:71], v[206:209], v[198:201], v[68:71]
	v_mfma_f32_16x16x32_bf16 v[64:67], v[214:217], v[198:201], v[64:67]
	s_setprio 0
	s_mov_b32 m0, s72
	v_lshl_add_u64 v[150:151], v[220:221], 0, s[40:41]
	s_barrier
	ds_read_b128 v[170:173], v156 offset:49152
	ds_read_b128 v[174:177], v156 offset:50176
	ds_read_b128 v[178:181], v156 offset:51200
	ds_read_b128 v[182:185], v156 offset:52224
	ds_read_b128 v[186:189], v156 offset:53248
	ds_read_b128 v[190:193], v156 offset:54272
	ds_read_b128 v[194:197], v156 offset:55296
	ds_read_b128 v[198:201], v156 offset:56320
	global_load_lds_dwordx4 v[150:151], off
	v_lshl_add_u64 v[150:151], v[222:223], 0, s[40:41]
	s_mov_b32 m0, s73
	s_nop 0
	global_load_lds_dwordx4 v[150:151], off
	s_barrier
; __device__ __forceinline__ float sigmoidf_(float x) { return 1.0f / (1.0f + __expf(-x)); }
; #define PG8_STAGE(bufoff, gbase, voff) do { _Pragma("unroll") for (int _i = 0; _i < 2; ++_i) \
;         __builtin_amdgcn_global_load_lds((const unsigned*)((const char*)(gbase) + (voff)[_i]), (LAS unsigned*)(lds + (bufoff) + ldsw + _i * 8192), 16, 0, 0); } while (0)
;     ...
;             PG8_WAIT_V(6); PG8_BAR; PG8_MMA(1, 1, At, B1); PG8_BAR;
;             PG8_LDB(B0, 1, 0); PG8_SCHED; PG8_LDA(At, 1, 0); PG8_STAGE(PG8_SA(0, 1), a2 + hA, voffA);
;             PG8_WAIT_L(8); PG8_BAR; PG8_WAIT_L(0); PG8_MMA(0, 0, At, B0); PG8_BAR; PG8_SCHED;
;             PG8_LDB(B1, 1, 1); PG8_STAGE(PG8_SB(1, 0), b3, voffB);
;             PG8_BAR; PG8_WAIT_L(0); PG8_MMA(0, 1, At, B1); PG8_BAR;
;             PG8_LDA(At, 1, 1); PG8_STAGE(PG8_SA(1, 0), a3, voffA);
;             PG8_BAR; PG8_WAIT_L(0); PG8_MMA(1, 0, At, B0); PG8_BAR; PG8_SCHED;
;             PG8_STAGE(PG8_SB(1, 1), b3 + hB, voffB);
;             PG8_WAIT_V(6); PG8_BAR; PG8_MMA(1, 1, At, B1); PG8_BAR;
;         }
;     __device__ __forceinline__ void operator()(const f32x4 (&acc)[2][2][4][2], const Unit& u, int wr, int wc, int fr, int fq) const {
;         const __amdgpu_buffer_rsrc_t rsrc = __builtin_amdgcn_make_buffer_rsrc((void*)z, 0, T_ALL * DIN * 2, 0x00020000);
;         const int row0 = row_off + u.pm * 256 + wr * 64 + fr, col0 = u.pn * 256 + wc * 32 + 8 * fq;
; #pragma unroll
;         for (int ai = 0; ai < 2; ++ai)
; #pragma unroll
;             for (int m = 0; m < 4; ++m) {
;                 const int row = row0 + ai * 128 + m * 16;
;                 const bf16_t* rowp = z + (size_t)row * DIN + col0;
; #pragma unroll
;                 for (int bj = 0; bj < 2; ++bj) {
;                     const u32x4 gw = *(const u32x4*)(rowp + O_GA + bj * 128);
;                     f32x4 g0, g1; unpack8(gw, g0, g1);
;                     f32x4 v0, v1;
; #pragma unroll
;                     for (int j = 0; j < 4; ++j) { v0[j] = sigmoidf_(g0[j]) * acc[ai][bj][m][0][j]; v1[j] = sigmoidf_(g1[j]) * acc[ai][bj][m][1][j]; }
;                     const u32x4 mw = *(const u32x4*)(rowp + bj * 128); f32x4 m0, m1; unpack8(mw, m0, m1); v0 += m0; v1 += m1;
;                     __builtin_amdgcn_raw_buffer_store_b128(pack8(v0, v1), rsrc, (unsigned)(((size_t)row * DIN + col0 + bj * 128) * 2), 0, 16  ); }
	s_waitcnt lgkmcnt(0)
	s_setprio 1
	s_waitcnt lgkmcnt(0)
	v_mfma_f32_16x16x32_bf16 v[60:63], v[140:143], v[170:173], v[60:63]
	v_mfma_f32_16x16x32_bf16 v[56:59], v[158:161], v[170:173], v[56:59]
	v_mfma_f32_16x16x32_bf16 v[44:47], v[140:143], v[178:181], v[44:47]
	v_mfma_f32_16x16x32_bf16 v[40:43], v[158:161], v[178:181], v[40:43]
	v_mfma_f32_16x16x32_bf16 v[28:31], v[140:143], v[186:189], v[28:31]
	v_mfma_f32_16x16x32_bf16 v[24:27], v[158:161], v[186:189], v[24:27]
	v_mfma_f32_16x16x32_bf16 v[12:15], v[140:143], v[194:197], v[12:15]
	v_mfma_f32_16x16x32_bf16 v[8:11], v[158:161], v[194:197], v[8:11]
	v_mfma_f32_16x16x32_bf16 v[60:63], v[146:149], v[174:177], v[60:63]
	v_mfma_f32_16x16x32_bf16 v[56:59], v[162:165], v[174:177], v[56:59]
	v_mfma_f32_16x16x32_bf16 v[44:47], v[146:149], v[182:185], v[44:47]
	v_mfma_f32_16x16x32_bf16 v[40:43], v[162:165], v[182:185], v[40:43]
	v_mfma_f32_16x16x32_bf16 v[28:31], v[146:149], v[190:193], v[28:31]
	v_mfma_f32_16x16x32_bf16 v[24:27], v[162:165], v[190:193], v[24:27]
	v_mfma_f32_16x16x32_bf16 v[12:15], v[146:149], v[198:201], v[12:15]
	v_mfma_f32_16x16x32_bf16 v[8:11], v[162:165], v[198:201], v[8:11]
	s_setprio 0
	s_barrier
	s_add_u32 s14, s14, 0x20080
	s_addc_u32 s15, s15, 0
	s_add_i32 s16, s16, s66
	v_lshl_add_u64 v[140:141], s[14:15], 0, v[130:131]
	s_mov_b32 m0, s16
	s_nop 0
	global_load_lds_dwordx4 v[140:141], off
	v_lshl_add_u64 v[140:141], s[14:15], 0, v[134:135]
	s_add_i32 m0, s16, 0x2000
	s_nop 0
	global_load_lds_dwordx4 v[140:141], off
	s_waitcnt vmcnt(6)
	s_barrier
	s_setprio 1
	v_mfma_f32_16x16x32_bf16 v[52:55], v[202:205], v[170:173], v[52:55]
	v_mfma_f32_16x16x32_bf16 v[48:51], v[210:213], v[170:173], v[48:51]
	v_mfma_f32_16x16x32_bf16 v[36:39], v[202:205], v[178:181], v[36:39]
	v_mfma_f32_16x16x32_bf16 v[32:35], v[210:213], v[178:181], v[32:35]
	v_mfma_f32_16x16x32_bf16 v[20:23], v[202:205], v[186:189], v[20:23]
	v_mfma_f32_16x16x32_bf16 v[16:19], v[210:213], v[186:189], v[16:19]
	v_mfma_f32_16x16x32_bf16 v[4:7], v[202:205], v[194:197], v[4:7]
	v_mfma_f32_16x16x32_bf16 v[0:3], v[210:213], v[194:197], v[0:3]
	v_mfma_f32_16x16x32_bf16 v[52:55], v[206:209], v[174:177], v[52:55]
	v_mfma_f32_16x16x32_bf16 v[48:51], v[214:217], v[174:177], v[48:51]
	v_mfma_f32_16x16x32_bf16 v[36:39], v[206:209], v[182:185], v[36:39]
	v_mfma_f32_16x16x32_bf16 v[32:35], v[214:217], v[182:185], v[32:35]
	v_mfma_f32_16x16x32_bf16 v[20:23], v[206:209], v[190:193], v[20:23]
	v_mfma_f32_16x16x32_bf16 v[16:19], v[214:217], v[190:193], v[16:19]
	v_mfma_f32_16x16x32_bf16 v[4:7], v[206:209], v[198:201], v[4:7]
	v_mfma_f32_16x16x32_bf16 v[0:3], v[214:217], v[198:201], v[0:3]
	s_setprio 0
	s_add_i32 s39, s39, 2
	s_add_u32 s19, s19, 0x100
	s_addc_u32 s33, s33, 0
	s_add_u32 s12, s12, 0x100
	s_addc_u32 s13, s13, 0
	s_cmp_gt_u32 s39, 5
	s_barrier
	s_cbranch_scc0 .LBB0_723
	v_lshl_add_u32 v158, s79, 8, v152
	v_lshl_or_b32 v140, s6, 8, v154
	v_add_u32_e32 v142, 0x4000, v158
	v_ashrrev_i32_e32 v141, 31, v140
	v_mad_i64_i32 v[150:151], s[6:7], v142, s77, 0
	v_lshl_add_u64 v[146:147], v[150:151], 1, s[26:27]
	v_lshlrev_b64 v[142:143], 1, v[140:141]
	v_lshl_add_u64 v[146:147], v[146:147], 0, v[142:143]
	v_add_co_u32_e32 v148, vcc, 0x1000, v146
	s_nop 1
	v_addc_co_u32_e32 v149, vcc, 0, v147, vcc
	v_subrev_u32_e32 v198, s26, v146
	v_add_u32_e32 v199, 0x1200, v198
	global_load_dwordx4 v[200:203], v199, s[26:27]
	v_add_u32_e32 v199, 0x0, v198
	global_load_dwordx4 v[204:207], v199, s[26:27]
	v_add_u32_e32 v199, 0x1300, v198
	global_load_dwordx4 v[208:211], v199, s[26:27]
	v_add_u32_e32 v199, 0x100, v198
	global_load_dwordx4 v[212:215], v199, s[26:27]
	v_add_u32_e32 v199, 0x23200, v198
	global_load_dwordx4 v[232:235], v199, s[26:27]
	v_add_u32_e32 v199, 0x22000, v198
	global_load_dwordx4 v[236:239], v199, s[26:27]
	v_add_u32_e32 v199, 0x23300, v198
	global_load_dwordx4 v[240:243], v199, s[26:27]
	v_add_u32_e32 v199, 0x22100, v198
	global_load_dwordx4 v[244:247], v199, s[26:27]
	v_add_u32_e32 v199, 0x45200, v198
	global_load_dwordx4 v[248:251], v199, s[26:27]
	v_add_u32_e32 v199, 0x44000, v198
	global_load_dwordx4 v[252:255], v199, s[26:27]
	s_waitcnt vmcnt(8)
	v_mov_b32_e32 v160, v200
	v_mov_b32_e32 v161, v201
	v_mov_b32_e32 v162, v202
	v_mov_b32_e32 v163, v203
	v_mov_b32_e32 v170, v204
	v_mov_b32_e32 v171, v205
	v_mov_b32_e32 v172, v206
	v_mov_b32_e32 v173, v207
	v_add_u32_e32 v199, 0x45300, v198
	global_load_dwordx4 v[200:203], v199, s[26:27]
	v_add_u32_e32 v199, 0x44100, v198
	global_load_dwordx4 v[204:207], v199, s[26:27]
	v_lshlrev_b32_e32 v141, 16, v160
	v_and_b32_e32 v151, 0xffff0000, v160
	v_lshlrev_b32_e32 v159, 16, v161
	v_and_b32_e32 v160, 0xffff0000, v161
	v_lshlrev_b32_e32 v161, 16, v162
	v_and_b32_e32 v162, 0xffff0000, v162
	v_mul_f32_e32 v141, 0xbfb8aa3b, v141
	v_mul_f32_e32 v161, 0xbfb8aa3b, v161
	v_mul_f32_e32 v151, 0xbfb8aa3b, v151
	v_mul_f32_e32 v176, 0xbfb8aa3b, v162
	v_mul_f32_e32 v165, 0xbfb8aa3b, v160
	v_exp_f32_e32 v160, v141
	v_exp_f32_e32 v162, v161
	v_exp_f32_e32 v161, v151
	v_lshlrev_b32_e32 v164, 16, v163
	v_mul_f32_e32 v159, 0xbfb8aa3b, v159
	v_mul_f32_e32 v174, 0xbfb8aa3b, v164
	v_exp_f32_e32 v164, v159
	v_exp_f32_e32 v165, v165
	v_and_b32_e32 v163, 0xffff0000, v163
	v_mul_f32_e32 v163, 0xbfb8aa3b, v163
	v_pk_add_f32 v[160:161], v[160:161], 1.0 op_sel_hi:[1,0]
	v_exp_f32_e32 v175, v163
	v_exp_f32_e32 v163, v176
	v_div_scale_f32 v141, s[6:7], v161, v161, 1.0
	v_pk_add_f32 v[164:165], v[164:165], 1.0 op_sel_hi:[1,0]
	v_div_scale_f32 v159, s[6:7], v160, v160, 1.0
	v_rcp_f32_e32 v183, v141
	v_div_scale_f32 v177, s[6:7], v165, v165, 1.0
	v_rcp_f32_e32 v184, v159
	v_div_scale_f32 v179, s[6:7], v164, v164, 1.0
; __device__ __forceinline__ float sigmoidf_(float x) { return 1.0f / (1.0f + __expf(-x)); }
; __device__ __forceinline__ u32x4 pack8(const f32x4 v0, const f32x4 v1) { u32x4 w; w.x = pk2(v0[0], v0[1]); w.y = pk2(v0[2], v0[3]); w.z = pk2(v1[0], v1[1]); w.w = pk2(v1[2], v1[3]); return w; }
; __device__ __forceinline__ void unpack8(const u32x4 w, f32x4& v0, f32x4& v1) { v0 = (f32x4){bflo(w.x), bfhi(w.x), bflo(w.y), bfhi(w.y)}; v1 = (f32x4){bflo(w.z), bfhi(w.z), bflo(w.w), bfhi(w.w)}; }
;     __device__ __forceinline__ void operator()(const f32x4 (&acc)[2][2][4][2], const Unit& u, int wr, int wc, int fr, int fq) const {
;     ...
;                 for (int bj = 0; bj < 2; ++bj) {
;                     const u32x4 gw = *(const u32x4*)(rowp + O_GA + bj * 128);
;                     f32x4 g0, g1; unpack8(gw, g0, g1);
;                     f32x4 v0, v1;
; #pragma unroll
;                     for (int j = 0; j < 4; ++j) { v0[j] = sigmoidf_(g0[j]) * acc[ai][bj][m][0][j]; v1[j] = sigmoidf_(g1[j]) * acc[ai][bj][m][1][j]; }
;                     const u32x4 mw = *(const u32x4*)(rowp + bj * 128); f32x4 m0, m1; unpack8(mw, m0, m1); v0 += m0; v1 += m1;
;                     __builtin_amdgcn_raw_buffer_store_b128(pack8(v0, v1), rsrc, (unsigned)(((size_t)row * DIN + col0 + bj * 128) * 2), 0, 16  ); }
	v_rcp_f32_e32 v185, v177
	v_pk_add_f32 v[162:163], v[162:163], 1.0 op_sel_hi:[1,0]
	v_rcp_f32_e32 v186, v179
	v_div_scale_f32 v181, s[6:7], v163, v163, 1.0
	v_fma_f32 v188, -v141, v183, 1.0
	v_div_scale_f32 v151, vcc, 1.0, v161, 1.0
	v_rcp_f32_e32 v187, v181
	v_fma_f32 v189, -v159, v184, 1.0
	v_fmac_f32_e32 v183, v188, v183
	v_div_scale_f32 v176, s[12:13], 1.0, v160, 1.0
	v_fma_f32 v190, -v177, v185, 1.0
	v_fmac_f32_e32 v184, v189, v184
	v_mul_f32_e32 v188, v151, v183
	v_div_scale_f32 v178, s[14:15], 1.0, v165, 1.0
	v_fma_f32 v191, -v179, v186, 1.0
	v_fmac_f32_e32 v185, v190, v185
	v_mul_f32_e32 v189, v176, v184
	v_fma_f32 v193, -v141, v188, v151
	v_div_scale_f32 v180, s[16:17], 1.0, v164, 1.0
	v_fmac_f32_e32 v186, v191, v186
	v_mul_f32_e32 v190, v178, v185
	v_fma_f32 v194, -v159, v189, v176
	v_fmac_f32_e32 v188, v193, v183
	v_fma_f32 v192, -v181, v187, 1.0
	v_mul_f32_e32 v191, v180, v186
	v_fma_f32 v195, -v177, v190, v178
	v_fmac_f32_e32 v189, v194, v184
	v_fma_f32 v141, -v141, v188, v151
	v_div_scale_f32 v182, s[18:19], 1.0, v163, 1.0
	v_fmac_f32_e32 v187, v192, v187
	v_fma_f32 v196, -v179, v191, v180
	v_fmac_f32_e32 v190, v195, v185
	v_fma_f32 v151, -v159, v189, v176
	v_div_fmas_f32 v141, v141, v183, v188
	s_mov_b64 vcc, s[12:13]
	v_mul_f32_e32 v192, v182, v187
	v_fmac_f32_e32 v191, v196, v186
	v_fma_f32 v159, -v177, v190, v178
	v_div_fixup_f32 v161, v141, v161, 1.0
	v_div_fmas_f32 v141, v151, v184, v189
	s_mov_b64 vcc, s[14:15]
	v_div_scale_f32 v151, s[6:7], v162, v162, 1.0
	v_fma_f32 v197, -v181, v192, v182
	v_fma_f32 v176, -v179, v191, v180
	v_div_fixup_f32 v160, v141, v160, 1.0
	v_div_fmas_f32 v141, v159, v185, v190
	s_mov_b64 vcc, s[16:17]
	v_rcp_f32_e32 v159, v151
	v_fmac_f32_e32 v192, v197, v187
	v_div_fixup_f32 v165, v141, v165, 1.0
	v_div_fmas_f32 v141, v176, v186, v191
	v_div_fixup_f32 v164, v141, v164, 1.0
	v_fma_f32 v141, -v181, v192, v182
	s_mov_b64 vcc, s[18:19]
	v_div_fmas_f32 v141, v141, v187, v192
	v_exp_f32_e32 v174, v174
	v_div_fixup_f32 v163, v141, v163, 1.0
	v_fma_f32 v141, -v151, v159, 1.0
	v_fmac_f32_e32 v159, v141, v159
	v_div_scale_f32 v141, vcc, 1.0, v162, 1.0
	v_mul_f32_e32 v176, v141, v159
	v_fma_f32 v177, -v151, v176, v141
	v_pk_add_f32 v[174:175], v[174:175], 1.0 op_sel_hi:[1,0]
	v_fmac_f32_e32 v176, v177, v159
	v_fma_f32 v141, -v151, v176, v141
	v_div_scale_f32 v151, s[6:7], v175, v175, 1.0
	v_rcp_f32_e32 v177, v151
	v_div_fmas_f32 v141, v141, v159, v176
	v_div_fixup_f32 v162, v141, v162, 1.0
	v_lshlrev_b32_e32 v178, 16, v172
	v_fma_f32 v141, -v151, v177, 1.0
	v_fmac_f32_e32 v177, v141, v177
	v_div_scale_f32 v141, vcc, 1.0, v175, 1.0
	v_mul_f32_e32 v159, v141, v177
	v_fma_f32 v176, -v151, v159, v141
	v_fmac_f32_e32 v159, v176, v177
	v_fma_f32 v141, -v151, v159, v141
	v_div_scale_f32 v151, s[6:7], v174, v174, 1.0
	v_rcp_f32_e32 v176, v151
	v_div_fmas_f32 v141, v141, v177, v159
	v_div_fixup_f32 v175, v141, v175, 1.0
	v_and_b32_e32 v179, 0xffff0000, v172
	v_fma_f32 v141, -v151, v176, 1.0
	v_fmac_f32_e32 v176, v141, v176
	v_div_scale_f32 v141, vcc, 1.0, v174, 1.0
	v_mul_f32_e32 v159, v141, v176
	v_fma_f32 v177, -v151, v159, v141
	v_fmac_f32_e32 v159, v177, v176
	v_fma_f32 v141, -v151, v159, v141
	v_div_fmas_f32 v141, v141, v176, v159
	v_div_fixup_f32 v174, v141, v174, 1.0
	v_lshlrev_b32_e32 v176, 16, v170
	v_and_b32_e32 v177, 0xffff0000, v170
	v_lshlrev_b32_e32 v172, 16, v173
	v_and_b32_e32 v173, 0xffff0000, v173
	v_lshlrev_b32_e32 v170, 16, v171
	v_and_b32_e32 v171, 0xffff0000, v171
	v_pk_fma_f32 v[124:125], v[124:125], v[160:161], v[176:177]
	v_pk_fma_f32 v[160:161], v[122:123], v[174:175], v[172:173]
	v_pk_fma_f32 v[122:123], v[120:121], v[162:163], v[178:179]
	v_add_lshl_u32 v141, v140, v150, 1
	v_pk_fma_f32 v[126:127], v[126:127], v[164:165], v[170:171]
	v_cvt_pk_bf16_f32 v120, v124, v125
	s_nop 0
	v_cvt_pk_bf16_f32 v121, v126, v127
	v_cvt_pk_bf16_f32 v122, v122, v123
	v_cvt_pk_bf16_f32 v123, v160, v161
	buffer_store_dwordx4 v[120:123], v141, s[20:23], 0 offen sc1
	s_nop 0
	s_waitcnt vmcnt(9)
	v_mov_b32_e32 v120, v208
	v_mov_b32_e32 v121, v209
	v_mov_b32_e32 v122, v210
	v_mov_b32_e32 v123, v211
	v_mov_b32_e32 v124, v212
	v_mov_b32_e32 v125, v213
	v_mov_b32_e32 v126, v214
	v_mov_b32_e32 v127, v215
	v_add_u32_e32 v199, 0x67200, v198
	global_load_dwordx4 v[208:211], v199, s[26:27]
	v_add_u32_e32 v199, 0x66000, v198
	global_load_dwordx4 v[212:215], v199, s[26:27]
	v_lshlrev_b32_e32 v146, 16, v120
	v_and_b32_e32 v120, 0xffff0000, v120
	v_lshlrev_b32_e32 v147, 16, v121
	v_and_b32_e32 v121, 0xffff0000, v121
	v_lshlrev_b32_e32 v148, 16, v122
	v_and_b32_e32 v122, 0xffff0000, v122
	v_lshlrev_b32_e32 v149, 16, v123
	v_and_b32_e32 v150, 0xffff0000, v123
	v_mul_f32_e32 v123, 0xbfb8aa3b, v146
	v_mul_f32_e32 v146, 0xbfb8aa3b, v148
	v_mul_f32_e32 v148, 0xbfb8aa3b, v120
	v_mul_f32_e32 v147, 0xbfb8aa3b, v147
	v_mul_f32_e32 v121, 0xbfb8aa3b, v121
	v_mul_f32_e32 v151, 0xbfb8aa3b, v122
	v_exp_f32_e32 v120, v123
	v_exp_f32_e32 v122, v146
	v_exp_f32_e32 v146, v147
	v_exp_f32_e32 v147, v121
	v_exp_f32_e32 v121, v148
	v_mul_f32_e32 v149, 0xbfb8aa3b, v149
	v_exp_f32_e32 v148, v149
	v_exp_f32_e32 v123, v151
	v_pk_add_f32 v[120:121], v[120:121], 1.0 op_sel_hi:[1,0]
	v_pk_add_f32 v[146:147], v[146:147], 1.0 op_sel_hi:[1,0]
	v_div_scale_f32 v149, s[6:7], v121, v121, 1.0
	v_rcp_f32_e32 v159, v149
	v_div_scale_f32 v151, vcc, 1.0, v121, 1.0
	v_div_scale_f32 v160, s[6:7], v120, v120, 1.0
	v_fma_f32 v162, -v149, v159, 1.0
	v_fmac_f32_e32 v159, v162, v159
	v_mul_f32_e32 v162, v151, v159
	v_rcp_f32_e32 v161, v160
	v_fma_f32 v163, -v149, v162, v151
	v_fmac_f32_e32 v162, v163, v159
	v_fma_f32 v149, -v149, v162, v151
	v_div_fmas_f32 v149, v149, v159, v162
; __device__ __forceinline__ float sigmoidf_(float x) { return 1.0f / (1.0f + __expf(-x)); }
; __device__ __forceinline__ u32x4 pack8(const f32x4 v0, const f32x4 v1) { u32x4 w; w.x = pk2(v0[0], v0[1]); w.y = pk2(v0[2], v0[3]); w.z = pk2(v1[0], v1[1]); w.w = pk2(v1[2], v1[3]); return w; }
; __device__ __forceinline__ void unpack8(const u32x4 w, f32x4& v0, f32x4& v1) { v0 = (f32x4){bflo(w.x), bfhi(w.x), bflo(w.y), bfhi(w.y)}; v1 = (f32x4){bflo(w.z), bfhi(w.z), bflo(w.w), bfhi(w.w)}; }
;     __device__ __forceinline__ void operator()(const f32x4 (&acc)[2][2][4][2], const Unit& u, int wr, int wc, int fr, int fq) const {
;     ...
;                 for (int bj = 0; bj < 2; ++bj) {
;                     const u32x4 gw = *(const u32x4*)(rowp + O_GA + bj * 128);
;                     f32x4 g0, g1; unpack8(gw, g0, g1);
;                     f32x4 v0, v1;
; #pragma unroll
;                     for (int j = 0; j < 4; ++j) { v0[j] = sigmoidf_(g0[j]) * acc[ai][bj][m][0][j]; v1[j] = sigmoidf_(g1[j]) * acc[ai][bj][m][1][j]; }
;                     const u32x4 mw = *(const u32x4*)(rowp + bj * 128); f32x4 m0, m1; unpack8(mw, m0, m1); v0 += m0; v1 += m1;
;                     __builtin_amdgcn_raw_buffer_store_b128(pack8(v0, v1), rsrc, (unsigned)(((size_t)row * DIN + col0 + bj * 128) * 2), 0, 16  ); }
	v_div_fixup_f32 v121, v149, v121, 1.0
	v_fma_f32 v149, -v160, v161, 1.0
	v_fmac_f32_e32 v161, v149, v161
	v_div_scale_f32 v149, vcc, 1.0, v120, 1.0
	v_mul_f32_e32 v151, v149, v161
	v_fma_f32 v159, -v160, v151, v149
	v_fmac_f32_e32 v151, v159, v161
	v_div_scale_f32 v159, s[6:7], v147, v147, 1.0
	v_fma_f32 v149, -v160, v151, v149
	v_rcp_f32_e32 v160, v159
	v_div_fmas_f32 v149, v149, v161, v151
	v_div_fixup_f32 v120, v149, v120, 1.0
	v_pk_add_f32 v[122:123], v[122:123], 1.0 op_sel_hi:[1,0]
	v_fma_f32 v149, -v159, v160, 1.0
	v_fmac_f32_e32 v160, v149, v160
	v_div_scale_f32 v149, vcc, 1.0, v147, 1.0
	v_mul_f32_e32 v151, v149, v160
	v_fma_f32 v161, -v159, v151, v149
	v_fmac_f32_e32 v151, v161, v160
	v_fma_f32 v149, -v159, v151, v149
	v_div_scale_f32 v159, s[6:7], v146, v146, 1.0
	v_rcp_f32_e32 v161, v159
	v_div_fmas_f32 v149, v149, v160, v151
	v_div_fixup_f32 v147, v149, v147, 1.0
	v_fma_f32 v149, -v159, v161, 1.0
	v_fmac_f32_e32 v161, v149, v161
	v_div_scale_f32 v149, vcc, 1.0, v146, 1.0
	v_mul_f32_e32 v151, v149, v161
	v_fma_f32 v160, -v159, v151, v149
	v_fmac_f32_e32 v151, v160, v161
	v_fma_f32 v159, -v159, v151, v149
	v_mul_f32_e32 v149, 0xbfb8aa3b, v150
	v_div_scale_f32 v150, s[6:7], v123, v123, 1.0
	v_rcp_f32_e32 v160, v150
	v_div_fmas_f32 v151, v159, v161, v151
	v_div_fixup_f32 v146, v151, v146, 1.0
	v_exp_f32_e32 v149, v149
	v_fma_f32 v151, -v150, v160, 1.0
	v_fmac_f32_e32 v160, v151, v160
	v_div_scale_f32 v151, vcc, 1.0, v123, 1.0
	v_mul_f32_e32 v159, v151, v160
	v_fma_f32 v161, -v150, v159, v151
	v_fmac_f32_e32 v159, v161, v160
	v_fma_f32 v150, -v150, v159, v151
	v_div_scale_f32 v151, s[6:7], v122, v122, 1.0
	v_rcp_f32_e32 v161, v151
	v_div_fmas_f32 v150, v150, v160, v159
	v_div_fixup_f32 v123, v150, v123, 1.0
	v_pk_add_f32 v[148:149], v[148:149], 1.0 op_sel_hi:[1,0]
	v_fma_f32 v150, -v151, v161, 1.0
	v_fmac_f32_e32 v161, v150, v161
	v_div_scale_f32 v150, vcc, 1.0, v122, 1.0
	v_mul_f32_e32 v159, v150, v161
	v_fma_f32 v160, -v151, v159, v150
	v_fmac_f32_e32 v159, v160, v161
	v_fma_f32 v150, -v151, v159, v150
	v_div_scale_f32 v151, s[6:7], v149, v149, 1.0
	v_rcp_f32_e32 v160, v151
	v_div_fmas_f32 v150, v150, v161, v159
	v_div_fixup_f32 v122, v150, v122, 1.0
	v_fma_f32 v150, -v151, v160, 1.0
	v_fmac_f32_e32 v160, v150, v160
	v_div_scale_f32 v150, vcc, 1.0, v149, 1.0
	v_mul_f32_e32 v159, v150, v160
	v_fma_f32 v161, -v151, v159, v150
	v_fmac_f32_e32 v159, v161, v160
	v_fma_f32 v150, -v151, v159, v150
	v_div_scale_f32 v151, s[6:7], v148, v148, 1.0
	v_rcp_f32_e32 v161, v151
	v_div_fmas_f32 v150, v150, v160, v159
	v_div_fixup_f32 v149, v150, v149, 1.0
	v_fma_f32 v150, -v151, v161, 1.0
	v_fmac_f32_e32 v161, v150, v161
	v_div_scale_f32 v150, vcc, 1.0, v148, 1.0
	v_mul_f32_e32 v159, v150, v161
	v_fma_f32 v160, -v151, v159, v150
	v_fmac_f32_e32 v159, v160, v161
	v_fma_f32 v150, -v151, v159, v150
	v_div_fmas_f32 v150, v150, v161, v159
	v_div_fixup_f32 v148, v150, v148, 1.0
	v_lshlrev_b32_e32 v150, 16, v124
	v_and_b32_e32 v151, 0xffff0000, v124
	v_lshlrev_b32_e32 v160, 16, v126
	v_and_b32_e32 v161, 0xffff0000, v126
	v_lshlrev_b32_e32 v126, 16, v127
	v_and_b32_e32 v127, 0xffff0000, v127
	v_lshlrev_b32_e32 v124, 16, v125
	v_and_b32_e32 v125, 0xffff0000, v125
	v_pk_fma_f32 v[116:117], v[116:117], v[120:121], v[150:151]
	v_pk_fma_f32 v[120:121], v[114:115], v[148:149], v[126:127]
	v_pk_fma_f32 v[114:115], v[112:113], v[122:123], v[160:161]
	v_cvt_pk_bf16_f32 v112, v116, v117
	v_pk_fma_f32 v[118:119], v[118:119], v[146:147], v[124:125]
	s_nop 0
	v_cvt_pk_bf16_f32 v113, v118, v119
	v_cvt_pk_bf16_f32 v114, v114, v115
	v_cvt_pk_bf16_f32 v115, v120, v121
	buffer_store_dwordx4 v[112:115], v141, s[20:23], 0 offen offset:256 sc1
	s_nop 1
	v_add_u32_e32 v112, 0x4010, v158
	v_mad_i64_i32 v[114:115], s[6:7], v112, s77, 0
	v_lshl_add_u64 v[112:113], v[114:115], 1, s[26:27]
	v_lshl_add_u64 v[112:113], v[112:113], 0, v[142:143]
	v_add_co_u32_e32 v116, vcc, s78, v112
	s_nop 1
	v_addc_co_u32_e32 v117, vcc, 0, v113, vcc
	s_waitcnt vmcnt(10)
	v_mov_b32_e32 v118, v232
	v_mov_b32_e32 v119, v233
	v_mov_b32_e32 v120, v234
	v_mov_b32_e32 v121, v235
	v_mov_b32_e32 v122, v236
	v_mov_b32_e32 v123, v237
	v_mov_b32_e32 v124, v238
	v_mov_b32_e32 v125, v239
	v_add_u32_e32 v199, 0x67300, v198
	global_load_dwordx4 v[232:235], v199, s[26:27]
	v_add_u32_e32 v199, 0x66100, v198
	global_load_dwordx4 v[236:239], v199, s[26:27]
	v_lshlrev_b32_e32 v115, 16, v118
	v_lshlrev_b32_e32 v127, 16, v119
	v_and_b32_e32 v141, 0xffff0000, v119
	v_lshlrev_b32_e32 v119, 16, v120
	v_mul_f32_e32 v115, 0xbfb8aa3b, v115
	v_and_b32_e32 v126, 0xffff0000, v118
	v_exp_f32_e32 v118, v115
	v_mul_f32_e32 v115, 0xbfb8aa3b, v119
	v_and_b32_e32 v146, 0xffff0000, v120
	v_exp_f32_e32 v120, v115
	v_mul_f32_e32 v115, 0xbfb8aa3b, v126
	v_exp_f32_e32 v119, v115
	v_mul_f32_e32 v115, 0xbfb8aa3b, v146
	v_lshlrev_b32_e32 v147, 16, v121
	v_and_b32_e32 v148, 0xffff0000, v121
	v_exp_f32_e32 v121, v115
	v_mul_f32_e32 v115, 0xbfb8aa3b, v127
	v_exp_f32_e32 v126, v115
	v_mul_f32_e32 v115, 0xbfb8aa3b, v141
	v_pk_add_f32 v[118:119], v[118:119], 1.0 op_sel_hi:[1,0]
	v_exp_f32_e32 v127, v115
	v_div_scale_f32 v115, s[6:7], v119, v119, 1.0
	v_rcp_f32_e32 v141, v115
	v_mul_f32_e32 v146, 0xbfb8aa3b, v147
	v_pk_add_f32 v[126:127], v[126:127], 1.0 op_sel_hi:[1,0]
	v_pk_add_f32 v[120:121], v[120:121], 1.0 op_sel_hi:[1,0]
	v_fma_f32 v147, -v115, v141, 1.0
	v_fmac_f32_e32 v141, v147, v141
	v_div_scale_f32 v147, vcc, 1.0, v119, 1.0
	v_mul_f32_e32 v149, v147, v141
	v_fma_f32 v150, -v115, v149, v147
	v_fmac_f32_e32 v149, v150, v141
	v_fma_f32 v115, -v115, v149, v147
	v_div_scale_f32 v147, s[6:7], v118, v118, 1.0
	v_rcp_f32_e32 v150, v147
; __device__ __forceinline__ float sigmoidf_(float x) { return 1.0f / (1.0f + __expf(-x)); }
; __device__ __forceinline__ u32x4 pack8(const f32x4 v0, const f32x4 v1) { u32x4 w; w.x = pk2(v0[0], v0[1]); w.y = pk2(v0[2], v0[3]); w.z = pk2(v1[0], v1[1]); w.w = pk2(v1[2], v1[3]); return w; }
; __device__ __forceinline__ void unpack8(const u32x4 w, f32x4& v0, f32x4& v1) { v0 = (f32x4){bflo(w.x), bfhi(w.x), bflo(w.y), bfhi(w.y)}; v1 = (f32x4){bflo(w.z), bfhi(w.z), bflo(w.w), bfhi(w.w)}; }
;     __device__ __forceinline__ void operator()(const f32x4 (&acc)[2][2][4][2], const Unit& u, int wr, int wc, int fr, int fq) const {
;     ...
;                 for (int bj = 0; bj < 2; ++bj) {
;                     const u32x4 gw = *(const u32x4*)(rowp + O_GA + bj * 128);
;                     f32x4 g0, g1; unpack8(gw, g0, g1);
;                     f32x4 v0, v1;
; #pragma unroll
;                     for (int j = 0; j < 4; ++j) { v0[j] = sigmoidf_(g0[j]) * acc[ai][bj][m][0][j]; v1[j] = sigmoidf_(g1[j]) * acc[ai][bj][m][1][j]; }
;                     const u32x4 mw = *(const u32x4*)(rowp + bj * 128); f32x4 m0, m1; unpack8(mw, m0, m1); v0 += m0; v1 += m1;
;                     __builtin_amdgcn_raw_buffer_store_b128(pack8(v0, v1), rsrc, (unsigned)(((size_t)row * DIN + col0 + bj * 128) * 2), 0, 16  ); }
	v_div_fmas_f32 v115, v115, v141, v149
	v_div_fixup_f32 v119, v115, v119, 1.0
	v_exp_f32_e32 v146, v146
	v_fma_f32 v115, -v147, v150, 1.0
	v_fmac_f32_e32 v150, v115, v150
	v_div_scale_f32 v115, vcc, 1.0, v118, 1.0
	v_mul_f32_e32 v141, v115, v150
	v_fma_f32 v149, -v147, v141, v115
	v_fmac_f32_e32 v141, v149, v150
	v_fma_f32 v115, -v147, v141, v115
	v_div_scale_f32 v147, s[6:7], v127, v127, 1.0
	v_rcp_f32_e32 v149, v147
	v_div_fmas_f32 v115, v115, v150, v141
	v_div_fixup_f32 v118, v115, v118, 1.0
	v_and_b32_e32 v151, 0xffff0000, v124
	v_fma_f32 v115, -v147, v149, 1.0
	v_fmac_f32_e32 v149, v115, v149
	v_div_scale_f32 v115, vcc, 1.0, v127, 1.0
	v_mul_f32_e32 v141, v115, v149
	v_fma_f32 v150, -v147, v141, v115
	v_fmac_f32_e32 v141, v150, v149
	v_fma_f32 v115, -v147, v141, v115
	v_div_scale_f32 v147, s[6:7], v126, v126, 1.0
	v_rcp_f32_e32 v150, v147
	v_div_fmas_f32 v115, v115, v149, v141
	v_div_fixup_f32 v127, v115, v127, 1.0
	v_fma_f32 v115, -v147, v150, 1.0
	v_fmac_f32_e32 v150, v115, v150
	v_div_scale_f32 v115, vcc, 1.0, v126, 1.0
	v_mul_f32_e32 v141, v115, v150
	v_fma_f32 v149, -v147, v141, v115
	v_fmac_f32_e32 v141, v149, v150
	v_fma_f32 v115, -v147, v141, v115
	v_mul_f32_e32 v147, 0xbfb8aa3b, v148
	v_div_scale_f32 v148, s[6:7], v121, v121, 1.0
	v_rcp_f32_e32 v149, v148
	v_div_fmas_f32 v115, v115, v150, v141
	v_div_fixup_f32 v126, v115, v126, 1.0
	v_exp_f32_e32 v147, v147
	v_fma_f32 v115, -v148, v149, 1.0
	v_fmac_f32_e32 v149, v115, v149
	v_div_scale_f32 v115, vcc, 1.0, v121, 1.0
	v_mul_f32_e32 v141, v115, v149
	v_fma_f32 v150, -v148, v141, v115
	v_fmac_f32_e32 v141, v150, v149
	v_fma_f32 v115, -v148, v141, v115
	v_div_scale_f32 v148, s[6:7], v120, v120, 1.0
	v_rcp_f32_e32 v150, v148
	v_div_fmas_f32 v115, v115, v149, v141
	v_div_fixup_f32 v121, v115, v121, 1.0
	v_pk_add_f32 v[146:147], v[146:147], 1.0 op_sel_hi:[1,0]
	v_fma_f32 v115, -v148, v150, 1.0
	v_fmac_f32_e32 v150, v115, v150
	v_div_scale_f32 v115, vcc, 1.0, v120, 1.0
	v_mul_f32_e32 v141, v115, v150
	v_fma_f32 v149, -v148, v141, v115
	v_fmac_f32_e32 v141, v149, v150
	v_fma_f32 v115, -v148, v141, v115
	v_div_scale_f32 v148, s[6:7], v147, v147, 1.0
	v_rcp_f32_e32 v149, v148
	v_div_fmas_f32 v115, v115, v150, v141
	v_div_fixup_f32 v120, v115, v120, 1.0
	v_fma_f32 v115, -v148, v149, 1.0
	v_fmac_f32_e32 v149, v115, v149
	v_div_scale_f32 v115, vcc, 1.0, v147, 1.0
	v_mul_f32_e32 v141, v115, v149
	v_fma_f32 v150, -v148, v141, v115
	v_fmac_f32_e32 v141, v150, v149
	v_fma_f32 v115, -v148, v141, v115
	v_div_scale_f32 v148, s[6:7], v146, v146, 1.0
	v_rcp_f32_e32 v150, v148
	v_div_fmas_f32 v115, v115, v149, v141
	v_div_fixup_f32 v147, v115, v147, 1.0
	v_fma_f32 v115, -v148, v150, 1.0
	v_fmac_f32_e32 v150, v115, v150
	v_div_scale_f32 v115, vcc, 1.0, v146, 1.0
	v_mul_f32_e32 v141, v115, v150
	v_fma_f32 v149, -v148, v141, v115
	v_fmac_f32_e32 v141, v149, v150
	v_fma_f32 v115, -v148, v141, v115
	v_div_fmas_f32 v115, v115, v150, v141
	v_div_fixup_f32 v146, v115, v146, 1.0
	v_lshlrev_b32_e32 v148, 16, v122
	v_and_b32_e32 v149, 0xffff0000, v122
	v_lshlrev_b32_e32 v150, 16, v124
	v_lshlrev_b32_e32 v124, 16, v125
	v_and_b32_e32 v125, 0xffff0000, v125
	v_lshlrev_b32_e32 v122, 16, v123
	v_and_b32_e32 v123, 0xffff0000, v123
	v_pk_fma_f32 v[108:109], v[108:109], v[118:119], v[148:149]
	v_pk_fma_f32 v[118:119], v[106:107], v[146:147], v[124:125]
	v_pk_fma_f32 v[106:107], v[104:105], v[120:121], v[150:151]
	v_add_lshl_u32 v120, v140, v114, 1
	v_pk_fma_f32 v[110:111], v[110:111], v[126:127], v[122:123]
	v_cvt_pk_bf16_f32 v104, v108, v109
	s_nop 0
	v_cvt_pk_bf16_f32 v105, v110, v111
	v_cvt_pk_bf16_f32 v106, v106, v107
	v_cvt_pk_bf16_f32 v107, v118, v119
	buffer_store_dwordx4 v[104:107], v120, s[20:23], 0 offen sc1
	s_nop 0
	s_waitcnt vmcnt(11)
	v_mov_b32_e32 v104, v240
	v_mov_b32_e32 v105, v241
	v_mov_b32_e32 v106, v242
	v_mov_b32_e32 v107, v243
	v_mov_b32_e32 v108, v244
	v_mov_b32_e32 v109, v245
	v_mov_b32_e32 v110, v246
	v_mov_b32_e32 v111, v247
	v_add_u32_e32 v199, 0x111200, v198
	global_load_dwordx4 v[240:243], v199, s[26:27]
	v_add_u32_e32 v199, 0x110000, v198
	global_load_dwordx4 v[244:247], v199, s[26:27]
	v_lshlrev_b32_e32 v114, 16, v105
	v_and_b32_e32 v115, 0xffff0000, v105
	v_lshlrev_b32_e32 v105, 16, v106
	v_lshlrev_b32_e32 v112, 16, v104
	v_and_b32_e32 v113, 0xffff0000, v104
	v_mul_f32_e32 v105, 0xbfb8aa3b, v105
	v_and_b32_e32 v116, 0xffff0000, v106
	v_mul_f32_e32 v104, 0xbfb8aa3b, v112
	v_exp_f32_e32 v106, v105
	v_mul_f32_e32 v105, 0xbfb8aa3b, v113
	v_exp_f32_e32 v104, v104
	v_exp_f32_e32 v105, v105
	v_mul_f32_e32 v113, 0xbfb8aa3b, v115
	v_lshlrev_b32_e32 v117, 16, v107
	v_and_b32_e32 v118, 0xffff0000, v107
	v_pk_add_f32 v[104:105], v[104:105], 1.0 op_sel_hi:[1,0]
	v_mul_f32_e32 v107, 0xbfb8aa3b, v116
	v_div_scale_f32 v115, s[6:7], v105, v105, 1.0
	v_rcp_f32_e32 v116, v115
	v_mul_f32_e32 v112, 0xbfb8aa3b, v114
	v_mul_f32_e32 v114, 0xbfb8aa3b, v117
	v_exp_f32_e32 v112, v112
	v_fma_f32 v117, -v115, v116, 1.0
	v_fmac_f32_e32 v116, v117, v116
	v_div_scale_f32 v117, vcc, 1.0, v105, 1.0
	v_mul_f32_e32 v119, v117, v116
	v_fma_f32 v121, -v115, v119, v117
	v_fmac_f32_e32 v119, v121, v116
	v_fma_f32 v115, -v115, v119, v117
	v_div_scale_f32 v117, s[6:7], v104, v104, 1.0
	v_rcp_f32_e32 v121, v117
	v_div_fmas_f32 v115, v115, v116, v119
	v_exp_f32_e32 v113, v113
	v_div_fixup_f32 v105, v115, v105, 1.0
	v_fma_f32 v115, -v117, v121, 1.0
	v_fmac_f32_e32 v121, v115, v121
	v_div_scale_f32 v115, vcc, 1.0, v104, 1.0
	v_mul_f32_e32 v116, v115, v121
	v_fma_f32 v119, -v117, v116, v115
	v_pk_add_f32 v[112:113], v[112:113], 1.0 op_sel_hi:[1,0]
	v_fmac_f32_e32 v116, v119, v121
	v_fma_f32 v115, -v117, v116, v115
; __device__ __forceinline__ float sigmoidf_(float x) { return 1.0f / (1.0f + __expf(-x)); }
; __device__ __forceinline__ u32x4 pack8(const f32x4 v0, const f32x4 v1) { u32x4 w; w.x = pk2(v0[0], v0[1]); w.y = pk2(v0[2], v0[3]); w.z = pk2(v1[0], v1[1]); w.w = pk2(v1[2], v1[3]); return w; }
; __device__ __forceinline__ void unpack8(const u32x4 w, f32x4& v0, f32x4& v1) { v0 = (f32x4){bflo(w.x), bfhi(w.x), bflo(w.y), bfhi(w.y)}; v1 = (f32x4){bflo(w.z), bfhi(w.z), bflo(w.w), bfhi(w.w)}; }
;     __device__ __forceinline__ void operator()(const f32x4 (&acc)[2][2][4][2], const Unit& u, int wr, int wc, int fr, int fq) const {
;     ...
;                 const int row = row0 + ai * 128 + m * 16;
;                 const bf16_t* rowp = z + (size_t)row * DIN + col0;
; #pragma unroll
;                 for (int bj = 0; bj < 2; ++bj) {
;                     const u32x4 gw = *(const u32x4*)(rowp + O_GA + bj * 128);
;                     f32x4 g0, g1; unpack8(gw, g0, g1);
;                     f32x4 v0, v1;
; #pragma unroll
;                     for (int j = 0; j < 4; ++j) { v0[j] = sigmoidf_(g0[j]) * acc[ai][bj][m][0][j]; v1[j] = sigmoidf_(g1[j]) * acc[ai][bj][m][1][j]; }
;                     const u32x4 mw = *(const u32x4*)(rowp + bj * 128); f32x4 m0, m1; unpack8(mw, m0, m1); v0 += m0; v1 += m1;
;                     __builtin_amdgcn_raw_buffer_store_b128(pack8(v0, v1), rsrc, (unsigned)(((size_t)row * DIN + col0 + bj * 128) * 2), 0, 16  ); }
	v_div_scale_f32 v117, s[6:7], v113, v113, 1.0
	v_rcp_f32_e32 v119, v117
	v_div_fmas_f32 v115, v115, v121, v116
	v_div_fixup_f32 v104, v115, v104, 1.0
	v_exp_f32_e32 v107, v107
	v_fma_f32 v115, -v117, v119, 1.0
	v_fmac_f32_e32 v119, v115, v119
	v_div_scale_f32 v115, vcc, 1.0, v113, 1.0
	v_mul_f32_e32 v116, v115, v119
	v_fma_f32 v121, -v117, v116, v115
	v_fmac_f32_e32 v116, v121, v119
	v_fma_f32 v115, -v117, v116, v115
	v_div_scale_f32 v117, s[6:7], v112, v112, 1.0
	v_rcp_f32_e32 v121, v117
	v_div_fmas_f32 v115, v115, v119, v116
	v_div_fixup_f32 v113, v115, v113, 1.0
	v_pk_add_f32 v[106:107], v[106:107], 1.0 op_sel_hi:[1,0]
	v_fma_f32 v115, -v117, v121, 1.0
	v_fmac_f32_e32 v121, v115, v121
	v_div_scale_f32 v115, vcc, 1.0, v112, 1.0
	v_mul_f32_e32 v116, v115, v121
	v_fma_f32 v119, -v117, v116, v115
	v_fmac_f32_e32 v116, v119, v121
	v_fma_f32 v117, -v117, v116, v115
	v_mul_f32_e32 v115, 0xbfb8aa3b, v118
	v_div_scale_f32 v118, s[6:7], v107, v107, 1.0
	v_rcp_f32_e32 v119, v118
	v_div_fmas_f32 v116, v117, v121, v116
	v_div_fixup_f32 v112, v116, v112, 1.0
	v_exp_f32_e32 v114, v114
	v_fma_f32 v116, -v118, v119, 1.0
	v_fmac_f32_e32 v119, v116, v119
	v_div_scale_f32 v116, vcc, 1.0, v107, 1.0
	v_mul_f32_e32 v117, v116, v119
	v_fma_f32 v121, -v118, v117, v116
	v_fmac_f32_e32 v117, v121, v119
	v_fma_f32 v116, -v118, v117, v116
	v_div_scale_f32 v118, s[6:7], v106, v106, 1.0
	v_rcp_f32_e32 v121, v118
	v_div_fmas_f32 v116, v116, v119, v117
	v_exp_f32_e32 v115, v115
	v_div_fixup_f32 v107, v116, v107, 1.0
	v_fma_f32 v116, -v118, v121, 1.0
	v_fmac_f32_e32 v121, v116, v121
	v_div_scale_f32 v116, vcc, 1.0, v106, 1.0
	v_mul_f32_e32 v117, v116, v121
	v_fma_f32 v119, -v118, v117, v116
	v_pk_add_f32 v[114:115], v[114:115], 1.0 op_sel_hi:[1,0]
	v_fmac_f32_e32 v117, v119, v121
	v_fma_f32 v116, -v118, v117, v116
	v_div_scale_f32 v118, s[6:7], v115, v115, 1.0
	v_rcp_f32_e32 v119, v118
	v_div_fmas_f32 v116, v116, v121, v117
	v_div_fixup_f32 v106, v116, v106, 1.0
	v_fma_f32 v116, -v118, v119, 1.0
	v_fmac_f32_e32 v119, v116, v119
	v_div_scale_f32 v116, vcc, 1.0, v115, 1.0
	v_mul_f32_e32 v117, v116, v119
	v_fma_f32 v121, -v118, v117, v116
	v_fmac_f32_e32 v117, v121, v119
	v_fma_f32 v116, -v118, v117, v116
	v_div_scale_f32 v118, s[6:7], v114, v114, 1.0
	v_rcp_f32_e32 v121, v118
	v_div_fmas_f32 v116, v116, v119, v117
	v_div_fixup_f32 v115, v116, v115, 1.0
	v_fma_f32 v116, -v118, v121, 1.0
	v_fmac_f32_e32 v121, v116, v121
	v_div_scale_f32 v116, vcc, 1.0, v114, 1.0
	v_mul_f32_e32 v117, v116, v121
	v_fma_f32 v119, -v118, v117, v116
	v_fmac_f32_e32 v117, v119, v121
	v_fma_f32 v116, -v118, v117, v116
	v_div_fmas_f32 v116, v116, v121, v117
	v_div_fixup_f32 v114, v116, v114, 1.0
	v_lshlrev_b32_e32 v116, 16, v108
	v_and_b32_e32 v117, 0xffff0000, v108
	v_lshlrev_b32_e32 v118, 16, v110
	v_and_b32_e32 v119, 0xffff0000, v110
	v_lshlrev_b32_e32 v110, 16, v111
	v_and_b32_e32 v111, 0xffff0000, v111
	v_lshlrev_b32_e32 v108, 16, v109
	v_and_b32_e32 v109, 0xffff0000, v109
	v_pk_fma_f32 v[100:101], v[100:101], v[104:105], v[116:117]
	v_pk_fma_f32 v[104:105], v[98:99], v[114:115], v[110:111]
	v_pk_fma_f32 v[98:99], v[96:97], v[106:107], v[118:119]
	v_cvt_pk_bf16_f32 v96, v100, v101
	v_pk_fma_f32 v[102:103], v[102:103], v[112:113], v[108:109]
	s_nop 0
	v_cvt_pk_bf16_f32 v97, v102, v103
	v_cvt_pk_bf16_f32 v98, v98, v99
	v_cvt_pk_bf16_f32 v99, v104, v105
	buffer_store_dwordx4 v[96:99], v120, s[20:23], 0 offen offset:256 sc1
	s_nop 1
	v_add_u32_e32 v96, 0x4020, v158
	v_mad_i64_i32 v[98:99], s[6:7], v96, s77, 0
	v_lshl_add_u64 v[96:97], v[98:99], 1, s[26:27]
	v_lshl_add_u64 v[96:97], v[96:97], 0, v[142:143]
	v_add_co_u32_e32 v100, vcc, s78, v96
	s_nop 1
	v_addc_co_u32_e32 v101, vcc, 0, v97, vcc
	s_waitcnt vmcnt(12)
	v_mov_b32_e32 v102, v248
	v_mov_b32_e32 v103, v249
	v_mov_b32_e32 v104, v250
	v_mov_b32_e32 v105, v251
	v_mov_b32_e32 v106, v252
	v_mov_b32_e32 v107, v253
	v_mov_b32_e32 v108, v254
	v_mov_b32_e32 v109, v255
	v_add_u32_e32 v199, 0x111300, v198
	global_load_dwordx4 v[248:251], v199, s[26:27]
	v_add_u32_e32 v199, 0x110100, v198
	global_load_dwordx4 v[252:255], v199, s[26:27]
	v_lshlrev_b32_e32 v99, 16, v102
	v_lshlrev_b32_e32 v111, 16, v103
	v_and_b32_e32 v112, 0xffff0000, v103
	v_lshlrev_b32_e32 v103, 16, v104
	v_mul_f32_e32 v99, 0xbfb8aa3b, v99
	v_and_b32_e32 v110, 0xffff0000, v102
	v_exp_f32_e32 v102, v99
	v_mul_f32_e32 v99, 0xbfb8aa3b, v103
	v_and_b32_e32 v113, 0xffff0000, v104
	v_exp_f32_e32 v104, v99
	v_mul_f32_e32 v99, 0xbfb8aa3b, v110
	v_exp_f32_e32 v103, v99
	v_mul_f32_e32 v99, 0xbfb8aa3b, v113
	v_lshlrev_b32_e32 v114, 16, v105
	v_and_b32_e32 v115, 0xffff0000, v105
	v_exp_f32_e32 v105, v99
	v_mul_f32_e32 v99, 0xbfb8aa3b, v111
	v_exp_f32_e32 v110, v99
	v_mul_f32_e32 v99, 0xbfb8aa3b, v112
	v_pk_add_f32 v[102:103], v[102:103], 1.0 op_sel_hi:[1,0]
	v_exp_f32_e32 v111, v99
	v_div_scale_f32 v99, s[6:7], v103, v103, 1.0
	v_rcp_f32_e32 v113, v99
	v_mul_f32_e32 v112, 0xbfb8aa3b, v114
	v_pk_add_f32 v[110:111], v[110:111], 1.0 op_sel_hi:[1,0]
	v_pk_add_f32 v[104:105], v[104:105], 1.0 op_sel_hi:[1,0]
	v_fma_f32 v114, -v99, v113, 1.0
	v_fmac_f32_e32 v113, v114, v113
	v_div_scale_f32 v114, vcc, 1.0, v103, 1.0
	v_mul_f32_e32 v116, v114, v113
	v_fma_f32 v117, -v99, v116, v114
	v_fmac_f32_e32 v116, v117, v113
	v_fma_f32 v99, -v99, v116, v114
	v_div_scale_f32 v114, s[6:7], v102, v102, 1.0
	v_rcp_f32_e32 v117, v114
	v_div_fmas_f32 v99, v99, v113, v116
	v_div_fixup_f32 v103, v99, v103, 1.0
	v_exp_f32_e32 v112, v112
	v_fma_f32 v99, -v114, v117, 1.0
	v_fmac_f32_e32 v117, v99, v117
	v_div_scale_f32 v99, vcc, 1.0, v102, 1.0
	v_mul_f32_e32 v113, v99, v117
	v_fma_f32 v116, -v114, v113, v99
; __device__ __forceinline__ float sigmoidf_(float x) { return 1.0f / (1.0f + __expf(-x)); }
; __device__ __forceinline__ u32x4 pack8(const f32x4 v0, const f32x4 v1) { u32x4 w; w.x = pk2(v0[0], v0[1]); w.y = pk2(v0[2], v0[3]); w.z = pk2(v1[0], v1[1]); w.w = pk2(v1[2], v1[3]); return w; }
; __device__ __forceinline__ void unpack8(const u32x4 w, f32x4& v0, f32x4& v1) { v0 = (f32x4){bflo(w.x), bfhi(w.x), bflo(w.y), bfhi(w.y)}; v1 = (f32x4){bflo(w.z), bfhi(w.z), bflo(w.w), bfhi(w.w)}; }
;     __device__ __forceinline__ void operator()(const f32x4 (&acc)[2][2][4][2], const Unit& u, int wr, int wc, int fr, int fq) const {
;     ...
;                 const int row = row0 + ai * 128 + m * 16;
;                 const bf16_t* rowp = z + (size_t)row * DIN + col0;
; #pragma unroll
;                 for (int bj = 0; bj < 2; ++bj) {
;                     const u32x4 gw = *(const u32x4*)(rowp + O_GA + bj * 128);
;                     f32x4 g0, g1; unpack8(gw, g0, g1);
;                     f32x4 v0, v1;
; #pragma unroll
;                     for (int j = 0; j < 4; ++j) { v0[j] = sigmoidf_(g0[j]) * acc[ai][bj][m][0][j]; v1[j] = sigmoidf_(g1[j]) * acc[ai][bj][m][1][j]; }
;                     const u32x4 mw = *(const u32x4*)(rowp + bj * 128); f32x4 m0, m1; unpack8(mw, m0, m1); v0 += m0; v1 += m1;
;                     __builtin_amdgcn_raw_buffer_store_b128(pack8(v0, v1), rsrc, (unsigned)(((size_t)row * DIN + col0 + bj * 128) * 2), 0, 16  ); }
	v_fmac_f32_e32 v113, v116, v117
	v_fma_f32 v99, -v114, v113, v99
	v_div_scale_f32 v114, s[6:7], v111, v111, 1.0
	v_rcp_f32_e32 v116, v114
	v_div_fmas_f32 v99, v99, v117, v113
	v_div_fixup_f32 v102, v99, v102, 1.0
	v_fma_f32 v99, -v114, v116, 1.0
	v_fmac_f32_e32 v116, v99, v116
	v_div_scale_f32 v99, vcc, 1.0, v111, 1.0
	v_mul_f32_e32 v113, v99, v116
	v_fma_f32 v117, -v114, v113, v99
	v_fmac_f32_e32 v113, v117, v116
	v_fma_f32 v99, -v114, v113, v99
	v_div_scale_f32 v114, s[6:7], v110, v110, 1.0
	v_rcp_f32_e32 v117, v114
	v_div_fmas_f32 v99, v99, v116, v113
	v_div_fixup_f32 v111, v99, v111, 1.0
	v_fma_f32 v99, -v114, v117, 1.0
	v_fmac_f32_e32 v117, v99, v117
	v_div_scale_f32 v99, vcc, 1.0, v110, 1.0
	v_mul_f32_e32 v116, v99, v117
	v_fma_f32 v113, -v114, v116, v99
	v_fmac_f32_e32 v116, v113, v117
	v_fma_f32 v99, -v114, v116, v99
	v_div_scale_f32 v114, s[6:7], v105, v105, 1.0
	v_mul_f32_e32 v113, 0xbfb8aa3b, v115
	v_rcp_f32_e32 v115, v114
	v_div_fmas_f32 v99, v99, v117, v116
	v_div_fixup_f32 v110, v99, v110, 1.0
	v_exp_f32_e32 v113, v113
	v_fma_f32 v99, -v114, v115, 1.0
	v_fmac_f32_e32 v115, v99, v115
	v_div_scale_f32 v99, vcc, 1.0, v105, 1.0
	v_mul_f32_e32 v116, v99, v115
	v_fma_f32 v117, -v114, v116, v99
	v_fmac_f32_e32 v116, v117, v115
	v_fma_f32 v99, -v114, v116, v99
	v_div_scale_f32 v114, s[6:7], v104, v104, 1.0
	v_rcp_f32_e32 v117, v114
	v_div_fmas_f32 v99, v99, v115, v116
	v_div_fixup_f32 v105, v99, v105, 1.0
	v_pk_add_f32 v[112:113], v[112:113], 1.0 op_sel_hi:[1,0]
	v_fma_f32 v99, -v114, v117, 1.0
	v_fmac_f32_e32 v117, v99, v117
	v_div_scale_f32 v99, vcc, 1.0, v104, 1.0
	v_mul_f32_e32 v115, v99, v117
	v_fma_f32 v116, -v114, v115, v99
	v_fmac_f32_e32 v115, v116, v117
	v_fma_f32 v99, -v114, v115, v99
	v_div_scale_f32 v114, s[6:7], v113, v113, 1.0
	v_rcp_f32_e32 v116, v114
	v_div_fmas_f32 v99, v99, v117, v115
	v_div_fixup_f32 v104, v99, v104, 1.0
	v_fma_f32 v99, -v114, v116, 1.0
	v_fmac_f32_e32 v116, v99, v116
	v_div_scale_f32 v99, vcc, 1.0, v113, 1.0
	v_mul_f32_e32 v115, v99, v116
	v_fma_f32 v117, -v114, v115, v99
	v_fmac_f32_e32 v115, v117, v116
	v_fma_f32 v99, -v114, v115, v99
	v_div_scale_f32 v114, s[6:7], v112, v112, 1.0
	v_rcp_f32_e32 v117, v114
	v_div_fmas_f32 v99, v99, v116, v115
	v_div_fixup_f32 v113, v99, v113, 1.0
	v_fma_f32 v99, -v114, v117, 1.0
	v_fmac_f32_e32 v117, v99, v117
	v_div_scale_f32 v99, vcc, 1.0, v112, 1.0
	v_mul_f32_e32 v115, v99, v117
	v_fma_f32 v116, -v114, v115, v99
	v_fmac_f32_e32 v115, v116, v117
	v_fma_f32 v99, -v114, v115, v99
	v_div_fmas_f32 v99, v99, v117, v115
	v_div_fixup_f32 v112, v99, v112, 1.0
	v_lshlrev_b32_e32 v114, 16, v106
	v_and_b32_e32 v115, 0xffff0000, v106
	v_lshlrev_b32_e32 v116, 16, v108
	v_and_b32_e32 v117, 0xffff0000, v108
	v_lshlrev_b32_e32 v108, 16, v109
	v_and_b32_e32 v109, 0xffff0000, v109
	v_lshlrev_b32_e32 v106, 16, v107
	v_and_b32_e32 v107, 0xffff0000, v107
	v_pk_fma_f32 v[92:93], v[92:93], v[102:103], v[114:115]
	v_pk_fma_f32 v[102:103], v[90:91], v[112:113], v[108:109]
	v_pk_fma_f32 v[90:91], v[88:89], v[104:105], v[116:117]
	v_add_lshl_u32 v104, v140, v98, 1
	v_pk_fma_f32 v[94:95], v[94:95], v[110:111], v[106:107]
	v_cvt_pk_bf16_f32 v88, v92, v93
	s_nop 0
	v_cvt_pk_bf16_f32 v89, v94, v95
	v_cvt_pk_bf16_f32 v90, v90, v91
	v_cvt_pk_bf16_f32 v91, v102, v103
	buffer_store_dwordx4 v[88:91], v104, s[20:23], 0 offen sc1
	s_nop 0
	s_waitcnt vmcnt(13)
	v_mov_b32_e32 v88, v200
	v_mov_b32_e32 v89, v201
	v_mov_b32_e32 v90, v202
	v_mov_b32_e32 v91, v203
	v_mov_b32_e32 v92, v204
	v_mov_b32_e32 v93, v205
	v_mov_b32_e32 v94, v206
	v_mov_b32_e32 v95, v207
	v_add_u32_e32 v199, 0x133200, v198
	global_load_dwordx4 v[200:203], v199, s[26:27]
	v_add_u32_e32 v199, 0x132000, v198
	global_load_dwordx4 v[204:207], v199, s[26:27]
	v_lshlrev_b32_e32 v98, 16, v89
	v_and_b32_e32 v99, 0xffff0000, v89
	v_lshlrev_b32_e32 v89, 16, v90
	v_lshlrev_b32_e32 v96, 16, v88
	v_and_b32_e32 v97, 0xffff0000, v88
	v_mul_f32_e32 v89, 0xbfb8aa3b, v89
	v_and_b32_e32 v100, 0xffff0000, v90
	v_mul_f32_e32 v88, 0xbfb8aa3b, v96
	v_exp_f32_e32 v90, v89
	v_mul_f32_e32 v89, 0xbfb8aa3b, v97
	v_exp_f32_e32 v88, v88
	v_exp_f32_e32 v89, v89
	v_mul_f32_e32 v97, 0xbfb8aa3b, v99
	v_lshlrev_b32_e32 v101, 16, v91
	v_and_b32_e32 v102, 0xffff0000, v91
	v_pk_add_f32 v[88:89], v[88:89], 1.0 op_sel_hi:[1,0]
	v_mul_f32_e32 v91, 0xbfb8aa3b, v100
	v_div_scale_f32 v99, s[6:7], v89, v89, 1.0
	v_rcp_f32_e32 v100, v99
	v_mul_f32_e32 v96, 0xbfb8aa3b, v98
	v_mul_f32_e32 v98, 0xbfb8aa3b, v101
	v_exp_f32_e32 v96, v96
	v_fma_f32 v101, -v99, v100, 1.0
	v_fmac_f32_e32 v100, v101, v100
	v_div_scale_f32 v101, vcc, 1.0, v89, 1.0
	v_mul_f32_e32 v103, v101, v100
	v_fma_f32 v105, -v99, v103, v101
	v_fmac_f32_e32 v103, v105, v100
	v_fma_f32 v99, -v99, v103, v101
	v_div_scale_f32 v101, s[6:7], v88, v88, 1.0
	v_rcp_f32_e32 v105, v101
	v_div_fmas_f32 v99, v99, v100, v103
	v_exp_f32_e32 v97, v97
	v_div_fixup_f32 v89, v99, v89, 1.0
	v_fma_f32 v99, -v101, v105, 1.0
	v_fmac_f32_e32 v105, v99, v105
	v_div_scale_f32 v99, vcc, 1.0, v88, 1.0
	v_mul_f32_e32 v100, v99, v105
	v_fma_f32 v103, -v101, v100, v99
	v_pk_add_f32 v[96:97], v[96:97], 1.0 op_sel_hi:[1,0]
	v_fmac_f32_e32 v100, v103, v105
	v_fma_f32 v99, -v101, v100, v99
	v_div_scale_f32 v101, s[6:7], v97, v97, 1.0
	v_rcp_f32_e32 v103, v101
	v_div_fmas_f32 v99, v99, v105, v100
	v_div_fixup_f32 v88, v99, v88, 1.0
	v_exp_f32_e32 v91, v91
	v_fma_f32 v99, -v101, v103, 1.0
	v_fmac_f32_e32 v103, v99, v103
	v_div_scale_f32 v99, vcc, 1.0, v97, 1.0
	v_mul_f32_e32 v100, v99, v103
	v_fma_f32 v105, -v101, v100, v99
	v_fmac_f32_e32 v100, v105, v103
	v_fma_f32 v99, -v101, v100, v99
	v_div_scale_f32 v101, s[6:7], v96, v96, 1.0
; __device__ __forceinline__ float sigmoidf_(float x) { return 1.0f / (1.0f + __expf(-x)); }
; __device__ __forceinline__ u32x4 pack8(const f32x4 v0, const f32x4 v1) { u32x4 w; w.x = pk2(v0[0], v0[1]); w.y = pk2(v0[2], v0[3]); w.z = pk2(v1[0], v1[1]); w.w = pk2(v1[2], v1[3]); return w; }
; __device__ __forceinline__ void unpack8(const u32x4 w, f32x4& v0, f32x4& v1) { v0 = (f32x4){bflo(w.x), bfhi(w.x), bflo(w.y), bfhi(w.y)}; v1 = (f32x4){bflo(w.z), bfhi(w.z), bflo(w.w), bfhi(w.w)}; }
;     __device__ __forceinline__ void operator()(const f32x4 (&acc)[2][2][4][2], const Unit& u, int wr, int wc, int fr, int fq) const {
;     ...
;                 const int row = row0 + ai * 128 + m * 16;
;                 const bf16_t* rowp = z + (size_t)row * DIN + col0;
; #pragma unroll
;                 for (int bj = 0; bj < 2; ++bj) {
;                     const u32x4 gw = *(const u32x4*)(rowp + O_GA + bj * 128);
;                     f32x4 g0, g1; unpack8(gw, g0, g1);
;                     f32x4 v0, v1;
; #pragma unroll
;                     for (int j = 0; j < 4; ++j) { v0[j] = sigmoidf_(g0[j]) * acc[ai][bj][m][0][j]; v1[j] = sigmoidf_(g1[j]) * acc[ai][bj][m][1][j]; }
;                     const u32x4 mw = *(const u32x4*)(rowp + bj * 128); f32x4 m0, m1; unpack8(mw, m0, m1); v0 += m0; v1 += m1;
;                     __builtin_amdgcn_raw_buffer_store_b128(pack8(v0, v1), rsrc, (unsigned)(((size_t)row * DIN + col0 + bj * 128) * 2), 0, 16  ); }
	v_rcp_f32_e32 v105, v101
	v_div_fmas_f32 v99, v99, v103, v100
	v_div_fixup_f32 v97, v99, v97, 1.0
	v_pk_add_f32 v[90:91], v[90:91], 1.0 op_sel_hi:[1,0]
	v_fma_f32 v99, -v101, v105, 1.0
	v_fmac_f32_e32 v105, v99, v105
	v_div_scale_f32 v99, vcc, 1.0, v96, 1.0
	v_mul_f32_e32 v100, v99, v105
	v_fma_f32 v103, -v101, v100, v99
	v_fmac_f32_e32 v100, v103, v105
	v_fma_f32 v101, -v101, v100, v99
	v_mul_f32_e32 v99, 0xbfb8aa3b, v102
	v_div_scale_f32 v102, s[6:7], v91, v91, 1.0
	v_rcp_f32_e32 v103, v102
	v_div_fmas_f32 v100, v101, v105, v100
	v_div_fixup_f32 v96, v100, v96, 1.0
	v_exp_f32_e32 v98, v98
	v_fma_f32 v100, -v102, v103, 1.0
	v_fmac_f32_e32 v103, v100, v103
	v_div_scale_f32 v100, vcc, 1.0, v91, 1.0
	v_mul_f32_e32 v101, v100, v103
	v_fma_f32 v105, -v102, v101, v100
	v_fmac_f32_e32 v101, v105, v103
	v_fma_f32 v100, -v102, v101, v100
	v_div_scale_f32 v102, s[6:7], v90, v90, 1.0
	v_rcp_f32_e32 v105, v102
	v_div_fmas_f32 v100, v100, v103, v101
	v_exp_f32_e32 v99, v99
	v_div_fixup_f32 v91, v100, v91, 1.0
	v_fma_f32 v100, -v102, v105, 1.0
	v_fmac_f32_e32 v105, v100, v105
	v_div_scale_f32 v100, vcc, 1.0, v90, 1.0
	v_mul_f32_e32 v101, v100, v105
	v_fma_f32 v103, -v102, v101, v100
	v_pk_add_f32 v[98:99], v[98:99], 1.0 op_sel_hi:[1,0]
	v_fmac_f32_e32 v101, v103, v105
	v_fma_f32 v100, -v102, v101, v100
	v_div_scale_f32 v102, s[6:7], v99, v99, 1.0
	v_rcp_f32_e32 v103, v102
	v_div_fmas_f32 v100, v100, v105, v101
	v_div_fixup_f32 v90, v100, v90, 1.0
	v_fma_f32 v100, -v102, v103, 1.0
	v_fmac_f32_e32 v103, v100, v103
	v_div_scale_f32 v100, vcc, 1.0, v99, 1.0
	v_mul_f32_e32 v101, v100, v103
	v_fma_f32 v105, -v102, v101, v100
	v_fmac_f32_e32 v101, v105, v103
	v_fma_f32 v100, -v102, v101, v100
	v_div_scale_f32 v102, s[6:7], v98, v98, 1.0
	v_rcp_f32_e32 v105, v102
	v_div_fmas_f32 v100, v100, v103, v101
	v_div_fixup_f32 v99, v100, v99, 1.0
	v_fma_f32 v100, -v102, v105, 1.0
	v_fmac_f32_e32 v105, v100, v105
	v_div_scale_f32 v100, vcc, 1.0, v98, 1.0
	v_mul_f32_e32 v101, v100, v105
	v_fma_f32 v103, -v102, v101, v100
	v_fmac_f32_e32 v101, v103, v105
	v_fma_f32 v100, -v102, v101, v100
	v_div_fmas_f32 v100, v100, v105, v101
	v_div_fixup_f32 v98, v100, v98, 1.0
	v_lshlrev_b32_e32 v100, 16, v92
	v_and_b32_e32 v101, 0xffff0000, v92
	v_lshlrev_b32_e32 v102, 16, v94
	v_and_b32_e32 v103, 0xffff0000, v94
	v_lshlrev_b32_e32 v94, 16, v95
	v_and_b32_e32 v95, 0xffff0000, v95
	v_lshlrev_b32_e32 v92, 16, v93
	v_and_b32_e32 v93, 0xffff0000, v93
	v_pk_fma_f32 v[84:85], v[84:85], v[88:89], v[100:101]
	v_pk_fma_f32 v[88:89], v[82:83], v[98:99], v[94:95]
	v_pk_fma_f32 v[82:83], v[80:81], v[90:91], v[102:103]
	v_cvt_pk_bf16_f32 v80, v84, v85
	v_pk_fma_f32 v[86:87], v[86:87], v[96:97], v[92:93]
	s_nop 0
	v_cvt_pk_bf16_f32 v81, v86, v87
	v_cvt_pk_bf16_f32 v82, v82, v83
	v_cvt_pk_bf16_f32 v83, v88, v89
	buffer_store_dwordx4 v[80:83], v104, s[20:23], 0 offen offset:256 sc1
	s_nop 1
	v_add_u32_e32 v80, 0x4030, v158
	v_mad_i64_i32 v[82:83], s[6:7], v80, s77, 0
	v_lshl_add_u64 v[80:81], v[82:83], 1, s[26:27]
	v_lshl_add_u64 v[80:81], v[80:81], 0, v[142:143]
	v_add_co_u32_e32 v84, vcc, s78, v80
	s_nop 1
	v_addc_co_u32_e32 v85, vcc, 0, v81, vcc
	s_waitcnt vmcnt(13)
	v_mov_b32_e32 v86, v208
	v_mov_b32_e32 v87, v209
	v_mov_b32_e32 v88, v210
	v_mov_b32_e32 v89, v211
	v_mov_b32_e32 v90, v212
	v_mov_b32_e32 v91, v213
	v_mov_b32_e32 v92, v214
	v_mov_b32_e32 v93, v215
	v_add_u32_e32 v199, 0x133300, v198
	global_load_dwordx4 v[208:211], v199, s[26:27]
	v_add_u32_e32 v199, 0x132100, v198
	global_load_dwordx4 v[212:215], v199, s[26:27]
	v_lshlrev_b32_e32 v83, 16, v86
	v_lshlrev_b32_e32 v95, 16, v87
	v_and_b32_e32 v96, 0xffff0000, v87
	v_lshlrev_b32_e32 v87, 16, v88
	v_mul_f32_e32 v83, 0xbfb8aa3b, v83
	v_and_b32_e32 v94, 0xffff0000, v86
	v_exp_f32_e32 v86, v83
	v_mul_f32_e32 v83, 0xbfb8aa3b, v87
	v_and_b32_e32 v97, 0xffff0000, v88
	v_exp_f32_e32 v88, v83
	v_mul_f32_e32 v83, 0xbfb8aa3b, v94
	v_exp_f32_e32 v87, v83
	v_mul_f32_e32 v83, 0xbfb8aa3b, v97
	v_lshlrev_b32_e32 v98, 16, v89
	v_and_b32_e32 v99, 0xffff0000, v89
	v_exp_f32_e32 v89, v83
	v_mul_f32_e32 v83, 0xbfb8aa3b, v95
	v_exp_f32_e32 v94, v83
	v_mul_f32_e32 v83, 0xbfb8aa3b, v96
	v_pk_add_f32 v[86:87], v[86:87], 1.0 op_sel_hi:[1,0]
	v_exp_f32_e32 v95, v83
	v_div_scale_f32 v83, s[6:7], v87, v87, 1.0
	v_rcp_f32_e32 v97, v83
	v_mul_f32_e32 v96, 0xbfb8aa3b, v98
	v_pk_add_f32 v[94:95], v[94:95], 1.0 op_sel_hi:[1,0]
	v_pk_add_f32 v[88:89], v[88:89], 1.0 op_sel_hi:[1,0]
	v_fma_f32 v98, -v83, v97, 1.0
	v_fmac_f32_e32 v97, v98, v97
	v_div_scale_f32 v98, vcc, 1.0, v87, 1.0
	v_mul_f32_e32 v100, v98, v97
	v_fma_f32 v101, -v83, v100, v98
	v_fmac_f32_e32 v100, v101, v97
	v_fma_f32 v83, -v83, v100, v98
	v_div_scale_f32 v98, s[6:7], v86, v86, 1.0
	v_rcp_f32_e32 v101, v98
	v_div_fmas_f32 v83, v83, v97, v100
	v_div_fixup_f32 v87, v83, v87, 1.0
	v_exp_f32_e32 v96, v96
	v_fma_f32 v83, -v98, v101, 1.0
	v_fmac_f32_e32 v101, v83, v101
	v_div_scale_f32 v83, vcc, 1.0, v86, 1.0
	v_mul_f32_e32 v97, v83, v101
	v_fma_f32 v100, -v98, v97, v83
	v_fmac_f32_e32 v97, v100, v101
	v_fma_f32 v83, -v98, v97, v83
	v_div_scale_f32 v98, s[6:7], v95, v95, 1.0
	v_rcp_f32_e32 v100, v98
	v_div_fmas_f32 v83, v83, v101, v97
	v_div_fixup_f32 v86, v83, v86, 1.0
	v_fma_f32 v83, -v98, v100, 1.0
	v_fmac_f32_e32 v100, v83, v100
	v_div_scale_f32 v83, vcc, 1.0, v95, 1.0
	v_mul_f32_e32 v97, v83, v100
	v_fma_f32 v101, -v98, v97, v83
	v_fmac_f32_e32 v97, v101, v100
	v_fma_f32 v83, -v98, v97, v83
	v_div_scale_f32 v98, s[6:7], v94, v94, 1.0
	v_rcp_f32_e32 v101, v98
	v_div_fmas_f32 v83, v83, v100, v97
	v_div_fixup_f32 v95, v83, v95, 1.0
	v_fma_f32 v83, -v98, v101, 1.0
	v_fmac_f32_e32 v101, v83, v101
; __device__ __forceinline__ float sigmoidf_(float x) { return 1.0f / (1.0f + __expf(-x)); }
; __device__ __forceinline__ u32x4 pack8(const f32x4 v0, const f32x4 v1) { u32x4 w; w.x = pk2(v0[0], v0[1]); w.y = pk2(v0[2], v0[3]); w.z = pk2(v1[0], v1[1]); w.w = pk2(v1[2], v1[3]); return w; }
; __device__ __forceinline__ void unpack8(const u32x4 w, f32x4& v0, f32x4& v1) { v0 = (f32x4){bflo(w.x), bfhi(w.x), bflo(w.y), bfhi(w.y)}; v1 = (f32x4){bflo(w.z), bfhi(w.z), bflo(w.w), bfhi(w.w)}; }
;     __device__ __forceinline__ void operator()(const f32x4 (&acc)[2][2][4][2], const Unit& u, int wr, int wc, int fr, int fq) const {
;     ...
;                 const int row = row0 + ai * 128 + m * 16;
;                 const bf16_t* rowp = z + (size_t)row * DIN + col0;
; #pragma unroll
;                 for (int bj = 0; bj < 2; ++bj) {
;                     const u32x4 gw = *(const u32x4*)(rowp + O_GA + bj * 128);
;                     f32x4 g0, g1; unpack8(gw, g0, g1);
;                     f32x4 v0, v1;
; #pragma unroll
;                     for (int j = 0; j < 4; ++j) { v0[j] = sigmoidf_(g0[j]) * acc[ai][bj][m][0][j]; v1[j] = sigmoidf_(g1[j]) * acc[ai][bj][m][1][j]; }
;                     const u32x4 mw = *(const u32x4*)(rowp + bj * 128); f32x4 m0, m1; unpack8(mw, m0, m1); v0 += m0; v1 += m1;
;                     __builtin_amdgcn_raw_buffer_store_b128(pack8(v0, v1), rsrc, (unsigned)(((size_t)row * DIN + col0 + bj * 128) * 2), 0, 16  ); }
	v_div_scale_f32 v83, vcc, 1.0, v94, 1.0
	v_mul_f32_e32 v100, v83, v101
	v_fma_f32 v97, -v98, v100, v83
	v_fmac_f32_e32 v100, v97, v101
	v_fma_f32 v83, -v98, v100, v83
	v_div_scale_f32 v98, s[6:7], v89, v89, 1.0
	v_mul_f32_e32 v97, 0xbfb8aa3b, v99
	v_rcp_f32_e32 v99, v98
	v_div_fmas_f32 v83, v83, v101, v100
	v_div_fixup_f32 v94, v83, v94, 1.0
	v_exp_f32_e32 v97, v97
	v_fma_f32 v83, -v98, v99, 1.0
	v_fmac_f32_e32 v99, v83, v99
	v_div_scale_f32 v83, vcc, 1.0, v89, 1.0
	v_mul_f32_e32 v100, v83, v99
	v_fma_f32 v101, -v98, v100, v83
	v_fmac_f32_e32 v100, v101, v99
	v_fma_f32 v83, -v98, v100, v83
	v_div_scale_f32 v98, s[6:7], v88, v88, 1.0
	v_rcp_f32_e32 v101, v98
	v_div_fmas_f32 v83, v83, v99, v100
	v_div_fixup_f32 v89, v83, v89, 1.0
	v_pk_add_f32 v[96:97], v[96:97], 1.0 op_sel_hi:[1,0]
	v_fma_f32 v83, -v98, v101, 1.0
	v_fmac_f32_e32 v101, v83, v101
	v_div_scale_f32 v83, vcc, 1.0, v88, 1.0
	v_mul_f32_e32 v99, v83, v101
	v_fma_f32 v100, -v98, v99, v83
	v_fmac_f32_e32 v99, v100, v101
	v_fma_f32 v83, -v98, v99, v83
	v_div_scale_f32 v98, s[6:7], v97, v97, 1.0
	v_rcp_f32_e32 v100, v98
	v_div_fmas_f32 v83, v83, v101, v99
	v_div_fixup_f32 v88, v83, v88, 1.0
	v_fma_f32 v83, -v98, v100, 1.0
	v_fmac_f32_e32 v100, v83, v100
	v_div_scale_f32 v83, vcc, 1.0, v97, 1.0
	v_mul_f32_e32 v99, v83, v100
	v_fma_f32 v101, -v98, v99, v83
	v_fmac_f32_e32 v99, v101, v100
	v_fma_f32 v83, -v98, v99, v83
	v_div_scale_f32 v98, s[6:7], v96, v96, 1.0
	v_rcp_f32_e32 v101, v98
	v_div_fmas_f32 v83, v83, v100, v99
	v_div_fixup_f32 v97, v83, v97, 1.0
	v_fma_f32 v83, -v98, v101, 1.0
	v_fmac_f32_e32 v101, v83, v101
	v_div_scale_f32 v83, vcc, 1.0, v96, 1.0
	v_mul_f32_e32 v99, v83, v101
	v_fma_f32 v100, -v98, v99, v83
	v_fmac_f32_e32 v99, v100, v101
	v_fma_f32 v83, -v98, v99, v83
	v_div_fmas_f32 v83, v83, v101, v99
	v_div_fixup_f32 v96, v83, v96, 1.0
	v_lshlrev_b32_e32 v98, 16, v90
	v_and_b32_e32 v99, 0xffff0000, v90
	v_lshlrev_b32_e32 v100, 16, v92
	v_and_b32_e32 v101, 0xffff0000, v92
	v_lshlrev_b32_e32 v92, 16, v93
	v_and_b32_e32 v93, 0xffff0000, v93
	v_lshlrev_b32_e32 v90, 16, v91
	v_and_b32_e32 v91, 0xffff0000, v91
	v_pk_fma_f32 v[76:77], v[76:77], v[86:87], v[98:99]
	v_pk_fma_f32 v[86:87], v[74:75], v[96:97], v[92:93]
	v_pk_fma_f32 v[74:75], v[72:73], v[88:89], v[100:101]
	v_add_lshl_u32 v88, v140, v82, 1
	v_pk_fma_f32 v[78:79], v[78:79], v[94:95], v[90:91]
	v_cvt_pk_bf16_f32 v72, v76, v77
	s_nop 0
	v_cvt_pk_bf16_f32 v73, v78, v79
	v_cvt_pk_bf16_f32 v74, v74, v75
	v_cvt_pk_bf16_f32 v75, v86, v87
	buffer_store_dwordx4 v[72:75], v88, s[20:23], 0 offen sc1
	s_nop 0
	s_waitcnt vmcnt(13)
	v_mov_b32_e32 v72, v232
	v_mov_b32_e32 v73, v233
	v_mov_b32_e32 v74, v234
	v_mov_b32_e32 v75, v235
	v_mov_b32_e32 v76, v236
	v_mov_b32_e32 v77, v237
	v_mov_b32_e32 v78, v238
	v_mov_b32_e32 v79, v239
	v_add_u32_e32 v199, 0x155200, v198
	global_load_dwordx4 v[232:235], v199, s[26:27]
	v_add_u32_e32 v199, 0x154000, v198
	global_load_dwordx4 v[236:239], v199, s[26:27]
	v_lshlrev_b32_e32 v82, 16, v73
	v_and_b32_e32 v83, 0xffff0000, v73
	v_lshlrev_b32_e32 v73, 16, v74
	v_lshlrev_b32_e32 v80, 16, v72
	v_and_b32_e32 v81, 0xffff0000, v72
	v_mul_f32_e32 v73, 0xbfb8aa3b, v73
	v_and_b32_e32 v84, 0xffff0000, v74
	v_mul_f32_e32 v72, 0xbfb8aa3b, v80
	v_exp_f32_e32 v74, v73
	v_mul_f32_e32 v73, 0xbfb8aa3b, v81
	v_exp_f32_e32 v72, v72
	v_exp_f32_e32 v73, v73
	v_mul_f32_e32 v81, 0xbfb8aa3b, v83
	v_lshlrev_b32_e32 v85, 16, v75
	v_and_b32_e32 v86, 0xffff0000, v75
	v_pk_add_f32 v[72:73], v[72:73], 1.0 op_sel_hi:[1,0]
	v_mul_f32_e32 v75, 0xbfb8aa3b, v84
	v_div_scale_f32 v83, s[6:7], v73, v73, 1.0
	v_rcp_f32_e32 v84, v83
	v_mul_f32_e32 v80, 0xbfb8aa3b, v82
	v_mul_f32_e32 v82, 0xbfb8aa3b, v85
	v_exp_f32_e32 v80, v80
	v_fma_f32 v85, -v83, v84, 1.0
	v_fmac_f32_e32 v84, v85, v84
	v_div_scale_f32 v85, vcc, 1.0, v73, 1.0
	v_mul_f32_e32 v87, v85, v84
	v_fma_f32 v89, -v83, v87, v85
	v_fmac_f32_e32 v87, v89, v84
	v_fma_f32 v83, -v83, v87, v85
	v_div_scale_f32 v85, s[6:7], v72, v72, 1.0
	v_rcp_f32_e32 v89, v85
	v_div_fmas_f32 v83, v83, v84, v87
	v_exp_f32_e32 v81, v81
	v_div_fixup_f32 v73, v83, v73, 1.0
	v_fma_f32 v83, -v85, v89, 1.0
	v_fmac_f32_e32 v89, v83, v89
	v_div_scale_f32 v83, vcc, 1.0, v72, 1.0
	v_mul_f32_e32 v84, v83, v89
	v_fma_f32 v87, -v85, v84, v83
	v_pk_add_f32 v[80:81], v[80:81], 1.0 op_sel_hi:[1,0]
	v_fmac_f32_e32 v84, v87, v89
	v_fma_f32 v83, -v85, v84, v83
	v_div_scale_f32 v85, s[6:7], v81, v81, 1.0
	v_rcp_f32_e32 v87, v85
	v_div_fmas_f32 v83, v83, v89, v84
	v_div_fixup_f32 v72, v83, v72, 1.0
	v_exp_f32_e32 v75, v75
	v_fma_f32 v83, -v85, v87, 1.0
	v_fmac_f32_e32 v87, v83, v87
	v_div_scale_f32 v83, vcc, 1.0, v81, 1.0
	v_mul_f32_e32 v84, v83, v87
	v_fma_f32 v89, -v85, v84, v83
	v_fmac_f32_e32 v84, v89, v87
	v_fma_f32 v83, -v85, v84, v83
	v_div_scale_f32 v85, s[6:7], v80, v80, 1.0
	v_rcp_f32_e32 v89, v85
	v_div_fmas_f32 v83, v83, v87, v84
	v_div_fixup_f32 v81, v83, v81, 1.0
	v_pk_add_f32 v[74:75], v[74:75], 1.0 op_sel_hi:[1,0]
	v_fma_f32 v83, -v85, v89, 1.0
	v_fmac_f32_e32 v89, v83, v89
	v_div_scale_f32 v83, vcc, 1.0, v80, 1.0
	v_mul_f32_e32 v84, v83, v89
	v_fma_f32 v87, -v85, v84, v83
	v_fmac_f32_e32 v84, v87, v89
	v_fma_f32 v85, -v85, v84, v83
	v_mul_f32_e32 v83, 0xbfb8aa3b, v86
	v_div_scale_f32 v86, s[6:7], v75, v75, 1.0
	v_rcp_f32_e32 v87, v86
	v_div_fmas_f32 v84, v85, v89, v84
	v_div_fixup_f32 v80, v84, v80, 1.0
	v_exp_f32_e32 v82, v82
	v_fma_f32 v84, -v86, v87, 1.0
	v_fmac_f32_e32 v87, v84, v87
	v_div_scale_f32 v84, vcc, 1.0, v75, 1.0
	v_mul_f32_e32 v85, v84, v87
	v_fma_f32 v89, -v86, v85, v84
	v_fmac_f32_e32 v85, v89, v87
	v_fma_f32 v84, -v86, v85, v84
	v_div_scale_f32 v86, s[6:7], v74, v74, 1.0
; __device__ __forceinline__ float sigmoidf_(float x) { return 1.0f / (1.0f + __expf(-x)); }
; __device__ __forceinline__ u32x4 pack8(const f32x4 v0, const f32x4 v1) { u32x4 w; w.x = pk2(v0[0], v0[1]); w.y = pk2(v0[2], v0[3]); w.z = pk2(v1[0], v1[1]); w.w = pk2(v1[2], v1[3]); return w; }
; __device__ __forceinline__ void unpack8(const u32x4 w, f32x4& v0, f32x4& v1) { v0 = (f32x4){bflo(w.x), bfhi(w.x), bflo(w.y), bfhi(w.y)}; v1 = (f32x4){bflo(w.z), bfhi(w.z), bflo(w.w), bfhi(w.w)}; }
;     __device__ __forceinline__ void operator()(const f32x4 (&acc)[2][2][4][2], const Unit& u, int wr, int wc, int fr, int fq) const {
;     ...
;                 const int row = row0 + ai * 128 + m * 16;
;                 const bf16_t* rowp = z + (size_t)row * DIN + col0;
; #pragma unroll
;                 for (int bj = 0; bj < 2; ++bj) {
;                     const u32x4 gw = *(const u32x4*)(rowp + O_GA + bj * 128);
;                     f32x4 g0, g1; unpack8(gw, g0, g1);
;                     f32x4 v0, v1;
; #pragma unroll
;                     for (int j = 0; j < 4; ++j) { v0[j] = sigmoidf_(g0[j]) * acc[ai][bj][m][0][j]; v1[j] = sigmoidf_(g1[j]) * acc[ai][bj][m][1][j]; }
;                     const u32x4 mw = *(const u32x4*)(rowp + bj * 128); f32x4 m0, m1; unpack8(mw, m0, m1); v0 += m0; v1 += m1;
;                     __builtin_amdgcn_raw_buffer_store_b128(pack8(v0, v1), rsrc, (unsigned)(((size_t)row * DIN + col0 + bj * 128) * 2), 0, 16  ); }
	v_rcp_f32_e32 v89, v86
	v_div_fmas_f32 v84, v84, v87, v85
	v_exp_f32_e32 v83, v83
	v_div_fixup_f32 v75, v84, v75, 1.0
	v_fma_f32 v84, -v86, v89, 1.0
	v_fmac_f32_e32 v89, v84, v89
	v_div_scale_f32 v84, vcc, 1.0, v74, 1.0
	v_mul_f32_e32 v85, v84, v89
	v_fma_f32 v87, -v86, v85, v84
	v_pk_add_f32 v[82:83], v[82:83], 1.0 op_sel_hi:[1,0]
	v_fmac_f32_e32 v85, v87, v89
	v_fma_f32 v84, -v86, v85, v84
	v_div_scale_f32 v86, s[6:7], v83, v83, 1.0
	v_rcp_f32_e32 v87, v86
	v_div_fmas_f32 v84, v84, v89, v85
	v_div_fixup_f32 v74, v84, v74, 1.0
	v_fma_f32 v84, -v86, v87, 1.0
	v_fmac_f32_e32 v87, v84, v87
	v_div_scale_f32 v84, vcc, 1.0, v83, 1.0
	v_mul_f32_e32 v85, v84, v87
	v_fma_f32 v89, -v86, v85, v84
	v_fmac_f32_e32 v85, v89, v87
	v_fma_f32 v84, -v86, v85, v84
	v_div_scale_f32 v86, s[6:7], v82, v82, 1.0
	v_rcp_f32_e32 v89, v86
	v_div_fmas_f32 v84, v84, v87, v85
	v_div_fixup_f32 v83, v84, v83, 1.0
	v_fma_f32 v84, -v86, v89, 1.0
	v_fmac_f32_e32 v89, v84, v89
	v_div_scale_f32 v84, vcc, 1.0, v82, 1.0
	v_mul_f32_e32 v85, v84, v89
	v_fma_f32 v87, -v86, v85, v84
	v_fmac_f32_e32 v85, v87, v89
	v_fma_f32 v84, -v86, v85, v84
	v_div_fmas_f32 v84, v84, v89, v85
	v_div_fixup_f32 v82, v84, v82, 1.0
	v_lshlrev_b32_e32 v84, 16, v76
	v_and_b32_e32 v85, 0xffff0000, v76
	v_lshlrev_b32_e32 v86, 16, v78
	v_and_b32_e32 v87, 0xffff0000, v78
	v_lshlrev_b32_e32 v78, 16, v79
	v_and_b32_e32 v79, 0xffff0000, v79
	v_lshlrev_b32_e32 v76, 16, v77
	v_and_b32_e32 v77, 0xffff0000, v77
	v_pk_fma_f32 v[68:69], v[68:69], v[72:73], v[84:85]
	v_pk_fma_f32 v[72:73], v[66:67], v[82:83], v[78:79]
	v_pk_fma_f32 v[66:67], v[64:65], v[74:75], v[86:87]
	v_cvt_pk_bf16_f32 v64, v68, v69
	v_pk_fma_f32 v[70:71], v[70:71], v[80:81], v[76:77]
	s_nop 0
	v_cvt_pk_bf16_f32 v65, v70, v71
	v_cvt_pk_bf16_f32 v66, v66, v67
	v_cvt_pk_bf16_f32 v67, v72, v73
	buffer_store_dwordx4 v[64:67], v88, s[20:23], 0 offen offset:256 sc1
	s_nop 1
	v_add_u32_e32 v64, 0x4080, v158
	v_mad_i64_i32 v[66:67], s[6:7], v64, s77, 0
	v_lshl_add_u64 v[64:65], v[66:67], 1, s[26:27]
	v_lshl_add_u64 v[64:65], v[64:65], 0, v[142:143]
	v_add_co_u32_e32 v68, vcc, s78, v64
	s_nop 1
	v_addc_co_u32_e32 v69, vcc, 0, v65, vcc
	s_waitcnt vmcnt(13)
	v_mov_b32_e32 v70, v240
	v_mov_b32_e32 v71, v241
	v_mov_b32_e32 v72, v242
	v_mov_b32_e32 v73, v243
	v_mov_b32_e32 v74, v244
	v_mov_b32_e32 v75, v245
	v_mov_b32_e32 v76, v246
	v_mov_b32_e32 v77, v247
	v_add_u32_e32 v199, 0x155300, v198
	global_load_dwordx4 v[240:243], v199, s[26:27]
	v_add_u32_e32 v199, 0x154100, v198
	global_load_dwordx4 v[244:247], v199, s[26:27]
	v_lshlrev_b32_e32 v67, 16, v70
	v_lshlrev_b32_e32 v79, 16, v71
	v_and_b32_e32 v80, 0xffff0000, v71
	v_lshlrev_b32_e32 v71, 16, v72
	v_mul_f32_e32 v67, 0xbfb8aa3b, v67
	v_and_b32_e32 v78, 0xffff0000, v70
	v_exp_f32_e32 v70, v67
	v_mul_f32_e32 v67, 0xbfb8aa3b, v71
	v_and_b32_e32 v81, 0xffff0000, v72
	v_exp_f32_e32 v72, v67
	v_mul_f32_e32 v67, 0xbfb8aa3b, v78
	v_exp_f32_e32 v71, v67
	v_mul_f32_e32 v67, 0xbfb8aa3b, v81
	v_lshlrev_b32_e32 v82, 16, v73
	v_and_b32_e32 v83, 0xffff0000, v73
	v_exp_f32_e32 v73, v67
	v_mul_f32_e32 v67, 0xbfb8aa3b, v79
	v_exp_f32_e32 v78, v67
	v_mul_f32_e32 v67, 0xbfb8aa3b, v80
	v_pk_add_f32 v[70:71], v[70:71], 1.0 op_sel_hi:[1,0]
	v_exp_f32_e32 v79, v67
	v_div_scale_f32 v67, s[6:7], v71, v71, 1.0
	v_rcp_f32_e32 v81, v67
	v_mul_f32_e32 v80, 0xbfb8aa3b, v82
	v_pk_add_f32 v[78:79], v[78:79], 1.0 op_sel_hi:[1,0]
	v_pk_add_f32 v[72:73], v[72:73], 1.0 op_sel_hi:[1,0]
	v_fma_f32 v82, -v67, v81, 1.0
	v_fmac_f32_e32 v81, v82, v81
	v_div_scale_f32 v82, vcc, 1.0, v71, 1.0
	v_mul_f32_e32 v84, v82, v81
	v_fma_f32 v85, -v67, v84, v82
	v_fmac_f32_e32 v84, v85, v81
	v_fma_f32 v67, -v67, v84, v82
	v_div_scale_f32 v82, s[6:7], v70, v70, 1.0
	v_rcp_f32_e32 v85, v82
	v_div_fmas_f32 v67, v67, v81, v84
	v_div_fixup_f32 v71, v67, v71, 1.0
	v_exp_f32_e32 v80, v80
	v_fma_f32 v67, -v82, v85, 1.0
	v_fmac_f32_e32 v85, v67, v85
	v_div_scale_f32 v67, vcc, 1.0, v70, 1.0
	v_mul_f32_e32 v81, v67, v85
	v_fma_f32 v84, -v82, v81, v67
	v_fmac_f32_e32 v81, v84, v85
	v_fma_f32 v67, -v82, v81, v67
	v_div_scale_f32 v82, s[6:7], v79, v79, 1.0
	v_rcp_f32_e32 v84, v82
	v_div_fmas_f32 v67, v67, v85, v81
	v_div_fixup_f32 v70, v67, v70, 1.0
	v_fma_f32 v67, -v82, v84, 1.0
	v_fmac_f32_e32 v84, v67, v84
	v_div_scale_f32 v67, vcc, 1.0, v79, 1.0
	v_mul_f32_e32 v81, v67, v84
	v_fma_f32 v85, -v82, v81, v67
	v_fmac_f32_e32 v81, v85, v84
	v_fma_f32 v67, -v82, v81, v67
	v_div_scale_f32 v82, s[6:7], v78, v78, 1.0
	v_rcp_f32_e32 v85, v82
	v_div_fmas_f32 v67, v67, v84, v81
	v_div_fixup_f32 v79, v67, v79, 1.0
	v_fma_f32 v67, -v82, v85, 1.0
	v_fmac_f32_e32 v85, v67, v85
	v_div_scale_f32 v67, vcc, 1.0, v78, 1.0
	v_mul_f32_e32 v84, v67, v85
	v_fma_f32 v81, -v82, v84, v67
	v_fmac_f32_e32 v84, v81, v85
	v_fma_f32 v67, -v82, v84, v67
	v_div_scale_f32 v82, s[6:7], v73, v73, 1.0
	v_mul_f32_e32 v81, 0xbfb8aa3b, v83
	v_rcp_f32_e32 v83, v82
	v_div_fmas_f32 v67, v67, v85, v84
	v_div_fixup_f32 v78, v67, v78, 1.0
	v_exp_f32_e32 v81, v81
	v_fma_f32 v67, -v82, v83, 1.0
	v_fmac_f32_e32 v83, v67, v83
	v_div_scale_f32 v67, vcc, 1.0, v73, 1.0
	v_mul_f32_e32 v84, v67, v83
	v_fma_f32 v85, -v82, v84, v67
	v_fmac_f32_e32 v84, v85, v83
	v_fma_f32 v67, -v82, v84, v67
	v_div_scale_f32 v82, s[6:7], v72, v72, 1.0
	v_rcp_f32_e32 v85, v82
	v_div_fmas_f32 v67, v67, v83, v84
	v_div_fixup_f32 v73, v67, v73, 1.0
	v_pk_add_f32 v[80:81], v[80:81], 1.0 op_sel_hi:[1,0]
	v_fma_f32 v67, -v82, v85, 1.0
	v_fmac_f32_e32 v85, v67, v85
	v_div_scale_f32 v67, vcc, 1.0, v72, 1.0
	v_mul_f32_e32 v83, v67, v85
	v_fma_f32 v84, -v82, v83, v67
	v_fmac_f32_e32 v83, v84, v85
	v_fma_f32 v67, -v82, v83, v67
	v_div_scale_f32 v82, s[6:7], v81, v81, 1.0
; __device__ __forceinline__ float sigmoidf_(float x) { return 1.0f / (1.0f + __expf(-x)); }
; __device__ __forceinline__ u32x4 pack8(const f32x4 v0, const f32x4 v1) { u32x4 w; w.x = pk2(v0[0], v0[1]); w.y = pk2(v0[2], v0[3]); w.z = pk2(v1[0], v1[1]); w.w = pk2(v1[2], v1[3]); return w; }
; __device__ __forceinline__ void unpack8(const u32x4 w, f32x4& v0, f32x4& v1) { v0 = (f32x4){bflo(w.x), bfhi(w.x), bflo(w.y), bfhi(w.y)}; v1 = (f32x4){bflo(w.z), bfhi(w.z), bflo(w.w), bfhi(w.w)}; }
;     __device__ __forceinline__ void operator()(const f32x4 (&acc)[2][2][4][2], const Unit& u, int wr, int wc, int fr, int fq) const {
;     ...
;                 const int row = row0 + ai * 128 + m * 16;
;                 const bf16_t* rowp = z + (size_t)row * DIN + col0;
; #pragma unroll
;                 for (int bj = 0; bj < 2; ++bj) {
;                     const u32x4 gw = *(const u32x4*)(rowp + O_GA + bj * 128);
;                     f32x4 g0, g1; unpack8(gw, g0, g1);
;                     f32x4 v0, v1;
; #pragma unroll
;                     for (int j = 0; j < 4; ++j) { v0[j] = sigmoidf_(g0[j]) * acc[ai][bj][m][0][j]; v1[j] = sigmoidf_(g1[j]) * acc[ai][bj][m][1][j]; }
;                     const u32x4 mw = *(const u32x4*)(rowp + bj * 128); f32x4 m0, m1; unpack8(mw, m0, m1); v0 += m0; v1 += m1;
;                     __builtin_amdgcn_raw_buffer_store_b128(pack8(v0, v1), rsrc, (unsigned)(((size_t)row * DIN + col0 + bj * 128) * 2), 0, 16  ); }
	v_rcp_f32_e32 v84, v82
	v_div_fmas_f32 v67, v67, v85, v83
	v_div_fixup_f32 v72, v67, v72, 1.0
	v_fma_f32 v67, -v82, v84, 1.0
	v_fmac_f32_e32 v84, v67, v84
	v_div_scale_f32 v67, vcc, 1.0, v81, 1.0
	v_mul_f32_e32 v83, v67, v84
	v_fma_f32 v85, -v82, v83, v67
	v_fmac_f32_e32 v83, v85, v84
	v_fma_f32 v67, -v82, v83, v67
	v_div_scale_f32 v82, s[6:7], v80, v80, 1.0
	v_rcp_f32_e32 v85, v82
	v_div_fmas_f32 v67, v67, v84, v83
	v_div_fixup_f32 v81, v67, v81, 1.0
	v_fma_f32 v67, -v82, v85, 1.0
	v_fmac_f32_e32 v85, v67, v85
	v_div_scale_f32 v67, vcc, 1.0, v80, 1.0
	v_mul_f32_e32 v83, v67, v85
	v_fma_f32 v84, -v82, v83, v67
	v_fmac_f32_e32 v83, v84, v85
	v_fma_f32 v67, -v82, v83, v67
	v_div_fmas_f32 v67, v67, v85, v83
	v_div_fixup_f32 v80, v67, v80, 1.0
	v_lshlrev_b32_e32 v82, 16, v74
	v_and_b32_e32 v83, 0xffff0000, v74
	v_lshlrev_b32_e32 v84, 16, v76
	v_and_b32_e32 v85, 0xffff0000, v76
	v_lshlrev_b32_e32 v76, 16, v77
	v_and_b32_e32 v77, 0xffff0000, v77
	v_lshlrev_b32_e32 v74, 16, v75
	v_and_b32_e32 v75, 0xffff0000, v75
	v_pk_fma_f32 v[60:61], v[60:61], v[70:71], v[82:83]
	v_pk_fma_f32 v[70:71], v[58:59], v[80:81], v[76:77]
	v_pk_fma_f32 v[58:59], v[56:57], v[72:73], v[84:85]
	v_add_lshl_u32 v72, v140, v66, 1
	v_pk_fma_f32 v[62:63], v[62:63], v[78:79], v[74:75]
	v_cvt_pk_bf16_f32 v56, v60, v61
	s_nop 0
	v_cvt_pk_bf16_f32 v57, v62, v63
	v_cvt_pk_bf16_f32 v58, v58, v59
	v_cvt_pk_bf16_f32 v59, v70, v71
	buffer_store_dwordx4 v[56:59], v72, s[20:23], 0 offen sc1
	s_nop 0
	s_waitcnt vmcnt(13)
	v_mov_b32_e32 v56, v248
	v_mov_b32_e32 v57, v249
	v_mov_b32_e32 v58, v250
	v_mov_b32_e32 v59, v251
	v_mov_b32_e32 v60, v252
	v_mov_b32_e32 v61, v253
	v_mov_b32_e32 v62, v254
	v_mov_b32_e32 v63, v255
	v_add_u32_e32 v199, 0x177200, v198
	global_load_dwordx4 v[248:251], v199, s[26:27]
	v_add_u32_e32 v199, 0x176000, v198
	global_load_dwordx4 v[252:255], v199, s[26:27]
	v_lshlrev_b32_e32 v66, 16, v57
	v_and_b32_e32 v67, 0xffff0000, v57
	v_lshlrev_b32_e32 v57, 16, v58
	v_lshlrev_b32_e32 v64, 16, v56
	v_and_b32_e32 v65, 0xffff0000, v56
	v_mul_f32_e32 v57, 0xbfb8aa3b, v57
	v_and_b32_e32 v68, 0xffff0000, v58
	v_mul_f32_e32 v56, 0xbfb8aa3b, v64
	v_exp_f32_e32 v58, v57
	v_mul_f32_e32 v57, 0xbfb8aa3b, v65
	v_exp_f32_e32 v56, v56
	v_exp_f32_e32 v57, v57
	v_mul_f32_e32 v65, 0xbfb8aa3b, v67
	v_lshlrev_b32_e32 v69, 16, v59
	v_and_b32_e32 v70, 0xffff0000, v59
	v_pk_add_f32 v[56:57], v[56:57], 1.0 op_sel_hi:[1,0]
	v_mul_f32_e32 v59, 0xbfb8aa3b, v68
	v_div_scale_f32 v67, s[6:7], v57, v57, 1.0
	v_rcp_f32_e32 v68, v67
	v_mul_f32_e32 v64, 0xbfb8aa3b, v66
	v_mul_f32_e32 v66, 0xbfb8aa3b, v69
	v_exp_f32_e32 v64, v64
	v_fma_f32 v69, -v67, v68, 1.0
	v_fmac_f32_e32 v68, v69, v68
	v_div_scale_f32 v69, vcc, 1.0, v57, 1.0
	v_mul_f32_e32 v71, v69, v68
	v_fma_f32 v73, -v67, v71, v69
	v_fmac_f32_e32 v71, v73, v68
	v_fma_f32 v67, -v67, v71, v69
	v_div_scale_f32 v69, s[6:7], v56, v56, 1.0
	v_rcp_f32_e32 v73, v69
	v_div_fmas_f32 v67, v67, v68, v71
	v_exp_f32_e32 v65, v65
	v_div_fixup_f32 v57, v67, v57, 1.0
	v_fma_f32 v67, -v69, v73, 1.0
	v_fmac_f32_e32 v73, v67, v73
	v_div_scale_f32 v67, vcc, 1.0, v56, 1.0
	v_mul_f32_e32 v68, v67, v73
	v_fma_f32 v71, -v69, v68, v67
	v_pk_add_f32 v[64:65], v[64:65], 1.0 op_sel_hi:[1,0]
	v_fmac_f32_e32 v68, v71, v73
	v_fma_f32 v67, -v69, v68, v67
	v_div_scale_f32 v69, s[6:7], v65, v65, 1.0
	v_rcp_f32_e32 v71, v69
	v_div_fmas_f32 v67, v67, v73, v68
	v_div_fixup_f32 v56, v67, v56, 1.0
	v_exp_f32_e32 v59, v59
	v_fma_f32 v67, -v69, v71, 1.0
	v_fmac_f32_e32 v71, v67, v71
	v_div_scale_f32 v67, vcc, 1.0, v65, 1.0
	v_mul_f32_e32 v68, v67, v71
	v_fma_f32 v73, -v69, v68, v67
	v_fmac_f32_e32 v68, v73, v71
	v_fma_f32 v67, -v69, v68, v67
	v_div_scale_f32 v69, s[6:7], v64, v64, 1.0
	v_rcp_f32_e32 v73, v69
	v_div_fmas_f32 v67, v67, v71, v68
	v_div_fixup_f32 v65, v67, v65, 1.0
	v_pk_add_f32 v[58:59], v[58:59], 1.0 op_sel_hi:[1,0]
	v_fma_f32 v67, -v69, v73, 1.0
	v_fmac_f32_e32 v73, v67, v73
	v_div_scale_f32 v67, vcc, 1.0, v64, 1.0
	v_mul_f32_e32 v68, v67, v73
	v_fma_f32 v71, -v69, v68, v67
	v_fmac_f32_e32 v68, v71, v73
	v_fma_f32 v69, -v69, v68, v67
	v_mul_f32_e32 v67, 0xbfb8aa3b, v70
	v_div_scale_f32 v70, s[6:7], v59, v59, 1.0
	v_rcp_f32_e32 v71, v70
	v_div_fmas_f32 v68, v69, v73, v68
	v_div_fixup_f32 v64, v68, v64, 1.0
	v_exp_f32_e32 v66, v66
	v_fma_f32 v68, -v70, v71, 1.0
	v_fmac_f32_e32 v71, v68, v71
	v_div_scale_f32 v68, vcc, 1.0, v59, 1.0
	v_mul_f32_e32 v69, v68, v71
	v_fma_f32 v73, -v70, v69, v68
	v_fmac_f32_e32 v69, v73, v71
	v_fma_f32 v68, -v70, v69, v68
	v_div_scale_f32 v70, s[6:7], v58, v58, 1.0
	v_rcp_f32_e32 v73, v70
	v_div_fmas_f32 v68, v68, v71, v69
	v_exp_f32_e32 v67, v67
	v_div_fixup_f32 v59, v68, v59, 1.0
	v_fma_f32 v68, -v70, v73, 1.0
	v_fmac_f32_e32 v73, v68, v73
	v_div_scale_f32 v68, vcc, 1.0, v58, 1.0
	v_mul_f32_e32 v69, v68, v73
	v_fma_f32 v71, -v70, v69, v68
	v_pk_add_f32 v[66:67], v[66:67], 1.0 op_sel_hi:[1,0]
	v_fmac_f32_e32 v69, v71, v73
	v_fma_f32 v68, -v70, v69, v68
	v_div_scale_f32 v70, s[6:7], v67, v67, 1.0
	v_rcp_f32_e32 v71, v70
	v_div_fmas_f32 v68, v68, v73, v69
	v_div_fixup_f32 v58, v68, v58, 1.0
	v_fma_f32 v68, -v70, v71, 1.0
	v_fmac_f32_e32 v71, v68, v71
	v_div_scale_f32 v68, vcc, 1.0, v67, 1.0
	v_mul_f32_e32 v69, v68, v71
	v_fma_f32 v73, -v70, v69, v68
	v_fmac_f32_e32 v69, v73, v71
	v_fma_f32 v68, -v70, v69, v68
	v_div_scale_f32 v70, s[6:7], v66, v66, 1.0
	v_rcp_f32_e32 v73, v70
	v_div_fmas_f32 v68, v68, v71, v69
	v_div_fixup_f32 v67, v68, v67, 1.0
	v_fma_f32 v68, -v70, v73, 1.0
	v_fmac_f32_e32 v73, v68, v73
	v_div_scale_f32 v68, vcc, 1.0, v66, 1.0
	v_mul_f32_e32 v69, v68, v73
	v_fma_f32 v71, -v70, v69, v68
	v_fmac_f32_e32 v69, v71, v73
	v_fma_f32 v68, -v70, v69, v68
	v_div_fmas_f32 v68, v68, v73, v69
	v_div_fixup_f32 v66, v68, v66, 1.0
	v_lshlrev_b32_e32 v68, 16, v60
	v_and_b32_e32 v69, 0xffff0000, v60
	v_lshlrev_b32_e32 v70, 16, v62
	v_and_b32_e32 v71, 0xffff0000, v62
	v_lshlrev_b32_e32 v62, 16, v63
	v_and_b32_e32 v63, 0xffff0000, v63
	v_lshlrev_b32_e32 v60, 16, v61
	v_and_b32_e32 v61, 0xffff0000, v61
	v_pk_fma_f32 v[52:53], v[52:53], v[56:57], v[68:69]
	v_pk_fma_f32 v[56:57], v[50:51], v[66:67], v[62:63]
	v_pk_fma_f32 v[50:51], v[48:49], v[58:59], v[70:71]
	v_cvt_pk_bf16_f32 v48, v52, v53
	v_pk_fma_f32 v[54:55], v[54:55], v[64:65], v[60:61]
	s_nop 0
	v_cvt_pk_bf16_f32 v49, v54, v55
	v_cvt_pk_bf16_f32 v50, v50, v51
	v_cvt_pk_bf16_f32 v51, v56, v57
	buffer_store_dwordx4 v[48:51], v72, s[20:23], 0 offen offset:256 sc1
	s_nop 1
	v_add_u32_e32 v48, 0x4090, v158
	v_mad_i64_i32 v[50:51], s[6:7], v48, s77, 0
	v_lshl_add_u64 v[48:49], v[50:51], 1, s[26:27]
	v_lshl_add_u64 v[48:49], v[48:49], 0, v[142:143]
	v_add_co_u32_e32 v52, vcc, s78, v48
	s_nop 1
	v_addc_co_u32_e32 v53, vcc, 0, v49, vcc
	s_waitcnt vmcnt(13)
; __device__ __forceinline__ float sigmoidf_(float x) { return 1.0f / (1.0f + __expf(-x)); }
; __device__ __forceinline__ u32x4 pack8(const f32x4 v0, const f32x4 v1) { u32x4 w; w.x = pk2(v0[0], v0[1]); w.y = pk2(v0[2], v0[3]); w.z = pk2(v1[0], v1[1]); w.w = pk2(v1[2], v1[3]); return w; }
; __device__ __forceinline__ void unpack8(const u32x4 w, f32x4& v0, f32x4& v1) { v0 = (f32x4){bflo(w.x), bfhi(w.x), bflo(w.y), bfhi(w.y)}; v1 = (f32x4){bflo(w.z), bfhi(w.z), bflo(w.w), bfhi(w.w)}; }
;     __device__ __forceinline__ void operator()(const f32x4 (&acc)[2][2][4][2], const Unit& u, int wr, int wc, int fr, int fq) const {
;     ...
;                 const int row = row0 + ai * 128 + m * 16;
;                 const bf16_t* rowp = z + (size_t)row * DIN + col0;
; #pragma unroll
;                 for (int bj = 0; bj < 2; ++bj) {
;                     const u32x4 gw = *(const u32x4*)(rowp + O_GA + bj * 128);
;                     f32x4 g0, g1; unpack8(gw, g0, g1);
;                     f32x4 v0, v1;
; #pragma unroll
;                     for (int j = 0; j < 4; ++j) { v0[j] = sigmoidf_(g0[j]) * acc[ai][bj][m][0][j]; v1[j] = sigmoidf_(g1[j]) * acc[ai][bj][m][1][j]; }
;                     const u32x4 mw = *(const u32x4*)(rowp + bj * 128); f32x4 m0, m1; unpack8(mw, m0, m1); v0 += m0; v1 += m1;
;                     __builtin_amdgcn_raw_buffer_store_b128(pack8(v0, v1), rsrc, (unsigned)(((size_t)row * DIN + col0 + bj * 128) * 2), 0, 16  ); }
	v_mov_b32_e32 v54, v200
	v_mov_b32_e32 v55, v201
	v_mov_b32_e32 v56, v202
	v_mov_b32_e32 v57, v203
	v_mov_b32_e32 v58, v204
	v_mov_b32_e32 v59, v205
	v_mov_b32_e32 v60, v206
	v_mov_b32_e32 v61, v207
	v_add_u32_e32 v199, 0x177300, v198
	global_load_dwordx4 v[200:203], v199, s[26:27]
	v_add_u32_e32 v199, 0x176100, v198
	global_load_dwordx4 v[204:207], v199, s[26:27]
	v_lshlrev_b32_e32 v51, 16, v54
	v_lshlrev_b32_e32 v63, 16, v55
	v_and_b32_e32 v64, 0xffff0000, v55
	v_lshlrev_b32_e32 v55, 16, v56
	v_mul_f32_e32 v51, 0xbfb8aa3b, v51
	v_and_b32_e32 v62, 0xffff0000, v54
	v_exp_f32_e32 v54, v51
	v_mul_f32_e32 v51, 0xbfb8aa3b, v55
	v_and_b32_e32 v65, 0xffff0000, v56
	v_exp_f32_e32 v56, v51
	v_mul_f32_e32 v51, 0xbfb8aa3b, v62
	v_exp_f32_e32 v55, v51
	v_mul_f32_e32 v51, 0xbfb8aa3b, v65
	v_lshlrev_b32_e32 v66, 16, v57
	v_and_b32_e32 v67, 0xffff0000, v57
	v_exp_f32_e32 v57, v51
	v_mul_f32_e32 v51, 0xbfb8aa3b, v63
	v_exp_f32_e32 v62, v51
	v_mul_f32_e32 v51, 0xbfb8aa3b, v64
	v_pk_add_f32 v[54:55], v[54:55], 1.0 op_sel_hi:[1,0]
	v_exp_f32_e32 v63, v51
	v_div_scale_f32 v51, s[6:7], v55, v55, 1.0
	v_rcp_f32_e32 v65, v51
	v_mul_f32_e32 v64, 0xbfb8aa3b, v66
	v_pk_add_f32 v[62:63], v[62:63], 1.0 op_sel_hi:[1,0]
	v_pk_add_f32 v[56:57], v[56:57], 1.0 op_sel_hi:[1,0]
	v_fma_f32 v66, -v51, v65, 1.0
	v_fmac_f32_e32 v65, v66, v65
	v_div_scale_f32 v66, vcc, 1.0, v55, 1.0
	v_mul_f32_e32 v68, v66, v65
	v_fma_f32 v69, -v51, v68, v66
	v_fmac_f32_e32 v68, v69, v65
	v_fma_f32 v51, -v51, v68, v66
	v_div_scale_f32 v66, s[6:7], v54, v54, 1.0
	v_rcp_f32_e32 v69, v66
	v_div_fmas_f32 v51, v51, v65, v68
	v_div_fixup_f32 v55, v51, v55, 1.0
	v_exp_f32_e32 v64, v64
	v_fma_f32 v51, -v66, v69, 1.0
	v_fmac_f32_e32 v69, v51, v69
	v_div_scale_f32 v51, vcc, 1.0, v54, 1.0
	v_mul_f32_e32 v65, v51, v69
	v_fma_f32 v68, -v66, v65, v51
	v_fmac_f32_e32 v65, v68, v69
	v_fma_f32 v51, -v66, v65, v51
	v_div_scale_f32 v66, s[6:7], v63, v63, 1.0
	v_rcp_f32_e32 v68, v66
	v_div_fmas_f32 v51, v51, v69, v65
	v_div_fixup_f32 v54, v51, v54, 1.0
	v_fma_f32 v51, -v66, v68, 1.0
	v_fmac_f32_e32 v68, v51, v68
	v_div_scale_f32 v51, vcc, 1.0, v63, 1.0
	v_mul_f32_e32 v65, v51, v68
	v_fma_f32 v69, -v66, v65, v51
	v_fmac_f32_e32 v65, v69, v68
	v_fma_f32 v51, -v66, v65, v51
	v_div_scale_f32 v66, s[6:7], v62, v62, 1.0
	v_rcp_f32_e32 v69, v66
	v_div_fmas_f32 v51, v51, v68, v65
	v_div_fixup_f32 v63, v51, v63, 1.0
	v_fma_f32 v51, -v66, v69, 1.0
	v_fmac_f32_e32 v69, v51, v69
	v_div_scale_f32 v51, vcc, 1.0, v62, 1.0
	v_mul_f32_e32 v68, v51, v69
	v_fma_f32 v65, -v66, v68, v51
	v_fmac_f32_e32 v68, v65, v69
	v_fma_f32 v51, -v66, v68, v51
	v_div_scale_f32 v66, s[6:7], v57, v57, 1.0
	v_mul_f32_e32 v65, 0xbfb8aa3b, v67
	v_rcp_f32_e32 v67, v66
	v_div_fmas_f32 v51, v51, v69, v68
	v_div_fixup_f32 v62, v51, v62, 1.0
	v_exp_f32_e32 v65, v65
	v_fma_f32 v51, -v66, v67, 1.0
	v_fmac_f32_e32 v67, v51, v67
	v_div_scale_f32 v51, vcc, 1.0, v57, 1.0
	v_mul_f32_e32 v68, v51, v67
	v_fma_f32 v69, -v66, v68, v51
	v_fmac_f32_e32 v68, v69, v67
	v_fma_f32 v51, -v66, v68, v51
	v_div_scale_f32 v66, s[6:7], v56, v56, 1.0
	v_rcp_f32_e32 v69, v66
	v_div_fmas_f32 v51, v51, v67, v68
	v_div_fixup_f32 v57, v51, v57, 1.0
	v_pk_add_f32 v[64:65], v[64:65], 1.0 op_sel_hi:[1,0]
	v_fma_f32 v51, -v66, v69, 1.0
	v_fmac_f32_e32 v69, v51, v69
	v_div_scale_f32 v51, vcc, 1.0, v56, 1.0
	v_mul_f32_e32 v67, v51, v69
	v_fma_f32 v68, -v66, v67, v51
	v_fmac_f32_e32 v67, v68, v69
	v_fma_f32 v51, -v66, v67, v51
	v_div_scale_f32 v66, s[6:7], v65, v65, 1.0
	v_rcp_f32_e32 v68, v66
	v_div_fmas_f32 v51, v51, v69, v67
	v_div_fixup_f32 v56, v51, v56, 1.0
	v_fma_f32 v51, -v66, v68, 1.0
	v_fmac_f32_e32 v68, v51, v68
	v_div_scale_f32 v51, vcc, 1.0, v65, 1.0
	v_mul_f32_e32 v67, v51, v68
	v_fma_f32 v69, -v66, v67, v51
	v_fmac_f32_e32 v67, v69, v68
	v_fma_f32 v51, -v66, v67, v51
	v_div_scale_f32 v66, s[6:7], v64, v64, 1.0
	v_rcp_f32_e32 v69, v66
	v_div_fmas_f32 v51, v51, v68, v67
	v_div_fixup_f32 v65, v51, v65, 1.0
	v_fma_f32 v51, -v66, v69, 1.0
	v_fmac_f32_e32 v69, v51, v69
	v_div_scale_f32 v51, vcc, 1.0, v64, 1.0
	v_mul_f32_e32 v67, v51, v69
	v_fma_f32 v68, -v66, v67, v51
	v_fmac_f32_e32 v67, v68, v69
	v_fma_f32 v51, -v66, v67, v51
	v_div_fmas_f32 v51, v51, v69, v67
	v_div_fixup_f32 v64, v51, v64, 1.0
	v_lshlrev_b32_e32 v66, 16, v58
	v_and_b32_e32 v67, 0xffff0000, v58
	v_lshlrev_b32_e32 v68, 16, v60
	v_and_b32_e32 v69, 0xffff0000, v60
	v_lshlrev_b32_e32 v60, 16, v61
	v_and_b32_e32 v61, 0xffff0000, v61
	v_lshlrev_b32_e32 v58, 16, v59
	v_and_b32_e32 v59, 0xffff0000, v59
	v_pk_fma_f32 v[44:45], v[44:45], v[54:55], v[66:67]
	v_pk_fma_f32 v[54:55], v[42:43], v[64:65], v[60:61]
	v_pk_fma_f32 v[42:43], v[40:41], v[56:57], v[68:69]
	v_add_lshl_u32 v56, v140, v50, 1
	v_pk_fma_f32 v[46:47], v[46:47], v[62:63], v[58:59]
	v_cvt_pk_bf16_f32 v40, v44, v45
	s_nop 0
	v_cvt_pk_bf16_f32 v41, v46, v47
	v_cvt_pk_bf16_f32 v42, v42, v43
	v_cvt_pk_bf16_f32 v43, v54, v55
	buffer_store_dwordx4 v[40:43], v56, s[20:23], 0 offen sc1
	s_nop 0
	s_waitcnt vmcnt(13)
; __device__ __forceinline__ float sigmoidf_(float x) { return 1.0f / (1.0f + __expf(-x)); }
; __device__ __forceinline__ u32x4 pack8(const f32x4 v0, const f32x4 v1) { u32x4 w; w.x = pk2(v0[0], v0[1]); w.y = pk2(v0[2], v0[3]); w.z = pk2(v1[0], v1[1]); w.w = pk2(v1[2], v1[3]); return w; }
; __device__ __forceinline__ void unpack8(const u32x4 w, f32x4& v0, f32x4& v1) { v0 = (f32x4){bflo(w.x), bfhi(w.x), bflo(w.y), bfhi(w.y)}; v1 = (f32x4){bflo(w.z), bfhi(w.z), bflo(w.w), bfhi(w.w)}; }
;     __device__ __forceinline__ void operator()(const f32x4 (&acc)[2][2][4][2], const Unit& u, int wr, int wc, int fr, int fq) const {
;     ...
;                 const int row = row0 + ai * 128 + m * 16;
;                 const bf16_t* rowp = z + (size_t)row * DIN + col0;
; #pragma unroll
;                 for (int bj = 0; bj < 2; ++bj) {
;                     const u32x4 gw = *(const u32x4*)(rowp + O_GA + bj * 128);
;                     f32x4 g0, g1; unpack8(gw, g0, g1);
;                     f32x4 v0, v1;
; #pragma unroll
;                     for (int j = 0; j < 4; ++j) { v0[j] = sigmoidf_(g0[j]) * acc[ai][bj][m][0][j]; v1[j] = sigmoidf_(g1[j]) * acc[ai][bj][m][1][j]; }
;                     const u32x4 mw = *(const u32x4*)(rowp + bj * 128); f32x4 m0, m1; unpack8(mw, m0, m1); v0 += m0; v1 += m1;
;                     __builtin_amdgcn_raw_buffer_store_b128(pack8(v0, v1), rsrc, (unsigned)(((size_t)row * DIN + col0 + bj * 128) * 2), 0, 16  ); }
	v_mov_b32_e32 v40, v208
	v_mov_b32_e32 v41, v209
	v_mov_b32_e32 v42, v210
	v_mov_b32_e32 v43, v211
	v_mov_b32_e32 v44, v212
	v_mov_b32_e32 v45, v213
	v_mov_b32_e32 v46, v214
	v_mov_b32_e32 v47, v215
	v_lshlrev_b32_e32 v50, 16, v41
	v_and_b32_e32 v51, 0xffff0000, v41
	v_lshlrev_b32_e32 v41, 16, v42
	v_lshlrev_b32_e32 v48, 16, v40
	v_and_b32_e32 v49, 0xffff0000, v40
	v_mul_f32_e32 v41, 0xbfb8aa3b, v41
	v_and_b32_e32 v52, 0xffff0000, v42
	v_mul_f32_e32 v40, 0xbfb8aa3b, v48
	v_exp_f32_e32 v42, v41
	v_mul_f32_e32 v41, 0xbfb8aa3b, v49
	v_exp_f32_e32 v40, v40
	v_exp_f32_e32 v41, v41
	v_mul_f32_e32 v49, 0xbfb8aa3b, v51
	v_lshlrev_b32_e32 v53, 16, v43
	v_and_b32_e32 v54, 0xffff0000, v43
	v_pk_add_f32 v[40:41], v[40:41], 1.0 op_sel_hi:[1,0]
	v_mul_f32_e32 v43, 0xbfb8aa3b, v52
	v_div_scale_f32 v51, s[6:7], v41, v41, 1.0
	v_rcp_f32_e32 v52, v51
	v_mul_f32_e32 v48, 0xbfb8aa3b, v50
	v_mul_f32_e32 v50, 0xbfb8aa3b, v53
	v_exp_f32_e32 v48, v48
	v_fma_f32 v53, -v51, v52, 1.0
	v_fmac_f32_e32 v52, v53, v52
	v_div_scale_f32 v53, vcc, 1.0, v41, 1.0
	v_mul_f32_e32 v55, v53, v52
	v_fma_f32 v57, -v51, v55, v53
	v_fmac_f32_e32 v55, v57, v52
	v_fma_f32 v51, -v51, v55, v53
	v_div_scale_f32 v53, s[6:7], v40, v40, 1.0
	v_rcp_f32_e32 v57, v53
	v_div_fmas_f32 v51, v51, v52, v55
	v_exp_f32_e32 v49, v49
	v_div_fixup_f32 v41, v51, v41, 1.0
	v_fma_f32 v51, -v53, v57, 1.0
	v_fmac_f32_e32 v57, v51, v57
	v_div_scale_f32 v51, vcc, 1.0, v40, 1.0
	v_mul_f32_e32 v52, v51, v57
	v_fma_f32 v55, -v53, v52, v51
	v_pk_add_f32 v[48:49], v[48:49], 1.0 op_sel_hi:[1,0]
	v_fmac_f32_e32 v52, v55, v57
	v_fma_f32 v51, -v53, v52, v51
	v_div_scale_f32 v53, s[6:7], v49, v49, 1.0
	v_rcp_f32_e32 v55, v53
	v_div_fmas_f32 v51, v51, v57, v52
	v_div_fixup_f32 v40, v51, v40, 1.0
	v_exp_f32_e32 v43, v43
	v_fma_f32 v51, -v53, v55, 1.0
	v_fmac_f32_e32 v55, v51, v55
	v_div_scale_f32 v51, vcc, 1.0, v49, 1.0
	v_mul_f32_e32 v52, v51, v55
	v_fma_f32 v57, -v53, v52, v51
	v_fmac_f32_e32 v52, v57, v55
	v_fma_f32 v51, -v53, v52, v51
	v_div_scale_f32 v53, s[6:7], v48, v48, 1.0
	v_rcp_f32_e32 v57, v53
	v_div_fmas_f32 v51, v51, v55, v52
	v_div_fixup_f32 v49, v51, v49, 1.0
	v_pk_add_f32 v[42:43], v[42:43], 1.0 op_sel_hi:[1,0]
	v_fma_f32 v51, -v53, v57, 1.0
	v_fmac_f32_e32 v57, v51, v57
	v_div_scale_f32 v51, vcc, 1.0, v48, 1.0
	v_mul_f32_e32 v52, v51, v57
	v_fma_f32 v55, -v53, v52, v51
	v_fmac_f32_e32 v52, v55, v57
	v_fma_f32 v53, -v53, v52, v51
	v_mul_f32_e32 v51, 0xbfb8aa3b, v54
	v_div_scale_f32 v54, s[6:7], v43, v43, 1.0
	v_rcp_f32_e32 v55, v54
	v_div_fmas_f32 v52, v53, v57, v52
	v_div_fixup_f32 v48, v52, v48, 1.0
	v_exp_f32_e32 v50, v50
	v_fma_f32 v52, -v54, v55, 1.0
	v_fmac_f32_e32 v55, v52, v55
	v_div_scale_f32 v52, vcc, 1.0, v43, 1.0
	v_mul_f32_e32 v53, v52, v55
	v_fma_f32 v57, -v54, v53, v52
	v_fmac_f32_e32 v53, v57, v55
	v_fma_f32 v52, -v54, v53, v52
	v_div_scale_f32 v54, s[6:7], v42, v42, 1.0
	v_rcp_f32_e32 v57, v54
	v_div_fmas_f32 v52, v52, v55, v53
	v_exp_f32_e32 v51, v51
	v_div_fixup_f32 v43, v52, v43, 1.0
	v_fma_f32 v52, -v54, v57, 1.0
	v_fmac_f32_e32 v57, v52, v57
	v_div_scale_f32 v52, vcc, 1.0, v42, 1.0
	v_mul_f32_e32 v53, v52, v57
	v_fma_f32 v55, -v54, v53, v52
	v_pk_add_f32 v[50:51], v[50:51], 1.0 op_sel_hi:[1,0]
	v_fmac_f32_e32 v53, v55, v57
	v_fma_f32 v52, -v54, v53, v52
	v_div_scale_f32 v54, s[6:7], v51, v51, 1.0
	v_rcp_f32_e32 v55, v54
	v_div_fmas_f32 v52, v52, v57, v53
	v_div_fixup_f32 v42, v52, v42, 1.0
	v_fma_f32 v52, -v54, v55, 1.0
	v_fmac_f32_e32 v55, v52, v55
	v_div_scale_f32 v52, vcc, 1.0, v51, 1.0
	v_mul_f32_e32 v53, v52, v55
	v_fma_f32 v57, -v54, v53, v52
	v_fmac_f32_e32 v53, v57, v55
	v_fma_f32 v52, -v54, v53, v52
	v_div_scale_f32 v54, s[6:7], v50, v50, 1.0
	v_rcp_f32_e32 v57, v54
	v_div_fmas_f32 v52, v52, v55, v53
	v_div_fixup_f32 v51, v52, v51, 1.0
	v_fma_f32 v52, -v54, v57, 1.0
	v_fmac_f32_e32 v57, v52, v57
	v_div_scale_f32 v52, vcc, 1.0, v50, 1.0
	v_mul_f32_e32 v53, v52, v57
	v_fma_f32 v55, -v54, v53, v52
	v_fmac_f32_e32 v53, v55, v57
	v_fma_f32 v52, -v54, v53, v52
	v_div_fmas_f32 v52, v52, v57, v53
	v_div_fixup_f32 v50, v52, v50, 1.0
	v_lshlrev_b32_e32 v52, 16, v44
	v_and_b32_e32 v53, 0xffff0000, v44
	v_lshlrev_b32_e32 v54, 16, v46
	v_and_b32_e32 v55, 0xffff0000, v46
	v_lshlrev_b32_e32 v46, 16, v47
	v_and_b32_e32 v47, 0xffff0000, v47
	v_lshlrev_b32_e32 v44, 16, v45
	v_and_b32_e32 v45, 0xffff0000, v45
	v_pk_fma_f32 v[36:37], v[36:37], v[40:41], v[52:53]
	v_pk_fma_f32 v[40:41], v[34:35], v[50:51], v[46:47]
	v_pk_fma_f32 v[34:35], v[32:33], v[42:43], v[54:55]
	v_cvt_pk_bf16_f32 v32, v36, v37
	v_pk_fma_f32 v[38:39], v[38:39], v[48:49], v[44:45]
	s_nop 0
	v_cvt_pk_bf16_f32 v33, v38, v39
	v_cvt_pk_bf16_f32 v34, v34, v35
	v_cvt_pk_bf16_f32 v35, v40, v41
	buffer_store_dwordx4 v[32:35], v56, s[20:23], 0 offen offset:256 sc1
	s_nop 1
	v_add_u32_e32 v32, 0x40a0, v158
	v_mad_i64_i32 v[34:35], s[6:7], v32, s77, 0
	v_lshl_add_u64 v[32:33], v[34:35], 1, s[26:27]
	v_lshl_add_u64 v[32:33], v[32:33], 0, v[142:143]
	v_add_co_u32_e32 v36, vcc, s78, v32
	s_nop 1
	v_addc_co_u32_e32 v37, vcc, 0, v33, vcc
	s_waitcnt vmcnt(11)
; __device__ __forceinline__ float sigmoidf_(float x) { return 1.0f / (1.0f + __expf(-x)); }
; __device__ __forceinline__ u32x4 pack8(const f32x4 v0, const f32x4 v1) { u32x4 w; w.x = pk2(v0[0], v0[1]); w.y = pk2(v0[2], v0[3]); w.z = pk2(v1[0], v1[1]); w.w = pk2(v1[2], v1[3]); return w; }
; __device__ __forceinline__ void unpack8(const u32x4 w, f32x4& v0, f32x4& v1) { v0 = (f32x4){bflo(w.x), bfhi(w.x), bflo(w.y), bfhi(w.y)}; v1 = (f32x4){bflo(w.z), bfhi(w.z), bflo(w.w), bfhi(w.w)}; }
;     __device__ __forceinline__ void operator()(const f32x4 (&acc)[2][2][4][2], const Unit& u, int wr, int wc, int fr, int fq) const {
;     ...
;                 const int row = row0 + ai * 128 + m * 16;
;                 const bf16_t* rowp = z + (size_t)row * DIN + col0;
; #pragma unroll
;                 for (int bj = 0; bj < 2; ++bj) {
;                     const u32x4 gw = *(const u32x4*)(rowp + O_GA + bj * 128);
;                     f32x4 g0, g1; unpack8(gw, g0, g1);
;                     f32x4 v0, v1;
; #pragma unroll
;                     for (int j = 0; j < 4; ++j) { v0[j] = sigmoidf_(g0[j]) * acc[ai][bj][m][0][j]; v1[j] = sigmoidf_(g1[j]) * acc[ai][bj][m][1][j]; }
;                     const u32x4 mw = *(const u32x4*)(rowp + bj * 128); f32x4 m0, m1; unpack8(mw, m0, m1); v0 += m0; v1 += m1;
;                     __builtin_amdgcn_raw_buffer_store_b128(pack8(v0, v1), rsrc, (unsigned)(((size_t)row * DIN + col0 + bj * 128) * 2), 0, 16  ); }
	v_mov_b32_e32 v38, v232
	v_mov_b32_e32 v39, v233
	v_mov_b32_e32 v40, v234
	v_mov_b32_e32 v41, v235
	v_mov_b32_e32 v42, v236
	v_mov_b32_e32 v43, v237
	v_mov_b32_e32 v44, v238
	v_mov_b32_e32 v45, v239
	v_lshlrev_b32_e32 v35, 16, v38
	v_lshlrev_b32_e32 v47, 16, v39
	v_and_b32_e32 v48, 0xffff0000, v39
	v_lshlrev_b32_e32 v39, 16, v40
	v_mul_f32_e32 v35, 0xbfb8aa3b, v35
	v_and_b32_e32 v46, 0xffff0000, v38
	v_exp_f32_e32 v38, v35
	v_mul_f32_e32 v35, 0xbfb8aa3b, v39
	v_and_b32_e32 v49, 0xffff0000, v40
	v_exp_f32_e32 v40, v35
	v_mul_f32_e32 v35, 0xbfb8aa3b, v46
	v_exp_f32_e32 v39, v35
	v_mul_f32_e32 v35, 0xbfb8aa3b, v49
	v_lshlrev_b32_e32 v50, 16, v41
	v_and_b32_e32 v51, 0xffff0000, v41
	v_exp_f32_e32 v41, v35
	v_mul_f32_e32 v35, 0xbfb8aa3b, v47
	v_exp_f32_e32 v46, v35
	v_mul_f32_e32 v35, 0xbfb8aa3b, v48
	v_pk_add_f32 v[38:39], v[38:39], 1.0 op_sel_hi:[1,0]
	v_exp_f32_e32 v47, v35
	v_div_scale_f32 v35, s[6:7], v39, v39, 1.0
	v_rcp_f32_e32 v49, v35
	v_mul_f32_e32 v48, 0xbfb8aa3b, v50
	v_pk_add_f32 v[46:47], v[46:47], 1.0 op_sel_hi:[1,0]
	v_pk_add_f32 v[40:41], v[40:41], 1.0 op_sel_hi:[1,0]
	v_fma_f32 v50, -v35, v49, 1.0
	v_fmac_f32_e32 v49, v50, v49
	v_div_scale_f32 v50, vcc, 1.0, v39, 1.0
	v_mul_f32_e32 v52, v50, v49
	v_fma_f32 v53, -v35, v52, v50
	v_fmac_f32_e32 v52, v53, v49
	v_fma_f32 v35, -v35, v52, v50
	v_div_scale_f32 v50, s[6:7], v38, v38, 1.0
	v_rcp_f32_e32 v53, v50
	v_div_fmas_f32 v35, v35, v49, v52
	v_div_fixup_f32 v39, v35, v39, 1.0
	v_exp_f32_e32 v48, v48
	v_fma_f32 v35, -v50, v53, 1.0
	v_fmac_f32_e32 v53, v35, v53
	v_div_scale_f32 v35, vcc, 1.0, v38, 1.0
	v_mul_f32_e32 v49, v35, v53
	v_fma_f32 v52, -v50, v49, v35
	v_fmac_f32_e32 v49, v52, v53
	v_fma_f32 v35, -v50, v49, v35
	v_div_scale_f32 v50, s[6:7], v47, v47, 1.0
	v_rcp_f32_e32 v52, v50
	v_div_fmas_f32 v35, v35, v53, v49
	v_div_fixup_f32 v38, v35, v38, 1.0
	v_fma_f32 v35, -v50, v52, 1.0
	v_fmac_f32_e32 v52, v35, v52
	v_div_scale_f32 v35, vcc, 1.0, v47, 1.0
	v_mul_f32_e32 v49, v35, v52
	v_fma_f32 v53, -v50, v49, v35
	v_fmac_f32_e32 v49, v53, v52
	v_fma_f32 v35, -v50, v49, v35
	v_div_scale_f32 v50, s[6:7], v46, v46, 1.0
	v_rcp_f32_e32 v53, v50
	v_div_fmas_f32 v35, v35, v52, v49
	v_div_fixup_f32 v47, v35, v47, 1.0
	v_fma_f32 v35, -v50, v53, 1.0
	v_fmac_f32_e32 v53, v35, v53
	v_div_scale_f32 v35, vcc, 1.0, v46, 1.0
	v_mul_f32_e32 v52, v35, v53
	v_fma_f32 v49, -v50, v52, v35
	v_fmac_f32_e32 v52, v49, v53
	v_fma_f32 v35, -v50, v52, v35
	v_div_scale_f32 v50, s[6:7], v41, v41, 1.0
	v_mul_f32_e32 v49, 0xbfb8aa3b, v51
	v_rcp_f32_e32 v51, v50
	v_div_fmas_f32 v35, v35, v53, v52
	v_div_fixup_f32 v46, v35, v46, 1.0
	v_exp_f32_e32 v49, v49
	v_fma_f32 v35, -v50, v51, 1.0
	v_fmac_f32_e32 v51, v35, v51
	v_div_scale_f32 v35, vcc, 1.0, v41, 1.0
	v_mul_f32_e32 v52, v35, v51
	v_fma_f32 v53, -v50, v52, v35
	v_fmac_f32_e32 v52, v53, v51
	v_fma_f32 v35, -v50, v52, v35
	v_div_scale_f32 v50, s[6:7], v40, v40, 1.0
	v_rcp_f32_e32 v53, v50
	v_div_fmas_f32 v35, v35, v51, v52
	v_div_fixup_f32 v41, v35, v41, 1.0
	v_pk_add_f32 v[48:49], v[48:49], 1.0 op_sel_hi:[1,0]
	v_fma_f32 v35, -v50, v53, 1.0
	v_fmac_f32_e32 v53, v35, v53
	v_div_scale_f32 v35, vcc, 1.0, v40, 1.0
	v_mul_f32_e32 v51, v35, v53
	v_fma_f32 v52, -v50, v51, v35
	v_fmac_f32_e32 v51, v52, v53
	v_fma_f32 v35, -v50, v51, v35
	v_div_scale_f32 v50, s[6:7], v49, v49, 1.0
	v_rcp_f32_e32 v52, v50
	v_div_fmas_f32 v35, v35, v53, v51
	v_div_fixup_f32 v40, v35, v40, 1.0
	v_fma_f32 v35, -v50, v52, 1.0
	v_fmac_f32_e32 v52, v35, v52
	v_div_scale_f32 v35, vcc, 1.0, v49, 1.0
	v_mul_f32_e32 v51, v35, v52
	v_fma_f32 v53, -v50, v51, v35
	v_fmac_f32_e32 v51, v53, v52
	v_fma_f32 v35, -v50, v51, v35
	v_div_scale_f32 v50, s[6:7], v48, v48, 1.0
	v_rcp_f32_e32 v53, v50
	v_div_fmas_f32 v35, v35, v52, v51
	v_div_fixup_f32 v49, v35, v49, 1.0
	v_fma_f32 v35, -v50, v53, 1.0
	v_fmac_f32_e32 v53, v35, v53
	v_div_scale_f32 v35, vcc, 1.0, v48, 1.0
	v_mul_f32_e32 v51, v35, v53
	v_fma_f32 v52, -v50, v51, v35
	v_fmac_f32_e32 v51, v52, v53
	v_fma_f32 v35, -v50, v51, v35
	v_div_fmas_f32 v35, v35, v53, v51
	v_div_fixup_f32 v48, v35, v48, 1.0
	v_lshlrev_b32_e32 v50, 16, v42
	v_and_b32_e32 v51, 0xffff0000, v42
	v_lshlrev_b32_e32 v52, 16, v44
	v_and_b32_e32 v53, 0xffff0000, v44
	v_lshlrev_b32_e32 v44, 16, v45
	v_and_b32_e32 v45, 0xffff0000, v45
	v_lshlrev_b32_e32 v42, 16, v43
	v_and_b32_e32 v43, 0xffff0000, v43
	v_pk_fma_f32 v[28:29], v[28:29], v[38:39], v[50:51]
	v_pk_fma_f32 v[38:39], v[26:27], v[48:49], v[44:45]
	v_pk_fma_f32 v[26:27], v[24:25], v[40:41], v[52:53]
	v_add_lshl_u32 v40, v140, v34, 1
	v_pk_fma_f32 v[30:31], v[30:31], v[46:47], v[42:43]
	v_cvt_pk_bf16_f32 v24, v28, v29
	s_nop 0
	v_cvt_pk_bf16_f32 v25, v30, v31
	v_cvt_pk_bf16_f32 v26, v26, v27
	v_cvt_pk_bf16_f32 v27, v38, v39
	buffer_store_dwordx4 v[24:27], v40, s[20:23], 0 offen sc1
	s_nop 0
	s_waitcnt vmcnt(9)
; __device__ __forceinline__ float sigmoidf_(float x) { return 1.0f / (1.0f + __expf(-x)); }
; __device__ __forceinline__ u32x4 pack8(const f32x4 v0, const f32x4 v1) { u32x4 w; w.x = pk2(v0[0], v0[1]); w.y = pk2(v0[2], v0[3]); w.z = pk2(v1[0], v1[1]); w.w = pk2(v1[2], v1[3]); return w; }
; __device__ __forceinline__ void unpack8(const u32x4 w, f32x4& v0, f32x4& v1) { v0 = (f32x4){bflo(w.x), bfhi(w.x), bflo(w.y), bfhi(w.y)}; v1 = (f32x4){bflo(w.z), bfhi(w.z), bflo(w.w), bfhi(w.w)}; }
;     __device__ __forceinline__ void operator()(const f32x4 (&acc)[2][2][4][2], const Unit& u, int wr, int wc, int fr, int fq) const {
;     ...
;                 const int row = row0 + ai * 128 + m * 16;
;                 const bf16_t* rowp = z + (size_t)row * DIN + col0;
; #pragma unroll
;                 for (int bj = 0; bj < 2; ++bj) {
;                     const u32x4 gw = *(const u32x4*)(rowp + O_GA + bj * 128);
;                     f32x4 g0, g1; unpack8(gw, g0, g1);
;                     f32x4 v0, v1;
; #pragma unroll
;                     for (int j = 0; j < 4; ++j) { v0[j] = sigmoidf_(g0[j]) * acc[ai][bj][m][0][j]; v1[j] = sigmoidf_(g1[j]) * acc[ai][bj][m][1][j]; }
;                     const u32x4 mw = *(const u32x4*)(rowp + bj * 128); f32x4 m0, m1; unpack8(mw, m0, m1); v0 += m0; v1 += m1;
;                     __builtin_amdgcn_raw_buffer_store_b128(pack8(v0, v1), rsrc, (unsigned)(((size_t)row * DIN + col0 + bj * 128) * 2), 0, 16  ); }
	v_mov_b32_e32 v24, v240
	v_mov_b32_e32 v25, v241
	v_mov_b32_e32 v26, v242
	v_mov_b32_e32 v27, v243
	v_mov_b32_e32 v28, v244
	v_mov_b32_e32 v29, v245
	v_mov_b32_e32 v30, v246
	v_mov_b32_e32 v31, v247
	v_lshlrev_b32_e32 v34, 16, v25
	v_and_b32_e32 v35, 0xffff0000, v25
	v_lshlrev_b32_e32 v25, 16, v26
	v_lshlrev_b32_e32 v32, 16, v24
	v_and_b32_e32 v33, 0xffff0000, v24
	v_mul_f32_e32 v25, 0xbfb8aa3b, v25
	v_and_b32_e32 v36, 0xffff0000, v26
	v_mul_f32_e32 v24, 0xbfb8aa3b, v32
	v_exp_f32_e32 v26, v25
	v_mul_f32_e32 v25, 0xbfb8aa3b, v33
	v_exp_f32_e32 v24, v24
	v_exp_f32_e32 v25, v25
	v_mul_f32_e32 v33, 0xbfb8aa3b, v35
	v_lshlrev_b32_e32 v37, 16, v27
	v_and_b32_e32 v38, 0xffff0000, v27
	v_pk_add_f32 v[24:25], v[24:25], 1.0 op_sel_hi:[1,0]
	v_mul_f32_e32 v27, 0xbfb8aa3b, v36
	v_div_scale_f32 v35, s[6:7], v25, v25, 1.0
	v_rcp_f32_e32 v36, v35
	v_mul_f32_e32 v32, 0xbfb8aa3b, v34
	v_mul_f32_e32 v34, 0xbfb8aa3b, v37
	v_exp_f32_e32 v32, v32
	v_fma_f32 v37, -v35, v36, 1.0
	v_fmac_f32_e32 v36, v37, v36
	v_div_scale_f32 v37, vcc, 1.0, v25, 1.0
	v_mul_f32_e32 v39, v37, v36
	v_fma_f32 v41, -v35, v39, v37
	v_fmac_f32_e32 v39, v41, v36
	v_fma_f32 v35, -v35, v39, v37
	v_div_scale_f32 v37, s[6:7], v24, v24, 1.0
	v_rcp_f32_e32 v41, v37
	v_div_fmas_f32 v35, v35, v36, v39
	v_exp_f32_e32 v33, v33
	v_div_fixup_f32 v25, v35, v25, 1.0
	v_fma_f32 v35, -v37, v41, 1.0
	v_fmac_f32_e32 v41, v35, v41
	v_div_scale_f32 v35, vcc, 1.0, v24, 1.0
	v_mul_f32_e32 v36, v35, v41
	v_fma_f32 v39, -v37, v36, v35
	v_pk_add_f32 v[32:33], v[32:33], 1.0 op_sel_hi:[1,0]
	v_fmac_f32_e32 v36, v39, v41
	v_fma_f32 v35, -v37, v36, v35
	v_div_scale_f32 v37, s[6:7], v33, v33, 1.0
	v_rcp_f32_e32 v39, v37
	v_div_fmas_f32 v35, v35, v41, v36
	v_div_fixup_f32 v24, v35, v24, 1.0
	v_exp_f32_e32 v27, v27
	v_fma_f32 v35, -v37, v39, 1.0
	v_fmac_f32_e32 v39, v35, v39
	v_div_scale_f32 v35, vcc, 1.0, v33, 1.0
	v_mul_f32_e32 v36, v35, v39
	v_fma_f32 v41, -v37, v36, v35
	v_fmac_f32_e32 v36, v41, v39
	v_fma_f32 v35, -v37, v36, v35
	v_div_scale_f32 v37, s[6:7], v32, v32, 1.0
	v_rcp_f32_e32 v41, v37
	v_div_fmas_f32 v35, v35, v39, v36
	v_div_fixup_f32 v33, v35, v33, 1.0
	v_pk_add_f32 v[26:27], v[26:27], 1.0 op_sel_hi:[1,0]
	v_fma_f32 v35, -v37, v41, 1.0
	v_fmac_f32_e32 v41, v35, v41
	v_div_scale_f32 v35, vcc, 1.0, v32, 1.0
	v_mul_f32_e32 v36, v35, v41
	v_fma_f32 v39, -v37, v36, v35
	v_fmac_f32_e32 v36, v39, v41
	v_fma_f32 v37, -v37, v36, v35
	v_mul_f32_e32 v35, 0xbfb8aa3b, v38
	v_div_scale_f32 v38, s[6:7], v27, v27, 1.0
	v_rcp_f32_e32 v39, v38
	v_div_fmas_f32 v36, v37, v41, v36
	v_div_fixup_f32 v32, v36, v32, 1.0
	v_exp_f32_e32 v34, v34
	v_fma_f32 v36, -v38, v39, 1.0
	v_fmac_f32_e32 v39, v36, v39
	v_div_scale_f32 v36, vcc, 1.0, v27, 1.0
	v_mul_f32_e32 v37, v36, v39
	v_fma_f32 v41, -v38, v37, v36
	v_fmac_f32_e32 v37, v41, v39
	v_fma_f32 v36, -v38, v37, v36
	v_div_scale_f32 v38, s[6:7], v26, v26, 1.0
	v_rcp_f32_e32 v41, v38
	v_div_fmas_f32 v36, v36, v39, v37
	v_exp_f32_e32 v35, v35
	v_div_fixup_f32 v27, v36, v27, 1.0
	v_fma_f32 v36, -v38, v41, 1.0
	v_fmac_f32_e32 v41, v36, v41
	v_div_scale_f32 v36, vcc, 1.0, v26, 1.0
	v_mul_f32_e32 v37, v36, v41
	v_fma_f32 v39, -v38, v37, v36
	v_pk_add_f32 v[34:35], v[34:35], 1.0 op_sel_hi:[1,0]
	v_fmac_f32_e32 v37, v39, v41
	v_fma_f32 v36, -v38, v37, v36
	v_div_scale_f32 v38, s[6:7], v35, v35, 1.0
	v_rcp_f32_e32 v39, v38
	v_div_fmas_f32 v36, v36, v41, v37
	v_div_fixup_f32 v26, v36, v26, 1.0
	v_fma_f32 v36, -v38, v39, 1.0
	v_fmac_f32_e32 v39, v36, v39
	v_div_scale_f32 v36, vcc, 1.0, v35, 1.0
	v_mul_f32_e32 v37, v36, v39
	v_fma_f32 v41, -v38, v37, v36
	v_fmac_f32_e32 v37, v41, v39
	v_fma_f32 v36, -v38, v37, v36
	v_div_scale_f32 v38, s[6:7], v34, v34, 1.0
	v_rcp_f32_e32 v41, v38
	v_div_fmas_f32 v36, v36, v39, v37
	v_div_fixup_f32 v35, v36, v35, 1.0
	v_fma_f32 v36, -v38, v41, 1.0
	v_fmac_f32_e32 v41, v36, v41
	v_div_scale_f32 v36, vcc, 1.0, v34, 1.0
	v_mul_f32_e32 v37, v36, v41
	v_fma_f32 v39, -v38, v37, v36
	v_fmac_f32_e32 v37, v39, v41
	v_fma_f32 v36, -v38, v37, v36
	v_div_fmas_f32 v36, v36, v41, v37
	v_div_fixup_f32 v34, v36, v34, 1.0
	v_lshlrev_b32_e32 v36, 16, v28
	v_and_b32_e32 v37, 0xffff0000, v28
	v_lshlrev_b32_e32 v38, 16, v30
	v_and_b32_e32 v39, 0xffff0000, v30
	v_lshlrev_b32_e32 v30, 16, v31
	v_and_b32_e32 v31, 0xffff0000, v31
	v_lshlrev_b32_e32 v28, 16, v29
	v_and_b32_e32 v29, 0xffff0000, v29
	v_pk_fma_f32 v[20:21], v[20:21], v[24:25], v[36:37]
	v_pk_fma_f32 v[24:25], v[18:19], v[34:35], v[30:31]
	v_pk_fma_f32 v[18:19], v[16:17], v[26:27], v[38:39]
	v_cvt_pk_bf16_f32 v16, v20, v21
	v_pk_fma_f32 v[22:23], v[22:23], v[32:33], v[28:29]
	s_nop 0
	v_cvt_pk_bf16_f32 v17, v22, v23
	v_cvt_pk_bf16_f32 v18, v18, v19
	v_cvt_pk_bf16_f32 v19, v24, v25
	buffer_store_dwordx4 v[16:19], v40, s[20:23], 0 offen offset:256 sc1
	s_nop 1
	v_add_u32_e32 v16, 0x40b0, v158
	v_mad_i64_i32 v[18:19], s[6:7], v16, s77, 0
	v_lshl_add_u64 v[16:17], v[18:19], 1, s[26:27]
	v_lshl_add_u64 v[16:17], v[16:17], 0, v[142:143]
	v_add_co_u32_e32 v20, vcc, s78, v16
	s_nop 1
	v_addc_co_u32_e32 v21, vcc, 0, v17, vcc
	s_waitcnt vmcnt(7)
; __device__ __forceinline__ float sigmoidf_(float x) { return 1.0f / (1.0f + __expf(-x)); }
; __device__ __forceinline__ u32x4 pack8(const f32x4 v0, const f32x4 v1) { u32x4 w; w.x = pk2(v0[0], v0[1]); w.y = pk2(v0[2], v0[3]); w.z = pk2(v1[0], v1[1]); w.w = pk2(v1[2], v1[3]); return w; }
; __device__ __forceinline__ void unpack8(const u32x4 w, f32x4& v0, f32x4& v1) { v0 = (f32x4){bflo(w.x), bfhi(w.x), bflo(w.y), bfhi(w.y)}; v1 = (f32x4){bflo(w.z), bfhi(w.z), bflo(w.w), bfhi(w.w)}; }
;     __device__ __forceinline__ void operator()(const f32x4 (&acc)[2][2][4][2], const Unit& u, int wr, int wc, int fr, int fq) const {
;     ...
;                 const int row = row0 + ai * 128 + m * 16;
;                 const bf16_t* rowp = z + (size_t)row * DIN + col0;
; #pragma unroll
;                 for (int bj = 0; bj < 2; ++bj) {
;                     const u32x4 gw = *(const u32x4*)(rowp + O_GA + bj * 128);
;                     f32x4 g0, g1; unpack8(gw, g0, g1);
;                     f32x4 v0, v1;
; #pragma unroll
;                     for (int j = 0; j < 4; ++j) { v0[j] = sigmoidf_(g0[j]) * acc[ai][bj][m][0][j]; v1[j] = sigmoidf_(g1[j]) * acc[ai][bj][m][1][j]; }
;                     const u32x4 mw = *(const u32x4*)(rowp + bj * 128); f32x4 m0, m1; unpack8(mw, m0, m1); v0 += m0; v1 += m1;
;                     __builtin_amdgcn_raw_buffer_store_b128(pack8(v0, v1), rsrc, (unsigned)(((size_t)row * DIN + col0 + bj * 128) * 2), 0, 16  ); }
	v_mov_b32_e32 v22, v248
	v_mov_b32_e32 v23, v249
	v_mov_b32_e32 v24, v250
	v_mov_b32_e32 v25, v251
	v_mov_b32_e32 v26, v252
	v_mov_b32_e32 v27, v253
	v_mov_b32_e32 v28, v254
	v_mov_b32_e32 v29, v255
	v_lshlrev_b32_e32 v19, 16, v22
	v_lshlrev_b32_e32 v31, 16, v23
	v_and_b32_e32 v32, 0xffff0000, v23
	v_lshlrev_b32_e32 v23, 16, v24
	v_mul_f32_e32 v19, 0xbfb8aa3b, v19
	v_and_b32_e32 v30, 0xffff0000, v22
	v_exp_f32_e32 v22, v19
	v_mul_f32_e32 v19, 0xbfb8aa3b, v23
	v_and_b32_e32 v33, 0xffff0000, v24
	v_exp_f32_e32 v24, v19
	v_mul_f32_e32 v19, 0xbfb8aa3b, v30
	v_exp_f32_e32 v23, v19
	v_mul_f32_e32 v19, 0xbfb8aa3b, v33
	v_lshlrev_b32_e32 v34, 16, v25
	v_and_b32_e32 v35, 0xffff0000, v25
	v_exp_f32_e32 v25, v19
	v_mul_f32_e32 v19, 0xbfb8aa3b, v31
	v_exp_f32_e32 v30, v19
	v_mul_f32_e32 v19, 0xbfb8aa3b, v32
	v_pk_add_f32 v[22:23], v[22:23], 1.0 op_sel_hi:[1,0]
	v_exp_f32_e32 v31, v19
	v_div_scale_f32 v19, s[6:7], v23, v23, 1.0
	v_rcp_f32_e32 v33, v19
	v_mul_f32_e32 v32, 0xbfb8aa3b, v34
	v_pk_add_f32 v[30:31], v[30:31], 1.0 op_sel_hi:[1,0]
	v_pk_add_f32 v[24:25], v[24:25], 1.0 op_sel_hi:[1,0]
	v_fma_f32 v34, -v19, v33, 1.0
	v_fmac_f32_e32 v33, v34, v33
	v_div_scale_f32 v34, vcc, 1.0, v23, 1.0
	v_mul_f32_e32 v36, v34, v33
	v_fma_f32 v37, -v19, v36, v34
	v_fmac_f32_e32 v36, v37, v33
	v_fma_f32 v19, -v19, v36, v34
	v_div_scale_f32 v34, s[6:7], v22, v22, 1.0
	v_rcp_f32_e32 v37, v34
	v_div_fmas_f32 v19, v19, v33, v36
	v_div_fixup_f32 v23, v19, v23, 1.0
	v_exp_f32_e32 v32, v32
	v_fma_f32 v19, -v34, v37, 1.0
	v_fmac_f32_e32 v37, v19, v37
	v_div_scale_f32 v19, vcc, 1.0, v22, 1.0
	v_mul_f32_e32 v33, v19, v37
	v_fma_f32 v36, -v34, v33, v19
	v_fmac_f32_e32 v33, v36, v37
	v_fma_f32 v19, -v34, v33, v19
	v_div_scale_f32 v34, s[6:7], v31, v31, 1.0
	v_rcp_f32_e32 v36, v34
	v_div_fmas_f32 v19, v19, v37, v33
	v_div_fixup_f32 v22, v19, v22, 1.0
	v_fma_f32 v19, -v34, v36, 1.0
	v_fmac_f32_e32 v36, v19, v36
	v_div_scale_f32 v19, vcc, 1.0, v31, 1.0
	v_mul_f32_e32 v33, v19, v36
	v_fma_f32 v37, -v34, v33, v19
	v_fmac_f32_e32 v33, v37, v36
	v_fma_f32 v19, -v34, v33, v19
	v_div_scale_f32 v34, s[6:7], v30, v30, 1.0
	v_rcp_f32_e32 v37, v34
	v_div_fmas_f32 v19, v19, v36, v33
	v_div_fixup_f32 v31, v19, v31, 1.0
	v_fma_f32 v19, -v34, v37, 1.0
	v_fmac_f32_e32 v37, v19, v37
	v_div_scale_f32 v19, vcc, 1.0, v30, 1.0
	v_mul_f32_e32 v36, v19, v37
	v_fma_f32 v33, -v34, v36, v19
	v_fmac_f32_e32 v36, v33, v37
	v_fma_f32 v19, -v34, v36, v19
	v_div_scale_f32 v34, s[6:7], v25, v25, 1.0
	v_mul_f32_e32 v33, 0xbfb8aa3b, v35
	v_rcp_f32_e32 v35, v34
	v_div_fmas_f32 v19, v19, v37, v36
	v_div_fixup_f32 v30, v19, v30, 1.0
	v_exp_f32_e32 v33, v33
	v_fma_f32 v19, -v34, v35, 1.0
	v_fmac_f32_e32 v35, v19, v35
	v_div_scale_f32 v19, vcc, 1.0, v25, 1.0
	v_mul_f32_e32 v36, v19, v35
	v_fma_f32 v37, -v34, v36, v19
	v_fmac_f32_e32 v36, v37, v35
	v_fma_f32 v19, -v34, v36, v19
	v_div_scale_f32 v34, s[6:7], v24, v24, 1.0
	v_rcp_f32_e32 v37, v34
	v_div_fmas_f32 v19, v19, v35, v36
	v_div_fixup_f32 v25, v19, v25, 1.0
	v_pk_add_f32 v[32:33], v[32:33], 1.0 op_sel_hi:[1,0]
	v_fma_f32 v19, -v34, v37, 1.0
	v_fmac_f32_e32 v37, v19, v37
	v_div_scale_f32 v19, vcc, 1.0, v24, 1.0
	v_mul_f32_e32 v35, v19, v37
	v_fma_f32 v36, -v34, v35, v19
	v_fmac_f32_e32 v35, v36, v37
	v_fma_f32 v19, -v34, v35, v19
	v_div_scale_f32 v34, s[6:7], v33, v33, 1.0
	v_rcp_f32_e32 v36, v34
	v_div_fmas_f32 v19, v19, v37, v35
	v_div_fixup_f32 v24, v19, v24, 1.0
	v_fma_f32 v19, -v34, v36, 1.0
	v_fmac_f32_e32 v36, v19, v36
	v_div_scale_f32 v19, vcc, 1.0, v33, 1.0
	v_mul_f32_e32 v35, v19, v36
	v_fma_f32 v37, -v34, v35, v19
	v_fmac_f32_e32 v35, v37, v36
	v_fma_f32 v19, -v34, v35, v19
	v_div_scale_f32 v34, s[6:7], v32, v32, 1.0
	v_rcp_f32_e32 v37, v34
	v_div_fmas_f32 v19, v19, v36, v35
	v_div_fixup_f32 v33, v19, v33, 1.0
	v_fma_f32 v19, -v34, v37, 1.0
	v_fmac_f32_e32 v37, v19, v37
	v_div_scale_f32 v19, vcc, 1.0, v32, 1.0
	v_mul_f32_e32 v35, v19, v37
	v_fma_f32 v36, -v34, v35, v19
	v_fmac_f32_e32 v35, v36, v37
	v_fma_f32 v19, -v34, v35, v19
	v_div_fmas_f32 v19, v19, v37, v35
	v_div_fixup_f32 v32, v19, v32, 1.0
	v_lshlrev_b32_e32 v34, 16, v26
	v_and_b32_e32 v35, 0xffff0000, v26
	v_lshlrev_b32_e32 v36, 16, v28
	v_and_b32_e32 v37, 0xffff0000, v28
	v_lshlrev_b32_e32 v28, 16, v29
	v_and_b32_e32 v29, 0xffff0000, v29
	v_lshlrev_b32_e32 v26, 16, v27
	v_and_b32_e32 v27, 0xffff0000, v27
	v_pk_fma_f32 v[12:13], v[12:13], v[22:23], v[34:35]
	v_pk_fma_f32 v[22:23], v[10:11], v[32:33], v[28:29]
	v_pk_fma_f32 v[10:11], v[8:9], v[24:25], v[36:37]
	v_add_lshl_u32 v24, v140, v18, 1
	v_pk_fma_f32 v[14:15], v[14:15], v[30:31], v[26:27]
	v_cvt_pk_bf16_f32 v8, v12, v13
	s_nop 0
	v_cvt_pk_bf16_f32 v9, v14, v15
	v_cvt_pk_bf16_f32 v10, v10, v11
	v_cvt_pk_bf16_f32 v11, v22, v23
	buffer_store_dwordx4 v[8:11], v24, s[20:23], 0 offen sc1
	s_nop 0
	s_waitcnt vmcnt(5)
; __device__ __forceinline__ float sigmoidf_(float x) { return 1.0f / (1.0f + __expf(-x)); }
; __device__ __forceinline__ u32x4 pack8(const f32x4 v0, const f32x4 v1) { u32x4 w; w.x = pk2(v0[0], v0[1]); w.y = pk2(v0[2], v0[3]); w.z = pk2(v1[0], v1[1]); w.w = pk2(v1[2], v1[3]); return w; }
; __device__ __forceinline__ void unpack8(const u32x4 w, f32x4& v0, f32x4& v1) { v0 = (f32x4){bflo(w.x), bfhi(w.x), bflo(w.y), bfhi(w.y)}; v1 = (f32x4){bflo(w.z), bfhi(w.z), bflo(w.w), bfhi(w.w)}; }
;     __device__ __forceinline__ void operator()(const f32x4 (&acc)[2][2][4][2], const Unit& u, int wr, int wc, int fr, int fq) const {
;         const __amdgpu_buffer_rsrc_t rsrc = __builtin_amdgcn_make_buffer_rsrc((void*)z, 0, T_ALL * DIN * 2, 0x00020000);
;         const int row0 = row_off + u.pm * 256 + wr * 64 + fr, col0 = u.pn * 256 + wc * 32 + 8 * fq;
; #pragma unroll
;         for (int ai = 0; ai < 2; ++ai)
; #pragma unroll
;             for (int m = 0; m < 4; ++m) {
;                 const int row = row0 + ai * 128 + m * 16;
;                 const bf16_t* rowp = z + (size_t)row * DIN + col0;
; #pragma unroll
;                 for (int bj = 0; bj < 2; ++bj) {
;                     const u32x4 gw = *(const u32x4*)(rowp + O_GA + bj * 128);
;                     f32x4 g0, g1; unpack8(gw, g0, g1);
;                     f32x4 v0, v1;
; #pragma unroll
;                     for (int j = 0; j < 4; ++j) { v0[j] = sigmoidf_(g0[j]) * acc[ai][bj][m][0][j]; v1[j] = sigmoidf_(g1[j]) * acc[ai][bj][m][1][j]; }
;                     const u32x4 mw = *(const u32x4*)(rowp + bj * 128); f32x4 m0, m1; unpack8(mw, m0, m1); v0 += m0; v1 += m1;
;                     __builtin_amdgcn_raw_buffer_store_b128(pack8(v0, v1), rsrc, (unsigned)(((size_t)row * DIN + col0 + bj * 128) * 2), 0, 16  ); }
;             }
;         asm volatile("s_waitcnt vmcnt(0)" ::: "memory");
;         if (fr == 0 && fq == 0) (void)__hip_atomic_fetch_add(ready + 64 * (pm_off + u.pm), 1u, __ATOMIC_RELAXED, __HIP_MEMORY_SCOPE_AGENT);
;     }
	v_mov_b32_e32 v8, v200
	v_mov_b32_e32 v9, v201
	v_mov_b32_e32 v10, v202
	v_mov_b32_e32 v11, v203
	v_mov_b32_e32 v12, v204
	v_mov_b32_e32 v13, v205
	v_mov_b32_e32 v14, v206
	v_mov_b32_e32 v15, v207
	v_lshlrev_b32_e32 v18, 16, v9
	v_and_b32_e32 v19, 0xffff0000, v9
	v_lshlrev_b32_e32 v9, 16, v10
	v_lshlrev_b32_e32 v16, 16, v8
	v_and_b32_e32 v17, 0xffff0000, v8
	v_mul_f32_e32 v9, 0xbfb8aa3b, v9
	v_and_b32_e32 v20, 0xffff0000, v10
	v_mul_f32_e32 v8, 0xbfb8aa3b, v16
	v_exp_f32_e32 v10, v9
	v_mul_f32_e32 v9, 0xbfb8aa3b, v17
	v_exp_f32_e32 v8, v8
	v_exp_f32_e32 v9, v9
	v_mul_f32_e32 v17, 0xbfb8aa3b, v19
	v_lshlrev_b32_e32 v21, 16, v11
	v_and_b32_e32 v22, 0xffff0000, v11
	v_pk_add_f32 v[8:9], v[8:9], 1.0 op_sel_hi:[1,0]
	v_mul_f32_e32 v11, 0xbfb8aa3b, v20
	v_div_scale_f32 v19, s[6:7], v9, v9, 1.0
	v_rcp_f32_e32 v20, v19
	v_mul_f32_e32 v16, 0xbfb8aa3b, v18
	v_mul_f32_e32 v18, 0xbfb8aa3b, v21
	v_exp_f32_e32 v16, v16
	v_fma_f32 v21, -v19, v20, 1.0
	v_fmac_f32_e32 v20, v21, v20
	v_div_scale_f32 v21, vcc, 1.0, v9, 1.0
	v_mul_f32_e32 v23, v21, v20
	v_fma_f32 v25, -v19, v23, v21
	v_fmac_f32_e32 v23, v25, v20
	v_fma_f32 v19, -v19, v23, v21
	v_div_scale_f32 v21, s[6:7], v8, v8, 1.0
	v_rcp_f32_e32 v25, v21
	v_div_fmas_f32 v19, v19, v20, v23
	v_exp_f32_e32 v17, v17
	v_div_fixup_f32 v9, v19, v9, 1.0
	v_fma_f32 v19, -v21, v25, 1.0
	v_fmac_f32_e32 v25, v19, v25
	v_div_scale_f32 v19, vcc, 1.0, v8, 1.0
	v_mul_f32_e32 v20, v19, v25
	v_fma_f32 v23, -v21, v20, v19
	v_pk_add_f32 v[16:17], v[16:17], 1.0 op_sel_hi:[1,0]
	v_fmac_f32_e32 v20, v23, v25
	v_fma_f32 v19, -v21, v20, v19
	v_div_scale_f32 v21, s[6:7], v17, v17, 1.0
	v_rcp_f32_e32 v23, v21
	v_div_fmas_f32 v19, v19, v25, v20
	v_div_fixup_f32 v8, v19, v8, 1.0
	v_exp_f32_e32 v11, v11
	v_fma_f32 v19, -v21, v23, 1.0
	v_fmac_f32_e32 v23, v19, v23
	v_div_scale_f32 v19, vcc, 1.0, v17, 1.0
	v_mul_f32_e32 v20, v19, v23
	v_fma_f32 v25, -v21, v20, v19
	v_fmac_f32_e32 v20, v25, v23
	v_fma_f32 v19, -v21, v20, v19
	v_div_scale_f32 v21, s[6:7], v16, v16, 1.0
	v_rcp_f32_e32 v25, v21
	v_div_fmas_f32 v19, v19, v23, v20
	v_div_fixup_f32 v17, v19, v17, 1.0
	v_pk_add_f32 v[10:11], v[10:11], 1.0 op_sel_hi:[1,0]
	v_fma_f32 v19, -v21, v25, 1.0
	v_fmac_f32_e32 v25, v19, v25
	v_div_scale_f32 v19, vcc, 1.0, v16, 1.0
	v_mul_f32_e32 v20, v19, v25
	v_fma_f32 v23, -v21, v20, v19
	v_fmac_f32_e32 v20, v23, v25
	v_fma_f32 v21, -v21, v20, v19
	v_mul_f32_e32 v19, 0xbfb8aa3b, v22
	v_div_scale_f32 v22, s[6:7], v11, v11, 1.0
	v_rcp_f32_e32 v23, v22
	v_div_fmas_f32 v20, v21, v25, v20
	v_div_fixup_f32 v16, v20, v16, 1.0
	v_exp_f32_e32 v18, v18
	v_fma_f32 v20, -v22, v23, 1.0
	v_fmac_f32_e32 v23, v20, v23
	v_div_scale_f32 v20, vcc, 1.0, v11, 1.0
	v_mul_f32_e32 v21, v20, v23
	v_fma_f32 v25, -v22, v21, v20
	v_fmac_f32_e32 v21, v25, v23
	v_fma_f32 v20, -v22, v21, v20
	v_div_scale_f32 v22, s[6:7], v10, v10, 1.0
	v_rcp_f32_e32 v25, v22
	v_div_fmas_f32 v20, v20, v23, v21
	v_exp_f32_e32 v19, v19
	v_div_fixup_f32 v11, v20, v11, 1.0
	v_fma_f32 v20, -v22, v25, 1.0
	v_fmac_f32_e32 v25, v20, v25
	v_div_scale_f32 v20, vcc, 1.0, v10, 1.0
	v_mul_f32_e32 v21, v20, v25
	v_fma_f32 v23, -v22, v21, v20
	v_pk_add_f32 v[18:19], v[18:19], 1.0 op_sel_hi:[1,0]
	v_fmac_f32_e32 v21, v23, v25
	v_fma_f32 v20, -v22, v21, v20
	v_div_scale_f32 v22, s[6:7], v19, v19, 1.0
	v_rcp_f32_e32 v23, v22
	v_div_fmas_f32 v20, v20, v25, v21
	v_div_fixup_f32 v10, v20, v10, 1.0
	v_fma_f32 v20, -v22, v23, 1.0
	v_fmac_f32_e32 v23, v20, v23
	v_div_scale_f32 v20, vcc, 1.0, v19, 1.0
	v_mul_f32_e32 v21, v20, v23
	v_fma_f32 v25, -v22, v21, v20
	v_fmac_f32_e32 v21, v25, v23
	v_fma_f32 v20, -v22, v21, v20
	v_div_scale_f32 v22, s[6:7], v18, v18, 1.0
	v_rcp_f32_e32 v25, v22
	v_div_fmas_f32 v20, v20, v23, v21
	v_div_fixup_f32 v19, v20, v19, 1.0
	v_fma_f32 v20, -v22, v25, 1.0
	v_fmac_f32_e32 v25, v20, v25
	v_div_scale_f32 v20, vcc, 1.0, v18, 1.0
	v_mul_f32_e32 v21, v20, v25
	v_fma_f32 v23, -v22, v21, v20
	v_fmac_f32_e32 v21, v23, v25
	v_fma_f32 v20, -v22, v21, v20
	v_div_fmas_f32 v20, v20, v25, v21
	v_div_fixup_f32 v18, v20, v18, 1.0
	v_lshlrev_b32_e32 v20, 16, v12
	v_and_b32_e32 v21, 0xffff0000, v12
	v_lshlrev_b32_e32 v22, 16, v14
	v_and_b32_e32 v23, 0xffff0000, v14
	v_lshlrev_b32_e32 v14, 16, v15
	v_and_b32_e32 v15, 0xffff0000, v15
	v_lshlrev_b32_e32 v12, 16, v13
	v_and_b32_e32 v13, 0xffff0000, v13
	v_pk_fma_f32 v[4:5], v[4:5], v[8:9], v[20:21]
	v_pk_fma_f32 v[8:9], v[2:3], v[18:19], v[14:15]
	v_pk_fma_f32 v[2:3], v[0:1], v[10:11], v[22:23]
	v_pk_fma_f32 v[6:7], v[6:7], v[16:17], v[12:13]
	v_cvt_pk_bf16_f32 v0, v4, v5
	s_nop 0
	v_cvt_pk_bf16_f32 v1, v6, v7
	v_cvt_pk_bf16_f32 v2, v2, v3
	v_cvt_pk_bf16_f32 v3, v8, v9
	buffer_store_dwordx4 v[0:3], v24, s[20:23], 0 offen offset:256 sc1
	s_waitcnt vmcnt(0)
	s_and_saveexec_b64 s[12:13], s[10:11]
	s_cbranch_execz .LBB0_715
	s_mov_b64 s[14:15], exec
	v_mbcnt_lo_u32_b32 v0, s14, 0
	v_mbcnt_hi_u32_b32 v0, s15, v0
	v_cmp_eq_u32_e32 vcc, 0, v0
	s_and_b64 s[6:7], exec, vcc
	s_mov_b64 exec, s[6:7]
	s_cbranch_execz .LBB0_715
	s_lshl_b32 s6, s79, 6
	s_addk_i32 s6, 0x1000
	s_ashr_i32 s7, s6, 31
	s_lshl_b64 s[6:7], s[6:7], 2
	s_add_u32 s6, s34, s6
	s_addc_u32 s7, s35, s7
	s_bcnt1_i32_b64 s8, s[14:15]
	v_mov_b32_e32 v0, s8
	global_atomic_add v131, v0, s[6:7]
	s_branch .LBB0_715

; #define PG8_STAGE(bufoff, gbase, voff) do { _Pragma("unroll") for (int _i = 0; _i < 2; ++_i) \
;         __builtin_amdgcn_global_load_lds((const unsigned*)((const char*)(gbase) + (voff)[_i]), (LAS unsigned*)(lds + (bufoff) + ldsw + _i * 8192), 16, 0, 0); } while (0)
; #define PG8_LDA(dst, b, h) do { _Pragma("unroll") for (int m = 0; m < 4; ++m) _Pragma("unroll") for (int k = 0; k < 2; ++k) dst[m][k] = *(const LAS bf16x8*)(lds + PG8_SA(b, h) + aoff + m * 2048 + k * 1024); } while (0)
; #define PG8_LDB(dst, b, h) do { _Pragma("unroll") for (int n = 0; n < 2; ++n) _Pragma("unroll") for (int k = 0; k < 2; ++k) dst[n][k] = *(const LAS bf16x8*)(lds + PG8_SB(b, h) + boff + n * 2048 + k * 1024); } while (0)
; #define PG8_MMA(ai, bj, At, Bt) do { __builtin_amdgcn_s_setprio(1); _Pragma("unroll") for (int m = 0; m < 4; ++m) _Pragma("unroll") for (int n = 0; n < 2; ++n) _Pragma("unroll") for (int k = 0; k < 2; ++k) \
;         acc[ai][bj][m][n] = __builtin_amdgcn_mfma_f32_16x16x32_bf16(Bt[n][k], At[m][k], acc[ai][bj][m][n], 0, 0, 0); __builtin_amdgcn_s_setprio(0); } while (0)
; #define PG8_WAIT_V(n) asm volatile("s_waitcnt vmcnt(" #n ")" ::: "memory")
; #define PG8_WAIT_L(n) asm volatile("s_waitcnt lgkmcnt(" #n ")" ::: "memory")
; #define PG8_BAR __builtin_amdgcn_s_barrier()
; #define PG8_SCHED __builtin_amdgcn_sched_barrier(0)
;     ...
;             PG8_LDB(B0, 0, 0); PG8_SCHED; PG8_LDA(At, 0, 0); PG8_STAGE(PG8_SA(1, 1), a1 + hA, voffA);
;             PG8_WAIT_L(8); PG8_BAR; PG8_WAIT_L(0); PG8_MMA(0, 0, At, B0); PG8_BAR; PG8_SCHED;
;             PG8_LDB(B1, 0, 1); PG8_STAGE(PG8_SB(0, 0), b2, voffB);
;             PG8_BAR; PG8_WAIT_L(0); PG8_MMA(0, 1, At, B1); PG8_BAR;
;             PG8_LDA(At, 0, 1); PG8_STAGE(PG8_SA(0, 0), a2, voffA);
;             PG8_BAR; PG8_WAIT_L(0); PG8_MMA(1, 0, At, B0); PG8_BAR; PG8_SCHED;
;             PG8_STAGE(PG8_SB(0, 1), b2 + hB, voffB);
;             PG8_WAIT_V(6); PG8_BAR; PG8_MMA(1, 1, At, B1); PG8_BAR;
.LBB0_958:
	ds_read_b128 v[156:159], v151
	ds_read_b128 v[160:163], v151 offset:1024
	ds_read_b128 v[170:173], v151 offset:2048
	ds_read_b128 v[174:177], v151 offset:3072
	s_add_u32 s43, s40, 0xfffc0080
	s_addc_u32 s44, s41, -1
	s_cmp_eq_u32 s42, 12
	s_cselect_b32 s57, s7, s44
	s_cselect_b32 s56, s8, s43
	s_cselect_b32 s55, s9, s39
	s_cselect_b32 s54, s29, s33
	v_lshl_add_u64 v[146:147], s[40:41], 0, v[138:139]
	s_add_i32 m0, s61, 0xc000
	ds_read_b128 v[178:181], v152
	ds_read_b128 v[182:185], v152 offset:1024
	ds_read_b128 v[186:189], v152 offset:2048
	ds_read_b128 v[190:193], v152 offset:3072
	ds_read_b128 v[194:197], v152 offset:4096
	ds_read_b128 v[198:201], v152 offset:5120
	ds_read_b128 v[202:205], v152 offset:6144
	ds_read_b128 v[206:209], v152 offset:7168
	global_load_lds_dwordx4 v[146:147], off
	v_lshl_add_u64 v[146:147], s[40:41], 0, v[136:137]
	s_add_i32 m0, s61, 0xe000
	s_nop 0
	global_load_lds_dwordx4 v[146:147], off
	s_waitcnt lgkmcnt(8)
	s_barrier
	s_waitcnt lgkmcnt(0)
	s_setprio 1
	s_waitcnt lgkmcnt(0)
	v_mfma_f32_16x16x32_bf16 v[124:127], v[156:159], v[178:181], v[124:127]
	v_mfma_f32_16x16x32_bf16 v[120:123], v[170:173], v[178:181], v[120:123]
	v_mfma_f32_16x16x32_bf16 v[108:111], v[156:159], v[186:189], v[108:111]
	v_mfma_f32_16x16x32_bf16 v[104:107], v[170:173], v[186:189], v[104:107]
	v_mfma_f32_16x16x32_bf16 v[92:95], v[156:159], v[194:197], v[92:95]
	v_mfma_f32_16x16x32_bf16 v[88:91], v[170:173], v[194:197], v[88:91]
	v_mfma_f32_16x16x32_bf16 v[76:79], v[156:159], v[202:205], v[76:79]
	v_mfma_f32_16x16x32_bf16 v[72:75], v[170:173], v[202:205], v[72:75]
	v_mfma_f32_16x16x32_bf16 v[124:127], v[160:163], v[182:185], v[124:127]
	v_mfma_f32_16x16x32_bf16 v[120:123], v[174:177], v[182:185], v[120:123]
	v_mfma_f32_16x16x32_bf16 v[108:111], v[160:163], v[190:193], v[108:111]
	v_mfma_f32_16x16x32_bf16 v[104:107], v[174:177], v[190:193], v[104:107]
	v_mfma_f32_16x16x32_bf16 v[92:95], v[160:163], v[198:201], v[92:95]
	v_mfma_f32_16x16x32_bf16 v[88:91], v[174:177], v[198:201], v[88:91]
	v_mfma_f32_16x16x32_bf16 v[76:79], v[160:163], v[206:209], v[76:79]
	v_mfma_f32_16x16x32_bf16 v[72:75], v[174:177], v[206:209], v[72:75]
	s_setprio 0
	s_barrier
	s_add_i32 s43, s69, s60
	v_lshl_add_u64 v[146:147], s[54:55], 0, v[130:131]
	s_mov_b32 m0, s43
	ds_read_b128 v[210:213], v153
	ds_read_b128 v[214:217], v153 offset:1024
	ds_read_b128 v[218:221], v153 offset:2048
	ds_read_b128 v[222:225], v153 offset:3072
	global_load_lds_dwordx4 v[146:147], off
	v_lshl_add_u64 v[164:165], s[54:55], 0, v[134:135]
	s_add_i32 m0, s43, 0x2000
	s_nop 0
	global_load_lds_dwordx4 v[164:165], off
	s_barrier
	s_waitcnt lgkmcnt(0)
	s_setprio 1
	s_waitcnt lgkmcnt(0)
	v_mfma_f32_16x16x32_bf16 v[116:119], v[210:213], v[178:181], v[116:119]
	v_mfma_f32_16x16x32_bf16 v[112:115], v[218:221], v[178:181], v[112:115]
	v_mfma_f32_16x16x32_bf16 v[100:103], v[210:213], v[186:189], v[100:103]
	v_mfma_f32_16x16x32_bf16 v[96:99], v[218:221], v[186:189], v[96:99]
	v_mfma_f32_16x16x32_bf16 v[84:87], v[210:213], v[194:197], v[84:87]
	v_mfma_f32_16x16x32_bf16 v[80:83], v[218:221], v[194:197], v[80:83]
	v_mfma_f32_16x16x32_bf16 v[68:71], v[210:213], v[202:205], v[68:71]
	v_mfma_f32_16x16x32_bf16 v[64:67], v[218:221], v[202:205], v[64:67]
	v_mfma_f32_16x16x32_bf16 v[116:119], v[214:217], v[182:185], v[116:119]
	v_mfma_f32_16x16x32_bf16 v[112:115], v[222:225], v[182:185], v[112:115]
	v_mfma_f32_16x16x32_bf16 v[100:103], v[214:217], v[190:193], v[100:103]
	v_mfma_f32_16x16x32_bf16 v[96:99], v[222:225], v[190:193], v[96:99]
	v_mfma_f32_16x16x32_bf16 v[84:87], v[214:217], v[198:201], v[84:87]
	v_mfma_f32_16x16x32_bf16 v[80:83], v[222:225], v[198:201], v[80:83]
	v_mfma_f32_16x16x32_bf16 v[68:71], v[214:217], v[206:209], v[68:71]
	v_mfma_f32_16x16x32_bf16 v[64:67], v[222:225], v[206:209], v[64:67]
	s_setprio 0
	s_mov_b32 m0, s61
	v_lshl_add_u64 v[226:227], s[56:57], 0, v[128:129]
	s_barrier
	ds_read_b128 v[178:181], v152 offset:16384
	ds_read_b128 v[182:185], v152 offset:17408
	ds_read_b128 v[186:189], v152 offset:18432
	ds_read_b128 v[190:193], v152 offset:19456
	ds_read_b128 v[194:197], v152 offset:20480
	ds_read_b128 v[198:201], v152 offset:21504
	ds_read_b128 v[202:205], v152 offset:22528
	ds_read_b128 v[206:209], v152 offset:23552
	global_load_lds_dwordx4 v[226:227], off
	v_lshl_add_u64 v[228:229], s[56:57], 0, v[132:133]
	s_mov_b32 m0, s62
	s_nop 0
	global_load_lds_dwordx4 v[228:229], off
	s_barrier
	s_waitcnt lgkmcnt(0)
	s_setprio 1
	s_waitcnt lgkmcnt(0)
	v_mfma_f32_16x16x32_bf16 v[60:63], v[156:159], v[178:181], v[60:63]
	v_mfma_f32_16x16x32_bf16 v[56:59], v[170:173], v[178:181], v[56:59]
	v_mfma_f32_16x16x32_bf16 v[44:47], v[156:159], v[186:189], v[44:47]
	v_mfma_f32_16x16x32_bf16 v[40:43], v[170:173], v[186:189], v[40:43]
	v_mfma_f32_16x16x32_bf16 v[28:31], v[156:159], v[194:197], v[28:31]
	v_mfma_f32_16x16x32_bf16 v[24:27], v[170:173], v[194:197], v[24:27]
	v_mfma_f32_16x16x32_bf16 v[12:15], v[156:159], v[202:205], v[12:15]
	v_mfma_f32_16x16x32_bf16 v[8:11], v[170:173], v[202:205], v[8:11]
	v_mfma_f32_16x16x32_bf16 v[60:63], v[160:163], v[182:185], v[60:63]
	v_mfma_f32_16x16x32_bf16 v[56:59], v[174:177], v[182:185], v[56:59]
	v_mfma_f32_16x16x32_bf16 v[44:47], v[160:163], v[190:193], v[44:47]
	v_mfma_f32_16x16x32_bf16 v[40:43], v[174:177], v[190:193], v[40:43]
	v_mfma_f32_16x16x32_bf16 v[28:31], v[160:163], v[198:201], v[28:31]
	v_mfma_f32_16x16x32_bf16 v[24:27], v[174:177], v[198:201], v[24:27]
	v_mfma_f32_16x16x32_bf16 v[12:15], v[160:163], v[206:209], v[12:15]
	v_mfma_f32_16x16x32_bf16 v[8:11], v[174:177], v[206:209], v[8:11]
	s_setprio 0
	s_barrier
; #define PG8_STAGE(bufoff, gbase, voff) do { _Pragma("unroll") for (int _i = 0; _i < 2; ++_i) \
;         __builtin_amdgcn_global_load_lds((const unsigned*)((const char*)(gbase) + (voff)[_i]), (LAS unsigned*)(lds + (bufoff) + ldsw + _i * 8192), 16, 0, 0); } while (0)
; #define PG8_LDA(dst, b, h) do { _Pragma("unroll") for (int m = 0; m < 4; ++m) _Pragma("unroll") for (int k = 0; k < 2; ++k) dst[m][k] = *(const LAS bf16x8*)(lds + PG8_SA(b, h) + aoff + m * 2048 + k * 1024); } while (0)
; #define PG8_LDB(dst, b, h) do { _Pragma("unroll") for (int n = 0; n < 2; ++n) _Pragma("unroll") for (int k = 0; k < 2; ++k) dst[n][k] = *(const LAS bf16x8*)(lds + PG8_SB(b, h) + boff + n * 2048 + k * 1024); } while (0)
; #define PG8_MMA(ai, bj, At, Bt) do { __builtin_amdgcn_s_setprio(1); _Pragma("unroll") for (int m = 0; m < 4; ++m) _Pragma("unroll") for (int n = 0; n < 2; ++n) _Pragma("unroll") for (int k = 0; k < 2; ++k) \
;         acc[ai][bj][m][n] = __builtin_amdgcn_mfma_f32_16x16x32_bf16(Bt[n][k], At[m][k], acc[ai][bj][m][n], 0, 0, 0); __builtin_amdgcn_s_setprio(0); } while (0)
; #define PG8_WAIT_V(n) asm volatile("s_waitcnt vmcnt(" #n ")" ::: "memory")
; #define PG8_WAIT_L(n) asm volatile("s_waitcnt lgkmcnt(" #n ")" ::: "memory")
; #define PG8_BAR __builtin_amdgcn_s_barrier()
; #define PG8_SCHED __builtin_amdgcn_sched_barrier(0)
;     ...
;             PG8_STAGE(PG8_SB(0, 1), b2 + hB, voffB);
;             PG8_WAIT_V(6); PG8_BAR; PG8_MMA(1, 1, At, B1); PG8_BAR;
;             PG8_LDB(B0, 1, 0); PG8_SCHED; PG8_LDA(At, 1, 0); PG8_STAGE(PG8_SA(0, 1), a2 + hA, voffA);
;             PG8_WAIT_L(8); PG8_BAR; PG8_WAIT_L(0); PG8_MMA(0, 0, At, B0); PG8_BAR; PG8_SCHED;
;             PG8_LDB(B1, 1, 1); PG8_STAGE(PG8_SB(1, 0), b3, voffB);
;             PG8_BAR; PG8_WAIT_L(0); PG8_MMA(0, 1, At, B1); PG8_BAR;
;             PG8_LDA(At, 1, 1); PG8_STAGE(PG8_SA(1, 0), a3, voffA);
;             PG8_BAR; PG8_WAIT_L(0); PG8_MMA(1, 0, At, B0); PG8_BAR; PG8_SCHED;
	s_add_u32 s44, s54, 0x40000
	s_addc_u32 s45, s55, 0
	s_add_i32 s43, s70, s60
	v_lshl_add_u64 v[156:157], s[44:45], 0, v[130:131]
	s_mov_b32 m0, s43
	s_nop 0
	global_load_lds_dwordx4 v[156:157], off
	v_lshl_add_u64 v[156:157], s[44:45], 0, v[134:135]
	s_add_i32 m0, s43, 0x2000
	s_nop 0
	global_load_lds_dwordx4 v[156:157], off
	s_waitcnt vmcnt(6)
	s_barrier
	s_setprio 1
	v_mfma_f32_16x16x32_bf16 v[52:55], v[210:213], v[178:181], v[52:55]
	v_mfma_f32_16x16x32_bf16 v[48:51], v[218:221], v[178:181], v[48:51]
	v_mfma_f32_16x16x32_bf16 v[36:39], v[210:213], v[186:189], v[36:39]
	v_mfma_f32_16x16x32_bf16 v[32:35], v[218:221], v[186:189], v[32:35]
	v_mfma_f32_16x16x32_bf16 v[20:23], v[210:213], v[194:197], v[20:23]
	v_mfma_f32_16x16x32_bf16 v[16:19], v[218:221], v[194:197], v[16:19]
	v_mfma_f32_16x16x32_bf16 v[4:7], v[210:213], v[202:205], v[4:7]
	v_mfma_f32_16x16x32_bf16 v[0:3], v[218:221], v[202:205], v[0:3]
	v_mfma_f32_16x16x32_bf16 v[52:55], v[214:217], v[182:185], v[52:55]
	v_mfma_f32_16x16x32_bf16 v[48:51], v[222:225], v[182:185], v[48:51]
	v_mfma_f32_16x16x32_bf16 v[36:39], v[214:217], v[190:193], v[36:39]
	v_mfma_f32_16x16x32_bf16 v[32:35], v[222:225], v[190:193], v[32:35]
	v_mfma_f32_16x16x32_bf16 v[20:23], v[214:217], v[198:201], v[20:23]
	v_mfma_f32_16x16x32_bf16 v[16:19], v[222:225], v[198:201], v[16:19]
	v_mfma_f32_16x16x32_bf16 v[4:7], v[214:217], v[206:209], v[4:7]
	v_mfma_f32_16x16x32_bf16 v[0:3], v[222:225], v[206:209], v[0:3]
	s_setprio 0
	s_add_i32 s43, 0, 0x18000
	v_add_u32_e32 v155, s43, v149
	s_barrier
	ds_read_b128 v[156:159], v155
	ds_read_b128 v[160:163], v155 offset:1024
	ds_read_b128 v[170:173], v155 offset:2048
	ds_read_b128 v[174:177], v155 offset:3072
	s_add_u32 s44, s56, 0x40000
	s_addc_u32 s45, s57, 0
	s_mov_b32 m0, s63
	v_lshl_add_u64 v[210:211], s[44:45], 0, v[128:129]
	ds_read_b128 v[178:181], v152 offset:32768
	ds_read_b128 v[182:185], v152 offset:33792
	ds_read_b128 v[186:189], v152 offset:34816
	ds_read_b128 v[190:193], v152 offset:35840
	ds_read_b128 v[194:197], v152 offset:36864
	ds_read_b128 v[198:201], v152 offset:37888
	ds_read_b128 v[202:205], v152 offset:38912
	ds_read_b128 v[206:209], v152 offset:39936
	global_load_lds_dwordx4 v[210:211], off
	v_lshl_add_u64 v[210:211], s[44:45], 0, v[132:133]
	s_mov_b32 m0, s64
	s_nop 0
	global_load_lds_dwordx4 v[210:211], off
	s_waitcnt lgkmcnt(8)
	s_barrier
	s_waitcnt lgkmcnt(0)
	s_setprio 1
	s_waitcnt lgkmcnt(0)
	v_mfma_f32_16x16x32_bf16 v[124:127], v[156:159], v[178:181], v[124:127]
	v_mfma_f32_16x16x32_bf16 v[120:123], v[170:173], v[178:181], v[120:123]
	v_mfma_f32_16x16x32_bf16 v[108:111], v[156:159], v[186:189], v[108:111]
	v_mfma_f32_16x16x32_bf16 v[104:107], v[170:173], v[186:189], v[104:107]
	v_mfma_f32_16x16x32_bf16 v[92:95], v[156:159], v[194:197], v[92:95]
	v_mfma_f32_16x16x32_bf16 v[88:91], v[170:173], v[194:197], v[88:91]
	v_mfma_f32_16x16x32_bf16 v[76:79], v[156:159], v[202:205], v[76:79]
	v_mfma_f32_16x16x32_bf16 v[72:75], v[170:173], v[202:205], v[72:75]
	v_mfma_f32_16x16x32_bf16 v[124:127], v[160:163], v[182:185], v[124:127]
	v_mfma_f32_16x16x32_bf16 v[120:123], v[174:177], v[182:185], v[120:123]
	v_mfma_f32_16x16x32_bf16 v[108:111], v[160:163], v[190:193], v[108:111]
	v_mfma_f32_16x16x32_bf16 v[104:107], v[174:177], v[190:193], v[104:107]
	v_mfma_f32_16x16x32_bf16 v[92:95], v[160:163], v[198:201], v[92:95]
	v_mfma_f32_16x16x32_bf16 v[88:91], v[174:177], v[198:201], v[88:91]
	v_mfma_f32_16x16x32_bf16 v[76:79], v[160:163], v[206:209], v[76:79]
	v_mfma_f32_16x16x32_bf16 v[72:75], v[174:177], v[206:209], v[72:75]
	s_setprio 0
	s_barrier
	s_add_i32 s56, 0, 0x1c000
	s_add_i32 s43, s43, s60
	v_add_u32_e32 v155, s56, v149
	v_lshl_add_u64 v[146:147], v[146:147], 0, s[30:31]
	s_mov_b32 m0, s43
	ds_read_b128 v[210:213], v155
	ds_read_b128 v[214:217], v155 offset:1024
	ds_read_b128 v[218:221], v155 offset:2048
	ds_read_b128 v[222:225], v155 offset:3072
	global_load_lds_dwordx4 v[146:147], off
	v_lshl_add_u64 v[146:147], v[164:165], 0, s[30:31]
	s_add_i32 m0, s43, 0x2000
	s_nop 0
	global_load_lds_dwordx4 v[146:147], off
	s_barrier
	s_waitcnt lgkmcnt(0)
	s_setprio 1
	s_waitcnt lgkmcnt(0)
	v_mfma_f32_16x16x32_bf16 v[116:119], v[210:213], v[178:181], v[116:119]
	v_mfma_f32_16x16x32_bf16 v[112:115], v[218:221], v[178:181], v[112:115]
	v_mfma_f32_16x16x32_bf16 v[100:103], v[210:213], v[186:189], v[100:103]
	v_mfma_f32_16x16x32_bf16 v[96:99], v[218:221], v[186:189], v[96:99]
	v_mfma_f32_16x16x32_bf16 v[84:87], v[210:213], v[194:197], v[84:87]
	v_mfma_f32_16x16x32_bf16 v[80:83], v[218:221], v[194:197], v[80:83]
	v_mfma_f32_16x16x32_bf16 v[68:71], v[210:213], v[202:205], v[68:71]
	v_mfma_f32_16x16x32_bf16 v[64:67], v[218:221], v[202:205], v[64:67]
	v_mfma_f32_16x16x32_bf16 v[116:119], v[214:217], v[182:185], v[116:119]
	v_mfma_f32_16x16x32_bf16 v[112:115], v[222:225], v[182:185], v[112:115]
	v_mfma_f32_16x16x32_bf16 v[100:103], v[214:217], v[190:193], v[100:103]
	v_mfma_f32_16x16x32_bf16 v[96:99], v[222:225], v[190:193], v[96:99]
	v_mfma_f32_16x16x32_bf16 v[84:87], v[214:217], v[198:201], v[84:87]
	v_mfma_f32_16x16x32_bf16 v[80:83], v[222:225], v[198:201], v[80:83]
	v_mfma_f32_16x16x32_bf16 v[68:71], v[214:217], v[206:209], v[68:71]
	v_mfma_f32_16x16x32_bf16 v[64:67], v[222:225], v[206:209], v[64:67]
	s_setprio 0
	s_mov_b32 m0, s66
	v_lshl_add_u64 v[146:147], v[226:227], 0, s[30:31]
	s_barrier
	ds_read_b128 v[178:181], v152 offset:49152
	ds_read_b128 v[182:185], v152 offset:50176
	ds_read_b128 v[186:189], v152 offset:51200
	ds_read_b128 v[190:193], v152 offset:52224
	ds_read_b128 v[194:197], v152 offset:53248
	ds_read_b128 v[198:201], v152 offset:54272
	ds_read_b128 v[202:205], v152 offset:55296
	ds_read_b128 v[206:209], v152 offset:56320
	global_load_lds_dwordx4 v[146:147], off
	v_lshl_add_u64 v[146:147], v[228:229], 0, s[30:31]
	s_mov_b32 m0, s67
	s_nop 0
	global_load_lds_dwordx4 v[146:147], off
	s_barrier
; #define PG8_STAGE(bufoff, gbase, voff) do { _Pragma("unroll") for (int _i = 0; _i < 2; ++_i) \
;         __builtin_amdgcn_global_load_lds((const unsigned*)((const char*)(gbase) + (voff)[_i]), (LAS unsigned*)(lds + (bufoff) + ldsw + _i * 8192), 16, 0, 0); } while (0)
; #define PG8_MMA(ai, bj, At, Bt) do { __builtin_amdgcn_s_setprio(1); _Pragma("unroll") for (int m = 0; m < 4; ++m) _Pragma("unroll") for (int n = 0; n < 2; ++n) _Pragma("unroll") for (int k = 0; k < 2; ++k) \
;         acc[ai][bj][m][n] = __builtin_amdgcn_mfma_f32_16x16x32_bf16(Bt[n][k], At[m][k], acc[ai][bj][m][n], 0, 0, 0); __builtin_amdgcn_s_setprio(0); } while (0)
; #define PG8_WAIT_V(n) asm volatile("s_waitcnt vmcnt(" #n ")" ::: "memory")
; #define PG8_WAIT_L(n) asm volatile("s_waitcnt lgkmcnt(" #n ")" ::: "memory")
; #define PG8_BAR __builtin_amdgcn_s_barrier()
; #define PG8_SCHED __builtin_amdgcn_sched_barrier(0)
;     ...
;             PG8_BAR; PG8_WAIT_L(0); PG8_MMA(1, 0, At, B0); PG8_BAR; PG8_SCHED;
;             PG8_STAGE(PG8_SB(1, 1), b3 + hB, voffB);
;             PG8_WAIT_V(6); PG8_BAR; PG8_MMA(1, 1, At, B1); PG8_BAR;
; __device__ __forceinline__ float row_rstd(const float* ssq, int row) {
;     const f32x4* p = (const f32x4*)(ssq + (size_t)row * 16);
;     const f32x4 a = p[0], b = p[1], c = p[2], d = p[3];
;     __device__ __forceinline__ void operator()(const f32x4 (&acc)[2][2][4][2], const Unit& u, int wr, int wc, int fr, int fq) const {
;     ...
;                 const int row = row0 + ai * 128 + m * 16; const float rs = row_rstd(ssq, row);
	s_waitcnt lgkmcnt(0)
	s_setprio 1
	s_waitcnt lgkmcnt(0)
	v_mfma_f32_16x16x32_bf16 v[60:63], v[156:159], v[178:181], v[60:63]
	v_mfma_f32_16x16x32_bf16 v[56:59], v[170:173], v[178:181], v[56:59]
	v_mfma_f32_16x16x32_bf16 v[44:47], v[156:159], v[186:189], v[44:47]
	v_mfma_f32_16x16x32_bf16 v[40:43], v[170:173], v[186:189], v[40:43]
	v_mfma_f32_16x16x32_bf16 v[28:31], v[156:159], v[194:197], v[28:31]
	v_mfma_f32_16x16x32_bf16 v[24:27], v[170:173], v[194:197], v[24:27]
	v_mfma_f32_16x16x32_bf16 v[12:15], v[156:159], v[202:205], v[12:15]
	v_mfma_f32_16x16x32_bf16 v[8:11], v[170:173], v[202:205], v[8:11]
	v_mfma_f32_16x16x32_bf16 v[60:63], v[160:163], v[182:185], v[60:63]
	v_mfma_f32_16x16x32_bf16 v[56:59], v[174:177], v[182:185], v[56:59]
	v_mfma_f32_16x16x32_bf16 v[44:47], v[160:163], v[190:193], v[44:47]
	v_mfma_f32_16x16x32_bf16 v[40:43], v[174:177], v[190:193], v[40:43]
	v_mfma_f32_16x16x32_bf16 v[28:31], v[160:163], v[198:201], v[28:31]
	v_mfma_f32_16x16x32_bf16 v[24:27], v[174:177], v[198:201], v[24:27]
	v_mfma_f32_16x16x32_bf16 v[12:15], v[160:163], v[206:209], v[12:15]
	v_mfma_f32_16x16x32_bf16 v[8:11], v[174:177], v[206:209], v[8:11]
	s_setprio 0
	s_barrier
	s_add_u32 s44, s54, 0x40080
	s_addc_u32 s45, s55, 0
	s_add_i32 s43, s56, s60
	v_lshl_add_u64 v[146:147], s[44:45], 0, v[130:131]
	s_mov_b32 m0, s43
	s_nop 0
	global_load_lds_dwordx4 v[146:147], off
	v_lshl_add_u64 v[146:147], s[44:45], 0, v[134:135]
	s_add_i32 m0, s43, 0x2000
	s_nop 0
	global_load_lds_dwordx4 v[146:147], off
	s_waitcnt vmcnt(6)
	s_barrier
	s_setprio 1
	v_mfma_f32_16x16x32_bf16 v[52:55], v[210:213], v[178:181], v[52:55]
	v_mfma_f32_16x16x32_bf16 v[48:51], v[218:221], v[178:181], v[48:51]
	v_mfma_f32_16x16x32_bf16 v[36:39], v[210:213], v[186:189], v[36:39]
	v_mfma_f32_16x16x32_bf16 v[32:35], v[218:221], v[186:189], v[32:35]
	v_mfma_f32_16x16x32_bf16 v[20:23], v[210:213], v[194:197], v[20:23]
	v_mfma_f32_16x16x32_bf16 v[16:19], v[218:221], v[194:197], v[16:19]
	v_mfma_f32_16x16x32_bf16 v[4:7], v[210:213], v[202:205], v[4:7]
	v_mfma_f32_16x16x32_bf16 v[0:3], v[218:221], v[202:205], v[0:3]
	v_mfma_f32_16x16x32_bf16 v[52:55], v[214:217], v[182:185], v[52:55]
	v_mfma_f32_16x16x32_bf16 v[48:51], v[222:225], v[182:185], v[48:51]
	v_mfma_f32_16x16x32_bf16 v[36:39], v[214:217], v[190:193], v[36:39]
	v_mfma_f32_16x16x32_bf16 v[32:35], v[222:225], v[190:193], v[32:35]
	v_mfma_f32_16x16x32_bf16 v[20:23], v[214:217], v[198:201], v[20:23]
	v_mfma_f32_16x16x32_bf16 v[16:19], v[222:225], v[198:201], v[16:19]
	v_mfma_f32_16x16x32_bf16 v[4:7], v[214:217], v[206:209], v[4:7]
	v_mfma_f32_16x16x32_bf16 v[0:3], v[222:225], v[206:209], v[0:3]
	s_setprio 0
	s_add_i32 s42, s42, 2
	s_add_u32 s33, s33, 0x100
	s_addc_u32 s39, s39, 0
	s_add_u32 s40, s40, 0x100
	s_addc_u32 s41, s41, 0
	s_cmp_gt_u32 s42, 13
	s_barrier
	s_cbranch_scc0 .LBB0_958
	v_lshl_add_u32 v146, s75, 8, v148
	v_ashrrev_i32_e32 v147, 31, v146
	v_lshlrev_b64 v[156:157], 6, v[146:147]
	v_lshl_add_u64 v[164:165], s[26:27], 0, v[156:157]
	v_subrev_u32_e32 v180, s26, v164
	v_add_u32_e32 v181, 0x0, v180
	global_load_dwordx4 v[182:185], v181, s[26:27]
	v_add_u32_e32 v181, 0x10, v180
	global_load_dwordx4 v[186:189], v181, s[26:27]
	v_add_u32_e32 v181, 0x20, v180
	global_load_dwordx4 v[190:193], v181, s[26:27]
	v_add_u32_e32 v181, 0x30, v180
	global_load_dwordx4 v[194:197], v181, s[26:27]
	v_add_u32_e32 v181, 0x400, v180
	global_load_dwordx4 v[198:201], v181, s[26:27]
	v_add_u32_e32 v181, 0x410, v180
	global_load_dwordx4 v[202:205], v181, s[26:27]
	v_add_u32_e32 v181, 0x420, v180
	global_load_dwordx4 v[206:209], v181, s[26:27]
	v_add_u32_e32 v181, 0x430, v180
	global_load_dwordx4 v[210:213], v181, s[26:27]
	v_add_u32_e32 v181, 0x800, v180
	global_load_dwordx4 v[214:217], v181, s[26:27]
	v_add_u32_e32 v181, 0x810, v180
	global_load_dwordx4 v[218:221], v181, s[26:27]
	v_add_u32_e32 v181, 0x820, v180
	global_load_dwordx4 v[222:225], v181, s[26:27]
	v_add_u32_e32 v181, 0x830, v180
	global_load_dwordx4 v[232:235], v181, s[26:27]
	v_add_u32_e32 v181, 0xc00, v180
	global_load_dwordx4 v[236:239], v181, s[26:27]
	v_add_u32_e32 v181, 0xc10, v180
	global_load_dwordx4 v[240:243], v181, s[26:27]
	v_add_u32_e32 v181, 0xc20, v180
	global_load_dwordx4 v[244:247], v181, s[26:27]
	v_add_u32_e32 v181, 0xc30, v180
	global_load_dwordx4 v[248:251], v181, s[26:27]
	v_or_b32_e32 v164, 16, v146
	v_lshl_or_b32 v147, s6, 9, v150
	v_ashrrev_i32_e32 v165, 31, v164
	v_lshl_add_u32 v155, v146, 13, v147
	s_waitcnt vmcnt(12)
; __device__ __forceinline__ u32x4 pack8(const f32x4 v0, const f32x4 v1) { u32x4 w; w.x = pk2(v0[0], v0[1]); w.y = pk2(v0[2], v0[3]); w.z = pk2(v1[0], v1[1]); w.w = pk2(v1[2], v1[3]); return w; }
; __device__ __forceinline__ float row_rstd(const float* ssq, int row) {
;     const f32x4* p = (const f32x4*)(ssq + (size_t)row * 16);
;     const f32x4 a = p[0], b = p[1], c = p[2], d = p[3];
;     const float s = ((a[0] + a[1]) + (a[2] + a[3])) + ((b[0] + b[1]) + (b[2] + b[3])) + ((c[0] + c[1]) + (c[2] + c[3])) + ((d[0] + d[1]) + (d[2] + d[3]));
;     return rsqrtf(s * (1.0f / 1024.0f) + 1e-6f);
;     __device__ __forceinline__ void operator()(const f32x4 (&acc)[2][2][4][2], const Unit& u, int wr, int wc, int fr, int fq) const {
;     ...
;                 const int row = row0 + ai * 128 + m * 16; const float rs = row_rstd(ssq, row);
;     ...
;                 for (int bj = 0; bj < 2; ++bj) { f32x4 v0 = acc[ai][bj][m][0] * rs, v1 = acc[ai][bj][m][1] * rs;
; #pragma unroll
;                     for (int j = 0; j < 4; ++j) { const float a = fmaxf(v0[j], 0.f), b = fmaxf(v1[j], 0.f); v0[j] = a * a; v1[j] = b * b; }
;                     __builtin_amdgcn_raw_buffer_store_b128(pack8(v0, v1), rsrc, (unsigned)(((size_t)row * DFF + col0 + bj * 128) * 2), 0, 16  ); }
	v_mov_b32_e32 v156, v182
	v_mov_b32_e32 v157, v183
	v_mov_b32_e32 v158, v184
	v_mov_b32_e32 v159, v185
	v_mov_b32_e32 v160, v186
	v_mov_b32_e32 v161, v187
	v_mov_b32_e32 v162, v188
	v_mov_b32_e32 v163, v189
	v_mov_b32_e32 v170, v190
	v_mov_b32_e32 v171, v191
	v_mov_b32_e32 v172, v192
	v_mov_b32_e32 v173, v193
	v_mov_b32_e32 v174, v194
	v_mov_b32_e32 v175, v195
	v_mov_b32_e32 v176, v196
	v_mov_b32_e32 v177, v197
	v_add_u32_e32 v181, 0x2000, v180
	global_load_dwordx4 v[182:185], v181, s[26:27]
	v_add_u32_e32 v181, 0x2010, v180
	global_load_dwordx4 v[186:189], v181, s[26:27]
	v_add_u32_e32 v181, 0x2020, v180
	global_load_dwordx4 v[190:193], v181, s[26:27]
	v_add_u32_e32 v181, 0x2030, v180
	global_load_dwordx4 v[194:197], v181, s[26:27]
	v_mov_b32_e32 v178, v157
	v_mov_b32_e32 v179, v158
	v_mov_b32_e32 v157, v159
	v_mov_b32_e32 v158, v161
	v_mov_b32_e32 v159, v162
	v_mov_b32_e32 v161, v163
	v_pk_add_f32 v[156:157], v[178:179], v[156:157]
	v_pk_add_f32 v[158:159], v[158:159], v[160:161]
	v_pk_add_f32 v[156:157], v[156:157], v[156:157] op_sel:[0,1] op_sel_hi:[1,0]
	v_pk_add_f32 v[158:159], v[158:159], v[158:159] op_sel:[0,1] op_sel_hi:[1,0]
	v_add_f32_e32 v162, v170, v171
	v_add_f32_e32 v170, v172, v173
	v_mov_b32_e32 v163, v176
	v_mov_b32_e32 v171, v177
	v_mov_b32_e32 v157, v174
	v_mov_b32_e32 v159, v175
	v_pk_add_f32 v[160:161], v[162:163], v[170:171]
	v_pk_add_f32 v[156:157], v[156:157], v[158:159]
	s_nop 0
	v_pk_add_f32 v[156:157], v[156:157], v[160:161]
	s_nop 0
	v_add_f32_e32 v156, v156, v157
	v_fmamk_f32 v156, v156, 0x3a800000, v154
	v_mul_f32_e32 v157, 0x4b800000, v156
	v_cmp_gt_f32_e32 vcc, s71, v156
	s_nop 1
	v_cndmask_b32_e32 v156, v156, v157, vcc
	v_rsq_f32_e32 v158, v156
	v_lshlrev_b64 v[156:157], 6, v[164:165]
	v_lshl_add_u64 v[156:157], s[26:27], 0, v[156:157]
	v_mul_f32_e32 v159, 0x45800000, v158
	v_cndmask_b32_e32 v158, v158, v159, vcc
	v_pk_mul_f32 v[126:127], v[126:127], v[158:159] op_sel_hi:[1,0]
	v_pk_mul_f32 v[124:125], v[124:125], v[158:159] op_sel_hi:[1,0]
	v_pk_mul_f32 v[122:123], v[122:123], v[158:159] op_sel_hi:[1,0]
	v_pk_mul_f32 v[120:121], v[120:121], v[158:159] op_sel_hi:[1,0]
	v_pk_mul_f32 v[114:115], v[114:115], v[158:159] op_sel_hi:[1,0]
	v_pk_mul_f32 v[112:113], v[112:113], v[158:159] op_sel_hi:[1,0]
	v_pk_mul_f32 v[118:119], v[118:119], v[158:159] op_sel_hi:[1,0]
	v_pk_mul_f32 v[116:117], v[116:117], v[158:159] op_sel_hi:[1,0]
	v_max_f32_e32 v124, 0, v124
	v_max_f32_e32 v120, 0, v120
	v_max_f32_e32 v125, 0, v125
	v_max_f32_e32 v121, 0, v121
	v_max_f32_e32 v126, 0, v126
	v_max_f32_e32 v122, 0, v122
	v_max_f32_e32 v127, 0, v127
	v_max_f32_e32 v123, 0, v123
	v_max_f32_e32 v112, 0, v112
	v_max_f32_e32 v113, 0, v113
	v_max_f32_e32 v114, 0, v114
	v_max_f32_e32 v115, 0, v115
	v_max_f32_e32 v116, 0, v116
	v_max_f32_e32 v117, 0, v117
	v_max_f32_e32 v118, 0, v118
	v_max_f32_e32 v119, 0, v119
	v_mul_f32_e32 v124, v124, v124
	v_mul_f32_e32 v120, v120, v120
	v_mul_f32_e32 v125, v125, v125
	v_mul_f32_e32 v121, v121, v121
	v_mul_f32_e32 v126, v126, v126
	v_mul_f32_e32 v122, v122, v122
	v_mul_f32_e32 v127, v127, v127
	v_mul_f32_e32 v123, v123, v123
	v_mul_f32_e32 v158, v112, v112
	v_mul_f32_e32 v159, v113, v113
	v_mul_f32_e32 v160, v114, v114
	v_mul_f32_e32 v161, v115, v115
	v_cvt_pk_bf16_f32 v112, v124, v125
	v_cvt_pk_bf16_f32 v113, v126, v127
	v_cvt_pk_bf16_f32 v114, v120, v121
	v_cvt_pk_bf16_f32 v115, v122, v123
	v_mul_f32_e32 v116, v116, v116
	v_mul_f32_e32 v117, v117, v117
	v_mul_f32_e32 v118, v118, v118
	v_mul_f32_e32 v119, v119, v119
	buffer_store_dwordx4 v[112:115], v155, s[16:19], 0 offen sc1
	s_nop 1
	v_cvt_pk_bf16_f32 v112, v116, v117
	v_cvt_pk_bf16_f32 v113, v118, v119
	v_cvt_pk_bf16_f32 v114, v158, v159
	v_cvt_pk_bf16_f32 v115, v160, v161
	buffer_store_dwordx4 v[112:115], v155, s[16:19], 0 offen offset:256 sc1
	s_nop 0
	v_or_b32_e32 v156, 32, v146
	v_ashrrev_i32_e32 v157, 31, v156
	v_lshl_add_u32 v155, v164, 13, v147
	s_waitcnt vmcnt(14)
	v_mov_b32_e32 v112, v198
	v_mov_b32_e32 v113, v199
	v_mov_b32_e32 v114, v200
	v_mov_b32_e32 v115, v201
	v_mov_b32_e32 v116, v202
	v_mov_b32_e32 v117, v203
	v_mov_b32_e32 v118, v204
	v_mov_b32_e32 v119, v205
	v_mov_b32_e32 v120, v206
	v_mov_b32_e32 v121, v207
	v_mov_b32_e32 v122, v208
	v_mov_b32_e32 v123, v209
	v_mov_b32_e32 v124, v210
	v_mov_b32_e32 v125, v211
	v_mov_b32_e32 v126, v212
	v_mov_b32_e32 v127, v213
	v_add_u32_e32 v181, 0x2400, v180
	global_load_dwordx4 v[198:201], v181, s[26:27]
	v_add_u32_e32 v181, 0x2410, v180
	global_load_dwordx4 v[202:205], v181, s[26:27]
	v_add_u32_e32 v181, 0x2420, v180
	global_load_dwordx4 v[206:209], v181, s[26:27]
	v_add_u32_e32 v181, 0x2430, v180
	global_load_dwordx4 v[210:213], v181, s[26:27]
	v_mov_b32_e32 v158, v113
	v_mov_b32_e32 v159, v114
	v_mov_b32_e32 v113, v115
	v_mov_b32_e32 v114, v117
	v_mov_b32_e32 v115, v118
	v_mov_b32_e32 v117, v119
	v_pk_add_f32 v[112:113], v[158:159], v[112:113]
	v_pk_add_f32 v[114:115], v[114:115], v[116:117]
	v_pk_add_f32 v[112:113], v[112:113], v[112:113] op_sel:[0,1] op_sel_hi:[1,0]
	v_pk_add_f32 v[114:115], v[114:115], v[114:115] op_sel:[0,1] op_sel_hi:[1,0]
	v_add_f32_e32 v118, v120, v121
	v_add_f32_e32 v120, v122, v123
	v_mov_b32_e32 v119, v126
	v_mov_b32_e32 v121, v127
	v_mov_b32_e32 v113, v124
	v_mov_b32_e32 v115, v125
	v_pk_add_f32 v[116:117], v[118:119], v[120:121]
	v_pk_add_f32 v[112:113], v[112:113], v[114:115]
	s_nop 0
	v_pk_add_f32 v[112:113], v[112:113], v[116:117]
	s_nop 0
	v_add_f32_e32 v112, v112, v113
	v_fmamk_f32 v112, v112, 0x3a800000, v154
	v_mul_f32_e32 v113, 0x4b800000, v112
	v_cmp_gt_f32_e32 vcc, s71, v112
	s_nop 1
	v_cndmask_b32_e32 v112, v112, v113, vcc
	v_rsq_f32_e32 v114, v112
; __device__ __forceinline__ u32x4 pack8(const f32x4 v0, const f32x4 v1) { u32x4 w; w.x = pk2(v0[0], v0[1]); w.y = pk2(v0[2], v0[3]); w.z = pk2(v1[0], v1[1]); w.w = pk2(v1[2], v1[3]); return w; }
; __device__ __forceinline__ float row_rstd(const float* ssq, int row) {
;     const f32x4* p = (const f32x4*)(ssq + (size_t)row * 16);
;     const f32x4 a = p[0], b = p[1], c = p[2], d = p[3];
;     const float s = ((a[0] + a[1]) + (a[2] + a[3])) + ((b[0] + b[1]) + (b[2] + b[3])) + ((c[0] + c[1]) + (c[2] + c[3])) + ((d[0] + d[1]) + (d[2] + d[3]));
;     return rsqrtf(s * (1.0f / 1024.0f) + 1e-6f);
;     __device__ __forceinline__ void operator()(const f32x4 (&acc)[2][2][4][2], const Unit& u, int wr, int wc, int fr, int fq) const {
;     ...
;                 const int row = row0 + ai * 128 + m * 16; const float rs = row_rstd(ssq, row);
;     ...
;                 for (int bj = 0; bj < 2; ++bj) { f32x4 v0 = acc[ai][bj][m][0] * rs, v1 = acc[ai][bj][m][1] * rs;
; #pragma unroll
;                     for (int j = 0; j < 4; ++j) { const float a = fmaxf(v0[j], 0.f), b = fmaxf(v1[j], 0.f); v0[j] = a * a; v1[j] = b * b; }
;                     __builtin_amdgcn_raw_buffer_store_b128(pack8(v0, v1), rsrc, (unsigned)(((size_t)row * DFF + col0 + bj * 128) * 2), 0, 16  ); }
	v_lshlrev_b64 v[112:113], 6, v[156:157]
	v_lshl_add_u64 v[112:113], s[26:27], 0, v[112:113]
	v_mul_f32_e32 v115, 0x45800000, v114
	v_cndmask_b32_e32 v114, v114, v115, vcc
	v_pk_mul_f32 v[110:111], v[110:111], v[114:115] op_sel_hi:[1,0]
	v_pk_mul_f32 v[108:109], v[108:109], v[114:115] op_sel_hi:[1,0]
	v_pk_mul_f32 v[106:107], v[106:107], v[114:115] op_sel_hi:[1,0]
	v_pk_mul_f32 v[104:105], v[104:105], v[114:115] op_sel_hi:[1,0]
	v_pk_mul_f32 v[98:99], v[98:99], v[114:115] op_sel_hi:[1,0]
	v_pk_mul_f32 v[96:97], v[96:97], v[114:115] op_sel_hi:[1,0]
	v_pk_mul_f32 v[102:103], v[102:103], v[114:115] op_sel_hi:[1,0]
	v_pk_mul_f32 v[100:101], v[100:101], v[114:115] op_sel_hi:[1,0]
	v_max_f32_e32 v108, 0, v108
	v_max_f32_e32 v104, 0, v104
	v_max_f32_e32 v109, 0, v109
	v_max_f32_e32 v105, 0, v105
	v_max_f32_e32 v110, 0, v110
	v_max_f32_e32 v106, 0, v106
	v_max_f32_e32 v111, 0, v111
	v_max_f32_e32 v107, 0, v107
	v_max_f32_e32 v96, 0, v96
	v_max_f32_e32 v97, 0, v97
	v_max_f32_e32 v98, 0, v98
	v_max_f32_e32 v99, 0, v99
	v_max_f32_e32 v100, 0, v100
	v_max_f32_e32 v101, 0, v101
	v_max_f32_e32 v102, 0, v102
	v_max_f32_e32 v103, 0, v103
	v_mul_f32_e32 v108, v108, v108
	v_mul_f32_e32 v104, v104, v104
	v_mul_f32_e32 v109, v109, v109
	v_mul_f32_e32 v105, v105, v105
	v_mul_f32_e32 v110, v110, v110
	v_mul_f32_e32 v106, v106, v106
	v_mul_f32_e32 v111, v111, v111
	v_mul_f32_e32 v107, v107, v107
	v_mul_f32_e32 v114, v96, v96
	v_mul_f32_e32 v115, v97, v97
	v_mul_f32_e32 v116, v98, v98
	v_mul_f32_e32 v117, v99, v99
	v_cvt_pk_bf16_f32 v96, v108, v109
	v_cvt_pk_bf16_f32 v97, v110, v111
	v_cvt_pk_bf16_f32 v98, v104, v105
	v_cvt_pk_bf16_f32 v99, v106, v107
	v_mul_f32_e32 v100, v100, v100
	v_mul_f32_e32 v101, v101, v101
	v_mul_f32_e32 v102, v102, v102
	v_mul_f32_e32 v103, v103, v103
	buffer_store_dwordx4 v[96:99], v155, s[16:19], 0 offen sc1
	s_nop 1
	v_cvt_pk_bf16_f32 v96, v100, v101
	v_cvt_pk_bf16_f32 v97, v102, v103
	v_cvt_pk_bf16_f32 v98, v114, v115
	v_cvt_pk_bf16_f32 v99, v116, v117
	buffer_store_dwordx4 v[96:99], v155, s[16:19], 0 offen offset:256 sc1
	s_nop 0
	v_or_b32_e32 v112, 48, v146
	v_ashrrev_i32_e32 v113, 31, v112
	v_lshl_add_u32 v116, v156, 13, v147
	s_waitcnt vmcnt(16)
	v_mov_b32_e32 v96, v214
	v_mov_b32_e32 v97, v215
	v_mov_b32_e32 v98, v216
	v_mov_b32_e32 v99, v217
	v_mov_b32_e32 v100, v218
	v_mov_b32_e32 v101, v219
	v_mov_b32_e32 v102, v220
	v_mov_b32_e32 v103, v221
	v_mov_b32_e32 v104, v222
	v_mov_b32_e32 v105, v223
	v_mov_b32_e32 v106, v224
	v_mov_b32_e32 v107, v225
	v_mov_b32_e32 v108, v232
	v_mov_b32_e32 v109, v233
	v_mov_b32_e32 v110, v234
	v_mov_b32_e32 v111, v235
	v_add_u32_e32 v181, 0x2800, v180
	global_load_dwordx4 v[214:217], v181, s[26:27]
	v_add_u32_e32 v181, 0x2810, v180
	global_load_dwordx4 v[218:221], v181, s[26:27]
	v_add_u32_e32 v181, 0x2820, v180
	global_load_dwordx4 v[222:225], v181, s[26:27]
	v_add_u32_e32 v181, 0x2830, v180
	global_load_dwordx4 v[232:235], v181, s[26:27]
	v_mov_b32_e32 v114, v97
	v_mov_b32_e32 v115, v98
	v_mov_b32_e32 v97, v99
	v_mov_b32_e32 v98, v101
	v_mov_b32_e32 v99, v102
	v_mov_b32_e32 v101, v103
	v_pk_add_f32 v[96:97], v[114:115], v[96:97]
	v_pk_add_f32 v[98:99], v[98:99], v[100:101]
	v_pk_add_f32 v[96:97], v[96:97], v[96:97] op_sel:[0,1] op_sel_hi:[1,0]
	v_pk_add_f32 v[98:99], v[98:99], v[98:99] op_sel:[0,1] op_sel_hi:[1,0]
	v_add_f32_e32 v102, v104, v105
	v_add_f32_e32 v104, v106, v107
	v_mov_b32_e32 v103, v110
	v_mov_b32_e32 v105, v111
	v_mov_b32_e32 v97, v108
	v_mov_b32_e32 v99, v109
	v_pk_add_f32 v[100:101], v[102:103], v[104:105]
	v_pk_add_f32 v[96:97], v[96:97], v[98:99]
	s_nop 0
	v_pk_add_f32 v[96:97], v[96:97], v[100:101]
	s_nop 0
	v_add_f32_e32 v96, v96, v97
	v_fmamk_f32 v96, v96, 0x3a800000, v154
	v_mul_f32_e32 v97, 0x4b800000, v96
	v_cmp_gt_f32_e32 vcc, s71, v96
	s_nop 1
	v_cndmask_b32_e32 v96, v96, v97, vcc
	v_rsq_f32_e32 v98, v96
	v_lshlrev_b64 v[96:97], 6, v[112:113]
	v_lshl_add_u64 v[96:97], s[26:27], 0, v[96:97]
	v_mul_f32_e32 v99, 0x45800000, v98
	v_cndmask_b32_e32 v98, v98, v99, vcc
	v_pk_mul_f32 v[94:95], v[94:95], v[98:99] op_sel_hi:[1,0]
	v_pk_mul_f32 v[92:93], v[92:93], v[98:99] op_sel_hi:[1,0]
	v_pk_mul_f32 v[90:91], v[90:91], v[98:99] op_sel_hi:[1,0]
	v_pk_mul_f32 v[88:89], v[88:89], v[98:99] op_sel_hi:[1,0]
	v_pk_mul_f32 v[82:83], v[82:83], v[98:99] op_sel_hi:[1,0]
	v_pk_mul_f32 v[80:81], v[80:81], v[98:99] op_sel_hi:[1,0]
	v_pk_mul_f32 v[86:87], v[86:87], v[98:99] op_sel_hi:[1,0]
	v_pk_mul_f32 v[84:85], v[84:85], v[98:99] op_sel_hi:[1,0]
	v_max_f32_e32 v92, 0, v92
	v_max_f32_e32 v88, 0, v88
	v_max_f32_e32 v93, 0, v93
	v_max_f32_e32 v89, 0, v89
	v_max_f32_e32 v94, 0, v94
	v_max_f32_e32 v90, 0, v90
	v_max_f32_e32 v95, 0, v95
	v_max_f32_e32 v91, 0, v91
	v_max_f32_e32 v80, 0, v80
	v_max_f32_e32 v81, 0, v81
	v_max_f32_e32 v82, 0, v82
	v_max_f32_e32 v83, 0, v83
	v_max_f32_e32 v84, 0, v84
	v_max_f32_e32 v85, 0, v85
	v_max_f32_e32 v86, 0, v86
	v_max_f32_e32 v87, 0, v87
	v_mul_f32_e32 v92, v92, v92
	v_mul_f32_e32 v88, v88, v88
	v_mul_f32_e32 v93, v93, v93
	v_mul_f32_e32 v89, v89, v89
	v_mul_f32_e32 v94, v94, v94
	v_mul_f32_e32 v90, v90, v90
	v_mul_f32_e32 v95, v95, v95
	v_mul_f32_e32 v91, v91, v91
	v_mul_f32_e32 v98, v80, v80
	v_mul_f32_e32 v99, v81, v81
	v_mul_f32_e32 v100, v82, v82
	v_mul_f32_e32 v101, v83, v83
	v_cvt_pk_bf16_f32 v80, v92, v93
	v_cvt_pk_bf16_f32 v81, v94, v95
	v_cvt_pk_bf16_f32 v82, v88, v89
	v_cvt_pk_bf16_f32 v83, v90, v91
	v_mul_f32_e32 v84, v84, v84
	v_mul_f32_e32 v85, v85, v85
	v_mul_f32_e32 v86, v86, v86
	v_mul_f32_e32 v87, v87, v87
	buffer_store_dwordx4 v[80:83], v116, s[16:19], 0 offen sc1
	s_nop 1
	v_cvt_pk_bf16_f32 v80, v84, v85
	v_cvt_pk_bf16_f32 v81, v86, v87
	v_cvt_pk_bf16_f32 v82, v98, v99
	v_cvt_pk_bf16_f32 v83, v100, v101
	buffer_store_dwordx4 v[80:83], v116, s[16:19], 0 offen offset:256 sc1
	s_nop 0
	v_add_u32_e32 v96, 0x80, v146
	v_ashrrev_i32_e32 v97, 31, v96
	v_lshl_add_u32 v100, v112, 13, v147
	s_waitcnt vmcnt(18)
; __device__ __forceinline__ u32x4 pack8(const f32x4 v0, const f32x4 v1) { u32x4 w; w.x = pk2(v0[0], v0[1]); w.y = pk2(v0[2], v0[3]); w.z = pk2(v1[0], v1[1]); w.w = pk2(v1[2], v1[3]); return w; }
; __device__ __forceinline__ float row_rstd(const float* ssq, int row) {
;     const f32x4* p = (const f32x4*)(ssq + (size_t)row * 16);
;     const f32x4 a = p[0], b = p[1], c = p[2], d = p[3];
;     const float s = ((a[0] + a[1]) + (a[2] + a[3])) + ((b[0] + b[1]) + (b[2] + b[3])) + ((c[0] + c[1]) + (c[2] + c[3])) + ((d[0] + d[1]) + (d[2] + d[3]));
;     return rsqrtf(s * (1.0f / 1024.0f) + 1e-6f);
;     __device__ __forceinline__ void operator()(const f32x4 (&acc)[2][2][4][2], const Unit& u, int wr, int wc, int fr, int fq) const {
;     ...
;                 const int row = row0 + ai * 128 + m * 16; const float rs = row_rstd(ssq, row);
;     ...
;                 for (int bj = 0; bj < 2; ++bj) { f32x4 v0 = acc[ai][bj][m][0] * rs, v1 = acc[ai][bj][m][1] * rs;
; #pragma unroll
;                     for (int j = 0; j < 4; ++j) { const float a = fmaxf(v0[j], 0.f), b = fmaxf(v1[j], 0.f); v0[j] = a * a; v1[j] = b * b; }
;                     __builtin_amdgcn_raw_buffer_store_b128(pack8(v0, v1), rsrc, (unsigned)(((size_t)row * DFF + col0 + bj * 128) * 2), 0, 16  ); }
	v_mov_b32_e32 v80, v236
	v_mov_b32_e32 v81, v237
	v_mov_b32_e32 v82, v238
	v_mov_b32_e32 v83, v239
	v_mov_b32_e32 v84, v240
	v_mov_b32_e32 v85, v241
	v_mov_b32_e32 v86, v242
	v_mov_b32_e32 v87, v243
	v_mov_b32_e32 v88, v244
	v_mov_b32_e32 v89, v245
	v_mov_b32_e32 v90, v246
	v_mov_b32_e32 v91, v247
	v_mov_b32_e32 v92, v248
	v_mov_b32_e32 v93, v249
	v_mov_b32_e32 v94, v250
	v_mov_b32_e32 v95, v251
	v_add_u32_e32 v181, 0x2c00, v180
	global_load_dwordx4 v[236:239], v181, s[26:27]
	v_add_u32_e32 v181, 0x2c10, v180
	global_load_dwordx4 v[240:243], v181, s[26:27]
	v_add_u32_e32 v181, 0x2c20, v180
	global_load_dwordx4 v[244:247], v181, s[26:27]
	v_add_u32_e32 v181, 0x2c30, v180
	global_load_dwordx4 v[248:251], v181, s[26:27]
	v_mov_b32_e32 v98, v81
	v_mov_b32_e32 v99, v82
	v_mov_b32_e32 v81, v83
	v_mov_b32_e32 v82, v85
	v_mov_b32_e32 v83, v86
	v_mov_b32_e32 v85, v87
	v_pk_add_f32 v[80:81], v[98:99], v[80:81]
	v_pk_add_f32 v[82:83], v[82:83], v[84:85]
	v_pk_add_f32 v[80:81], v[80:81], v[80:81] op_sel:[0,1] op_sel_hi:[1,0]
	v_pk_add_f32 v[82:83], v[82:83], v[82:83] op_sel:[0,1] op_sel_hi:[1,0]
	v_add_f32_e32 v86, v88, v89
	v_add_f32_e32 v88, v90, v91
	v_mov_b32_e32 v87, v94
	v_mov_b32_e32 v89, v95
	v_mov_b32_e32 v81, v92
	v_mov_b32_e32 v83, v93
	v_pk_add_f32 v[84:85], v[86:87], v[88:89]
	v_pk_add_f32 v[80:81], v[80:81], v[82:83]
	s_nop 0
	v_pk_add_f32 v[80:81], v[80:81], v[84:85]
	s_nop 0
	v_add_f32_e32 v80, v80, v81
	v_fmamk_f32 v80, v80, 0x3a800000, v154
	v_mul_f32_e32 v81, 0x4b800000, v80
	v_cmp_gt_f32_e32 vcc, s71, v80
	s_nop 1
	v_cndmask_b32_e32 v80, v80, v81, vcc
	v_rsq_f32_e32 v82, v80
	v_lshlrev_b64 v[80:81], 6, v[96:97]
	v_lshl_add_u64 v[80:81], s[26:27], 0, v[80:81]
	v_mul_f32_e32 v83, 0x45800000, v82
	v_cndmask_b32_e32 v82, v82, v83, vcc
	v_pk_mul_f32 v[78:79], v[78:79], v[82:83] op_sel_hi:[1,0]
	v_pk_mul_f32 v[76:77], v[76:77], v[82:83] op_sel_hi:[1,0]
	v_pk_mul_f32 v[74:75], v[74:75], v[82:83] op_sel_hi:[1,0]
	v_pk_mul_f32 v[72:73], v[72:73], v[82:83] op_sel_hi:[1,0]
	v_pk_mul_f32 v[66:67], v[66:67], v[82:83] op_sel_hi:[1,0]
	v_pk_mul_f32 v[64:65], v[64:65], v[82:83] op_sel_hi:[1,0]
	v_pk_mul_f32 v[70:71], v[70:71], v[82:83] op_sel_hi:[1,0]
	v_pk_mul_f32 v[68:69], v[68:69], v[82:83] op_sel_hi:[1,0]
	v_max_f32_e32 v76, 0, v76
	v_max_f32_e32 v72, 0, v72
	v_max_f32_e32 v77, 0, v77
	v_max_f32_e32 v73, 0, v73
	v_max_f32_e32 v78, 0, v78
	v_max_f32_e32 v74, 0, v74
	v_max_f32_e32 v79, 0, v79
	v_max_f32_e32 v75, 0, v75
	v_max_f32_e32 v64, 0, v64
	v_max_f32_e32 v65, 0, v65
	v_max_f32_e32 v66, 0, v66
	v_max_f32_e32 v67, 0, v67
	v_max_f32_e32 v68, 0, v68
	v_max_f32_e32 v69, 0, v69
	v_max_f32_e32 v70, 0, v70
	v_max_f32_e32 v71, 0, v71
	v_mul_f32_e32 v76, v76, v76
	v_mul_f32_e32 v72, v72, v72
	v_mul_f32_e32 v77, v77, v77
	v_mul_f32_e32 v73, v73, v73
	v_mul_f32_e32 v78, v78, v78
	v_mul_f32_e32 v74, v74, v74
	v_mul_f32_e32 v79, v79, v79
	v_mul_f32_e32 v75, v75, v75
	v_mul_f32_e32 v82, v64, v64
	v_mul_f32_e32 v83, v65, v65
	v_mul_f32_e32 v84, v66, v66
	v_mul_f32_e32 v85, v67, v67
	v_cvt_pk_bf16_f32 v64, v76, v77
	v_cvt_pk_bf16_f32 v65, v78, v79
	v_cvt_pk_bf16_f32 v66, v72, v73
	v_cvt_pk_bf16_f32 v67, v74, v75
	v_mul_f32_e32 v68, v68, v68
	v_mul_f32_e32 v69, v69, v69
	v_mul_f32_e32 v70, v70, v70
	v_mul_f32_e32 v71, v71, v71
	buffer_store_dwordx4 v[64:67], v100, s[16:19], 0 offen sc1
	s_nop 1
	v_cvt_pk_bf16_f32 v64, v68, v69
	v_cvt_pk_bf16_f32 v65, v70, v71
	v_cvt_pk_bf16_f32 v66, v82, v83
	v_cvt_pk_bf16_f32 v67, v84, v85
	buffer_store_dwordx4 v[64:67], v100, s[16:19], 0 offen offset:256 sc1
	s_nop 0
	v_add_u32_e32 v80, 0x90, v146
	v_ashrrev_i32_e32 v81, 31, v80
	v_lshl_add_u32 v84, v96, 13, v147
	s_waitcnt vmcnt(20)
	v_mov_b32_e32 v64, v182
	v_mov_b32_e32 v65, v183
	v_mov_b32_e32 v66, v184
	v_mov_b32_e32 v67, v185
	v_mov_b32_e32 v68, v186
	v_mov_b32_e32 v69, v187
	v_mov_b32_e32 v70, v188
	v_mov_b32_e32 v71, v189
	v_mov_b32_e32 v72, v190
	v_mov_b32_e32 v73, v191
	v_mov_b32_e32 v74, v192
	v_mov_b32_e32 v75, v193
	v_mov_b32_e32 v76, v194
	v_mov_b32_e32 v77, v195
	v_mov_b32_e32 v78, v196
	v_mov_b32_e32 v79, v197
	v_mov_b32_e32 v82, v65
	v_mov_b32_e32 v83, v66
	v_mov_b32_e32 v65, v67
	v_mov_b32_e32 v66, v69
	v_mov_b32_e32 v67, v70
	v_mov_b32_e32 v69, v71
	v_pk_add_f32 v[64:65], v[82:83], v[64:65]
	v_pk_add_f32 v[66:67], v[66:67], v[68:69]
	v_pk_add_f32 v[64:65], v[64:65], v[64:65] op_sel:[0,1] op_sel_hi:[1,0]
	v_pk_add_f32 v[66:67], v[66:67], v[66:67] op_sel:[0,1] op_sel_hi:[1,0]
	v_add_f32_e32 v70, v72, v73
	v_add_f32_e32 v72, v74, v75
	v_mov_b32_e32 v71, v78
	v_mov_b32_e32 v73, v79
	v_mov_b32_e32 v65, v76
	v_mov_b32_e32 v67, v77
	v_pk_add_f32 v[68:69], v[70:71], v[72:73]
	v_pk_add_f32 v[64:65], v[64:65], v[66:67]
	s_nop 0
	v_pk_add_f32 v[64:65], v[64:65], v[68:69]
	s_nop 0
	v_add_f32_e32 v64, v64, v65
	v_fmamk_f32 v64, v64, 0x3a800000, v154
	v_mul_f32_e32 v65, 0x4b800000, v64
	v_cmp_gt_f32_e32 vcc, s71, v64
	s_nop 1
	v_cndmask_b32_e32 v64, v64, v65, vcc
	v_rsq_f32_e32 v66, v64
	v_lshlrev_b64 v[64:65], 6, v[80:81]
	v_lshl_add_u64 v[64:65], s[26:27], 0, v[64:65]
	v_mul_f32_e32 v67, 0x45800000, v66
	v_cndmask_b32_e32 v66, v66, v67, vcc
	v_pk_mul_f32 v[62:63], v[62:63], v[66:67] op_sel_hi:[1,0]
	v_pk_mul_f32 v[60:61], v[60:61], v[66:67] op_sel_hi:[1,0]
	v_pk_mul_f32 v[58:59], v[58:59], v[66:67] op_sel_hi:[1,0]
	v_pk_mul_f32 v[56:57], v[56:57], v[66:67] op_sel_hi:[1,0]
	v_pk_mul_f32 v[50:51], v[50:51], v[66:67] op_sel_hi:[1,0]
	v_pk_mul_f32 v[48:49], v[48:49], v[66:67] op_sel_hi:[1,0]
	v_pk_mul_f32 v[54:55], v[54:55], v[66:67] op_sel_hi:[1,0]
	v_pk_mul_f32 v[52:53], v[52:53], v[66:67] op_sel_hi:[1,0]
	v_max_f32_e32 v60, 0, v60
	v_max_f32_e32 v56, 0, v56
	v_max_f32_e32 v61, 0, v61
	v_max_f32_e32 v57, 0, v57
	v_max_f32_e32 v62, 0, v62
	v_max_f32_e32 v58, 0, v58
	v_max_f32_e32 v63, 0, v63
	v_max_f32_e32 v59, 0, v59
	v_max_f32_e32 v48, 0, v48
	v_max_f32_e32 v49, 0, v49
	v_max_f32_e32 v50, 0, v50
	v_max_f32_e32 v51, 0, v51
	v_max_f32_e32 v52, 0, v52
	v_max_f32_e32 v53, 0, v53
	v_max_f32_e32 v54, 0, v54
	v_max_f32_e32 v55, 0, v55
	v_mul_f32_e32 v60, v60, v60
	v_mul_f32_e32 v56, v56, v56
	v_mul_f32_e32 v61, v61, v61
	v_mul_f32_e32 v57, v57, v57
	v_mul_f32_e32 v62, v62, v62
	v_mul_f32_e32 v58, v58, v58
	v_mul_f32_e32 v63, v63, v63
	v_mul_f32_e32 v59, v59, v59
	v_mul_f32_e32 v66, v48, v48
	v_mul_f32_e32 v67, v49, v49
	v_mul_f32_e32 v68, v50, v50
	v_mul_f32_e32 v69, v51, v51
	v_cvt_pk_bf16_f32 v48, v60, v61
	v_cvt_pk_bf16_f32 v49, v62, v63
	v_cvt_pk_bf16_f32 v50, v56, v57
	v_cvt_pk_bf16_f32 v51, v58, v59
	v_mul_f32_e32 v52, v52, v52
	v_mul_f32_e32 v53, v53, v53
	v_mul_f32_e32 v54, v54, v54
	v_mul_f32_e32 v55, v55, v55
	buffer_store_dwordx4 v[48:51], v84, s[16:19], 0 offen sc1
	s_nop 1
	v_cvt_pk_bf16_f32 v48, v52, v53
	v_cvt_pk_bf16_f32 v49, v54, v55
	v_cvt_pk_bf16_f32 v50, v66, v67
	v_cvt_pk_bf16_f32 v51, v68, v69
	buffer_store_dwordx4 v[48:51], v84, s[16:19], 0 offen offset:256 sc1
	s_nop 0
	v_add_u32_e32 v64, 0xa0, v146
	v_ashrrev_i32_e32 v65, 31, v64
	v_lshl_add_u32 v68, v80, 13, v147
	s_waitcnt vmcnt(16)
; __device__ __forceinline__ u32x4 pack8(const f32x4 v0, const f32x4 v1) { u32x4 w; w.x = pk2(v0[0], v0[1]); w.y = pk2(v0[2], v0[3]); w.z = pk2(v1[0], v1[1]); w.w = pk2(v1[2], v1[3]); return w; }
; __device__ __forceinline__ float row_rstd(const float* ssq, int row) {
;     const f32x4* p = (const f32x4*)(ssq + (size_t)row * 16);
;     const f32x4 a = p[0], b = p[1], c = p[2], d = p[3];
;     const float s = ((a[0] + a[1]) + (a[2] + a[3])) + ((b[0] + b[1]) + (b[2] + b[3])) + ((c[0] + c[1]) + (c[2] + c[3])) + ((d[0] + d[1]) + (d[2] + d[3]));
;     return rsqrtf(s * (1.0f / 1024.0f) + 1e-6f);
;     __device__ __forceinline__ void operator()(const f32x4 (&acc)[2][2][4][2], const Unit& u, int wr, int wc, int fr, int fq) const {
;     ...
;                 const int row = row0 + ai * 128 + m * 16; const float rs = row_rstd(ssq, row);
;     ...
;                 for (int bj = 0; bj < 2; ++bj) { f32x4 v0 = acc[ai][bj][m][0] * rs, v1 = acc[ai][bj][m][1] * rs;
; #pragma unroll
;                     for (int j = 0; j < 4; ++j) { const float a = fmaxf(v0[j], 0.f), b = fmaxf(v1[j], 0.f); v0[j] = a * a; v1[j] = b * b; }
;                     __builtin_amdgcn_raw_buffer_store_b128(pack8(v0, v1), rsrc, (unsigned)(((size_t)row * DFF + col0 + bj * 128) * 2), 0, 16  ); }
	v_mov_b32_e32 v48, v198
	v_mov_b32_e32 v49, v199
	v_mov_b32_e32 v50, v200
	v_mov_b32_e32 v51, v201
	v_mov_b32_e32 v52, v202
	v_mov_b32_e32 v53, v203
	v_mov_b32_e32 v54, v204
	v_mov_b32_e32 v55, v205
	v_mov_b32_e32 v56, v206
	v_mov_b32_e32 v57, v207
	v_mov_b32_e32 v58, v208
	v_mov_b32_e32 v59, v209
	v_mov_b32_e32 v60, v210
	v_mov_b32_e32 v61, v211
	v_mov_b32_e32 v62, v212
	v_mov_b32_e32 v63, v213
	v_mov_b32_e32 v66, v49
	v_mov_b32_e32 v67, v50
	v_mov_b32_e32 v49, v51
	v_mov_b32_e32 v50, v53
	v_mov_b32_e32 v51, v54
	v_mov_b32_e32 v53, v55
	v_pk_add_f32 v[48:49], v[66:67], v[48:49]
	v_pk_add_f32 v[50:51], v[50:51], v[52:53]
	v_pk_add_f32 v[48:49], v[48:49], v[48:49] op_sel:[0,1] op_sel_hi:[1,0]
	v_pk_add_f32 v[50:51], v[50:51], v[50:51] op_sel:[0,1] op_sel_hi:[1,0]
	v_add_f32_e32 v54, v56, v57
	v_add_f32_e32 v56, v58, v59
	v_mov_b32_e32 v55, v62
	v_mov_b32_e32 v57, v63
	v_mov_b32_e32 v49, v60
	v_mov_b32_e32 v51, v61
	v_pk_add_f32 v[52:53], v[54:55], v[56:57]
	v_pk_add_f32 v[48:49], v[48:49], v[50:51]
	s_nop 0
	v_pk_add_f32 v[48:49], v[48:49], v[52:53]
	s_nop 0
	v_add_f32_e32 v48, v48, v49
	v_fmamk_f32 v48, v48, 0x3a800000, v154
	v_mul_f32_e32 v49, 0x4b800000, v48
	v_cmp_gt_f32_e32 vcc, s71, v48
	s_nop 1
	v_cndmask_b32_e32 v48, v48, v49, vcc
	v_rsq_f32_e32 v50, v48
	v_lshlrev_b64 v[48:49], 6, v[64:65]
	v_lshl_add_u64 v[48:49], s[26:27], 0, v[48:49]
	v_mul_f32_e32 v51, 0x45800000, v50
	v_cndmask_b32_e32 v50, v50, v51, vcc
	v_pk_mul_f32 v[46:47], v[46:47], v[50:51] op_sel_hi:[1,0]
	v_pk_mul_f32 v[44:45], v[44:45], v[50:51] op_sel_hi:[1,0]
	v_pk_mul_f32 v[42:43], v[42:43], v[50:51] op_sel_hi:[1,0]
	v_pk_mul_f32 v[40:41], v[40:41], v[50:51] op_sel_hi:[1,0]
	v_pk_mul_f32 v[34:35], v[34:35], v[50:51] op_sel_hi:[1,0]
	v_pk_mul_f32 v[32:33], v[32:33], v[50:51] op_sel_hi:[1,0]
	v_pk_mul_f32 v[38:39], v[38:39], v[50:51] op_sel_hi:[1,0]
	v_pk_mul_f32 v[36:37], v[36:37], v[50:51] op_sel_hi:[1,0]
	v_max_f32_e32 v44, 0, v44
	v_max_f32_e32 v40, 0, v40
	v_max_f32_e32 v45, 0, v45
	v_max_f32_e32 v41, 0, v41
	v_max_f32_e32 v46, 0, v46
	v_max_f32_e32 v42, 0, v42
	v_max_f32_e32 v47, 0, v47
	v_max_f32_e32 v43, 0, v43
	v_max_f32_e32 v32, 0, v32
	v_max_f32_e32 v33, 0, v33
	v_max_f32_e32 v34, 0, v34
	v_max_f32_e32 v35, 0, v35
	v_max_f32_e32 v36, 0, v36
	v_max_f32_e32 v37, 0, v37
	v_max_f32_e32 v38, 0, v38
	v_max_f32_e32 v39, 0, v39
	v_mul_f32_e32 v44, v44, v44
	v_mul_f32_e32 v40, v40, v40
	v_mul_f32_e32 v45, v45, v45
	v_mul_f32_e32 v41, v41, v41
	v_mul_f32_e32 v46, v46, v46
	v_mul_f32_e32 v42, v42, v42
	v_mul_f32_e32 v47, v47, v47
	v_mul_f32_e32 v43, v43, v43
	v_mul_f32_e32 v50, v32, v32
	v_mul_f32_e32 v51, v33, v33
	v_mul_f32_e32 v52, v34, v34
	v_mul_f32_e32 v53, v35, v35
	v_cvt_pk_bf16_f32 v32, v44, v45
	v_cvt_pk_bf16_f32 v33, v46, v47
	v_cvt_pk_bf16_f32 v34, v40, v41
	v_cvt_pk_bf16_f32 v35, v42, v43
	v_mul_f32_e32 v36, v36, v36
	v_mul_f32_e32 v37, v37, v37
	v_mul_f32_e32 v38, v38, v38
	v_mul_f32_e32 v39, v39, v39
	buffer_store_dwordx4 v[32:35], v68, s[16:19], 0 offen sc1
	s_nop 1
	v_cvt_pk_bf16_f32 v32, v36, v37
	v_cvt_pk_bf16_f32 v33, v38, v39
	v_cvt_pk_bf16_f32 v34, v50, v51
	v_cvt_pk_bf16_f32 v35, v52, v53
	buffer_store_dwordx4 v[32:35], v68, s[16:19], 0 offen offset:256 sc1
	s_nop 0
	v_add_u32_e32 v48, 0xb0, v146
	v_ashrrev_i32_e32 v49, 31, v48
	v_lshl_add_u32 v52, v64, 13, v147
	s_waitcnt vmcnt(12)
	v_mov_b32_e32 v32, v214
	v_mov_b32_e32 v33, v215
	v_mov_b32_e32 v34, v216
	v_mov_b32_e32 v35, v217
	v_mov_b32_e32 v36, v218
	v_mov_b32_e32 v37, v219
	v_mov_b32_e32 v38, v220
	v_mov_b32_e32 v39, v221
	v_mov_b32_e32 v40, v222
	v_mov_b32_e32 v41, v223
	v_mov_b32_e32 v42, v224
	v_mov_b32_e32 v43, v225
	v_mov_b32_e32 v44, v232
	v_mov_b32_e32 v45, v233
	v_mov_b32_e32 v46, v234
	v_mov_b32_e32 v47, v235
	v_mov_b32_e32 v50, v33
	v_mov_b32_e32 v51, v34
	v_mov_b32_e32 v33, v35
	v_mov_b32_e32 v34, v37
	v_mov_b32_e32 v35, v38
	v_mov_b32_e32 v37, v39
	v_pk_add_f32 v[32:33], v[50:51], v[32:33]
	v_pk_add_f32 v[34:35], v[34:35], v[36:37]
	v_pk_add_f32 v[32:33], v[32:33], v[32:33] op_sel:[0,1] op_sel_hi:[1,0]
	v_pk_add_f32 v[34:35], v[34:35], v[34:35] op_sel:[0,1] op_sel_hi:[1,0]
	v_add_f32_e32 v38, v40, v41
	v_add_f32_e32 v40, v42, v43
	v_mov_b32_e32 v39, v46
	v_mov_b32_e32 v41, v47
	v_mov_b32_e32 v33, v44
	v_mov_b32_e32 v35, v45
	v_pk_add_f32 v[36:37], v[38:39], v[40:41]
	v_pk_add_f32 v[32:33], v[32:33], v[34:35]
	s_nop 0
	v_pk_add_f32 v[32:33], v[32:33], v[36:37]
	s_nop 0
	v_add_f32_e32 v32, v32, v33
	v_fmamk_f32 v32, v32, 0x3a800000, v154
	v_mul_f32_e32 v33, 0x4b800000, v32
	v_cmp_gt_f32_e32 vcc, s71, v32
	s_nop 1
	v_cndmask_b32_e32 v32, v32, v33, vcc
	v_rsq_f32_e32 v34, v32
	v_lshlrev_b64 v[32:33], 6, v[48:49]
	v_lshl_add_u64 v[32:33], s[26:27], 0, v[32:33]
	v_mul_f32_e32 v35, 0x45800000, v34
	v_cndmask_b32_e32 v34, v34, v35, vcc
	v_pk_mul_f32 v[30:31], v[30:31], v[34:35] op_sel_hi:[1,0]
	v_pk_mul_f32 v[28:29], v[28:29], v[34:35] op_sel_hi:[1,0]
	v_pk_mul_f32 v[26:27], v[26:27], v[34:35] op_sel_hi:[1,0]
	v_pk_mul_f32 v[24:25], v[24:25], v[34:35] op_sel_hi:[1,0]
	v_pk_mul_f32 v[18:19], v[18:19], v[34:35] op_sel_hi:[1,0]
	v_pk_mul_f32 v[16:17], v[16:17], v[34:35] op_sel_hi:[1,0]
	v_pk_mul_f32 v[22:23], v[22:23], v[34:35] op_sel_hi:[1,0]
	v_pk_mul_f32 v[20:21], v[20:21], v[34:35] op_sel_hi:[1,0]
	v_max_f32_e32 v28, 0, v28
	v_max_f32_e32 v24, 0, v24
	v_max_f32_e32 v29, 0, v29
	v_max_f32_e32 v25, 0, v25
	v_max_f32_e32 v30, 0, v30
	v_max_f32_e32 v26, 0, v26
	v_max_f32_e32 v31, 0, v31
	v_max_f32_e32 v27, 0, v27
	v_max_f32_e32 v16, 0, v16
	v_max_f32_e32 v17, 0, v17
	v_max_f32_e32 v18, 0, v18
	v_max_f32_e32 v19, 0, v19
	v_max_f32_e32 v20, 0, v20
	v_max_f32_e32 v21, 0, v21
	v_max_f32_e32 v22, 0, v22
	v_max_f32_e32 v23, 0, v23
	v_mul_f32_e32 v28, v28, v28
	v_mul_f32_e32 v24, v24, v24
	v_mul_f32_e32 v29, v29, v29
	v_mul_f32_e32 v25, v25, v25
	v_mul_f32_e32 v30, v30, v30
	v_mul_f32_e32 v26, v26, v26
	v_mul_f32_e32 v31, v31, v31
	v_mul_f32_e32 v27, v27, v27
	v_mul_f32_e32 v34, v16, v16
	v_mul_f32_e32 v35, v17, v17
	v_mul_f32_e32 v36, v18, v18
	v_mul_f32_e32 v37, v19, v19
	v_cvt_pk_bf16_f32 v16, v28, v29
	v_cvt_pk_bf16_f32 v17, v30, v31
	v_cvt_pk_bf16_f32 v18, v24, v25
	v_cvt_pk_bf16_f32 v19, v26, v27
	v_mul_f32_e32 v20, v20, v20
	v_mul_f32_e32 v21, v21, v21
	v_mul_f32_e32 v22, v22, v22
	v_mul_f32_e32 v23, v23, v23
	buffer_store_dwordx4 v[16:19], v52, s[16:19], 0 offen sc1
	s_nop 1
	v_cvt_pk_bf16_f32 v16, v20, v21
	v_cvt_pk_bf16_f32 v17, v22, v23
	v_cvt_pk_bf16_f32 v18, v34, v35
	v_cvt_pk_bf16_f32 v19, v36, v37
	buffer_store_dwordx4 v[16:19], v52, s[16:19], 0 offen offset:256 sc1
	s_nop 0
	s_waitcnt vmcnt(8)
; __device__ __forceinline__ u32x4 pack8(const f32x4 v0, const f32x4 v1) { u32x4 w; w.x = pk2(v0[0], v0[1]); w.y = pk2(v0[2], v0[3]); w.z = pk2(v1[0], v1[1]); w.w = pk2(v1[2], v1[3]); return w; }
;     __device__ __forceinline__ void operator()(const f32x4 (&acc)[2][2][4][2], const Unit& u, int wr, int wc, int fr, int fq) const {
;     ...
;                 const int row = row0 + ai * 128 + m * 16; const float rs = row_rstd(ssq, row);
;     ...
;                 for (int bj = 0; bj < 2; ++bj) { f32x4 v0 = acc[ai][bj][m][0] * rs, v1 = acc[ai][bj][m][1] * rs;
; #pragma unroll
;                     for (int j = 0; j < 4; ++j) { const float a = fmaxf(v0[j], 0.f), b = fmaxf(v1[j], 0.f); v0[j] = a * a; v1[j] = b * b; }
;                     __builtin_amdgcn_raw_buffer_store_b128(pack8(v0, v1), rsrc, (unsigned)(((size_t)row * DFF + col0 + bj * 128) * 2), 0, 16  ); }
;             }
;         asm volatile("s_waitcnt vmcnt(0)" ::: "memory");
;         if (fr == 0 && fq == 0) (void)__hip_atomic_fetch_add(ready + 64 * (pm_off + u.pm), 1u, __ATOMIC_RELAXED, __HIP_MEMORY_SCOPE_AGENT);
	v_mov_b32_e32 v16, v236
	v_mov_b32_e32 v17, v237
	v_mov_b32_e32 v18, v238
	v_mov_b32_e32 v19, v239
	v_mov_b32_e32 v20, v240
	v_mov_b32_e32 v21, v241
	v_mov_b32_e32 v22, v242
	v_mov_b32_e32 v23, v243
	v_mov_b32_e32 v24, v244
	v_mov_b32_e32 v25, v245
	v_mov_b32_e32 v26, v246
	v_mov_b32_e32 v27, v247
	v_mov_b32_e32 v28, v248
	v_mov_b32_e32 v29, v249
	v_mov_b32_e32 v30, v250
	v_mov_b32_e32 v31, v251
	v_mov_b32_e32 v32, v17
	v_mov_b32_e32 v33, v18
	v_mov_b32_e32 v17, v19
	v_mov_b32_e32 v18, v21
	v_mov_b32_e32 v19, v22
	v_mov_b32_e32 v21, v23
	v_pk_add_f32 v[16:17], v[32:33], v[16:17]
	v_pk_add_f32 v[18:19], v[18:19], v[20:21]
	v_pk_add_f32 v[16:17], v[16:17], v[16:17] op_sel:[0,1] op_sel_hi:[1,0]
	v_pk_add_f32 v[18:19], v[18:19], v[18:19] op_sel:[0,1] op_sel_hi:[1,0]
	v_add_f32_e32 v22, v24, v25
	v_add_f32_e32 v24, v26, v27
	v_mov_b32_e32 v23, v30
	v_mov_b32_e32 v25, v31
	v_mov_b32_e32 v17, v28
	v_mov_b32_e32 v19, v29
	v_pk_add_f32 v[20:21], v[22:23], v[24:25]
	v_pk_add_f32 v[16:17], v[16:17], v[18:19]
	s_nop 0
	v_pk_add_f32 v[16:17], v[16:17], v[20:21]
	s_nop 0
	v_add_f32_e32 v16, v16, v17
	v_fmamk_f32 v16, v16, 0x3a800000, v154
	v_mul_f32_e32 v17, 0x4b800000, v16
	v_cmp_gt_f32_e32 vcc, s71, v16
	s_nop 1
	v_cndmask_b32_e32 v16, v16, v17, vcc
	v_rsq_f32_e32 v16, v16
	v_lshl_add_u32 v17, v48, 13, v147
	v_mul_f32_e32 v18, 0x45800000, v16
	v_cndmask_b32_e32 v16, v16, v18, vcc
	v_pk_mul_f32 v[14:15], v[14:15], v[16:17] op_sel_hi:[1,0]
	v_pk_mul_f32 v[12:13], v[12:13], v[16:17] op_sel_hi:[1,0]
	v_pk_mul_f32 v[10:11], v[10:11], v[16:17] op_sel_hi:[1,0]
	v_pk_mul_f32 v[8:9], v[8:9], v[16:17] op_sel_hi:[1,0]
	v_pk_mul_f32 v[2:3], v[2:3], v[16:17] op_sel_hi:[1,0]
	v_pk_mul_f32 v[0:1], v[0:1], v[16:17] op_sel_hi:[1,0]
	v_pk_mul_f32 v[6:7], v[6:7], v[16:17] op_sel_hi:[1,0]
	v_pk_mul_f32 v[4:5], v[4:5], v[16:17] op_sel_hi:[1,0]
	v_max_f32_e32 v12, 0, v12
	v_max_f32_e32 v8, 0, v8
	v_max_f32_e32 v13, 0, v13
	v_max_f32_e32 v9, 0, v9
	v_max_f32_e32 v14, 0, v14
	v_max_f32_e32 v10, 0, v10
	v_max_f32_e32 v15, 0, v15
	v_max_f32_e32 v11, 0, v11
	v_max_f32_e32 v0, 0, v0
	v_max_f32_e32 v1, 0, v1
	v_max_f32_e32 v2, 0, v2
	v_max_f32_e32 v3, 0, v3
	v_max_f32_e32 v4, 0, v4
	v_max_f32_e32 v5, 0, v5
	v_max_f32_e32 v6, 0, v6
	v_max_f32_e32 v7, 0, v7
	v_mul_f32_e32 v12, v12, v12
	v_mul_f32_e32 v8, v8, v8
	v_mul_f32_e32 v13, v13, v13
	v_mul_f32_e32 v9, v9, v9
	v_mul_f32_e32 v14, v14, v14
	v_mul_f32_e32 v10, v10, v10
	v_mul_f32_e32 v15, v15, v15
	v_mul_f32_e32 v11, v11, v11
	v_mul_f32_e32 v16, v0, v0
	v_mul_f32_e32 v18, v1, v1
	v_mul_f32_e32 v19, v2, v2
	v_mul_f32_e32 v20, v3, v3
	v_cvt_pk_bf16_f32 v0, v12, v13
	v_cvt_pk_bf16_f32 v1, v14, v15
	v_cvt_pk_bf16_f32 v2, v8, v9
	v_cvt_pk_bf16_f32 v3, v10, v11
	v_mul_f32_e32 v4, v4, v4
	v_mul_f32_e32 v5, v5, v5
	v_mul_f32_e32 v6, v6, v6
	v_mul_f32_e32 v7, v7, v7
	buffer_store_dwordx4 v[0:3], v17, s[16:19], 0 offen sc1
	s_nop 1
	v_cvt_pk_bf16_f32 v0, v4, v5
	v_cvt_pk_bf16_f32 v1, v6, v7
	v_cvt_pk_bf16_f32 v2, v16, v18
	v_cvt_pk_bf16_f32 v3, v19, v20
	buffer_store_dwordx4 v[0:3], v17, s[16:19], 0 offen offset:256 sc1
	s_waitcnt vmcnt(0)
	s_and_saveexec_b64 s[40:41], s[10:11]
	s_cbranch_execz .LBB0_950
	s_mov_b64 s[54:55], exec
	v_mbcnt_lo_u32_b32 v0, s54, 0
	v_mbcnt_hi_u32_b32 v0, s55, v0
	v_cmp_eq_u32_e32 vcc, 0, v0
	s_and_b64 s[6:7], exec, vcc
	s_mov_b64 exec, s[6:7]
	s_cbranch_execz .LBB0_950
	s_lshl_b32 s6, s75, 6
	s_ashr_i32 s7, s6, 31
	s_lshl_b64 s[6:7], s[6:7], 2
	s_add_u32 s6, s73, s6
	s_addc_u32 s7, s74, s7
	s_bcnt1_i32_b64 s8, s[54:55]
	v_mov_b32_e32 v0, s8
	global_atomic_add v131, v0, s[6:7]
	s_branch .LBB0_950

; #define PG8_STAGE(bufoff, gbase, voff) do { _Pragma("unroll") for (int _i = 0; _i < 2; ++_i) \
;         __builtin_amdgcn_global_load_lds((const unsigned*)((const char*)(gbase) + (voff)[_i]), (LAS unsigned*)(lds + (bufoff) + ldsw + _i * 8192), 16, 0, 0); } while (0)
; #define PG8_LDA(dst, b, h) do { _Pragma("unroll") for (int m = 0; m < 4; ++m) _Pragma("unroll") for (int k = 0; k < 2; ++k) dst[m][k] = *(const LAS bf16x8*)(lds + PG8_SA(b, h) + aoff + m * 2048 + k * 1024); } while (0)
; #define PG8_LDB(dst, b, h) do { _Pragma("unroll") for (int n = 0; n < 2; ++n) _Pragma("unroll") for (int k = 0; k < 2; ++k) dst[n][k] = *(const LAS bf16x8*)(lds + PG8_SB(b, h) + boff + n * 2048 + k * 1024); } while (0)
; #define PG8_MMA(ai, bj, At, Bt) do { __builtin_amdgcn_s_setprio(1); _Pragma("unroll") for (int m = 0; m < 4; ++m) _Pragma("unroll") for (int n = 0; n < 2; ++n) _Pragma("unroll") for (int k = 0; k < 2; ++k) \
;         acc[ai][bj][m][n] = __builtin_amdgcn_mfma_f32_16x16x32_bf16(Bt[n][k], At[m][k], acc[ai][bj][m][n], 0, 0, 0); __builtin_amdgcn_s_setprio(0); } while (0)
; #define PG8_WAIT_V(n) asm volatile("s_waitcnt vmcnt(" #n ")" ::: "memory")
; #define PG8_WAIT_L(n) asm volatile("s_waitcnt lgkmcnt(" #n ")" ::: "memory")
; #define PG8_BAR __builtin_amdgcn_s_barrier()
; #define PG8_SCHED __builtin_amdgcn_sched_barrier(0)
;     ...
;             PG8_LDB(B0, 0, 0); PG8_SCHED; PG8_LDA(At, 0, 0); PG8_STAGE(PG8_SA(1, 1), a1 + hA, voffA);
;             PG8_WAIT_L(8); PG8_BAR; PG8_WAIT_L(0); PG8_MMA(0, 0, At, B0); PG8_BAR; PG8_SCHED;
;             PG8_LDB(B1, 0, 1); PG8_STAGE(PG8_SB(0, 0), b2, voffB);
;             PG8_BAR; PG8_WAIT_L(0); PG8_MMA(0, 1, At, B1); PG8_BAR;
;             PG8_LDA(At, 0, 1); PG8_STAGE(PG8_SA(0, 0), a2, voffA);
;             PG8_BAR; PG8_WAIT_L(0); PG8_MMA(1, 0, At, B0); PG8_BAR; PG8_SCHED;
;             PG8_STAGE(PG8_SB(0, 1), b2 + hB, voffB);
;             PG8_WAIT_V(6); PG8_BAR; PG8_MMA(1, 1, At, B1); PG8_BAR;
.LBB0_981:
	ds_read_b128 v[150:153], v143
	ds_read_b128 v[154:157], v143 offset:1024
	ds_read_b128 v[158:161], v143 offset:2048
	ds_read_b128 v[162:165], v143 offset:3072
	s_add_u32 s40, s38, 0xfffc0080
	s_addc_u32 s41, s39, -1
	s_cmp_eq_u32 s42, 12
	s_cselect_b32 s55, s7, s41
	s_cselect_b32 s54, s8, s40
	s_cselect_b32 s41, s9, s35
	s_cselect_b32 s40, s25, s33
	v_lshl_add_u64 v[202:203], s[38:39], 0, v[138:139]
	s_add_i32 m0, s61, 0xc000
	ds_read_b128 v[170:173], v146
	ds_read_b128 v[174:177], v146 offset:1024
	ds_read_b128 v[178:181], v146 offset:2048
	ds_read_b128 v[182:185], v146 offset:3072
	ds_read_b128 v[186:189], v146 offset:4096
	ds_read_b128 v[190:193], v146 offset:5120
	ds_read_b128 v[194:197], v146 offset:6144
	ds_read_b128 v[198:201], v146 offset:7168
	global_load_lds_dwordx4 v[202:203], off
	v_lshl_add_u64 v[202:203], s[38:39], 0, v[136:137]
	s_add_i32 m0, s61, 0xe000
	s_nop 0
	global_load_lds_dwordx4 v[202:203], off
	s_waitcnt lgkmcnt(8)
	s_barrier
	s_waitcnt lgkmcnt(0)
	s_setprio 1
	s_waitcnt lgkmcnt(0)
	v_mfma_f32_16x16x32_bf16 v[124:127], v[150:153], v[170:173], v[124:127]
	v_mfma_f32_16x16x32_bf16 v[120:123], v[158:161], v[170:173], v[120:123]
	v_mfma_f32_16x16x32_bf16 v[108:111], v[150:153], v[178:181], v[108:111]
	v_mfma_f32_16x16x32_bf16 v[104:107], v[158:161], v[178:181], v[104:107]
	v_mfma_f32_16x16x32_bf16 v[92:95], v[150:153], v[186:189], v[92:95]
	v_mfma_f32_16x16x32_bf16 v[88:91], v[158:161], v[186:189], v[88:91]
	v_mfma_f32_16x16x32_bf16 v[76:79], v[150:153], v[194:197], v[76:79]
	v_mfma_f32_16x16x32_bf16 v[72:75], v[158:161], v[194:197], v[72:75]
	v_mfma_f32_16x16x32_bf16 v[124:127], v[154:157], v[174:177], v[124:127]
	v_mfma_f32_16x16x32_bf16 v[120:123], v[162:165], v[174:177], v[120:123]
	v_mfma_f32_16x16x32_bf16 v[108:111], v[154:157], v[182:185], v[108:111]
	v_mfma_f32_16x16x32_bf16 v[104:107], v[162:165], v[182:185], v[104:107]
	v_mfma_f32_16x16x32_bf16 v[92:95], v[154:157], v[190:193], v[92:95]
	v_mfma_f32_16x16x32_bf16 v[88:91], v[162:165], v[190:193], v[88:91]
	v_mfma_f32_16x16x32_bf16 v[76:79], v[154:157], v[198:201], v[76:79]
	v_mfma_f32_16x16x32_bf16 v[72:75], v[162:165], v[198:201], v[72:75]
	s_setprio 0
	s_barrier
	s_add_i32 s43, s69, s60
	v_lshl_add_u64 v[218:219], s[40:41], 0, v[130:131]
	s_mov_b32 m0, s43
	ds_read_b128 v[202:205], v147
	ds_read_b128 v[206:209], v147 offset:1024
	ds_read_b128 v[210:213], v147 offset:2048
	ds_read_b128 v[214:217], v147 offset:3072
	global_load_lds_dwordx4 v[218:219], off
	v_lshl_add_u64 v[220:221], s[40:41], 0, v[134:135]
	s_add_i32 m0, s43, 0x2000
	s_nop 0
	global_load_lds_dwordx4 v[220:221], off
	s_barrier
	s_waitcnt lgkmcnt(0)
	s_setprio 1
	s_waitcnt lgkmcnt(0)
	v_mfma_f32_16x16x32_bf16 v[116:119], v[202:205], v[170:173], v[116:119]
	v_mfma_f32_16x16x32_bf16 v[112:115], v[210:213], v[170:173], v[112:115]
	v_mfma_f32_16x16x32_bf16 v[100:103], v[202:205], v[178:181], v[100:103]
	v_mfma_f32_16x16x32_bf16 v[96:99], v[210:213], v[178:181], v[96:99]
	v_mfma_f32_16x16x32_bf16 v[84:87], v[202:205], v[186:189], v[84:87]
	v_mfma_f32_16x16x32_bf16 v[80:83], v[210:213], v[186:189], v[80:83]
	v_mfma_f32_16x16x32_bf16 v[68:71], v[202:205], v[194:197], v[68:71]
	v_mfma_f32_16x16x32_bf16 v[64:67], v[210:213], v[194:197], v[64:67]
	v_mfma_f32_16x16x32_bf16 v[116:119], v[206:209], v[174:177], v[116:119]
	v_mfma_f32_16x16x32_bf16 v[112:115], v[214:217], v[174:177], v[112:115]
	v_mfma_f32_16x16x32_bf16 v[100:103], v[206:209], v[182:185], v[100:103]
	v_mfma_f32_16x16x32_bf16 v[96:99], v[214:217], v[182:185], v[96:99]
	v_mfma_f32_16x16x32_bf16 v[84:87], v[206:209], v[190:193], v[84:87]
	v_mfma_f32_16x16x32_bf16 v[80:83], v[214:217], v[190:193], v[80:83]
	v_mfma_f32_16x16x32_bf16 v[68:71], v[206:209], v[198:201], v[68:71]
	v_mfma_f32_16x16x32_bf16 v[64:67], v[214:217], v[198:201], v[64:67]
	s_setprio 0
	s_mov_b32 m0, s61
	v_lshl_add_u64 v[222:223], s[54:55], 0, v[128:129]
	s_barrier
	ds_read_b128 v[170:173], v146 offset:16384
	ds_read_b128 v[174:177], v146 offset:17408
	ds_read_b128 v[178:181], v146 offset:18432
	ds_read_b128 v[182:185], v146 offset:19456
	ds_read_b128 v[186:189], v146 offset:20480
	ds_read_b128 v[190:193], v146 offset:21504
	ds_read_b128 v[194:197], v146 offset:22528
	ds_read_b128 v[198:201], v146 offset:23552
	global_load_lds_dwordx4 v[222:223], off
	v_lshl_add_u64 v[224:225], s[54:55], 0, v[132:133]
	s_mov_b32 m0, s62
	s_nop 0
	global_load_lds_dwordx4 v[224:225], off
	s_barrier
	s_waitcnt lgkmcnt(0)
	s_setprio 1
	s_waitcnt lgkmcnt(0)
	v_mfma_f32_16x16x32_bf16 v[60:63], v[150:153], v[170:173], v[60:63]
	v_mfma_f32_16x16x32_bf16 v[56:59], v[158:161], v[170:173], v[56:59]
	v_mfma_f32_16x16x32_bf16 v[44:47], v[150:153], v[178:181], v[44:47]
	v_mfma_f32_16x16x32_bf16 v[40:43], v[158:161], v[178:181], v[40:43]
	v_mfma_f32_16x16x32_bf16 v[28:31], v[150:153], v[186:189], v[28:31]
	v_mfma_f32_16x16x32_bf16 v[24:27], v[158:161], v[186:189], v[24:27]
	v_mfma_f32_16x16x32_bf16 v[12:15], v[150:153], v[194:197], v[12:15]
	v_mfma_f32_16x16x32_bf16 v[8:11], v[158:161], v[194:197], v[8:11]
	v_mfma_f32_16x16x32_bf16 v[60:63], v[154:157], v[174:177], v[60:63]
	v_mfma_f32_16x16x32_bf16 v[56:59], v[162:165], v[174:177], v[56:59]
	v_mfma_f32_16x16x32_bf16 v[44:47], v[154:157], v[182:185], v[44:47]
	v_mfma_f32_16x16x32_bf16 v[40:43], v[162:165], v[182:185], v[40:43]
	v_mfma_f32_16x16x32_bf16 v[28:31], v[154:157], v[190:193], v[28:31]
	v_mfma_f32_16x16x32_bf16 v[24:27], v[162:165], v[190:193], v[24:27]
	v_mfma_f32_16x16x32_bf16 v[12:15], v[154:157], v[198:201], v[12:15]
	v_mfma_f32_16x16x32_bf16 v[8:11], v[162:165], v[198:201], v[8:11]
	s_setprio 0
	s_barrier
; #define PG8_STAGE(bufoff, gbase, voff) do { _Pragma("unroll") for (int _i = 0; _i < 2; ++_i) \
;         __builtin_amdgcn_global_load_lds((const unsigned*)((const char*)(gbase) + (voff)[_i]), (LAS unsigned*)(lds + (bufoff) + ldsw + _i * 8192), 16, 0, 0); } while (0)
; #define PG8_LDA(dst, b, h) do { _Pragma("unroll") for (int m = 0; m < 4; ++m) _Pragma("unroll") for (int k = 0; k < 2; ++k) dst[m][k] = *(const LAS bf16x8*)(lds + PG8_SA(b, h) + aoff + m * 2048 + k * 1024); } while (0)
; #define PG8_LDB(dst, b, h) do { _Pragma("unroll") for (int n = 0; n < 2; ++n) _Pragma("unroll") for (int k = 0; k < 2; ++k) dst[n][k] = *(const LAS bf16x8*)(lds + PG8_SB(b, h) + boff + n * 2048 + k * 1024); } while (0)
; #define PG8_MMA(ai, bj, At, Bt) do { __builtin_amdgcn_s_setprio(1); _Pragma("unroll") for (int m = 0; m < 4; ++m) _Pragma("unroll") for (int n = 0; n < 2; ++n) _Pragma("unroll") for (int k = 0; k < 2; ++k) \
;         acc[ai][bj][m][n] = __builtin_amdgcn_mfma_f32_16x16x32_bf16(Bt[n][k], At[m][k], acc[ai][bj][m][n], 0, 0, 0); __builtin_amdgcn_s_setprio(0); } while (0)
; #define PG8_WAIT_V(n) asm volatile("s_waitcnt vmcnt(" #n ")" ::: "memory")
; #define PG8_WAIT_L(n) asm volatile("s_waitcnt lgkmcnt(" #n ")" ::: "memory")
; #define PG8_BAR __builtin_amdgcn_s_barrier()
; #define PG8_SCHED __builtin_amdgcn_sched_barrier(0)
;     ...
;             PG8_STAGE(PG8_SB(0, 1), b2 + hB, voffB);
;             PG8_WAIT_V(6); PG8_BAR; PG8_MMA(1, 1, At, B1); PG8_BAR;
;             PG8_LDB(B0, 1, 0); PG8_SCHED; PG8_LDA(At, 1, 0); PG8_STAGE(PG8_SA(0, 1), a2 + hA, voffA);
;             PG8_WAIT_L(8); PG8_BAR; PG8_WAIT_L(0); PG8_MMA(0, 0, At, B0); PG8_BAR; PG8_SCHED;
;             PG8_LDB(B1, 1, 1); PG8_STAGE(PG8_SB(1, 0), b3, voffB);
;             PG8_BAR; PG8_WAIT_L(0); PG8_MMA(0, 1, At, B1); PG8_BAR;
;             PG8_LDA(At, 1, 1); PG8_STAGE(PG8_SA(1, 0), a3, voffA);
;             PG8_BAR; PG8_WAIT_L(0); PG8_MMA(1, 0, At, B0); PG8_BAR; PG8_SCHED;
;             PG8_STAGE(PG8_SB(1, 1), b3 + hB, voffB);
;             PG8_WAIT_V(6); PG8_BAR; PG8_MMA(1, 1, At, B1); PG8_BAR;
	s_add_u32 s44, s40, 0x40000
	s_addc_u32 s45, s41, 0
	s_add_i32 s43, s70, s60
	v_lshl_add_u64 v[150:151], s[44:45], 0, v[130:131]
	s_mov_b32 m0, s43
	s_nop 0
	global_load_lds_dwordx4 v[150:151], off
	v_lshl_add_u64 v[150:151], s[44:45], 0, v[134:135]
	s_add_i32 m0, s43, 0x2000
	s_nop 0
	global_load_lds_dwordx4 v[150:151], off
	s_waitcnt vmcnt(6)
	s_barrier
	s_setprio 1
	v_mfma_f32_16x16x32_bf16 v[52:55], v[202:205], v[170:173], v[52:55]
	v_mfma_f32_16x16x32_bf16 v[48:51], v[210:213], v[170:173], v[48:51]
	v_mfma_f32_16x16x32_bf16 v[36:39], v[202:205], v[178:181], v[36:39]
	v_mfma_f32_16x16x32_bf16 v[32:35], v[210:213], v[178:181], v[32:35]
	v_mfma_f32_16x16x32_bf16 v[20:23], v[202:205], v[186:189], v[20:23]
	v_mfma_f32_16x16x32_bf16 v[16:19], v[210:213], v[186:189], v[16:19]
	v_mfma_f32_16x16x32_bf16 v[4:7], v[202:205], v[194:197], v[4:7]
	v_mfma_f32_16x16x32_bf16 v[0:3], v[210:213], v[194:197], v[0:3]
	v_mfma_f32_16x16x32_bf16 v[52:55], v[206:209], v[174:177], v[52:55]
	v_mfma_f32_16x16x32_bf16 v[48:51], v[214:217], v[174:177], v[48:51]
	v_mfma_f32_16x16x32_bf16 v[36:39], v[206:209], v[182:185], v[36:39]
	v_mfma_f32_16x16x32_bf16 v[32:35], v[214:217], v[182:185], v[32:35]
	v_mfma_f32_16x16x32_bf16 v[20:23], v[206:209], v[190:193], v[20:23]
	v_mfma_f32_16x16x32_bf16 v[16:19], v[214:217], v[190:193], v[16:19]
	v_mfma_f32_16x16x32_bf16 v[4:7], v[206:209], v[198:201], v[4:7]
	v_mfma_f32_16x16x32_bf16 v[0:3], v[214:217], v[198:201], v[0:3]
	s_setprio 0
	s_add_i32 s43, 0, 0x18000
	v_add_u32_e32 v149, s43, v141
	s_barrier
	ds_read_b128 v[150:153], v149
	ds_read_b128 v[154:157], v149 offset:1024
	ds_read_b128 v[158:161], v149 offset:2048
	ds_read_b128 v[162:165], v149 offset:3072
	s_add_u32 s44, s54, 0x40000
	s_addc_u32 s45, s55, 0
	s_mov_b32 m0, s63
	v_lshl_add_u64 v[202:203], s[44:45], 0, v[128:129]
	ds_read_b128 v[170:173], v146 offset:32768
	ds_read_b128 v[174:177], v146 offset:33792
	ds_read_b128 v[178:181], v146 offset:34816
	ds_read_b128 v[182:185], v146 offset:35840
	ds_read_b128 v[186:189], v146 offset:36864
	ds_read_b128 v[190:193], v146 offset:37888
	ds_read_b128 v[194:197], v146 offset:38912
	ds_read_b128 v[198:201], v146 offset:39936
	global_load_lds_dwordx4 v[202:203], off
	v_lshl_add_u64 v[202:203], s[44:45], 0, v[132:133]
	s_mov_b32 m0, s64
	s_nop 0
	global_load_lds_dwordx4 v[202:203], off
	s_waitcnt lgkmcnt(8)
	s_barrier
	s_waitcnt lgkmcnt(0)
	s_setprio 1
	s_waitcnt lgkmcnt(0)
	v_mfma_f32_16x16x32_bf16 v[124:127], v[150:153], v[170:173], v[124:127]
	v_mfma_f32_16x16x32_bf16 v[120:123], v[158:161], v[170:173], v[120:123]
	v_mfma_f32_16x16x32_bf16 v[108:111], v[150:153], v[178:181], v[108:111]
	v_mfma_f32_16x16x32_bf16 v[104:107], v[158:161], v[178:181], v[104:107]
	v_mfma_f32_16x16x32_bf16 v[92:95], v[150:153], v[186:189], v[92:95]
	v_mfma_f32_16x16x32_bf16 v[88:91], v[158:161], v[186:189], v[88:91]
	v_mfma_f32_16x16x32_bf16 v[76:79], v[150:153], v[194:197], v[76:79]
	v_mfma_f32_16x16x32_bf16 v[72:75], v[158:161], v[194:197], v[72:75]
	v_mfma_f32_16x16x32_bf16 v[124:127], v[154:157], v[174:177], v[124:127]
	v_mfma_f32_16x16x32_bf16 v[120:123], v[162:165], v[174:177], v[120:123]
	v_mfma_f32_16x16x32_bf16 v[108:111], v[154:157], v[182:185], v[108:111]
	v_mfma_f32_16x16x32_bf16 v[104:107], v[162:165], v[182:185], v[104:107]
	v_mfma_f32_16x16x32_bf16 v[92:95], v[154:157], v[190:193], v[92:95]
	v_mfma_f32_16x16x32_bf16 v[88:91], v[162:165], v[190:193], v[88:91]
	v_mfma_f32_16x16x32_bf16 v[76:79], v[154:157], v[198:201], v[76:79]
	v_mfma_f32_16x16x32_bf16 v[72:75], v[162:165], v[198:201], v[72:75]
	s_setprio 0
	s_barrier
	s_add_i32 s44, 0, 0x1c000
	s_add_i32 s43, s43, s60
	v_add_u32_e32 v149, s44, v141
	v_lshl_add_u64 v[218:219], v[218:219], 0, s[26:27]
	s_mov_b32 m0, s43
	ds_read_b128 v[202:205], v149
	ds_read_b128 v[206:209], v149 offset:1024
	ds_read_b128 v[210:213], v149 offset:2048
	ds_read_b128 v[214:217], v149 offset:3072
	global_load_lds_dwordx4 v[218:219], off
	v_lshl_add_u64 v[218:219], v[220:221], 0, s[26:27]
	s_add_i32 m0, s43, 0x2000
	s_nop 0
	global_load_lds_dwordx4 v[218:219], off
	s_barrier
	s_waitcnt lgkmcnt(0)
	s_setprio 1
	s_waitcnt lgkmcnt(0)
	v_mfma_f32_16x16x32_bf16 v[116:119], v[202:205], v[170:173], v[116:119]
	v_mfma_f32_16x16x32_bf16 v[112:115], v[210:213], v[170:173], v[112:115]
	v_mfma_f32_16x16x32_bf16 v[100:103], v[202:205], v[178:181], v[100:103]
	v_mfma_f32_16x16x32_bf16 v[96:99], v[210:213], v[178:181], v[96:99]
	v_mfma_f32_16x16x32_bf16 v[84:87], v[202:205], v[186:189], v[84:87]
	v_mfma_f32_16x16x32_bf16 v[80:83], v[210:213], v[186:189], v[80:83]
	v_mfma_f32_16x16x32_bf16 v[68:71], v[202:205], v[194:197], v[68:71]
	v_mfma_f32_16x16x32_bf16 v[64:67], v[210:213], v[194:197], v[64:67]
	v_mfma_f32_16x16x32_bf16 v[116:119], v[206:209], v[174:177], v[116:119]
	v_mfma_f32_16x16x32_bf16 v[112:115], v[214:217], v[174:177], v[112:115]
	v_mfma_f32_16x16x32_bf16 v[100:103], v[206:209], v[182:185], v[100:103]
	v_mfma_f32_16x16x32_bf16 v[96:99], v[214:217], v[182:185], v[96:99]
	v_mfma_f32_16x16x32_bf16 v[84:87], v[206:209], v[190:193], v[84:87]
	v_mfma_f32_16x16x32_bf16 v[80:83], v[214:217], v[190:193], v[80:83]
	v_mfma_f32_16x16x32_bf16 v[68:71], v[206:209], v[198:201], v[68:71]
	v_mfma_f32_16x16x32_bf16 v[64:67], v[214:217], v[198:201], v[64:67]
	s_setprio 0
	s_mov_b32 m0, s66
	v_lshl_add_u64 v[218:219], v[222:223], 0, s[26:27]
	s_barrier
	ds_read_b128 v[170:173], v146 offset:49152
	ds_read_b128 v[174:177], v146 offset:50176
	ds_read_b128 v[178:181], v146 offset:51200
	ds_read_b128 v[182:185], v146 offset:52224
	ds_read_b128 v[186:189], v146 offset:53248
	ds_read_b128 v[190:193], v146 offset:54272
	ds_read_b128 v[194:197], v146 offset:55296
	ds_read_b128 v[198:201], v146 offset:56320
	global_load_lds_dwordx4 v[218:219], off
	v_lshl_add_u64 v[218:219], v[224:225], 0, s[26:27]
	s_mov_b32 m0, s67
	s_nop 0
	global_load_lds_dwordx4 v[218:219], off
	s_barrier
; #define PG8_STAGE(bufoff, gbase, voff) do { _Pragma("unroll") for (int _i = 0; _i < 2; ++_i) \
;         __builtin_amdgcn_global_load_lds((const unsigned*)((const char*)(gbase) + (voff)[_i]), (LAS unsigned*)(lds + (bufoff) + ldsw + _i * 8192), 16, 0, 0); } while (0)
; #define PG8_LDA(dst, b, h) do { _Pragma("unroll") for (int m = 0; m < 4; ++m) _Pragma("unroll") for (int k = 0; k < 2; ++k) dst[m][k] = *(const LAS bf16x8*)(lds + PG8_SA(b, h) + aoff + m * 2048 + k * 1024); } while (0)
; #define PG8_MMA(ai, bj, At, Bt) do { __builtin_amdgcn_s_setprio(1); _Pragma("unroll") for (int m = 0; m < 4; ++m) _Pragma("unroll") for (int n = 0; n < 2; ++n) _Pragma("unroll") for (int k = 0; k < 2; ++k) \
;         acc[ai][bj][m][n] = __builtin_amdgcn_mfma_f32_16x16x32_bf16(Bt[n][k], At[m][k], acc[ai][bj][m][n], 0, 0, 0); __builtin_amdgcn_s_setprio(0); } while (0)
; #define PG8_WAIT_V(n) asm volatile("s_waitcnt vmcnt(" #n ")" ::: "memory")
; #define PG8_WAIT_L(n) asm volatile("s_waitcnt lgkmcnt(" #n ")" ::: "memory")
; #define PG8_BAR __builtin_amdgcn_s_barrier()
; #define PG8_SCHED __builtin_amdgcn_sched_barrier(0)
;     ...
;             PG8_BAR; PG8_WAIT_L(0); PG8_MMA(0, 1, At, B1); PG8_BAR;
;             PG8_LDA(At, 1, 1); PG8_STAGE(PG8_SA(1, 0), a3, voffA);
;             PG8_BAR; PG8_WAIT_L(0); PG8_MMA(1, 0, At, B0); PG8_BAR; PG8_SCHED;
;             PG8_STAGE(PG8_SB(1, 1), b3 + hB, voffB);
;             PG8_WAIT_V(6); PG8_BAR; PG8_MMA(1, 1, At, B1); PG8_BAR;
;         }
;         E(acc, cur, wr, wc, fr, fq);
; __device__ __forceinline__ float row_rstd(const float* ssq, int row) {
;     const f32x4* p = (const f32x4*)(ssq + (size_t)row * 16);
;     const f32x4 a = p[0], b = p[1], c = p[2], d = p[3];
;     const float s = ((a[0] + a[1]) + (a[2] + a[3])) + ((b[0] + b[1]) + (b[2] + b[3])) + ((c[0] + c[1]) + (c[2] + c[3])) + ((d[0] + d[1]) + (d[2] + d[3]));
;     return rsqrtf(s * (1.0f / 1024.0f) + 1e-6f);
	s_waitcnt lgkmcnt(0)
	s_setprio 1
	s_waitcnt lgkmcnt(0)
	v_mfma_f32_16x16x32_bf16 v[60:63], v[150:153], v[170:173], v[60:63]
	v_mfma_f32_16x16x32_bf16 v[56:59], v[158:161], v[170:173], v[56:59]
	v_mfma_f32_16x16x32_bf16 v[44:47], v[150:153], v[178:181], v[44:47]
	v_mfma_f32_16x16x32_bf16 v[40:43], v[158:161], v[178:181], v[40:43]
	v_mfma_f32_16x16x32_bf16 v[28:31], v[150:153], v[186:189], v[28:31]
	v_mfma_f32_16x16x32_bf16 v[24:27], v[158:161], v[186:189], v[24:27]
	v_mfma_f32_16x16x32_bf16 v[12:15], v[150:153], v[194:197], v[12:15]
	v_mfma_f32_16x16x32_bf16 v[8:11], v[158:161], v[194:197], v[8:11]
	v_mfma_f32_16x16x32_bf16 v[60:63], v[154:157], v[174:177], v[60:63]
	v_mfma_f32_16x16x32_bf16 v[56:59], v[162:165], v[174:177], v[56:59]
	v_mfma_f32_16x16x32_bf16 v[44:47], v[154:157], v[182:185], v[44:47]
	v_mfma_f32_16x16x32_bf16 v[40:43], v[162:165], v[182:185], v[40:43]
	v_mfma_f32_16x16x32_bf16 v[28:31], v[154:157], v[190:193], v[28:31]
	v_mfma_f32_16x16x32_bf16 v[24:27], v[162:165], v[190:193], v[24:27]
	v_mfma_f32_16x16x32_bf16 v[12:15], v[154:157], v[198:201], v[12:15]
	v_mfma_f32_16x16x32_bf16 v[8:11], v[162:165], v[198:201], v[8:11]
	s_setprio 0
	s_barrier
	s_add_u32 s40, s40, 0x40080
	s_addc_u32 s41, s41, 0
	s_add_i32 s43, s44, s60
	v_lshl_add_u64 v[150:151], s[40:41], 0, v[130:131]
	s_mov_b32 m0, s43
	s_nop 0
	global_load_lds_dwordx4 v[150:151], off
	v_lshl_add_u64 v[150:151], s[40:41], 0, v[134:135]
	s_add_i32 m0, s43, 0x2000
	s_nop 0
	global_load_lds_dwordx4 v[150:151], off
	s_waitcnt vmcnt(6)
	s_barrier
	s_setprio 1
	v_mfma_f32_16x16x32_bf16 v[52:55], v[202:205], v[170:173], v[52:55]
	v_mfma_f32_16x16x32_bf16 v[48:51], v[210:213], v[170:173], v[48:51]
	v_mfma_f32_16x16x32_bf16 v[36:39], v[202:205], v[178:181], v[36:39]
	v_mfma_f32_16x16x32_bf16 v[32:35], v[210:213], v[178:181], v[32:35]
	v_mfma_f32_16x16x32_bf16 v[20:23], v[202:205], v[186:189], v[20:23]
	v_mfma_f32_16x16x32_bf16 v[16:19], v[210:213], v[186:189], v[16:19]
	v_mfma_f32_16x16x32_bf16 v[4:7], v[202:205], v[194:197], v[4:7]
	v_mfma_f32_16x16x32_bf16 v[0:3], v[210:213], v[194:197], v[0:3]
	v_mfma_f32_16x16x32_bf16 v[52:55], v[206:209], v[174:177], v[52:55]
	v_mfma_f32_16x16x32_bf16 v[48:51], v[214:217], v[174:177], v[48:51]
	v_mfma_f32_16x16x32_bf16 v[36:39], v[206:209], v[182:185], v[36:39]
	v_mfma_f32_16x16x32_bf16 v[32:35], v[214:217], v[182:185], v[32:35]
	v_mfma_f32_16x16x32_bf16 v[20:23], v[206:209], v[190:193], v[20:23]
	v_mfma_f32_16x16x32_bf16 v[16:19], v[214:217], v[190:193], v[16:19]
	v_mfma_f32_16x16x32_bf16 v[4:7], v[206:209], v[198:201], v[4:7]
	v_mfma_f32_16x16x32_bf16 v[0:3], v[214:217], v[198:201], v[0:3]
	s_setprio 0
	s_add_i32 s42, s42, 2
	s_add_u32 s33, s33, 0x100
	s_addc_u32 s35, s35, 0
	s_add_u32 s38, s38, 0x100
	s_addc_u32 s39, s39, 0
	s_cmp_gt_u32 s42, 13
	s_barrier
	s_cbranch_scc0 .LBB0_981
	v_lshl_add_u32 v150, s75, 8, v140
	v_add_u32_e32 v164, 0x4000, v150
	v_ashrrev_i32_e32 v165, 31, v164
	v_lshlrev_b64 v[152:153], 6, v[164:165]
	v_lshl_add_u64 v[170:171], s[18:19], 0, v[152:153]
	v_subrev_u32_e32 v176, s18, v170
	v_add_u32_e32 v177, 0x0, v176
	global_load_dwordx4 v[178:181], v177, s[18:19]
	v_add_u32_e32 v177, 0x10, v176
	global_load_dwordx4 v[182:185], v177, s[18:19]
	v_add_u32_e32 v177, 0x20, v176
	global_load_dwordx4 v[186:189], v177, s[18:19]
	v_add_u32_e32 v177, 0x30, v176
	global_load_dwordx4 v[190:193], v177, s[18:19]
	v_add_u32_e32 v177, 0x400, v176
	global_load_dwordx4 v[194:197], v177, s[18:19]
	v_add_u32_e32 v177, 0x410, v176
	global_load_dwordx4 v[198:201], v177, s[18:19]
	v_add_u32_e32 v177, 0x420, v176
	global_load_dwordx4 v[202:205], v177, s[18:19]
	v_add_u32_e32 v177, 0x430, v176
	global_load_dwordx4 v[206:209], v177, s[18:19]
	v_add_u32_e32 v177, 0x800, v176
	global_load_dwordx4 v[210:213], v177, s[18:19]
	v_add_u32_e32 v177, 0x810, v176
	global_load_dwordx4 v[214:217], v177, s[18:19]
	v_add_u32_e32 v177, 0x820, v176
	global_load_dwordx4 v[232:235], v177, s[18:19]
	v_add_u32_e32 v177, 0x830, v176
	global_load_dwordx4 v[236:239], v177, s[18:19]
	v_add_u32_e32 v177, 0xc00, v176
	global_load_dwordx4 v[240:243], v177, s[18:19]
	v_add_u32_e32 v177, 0xc10, v176
	global_load_dwordx4 v[244:247], v177, s[18:19]
	v_add_u32_e32 v177, 0xc20, v176
	global_load_dwordx4 v[248:251], v177, s[18:19]
	v_add_u32_e32 v177, 0xc30, v176
	global_load_dwordx4 v[252:255], v177, s[18:19]
	s_nop 0
	v_lshl_or_b32 v149, s6, 9, v142
	v_lshl_add_u32 v151, v164, 13, v149
	v_add_u32_e32 v174, 0x4010, v150
	v_ashrrev_i32_e32 v175, 31, v174
	s_waitcnt vmcnt(12)
; __device__ __forceinline__ u32x4 pack8(const f32x4 v0, const f32x4 v1) { u32x4 w; w.x = pk2(v0[0], v0[1]); w.y = pk2(v0[2], v0[3]); w.z = pk2(v1[0], v1[1]); w.w = pk2(v1[2], v1[3]); return w; }
; __device__ __forceinline__ float row_rstd(const float* ssq, int row) {
;     const f32x4* p = (const f32x4*)(ssq + (size_t)row * 16);
;     const f32x4 a = p[0], b = p[1], c = p[2], d = p[3];
;     const float s = ((a[0] + a[1]) + (a[2] + a[3])) + ((b[0] + b[1]) + (b[2] + b[3])) + ((c[0] + c[1]) + (c[2] + c[3])) + ((d[0] + d[1]) + (d[2] + d[3]));
;     return rsqrtf(s * (1.0f / 1024.0f) + 1e-6f);
;     __device__ __forceinline__ void operator()(const f32x4 (&acc)[2][2][4][2], const Unit& u, int wr, int wc, int fr, int fq) const {
;     ...
;         const int row0 = row_off + u.pm * 256 + wr * 64 + fr, col0 = u.pn * 256 + wc * 32 + 8 * fq;
; #pragma unroll
;         for (int ai = 0; ai < 2; ++ai)
; #pragma unroll
;             for (int m = 0; m < 4; ++m) {
;                 const int row = row0 + ai * 128 + m * 16; const float rs = row_rstd(ssq, row);
; #pragma unroll
;                 for (int bj = 0; bj < 2; ++bj) { f32x4 v0 = acc[ai][bj][m][0] * rs, v1 = acc[ai][bj][m][1] * rs;
; #pragma unroll
;                     for (int j = 0; j < 4; ++j) { const float a = fmaxf(v0[j], 0.f), b = fmaxf(v1[j], 0.f); v0[j] = a * a; v1[j] = b * b; }
;                     __builtin_amdgcn_raw_buffer_store_b128(pack8(v0, v1), rsrc, (unsigned)(((size_t)row * DFF + col0 + bj * 128) * 2), 0, 16  ); }
	v_mov_b32_e32 v152, v178
	v_mov_b32_e32 v153, v179
	v_mov_b32_e32 v154, v180
	v_mov_b32_e32 v155, v181
	v_mov_b32_e32 v156, v182
	v_mov_b32_e32 v157, v183
	v_mov_b32_e32 v158, v184
	v_mov_b32_e32 v159, v185
	v_mov_b32_e32 v160, v186
	v_mov_b32_e32 v161, v187
	v_mov_b32_e32 v162, v188
	v_mov_b32_e32 v163, v189
	v_mov_b32_e32 v170, v190
	v_mov_b32_e32 v171, v191
	v_mov_b32_e32 v172, v192
	v_mov_b32_e32 v173, v193
	v_add_u32_e32 v177, 0x2000, v176
	global_load_dwordx4 v[178:181], v177, s[18:19]
	v_add_u32_e32 v177, 0x2010, v176
	global_load_dwordx4 v[182:185], v177, s[18:19]
	v_add_u32_e32 v177, 0x2020, v176
	global_load_dwordx4 v[186:189], v177, s[18:19]
	v_add_u32_e32 v177, 0x2030, v176
	global_load_dwordx4 v[190:193], v177, s[18:19]
	v_mov_b32_e32 v164, v153
	v_mov_b32_e32 v165, v154
	v_mov_b32_e32 v153, v155
	v_mov_b32_e32 v154, v157
	v_mov_b32_e32 v155, v158
	v_mov_b32_e32 v157, v159
	v_pk_add_f32 v[152:153], v[164:165], v[152:153]
	v_pk_add_f32 v[154:155], v[154:155], v[156:157]
	v_pk_add_f32 v[152:153], v[152:153], v[152:153] op_sel:[0,1] op_sel_hi:[1,0]
	v_pk_add_f32 v[154:155], v[154:155], v[154:155] op_sel:[0,1] op_sel_hi:[1,0]
	v_add_f32_e32 v158, v160, v161
	v_add_f32_e32 v160, v162, v163
	v_mov_b32_e32 v159, v172
	v_mov_b32_e32 v161, v173
	v_mov_b32_e32 v153, v170
	v_mov_b32_e32 v155, v171
	v_pk_add_f32 v[156:157], v[158:159], v[160:161]
	v_pk_add_f32 v[152:153], v[152:153], v[154:155]
	s_nop 0
	v_pk_add_f32 v[152:153], v[152:153], v[156:157]
	s_nop 0
	v_add_f32_e32 v152, v152, v153
	v_fmamk_f32 v152, v152, 0x3a800000, v148
	v_mul_f32_e32 v153, 0x4b800000, v152
	v_cmp_gt_f32_e32 vcc, s71, v152
	s_nop 1
	v_cndmask_b32_e32 v152, v152, v153, vcc
	v_rsq_f32_e32 v154, v152
	v_lshlrev_b64 v[152:153], 6, v[174:175]
	v_lshl_add_u64 v[152:153], s[18:19], 0, v[152:153]
	v_mul_f32_e32 v155, 0x45800000, v154
	v_cndmask_b32_e32 v154, v154, v155, vcc
	v_pk_mul_f32 v[126:127], v[126:127], v[154:155] op_sel_hi:[1,0]
	v_pk_mul_f32 v[124:125], v[124:125], v[154:155] op_sel_hi:[1,0]
	v_pk_mul_f32 v[122:123], v[122:123], v[154:155] op_sel_hi:[1,0]
	v_pk_mul_f32 v[120:121], v[120:121], v[154:155] op_sel_hi:[1,0]
	v_pk_mul_f32 v[114:115], v[114:115], v[154:155] op_sel_hi:[1,0]
	v_pk_mul_f32 v[112:113], v[112:113], v[154:155] op_sel_hi:[1,0]
	v_pk_mul_f32 v[118:119], v[118:119], v[154:155] op_sel_hi:[1,0]
	v_pk_mul_f32 v[116:117], v[116:117], v[154:155] op_sel_hi:[1,0]
	v_max_f32_e32 v124, 0, v124
	v_max_f32_e32 v120, 0, v120
	v_max_f32_e32 v125, 0, v125
	v_max_f32_e32 v121, 0, v121
	v_max_f32_e32 v126, 0, v126
	v_max_f32_e32 v122, 0, v122
	v_max_f32_e32 v127, 0, v127
	v_max_f32_e32 v123, 0, v123
	v_max_f32_e32 v112, 0, v112
	v_max_f32_e32 v113, 0, v113
	v_max_f32_e32 v114, 0, v114
	v_max_f32_e32 v115, 0, v115
	v_max_f32_e32 v116, 0, v116
	v_max_f32_e32 v117, 0, v117
	v_max_f32_e32 v118, 0, v118
	v_max_f32_e32 v119, 0, v119
	v_mul_f32_e32 v124, v124, v124
	v_mul_f32_e32 v120, v120, v120
	v_mul_f32_e32 v125, v125, v125
	v_mul_f32_e32 v121, v121, v121
	v_mul_f32_e32 v126, v126, v126
	v_mul_f32_e32 v122, v122, v122
	v_mul_f32_e32 v127, v127, v127
	v_mul_f32_e32 v123, v123, v123
	v_mul_f32_e32 v154, v112, v112
	v_mul_f32_e32 v155, v113, v113
	v_mul_f32_e32 v156, v114, v114
	v_mul_f32_e32 v157, v115, v115
	v_cvt_pk_bf16_f32 v112, v124, v125
	v_cvt_pk_bf16_f32 v113, v126, v127
	v_cvt_pk_bf16_f32 v114, v120, v121
	v_cvt_pk_bf16_f32 v115, v122, v123
	v_mul_f32_e32 v116, v116, v116
	v_mul_f32_e32 v117, v117, v117
	v_mul_f32_e32 v118, v118, v118
	v_mul_f32_e32 v119, v119, v119
	buffer_store_dwordx4 v[112:115], v151, s[12:15], 0 offen sc1
	s_nop 1
	v_cvt_pk_bf16_f32 v112, v116, v117
	v_cvt_pk_bf16_f32 v113, v118, v119
	v_cvt_pk_bf16_f32 v114, v154, v155
	v_cvt_pk_bf16_f32 v115, v156, v157
	buffer_store_dwordx4 v[112:115], v151, s[12:15], 0 offen offset:256 sc1
	s_nop 0
	v_add_u32_e32 v152, 0x4020, v150
	v_ashrrev_i32_e32 v153, 31, v152
	v_lshl_add_u32 v151, v174, 13, v149
	s_waitcnt vmcnt(14)
	v_mov_b32_e32 v112, v194
	v_mov_b32_e32 v113, v195
	v_mov_b32_e32 v114, v196
	v_mov_b32_e32 v115, v197
	v_mov_b32_e32 v116, v198
	v_mov_b32_e32 v117, v199
	v_mov_b32_e32 v118, v200
	v_mov_b32_e32 v119, v201
	v_mov_b32_e32 v120, v202
	v_mov_b32_e32 v121, v203
	v_mov_b32_e32 v122, v204
	v_mov_b32_e32 v123, v205
	v_mov_b32_e32 v124, v206
	v_mov_b32_e32 v125, v207
	v_mov_b32_e32 v126, v208
	v_mov_b32_e32 v127, v209
	v_add_u32_e32 v177, 0x2400, v176
	global_load_dwordx4 v[194:197], v177, s[18:19]
	v_add_u32_e32 v177, 0x2410, v176
	global_load_dwordx4 v[198:201], v177, s[18:19]
	v_add_u32_e32 v177, 0x2420, v176
	global_load_dwordx4 v[202:205], v177, s[18:19]
	v_add_u32_e32 v177, 0x2430, v176
	global_load_dwordx4 v[206:209], v177, s[18:19]
	v_mov_b32_e32 v154, v113
	v_mov_b32_e32 v155, v114
	v_mov_b32_e32 v113, v115
	v_mov_b32_e32 v114, v117
	v_mov_b32_e32 v115, v118
	v_mov_b32_e32 v117, v119
	v_pk_add_f32 v[112:113], v[154:155], v[112:113]
	v_pk_add_f32 v[114:115], v[114:115], v[116:117]
	v_pk_add_f32 v[112:113], v[112:113], v[112:113] op_sel:[0,1] op_sel_hi:[1,0]
	v_pk_add_f32 v[114:115], v[114:115], v[114:115] op_sel:[0,1] op_sel_hi:[1,0]
	v_add_f32_e32 v118, v120, v121
	v_add_f32_e32 v120, v122, v123
	v_mov_b32_e32 v119, v126
	v_mov_b32_e32 v121, v127
	v_mov_b32_e32 v113, v124
	v_mov_b32_e32 v115, v125
	v_pk_add_f32 v[116:117], v[118:119], v[120:121]
	v_pk_add_f32 v[112:113], v[112:113], v[114:115]
	s_nop 0
	v_pk_add_f32 v[112:113], v[112:113], v[116:117]
	s_nop 0
	v_add_f32_e32 v112, v112, v113
	v_fmamk_f32 v112, v112, 0x3a800000, v148
	v_mul_f32_e32 v113, 0x4b800000, v112
	v_cmp_gt_f32_e32 vcc, s71, v112
	s_nop 1
	v_cndmask_b32_e32 v112, v112, v113, vcc
	v_rsq_f32_e32 v114, v112
; __device__ __forceinline__ u32x4 pack8(const f32x4 v0, const f32x4 v1) { u32x4 w; w.x = pk2(v0[0], v0[1]); w.y = pk2(v0[2], v0[3]); w.z = pk2(v1[0], v1[1]); w.w = pk2(v1[2], v1[3]); return w; }
; __device__ __forceinline__ float row_rstd(const float* ssq, int row) {
;     const f32x4* p = (const f32x4*)(ssq + (size_t)row * 16);
;     const f32x4 a = p[0], b = p[1], c = p[2], d = p[3];
;     const float s = ((a[0] + a[1]) + (a[2] + a[3])) + ((b[0] + b[1]) + (b[2] + b[3])) + ((c[0] + c[1]) + (c[2] + c[3])) + ((d[0] + d[1]) + (d[2] + d[3]));
;     return rsqrtf(s * (1.0f / 1024.0f) + 1e-6f);
;     __device__ __forceinline__ void operator()(const f32x4 (&acc)[2][2][4][2], const Unit& u, int wr, int wc, int fr, int fq) const {
;     ...
;                 const int row = row0 + ai * 128 + m * 16; const float rs = row_rstd(ssq, row);
; #pragma unroll
;                 for (int bj = 0; bj < 2; ++bj) { f32x4 v0 = acc[ai][bj][m][0] * rs, v1 = acc[ai][bj][m][1] * rs;
; #pragma unroll
;                     for (int j = 0; j < 4; ++j) { const float a = fmaxf(v0[j], 0.f), b = fmaxf(v1[j], 0.f); v0[j] = a * a; v1[j] = b * b; }
;                     __builtin_amdgcn_raw_buffer_store_b128(pack8(v0, v1), rsrc, (unsigned)(((size_t)row * DFF + col0 + bj * 128) * 2), 0, 16  ); }
	v_lshlrev_b64 v[112:113], 6, v[152:153]
	v_lshl_add_u64 v[112:113], s[18:19], 0, v[112:113]
	v_mul_f32_e32 v115, 0x45800000, v114
	v_cndmask_b32_e32 v114, v114, v115, vcc
	v_pk_mul_f32 v[110:111], v[110:111], v[114:115] op_sel_hi:[1,0]
	v_pk_mul_f32 v[108:109], v[108:109], v[114:115] op_sel_hi:[1,0]
	v_pk_mul_f32 v[106:107], v[106:107], v[114:115] op_sel_hi:[1,0]
	v_pk_mul_f32 v[104:105], v[104:105], v[114:115] op_sel_hi:[1,0]
	v_pk_mul_f32 v[98:99], v[98:99], v[114:115] op_sel_hi:[1,0]
	v_pk_mul_f32 v[96:97], v[96:97], v[114:115] op_sel_hi:[1,0]
	v_pk_mul_f32 v[102:103], v[102:103], v[114:115] op_sel_hi:[1,0]
	v_pk_mul_f32 v[100:101], v[100:101], v[114:115] op_sel_hi:[1,0]
	v_max_f32_e32 v108, 0, v108
	v_max_f32_e32 v104, 0, v104
	v_max_f32_e32 v109, 0, v109
	v_max_f32_e32 v105, 0, v105
	v_max_f32_e32 v110, 0, v110
	v_max_f32_e32 v106, 0, v106
	v_max_f32_e32 v111, 0, v111
	v_max_f32_e32 v107, 0, v107
	v_max_f32_e32 v96, 0, v96
	v_max_f32_e32 v97, 0, v97
	v_max_f32_e32 v98, 0, v98
	v_max_f32_e32 v99, 0, v99
	v_max_f32_e32 v100, 0, v100
	v_max_f32_e32 v101, 0, v101
	v_max_f32_e32 v102, 0, v102
	v_max_f32_e32 v103, 0, v103
	v_mul_f32_e32 v108, v108, v108
	v_mul_f32_e32 v104, v104, v104
	v_mul_f32_e32 v109, v109, v109
	v_mul_f32_e32 v105, v105, v105
	v_mul_f32_e32 v110, v110, v110
	v_mul_f32_e32 v106, v106, v106
	v_mul_f32_e32 v111, v111, v111
	v_mul_f32_e32 v107, v107, v107
	v_mul_f32_e32 v114, v96, v96
	v_mul_f32_e32 v115, v97, v97
	v_mul_f32_e32 v116, v98, v98
	v_mul_f32_e32 v117, v99, v99
	v_cvt_pk_bf16_f32 v96, v108, v109
	v_cvt_pk_bf16_f32 v97, v110, v111
	v_cvt_pk_bf16_f32 v98, v104, v105
	v_cvt_pk_bf16_f32 v99, v106, v107
	v_mul_f32_e32 v100, v100, v100
	v_mul_f32_e32 v101, v101, v101
	v_mul_f32_e32 v102, v102, v102
	v_mul_f32_e32 v103, v103, v103
	buffer_store_dwordx4 v[96:99], v151, s[12:15], 0 offen sc1
	s_nop 1
	v_cvt_pk_bf16_f32 v96, v100, v101
	v_cvt_pk_bf16_f32 v97, v102, v103
	v_cvt_pk_bf16_f32 v98, v114, v115
	v_cvt_pk_bf16_f32 v99, v116, v117
	buffer_store_dwordx4 v[96:99], v151, s[12:15], 0 offen offset:256 sc1
	s_nop 0
	v_add_u32_e32 v112, 0x4030, v150
	v_ashrrev_i32_e32 v113, 31, v112
	v_lshl_add_u32 v116, v152, 13, v149
	s_waitcnt vmcnt(16)
	v_mov_b32_e32 v96, v210
	v_mov_b32_e32 v97, v211
	v_mov_b32_e32 v98, v212
	v_mov_b32_e32 v99, v213
	v_mov_b32_e32 v100, v214
	v_mov_b32_e32 v101, v215
	v_mov_b32_e32 v102, v216
	v_mov_b32_e32 v103, v217
	v_mov_b32_e32 v104, v232
	v_mov_b32_e32 v105, v233
	v_mov_b32_e32 v106, v234
	v_mov_b32_e32 v107, v235
	v_mov_b32_e32 v108, v236
	v_mov_b32_e32 v109, v237
	v_mov_b32_e32 v110, v238
	v_mov_b32_e32 v111, v239
	v_add_u32_e32 v177, 0x2800, v176
	global_load_dwordx4 v[210:213], v177, s[18:19]
	v_add_u32_e32 v177, 0x2810, v176
	global_load_dwordx4 v[214:217], v177, s[18:19]
	v_add_u32_e32 v177, 0x2820, v176
	global_load_dwordx4 v[232:235], v177, s[18:19]
	v_add_u32_e32 v177, 0x2830, v176
	global_load_dwordx4 v[236:239], v177, s[18:19]
	v_mov_b32_e32 v114, v97
	v_mov_b32_e32 v115, v98
	v_mov_b32_e32 v97, v99
	v_mov_b32_e32 v98, v101
	v_mov_b32_e32 v99, v102
	v_mov_b32_e32 v101, v103
	v_pk_add_f32 v[96:97], v[114:115], v[96:97]
	v_pk_add_f32 v[98:99], v[98:99], v[100:101]
	v_pk_add_f32 v[96:97], v[96:97], v[96:97] op_sel:[0,1] op_sel_hi:[1,0]
	v_pk_add_f32 v[98:99], v[98:99], v[98:99] op_sel:[0,1] op_sel_hi:[1,0]
	v_add_f32_e32 v102, v104, v105
	v_add_f32_e32 v104, v106, v107
	v_mov_b32_e32 v103, v110
	v_mov_b32_e32 v105, v111
	v_mov_b32_e32 v97, v108
	v_mov_b32_e32 v99, v109
	v_pk_add_f32 v[100:101], v[102:103], v[104:105]
	v_pk_add_f32 v[96:97], v[96:97], v[98:99]
	s_nop 0
	v_pk_add_f32 v[96:97], v[96:97], v[100:101]
	s_nop 0
	v_add_f32_e32 v96, v96, v97
	v_fmamk_f32 v96, v96, 0x3a800000, v148
	v_mul_f32_e32 v97, 0x4b800000, v96
	v_cmp_gt_f32_e32 vcc, s71, v96
	s_nop 1
	v_cndmask_b32_e32 v96, v96, v97, vcc
	v_rsq_f32_e32 v98, v96
	v_lshlrev_b64 v[96:97], 6, v[112:113]
	v_lshl_add_u64 v[96:97], s[18:19], 0, v[96:97]
	v_mul_f32_e32 v99, 0x45800000, v98
	v_cndmask_b32_e32 v98, v98, v99, vcc
	v_pk_mul_f32 v[94:95], v[94:95], v[98:99] op_sel_hi:[1,0]
	v_pk_mul_f32 v[92:93], v[92:93], v[98:99] op_sel_hi:[1,0]
	v_pk_mul_f32 v[90:91], v[90:91], v[98:99] op_sel_hi:[1,0]
	v_pk_mul_f32 v[88:89], v[88:89], v[98:99] op_sel_hi:[1,0]
	v_pk_mul_f32 v[82:83], v[82:83], v[98:99] op_sel_hi:[1,0]
	v_pk_mul_f32 v[80:81], v[80:81], v[98:99] op_sel_hi:[1,0]
	v_pk_mul_f32 v[86:87], v[86:87], v[98:99] op_sel_hi:[1,0]
	v_pk_mul_f32 v[84:85], v[84:85], v[98:99] op_sel_hi:[1,0]
	v_max_f32_e32 v92, 0, v92
	v_max_f32_e32 v88, 0, v88
	v_max_f32_e32 v93, 0, v93
	v_max_f32_e32 v89, 0, v89
	v_max_f32_e32 v94, 0, v94
	v_max_f32_e32 v90, 0, v90
	v_max_f32_e32 v95, 0, v95
	v_max_f32_e32 v91, 0, v91
	v_max_f32_e32 v80, 0, v80
	v_max_f32_e32 v81, 0, v81
	v_max_f32_e32 v82, 0, v82
	v_max_f32_e32 v83, 0, v83
	v_max_f32_e32 v84, 0, v84
	v_max_f32_e32 v85, 0, v85
	v_max_f32_e32 v86, 0, v86
	v_max_f32_e32 v87, 0, v87
	v_mul_f32_e32 v92, v92, v92
	v_mul_f32_e32 v88, v88, v88
	v_mul_f32_e32 v93, v93, v93
	v_mul_f32_e32 v89, v89, v89
	v_mul_f32_e32 v94, v94, v94
	v_mul_f32_e32 v90, v90, v90
	v_mul_f32_e32 v95, v95, v95
	v_mul_f32_e32 v91, v91, v91
	v_mul_f32_e32 v98, v80, v80
	v_mul_f32_e32 v99, v81, v81
	v_mul_f32_e32 v100, v82, v82
	v_mul_f32_e32 v101, v83, v83
	v_cvt_pk_bf16_f32 v80, v92, v93
	v_cvt_pk_bf16_f32 v81, v94, v95
	v_cvt_pk_bf16_f32 v82, v88, v89
	v_cvt_pk_bf16_f32 v83, v90, v91
	v_mul_f32_e32 v84, v84, v84
	v_mul_f32_e32 v85, v85, v85
	v_mul_f32_e32 v86, v86, v86
	v_mul_f32_e32 v87, v87, v87
	buffer_store_dwordx4 v[80:83], v116, s[12:15], 0 offen sc1
	s_nop 1
	v_cvt_pk_bf16_f32 v80, v84, v85
	v_cvt_pk_bf16_f32 v81, v86, v87
	v_cvt_pk_bf16_f32 v82, v98, v99
	v_cvt_pk_bf16_f32 v83, v100, v101
	buffer_store_dwordx4 v[80:83], v116, s[12:15], 0 offen offset:256 sc1
	s_nop 0
	v_add_u32_e32 v96, 0x4080, v150
	v_ashrrev_i32_e32 v97, 31, v96
	v_lshl_add_u32 v100, v112, 13, v149
	s_waitcnt vmcnt(18)
; __device__ __forceinline__ u32x4 pack8(const f32x4 v0, const f32x4 v1) { u32x4 w; w.x = pk2(v0[0], v0[1]); w.y = pk2(v0[2], v0[3]); w.z = pk2(v1[0], v1[1]); w.w = pk2(v1[2], v1[3]); return w; }
; __device__ __forceinline__ float row_rstd(const float* ssq, int row) {
;     const f32x4* p = (const f32x4*)(ssq + (size_t)row * 16);
;     const f32x4 a = p[0], b = p[1], c = p[2], d = p[3];
;     const float s = ((a[0] + a[1]) + (a[2] + a[3])) + ((b[0] + b[1]) + (b[2] + b[3])) + ((c[0] + c[1]) + (c[2] + c[3])) + ((d[0] + d[1]) + (d[2] + d[3]));
;     return rsqrtf(s * (1.0f / 1024.0f) + 1e-6f);
;     __device__ __forceinline__ void operator()(const f32x4 (&acc)[2][2][4][2], const Unit& u, int wr, int wc, int fr, int fq) const {
;     ...
;                 const int row = row0 + ai * 128 + m * 16; const float rs = row_rstd(ssq, row);
; #pragma unroll
;                 for (int bj = 0; bj < 2; ++bj) { f32x4 v0 = acc[ai][bj][m][0] * rs, v1 = acc[ai][bj][m][1] * rs;
; #pragma unroll
;                     for (int j = 0; j < 4; ++j) { const float a = fmaxf(v0[j], 0.f), b = fmaxf(v1[j], 0.f); v0[j] = a * a; v1[j] = b * b; }
;                     __builtin_amdgcn_raw_buffer_store_b128(pack8(v0, v1), rsrc, (unsigned)(((size_t)row * DFF + col0 + bj * 128) * 2), 0, 16  ); }
	v_mov_b32_e32 v80, v240
	v_mov_b32_e32 v81, v241
	v_mov_b32_e32 v82, v242
	v_mov_b32_e32 v83, v243
	v_mov_b32_e32 v84, v244
	v_mov_b32_e32 v85, v245
	v_mov_b32_e32 v86, v246
	v_mov_b32_e32 v87, v247
	v_mov_b32_e32 v88, v248
	v_mov_b32_e32 v89, v249
	v_mov_b32_e32 v90, v250
	v_mov_b32_e32 v91, v251
	v_mov_b32_e32 v92, v252
	v_mov_b32_e32 v93, v253
	v_mov_b32_e32 v94, v254
	v_mov_b32_e32 v95, v255
	v_add_u32_e32 v177, 0x2c00, v176
	global_load_dwordx4 v[240:243], v177, s[18:19]
	v_add_u32_e32 v177, 0x2c10, v176
	global_load_dwordx4 v[244:247], v177, s[18:19]
	v_add_u32_e32 v177, 0x2c20, v176
	global_load_dwordx4 v[248:251], v177, s[18:19]
	v_add_u32_e32 v177, 0x2c30, v176
	global_load_dwordx4 v[252:255], v177, s[18:19]
	v_mov_b32_e32 v98, v81
	v_mov_b32_e32 v99, v82
	v_mov_b32_e32 v81, v83
	v_mov_b32_e32 v82, v85
	v_mov_b32_e32 v83, v86
	v_mov_b32_e32 v85, v87
	v_pk_add_f32 v[80:81], v[98:99], v[80:81]
	v_pk_add_f32 v[82:83], v[82:83], v[84:85]
	v_pk_add_f32 v[80:81], v[80:81], v[80:81] op_sel:[0,1] op_sel_hi:[1,0]
	v_pk_add_f32 v[82:83], v[82:83], v[82:83] op_sel:[0,1] op_sel_hi:[1,0]
	v_add_f32_e32 v86, v88, v89
	v_add_f32_e32 v88, v90, v91
	v_mov_b32_e32 v87, v94
	v_mov_b32_e32 v89, v95
	v_mov_b32_e32 v81, v92
	v_mov_b32_e32 v83, v93
	v_pk_add_f32 v[84:85], v[86:87], v[88:89]
	v_pk_add_f32 v[80:81], v[80:81], v[82:83]
	s_nop 0
	v_pk_add_f32 v[80:81], v[80:81], v[84:85]
	s_nop 0
	v_add_f32_e32 v80, v80, v81
	v_fmamk_f32 v80, v80, 0x3a800000, v148
	v_mul_f32_e32 v81, 0x4b800000, v80
	v_cmp_gt_f32_e32 vcc, s71, v80
	s_nop 1
	v_cndmask_b32_e32 v80, v80, v81, vcc
	v_rsq_f32_e32 v82, v80
	v_lshlrev_b64 v[80:81], 6, v[96:97]
	v_lshl_add_u64 v[80:81], s[18:19], 0, v[80:81]
	v_mul_f32_e32 v83, 0x45800000, v82
	v_cndmask_b32_e32 v82, v82, v83, vcc
	v_pk_mul_f32 v[78:79], v[78:79], v[82:83] op_sel_hi:[1,0]
	v_pk_mul_f32 v[76:77], v[76:77], v[82:83] op_sel_hi:[1,0]
	v_pk_mul_f32 v[74:75], v[74:75], v[82:83] op_sel_hi:[1,0]
	v_pk_mul_f32 v[72:73], v[72:73], v[82:83] op_sel_hi:[1,0]
	v_pk_mul_f32 v[66:67], v[66:67], v[82:83] op_sel_hi:[1,0]
	v_pk_mul_f32 v[64:65], v[64:65], v[82:83] op_sel_hi:[1,0]
	v_pk_mul_f32 v[70:71], v[70:71], v[82:83] op_sel_hi:[1,0]
	v_pk_mul_f32 v[68:69], v[68:69], v[82:83] op_sel_hi:[1,0]
	v_max_f32_e32 v76, 0, v76
	v_max_f32_e32 v72, 0, v72
	v_max_f32_e32 v77, 0, v77
	v_max_f32_e32 v73, 0, v73
	v_max_f32_e32 v78, 0, v78
	v_max_f32_e32 v74, 0, v74
	v_max_f32_e32 v79, 0, v79
	v_max_f32_e32 v75, 0, v75
	v_max_f32_e32 v64, 0, v64
	v_max_f32_e32 v65, 0, v65
	v_max_f32_e32 v66, 0, v66
	v_max_f32_e32 v67, 0, v67
	v_max_f32_e32 v68, 0, v68
	v_max_f32_e32 v69, 0, v69
	v_max_f32_e32 v70, 0, v70
	v_max_f32_e32 v71, 0, v71
	v_mul_f32_e32 v76, v76, v76
	v_mul_f32_e32 v72, v72, v72
	v_mul_f32_e32 v77, v77, v77
	v_mul_f32_e32 v73, v73, v73
	v_mul_f32_e32 v78, v78, v78
	v_mul_f32_e32 v74, v74, v74
	v_mul_f32_e32 v79, v79, v79
	v_mul_f32_e32 v75, v75, v75
	v_mul_f32_e32 v82, v64, v64
	v_mul_f32_e32 v83, v65, v65
	v_mul_f32_e32 v84, v66, v66
	v_mul_f32_e32 v85, v67, v67
	v_cvt_pk_bf16_f32 v64, v76, v77
	v_cvt_pk_bf16_f32 v65, v78, v79
	v_cvt_pk_bf16_f32 v66, v72, v73
	v_cvt_pk_bf16_f32 v67, v74, v75
	v_mul_f32_e32 v68, v68, v68
	v_mul_f32_e32 v69, v69, v69
	v_mul_f32_e32 v70, v70, v70
	v_mul_f32_e32 v71, v71, v71
	buffer_store_dwordx4 v[64:67], v100, s[12:15], 0 offen sc1
	s_nop 1
	v_cvt_pk_bf16_f32 v64, v68, v69
	v_cvt_pk_bf16_f32 v65, v70, v71
	v_cvt_pk_bf16_f32 v66, v82, v83
	v_cvt_pk_bf16_f32 v67, v84, v85
	buffer_store_dwordx4 v[64:67], v100, s[12:15], 0 offen offset:256 sc1
	s_nop 0
	v_add_u32_e32 v80, 0x4090, v150
	v_ashrrev_i32_e32 v81, 31, v80
	v_lshl_add_u32 v84, v96, 13, v149
	s_waitcnt vmcnt(20)
	v_mov_b32_e32 v64, v178
	v_mov_b32_e32 v65, v179
	v_mov_b32_e32 v66, v180
	v_mov_b32_e32 v67, v181
	v_mov_b32_e32 v68, v182
	v_mov_b32_e32 v69, v183
	v_mov_b32_e32 v70, v184
	v_mov_b32_e32 v71, v185
	v_mov_b32_e32 v72, v186
	v_mov_b32_e32 v73, v187
	v_mov_b32_e32 v74, v188
	v_mov_b32_e32 v75, v189
	v_mov_b32_e32 v76, v190
	v_mov_b32_e32 v77, v191
	v_mov_b32_e32 v78, v192
	v_mov_b32_e32 v79, v193
	v_mov_b32_e32 v82, v65
	v_mov_b32_e32 v83, v66
	v_mov_b32_e32 v65, v67
	v_mov_b32_e32 v66, v69
	v_mov_b32_e32 v67, v70
	v_mov_b32_e32 v69, v71
	v_pk_add_f32 v[64:65], v[82:83], v[64:65]
	v_pk_add_f32 v[66:67], v[66:67], v[68:69]
	v_pk_add_f32 v[64:65], v[64:65], v[64:65] op_sel:[0,1] op_sel_hi:[1,0]
	v_pk_add_f32 v[66:67], v[66:67], v[66:67] op_sel:[0,1] op_sel_hi:[1,0]
	v_add_f32_e32 v70, v72, v73
	v_add_f32_e32 v72, v74, v75
	v_mov_b32_e32 v71, v78
	v_mov_b32_e32 v73, v79
	v_mov_b32_e32 v65, v76
	v_mov_b32_e32 v67, v77
	v_pk_add_f32 v[68:69], v[70:71], v[72:73]
	v_pk_add_f32 v[64:65], v[64:65], v[66:67]
	s_nop 0
	v_pk_add_f32 v[64:65], v[64:65], v[68:69]
	s_nop 0
	v_add_f32_e32 v64, v64, v65
	v_fmamk_f32 v64, v64, 0x3a800000, v148
	v_mul_f32_e32 v65, 0x4b800000, v64
	v_cmp_gt_f32_e32 vcc, s71, v64
	s_nop 1
	v_cndmask_b32_e32 v64, v64, v65, vcc
	v_rsq_f32_e32 v66, v64
	v_lshlrev_b64 v[64:65], 6, v[80:81]
	v_lshl_add_u64 v[64:65], s[18:19], 0, v[64:65]
	v_mul_f32_e32 v67, 0x45800000, v66
	v_cndmask_b32_e32 v66, v66, v67, vcc
	v_pk_mul_f32 v[62:63], v[62:63], v[66:67] op_sel_hi:[1,0]
	v_pk_mul_f32 v[60:61], v[60:61], v[66:67] op_sel_hi:[1,0]
	v_pk_mul_f32 v[58:59], v[58:59], v[66:67] op_sel_hi:[1,0]
	v_pk_mul_f32 v[56:57], v[56:57], v[66:67] op_sel_hi:[1,0]
	v_pk_mul_f32 v[50:51], v[50:51], v[66:67] op_sel_hi:[1,0]
	v_pk_mul_f32 v[48:49], v[48:49], v[66:67] op_sel_hi:[1,0]
	v_pk_mul_f32 v[54:55], v[54:55], v[66:67] op_sel_hi:[1,0]
	v_pk_mul_f32 v[52:53], v[52:53], v[66:67] op_sel_hi:[1,0]
	v_max_f32_e32 v60, 0, v60
	v_max_f32_e32 v56, 0, v56
	v_max_f32_e32 v61, 0, v61
	v_max_f32_e32 v57, 0, v57
	v_max_f32_e32 v62, 0, v62
	v_max_f32_e32 v58, 0, v58
	v_max_f32_e32 v63, 0, v63
	v_max_f32_e32 v59, 0, v59
	v_max_f32_e32 v48, 0, v48
	v_max_f32_e32 v49, 0, v49
	v_max_f32_e32 v50, 0, v50
	v_max_f32_e32 v51, 0, v51
	v_max_f32_e32 v52, 0, v52
	v_max_f32_e32 v53, 0, v53
	v_max_f32_e32 v54, 0, v54
	v_max_f32_e32 v55, 0, v55
	v_mul_f32_e32 v60, v60, v60
	v_mul_f32_e32 v56, v56, v56
	v_mul_f32_e32 v61, v61, v61
	v_mul_f32_e32 v57, v57, v57
	v_mul_f32_e32 v62, v62, v62
	v_mul_f32_e32 v58, v58, v58
	v_mul_f32_e32 v63, v63, v63
	v_mul_f32_e32 v59, v59, v59
	v_mul_f32_e32 v66, v48, v48
	v_mul_f32_e32 v67, v49, v49
	v_mul_f32_e32 v68, v50, v50
	v_mul_f32_e32 v69, v51, v51
	v_cvt_pk_bf16_f32 v48, v60, v61
	v_cvt_pk_bf16_f32 v49, v62, v63
	v_cvt_pk_bf16_f32 v50, v56, v57
	v_cvt_pk_bf16_f32 v51, v58, v59
	v_mul_f32_e32 v52, v52, v52
	v_mul_f32_e32 v53, v53, v53
	v_mul_f32_e32 v54, v54, v54
	v_mul_f32_e32 v55, v55, v55
	buffer_store_dwordx4 v[48:51], v84, s[12:15], 0 offen sc1
	s_nop 1
	v_cvt_pk_bf16_f32 v48, v52, v53
	v_cvt_pk_bf16_f32 v49, v54, v55
	v_cvt_pk_bf16_f32 v50, v66, v67
	v_cvt_pk_bf16_f32 v51, v68, v69
	buffer_store_dwordx4 v[48:51], v84, s[12:15], 0 offen offset:256 sc1
	s_nop 0
	v_add_u32_e32 v64, 0x40a0, v150
	v_ashrrev_i32_e32 v65, 31, v64
	v_lshl_add_u32 v68, v80, 13, v149
	s_waitcnt vmcnt(16)
; __device__ __forceinline__ u32x4 pack8(const f32x4 v0, const f32x4 v1) { u32x4 w; w.x = pk2(v0[0], v0[1]); w.y = pk2(v0[2], v0[3]); w.z = pk2(v1[0], v1[1]); w.w = pk2(v1[2], v1[3]); return w; }
; __device__ __forceinline__ float row_rstd(const float* ssq, int row) {
;     const f32x4* p = (const f32x4*)(ssq + (size_t)row * 16);
;     const f32x4 a = p[0], b = p[1], c = p[2], d = p[3];
;     const float s = ((a[0] + a[1]) + (a[2] + a[3])) + ((b[0] + b[1]) + (b[2] + b[3])) + ((c[0] + c[1]) + (c[2] + c[3])) + ((d[0] + d[1]) + (d[2] + d[3]));
;     return rsqrtf(s * (1.0f / 1024.0f) + 1e-6f);
;     __device__ __forceinline__ void operator()(const f32x4 (&acc)[2][2][4][2], const Unit& u, int wr, int wc, int fr, int fq) const {
;     ...
;                 const int row = row0 + ai * 128 + m * 16; const float rs = row_rstd(ssq, row);
; #pragma unroll
;                 for (int bj = 0; bj < 2; ++bj) { f32x4 v0 = acc[ai][bj][m][0] * rs, v1 = acc[ai][bj][m][1] * rs;
; #pragma unroll
;                     for (int j = 0; j < 4; ++j) { const float a = fmaxf(v0[j], 0.f), b = fmaxf(v1[j], 0.f); v0[j] = a * a; v1[j] = b * b; }
;                     __builtin_amdgcn_raw_buffer_store_b128(pack8(v0, v1), rsrc, (unsigned)(((size_t)row * DFF + col0 + bj * 128) * 2), 0, 16  ); }
	v_mov_b32_e32 v48, v194
	v_mov_b32_e32 v49, v195
	v_mov_b32_e32 v50, v196
	v_mov_b32_e32 v51, v197
	v_mov_b32_e32 v52, v198
	v_mov_b32_e32 v53, v199
	v_mov_b32_e32 v54, v200
	v_mov_b32_e32 v55, v201
	v_mov_b32_e32 v56, v202
	v_mov_b32_e32 v57, v203
	v_mov_b32_e32 v58, v204
	v_mov_b32_e32 v59, v205
	v_mov_b32_e32 v60, v206
	v_mov_b32_e32 v61, v207
	v_mov_b32_e32 v62, v208
	v_mov_b32_e32 v63, v209
	v_mov_b32_e32 v66, v49
	v_mov_b32_e32 v67, v50
	v_mov_b32_e32 v49, v51
	v_mov_b32_e32 v50, v53
	v_mov_b32_e32 v51, v54
	v_mov_b32_e32 v53, v55
	v_pk_add_f32 v[48:49], v[66:67], v[48:49]
	v_pk_add_f32 v[50:51], v[50:51], v[52:53]
	v_pk_add_f32 v[48:49], v[48:49], v[48:49] op_sel:[0,1] op_sel_hi:[1,0]
	v_pk_add_f32 v[50:51], v[50:51], v[50:51] op_sel:[0,1] op_sel_hi:[1,0]
	v_add_f32_e32 v54, v56, v57
	v_add_f32_e32 v56, v58, v59
	v_mov_b32_e32 v55, v62
	v_mov_b32_e32 v57, v63
	v_mov_b32_e32 v49, v60
	v_mov_b32_e32 v51, v61
	v_pk_add_f32 v[52:53], v[54:55], v[56:57]
	v_pk_add_f32 v[48:49], v[48:49], v[50:51]
	s_nop 0
	v_pk_add_f32 v[48:49], v[48:49], v[52:53]
	s_nop 0
	v_add_f32_e32 v48, v48, v49
	v_fmamk_f32 v48, v48, 0x3a800000, v148
	v_mul_f32_e32 v49, 0x4b800000, v48
	v_cmp_gt_f32_e32 vcc, s71, v48
	s_nop 1
	v_cndmask_b32_e32 v48, v48, v49, vcc
	v_rsq_f32_e32 v50, v48
	v_lshlrev_b64 v[48:49], 6, v[64:65]
	v_lshl_add_u64 v[48:49], s[18:19], 0, v[48:49]
	v_mul_f32_e32 v51, 0x45800000, v50
	v_cndmask_b32_e32 v50, v50, v51, vcc
	v_pk_mul_f32 v[46:47], v[46:47], v[50:51] op_sel_hi:[1,0]
	v_pk_mul_f32 v[44:45], v[44:45], v[50:51] op_sel_hi:[1,0]
	v_pk_mul_f32 v[42:43], v[42:43], v[50:51] op_sel_hi:[1,0]
	v_pk_mul_f32 v[40:41], v[40:41], v[50:51] op_sel_hi:[1,0]
	v_pk_mul_f32 v[34:35], v[34:35], v[50:51] op_sel_hi:[1,0]
	v_pk_mul_f32 v[32:33], v[32:33], v[50:51] op_sel_hi:[1,0]
	v_pk_mul_f32 v[38:39], v[38:39], v[50:51] op_sel_hi:[1,0]
	v_pk_mul_f32 v[36:37], v[36:37], v[50:51] op_sel_hi:[1,0]
	v_max_f32_e32 v44, 0, v44
	v_max_f32_e32 v40, 0, v40
	v_max_f32_e32 v45, 0, v45
	v_max_f32_e32 v41, 0, v41
	v_max_f32_e32 v46, 0, v46
	v_max_f32_e32 v42, 0, v42
	v_max_f32_e32 v47, 0, v47
	v_max_f32_e32 v43, 0, v43
	v_max_f32_e32 v32, 0, v32
	v_max_f32_e32 v33, 0, v33
	v_max_f32_e32 v34, 0, v34
	v_max_f32_e32 v35, 0, v35
	v_max_f32_e32 v36, 0, v36
	v_max_f32_e32 v37, 0, v37
	v_max_f32_e32 v38, 0, v38
	v_max_f32_e32 v39, 0, v39
	v_mul_f32_e32 v44, v44, v44
	v_mul_f32_e32 v40, v40, v40
	v_mul_f32_e32 v45, v45, v45
	v_mul_f32_e32 v41, v41, v41
	v_mul_f32_e32 v46, v46, v46
	v_mul_f32_e32 v42, v42, v42
	v_mul_f32_e32 v47, v47, v47
	v_mul_f32_e32 v43, v43, v43
	v_mul_f32_e32 v50, v32, v32
	v_mul_f32_e32 v51, v33, v33
	v_mul_f32_e32 v52, v34, v34
	v_mul_f32_e32 v53, v35, v35
	v_cvt_pk_bf16_f32 v32, v44, v45
	v_cvt_pk_bf16_f32 v33, v46, v47
	v_cvt_pk_bf16_f32 v34, v40, v41
	v_cvt_pk_bf16_f32 v35, v42, v43
	v_mul_f32_e32 v36, v36, v36
	v_mul_f32_e32 v37, v37, v37
	v_mul_f32_e32 v38, v38, v38
	v_mul_f32_e32 v39, v39, v39
	buffer_store_dwordx4 v[32:35], v68, s[12:15], 0 offen sc1
	s_nop 1
	v_cvt_pk_bf16_f32 v32, v36, v37
	v_cvt_pk_bf16_f32 v33, v38, v39
	v_cvt_pk_bf16_f32 v34, v50, v51
	v_cvt_pk_bf16_f32 v35, v52, v53
	buffer_store_dwordx4 v[32:35], v68, s[12:15], 0 offen offset:256 sc1
	s_nop 0
	v_add_u32_e32 v48, 0x40b0, v150
	v_ashrrev_i32_e32 v49, 31, v48
	v_lshl_add_u32 v52, v64, 13, v149
	s_waitcnt vmcnt(12)
	v_mov_b32_e32 v32, v210
	v_mov_b32_e32 v33, v211
	v_mov_b32_e32 v34, v212
	v_mov_b32_e32 v35, v213
	v_mov_b32_e32 v36, v214
	v_mov_b32_e32 v37, v215
	v_mov_b32_e32 v38, v216
	v_mov_b32_e32 v39, v217
	v_mov_b32_e32 v40, v232
	v_mov_b32_e32 v41, v233
	v_mov_b32_e32 v42, v234
	v_mov_b32_e32 v43, v235
	v_mov_b32_e32 v44, v236
	v_mov_b32_e32 v45, v237
	v_mov_b32_e32 v46, v238
	v_mov_b32_e32 v47, v239
	v_mov_b32_e32 v50, v33
	v_mov_b32_e32 v51, v34
	v_mov_b32_e32 v33, v35
	v_mov_b32_e32 v34, v37
	v_mov_b32_e32 v35, v38
	v_mov_b32_e32 v37, v39
	v_pk_add_f32 v[32:33], v[50:51], v[32:33]
	v_pk_add_f32 v[34:35], v[34:35], v[36:37]
	v_pk_add_f32 v[32:33], v[32:33], v[32:33] op_sel:[0,1] op_sel_hi:[1,0]
	v_pk_add_f32 v[34:35], v[34:35], v[34:35] op_sel:[0,1] op_sel_hi:[1,0]
	v_add_f32_e32 v38, v40, v41
	v_add_f32_e32 v40, v42, v43
	v_mov_b32_e32 v39, v46
	v_mov_b32_e32 v41, v47
	v_mov_b32_e32 v33, v44
	v_mov_b32_e32 v35, v45
	v_pk_add_f32 v[36:37], v[38:39], v[40:41]
	v_pk_add_f32 v[32:33], v[32:33], v[34:35]
	s_nop 0
	v_pk_add_f32 v[32:33], v[32:33], v[36:37]
	s_nop 0
	v_add_f32_e32 v32, v32, v33
	v_fmamk_f32 v32, v32, 0x3a800000, v148
	v_mul_f32_e32 v33, 0x4b800000, v32
	v_cmp_gt_f32_e32 vcc, s71, v32
	s_nop 1
	v_cndmask_b32_e32 v32, v32, v33, vcc
	v_rsq_f32_e32 v34, v32
	v_lshlrev_b64 v[32:33], 6, v[48:49]
	v_lshl_add_u64 v[32:33], s[18:19], 0, v[32:33]
	v_mul_f32_e32 v35, 0x45800000, v34
	v_cndmask_b32_e32 v34, v34, v35, vcc
	v_pk_mul_f32 v[30:31], v[30:31], v[34:35] op_sel_hi:[1,0]
	v_pk_mul_f32 v[28:29], v[28:29], v[34:35] op_sel_hi:[1,0]
	v_pk_mul_f32 v[26:27], v[26:27], v[34:35] op_sel_hi:[1,0]
	v_pk_mul_f32 v[24:25], v[24:25], v[34:35] op_sel_hi:[1,0]
	v_pk_mul_f32 v[18:19], v[18:19], v[34:35] op_sel_hi:[1,0]
	v_pk_mul_f32 v[16:17], v[16:17], v[34:35] op_sel_hi:[1,0]
	v_pk_mul_f32 v[22:23], v[22:23], v[34:35] op_sel_hi:[1,0]
	v_pk_mul_f32 v[20:21], v[20:21], v[34:35] op_sel_hi:[1,0]
	v_max_f32_e32 v28, 0, v28
	v_max_f32_e32 v24, 0, v24
	v_max_f32_e32 v29, 0, v29
	v_max_f32_e32 v25, 0, v25
	v_max_f32_e32 v30, 0, v30
	v_max_f32_e32 v26, 0, v26
	v_max_f32_e32 v31, 0, v31
	v_max_f32_e32 v27, 0, v27
	v_max_f32_e32 v16, 0, v16
	v_max_f32_e32 v17, 0, v17
	v_max_f32_e32 v18, 0, v18
	v_max_f32_e32 v19, 0, v19
	v_max_f32_e32 v20, 0, v20
	v_max_f32_e32 v21, 0, v21
	v_max_f32_e32 v22, 0, v22
	v_max_f32_e32 v23, 0, v23
	v_mul_f32_e32 v28, v28, v28
	v_mul_f32_e32 v24, v24, v24
	v_mul_f32_e32 v29, v29, v29
	v_mul_f32_e32 v25, v25, v25
	v_mul_f32_e32 v30, v30, v30
	v_mul_f32_e32 v26, v26, v26
	v_mul_f32_e32 v31, v31, v31
	v_mul_f32_e32 v27, v27, v27
	v_mul_f32_e32 v34, v16, v16
	v_mul_f32_e32 v35, v17, v17
	v_mul_f32_e32 v36, v18, v18
	v_mul_f32_e32 v37, v19, v19
	v_cvt_pk_bf16_f32 v16, v28, v29
	v_cvt_pk_bf16_f32 v17, v30, v31
	v_cvt_pk_bf16_f32 v18, v24, v25
	v_cvt_pk_bf16_f32 v19, v26, v27
	v_mul_f32_e32 v20, v20, v20
	v_mul_f32_e32 v21, v21, v21
	v_mul_f32_e32 v22, v22, v22
	v_mul_f32_e32 v23, v23, v23
	buffer_store_dwordx4 v[16:19], v52, s[12:15], 0 offen sc1
	s_nop 1
	v_cvt_pk_bf16_f32 v16, v20, v21
	v_cvt_pk_bf16_f32 v17, v22, v23
	v_cvt_pk_bf16_f32 v18, v34, v35
	v_cvt_pk_bf16_f32 v19, v36, v37
	buffer_store_dwordx4 v[16:19], v52, s[12:15], 0 offen offset:256 sc1
	s_nop 0
	s_waitcnt vmcnt(8)
; __device__ __forceinline__ u32x4 pack8(const f32x4 v0, const f32x4 v1) { u32x4 w; w.x = pk2(v0[0], v0[1]); w.y = pk2(v0[2], v0[3]); w.z = pk2(v1[0], v1[1]); w.w = pk2(v1[2], v1[3]); return w; }
;     __device__ __forceinline__ void operator()(const f32x4 (&acc)[2][2][4][2], const Unit& u, int wr, int wc, int fr, int fq) const {
;     ...
;                 const int row = row0 + ai * 128 + m * 16; const float rs = row_rstd(ssq, row);
; #pragma unroll
;                 for (int bj = 0; bj < 2; ++bj) { f32x4 v0 = acc[ai][bj][m][0] * rs, v1 = acc[ai][bj][m][1] * rs;
; #pragma unroll
;                     for (int j = 0; j < 4; ++j) { const float a = fmaxf(v0[j], 0.f), b = fmaxf(v1[j], 0.f); v0[j] = a * a; v1[j] = b * b; }
;                     __builtin_amdgcn_raw_buffer_store_b128(pack8(v0, v1), rsrc, (unsigned)(((size_t)row * DFF + col0 + bj * 128) * 2), 0, 16  ); }
;             }
;         asm volatile("s_waitcnt vmcnt(0)" ::: "memory");
;         if (fr == 0 && fq == 0) (void)__hip_atomic_fetch_add(ready + 64 * (pm_off + u.pm), 1u, __ATOMIC_RELAXED, __HIP_MEMORY_SCOPE_AGENT);
	v_mov_b32_e32 v16, v240
	v_mov_b32_e32 v17, v241
	v_mov_b32_e32 v18, v242
	v_mov_b32_e32 v19, v243
	v_mov_b32_e32 v20, v244
	v_mov_b32_e32 v21, v245
	v_mov_b32_e32 v22, v246
	v_mov_b32_e32 v23, v247
	v_mov_b32_e32 v24, v248
	v_mov_b32_e32 v25, v249
	v_mov_b32_e32 v26, v250
	v_mov_b32_e32 v27, v251
	v_mov_b32_e32 v28, v252
	v_mov_b32_e32 v29, v253
	v_mov_b32_e32 v30, v254
	v_mov_b32_e32 v31, v255
	v_mov_b32_e32 v32, v17
	v_mov_b32_e32 v33, v18
	v_mov_b32_e32 v17, v19
	v_mov_b32_e32 v18, v21
	v_mov_b32_e32 v19, v22
	v_mov_b32_e32 v21, v23
	v_pk_add_f32 v[16:17], v[32:33], v[16:17]
	v_pk_add_f32 v[18:19], v[18:19], v[20:21]
	v_pk_add_f32 v[16:17], v[16:17], v[16:17] op_sel:[0,1] op_sel_hi:[1,0]
	v_pk_add_f32 v[18:19], v[18:19], v[18:19] op_sel:[0,1] op_sel_hi:[1,0]
	v_add_f32_e32 v22, v24, v25
	v_add_f32_e32 v24, v26, v27
	v_mov_b32_e32 v23, v30
	v_mov_b32_e32 v25, v31
	v_mov_b32_e32 v17, v28
	v_mov_b32_e32 v19, v29
	v_pk_add_f32 v[20:21], v[22:23], v[24:25]
	v_pk_add_f32 v[16:17], v[16:17], v[18:19]
	s_nop 0
	v_pk_add_f32 v[16:17], v[16:17], v[20:21]
	s_nop 0
	v_add_f32_e32 v16, v16, v17
	v_fmamk_f32 v16, v16, 0x3a800000, v148
	v_mul_f32_e32 v17, 0x4b800000, v16
	v_cmp_gt_f32_e32 vcc, s71, v16
	s_nop 1
	v_cndmask_b32_e32 v16, v16, v17, vcc
	v_rsq_f32_e32 v16, v16
	v_lshl_add_u32 v17, v48, 13, v149
	v_mul_f32_e32 v18, 0x45800000, v16
	v_cndmask_b32_e32 v16, v16, v18, vcc
	v_pk_mul_f32 v[14:15], v[14:15], v[16:17] op_sel_hi:[1,0]
	v_pk_mul_f32 v[12:13], v[12:13], v[16:17] op_sel_hi:[1,0]
	v_pk_mul_f32 v[10:11], v[10:11], v[16:17] op_sel_hi:[1,0]
	v_pk_mul_f32 v[8:9], v[8:9], v[16:17] op_sel_hi:[1,0]
	v_pk_mul_f32 v[2:3], v[2:3], v[16:17] op_sel_hi:[1,0]
	v_pk_mul_f32 v[0:1], v[0:1], v[16:17] op_sel_hi:[1,0]
	v_pk_mul_f32 v[6:7], v[6:7], v[16:17] op_sel_hi:[1,0]
	v_pk_mul_f32 v[4:5], v[4:5], v[16:17] op_sel_hi:[1,0]
	v_max_f32_e32 v12, 0, v12
	v_max_f32_e32 v8, 0, v8
	v_max_f32_e32 v13, 0, v13
	v_max_f32_e32 v9, 0, v9
	v_max_f32_e32 v14, 0, v14
	v_max_f32_e32 v10, 0, v10
	v_max_f32_e32 v15, 0, v15
	v_max_f32_e32 v11, 0, v11
	v_max_f32_e32 v0, 0, v0
	v_max_f32_e32 v1, 0, v1
	v_max_f32_e32 v2, 0, v2
	v_max_f32_e32 v3, 0, v3
	v_max_f32_e32 v4, 0, v4
	v_max_f32_e32 v5, 0, v5
	v_max_f32_e32 v6, 0, v6
	v_max_f32_e32 v7, 0, v7
	v_mul_f32_e32 v12, v12, v12
	v_mul_f32_e32 v8, v8, v8
	v_mul_f32_e32 v13, v13, v13
	v_mul_f32_e32 v9, v9, v9
	v_mul_f32_e32 v14, v14, v14
	v_mul_f32_e32 v10, v10, v10
	v_mul_f32_e32 v15, v15, v15
	v_mul_f32_e32 v11, v11, v11
	v_mul_f32_e32 v16, v0, v0
	v_mul_f32_e32 v18, v1, v1
	v_mul_f32_e32 v19, v2, v2
	v_mul_f32_e32 v20, v3, v3
	v_cvt_pk_bf16_f32 v0, v12, v13
	v_cvt_pk_bf16_f32 v1, v14, v15
	v_cvt_pk_bf16_f32 v2, v8, v9
	v_cvt_pk_bf16_f32 v3, v10, v11
	v_mul_f32_e32 v4, v4, v4
	v_mul_f32_e32 v5, v5, v5
	v_mul_f32_e32 v6, v6, v6
	v_mul_f32_e32 v7, v7, v7
	buffer_store_dwordx4 v[0:3], v17, s[12:15], 0 offen sc1
	s_nop 1
	v_cvt_pk_bf16_f32 v0, v4, v5
	v_cvt_pk_bf16_f32 v1, v6, v7
	v_cvt_pk_bf16_f32 v2, v16, v18
	v_cvt_pk_bf16_f32 v3, v19, v20
	buffer_store_dwordx4 v[0:3], v17, s[12:15], 0 offen offset:256 sc1
	s_waitcnt vmcnt(0)
	s_and_saveexec_b64 s[38:39], s[10:11]
	s_cbranch_execz .LBB0_973
	s_mov_b64 s[40:41], exec
	v_mbcnt_lo_u32_b32 v0, s40, 0
	v_mbcnt_hi_u32_b32 v0, s41, v0
	v_cmp_eq_u32_e32 vcc, 0, v0
	s_and_b64 s[6:7], exec, vcc
	s_mov_b64 exec, s[6:7]
	s_cbranch_execz .LBB0_973
	s_lshl_b32 s6, s75, 6
	s_addk_i32 s6, 0x1000
	s_ashr_i32 s7, s6, 31
	s_lshl_b64 s[6:7], s[6:7], 2
	s_add_u32 s6, s73, s6
	s_addc_u32 s7, s74, s7
	s_bcnt1_i32_b64 s8, s[40:41]
	v_mov_b32_e32 v0, s8
	global_atomic_add v131, v0, s[6:7]
	s_branch .LBB0_973

; #define PG8_STAGE(bufoff, gbase, voff) do { _Pragma("unroll") for (int _i = 0; _i < 2; ++_i) \
;         __builtin_amdgcn_global_load_lds((const unsigned*)((const char*)(gbase) + (voff)[_i]), (LAS unsigned*)(lds + (bufoff) + ldsw + _i * 8192), 16, 0, 0); } while (0)
; #define PG8_LDA(dst, b, h) do { _Pragma("unroll") for (int m = 0; m < 4; ++m) _Pragma("unroll") for (int k = 0; k < 2; ++k) dst[m][k] = *(const LAS bf16x8*)(lds + PG8_SA(b, h) + aoff + m * 2048 + k * 1024); } while (0)
; #define PG8_LDB(dst, b, h) do { _Pragma("unroll") for (int n = 0; n < 2; ++n) _Pragma("unroll") for (int k = 0; k < 2; ++k) dst[n][k] = *(const LAS bf16x8*)(lds + PG8_SB(b, h) + boff + n * 2048 + k * 1024); } while (0)
; #define PG8_MMA(ai, bj, At, Bt) do { __builtin_amdgcn_s_setprio(1); _Pragma("unroll") for (int m = 0; m < 4; ++m) _Pragma("unroll") for (int n = 0; n < 2; ++n) _Pragma("unroll") for (int k = 0; k < 2; ++k) \
;         acc[ai][bj][m][n] = __builtin_amdgcn_mfma_f32_16x16x32_bf16(Bt[n][k], At[m][k], acc[ai][bj][m][n], 0, 0, 0); __builtin_amdgcn_s_setprio(0); } while (0)
; #define PG8_WAIT_L(n) asm volatile("s_waitcnt lgkmcnt(" #n ")" ::: "memory")
; #define PG8_BAR __builtin_amdgcn_s_barrier()
; #define PG8_SCHED __builtin_amdgcn_sched_barrier(0)
;     ...
;             const bool last = (t == nt - 2);
;             const char* a1 = cA + (size_t)(t + 1) * kstep;
;             const char* a2 = last ? nA : cA + (size_t)(t + 2) * kstep; const char* b2 = last ? nB : cB + (size_t)(t + 2) * kstep;
;             const char* a3 = a2 + kstep; const char* b3 = b2 + kstep;
;             if (last && has_next) PG8_A_READY(nxt);
;             PG8_LDB(B0, 0, 0); PG8_SCHED; PG8_LDA(At, 0, 0); PG8_STAGE(PG8_SA(1, 1), a1 + hA, voffA);
;             PG8_WAIT_L(8); PG8_BAR; PG8_WAIT_L(0); PG8_MMA(0, 0, At, B0); PG8_BAR; PG8_SCHED;
;             PG8_LDB(B1, 0, 1); PG8_STAGE(PG8_SB(0, 0), b2, voffB);
;             PG8_BAR; PG8_WAIT_L(0); PG8_MMA(0, 1, At, B1); PG8_BAR;
;             PG8_LDA(At, 0, 1); PG8_STAGE(PG8_SA(0, 0), a2, voffA);
;             PG8_BAR; PG8_WAIT_L(0); PG8_MMA(1, 0, At, B0); PG8_BAR; PG8_SCHED;
.LBB0_1288:
	ds_read_b128 v[146:149], v155
	ds_read_b128 v[160:163], v155 offset:1024
	ds_read_b128 v[170:173], v155 offset:2048
	ds_read_b128 v[174:177], v155 offset:3072
	s_add_u32 s36, s34, 0xfffc0080
	s_addc_u32 s37, s35, -1
	s_cmp_eq_u32 s42, 12
	s_cselect_b32 s39, s7, s37
	s_cselect_b32 s38, s8, s36
	s_cselect_b32 s37, s9, s33
	s_cselect_b32 s36, s23, s25
	v_lshl_add_u64 v[150:151], s[34:35], 0, v[138:139]
	s_add_i32 m0, s31, 0xc000
	ds_read_b128 v[178:181], v156
	ds_read_b128 v[182:185], v156 offset:1024
	ds_read_b128 v[186:189], v156 offset:2048
	ds_read_b128 v[190:193], v156 offset:3072
	ds_read_b128 v[194:197], v156 offset:4096
	ds_read_b128 v[198:201], v156 offset:5120
	ds_read_b128 v[202:205], v156 offset:6144
	ds_read_b128 v[206:209], v156 offset:7168
	global_load_lds_dwordx4 v[150:151], off
	v_lshl_add_u64 v[150:151], s[34:35], 0, v[136:137]
	s_add_i32 m0, s31, 0xe000
	s_nop 0
	global_load_lds_dwordx4 v[150:151], off
	s_waitcnt lgkmcnt(8)
	s_barrier
	s_waitcnt lgkmcnt(0)
	s_setprio 1
	s_waitcnt lgkmcnt(0)
	v_mfma_f32_16x16x32_bf16 v[124:127], v[146:149], v[178:181], v[124:127]
	v_mfma_f32_16x16x32_bf16 v[120:123], v[170:173], v[178:181], v[120:123]
	v_mfma_f32_16x16x32_bf16 v[108:111], v[146:149], v[186:189], v[108:111]
	v_mfma_f32_16x16x32_bf16 v[104:107], v[170:173], v[186:189], v[104:107]
	v_mfma_f32_16x16x32_bf16 v[92:95], v[146:149], v[194:197], v[92:95]
	v_mfma_f32_16x16x32_bf16 v[88:91], v[170:173], v[194:197], v[88:91]
	v_mfma_f32_16x16x32_bf16 v[76:79], v[146:149], v[202:205], v[76:79]
	v_mfma_f32_16x16x32_bf16 v[72:75], v[170:173], v[202:205], v[72:75]
	v_mfma_f32_16x16x32_bf16 v[124:127], v[160:163], v[182:185], v[124:127]
	v_mfma_f32_16x16x32_bf16 v[120:123], v[174:177], v[182:185], v[120:123]
	v_mfma_f32_16x16x32_bf16 v[108:111], v[160:163], v[190:193], v[108:111]
	v_mfma_f32_16x16x32_bf16 v[104:107], v[174:177], v[190:193], v[104:107]
	v_mfma_f32_16x16x32_bf16 v[92:95], v[160:163], v[198:201], v[92:95]
	v_mfma_f32_16x16x32_bf16 v[88:91], v[174:177], v[198:201], v[88:91]
	v_mfma_f32_16x16x32_bf16 v[76:79], v[160:163], v[206:209], v[76:79]
	v_mfma_f32_16x16x32_bf16 v[72:75], v[174:177], v[206:209], v[72:75]
	s_setprio 0
	s_barrier
	s_add_i32 s43, s63, s55
	v_lshl_add_u64 v[150:151], s[36:37], 0, v[130:131]
	s_mov_b32 m0, s43
	ds_read_b128 v[210:213], v157
	ds_read_b128 v[214:217], v157 offset:1024
	ds_read_b128 v[218:221], v157 offset:2048
	ds_read_b128 v[222:225], v157 offset:3072
	global_load_lds_dwordx4 v[150:151], off
	v_lshl_add_u64 v[164:165], s[36:37], 0, v[134:135]
	s_add_i32 m0, s43, 0x2000
	s_nop 0
	global_load_lds_dwordx4 v[164:165], off
	s_barrier
	s_waitcnt lgkmcnt(0)
	s_setprio 1
	s_waitcnt lgkmcnt(0)
	v_mfma_f32_16x16x32_bf16 v[116:119], v[210:213], v[178:181], v[116:119]
	v_mfma_f32_16x16x32_bf16 v[112:115], v[218:221], v[178:181], v[112:115]
	v_mfma_f32_16x16x32_bf16 v[100:103], v[210:213], v[186:189], v[100:103]
	v_mfma_f32_16x16x32_bf16 v[96:99], v[218:221], v[186:189], v[96:99]
	v_mfma_f32_16x16x32_bf16 v[84:87], v[210:213], v[194:197], v[84:87]
	v_mfma_f32_16x16x32_bf16 v[80:83], v[218:221], v[194:197], v[80:83]
	v_mfma_f32_16x16x32_bf16 v[68:71], v[210:213], v[202:205], v[68:71]
	v_mfma_f32_16x16x32_bf16 v[64:67], v[218:221], v[202:205], v[64:67]
	v_mfma_f32_16x16x32_bf16 v[116:119], v[214:217], v[182:185], v[116:119]
	v_mfma_f32_16x16x32_bf16 v[112:115], v[222:225], v[182:185], v[112:115]
	v_mfma_f32_16x16x32_bf16 v[100:103], v[214:217], v[190:193], v[100:103]
	v_mfma_f32_16x16x32_bf16 v[96:99], v[222:225], v[190:193], v[96:99]
	v_mfma_f32_16x16x32_bf16 v[84:87], v[214:217], v[198:201], v[84:87]
	v_mfma_f32_16x16x32_bf16 v[80:83], v[222:225], v[198:201], v[80:83]
	v_mfma_f32_16x16x32_bf16 v[68:71], v[214:217], v[206:209], v[68:71]
	v_mfma_f32_16x16x32_bf16 v[64:67], v[222:225], v[206:209], v[64:67]
	s_setprio 0
	s_mov_b32 m0, s31
	v_lshl_add_u64 v[226:227], s[38:39], 0, v[128:129]
	s_barrier
	ds_read_b128 v[178:181], v156 offset:16384
	ds_read_b128 v[182:185], v156 offset:17408
	ds_read_b128 v[186:189], v156 offset:18432
	ds_read_b128 v[190:193], v156 offset:19456
	ds_read_b128 v[194:197], v156 offset:20480
	ds_read_b128 v[198:201], v156 offset:21504
	ds_read_b128 v[202:205], v156 offset:22528
	ds_read_b128 v[206:209], v156 offset:23552
	global_load_lds_dwordx4 v[226:227], off
	v_lshl_add_u64 v[228:229], s[38:39], 0, v[132:133]
	s_mov_b32 m0, s56
	s_nop 0
	global_load_lds_dwordx4 v[228:229], off
	s_barrier
	s_waitcnt lgkmcnt(0)
	s_setprio 1
	s_waitcnt lgkmcnt(0)
	v_mfma_f32_16x16x32_bf16 v[60:63], v[146:149], v[178:181], v[60:63]
	v_mfma_f32_16x16x32_bf16 v[56:59], v[170:173], v[178:181], v[56:59]
	v_mfma_f32_16x16x32_bf16 v[44:47], v[146:149], v[186:189], v[44:47]
	v_mfma_f32_16x16x32_bf16 v[40:43], v[170:173], v[186:189], v[40:43]
	v_mfma_f32_16x16x32_bf16 v[28:31], v[146:149], v[194:197], v[28:31]
	v_mfma_f32_16x16x32_bf16 v[24:27], v[170:173], v[194:197], v[24:27]
	v_mfma_f32_16x16x32_bf16 v[12:15], v[146:149], v[202:205], v[12:15]
	v_mfma_f32_16x16x32_bf16 v[8:11], v[170:173], v[202:205], v[8:11]
	v_mfma_f32_16x16x32_bf16 v[60:63], v[160:163], v[182:185], v[60:63]
	v_mfma_f32_16x16x32_bf16 v[56:59], v[174:177], v[182:185], v[56:59]
	v_mfma_f32_16x16x32_bf16 v[44:47], v[160:163], v[190:193], v[44:47]
	v_mfma_f32_16x16x32_bf16 v[40:43], v[174:177], v[190:193], v[40:43]
	v_mfma_f32_16x16x32_bf16 v[28:31], v[160:163], v[198:201], v[28:31]
	v_mfma_f32_16x16x32_bf16 v[24:27], v[174:177], v[198:201], v[24:27]
	v_mfma_f32_16x16x32_bf16 v[12:15], v[160:163], v[206:209], v[12:15]
	v_mfma_f32_16x16x32_bf16 v[8:11], v[174:177], v[206:209], v[8:11]
	s_setprio 0
	s_barrier
; #define PG8_STAGE(bufoff, gbase, voff) do { _Pragma("unroll") for (int _i = 0; _i < 2; ++_i) \
;         __builtin_amdgcn_global_load_lds((const unsigned*)((const char*)(gbase) + (voff)[_i]), (LAS unsigned*)(lds + (bufoff) + ldsw + _i * 8192), 16, 0, 0); } while (0)
; #define PG8_LDA(dst, b, h) do { _Pragma("unroll") for (int m = 0; m < 4; ++m) _Pragma("unroll") for (int k = 0; k < 2; ++k) dst[m][k] = *(const LAS bf16x8*)(lds + PG8_SA(b, h) + aoff + m * 2048 + k * 1024); } while (0)
; #define PG8_LDB(dst, b, h) do { _Pragma("unroll") for (int n = 0; n < 2; ++n) _Pragma("unroll") for (int k = 0; k < 2; ++k) dst[n][k] = *(const LAS bf16x8*)(lds + PG8_SB(b, h) + boff + n * 2048 + k * 1024); } while (0)
; #define PG8_MMA(ai, bj, At, Bt) do { __builtin_amdgcn_s_setprio(1); _Pragma("unroll") for (int m = 0; m < 4; ++m) _Pragma("unroll") for (int n = 0; n < 2; ++n) _Pragma("unroll") for (int k = 0; k < 2; ++k) \
;         acc[ai][bj][m][n] = __builtin_amdgcn_mfma_f32_16x16x32_bf16(Bt[n][k], At[m][k], acc[ai][bj][m][n], 0, 0, 0); __builtin_amdgcn_s_setprio(0); } while (0)
; #define PG8_WAIT_V(n) asm volatile("s_waitcnt vmcnt(" #n ")" ::: "memory")
; #define PG8_WAIT_L(n) asm volatile("s_waitcnt lgkmcnt(" #n ")" ::: "memory")
; #define PG8_BAR __builtin_amdgcn_s_barrier()
; #define PG8_SCHED __builtin_amdgcn_sched_barrier(0)
;     ...
;             PG8_STAGE(PG8_SB(0, 1), b2 + hB, voffB);
;             PG8_WAIT_V(6); PG8_BAR; PG8_MMA(1, 1, At, B1); PG8_BAR;
;             PG8_LDB(B0, 1, 0); PG8_SCHED; PG8_LDA(At, 1, 0); PG8_STAGE(PG8_SA(0, 1), a2 + hA, voffA);
;             PG8_WAIT_L(8); PG8_BAR; PG8_WAIT_L(0); PG8_MMA(0, 0, At, B0); PG8_BAR; PG8_SCHED;
;             PG8_LDB(B1, 1, 1); PG8_STAGE(PG8_SB(1, 0), b3, voffB);
;             PG8_BAR; PG8_WAIT_L(0); PG8_MMA(0, 1, At, B1); PG8_BAR;
;             PG8_LDA(At, 1, 1); PG8_STAGE(PG8_SA(1, 0), a3, voffA);
	s_add_u32 s44, s36, 0x40000
	s_addc_u32 s45, s37, 0
	s_add_i32 s43, s64, s55
	v_lshl_add_u64 v[146:147], s[44:45], 0, v[130:131]
	s_mov_b32 m0, s43
	s_nop 0
	global_load_lds_dwordx4 v[146:147], off
	v_lshl_add_u64 v[146:147], s[44:45], 0, v[134:135]
	s_add_i32 m0, s43, 0x2000
	s_nop 0
	global_load_lds_dwordx4 v[146:147], off
	s_waitcnt vmcnt(6)
	s_barrier
	s_setprio 1
	v_mfma_f32_16x16x32_bf16 v[52:55], v[210:213], v[178:181], v[52:55]
	v_mfma_f32_16x16x32_bf16 v[48:51], v[218:221], v[178:181], v[48:51]
	v_mfma_f32_16x16x32_bf16 v[36:39], v[210:213], v[186:189], v[36:39]
	v_mfma_f32_16x16x32_bf16 v[32:35], v[218:221], v[186:189], v[32:35]
	v_mfma_f32_16x16x32_bf16 v[20:23], v[210:213], v[194:197], v[20:23]
	v_mfma_f32_16x16x32_bf16 v[16:19], v[218:221], v[194:197], v[16:19]
	v_mfma_f32_16x16x32_bf16 v[4:7], v[210:213], v[202:205], v[4:7]
	v_mfma_f32_16x16x32_bf16 v[0:3], v[218:221], v[202:205], v[0:3]
	v_mfma_f32_16x16x32_bf16 v[52:55], v[214:217], v[182:185], v[52:55]
	v_mfma_f32_16x16x32_bf16 v[48:51], v[222:225], v[182:185], v[48:51]
	v_mfma_f32_16x16x32_bf16 v[36:39], v[214:217], v[190:193], v[36:39]
	v_mfma_f32_16x16x32_bf16 v[32:35], v[222:225], v[190:193], v[32:35]
	v_mfma_f32_16x16x32_bf16 v[20:23], v[214:217], v[198:201], v[20:23]
	v_mfma_f32_16x16x32_bf16 v[16:19], v[222:225], v[198:201], v[16:19]
	v_mfma_f32_16x16x32_bf16 v[4:7], v[214:217], v[206:209], v[4:7]
	v_mfma_f32_16x16x32_bf16 v[0:3], v[222:225], v[206:209], v[0:3]
	s_setprio 0
	s_add_i32 s43, 0, 0x18000
	v_add_u32_e32 v159, s43, v153
	s_barrier
	ds_read_b128 v[146:149], v159
	ds_read_b128 v[160:163], v159 offset:1024
	ds_read_b128 v[170:173], v159 offset:2048
	ds_read_b128 v[174:177], v159 offset:3072
	s_add_u32 s38, s38, 0x40000
	s_addc_u32 s39, s39, 0
	s_mov_b32 m0, s57
	v_lshl_add_u64 v[210:211], s[38:39], 0, v[128:129]
	ds_read_b128 v[178:181], v156 offset:32768
	ds_read_b128 v[182:185], v156 offset:33792
	ds_read_b128 v[186:189], v156 offset:34816
	ds_read_b128 v[190:193], v156 offset:35840
	ds_read_b128 v[194:197], v156 offset:36864
	ds_read_b128 v[198:201], v156 offset:37888
	ds_read_b128 v[202:205], v156 offset:38912
	ds_read_b128 v[206:209], v156 offset:39936
	global_load_lds_dwordx4 v[210:211], off
	v_lshl_add_u64 v[210:211], s[38:39], 0, v[132:133]
	s_mov_b32 m0, s58
	s_nop 0
	global_load_lds_dwordx4 v[210:211], off
	s_waitcnt lgkmcnt(8)
	s_barrier
	s_waitcnt lgkmcnt(0)
	s_setprio 1
	s_waitcnt lgkmcnt(0)
	v_mfma_f32_16x16x32_bf16 v[124:127], v[146:149], v[178:181], v[124:127]
	v_mfma_f32_16x16x32_bf16 v[120:123], v[170:173], v[178:181], v[120:123]
	v_mfma_f32_16x16x32_bf16 v[108:111], v[146:149], v[186:189], v[108:111]
	v_mfma_f32_16x16x32_bf16 v[104:107], v[170:173], v[186:189], v[104:107]
	v_mfma_f32_16x16x32_bf16 v[92:95], v[146:149], v[194:197], v[92:95]
	v_mfma_f32_16x16x32_bf16 v[88:91], v[170:173], v[194:197], v[88:91]
	v_mfma_f32_16x16x32_bf16 v[76:79], v[146:149], v[202:205], v[76:79]
	v_mfma_f32_16x16x32_bf16 v[72:75], v[170:173], v[202:205], v[72:75]
	v_mfma_f32_16x16x32_bf16 v[124:127], v[160:163], v[182:185], v[124:127]
	v_mfma_f32_16x16x32_bf16 v[120:123], v[174:177], v[182:185], v[120:123]
	v_mfma_f32_16x16x32_bf16 v[108:111], v[160:163], v[190:193], v[108:111]
	v_mfma_f32_16x16x32_bf16 v[104:107], v[174:177], v[190:193], v[104:107]
	v_mfma_f32_16x16x32_bf16 v[92:95], v[160:163], v[198:201], v[92:95]
	v_mfma_f32_16x16x32_bf16 v[88:91], v[174:177], v[198:201], v[88:91]
	v_mfma_f32_16x16x32_bf16 v[76:79], v[160:163], v[206:209], v[76:79]
	v_mfma_f32_16x16x32_bf16 v[72:75], v[174:177], v[206:209], v[72:75]
	s_setprio 0
	s_barrier
	s_add_i32 s38, 0, 0x1c000
	s_add_i32 s39, s43, s55
	v_add_u32_e32 v159, s38, v153
	v_lshl_add_u64 v[150:151], v[150:151], 0, s[20:21]
	s_mov_b32 m0, s39
	ds_read_b128 v[210:213], v159
	ds_read_b128 v[214:217], v159 offset:1024
	ds_read_b128 v[218:221], v159 offset:2048
	ds_read_b128 v[222:225], v159 offset:3072
	global_load_lds_dwordx4 v[150:151], off
	v_lshl_add_u64 v[150:151], v[164:165], 0, s[20:21]
	s_add_i32 m0, s39, 0x2000
	s_nop 0
	global_load_lds_dwordx4 v[150:151], off
	s_barrier
	s_waitcnt lgkmcnt(0)
	s_setprio 1
	s_waitcnt lgkmcnt(0)
	v_mfma_f32_16x16x32_bf16 v[116:119], v[210:213], v[178:181], v[116:119]
	v_mfma_f32_16x16x32_bf16 v[112:115], v[218:221], v[178:181], v[112:115]
	v_mfma_f32_16x16x32_bf16 v[100:103], v[210:213], v[186:189], v[100:103]
	v_mfma_f32_16x16x32_bf16 v[96:99], v[218:221], v[186:189], v[96:99]
	v_mfma_f32_16x16x32_bf16 v[84:87], v[210:213], v[194:197], v[84:87]
	v_mfma_f32_16x16x32_bf16 v[80:83], v[218:221], v[194:197], v[80:83]
	v_mfma_f32_16x16x32_bf16 v[68:71], v[210:213], v[202:205], v[68:71]
	v_mfma_f32_16x16x32_bf16 v[64:67], v[218:221], v[202:205], v[64:67]
	v_mfma_f32_16x16x32_bf16 v[116:119], v[214:217], v[182:185], v[116:119]
	v_mfma_f32_16x16x32_bf16 v[112:115], v[222:225], v[182:185], v[112:115]
	v_mfma_f32_16x16x32_bf16 v[100:103], v[214:217], v[190:193], v[100:103]
	v_mfma_f32_16x16x32_bf16 v[96:99], v[222:225], v[190:193], v[96:99]
	v_mfma_f32_16x16x32_bf16 v[84:87], v[214:217], v[198:201], v[84:87]
	v_mfma_f32_16x16x32_bf16 v[80:83], v[222:225], v[198:201], v[80:83]
	v_mfma_f32_16x16x32_bf16 v[68:71], v[214:217], v[206:209], v[68:71]
	v_mfma_f32_16x16x32_bf16 v[64:67], v[222:225], v[206:209], v[64:67]
	s_setprio 0
	s_mov_b32 m0, s60
	v_lshl_add_u64 v[150:151], v[226:227], 0, s[20:21]
	s_barrier
	ds_read_b128 v[178:181], v156 offset:49152
	ds_read_b128 v[182:185], v156 offset:50176
	ds_read_b128 v[186:189], v156 offset:51200
	ds_read_b128 v[190:193], v156 offset:52224
	ds_read_b128 v[194:197], v156 offset:53248
	ds_read_b128 v[198:201], v156 offset:54272
	ds_read_b128 v[202:205], v156 offset:55296
	ds_read_b128 v[206:209], v156 offset:56320
	global_load_lds_dwordx4 v[150:151], off
	v_lshl_add_u64 v[150:151], v[228:229], 0, s[20:21]
	s_mov_b32 m0, s61
	s_nop 0
	global_load_lds_dwordx4 v[150:151], off
	s_barrier
; #define PG8_STAGE(bufoff, gbase, voff) do { _Pragma("unroll") for (int _i = 0; _i < 2; ++_i) \
;         __builtin_amdgcn_global_load_lds((const unsigned*)((const char*)(gbase) + (voff)[_i]), (LAS unsigned*)(lds + (bufoff) + ldsw + _i * 8192), 16, 0, 0); } while (0)
; #define PG8_LDA(dst, b, h) do { _Pragma("unroll") for (int m = 0; m < 4; ++m) _Pragma("unroll") for (int k = 0; k < 2; ++k) dst[m][k] = *(const LAS bf16x8*)(lds + PG8_SA(b, h) + aoff + m * 2048 + k * 1024); } while (0)
; #define PG8_MMA(ai, bj, At, Bt) do { __builtin_amdgcn_s_setprio(1); _Pragma("unroll") for (int m = 0; m < 4; ++m) _Pragma("unroll") for (int n = 0; n < 2; ++n) _Pragma("unroll") for (int k = 0; k < 2; ++k) \
;         acc[ai][bj][m][n] = __builtin_amdgcn_mfma_f32_16x16x32_bf16(Bt[n][k], At[m][k], acc[ai][bj][m][n], 0, 0, 0); __builtin_amdgcn_s_setprio(0); } while (0)
; #define PG8_WAIT_V(n) asm volatile("s_waitcnt vmcnt(" #n ")" ::: "memory")
; #define PG8_WAIT_L(n) asm volatile("s_waitcnt lgkmcnt(" #n ")" ::: "memory")
; #define PG8_BAR __builtin_amdgcn_s_barrier()
; #define PG8_SCHED __builtin_amdgcn_sched_barrier(0)
;     ...
;             PG8_LDA(At, 1, 1); PG8_STAGE(PG8_SA(1, 0), a3, voffA);
;             PG8_BAR; PG8_WAIT_L(0); PG8_MMA(1, 0, At, B0); PG8_BAR; PG8_SCHED;
;             PG8_STAGE(PG8_SB(1, 1), b3 + hB, voffB);
;             PG8_WAIT_V(6); PG8_BAR; PG8_MMA(1, 1, At, B1); PG8_BAR;
;         }
;         E(acc, cur, wr, wc, fr, fq);
; __device__ __forceinline__ float row_rstd(const float* ssq, int row) {
;     const f32x4* p = (const f32x4*)(ssq + (size_t)row * 16);
;     const f32x4 a = p[0], b = p[1], c = p[2], d = p[3];
;     const float s = ((a[0] + a[1]) + (a[2] + a[3])) + ((b[0] + b[1]) + (b[2] + b[3])) + ((c[0] + c[1]) + (c[2] + c[3])) + ((d[0] + d[1]) + (d[2] + d[3]));
;     return rsqrtf(s * (1.0f / 1024.0f) + 1e-6f);
	s_waitcnt lgkmcnt(0)
	s_setprio 1
	s_waitcnt lgkmcnt(0)
	v_mfma_f32_16x16x32_bf16 v[60:63], v[146:149], v[178:181], v[60:63]
	v_mfma_f32_16x16x32_bf16 v[56:59], v[170:173], v[178:181], v[56:59]
	v_mfma_f32_16x16x32_bf16 v[44:47], v[146:149], v[186:189], v[44:47]
	v_mfma_f32_16x16x32_bf16 v[40:43], v[170:173], v[186:189], v[40:43]
	v_mfma_f32_16x16x32_bf16 v[28:31], v[146:149], v[194:197], v[28:31]
	v_mfma_f32_16x16x32_bf16 v[24:27], v[170:173], v[194:197], v[24:27]
	v_mfma_f32_16x16x32_bf16 v[12:15], v[146:149], v[202:205], v[12:15]
	v_mfma_f32_16x16x32_bf16 v[8:11], v[170:173], v[202:205], v[8:11]
	v_mfma_f32_16x16x32_bf16 v[60:63], v[160:163], v[182:185], v[60:63]
	v_mfma_f32_16x16x32_bf16 v[56:59], v[174:177], v[182:185], v[56:59]
	v_mfma_f32_16x16x32_bf16 v[44:47], v[160:163], v[190:193], v[44:47]
	v_mfma_f32_16x16x32_bf16 v[40:43], v[174:177], v[190:193], v[40:43]
	v_mfma_f32_16x16x32_bf16 v[28:31], v[160:163], v[198:201], v[28:31]
	v_mfma_f32_16x16x32_bf16 v[24:27], v[174:177], v[198:201], v[24:27]
	v_mfma_f32_16x16x32_bf16 v[12:15], v[160:163], v[206:209], v[12:15]
	v_mfma_f32_16x16x32_bf16 v[8:11], v[174:177], v[206:209], v[8:11]
	s_setprio 0
	s_barrier
	s_add_u32 s36, s36, 0x40080
	s_addc_u32 s37, s37, 0
	s_add_i32 s38, s38, s55
	v_lshl_add_u64 v[146:147], s[36:37], 0, v[130:131]
	s_mov_b32 m0, s38
	s_nop 0
	global_load_lds_dwordx4 v[146:147], off
	v_lshl_add_u64 v[146:147], s[36:37], 0, v[134:135]
	s_add_i32 m0, s38, 0x2000
	s_nop 0
	global_load_lds_dwordx4 v[146:147], off
	s_waitcnt vmcnt(6)
	s_barrier
	s_setprio 1
	v_mfma_f32_16x16x32_bf16 v[52:55], v[210:213], v[178:181], v[52:55]
	v_mfma_f32_16x16x32_bf16 v[48:51], v[218:221], v[178:181], v[48:51]
	v_mfma_f32_16x16x32_bf16 v[36:39], v[210:213], v[186:189], v[36:39]
	v_mfma_f32_16x16x32_bf16 v[32:35], v[218:221], v[186:189], v[32:35]
	v_mfma_f32_16x16x32_bf16 v[20:23], v[210:213], v[194:197], v[20:23]
	v_mfma_f32_16x16x32_bf16 v[16:19], v[218:221], v[194:197], v[16:19]
	v_mfma_f32_16x16x32_bf16 v[4:7], v[210:213], v[202:205], v[4:7]
	v_mfma_f32_16x16x32_bf16 v[0:3], v[218:221], v[202:205], v[0:3]
	v_mfma_f32_16x16x32_bf16 v[52:55], v[214:217], v[182:185], v[52:55]
	v_mfma_f32_16x16x32_bf16 v[48:51], v[222:225], v[182:185], v[48:51]
	v_mfma_f32_16x16x32_bf16 v[36:39], v[214:217], v[190:193], v[36:39]
	v_mfma_f32_16x16x32_bf16 v[32:35], v[222:225], v[190:193], v[32:35]
	v_mfma_f32_16x16x32_bf16 v[20:23], v[214:217], v[198:201], v[20:23]
	v_mfma_f32_16x16x32_bf16 v[16:19], v[222:225], v[198:201], v[16:19]
	v_mfma_f32_16x16x32_bf16 v[4:7], v[214:217], v[206:209], v[4:7]
	v_mfma_f32_16x16x32_bf16 v[0:3], v[222:225], v[206:209], v[0:3]
	s_setprio 0
	s_add_i32 s42, s42, 2
	s_add_u32 s25, s25, 0x100
	s_addc_u32 s33, s33, 0
	s_add_u32 s34, s34, 0x100
	s_addc_u32 s35, s35, 0
	s_cmp_gt_u32 s42, 13
	s_barrier
	s_cbranch_scc0 .LBB0_1288
	v_lshl_add_u32 v150, s30, 8, v152
	v_ashrrev_i32_e32 v151, 31, v150
	v_lshlrev_b64 v[146:147], 6, v[150:151]
	v_lshl_add_u64 v[146:147], s[18:19], 0, v[146:147]
	v_subrev_u32_e32 v186, s18, v146
	v_add_u32_e32 v187, 0x0, v186
	global_load_dwordx4 v[188:191], v187, s[18:19]
	v_add_u32_e32 v187, 0x10, v186
	global_load_dwordx4 v[192:195], v187, s[18:19]
	v_add_u32_e32 v187, 0x20, v186
	global_load_dwordx4 v[196:199], v187, s[18:19]
	v_add_u32_e32 v187, 0x30, v186
	global_load_dwordx4 v[200:203], v187, s[18:19]
	v_add_u32_e32 v187, 0x400, v186
	global_load_dwordx4 v[204:207], v187, s[18:19]
	v_add_u32_e32 v187, 0x410, v186
	global_load_dwordx4 v[208:211], v187, s[18:19]
	v_add_u32_e32 v187, 0x420, v186
	global_load_dwordx4 v[212:215], v187, s[18:19]
	v_add_u32_e32 v187, 0x430, v186
	global_load_dwordx4 v[216:219], v187, s[18:19]
	v_add_u32_e32 v187, 0x800, v186
	global_load_dwordx4 v[220:223], v187, s[18:19]
	v_add_u32_e32 v187, 0x810, v186
	global_load_dwordx4 v[232:235], v187, s[18:19]
	v_add_u32_e32 v187, 0x820, v186
	global_load_dwordx4 v[236:239], v187, s[18:19]
	v_add_u32_e32 v187, 0x830, v186
	global_load_dwordx4 v[240:243], v187, s[18:19]
	v_lshl_or_b32 v148, s6, 8, v154
	v_mov_b64_e32 v[146:147], s[16:17]
	v_ashrrev_i32_e32 v149, 31, v148
	v_mad_i64_i32 v[164:165], s[6:7], v150, s66, v[146:147]
	v_or_b32_e32 v182, 16, v150
	v_lshlrev_b64 v[148:149], 1, v[148:149]
	v_ashrrev_i32_e32 v183, 31, v182
	s_mov_b32 s30, s24
	s_mov_b64 s[34:35], s[28:29]
	s_mov_b64 s[36:37], s[26:27]
	s_waitcnt vmcnt(8)
; __device__ __forceinline__ u32x4 pack8(const f32x4 v0, const f32x4 v1) { u32x4 w; w.x = pk2(v0[0], v0[1]); w.y = pk2(v0[2], v0[3]); w.z = pk2(v1[0], v1[1]); w.w = pk2(v1[2], v1[3]); return w; }
; __device__ __forceinline__ float row_rstd(const float* ssq, int row) {
;     const f32x4* p = (const f32x4*)(ssq + (size_t)row * 16);
;     const f32x4 a = p[0], b = p[1], c = p[2], d = p[3];
;     const float s = ((a[0] + a[1]) + (a[2] + a[3])) + ((b[0] + b[1]) + (b[2] + b[3])) + ((c[0] + c[1]) + (c[2] + c[3])) + ((d[0] + d[1]) + (d[2] + d[3]));
;     return rsqrtf(s * (1.0f / 1024.0f) + 1e-6f);
;     __device__ __forceinline__ void operator()(const f32x4 (&acc)[2][2][4][2], const Unit& u, int wr, int wc, int fr, int fq) const {
;         const int row0 = u.pm * 256 + wr * 64 + fr, col0 = u.pn * 256 + wc * 32 + 8 * fq;
; #pragma unroll
;         for (int ai = 0; ai < 2; ++ai)
; #pragma unroll
;             for (int m = 0; m < 4; ++m) {
;                 const int row = row0 + ai * 128 + m * 16; const float rs = row_rstd(ssq, row);
;                 bf16_t* rowp = O + (size_t)row * ldc + col0;
; #pragma unroll
;                 for (int bj = 0; bj < 2; ++bj) { f32x4 v0 = acc[ai][bj][m][0] * rs, v1 = acc[ai][bj][m][1] * rs;
;                     if (ACT == 1) {
; #pragma unroll
;                         for (int j = 0; j < 4; ++j) { const float a = fmaxf(v0[j], 0.f), b = fmaxf(v1[j], 0.f); v0[j] = a * a; v1[j] = b * b; } }
;                     *(u32x4*)(rowp + bj * 128) = pack8(v0, v1); }
	v_mov_b32_e32 v160, v188
	v_mov_b32_e32 v161, v189
	v_mov_b32_e32 v162, v190
	v_mov_b32_e32 v163, v191
	v_mov_b32_e32 v170, v192
	v_mov_b32_e32 v171, v193
	v_mov_b32_e32 v172, v194
	v_mov_b32_e32 v173, v195
	v_mov_b32_e32 v174, v196
	v_mov_b32_e32 v175, v197
	v_mov_b32_e32 v176, v198
	v_mov_b32_e32 v177, v199
	v_mov_b32_e32 v178, v200
	v_mov_b32_e32 v179, v201
	v_mov_b32_e32 v180, v202
	v_mov_b32_e32 v181, v203
	v_add_u32_e32 v187, 0xc00, v186
	global_load_dwordx4 v[188:191], v187, s[18:19]
	v_add_u32_e32 v187, 0xc10, v186
	global_load_dwordx4 v[192:195], v187, s[18:19]
	v_add_u32_e32 v187, 0xc20, v186
	global_load_dwordx4 v[196:199], v187, s[18:19]
	v_add_u32_e32 v187, 0xc30, v186
	global_load_dwordx4 v[200:203], v187, s[18:19]
	v_mov_b32_e32 v184, v161
	v_mov_b32_e32 v185, v162
	v_mov_b32_e32 v161, v163
	v_mov_b32_e32 v162, v171
	v_mov_b32_e32 v163, v172
	v_mov_b32_e32 v171, v173
	v_pk_add_f32 v[160:161], v[184:185], v[160:161]
	v_pk_add_f32 v[162:163], v[162:163], v[170:171]
	v_pk_add_f32 v[160:161], v[160:161], v[160:161] op_sel:[0,1] op_sel_hi:[1,0]
	v_pk_add_f32 v[162:163], v[162:163], v[162:163] op_sel:[0,1] op_sel_hi:[1,0]
	v_add_f32_e32 v172, v174, v175
	v_add_f32_e32 v174, v176, v177
	v_mov_b32_e32 v173, v180
	v_mov_b32_e32 v175, v181
	v_mov_b32_e32 v161, v178
	v_mov_b32_e32 v163, v179
	v_pk_add_f32 v[170:171], v[172:173], v[174:175]
	v_pk_add_f32 v[160:161], v[160:161], v[162:163]
	v_lshlrev_b64 v[162:163], 6, v[182:183]
	v_pk_add_f32 v[160:161], v[160:161], v[170:171]
	v_lshl_add_u64 v[162:163], s[18:19], 0, v[162:163]
	v_add_f32_e32 v151, v160, v161
	v_fmamk_f32 v151, v151, 0x3a800000, v158
	v_mul_f32_e32 v159, 0x4b800000, v151
	v_cmp_gt_f32_e32 vcc, s65, v151
	v_lshl_add_u64 v[160:161], v[164:165], 0, v[148:149]
	s_nop 0
	v_cndmask_b32_e32 v151, v151, v159, vcc
	v_rsq_f32_e32 v151, v151
	s_nop 0
	v_mul_f32_e32 v159, 0x45800000, v151
	v_cndmask_b32_e32 v164, v151, v159, vcc
	v_pk_mul_f32 v[126:127], v[126:127], v[164:165] op_sel_hi:[1,0]
	v_pk_mul_f32 v[124:125], v[124:125], v[164:165] op_sel_hi:[1,0]
	v_pk_mul_f32 v[122:123], v[122:123], v[164:165] op_sel_hi:[1,0]
	v_pk_mul_f32 v[120:121], v[120:121], v[164:165] op_sel_hi:[1,0]
	v_pk_mul_f32 v[118:119], v[118:119], v[164:165] op_sel_hi:[1,0]
	v_pk_mul_f32 v[116:117], v[116:117], v[164:165] op_sel_hi:[1,0]
	v_pk_mul_f32 v[170:171], v[114:115], v[164:165] op_sel_hi:[1,0]
	v_pk_mul_f32 v[164:165], v[112:113], v[164:165] op_sel_hi:[1,0]
	v_cvt_pk_bf16_f32 v112, v124, v125
	v_cvt_pk_bf16_f32 v113, v126, v127
	v_cvt_pk_bf16_f32 v114, v120, v121
	v_cvt_pk_bf16_f32 v115, v122, v123
	global_store_dwordx4 v[160:161], v[112:115], off
	s_nop 1
	v_cvt_pk_bf16_f32 v112, v116, v117
	v_cvt_pk_bf16_f32 v113, v118, v119
	v_cvt_pk_bf16_f32 v114, v164, v165
	v_cvt_pk_bf16_f32 v115, v170, v171
	global_store_dwordx4 v[160:161], v[112:115], off offset:256
	s_nop 0
	v_or_b32_e32 v160, 32, v150
	v_mad_i64_i32 v[162:163], s[6:7], v182, s66, v[146:147]
	v_ashrrev_i32_e32 v161, 31, v160
	s_waitcnt vmcnt(10)
	v_mov_b32_e32 v112, v204
	v_mov_b32_e32 v113, v205
	v_mov_b32_e32 v114, v206
	v_mov_b32_e32 v115, v207
	v_mov_b32_e32 v116, v208
	v_mov_b32_e32 v117, v209
	v_mov_b32_e32 v118, v210
	v_mov_b32_e32 v119, v211
	v_mov_b32_e32 v120, v212
	v_mov_b32_e32 v121, v213
	v_mov_b32_e32 v122, v214
	v_mov_b32_e32 v123, v215
	v_mov_b32_e32 v124, v216
	v_mov_b32_e32 v125, v217
	v_mov_b32_e32 v126, v218
	v_mov_b32_e32 v127, v219
	v_add_u32_e32 v187, 0x2000, v186
	global_load_dwordx4 v[204:207], v187, s[18:19]
	v_add_u32_e32 v187, 0x2010, v186
	global_load_dwordx4 v[208:211], v187, s[18:19]
	v_add_u32_e32 v187, 0x2020, v186
	global_load_dwordx4 v[212:215], v187, s[18:19]
	v_add_u32_e32 v187, 0x2030, v186
	global_load_dwordx4 v[216:219], v187, s[18:19]
	v_mov_b32_e32 v164, v113
	v_mov_b32_e32 v165, v114
	v_mov_b32_e32 v113, v115
	v_mov_b32_e32 v114, v117
	v_mov_b32_e32 v115, v118
	v_mov_b32_e32 v117, v119
	v_pk_add_f32 v[112:113], v[164:165], v[112:113]
	v_pk_add_f32 v[114:115], v[114:115], v[116:117]
	v_pk_add_f32 v[112:113], v[112:113], v[112:113] op_sel:[0,1] op_sel_hi:[1,0]
	v_pk_add_f32 v[114:115], v[114:115], v[114:115] op_sel:[0,1] op_sel_hi:[1,0]
	v_add_f32_e32 v118, v120, v121
	v_add_f32_e32 v120, v122, v123
	v_mov_b32_e32 v119, v126
	v_mov_b32_e32 v121, v127
	v_mov_b32_e32 v113, v124
	v_mov_b32_e32 v115, v125
	v_pk_add_f32 v[116:117], v[118:119], v[120:121]
	v_pk_add_f32 v[112:113], v[112:113], v[114:115]
	v_lshlrev_b64 v[114:115], 6, v[160:161]
	v_pk_add_f32 v[112:113], v[112:113], v[116:117]
	v_lshl_add_u64 v[114:115], s[18:19], 0, v[114:115]
	v_add_f32_e32 v112, v112, v113
	v_fmamk_f32 v112, v112, 0x3a800000, v158
	v_mul_f32_e32 v113, 0x4b800000, v112
	v_cmp_gt_f32_e32 vcc, s65, v112
	s_nop 1
	v_cndmask_b32_e32 v112, v112, v113, vcc
	v_rsq_f32_e32 v116, v112
	v_lshl_add_u64 v[112:113], v[162:163], 0, v[148:149]
	v_mul_f32_e32 v117, 0x45800000, v116
	v_cndmask_b32_e32 v116, v116, v117, vcc
	v_pk_mul_f32 v[110:111], v[110:111], v[116:117] op_sel_hi:[1,0]
	v_pk_mul_f32 v[108:109], v[108:109], v[116:117] op_sel_hi:[1,0]
	v_pk_mul_f32 v[106:107], v[106:107], v[116:117] op_sel_hi:[1,0]
	v_pk_mul_f32 v[104:105], v[104:105], v[116:117] op_sel_hi:[1,0]
	v_pk_mul_f32 v[102:103], v[102:103], v[116:117] op_sel_hi:[1,0]
	v_pk_mul_f32 v[100:101], v[100:101], v[116:117] op_sel_hi:[1,0]
	v_pk_mul_f32 v[118:119], v[98:99], v[116:117] op_sel_hi:[1,0]
	v_pk_mul_f32 v[116:117], v[96:97], v[116:117] op_sel_hi:[1,0]
	v_cvt_pk_bf16_f32 v96, v108, v109
	v_cvt_pk_bf16_f32 v97, v110, v111
	v_cvt_pk_bf16_f32 v98, v104, v105
	v_cvt_pk_bf16_f32 v99, v106, v107
	global_store_dwordx4 v[112:113], v[96:99], off
	s_nop 1
	v_cvt_pk_bf16_f32 v96, v100, v101
	v_cvt_pk_bf16_f32 v97, v102, v103
	v_cvt_pk_bf16_f32 v98, v116, v117
	v_cvt_pk_bf16_f32 v99, v118, v119
	global_store_dwordx4 v[112:113], v[96:99], off offset:256
	s_nop 0
	v_or_b32_e32 v112, 48, v150
	v_mad_i64_i32 v[114:115], s[6:7], v160, s66, v[146:147]
	v_ashrrev_i32_e32 v113, 31, v112
	s_waitcnt vmcnt(12)
; __device__ __forceinline__ u32x4 pack8(const f32x4 v0, const f32x4 v1) { u32x4 w; w.x = pk2(v0[0], v0[1]); w.y = pk2(v0[2], v0[3]); w.z = pk2(v1[0], v1[1]); w.w = pk2(v1[2], v1[3]); return w; }
; __device__ __forceinline__ float row_rstd(const float* ssq, int row) {
;     const f32x4* p = (const f32x4*)(ssq + (size_t)row * 16);
;     const f32x4 a = p[0], b = p[1], c = p[2], d = p[3];
;     const float s = ((a[0] + a[1]) + (a[2] + a[3])) + ((b[0] + b[1]) + (b[2] + b[3])) + ((c[0] + c[1]) + (c[2] + c[3])) + ((d[0] + d[1]) + (d[2] + d[3]));
;     return rsqrtf(s * (1.0f / 1024.0f) + 1e-6f);
;     __device__ __forceinline__ void operator()(const f32x4 (&acc)[2][2][4][2], const Unit& u, int wr, int wc, int fr, int fq) const {
;         const int row0 = u.pm * 256 + wr * 64 + fr, col0 = u.pn * 256 + wc * 32 + 8 * fq;
; #pragma unroll
;         for (int ai = 0; ai < 2; ++ai)
; #pragma unroll
;             for (int m = 0; m < 4; ++m) {
;                 const int row = row0 + ai * 128 + m * 16; const float rs = row_rstd(ssq, row);
;                 bf16_t* rowp = O + (size_t)row * ldc + col0;
; #pragma unroll
;                 for (int bj = 0; bj < 2; ++bj) { f32x4 v0 = acc[ai][bj][m][0] * rs, v1 = acc[ai][bj][m][1] * rs;
;                     if (ACT == 1) {
; #pragma unroll
;                         for (int j = 0; j < 4; ++j) { const float a = fmaxf(v0[j], 0.f), b = fmaxf(v1[j], 0.f); v0[j] = a * a; v1[j] = b * b; } }
;                     *(u32x4*)(rowp + bj * 128) = pack8(v0, v1); }
	v_mov_b32_e32 v96, v220
	v_mov_b32_e32 v97, v221
	v_mov_b32_e32 v98, v222
	v_mov_b32_e32 v99, v223
	v_mov_b32_e32 v100, v232
	v_mov_b32_e32 v101, v233
	v_mov_b32_e32 v102, v234
	v_mov_b32_e32 v103, v235
	v_mov_b32_e32 v104, v236
	v_mov_b32_e32 v105, v237
	v_mov_b32_e32 v106, v238
	v_mov_b32_e32 v107, v239
	v_mov_b32_e32 v108, v240
	v_mov_b32_e32 v109, v241
	v_mov_b32_e32 v110, v242
	v_mov_b32_e32 v111, v243
	v_add_u32_e32 v187, 0x2400, v186
	global_load_dwordx4 v[220:223], v187, s[18:19]
	v_add_u32_e32 v187, 0x2410, v186
	global_load_dwordx4 v[232:235], v187, s[18:19]
	v_add_u32_e32 v187, 0x2420, v186
	global_load_dwordx4 v[236:239], v187, s[18:19]
	v_add_u32_e32 v187, 0x2430, v186
	global_load_dwordx4 v[240:243], v187, s[18:19]
	v_mov_b32_e32 v116, v97
	v_mov_b32_e32 v117, v98
	v_mov_b32_e32 v97, v99
	v_mov_b32_e32 v98, v101
	v_mov_b32_e32 v99, v102
	v_mov_b32_e32 v101, v103
	v_pk_add_f32 v[96:97], v[116:117], v[96:97]
	v_pk_add_f32 v[98:99], v[98:99], v[100:101]
	v_pk_add_f32 v[96:97], v[96:97], v[96:97] op_sel:[0,1] op_sel_hi:[1,0]
	v_pk_add_f32 v[98:99], v[98:99], v[98:99] op_sel:[0,1] op_sel_hi:[1,0]
	v_add_f32_e32 v102, v104, v105
	v_add_f32_e32 v104, v106, v107
	v_mov_b32_e32 v103, v110
	v_mov_b32_e32 v105, v111
	v_mov_b32_e32 v97, v108
	v_mov_b32_e32 v99, v109
	v_pk_add_f32 v[100:101], v[102:103], v[104:105]
	v_pk_add_f32 v[96:97], v[96:97], v[98:99]
	v_lshlrev_b64 v[98:99], 6, v[112:113]
	v_pk_add_f32 v[96:97], v[96:97], v[100:101]
	v_lshl_add_u64 v[98:99], s[18:19], 0, v[98:99]
	v_add_f32_e32 v96, v96, v97
	v_fmamk_f32 v96, v96, 0x3a800000, v158
	v_mul_f32_e32 v97, 0x4b800000, v96
	v_cmp_gt_f32_e32 vcc, s65, v96
	s_nop 1
	v_cndmask_b32_e32 v96, v96, v97, vcc
	v_rsq_f32_e32 v100, v96
	v_lshl_add_u64 v[96:97], v[114:115], 0, v[148:149]
	v_mul_f32_e32 v101, 0x45800000, v100
	v_cndmask_b32_e32 v100, v100, v101, vcc
	v_pk_mul_f32 v[94:95], v[94:95], v[100:101] op_sel_hi:[1,0]
	v_pk_mul_f32 v[92:93], v[92:93], v[100:101] op_sel_hi:[1,0]
	v_pk_mul_f32 v[90:91], v[90:91], v[100:101] op_sel_hi:[1,0]
	v_pk_mul_f32 v[88:89], v[88:89], v[100:101] op_sel_hi:[1,0]
	v_pk_mul_f32 v[86:87], v[86:87], v[100:101] op_sel_hi:[1,0]
	v_pk_mul_f32 v[84:85], v[84:85], v[100:101] op_sel_hi:[1,0]
	v_pk_mul_f32 v[102:103], v[82:83], v[100:101] op_sel_hi:[1,0]
	v_pk_mul_f32 v[100:101], v[80:81], v[100:101] op_sel_hi:[1,0]
	v_cvt_pk_bf16_f32 v80, v92, v93
	v_cvt_pk_bf16_f32 v81, v94, v95
	v_cvt_pk_bf16_f32 v82, v88, v89
	v_cvt_pk_bf16_f32 v83, v90, v91
	global_store_dwordx4 v[96:97], v[80:83], off
	s_nop 1
	v_cvt_pk_bf16_f32 v80, v84, v85
	v_cvt_pk_bf16_f32 v81, v86, v87
	v_cvt_pk_bf16_f32 v82, v100, v101
	v_cvt_pk_bf16_f32 v83, v102, v103
	global_store_dwordx4 v[96:97], v[80:83], off offset:256
	s_nop 0
	v_add_u32_e32 v96, 0x80, v150
	v_mad_i64_i32 v[98:99], s[6:7], v112, s66, v[146:147]
	v_ashrrev_i32_e32 v97, 31, v96
	s_waitcnt vmcnt(14)
	v_mov_b32_e32 v80, v188
	v_mov_b32_e32 v81, v189
	v_mov_b32_e32 v82, v190
	v_mov_b32_e32 v83, v191
	v_mov_b32_e32 v84, v192
	v_mov_b32_e32 v85, v193
	v_mov_b32_e32 v86, v194
	v_mov_b32_e32 v87, v195
	v_mov_b32_e32 v88, v196
	v_mov_b32_e32 v89, v197
	v_mov_b32_e32 v90, v198
	v_mov_b32_e32 v91, v199
	v_mov_b32_e32 v92, v200
	v_mov_b32_e32 v93, v201
	v_mov_b32_e32 v94, v202
	v_mov_b32_e32 v95, v203
	v_add_u32_e32 v187, 0x2800, v186
	global_load_dwordx4 v[188:191], v187, s[18:19]
	v_add_u32_e32 v187, 0x2810, v186
	global_load_dwordx4 v[192:195], v187, s[18:19]
	v_add_u32_e32 v187, 0x2820, v186
	global_load_dwordx4 v[196:199], v187, s[18:19]
	v_add_u32_e32 v187, 0x2830, v186
	global_load_dwordx4 v[200:203], v187, s[18:19]
	v_mov_b32_e32 v100, v81
	v_mov_b32_e32 v101, v82
	v_mov_b32_e32 v81, v83
	v_mov_b32_e32 v82, v85
	v_mov_b32_e32 v83, v86
	v_mov_b32_e32 v85, v87
	v_pk_add_f32 v[80:81], v[100:101], v[80:81]
	v_pk_add_f32 v[82:83], v[82:83], v[84:85]
	v_pk_add_f32 v[80:81], v[80:81], v[80:81] op_sel:[0,1] op_sel_hi:[1,0]
	v_pk_add_f32 v[82:83], v[82:83], v[82:83] op_sel:[0,1] op_sel_hi:[1,0]
	v_add_f32_e32 v86, v88, v89
	v_add_f32_e32 v88, v90, v91
	v_mov_b32_e32 v87, v94
	v_mov_b32_e32 v89, v95
	v_mov_b32_e32 v81, v92
	v_mov_b32_e32 v83, v93
	v_pk_add_f32 v[84:85], v[86:87], v[88:89]
	v_pk_add_f32 v[80:81], v[80:81], v[82:83]
	v_lshlrev_b64 v[82:83], 6, v[96:97]
	v_pk_add_f32 v[80:81], v[80:81], v[84:85]
	v_lshl_add_u64 v[82:83], s[18:19], 0, v[82:83]
	v_add_f32_e32 v80, v80, v81
	v_fmamk_f32 v80, v80, 0x3a800000, v158
	v_mul_f32_e32 v81, 0x4b800000, v80
	v_cmp_gt_f32_e32 vcc, s65, v80
	s_nop 1
	v_cndmask_b32_e32 v80, v80, v81, vcc
	v_rsq_f32_e32 v84, v80
	v_lshl_add_u64 v[80:81], v[98:99], 0, v[148:149]
	v_mul_f32_e32 v85, 0x45800000, v84
	v_cndmask_b32_e32 v84, v84, v85, vcc
	v_pk_mul_f32 v[78:79], v[78:79], v[84:85] op_sel_hi:[1,0]
	v_pk_mul_f32 v[76:77], v[76:77], v[84:85] op_sel_hi:[1,0]
	v_pk_mul_f32 v[74:75], v[74:75], v[84:85] op_sel_hi:[1,0]
	v_pk_mul_f32 v[72:73], v[72:73], v[84:85] op_sel_hi:[1,0]
	v_pk_mul_f32 v[70:71], v[70:71], v[84:85] op_sel_hi:[1,0]
	v_pk_mul_f32 v[68:69], v[68:69], v[84:85] op_sel_hi:[1,0]
	v_pk_mul_f32 v[86:87], v[66:67], v[84:85] op_sel_hi:[1,0]
	v_pk_mul_f32 v[84:85], v[64:65], v[84:85] op_sel_hi:[1,0]
	v_cvt_pk_bf16_f32 v64, v76, v77
	v_cvt_pk_bf16_f32 v65, v78, v79
	v_cvt_pk_bf16_f32 v66, v72, v73
	v_cvt_pk_bf16_f32 v67, v74, v75
	global_store_dwordx4 v[80:81], v[64:67], off
	s_nop 1
	v_cvt_pk_bf16_f32 v64, v68, v69
	v_cvt_pk_bf16_f32 v65, v70, v71
	v_cvt_pk_bf16_f32 v66, v84, v85
	v_cvt_pk_bf16_f32 v67, v86, v87
	global_store_dwordx4 v[80:81], v[64:67], off offset:256
	s_nop 0
	v_add_u32_e32 v80, 0x90, v150
	v_mad_i64_i32 v[82:83], s[6:7], v96, s66, v[146:147]
	v_ashrrev_i32_e32 v81, 31, v80
	s_waitcnt vmcnt(14)
; __device__ __forceinline__ u32x4 pack8(const f32x4 v0, const f32x4 v1) { u32x4 w; w.x = pk2(v0[0], v0[1]); w.y = pk2(v0[2], v0[3]); w.z = pk2(v1[0], v1[1]); w.w = pk2(v1[2], v1[3]); return w; }
; __device__ __forceinline__ float row_rstd(const float* ssq, int row) {
;     const f32x4* p = (const f32x4*)(ssq + (size_t)row * 16);
;     const f32x4 a = p[0], b = p[1], c = p[2], d = p[3];
;     const float s = ((a[0] + a[1]) + (a[2] + a[3])) + ((b[0] + b[1]) + (b[2] + b[3])) + ((c[0] + c[1]) + (c[2] + c[3])) + ((d[0] + d[1]) + (d[2] + d[3]));
;     return rsqrtf(s * (1.0f / 1024.0f) + 1e-6f);
;     __device__ __forceinline__ void operator()(const f32x4 (&acc)[2][2][4][2], const Unit& u, int wr, int wc, int fr, int fq) const {
;         const int row0 = u.pm * 256 + wr * 64 + fr, col0 = u.pn * 256 + wc * 32 + 8 * fq;
; #pragma unroll
;         for (int ai = 0; ai < 2; ++ai)
; #pragma unroll
;             for (int m = 0; m < 4; ++m) {
;                 const int row = row0 + ai * 128 + m * 16; const float rs = row_rstd(ssq, row);
;                 bf16_t* rowp = O + (size_t)row * ldc + col0;
; #pragma unroll
;                 for (int bj = 0; bj < 2; ++bj) { f32x4 v0 = acc[ai][bj][m][0] * rs, v1 = acc[ai][bj][m][1] * rs;
;                     if (ACT == 1) {
; #pragma unroll
;                         for (int j = 0; j < 4; ++j) { const float a = fmaxf(v0[j], 0.f), b = fmaxf(v1[j], 0.f); v0[j] = a * a; v1[j] = b * b; } }
;                     *(u32x4*)(rowp + bj * 128) = pack8(v0, v1); }
	v_mov_b32_e32 v64, v204
	v_mov_b32_e32 v65, v205
	v_mov_b32_e32 v66, v206
	v_mov_b32_e32 v67, v207
	v_mov_b32_e32 v68, v208
	v_mov_b32_e32 v69, v209
	v_mov_b32_e32 v70, v210
	v_mov_b32_e32 v71, v211
	v_mov_b32_e32 v72, v212
	v_mov_b32_e32 v73, v213
	v_mov_b32_e32 v74, v214
	v_mov_b32_e32 v75, v215
	v_mov_b32_e32 v76, v216
	v_mov_b32_e32 v77, v217
	v_mov_b32_e32 v78, v218
	v_mov_b32_e32 v79, v219
	v_add_u32_e32 v187, 0x2c00, v186
	global_load_dwordx4 v[204:207], v187, s[18:19]
	v_add_u32_e32 v187, 0x2c10, v186
	global_load_dwordx4 v[208:211], v187, s[18:19]
	v_add_u32_e32 v187, 0x2c20, v186
	global_load_dwordx4 v[212:215], v187, s[18:19]
	v_add_u32_e32 v187, 0x2c30, v186
	global_load_dwordx4 v[216:219], v187, s[18:19]
	v_mov_b32_e32 v84, v65
	v_mov_b32_e32 v85, v66
	v_mov_b32_e32 v65, v67
	v_mov_b32_e32 v66, v69
	v_mov_b32_e32 v67, v70
	v_mov_b32_e32 v69, v71
	v_pk_add_f32 v[64:65], v[84:85], v[64:65]
	v_pk_add_f32 v[66:67], v[66:67], v[68:69]
	v_pk_add_f32 v[64:65], v[64:65], v[64:65] op_sel:[0,1] op_sel_hi:[1,0]
	v_pk_add_f32 v[66:67], v[66:67], v[66:67] op_sel:[0,1] op_sel_hi:[1,0]
	v_add_f32_e32 v70, v72, v73
	v_add_f32_e32 v72, v74, v75
	v_mov_b32_e32 v71, v78
	v_mov_b32_e32 v73, v79
	v_mov_b32_e32 v65, v76
	v_mov_b32_e32 v67, v77
	v_pk_add_f32 v[68:69], v[70:71], v[72:73]
	v_pk_add_f32 v[64:65], v[64:65], v[66:67]
	v_lshlrev_b64 v[66:67], 6, v[80:81]
	v_pk_add_f32 v[64:65], v[64:65], v[68:69]
	v_lshl_add_u64 v[66:67], s[18:19], 0, v[66:67]
	v_add_f32_e32 v64, v64, v65
	v_fmamk_f32 v64, v64, 0x3a800000, v158
	v_mul_f32_e32 v65, 0x4b800000, v64
	v_cmp_gt_f32_e32 vcc, s65, v64
	s_nop 1
	v_cndmask_b32_e32 v64, v64, v65, vcc
	v_rsq_f32_e32 v68, v64
	v_lshl_add_u64 v[64:65], v[82:83], 0, v[148:149]
	v_mul_f32_e32 v69, 0x45800000, v68
	v_cndmask_b32_e32 v68, v68, v69, vcc
	v_pk_mul_f32 v[62:63], v[62:63], v[68:69] op_sel_hi:[1,0]
	v_pk_mul_f32 v[60:61], v[60:61], v[68:69] op_sel_hi:[1,0]
	v_pk_mul_f32 v[58:59], v[58:59], v[68:69] op_sel_hi:[1,0]
	v_pk_mul_f32 v[56:57], v[56:57], v[68:69] op_sel_hi:[1,0]
	v_pk_mul_f32 v[54:55], v[54:55], v[68:69] op_sel_hi:[1,0]
	v_pk_mul_f32 v[52:53], v[52:53], v[68:69] op_sel_hi:[1,0]
	v_pk_mul_f32 v[70:71], v[50:51], v[68:69] op_sel_hi:[1,0]
	v_pk_mul_f32 v[68:69], v[48:49], v[68:69] op_sel_hi:[1,0]
	v_cvt_pk_bf16_f32 v48, v60, v61
	v_cvt_pk_bf16_f32 v49, v62, v63
	v_cvt_pk_bf16_f32 v50, v56, v57
	v_cvt_pk_bf16_f32 v51, v58, v59
	global_store_dwordx4 v[64:65], v[48:51], off
	s_nop 1
	v_cvt_pk_bf16_f32 v48, v52, v53
	v_cvt_pk_bf16_f32 v49, v54, v55
	v_cvt_pk_bf16_f32 v50, v68, v69
	v_cvt_pk_bf16_f32 v51, v70, v71
	global_store_dwordx4 v[64:65], v[48:51], off offset:256
	s_nop 0
	v_add_u32_e32 v64, 0xa0, v150
	v_mad_i64_i32 v[66:67], s[6:7], v80, s66, v[146:147]
	v_ashrrev_i32_e32 v65, 31, v64
	s_waitcnt vmcnt(14)
	v_mov_b32_e32 v48, v220
	v_mov_b32_e32 v49, v221
	v_mov_b32_e32 v50, v222
	v_mov_b32_e32 v51, v223
	v_mov_b32_e32 v52, v232
	v_mov_b32_e32 v53, v233
	v_mov_b32_e32 v54, v234
	v_mov_b32_e32 v55, v235
	v_mov_b32_e32 v56, v236
	v_mov_b32_e32 v57, v237
	v_mov_b32_e32 v58, v238
	v_mov_b32_e32 v59, v239
	v_mov_b32_e32 v60, v240
	v_mov_b32_e32 v61, v241
	v_mov_b32_e32 v62, v242
	v_mov_b32_e32 v63, v243
	v_mov_b32_e32 v68, v49
	v_mov_b32_e32 v69, v50
	v_mov_b32_e32 v49, v51
	v_mov_b32_e32 v50, v53
	v_mov_b32_e32 v51, v54
	v_mov_b32_e32 v53, v55
	v_pk_add_f32 v[48:49], v[68:69], v[48:49]
	v_pk_add_f32 v[50:51], v[50:51], v[52:53]
	v_pk_add_f32 v[48:49], v[48:49], v[48:49] op_sel:[0,1] op_sel_hi:[1,0]
	v_pk_add_f32 v[50:51], v[50:51], v[50:51] op_sel:[0,1] op_sel_hi:[1,0]
	v_add_f32_e32 v54, v56, v57
	v_add_f32_e32 v56, v58, v59
	v_mov_b32_e32 v55, v62
	v_mov_b32_e32 v57, v63
	v_mov_b32_e32 v49, v60
	v_mov_b32_e32 v51, v61
	v_pk_add_f32 v[52:53], v[54:55], v[56:57]
	v_pk_add_f32 v[48:49], v[48:49], v[50:51]
	v_lshlrev_b64 v[50:51], 6, v[64:65]
	v_pk_add_f32 v[48:49], v[48:49], v[52:53]
	v_lshl_add_u64 v[50:51], s[18:19], 0, v[50:51]
	v_add_f32_e32 v48, v48, v49
	v_fmamk_f32 v48, v48, 0x3a800000, v158
	v_mul_f32_e32 v49, 0x4b800000, v48
	v_cmp_gt_f32_e32 vcc, s65, v48
	s_nop 1
	v_cndmask_b32_e32 v48, v48, v49, vcc
	v_rsq_f32_e32 v52, v48
	v_lshl_add_u64 v[48:49], v[66:67], 0, v[148:149]
	v_mul_f32_e32 v53, 0x45800000, v52
	v_cndmask_b32_e32 v52, v52, v53, vcc
	v_pk_mul_f32 v[46:47], v[46:47], v[52:53] op_sel_hi:[1,0]
	v_pk_mul_f32 v[44:45], v[44:45], v[52:53] op_sel_hi:[1,0]
	v_pk_mul_f32 v[42:43], v[42:43], v[52:53] op_sel_hi:[1,0]
	v_pk_mul_f32 v[40:41], v[40:41], v[52:53] op_sel_hi:[1,0]
	v_pk_mul_f32 v[38:39], v[38:39], v[52:53] op_sel_hi:[1,0]
	v_pk_mul_f32 v[36:37], v[36:37], v[52:53] op_sel_hi:[1,0]
	v_pk_mul_f32 v[54:55], v[34:35], v[52:53] op_sel_hi:[1,0]
	v_pk_mul_f32 v[52:53], v[32:33], v[52:53] op_sel_hi:[1,0]
	v_cvt_pk_bf16_f32 v32, v44, v45
	v_cvt_pk_bf16_f32 v33, v46, v47
	v_cvt_pk_bf16_f32 v34, v40, v41
	v_cvt_pk_bf16_f32 v35, v42, v43
	global_store_dwordx4 v[48:49], v[32:35], off
	s_nop 1
	v_cvt_pk_bf16_f32 v32, v36, v37
	v_cvt_pk_bf16_f32 v33, v38, v39
	v_cvt_pk_bf16_f32 v34, v52, v53
	v_cvt_pk_bf16_f32 v35, v54, v55
	global_store_dwordx4 v[48:49], v[32:35], off offset:256
	s_nop 0
	v_add_u32_e32 v48, 0xb0, v150
	v_mad_i64_i32 v[50:51], s[6:7], v64, s66, v[146:147]
	v_ashrrev_i32_e32 v49, 31, v48
	s_mov_b32 s6, s22
	s_waitcnt vmcnt(10)
; #define PG8_WAIT_V(n) asm volatile("s_waitcnt vmcnt(" #n ")" ::: "memory")
; #define PG8_BAR __builtin_amdgcn_s_barrier()
; __device__ __forceinline__ u32x4 pack8(const f32x4 v0, const f32x4 v1) { u32x4 w; w.x = pk2(v0[0], v0[1]); w.y = pk2(v0[2], v0[3]); w.z = pk2(v1[0], v1[1]); w.w = pk2(v1[2], v1[3]); return w; }
;     ...
;         cur = nxt; cA = nA; cB = nB; ++ui;
;     }
;     PG8_WAIT_V(0);
;     if (wr == 0) PG8_BAR;
;     PG8_BAR;
;     __device__ __forceinline__ void operator()(const f32x4 (&acc)[2][2][4][2], const Unit& u, int wr, int wc, int fr, int fq) const {
;         const int row0 = u.pm * 256 + wr * 64 + fr, col0 = u.pn * 256 + wc * 32 + 8 * fq;
; #pragma unroll
;         for (int ai = 0; ai < 2; ++ai)
; #pragma unroll
;             for (int m = 0; m < 4; ++m) {
;                 const int row = row0 + ai * 128 + m * 16; const float rs = row_rstd(ssq, row);
;                 bf16_t* rowp = O + (size_t)row * ldc + col0;
; #pragma unroll
;                 for (int bj = 0; bj < 2; ++bj) { f32x4 v0 = acc[ai][bj][m][0] * rs, v1 = acc[ai][bj][m][1] * rs;
;                     if (ACT == 1) {
; #pragma unroll
;                         for (int j = 0; j < 4; ++j) { const float a = fmaxf(v0[j], 0.f), b = fmaxf(v1[j], 0.f); v0[j] = a * a; v1[j] = b * b; } }
;                     *(u32x4*)(rowp + bj * 128) = pack8(v0, v1); }
	v_mov_b32_e32 v32, v188
	v_mov_b32_e32 v33, v189
	v_mov_b32_e32 v34, v190
	v_mov_b32_e32 v35, v191
	v_mov_b32_e32 v36, v192
	v_mov_b32_e32 v37, v193
	v_mov_b32_e32 v38, v194
	v_mov_b32_e32 v39, v195
	v_mov_b32_e32 v40, v196
	v_mov_b32_e32 v41, v197
	v_mov_b32_e32 v42, v198
	v_mov_b32_e32 v43, v199
	v_mov_b32_e32 v44, v200
	v_mov_b32_e32 v45, v201
	v_mov_b32_e32 v46, v202
	v_mov_b32_e32 v47, v203
	v_mov_b32_e32 v52, v33
	v_mov_b32_e32 v53, v34
	v_mov_b32_e32 v33, v35
	v_mov_b32_e32 v34, v37
	v_mov_b32_e32 v35, v38
	v_mov_b32_e32 v37, v39
	v_pk_add_f32 v[32:33], v[52:53], v[32:33]
	v_pk_add_f32 v[34:35], v[34:35], v[36:37]
	v_pk_add_f32 v[32:33], v[32:33], v[32:33] op_sel:[0,1] op_sel_hi:[1,0]
	v_pk_add_f32 v[34:35], v[34:35], v[34:35] op_sel:[0,1] op_sel_hi:[1,0]
	v_add_f32_e32 v38, v40, v41
	v_add_f32_e32 v40, v42, v43
	v_mov_b32_e32 v39, v46
	v_mov_b32_e32 v41, v47
	v_mov_b32_e32 v33, v44
	v_mov_b32_e32 v35, v45
	v_pk_add_f32 v[36:37], v[38:39], v[40:41]
	v_pk_add_f32 v[32:33], v[32:33], v[34:35]
	v_lshlrev_b64 v[34:35], 6, v[48:49]
	v_pk_add_f32 v[32:33], v[32:33], v[36:37]
	v_lshl_add_u64 v[34:35], s[18:19], 0, v[34:35]
	v_add_f32_e32 v32, v32, v33
	v_fmamk_f32 v32, v32, 0x3a800000, v158
	v_mul_f32_e32 v33, 0x4b800000, v32
	v_cmp_gt_f32_e32 vcc, s65, v32
	s_nop 1
	v_cndmask_b32_e32 v32, v32, v33, vcc
	v_rsq_f32_e32 v36, v32
	v_lshl_add_u64 v[32:33], v[50:51], 0, v[148:149]
	v_mul_f32_e32 v37, 0x45800000, v36
	v_cndmask_b32_e32 v36, v36, v37, vcc
	v_pk_mul_f32 v[30:31], v[30:31], v[36:37] op_sel_hi:[1,0]
	v_pk_mul_f32 v[28:29], v[28:29], v[36:37] op_sel_hi:[1,0]
	v_pk_mul_f32 v[26:27], v[26:27], v[36:37] op_sel_hi:[1,0]
	v_pk_mul_f32 v[24:25], v[24:25], v[36:37] op_sel_hi:[1,0]
	v_pk_mul_f32 v[22:23], v[22:23], v[36:37] op_sel_hi:[1,0]
	v_pk_mul_f32 v[20:21], v[20:21], v[36:37] op_sel_hi:[1,0]
	v_pk_mul_f32 v[38:39], v[18:19], v[36:37] op_sel_hi:[1,0]
	v_pk_mul_f32 v[36:37], v[16:17], v[36:37] op_sel_hi:[1,0]
	v_cvt_pk_bf16_f32 v16, v28, v29
	v_cvt_pk_bf16_f32 v17, v30, v31
	v_cvt_pk_bf16_f32 v18, v24, v25
	v_cvt_pk_bf16_f32 v19, v26, v27
	global_store_dwordx4 v[32:33], v[16:19], off
	s_and_b64 vcc, exec, s[10:11]
	s_nop 0
	v_cvt_pk_bf16_f32 v16, v20, v21
	v_cvt_pk_bf16_f32 v17, v22, v23
	v_cvt_pk_bf16_f32 v18, v36, v37
	v_cvt_pk_bf16_f32 v19, v38, v39
	global_store_dwordx4 v[32:33], v[16:19], off offset:256
	s_nop 0
	s_waitcnt vmcnt(6)
	v_mov_b32_e32 v16, v204
	v_mov_b32_e32 v17, v205
	v_mov_b32_e32 v18, v206
	v_mov_b32_e32 v19, v207
	v_mov_b32_e32 v20, v208
	v_mov_b32_e32 v21, v209
	v_mov_b32_e32 v22, v210
	v_mov_b32_e32 v23, v211
	v_mov_b32_e32 v24, v212
	v_mov_b32_e32 v25, v213
	v_mov_b32_e32 v26, v214
	v_mov_b32_e32 v27, v215
	v_mov_b32_e32 v28, v216
	v_mov_b32_e32 v29, v217
	v_mov_b32_e32 v30, v218
	v_mov_b32_e32 v31, v219
	v_mov_b32_e32 v32, v17
	v_mov_b32_e32 v33, v18
	v_mov_b32_e32 v17, v19
	v_mov_b32_e32 v18, v21
	v_mov_b32_e32 v19, v22
	v_mov_b32_e32 v21, v23
	v_pk_add_f32 v[16:17], v[32:33], v[16:17]
	v_pk_add_f32 v[18:19], v[18:19], v[20:21]
	v_pk_add_f32 v[16:17], v[16:17], v[16:17] op_sel:[0,1] op_sel_hi:[1,0]
	v_pk_add_f32 v[18:19], v[18:19], v[18:19] op_sel:[0,1] op_sel_hi:[1,0]
	v_add_f32_e32 v22, v24, v25
	v_add_f32_e32 v24, v26, v27
	v_mov_b32_e32 v23, v30
	v_mov_b32_e32 v25, v31
	v_mov_b32_e32 v17, v28
	v_mov_b32_e32 v19, v29
	v_pk_add_f32 v[20:21], v[22:23], v[24:25]
	v_pk_add_f32 v[16:17], v[16:17], v[18:19]
	s_nop 0
	v_pk_add_f32 v[16:17], v[16:17], v[20:21]
	s_nop 0
	v_add_f32_e32 v16, v16, v17
	v_fmamk_f32 v16, v16, 0x3a800000, v158
	v_mul_f32_e32 v17, 0x4b800000, v16
	v_cmp_gt_f32_e64 s[10:11], s65, v16
	s_nop 1
	v_cndmask_b32_e64 v16, v16, v17, s[10:11]
	v_rsq_f32_e32 v18, v16
	v_mad_i64_i32 v[16:17], s[8:9], v48, s66, v[146:147]
	v_lshl_add_u64 v[16:17], v[16:17], 0, v[148:149]
	v_mul_f32_e32 v19, 0x45800000, v18
	v_cndmask_b32_e64 v18, v18, v19, s[10:11]
	v_pk_mul_f32 v[14:15], v[14:15], v[18:19] op_sel_hi:[1,0]
	v_pk_mul_f32 v[12:13], v[12:13], v[18:19] op_sel_hi:[1,0]
	v_pk_mul_f32 v[10:11], v[10:11], v[18:19] op_sel_hi:[1,0]
	v_pk_mul_f32 v[8:9], v[8:9], v[18:19] op_sel_hi:[1,0]
	v_pk_mul_f32 v[6:7], v[6:7], v[18:19] op_sel_hi:[1,0]
	v_pk_mul_f32 v[4:5], v[4:5], v[18:19] op_sel_hi:[1,0]
	v_pk_mul_f32 v[20:21], v[2:3], v[18:19] op_sel_hi:[1,0]
	v_pk_mul_f32 v[18:19], v[0:1], v[18:19] op_sel_hi:[1,0]
	v_cvt_pk_bf16_f32 v0, v12, v13
	v_cvt_pk_bf16_f32 v1, v14, v15
	v_cvt_pk_bf16_f32 v2, v8, v9
	v_cvt_pk_bf16_f32 v3, v10, v11
	global_store_dwordx4 v[16:17], v[0:3], off
	s_nop 1
	v_cvt_pk_bf16_f32 v0, v4, v5
	v_cvt_pk_bf16_f32 v1, v6, v7
	v_cvt_pk_bf16_f32 v2, v18, v19
	v_cvt_pk_bf16_f32 v3, v20, v21
	global_store_dwordx4 v[16:17], v[0:3], off offset:256
	s_cbranch_vccz .LBB0_1281
	s_waitcnt vmcnt(0)
	s_cmpk_gt_u32 s53, 0xff
	s_cbranch_scc1 .LBB0_1292
	s_barrier

; #define PG8_STAGE(bufoff, gbase, voff) do { _Pragma("unroll") for (int _i = 0; _i < 2; ++_i) \
;         __builtin_amdgcn_global_load_lds((const unsigned*)((const char*)(gbase) + (voff)[_i]), (LAS unsigned*)(lds + (bufoff) + ldsw + _i * 8192), 16, 0, 0); } while (0)
; #define PG8_LDA(dst, b, h) do { _Pragma("unroll") for (int m = 0; m < 4; ++m) _Pragma("unroll") for (int k = 0; k < 2; ++k) dst[m][k] = *(const LAS bf16x8*)(lds + PG8_SA(b, h) + aoff + m * 2048 + k * 1024); } while (0)
; #define PG8_LDB(dst, b, h) do { _Pragma("unroll") for (int n = 0; n < 2; ++n) _Pragma("unroll") for (int k = 0; k < 2; ++k) dst[n][k] = *(const LAS bf16x8*)(lds + PG8_SB(b, h) + boff + n * 2048 + k * 1024); } while (0)
; #define PG8_MMA(ai, bj, At, Bt) do { __builtin_amdgcn_s_setprio(1); _Pragma("unroll") for (int m = 0; m < 4; ++m) _Pragma("unroll") for (int n = 0; n < 2; ++n) _Pragma("unroll") for (int k = 0; k < 2; ++k) \
;         acc[ai][bj][m][n] = __builtin_amdgcn_mfma_f32_16x16x32_bf16(Bt[n][k], At[m][k], acc[ai][bj][m][n], 0, 0, 0); __builtin_amdgcn_s_setprio(0); } while (0)
; #define PG8_WAIT_L(n) asm volatile("s_waitcnt lgkmcnt(" #n ")" ::: "memory")
; #define PG8_BAR __builtin_amdgcn_s_barrier()
; #define PG8_SCHED __builtin_amdgcn_sched_barrier(0)
;     ...
;             const bool last = (t == nt - 2);
;             const char* a1 = cA + (size_t)(t + 1) * kstep;
;             const char* a2 = last ? nA : cA + (size_t)(t + 2) * kstep; const char* b2 = last ? nB : cB + (size_t)(t + 2) * kstep;
;             const char* a3 = a2 + kstep; const char* b3 = b2 + kstep;
;             if (last && has_next) PG8_A_READY(nxt);
;             PG8_LDB(B0, 0, 0); PG8_SCHED; PG8_LDA(At, 0, 0); PG8_STAGE(PG8_SA(1, 1), a1 + hA, voffA);
;             PG8_WAIT_L(8); PG8_BAR; PG8_WAIT_L(0); PG8_MMA(0, 0, At, B0); PG8_BAR; PG8_SCHED;
;             PG8_LDB(B1, 0, 1); PG8_STAGE(PG8_SB(0, 0), b2, voffB);
;             PG8_BAR; PG8_WAIT_L(0); PG8_MMA(0, 1, At, B1); PG8_BAR;
;             PG8_LDA(At, 0, 1); PG8_STAGE(PG8_SA(0, 0), a2, voffA);
;             PG8_BAR; PG8_WAIT_L(0); PG8_MMA(1, 0, At, B0); PG8_BAR; PG8_SCHED;
.LBB0_1841:
	ds_read_b128 v[146:149], v159
	ds_read_b128 v[150:153], v159 offset:1024
	ds_read_b128 v[162:165], v159 offset:2048
	ds_read_b128 v[170:173], v159 offset:3072
	s_add_u32 s14, s12, 0xfffe0080
	s_addc_u32 s15, s13, -1
	s_cmp_eq_u32 s45, 4
	s_cselect_b32 s17, s7, s15
	s_cselect_b32 s16, s18, s14
	s_cselect_b32 s15, s19, s44
	s_cselect_b32 s14, s33, s39
	v_lshl_add_u64 v[154:155], s[12:13], 0, v[138:139]
	s_add_i32 m0, s62, 0xc000
	ds_read_b128 v[174:177], v160
	ds_read_b128 v[178:181], v160 offset:1024
	ds_read_b128 v[182:185], v160 offset:2048
	ds_read_b128 v[186:189], v160 offset:3072
	ds_read_b128 v[190:193], v160 offset:4096
	ds_read_b128 v[194:197], v160 offset:5120
	ds_read_b128 v[198:201], v160 offset:6144
	ds_read_b128 v[202:205], v160 offset:7168
	global_load_lds_dwordx4 v[154:155], off
	v_lshl_add_u64 v[154:155], s[12:13], 0, v[136:137]
	s_add_i32 m0, s62, 0xe000
	s_nop 0
	global_load_lds_dwordx4 v[154:155], off
	s_waitcnt lgkmcnt(8)
	s_barrier
	s_waitcnt lgkmcnt(0)
	s_setprio 1
	s_waitcnt lgkmcnt(0)
	v_mfma_f32_16x16x32_bf16 v[124:127], v[146:149], v[174:177], v[124:127]
	v_mfma_f32_16x16x32_bf16 v[120:123], v[162:165], v[174:177], v[120:123]
	v_mfma_f32_16x16x32_bf16 v[108:111], v[146:149], v[182:185], v[108:111]
	v_mfma_f32_16x16x32_bf16 v[104:107], v[162:165], v[182:185], v[104:107]
	v_mfma_f32_16x16x32_bf16 v[92:95], v[146:149], v[190:193], v[92:95]
	v_mfma_f32_16x16x32_bf16 v[88:91], v[162:165], v[190:193], v[88:91]
	v_mfma_f32_16x16x32_bf16 v[76:79], v[146:149], v[198:201], v[76:79]
	v_mfma_f32_16x16x32_bf16 v[72:75], v[162:165], v[198:201], v[72:75]
	v_mfma_f32_16x16x32_bf16 v[124:127], v[150:153], v[178:181], v[124:127]
	v_mfma_f32_16x16x32_bf16 v[120:123], v[170:173], v[178:181], v[120:123]
	v_mfma_f32_16x16x32_bf16 v[108:111], v[150:153], v[186:189], v[108:111]
	v_mfma_f32_16x16x32_bf16 v[104:107], v[170:173], v[186:189], v[104:107]
	v_mfma_f32_16x16x32_bf16 v[92:95], v[150:153], v[194:197], v[92:95]
	v_mfma_f32_16x16x32_bf16 v[88:91], v[170:173], v[194:197], v[88:91]
	v_mfma_f32_16x16x32_bf16 v[76:79], v[150:153], v[202:205], v[76:79]
	v_mfma_f32_16x16x32_bf16 v[72:75], v[170:173], v[202:205], v[72:75]
	s_setprio 0
	s_barrier
	s_add_i32 s55, s71, s61
	v_lshl_add_u64 v[154:155], s[14:15], 0, v[130:131]
	s_mov_b32 m0, s55
	ds_read_b128 v[206:209], v161
	ds_read_b128 v[210:213], v161 offset:1024
	ds_read_b128 v[214:217], v161 offset:2048
	ds_read_b128 v[218:221], v161 offset:3072
	global_load_lds_dwordx4 v[154:155], off
	v_lshl_add_u64 v[222:223], s[14:15], 0, v[134:135]
	s_add_i32 m0, s55, 0x2000
	s_nop 0
	global_load_lds_dwordx4 v[222:223], off
	s_barrier
	s_waitcnt lgkmcnt(0)
	s_setprio 1
	s_waitcnt lgkmcnt(0)
	v_mfma_f32_16x16x32_bf16 v[116:119], v[206:209], v[174:177], v[116:119]
	v_mfma_f32_16x16x32_bf16 v[112:115], v[214:217], v[174:177], v[112:115]
	v_mfma_f32_16x16x32_bf16 v[100:103], v[206:209], v[182:185], v[100:103]
	v_mfma_f32_16x16x32_bf16 v[96:99], v[214:217], v[182:185], v[96:99]
	v_mfma_f32_16x16x32_bf16 v[84:87], v[206:209], v[190:193], v[84:87]
	v_mfma_f32_16x16x32_bf16 v[80:83], v[214:217], v[190:193], v[80:83]
	v_mfma_f32_16x16x32_bf16 v[68:71], v[206:209], v[198:201], v[68:71]
	v_mfma_f32_16x16x32_bf16 v[64:67], v[214:217], v[198:201], v[64:67]
	v_mfma_f32_16x16x32_bf16 v[116:119], v[210:213], v[178:181], v[116:119]
	v_mfma_f32_16x16x32_bf16 v[112:115], v[218:221], v[178:181], v[112:115]
	v_mfma_f32_16x16x32_bf16 v[100:103], v[210:213], v[186:189], v[100:103]
	v_mfma_f32_16x16x32_bf16 v[96:99], v[218:221], v[186:189], v[96:99]
	v_mfma_f32_16x16x32_bf16 v[84:87], v[210:213], v[194:197], v[84:87]
	v_mfma_f32_16x16x32_bf16 v[80:83], v[218:221], v[194:197], v[80:83]
	v_mfma_f32_16x16x32_bf16 v[68:71], v[210:213], v[202:205], v[68:71]
	v_mfma_f32_16x16x32_bf16 v[64:67], v[218:221], v[202:205], v[64:67]
	s_setprio 0
	s_mov_b32 m0, s62
	v_lshl_add_u64 v[224:225], s[16:17], 0, v[128:129]
	s_barrier
	ds_read_b128 v[174:177], v160 offset:16384
	ds_read_b128 v[178:181], v160 offset:17408
	ds_read_b128 v[182:185], v160 offset:18432
	ds_read_b128 v[186:189], v160 offset:19456
	ds_read_b128 v[190:193], v160 offset:20480
	ds_read_b128 v[194:197], v160 offset:21504
	ds_read_b128 v[198:201], v160 offset:22528
	ds_read_b128 v[202:205], v160 offset:23552
	global_load_lds_dwordx4 v[224:225], off
	v_lshl_add_u64 v[226:227], s[16:17], 0, v[132:133]
	s_mov_b32 m0, s63
	s_nop 0
	global_load_lds_dwordx4 v[226:227], off
	s_barrier
	s_waitcnt lgkmcnt(0)
	s_setprio 1
	s_waitcnt lgkmcnt(0)
	v_mfma_f32_16x16x32_bf16 v[60:63], v[146:149], v[174:177], v[60:63]
	v_mfma_f32_16x16x32_bf16 v[56:59], v[162:165], v[174:177], v[56:59]
	v_mfma_f32_16x16x32_bf16 v[44:47], v[146:149], v[182:185], v[44:47]
	v_mfma_f32_16x16x32_bf16 v[40:43], v[162:165], v[182:185], v[40:43]
	v_mfma_f32_16x16x32_bf16 v[28:31], v[146:149], v[190:193], v[28:31]
	v_mfma_f32_16x16x32_bf16 v[24:27], v[162:165], v[190:193], v[24:27]
	v_mfma_f32_16x16x32_bf16 v[12:15], v[146:149], v[198:201], v[12:15]
	v_mfma_f32_16x16x32_bf16 v[8:11], v[162:165], v[198:201], v[8:11]
	v_mfma_f32_16x16x32_bf16 v[60:63], v[150:153], v[178:181], v[60:63]
	v_mfma_f32_16x16x32_bf16 v[56:59], v[170:173], v[178:181], v[56:59]
	v_mfma_f32_16x16x32_bf16 v[44:47], v[150:153], v[186:189], v[44:47]
	v_mfma_f32_16x16x32_bf16 v[40:43], v[170:173], v[186:189], v[40:43]
	v_mfma_f32_16x16x32_bf16 v[28:31], v[150:153], v[194:197], v[28:31]
	v_mfma_f32_16x16x32_bf16 v[24:27], v[170:173], v[194:197], v[24:27]
	v_mfma_f32_16x16x32_bf16 v[12:15], v[150:153], v[202:205], v[12:15]
	v_mfma_f32_16x16x32_bf16 v[8:11], v[170:173], v[202:205], v[8:11]
	s_setprio 0
	s_barrier
; #define PG8_STAGE(bufoff, gbase, voff) do { _Pragma("unroll") for (int _i = 0; _i < 2; ++_i) \
;         __builtin_amdgcn_global_load_lds((const unsigned*)((const char*)(gbase) + (voff)[_i]), (LAS unsigned*)(lds + (bufoff) + ldsw + _i * 8192), 16, 0, 0); } while (0)
; #define PG8_LDA(dst, b, h) do { _Pragma("unroll") for (int m = 0; m < 4; ++m) _Pragma("unroll") for (int k = 0; k < 2; ++k) dst[m][k] = *(const LAS bf16x8*)(lds + PG8_SA(b, h) + aoff + m * 2048 + k * 1024); } while (0)
; #define PG8_LDB(dst, b, h) do { _Pragma("unroll") for (int n = 0; n < 2; ++n) _Pragma("unroll") for (int k = 0; k < 2; ++k) dst[n][k] = *(const LAS bf16x8*)(lds + PG8_SB(b, h) + boff + n * 2048 + k * 1024); } while (0)
; #define PG8_MMA(ai, bj, At, Bt) do { __builtin_amdgcn_s_setprio(1); _Pragma("unroll") for (int m = 0; m < 4; ++m) _Pragma("unroll") for (int n = 0; n < 2; ++n) _Pragma("unroll") for (int k = 0; k < 2; ++k) \
;         acc[ai][bj][m][n] = __builtin_amdgcn_mfma_f32_16x16x32_bf16(Bt[n][k], At[m][k], acc[ai][bj][m][n], 0, 0, 0); __builtin_amdgcn_s_setprio(0); } while (0)
; #define PG8_WAIT_V(n) asm volatile("s_waitcnt vmcnt(" #n ")" ::: "memory")
; #define PG8_WAIT_L(n) asm volatile("s_waitcnt lgkmcnt(" #n ")" ::: "memory")
; #define PG8_BAR __builtin_amdgcn_s_barrier()
; #define PG8_SCHED __builtin_amdgcn_sched_barrier(0)
;     ...
;             PG8_STAGE(PG8_SB(0, 1), b2 + hB, voffB);
;             PG8_WAIT_V(6); PG8_BAR; PG8_MMA(1, 1, At, B1); PG8_BAR;
;             PG8_LDB(B0, 1, 0); PG8_SCHED; PG8_LDA(At, 1, 0); PG8_STAGE(PG8_SA(0, 1), a2 + hA, voffA);
;             PG8_WAIT_L(8); PG8_BAR; PG8_WAIT_L(0); PG8_MMA(0, 0, At, B0); PG8_BAR; PG8_SCHED;
;             PG8_LDB(B1, 1, 1); PG8_STAGE(PG8_SB(1, 0), b3, voffB);
;             PG8_BAR; PG8_WAIT_L(0); PG8_MMA(0, 1, At, B1); PG8_BAR;
;             PG8_LDA(At, 1, 1); PG8_STAGE(PG8_SA(1, 0), a3, voffA);
	s_add_u32 s76, s14, 0x20000
	s_addc_u32 s77, s15, 0
	s_add_i32 s55, s72, s61
	v_lshl_add_u64 v[146:147], s[76:77], 0, v[130:131]
	s_mov_b32 m0, s55
	s_nop 0
	global_load_lds_dwordx4 v[146:147], off
	v_lshl_add_u64 v[146:147], s[76:77], 0, v[134:135]
	s_add_i32 m0, s55, 0x2000
	s_nop 0
	global_load_lds_dwordx4 v[146:147], off
	s_waitcnt vmcnt(6)
	s_barrier
	s_setprio 1
	v_mfma_f32_16x16x32_bf16 v[52:55], v[206:209], v[174:177], v[52:55]
	v_mfma_f32_16x16x32_bf16 v[48:51], v[214:217], v[174:177], v[48:51]
	v_mfma_f32_16x16x32_bf16 v[36:39], v[206:209], v[182:185], v[36:39]
	v_mfma_f32_16x16x32_bf16 v[32:35], v[214:217], v[182:185], v[32:35]
	v_mfma_f32_16x16x32_bf16 v[20:23], v[206:209], v[190:193], v[20:23]
	v_mfma_f32_16x16x32_bf16 v[16:19], v[214:217], v[190:193], v[16:19]
	v_mfma_f32_16x16x32_bf16 v[4:7], v[206:209], v[198:201], v[4:7]
	v_mfma_f32_16x16x32_bf16 v[0:3], v[214:217], v[198:201], v[0:3]
	v_mfma_f32_16x16x32_bf16 v[52:55], v[210:213], v[178:181], v[52:55]
	v_mfma_f32_16x16x32_bf16 v[48:51], v[218:221], v[178:181], v[48:51]
	v_mfma_f32_16x16x32_bf16 v[36:39], v[210:213], v[186:189], v[36:39]
	v_mfma_f32_16x16x32_bf16 v[32:35], v[218:221], v[186:189], v[32:35]
	v_mfma_f32_16x16x32_bf16 v[20:23], v[210:213], v[194:197], v[20:23]
	v_mfma_f32_16x16x32_bf16 v[16:19], v[218:221], v[194:197], v[16:19]
	v_mfma_f32_16x16x32_bf16 v[4:7], v[210:213], v[202:205], v[4:7]
	v_mfma_f32_16x16x32_bf16 v[0:3], v[218:221], v[202:205], v[0:3]
	s_setprio 0
	s_add_i32 s55, 0, 0x18000
	v_add_u32_e32 v169, s55, v157
	s_barrier
	ds_read_b128 v[146:149], v169
	ds_read_b128 v[150:153], v169 offset:1024
	ds_read_b128 v[162:165], v169 offset:2048
	ds_read_b128 v[170:173], v169 offset:3072
	s_add_u32 s16, s16, 0x20000
	s_addc_u32 s17, s17, 0
	s_mov_b32 m0, s64
	v_lshl_add_u64 v[206:207], s[16:17], 0, v[128:129]
	ds_read_b128 v[174:177], v160 offset:32768
	ds_read_b128 v[178:181], v160 offset:33792
	ds_read_b128 v[182:185], v160 offset:34816
	ds_read_b128 v[186:189], v160 offset:35840
	ds_read_b128 v[190:193], v160 offset:36864
	ds_read_b128 v[194:197], v160 offset:37888
	ds_read_b128 v[198:201], v160 offset:38912
	ds_read_b128 v[202:205], v160 offset:39936
	global_load_lds_dwordx4 v[206:207], off
	v_lshl_add_u64 v[206:207], s[16:17], 0, v[132:133]
	s_mov_b32 m0, s65
	s_nop 0
	global_load_lds_dwordx4 v[206:207], off
	s_waitcnt lgkmcnt(8)
	s_barrier
	s_waitcnt lgkmcnt(0)
	s_setprio 1
	s_waitcnt lgkmcnt(0)
	v_mfma_f32_16x16x32_bf16 v[124:127], v[146:149], v[174:177], v[124:127]
	v_mfma_f32_16x16x32_bf16 v[120:123], v[162:165], v[174:177], v[120:123]
	v_mfma_f32_16x16x32_bf16 v[108:111], v[146:149], v[182:185], v[108:111]
	v_mfma_f32_16x16x32_bf16 v[104:107], v[162:165], v[182:185], v[104:107]
	v_mfma_f32_16x16x32_bf16 v[92:95], v[146:149], v[190:193], v[92:95]
	v_mfma_f32_16x16x32_bf16 v[88:91], v[162:165], v[190:193], v[88:91]
	v_mfma_f32_16x16x32_bf16 v[76:79], v[146:149], v[198:201], v[76:79]
	v_mfma_f32_16x16x32_bf16 v[72:75], v[162:165], v[198:201], v[72:75]
	v_mfma_f32_16x16x32_bf16 v[124:127], v[150:153], v[178:181], v[124:127]
	v_mfma_f32_16x16x32_bf16 v[120:123], v[170:173], v[178:181], v[120:123]
	v_mfma_f32_16x16x32_bf16 v[108:111], v[150:153], v[186:189], v[108:111]
	v_mfma_f32_16x16x32_bf16 v[104:107], v[170:173], v[186:189], v[104:107]
	v_mfma_f32_16x16x32_bf16 v[92:95], v[150:153], v[194:197], v[92:95]
	v_mfma_f32_16x16x32_bf16 v[88:91], v[170:173], v[194:197], v[88:91]
	v_mfma_f32_16x16x32_bf16 v[76:79], v[150:153], v[202:205], v[76:79]
	v_mfma_f32_16x16x32_bf16 v[72:75], v[170:173], v[202:205], v[72:75]
	s_setprio 0
	s_barrier
	s_add_i32 s16, 0, 0x1c000
	s_add_i32 s17, s55, s61
	v_add_u32_e32 v169, s16, v157
	v_lshl_add_u64 v[154:155], v[154:155], 0, s[40:41]
	s_mov_b32 m0, s17
	ds_read_b128 v[206:209], v169
	ds_read_b128 v[210:213], v169 offset:1024
	ds_read_b128 v[214:217], v169 offset:2048
	ds_read_b128 v[218:221], v169 offset:3072
	global_load_lds_dwordx4 v[154:155], off
	v_lshl_add_u64 v[154:155], v[222:223], 0, s[40:41]
	s_add_i32 m0, s17, 0x2000
	s_nop 0
	global_load_lds_dwordx4 v[154:155], off
	s_barrier
	s_waitcnt lgkmcnt(0)
	s_setprio 1
	s_waitcnt lgkmcnt(0)
	v_mfma_f32_16x16x32_bf16 v[116:119], v[206:209], v[174:177], v[116:119]
	v_mfma_f32_16x16x32_bf16 v[112:115], v[214:217], v[174:177], v[112:115]
	v_mfma_f32_16x16x32_bf16 v[100:103], v[206:209], v[182:185], v[100:103]
	v_mfma_f32_16x16x32_bf16 v[96:99], v[214:217], v[182:185], v[96:99]
	v_mfma_f32_16x16x32_bf16 v[84:87], v[206:209], v[190:193], v[84:87]
	v_mfma_f32_16x16x32_bf16 v[80:83], v[214:217], v[190:193], v[80:83]
	v_mfma_f32_16x16x32_bf16 v[68:71], v[206:209], v[198:201], v[68:71]
	v_mfma_f32_16x16x32_bf16 v[64:67], v[214:217], v[198:201], v[64:67]
	v_mfma_f32_16x16x32_bf16 v[116:119], v[210:213], v[178:181], v[116:119]
	v_mfma_f32_16x16x32_bf16 v[112:115], v[218:221], v[178:181], v[112:115]
	v_mfma_f32_16x16x32_bf16 v[100:103], v[210:213], v[186:189], v[100:103]
	v_mfma_f32_16x16x32_bf16 v[96:99], v[218:221], v[186:189], v[96:99]
	v_mfma_f32_16x16x32_bf16 v[84:87], v[210:213], v[194:197], v[84:87]
	v_mfma_f32_16x16x32_bf16 v[80:83], v[218:221], v[194:197], v[80:83]
	v_mfma_f32_16x16x32_bf16 v[68:71], v[210:213], v[202:205], v[68:71]
	v_mfma_f32_16x16x32_bf16 v[64:67], v[218:221], v[202:205], v[64:67]
	s_setprio 0
	s_mov_b32 m0, s67
	v_lshl_add_u64 v[154:155], v[224:225], 0, s[40:41]
	s_barrier
	ds_read_b128 v[174:177], v160 offset:49152
	ds_read_b128 v[178:181], v160 offset:50176
	ds_read_b128 v[182:185], v160 offset:51200
	ds_read_b128 v[186:189], v160 offset:52224
	ds_read_b128 v[190:193], v160 offset:53248
	ds_read_b128 v[194:197], v160 offset:54272
	ds_read_b128 v[198:201], v160 offset:55296
	ds_read_b128 v[202:205], v160 offset:56320
	global_load_lds_dwordx4 v[154:155], off
	v_lshl_add_u64 v[154:155], v[226:227], 0, s[40:41]
	s_mov_b32 m0, s68
	s_nop 0
	global_load_lds_dwordx4 v[154:155], off
	s_barrier
; #define PG8_STAGE(bufoff, gbase, voff) do { _Pragma("unroll") for (int _i = 0; _i < 2; ++_i) \
;         __builtin_amdgcn_global_load_lds((const unsigned*)((const char*)(gbase) + (voff)[_i]), (LAS unsigned*)(lds + (bufoff) + ldsw + _i * 8192), 16, 0, 0); } while (0)
; #define PG8_MMA(ai, bj, At, Bt) do { __builtin_amdgcn_s_setprio(1); _Pragma("unroll") for (int m = 0; m < 4; ++m) _Pragma("unroll") for (int n = 0; n < 2; ++n) _Pragma("unroll") for (int k = 0; k < 2; ++k) \
;         acc[ai][bj][m][n] = __builtin_amdgcn_mfma_f32_16x16x32_bf16(Bt[n][k], At[m][k], acc[ai][bj][m][n], 0, 0, 0); __builtin_amdgcn_s_setprio(0); } while (0)
; #define PG8_WAIT_V(n) asm volatile("s_waitcnt vmcnt(" #n ")" ::: "memory")
; #define PG8_WAIT_L(n) asm volatile("s_waitcnt lgkmcnt(" #n ")" ::: "memory")
; #define PG8_BAR __builtin_amdgcn_s_barrier()
; #define PG8_SCHED __builtin_amdgcn_sched_barrier(0)
;     ...
;             PG8_BAR; PG8_WAIT_L(0); PG8_MMA(1, 0, At, B0); PG8_BAR; PG8_SCHED;
;             PG8_STAGE(PG8_SB(1, 1), b3 + hB, voffB);
;             PG8_WAIT_V(6); PG8_BAR; PG8_MMA(1, 1, At, B1); PG8_BAR;
;         }
;         E(acc, cur, wr, wc, fr, fq);
;     __device__ __forceinline__ void operator()(const f32x4 (&acc)[2][2][4][2], const Unit& u, int wr, int wc, int fr, int fq) const {
;         const __amdgpu_buffer_rsrc_t rsrc = __builtin_amdgcn_make_buffer_rsrc((void*)z, 0, T_ALL * DIN * 2, 0x00020000);
;         const int row0 = row_off + u.pm * 256 + wr * 64 + fr, col0 = u.pn * 256 + wc * 32 + 8 * fq;
; #pragma unroll
;         for (int ai = 0; ai < 2; ++ai)
; #pragma unroll
;             for (int m = 0; m < 4; ++m) {
;                 const int row = row0 + ai * 128 + m * 16;
;                 const bf16_t* rowp = z + (size_t)row * DIN + col0;
; #pragma unroll
;                 for (int bj = 0; bj < 2; ++bj) {
;                     const u32x4 gw = *(const u32x4*)(rowp + O_GA + bj * 128);
	s_waitcnt lgkmcnt(0)
	s_setprio 1
	s_waitcnt lgkmcnt(0)
	v_mfma_f32_16x16x32_bf16 v[60:63], v[146:149], v[174:177], v[60:63]
	v_mfma_f32_16x16x32_bf16 v[56:59], v[162:165], v[174:177], v[56:59]
	v_mfma_f32_16x16x32_bf16 v[44:47], v[146:149], v[182:185], v[44:47]
	v_mfma_f32_16x16x32_bf16 v[40:43], v[162:165], v[182:185], v[40:43]
	v_mfma_f32_16x16x32_bf16 v[28:31], v[146:149], v[190:193], v[28:31]
	v_mfma_f32_16x16x32_bf16 v[24:27], v[162:165], v[190:193], v[24:27]
	v_mfma_f32_16x16x32_bf16 v[12:15], v[146:149], v[198:201], v[12:15]
	v_mfma_f32_16x16x32_bf16 v[8:11], v[162:165], v[198:201], v[8:11]
	v_mfma_f32_16x16x32_bf16 v[60:63], v[150:153], v[178:181], v[60:63]
	v_mfma_f32_16x16x32_bf16 v[56:59], v[170:173], v[178:181], v[56:59]
	v_mfma_f32_16x16x32_bf16 v[44:47], v[150:153], v[186:189], v[44:47]
	v_mfma_f32_16x16x32_bf16 v[40:43], v[170:173], v[186:189], v[40:43]
	v_mfma_f32_16x16x32_bf16 v[28:31], v[150:153], v[194:197], v[28:31]
	v_mfma_f32_16x16x32_bf16 v[24:27], v[170:173], v[194:197], v[24:27]
	v_mfma_f32_16x16x32_bf16 v[12:15], v[150:153], v[202:205], v[12:15]
	v_mfma_f32_16x16x32_bf16 v[8:11], v[170:173], v[202:205], v[8:11]
	s_setprio 0
	s_barrier
	s_add_u32 s14, s14, 0x20080
	s_addc_u32 s15, s15, 0
	s_add_i32 s16, s16, s61
	v_lshl_add_u64 v[146:147], s[14:15], 0, v[130:131]
	s_mov_b32 m0, s16
	s_nop 0
	global_load_lds_dwordx4 v[146:147], off
	v_lshl_add_u64 v[146:147], s[14:15], 0, v[134:135]
	s_add_i32 m0, s16, 0x2000
	s_nop 0
	global_load_lds_dwordx4 v[146:147], off
	s_waitcnt vmcnt(6)
	s_barrier
	s_setprio 1
	v_mfma_f32_16x16x32_bf16 v[52:55], v[206:209], v[174:177], v[52:55]
	v_mfma_f32_16x16x32_bf16 v[48:51], v[214:217], v[174:177], v[48:51]
	v_mfma_f32_16x16x32_bf16 v[36:39], v[206:209], v[182:185], v[36:39]
	v_mfma_f32_16x16x32_bf16 v[32:35], v[214:217], v[182:185], v[32:35]
	v_mfma_f32_16x16x32_bf16 v[20:23], v[206:209], v[190:193], v[20:23]
	v_mfma_f32_16x16x32_bf16 v[16:19], v[214:217], v[190:193], v[16:19]
	v_mfma_f32_16x16x32_bf16 v[4:7], v[206:209], v[198:201], v[4:7]
	v_mfma_f32_16x16x32_bf16 v[0:3], v[214:217], v[198:201], v[0:3]
	v_mfma_f32_16x16x32_bf16 v[52:55], v[210:213], v[178:181], v[52:55]
	v_mfma_f32_16x16x32_bf16 v[48:51], v[218:221], v[178:181], v[48:51]
	v_mfma_f32_16x16x32_bf16 v[36:39], v[210:213], v[186:189], v[36:39]
	v_mfma_f32_16x16x32_bf16 v[32:35], v[218:221], v[186:189], v[32:35]
	v_mfma_f32_16x16x32_bf16 v[20:23], v[210:213], v[194:197], v[20:23]
	v_mfma_f32_16x16x32_bf16 v[16:19], v[218:221], v[194:197], v[16:19]
	v_mfma_f32_16x16x32_bf16 v[4:7], v[210:213], v[202:205], v[4:7]
	v_mfma_f32_16x16x32_bf16 v[0:3], v[218:221], v[202:205], v[0:3]
	s_setprio 0
	s_add_i32 s45, s45, 2
	s_add_u32 s39, s39, 0x100
	s_addc_u32 s44, s44, 0
	s_add_u32 s12, s12, 0x100
	s_addc_u32 s13, s13, 0
	s_cmp_gt_u32 s45, 5
	s_barrier
	s_cbranch_scc0 .LBB0_1841
	v_lshl_or_b32 v146, s6, 8, v158
	v_lshl_add_u32 v162, s75, 8, v156
	v_ashrrev_i32_e32 v147, 31, v146
	v_mad_i64_i32 v[154:155], s[6:7], v162, s73, 0
	v_lshl_add_u64 v[150:151], v[154:155], 1, s[36:37]
	v_lshlrev_b64 v[148:149], 1, v[146:147]
	v_lshl_add_u64 v[150:151], v[150:151], 0, v[148:149]
	v_add_co_u32_e32 v152, vcc, 0x1000, v150
	s_nop 1
	v_addc_co_u32_e32 v153, vcc, 0, v151, vcc
	v_subrev_u32_e32 v201, s36, v150
	v_add_u32_e32 v202, 0x1200, v201
	global_load_dwordx4 v[204:207], v202, s[36:37]
	v_add_u32_e32 v202, 0x0, v201
	global_load_dwordx4 v[208:211], v202, s[36:37]
	v_add_u32_e32 v202, 0x1300, v201
	global_load_dwordx4 v[212:215], v202, s[36:37]
	v_add_u32_e32 v202, 0x100, v201
	global_load_dwordx4 v[216:219], v202, s[36:37]
	v_add_u32_e32 v202, 0x23200, v201
	global_load_dwordx4 v[232:235], v202, s[36:37]
	v_add_u32_e32 v202, 0x22000, v201
	global_load_dwordx4 v[236:239], v202, s[36:37]
	v_add_u32_e32 v202, 0x23300, v201
	global_load_dwordx4 v[240:243], v202, s[36:37]
	v_add_u32_e32 v202, 0x22100, v201
	global_load_dwordx4 v[244:247], v202, s[36:37]
	v_add_u32_e32 v202, 0x45200, v201
	global_load_dwordx4 v[248:251], v202, s[36:37]
	v_add_u32_e32 v202, 0x44000, v201
	global_load_dwordx4 v[252:255], v202, s[36:37]
	s_waitcnt vmcnt(8)
	v_mov_b32_e32 v170, v204
	v_mov_b32_e32 v171, v205
	v_mov_b32_e32 v172, v206
	v_mov_b32_e32 v173, v207
	v_mov_b32_e32 v174, v208
	v_mov_b32_e32 v175, v209
	v_mov_b32_e32 v176, v210
	v_mov_b32_e32 v177, v211
	v_add_u32_e32 v202, 0x45300, v201
	global_load_dwordx4 v[204:207], v202, s[36:37]
	v_add_u32_e32 v202, 0x44100, v201
	global_load_dwordx4 v[208:211], v202, s[36:37]
	v_lshlrev_b32_e32 v147, 16, v170
	v_and_b32_e32 v155, 0xffff0000, v170
	v_lshlrev_b32_e32 v165, 16, v172
	v_and_b32_e32 v164, 0xffff0000, v171
	v_lshlrev_b32_e32 v170, 16, v173
	v_mul_f32_e32 v147, 0xbfb8aa3b, v147
	v_mul_f32_e32 v165, 0xbfb8aa3b, v165
	v_mul_f32_e32 v155, 0xbfb8aa3b, v155
	v_lshlrev_b32_e32 v163, 16, v171
	v_and_b32_e32 v171, 0xffff0000, v173
	v_mul_f32_e32 v178, 0xbfb8aa3b, v170
	v_mul_f32_e32 v173, 0xbfb8aa3b, v164
	v_exp_f32_e32 v164, v147
	v_exp_f32_e32 v170, v165
	v_exp_f32_e32 v165, v155
	v_mul_f32_e32 v163, 0xbfb8aa3b, v163
	v_and_b32_e32 v169, 0xffff0000, v172
	v_exp_f32_e32 v172, v163
	v_exp_f32_e32 v173, v173
	v_mul_f32_e32 v169, 0xbfb8aa3b, v169
	v_mul_f32_e32 v171, 0xbfb8aa3b, v171
	v_pk_add_f32 v[164:165], v[164:165], 1.0 op_sel_hi:[1,0]
	v_exp_f32_e32 v179, v171
	v_exp_f32_e32 v171, v169
	v_div_scale_f32 v147, s[6:7], v165, v165, 1.0
	v_pk_add_f32 v[172:173], v[172:173], 1.0 op_sel_hi:[1,0]
	v_div_scale_f32 v163, s[6:7], v164, v164, 1.0
	v_rcp_f32_e32 v186, v147
	v_div_scale_f32 v180, s[6:7], v173, v173, 1.0
	v_rcp_f32_e32 v187, v163
	v_div_scale_f32 v182, s[6:7], v172, v172, 1.0
	v_rcp_f32_e32 v188, v180
; __device__ __forceinline__ u32x4 pack8(const f32x4 v0, const f32x4 v1) { u32x4 w; w.x = pk2(v0[0], v0[1]); w.y = pk2(v0[2], v0[3]); w.z = pk2(v1[0], v1[1]); w.w = pk2(v1[2], v1[3]); return w; }
; __device__ __forceinline__ void unpack8(const u32x4 w, f32x4& v0, f32x4& v1) { v0 = (f32x4){bflo(w.x), bfhi(w.x), bflo(w.y), bfhi(w.y)}; v1 = (f32x4){bflo(w.z), bfhi(w.z), bflo(w.w), bfhi(w.w)}; }
; __device__ __forceinline__ float sigmoidf_(float x) { return 1.0f / (1.0f + __expf(-x)); }
;     __device__ __forceinline__ void operator()(const f32x4 (&acc)[2][2][4][2], const Unit& u, int wr, int wc, int fr, int fq) const {
;     ...
;                 const int row = row0 + ai * 128 + m * 16;
;                 const bf16_t* rowp = z + (size_t)row * DIN + col0;
; #pragma unroll
;                 for (int bj = 0; bj < 2; ++bj) {
;                     const u32x4 gw = *(const u32x4*)(rowp + O_GA + bj * 128);
;                     f32x4 g0, g1; unpack8(gw, g0, g1);
;                     f32x4 v0, v1;
; #pragma unroll
;                     for (int j = 0; j < 4; ++j) { v0[j] = sigmoidf_(g0[j]) * acc[ai][bj][m][0][j]; v1[j] = sigmoidf_(g1[j]) * acc[ai][bj][m][1][j]; }
;                     const u32x4 mw = *(const u32x4*)(rowp + bj * 128); f32x4 m0, m1; unpack8(mw, m0, m1); v0 += m0; v1 += m1;
;                     __builtin_amdgcn_raw_buffer_store_b128(pack8(v0, v1), rsrc, (unsigned)(((size_t)row * DIN + col0 + bj * 128) * 2), 0, 16  ); }
	v_pk_add_f32 v[170:171], v[170:171], 1.0 op_sel_hi:[1,0]
	v_rcp_f32_e32 v189, v182
	v_div_scale_f32 v184, s[6:7], v171, v171, 1.0
	v_fma_f32 v191, -v147, v186, 1.0
	v_div_scale_f32 v155, vcc, 1.0, v165, 1.0
	v_rcp_f32_e32 v190, v184
	v_fma_f32 v192, -v163, v187, 1.0
	v_fmac_f32_e32 v186, v191, v186
	v_div_scale_f32 v169, s[12:13], 1.0, v164, 1.0
	v_fma_f32 v193, -v180, v188, 1.0
	v_fmac_f32_e32 v187, v192, v187
	v_mul_f32_e32 v191, v155, v186
	v_div_scale_f32 v181, s[14:15], 1.0, v173, 1.0
	v_fma_f32 v194, -v182, v189, 1.0
	v_fmac_f32_e32 v188, v193, v188
	v_mul_f32_e32 v192, v169, v187
	v_fma_f32 v196, -v147, v191, v155
	v_div_scale_f32 v183, s[16:17], 1.0, v172, 1.0
	v_fmac_f32_e32 v189, v194, v189
	v_mul_f32_e32 v193, v181, v188
	v_fma_f32 v197, -v163, v192, v169
	v_fmac_f32_e32 v191, v196, v186
	v_fma_f32 v195, -v184, v190, 1.0
	v_mul_f32_e32 v194, v183, v189
	v_fma_f32 v198, -v180, v193, v181
	v_fmac_f32_e32 v192, v197, v187
	v_fma_f32 v147, -v147, v191, v155
	v_div_scale_f32 v185, s[18:19], 1.0, v171, 1.0
	v_fmac_f32_e32 v190, v195, v190
	v_fma_f32 v199, -v182, v194, v183
	v_fmac_f32_e32 v193, v198, v188
	v_fma_f32 v155, -v163, v192, v169
	v_div_fmas_f32 v147, v147, v186, v191
	s_mov_b64 vcc, s[12:13]
	v_mul_f32_e32 v195, v185, v190
	v_fmac_f32_e32 v194, v199, v189
	v_fma_f32 v163, -v180, v193, v181
	v_div_fixup_f32 v165, v147, v165, 1.0
	v_div_fmas_f32 v147, v155, v187, v192
	s_mov_b64 vcc, s[14:15]
	v_div_scale_f32 v155, s[6:7], v170, v170, 1.0
	v_fma_f32 v200, -v184, v195, v185
	v_fma_f32 v169, -v182, v194, v183
	v_div_fixup_f32 v164, v147, v164, 1.0
	v_div_fmas_f32 v147, v163, v188, v193
	s_mov_b64 vcc, s[16:17]
	v_rcp_f32_e32 v163, v155
	v_fmac_f32_e32 v195, v200, v190
	v_div_fixup_f32 v173, v147, v173, 1.0
	v_div_fmas_f32 v147, v169, v189, v194
	v_div_fixup_f32 v172, v147, v172, 1.0
	v_fma_f32 v147, -v184, v195, v185
	s_mov_b64 vcc, s[18:19]
	v_div_fmas_f32 v147, v147, v190, v195
	v_exp_f32_e32 v178, v178
	v_div_fixup_f32 v171, v147, v171, 1.0
	v_fma_f32 v147, -v155, v163, 1.0
	v_fmac_f32_e32 v163, v147, v163
	v_div_scale_f32 v147, vcc, 1.0, v170, 1.0
	v_mul_f32_e32 v169, v147, v163
	v_fma_f32 v180, -v155, v169, v147
	v_pk_add_f32 v[178:179], v[178:179], 1.0 op_sel_hi:[1,0]
	v_fmac_f32_e32 v169, v180, v163
	v_fma_f32 v147, -v155, v169, v147
	v_div_scale_f32 v155, s[6:7], v179, v179, 1.0
	v_rcp_f32_e32 v180, v155
	v_div_fmas_f32 v147, v147, v163, v169
	v_div_fixup_f32 v170, v147, v170, 1.0
	v_and_b32_e32 v181, 0xffff0000, v174
	v_fma_f32 v147, -v155, v180, 1.0
	v_fmac_f32_e32 v180, v147, v180
	v_div_scale_f32 v147, vcc, 1.0, v179, 1.0
	v_mul_f32_e32 v163, v147, v180
	v_fma_f32 v169, -v155, v163, v147
	v_fmac_f32_e32 v163, v169, v180
	v_fma_f32 v147, -v155, v163, v147
	v_div_scale_f32 v155, s[6:7], v178, v178, 1.0
	v_rcp_f32_e32 v169, v155
	v_div_fmas_f32 v147, v147, v180, v163
	v_div_fixup_f32 v179, v147, v179, 1.0
	v_lshlrev_b32_e32 v182, 16, v176
	v_fma_f32 v147, -v155, v169, 1.0
	v_fmac_f32_e32 v169, v147, v169
	v_div_scale_f32 v147, vcc, 1.0, v178, 1.0
	v_mul_f32_e32 v163, v147, v169
	v_fma_f32 v180, -v155, v163, v147
	v_fmac_f32_e32 v163, v180, v169
	v_fma_f32 v147, -v155, v163, v147
	v_div_fmas_f32 v147, v147, v169, v163
	v_div_fixup_f32 v178, v147, v178, 1.0
	v_lshlrev_b32_e32 v180, 16, v174
	v_and_b32_e32 v183, 0xffff0000, v176
	v_lshlrev_b32_e32 v176, 16, v177
	v_and_b32_e32 v177, 0xffff0000, v177
	v_lshlrev_b32_e32 v174, 16, v175
	v_and_b32_e32 v175, 0xffff0000, v175
	v_pk_fma_f32 v[124:125], v[124:125], v[164:165], v[180:181]
	v_pk_fma_f32 v[164:165], v[122:123], v[178:179], v[176:177]
	v_pk_fma_f32 v[122:123], v[120:121], v[170:171], v[182:183]
	v_add_lshl_u32 v147, v146, v154, 1
	v_pk_fma_f32 v[126:127], v[126:127], v[172:173], v[174:175]
	v_cvt_pk_bf16_f32 v120, v124, v125
	s_nop 0
	v_cvt_pk_bf16_f32 v121, v126, v127
	v_cvt_pk_bf16_f32 v122, v122, v123
	v_cvt_pk_bf16_f32 v123, v164, v165
	buffer_store_dwordx4 v[120:123], v147, s[20:23], 0 offen sc1
	s_nop 0
	s_waitcnt vmcnt(9)
	v_mov_b32_e32 v120, v212
	v_mov_b32_e32 v121, v213
	v_mov_b32_e32 v122, v214
	v_mov_b32_e32 v123, v215
	v_mov_b32_e32 v124, v216
	v_mov_b32_e32 v125, v217
	v_mov_b32_e32 v126, v218
	v_mov_b32_e32 v127, v219
	v_add_u32_e32 v202, 0x67200, v201
	global_load_dwordx4 v[212:215], v202, s[36:37]
	v_add_u32_e32 v202, 0x66000, v201
	global_load_dwordx4 v[216:219], v202, s[36:37]
	v_lshlrev_b32_e32 v150, 16, v120
	v_and_b32_e32 v120, 0xffff0000, v120
	v_lshlrev_b32_e32 v151, 16, v121
	v_and_b32_e32 v121, 0xffff0000, v121
	v_lshlrev_b32_e32 v152, 16, v122
	v_and_b32_e32 v122, 0xffff0000, v122
	v_lshlrev_b32_e32 v153, 16, v123
	v_and_b32_e32 v154, 0xffff0000, v123
	v_mul_f32_e32 v123, 0xbfb8aa3b, v150
	v_mul_f32_e32 v150, 0xbfb8aa3b, v152
	v_mul_f32_e32 v152, 0xbfb8aa3b, v120
	v_mul_f32_e32 v151, 0xbfb8aa3b, v151
	v_mul_f32_e32 v121, 0xbfb8aa3b, v121
	v_mul_f32_e32 v155, 0xbfb8aa3b, v122
	v_exp_f32_e32 v120, v123
	v_exp_f32_e32 v122, v150
	v_exp_f32_e32 v150, v151
	v_exp_f32_e32 v151, v121
	v_exp_f32_e32 v121, v152
	v_mul_f32_e32 v153, 0xbfb8aa3b, v153
	v_exp_f32_e32 v152, v153
	v_exp_f32_e32 v123, v155
	v_pk_add_f32 v[120:121], v[120:121], 1.0 op_sel_hi:[1,0]
	v_pk_add_f32 v[150:151], v[150:151], 1.0 op_sel_hi:[1,0]
	v_div_scale_f32 v153, s[6:7], v121, v121, 1.0
	v_rcp_f32_e32 v163, v153
	v_div_scale_f32 v155, vcc, 1.0, v121, 1.0
	v_div_scale_f32 v164, s[6:7], v120, v120, 1.0
	v_fma_f32 v169, -v153, v163, 1.0
	v_fmac_f32_e32 v163, v169, v163
	v_mul_f32_e32 v169, v155, v163
	v_rcp_f32_e32 v165, v164
	v_fma_f32 v170, -v153, v169, v155
	v_fmac_f32_e32 v169, v170, v163
	v_fma_f32 v153, -v153, v169, v155
	v_div_fmas_f32 v153, v153, v163, v169
; __device__ __forceinline__ u32x4 pack8(const f32x4 v0, const f32x4 v1) { u32x4 w; w.x = pk2(v0[0], v0[1]); w.y = pk2(v0[2], v0[3]); w.z = pk2(v1[0], v1[1]); w.w = pk2(v1[2], v1[3]); return w; }
; __device__ __forceinline__ void unpack8(const u32x4 w, f32x4& v0, f32x4& v1) { v0 = (f32x4){bflo(w.x), bfhi(w.x), bflo(w.y), bfhi(w.y)}; v1 = (f32x4){bflo(w.z), bfhi(w.z), bflo(w.w), bfhi(w.w)}; }
; __device__ __forceinline__ float sigmoidf_(float x) { return 1.0f / (1.0f + __expf(-x)); }
;     __device__ __forceinline__ void operator()(const f32x4 (&acc)[2][2][4][2], const Unit& u, int wr, int wc, int fr, int fq) const {
;     ...
;                 const int row = row0 + ai * 128 + m * 16;
;                 const bf16_t* rowp = z + (size_t)row * DIN + col0;
; #pragma unroll
;                 for (int bj = 0; bj < 2; ++bj) {
;                     const u32x4 gw = *(const u32x4*)(rowp + O_GA + bj * 128);
;                     f32x4 g0, g1; unpack8(gw, g0, g1);
;                     f32x4 v0, v1;
; #pragma unroll
;                     for (int j = 0; j < 4; ++j) { v0[j] = sigmoidf_(g0[j]) * acc[ai][bj][m][0][j]; v1[j] = sigmoidf_(g1[j]) * acc[ai][bj][m][1][j]; }
;                     const u32x4 mw = *(const u32x4*)(rowp + bj * 128); f32x4 m0, m1; unpack8(mw, m0, m1); v0 += m0; v1 += m1;
;                     __builtin_amdgcn_raw_buffer_store_b128(pack8(v0, v1), rsrc, (unsigned)(((size_t)row * DIN + col0 + bj * 128) * 2), 0, 16  ); }
	v_div_fixup_f32 v121, v153, v121, 1.0
	v_fma_f32 v153, -v164, v165, 1.0
	v_fmac_f32_e32 v165, v153, v165
	v_div_scale_f32 v153, vcc, 1.0, v120, 1.0
	v_mul_f32_e32 v155, v153, v165
	v_fma_f32 v163, -v164, v155, v153
	v_fmac_f32_e32 v155, v163, v165
	v_div_scale_f32 v163, s[6:7], v151, v151, 1.0
	v_fma_f32 v153, -v164, v155, v153
	v_rcp_f32_e32 v164, v163
	v_div_fmas_f32 v153, v153, v165, v155
	v_div_fixup_f32 v120, v153, v120, 1.0
	v_pk_add_f32 v[122:123], v[122:123], 1.0 op_sel_hi:[1,0]
	v_fma_f32 v153, -v163, v164, 1.0
	v_fmac_f32_e32 v164, v153, v164
	v_div_scale_f32 v153, vcc, 1.0, v151, 1.0
	v_mul_f32_e32 v155, v153, v164
	v_fma_f32 v165, -v163, v155, v153
	v_fmac_f32_e32 v155, v165, v164
	v_fma_f32 v153, -v163, v155, v153
	v_div_scale_f32 v163, s[6:7], v150, v150, 1.0
	v_rcp_f32_e32 v165, v163
	v_div_fmas_f32 v153, v153, v164, v155
	v_div_fixup_f32 v151, v153, v151, 1.0
	v_fma_f32 v153, -v163, v165, 1.0
	v_fmac_f32_e32 v165, v153, v165
	v_div_scale_f32 v153, vcc, 1.0, v150, 1.0
	v_mul_f32_e32 v155, v153, v165
	v_fma_f32 v164, -v163, v155, v153
	v_fmac_f32_e32 v155, v164, v165
	v_fma_f32 v163, -v163, v155, v153
	v_mul_f32_e32 v153, 0xbfb8aa3b, v154
	v_div_scale_f32 v154, s[6:7], v123, v123, 1.0
	v_rcp_f32_e32 v164, v154
	v_div_fmas_f32 v155, v163, v165, v155
	v_div_fixup_f32 v150, v155, v150, 1.0
	v_exp_f32_e32 v153, v153
	v_fma_f32 v155, -v154, v164, 1.0
	v_fmac_f32_e32 v164, v155, v164
	v_div_scale_f32 v155, vcc, 1.0, v123, 1.0
	v_mul_f32_e32 v163, v155, v164
	v_fma_f32 v165, -v154, v163, v155
	v_fmac_f32_e32 v163, v165, v164
	v_fma_f32 v154, -v154, v163, v155
	v_div_scale_f32 v155, s[6:7], v122, v122, 1.0
	v_rcp_f32_e32 v165, v155
	v_div_fmas_f32 v154, v154, v164, v163
	v_div_fixup_f32 v123, v154, v123, 1.0
	v_pk_add_f32 v[152:153], v[152:153], 1.0 op_sel_hi:[1,0]
	v_fma_f32 v154, -v155, v165, 1.0
	v_fmac_f32_e32 v165, v154, v165
	v_div_scale_f32 v154, vcc, 1.0, v122, 1.0
	v_mul_f32_e32 v163, v154, v165
	v_fma_f32 v164, -v155, v163, v154
	v_fmac_f32_e32 v163, v164, v165
	v_fma_f32 v154, -v155, v163, v154
	v_div_scale_f32 v155, s[6:7], v153, v153, 1.0
	v_rcp_f32_e32 v164, v155
	v_div_fmas_f32 v154, v154, v165, v163
	v_div_fixup_f32 v122, v154, v122, 1.0
	v_fma_f32 v154, -v155, v164, 1.0
	v_fmac_f32_e32 v164, v154, v164
	v_div_scale_f32 v154, vcc, 1.0, v153, 1.0
	v_mul_f32_e32 v163, v154, v164
	v_fma_f32 v165, -v155, v163, v154
	v_fmac_f32_e32 v163, v165, v164
	v_fma_f32 v154, -v155, v163, v154
	v_div_scale_f32 v155, s[6:7], v152, v152, 1.0
	v_rcp_f32_e32 v165, v155
	v_div_fmas_f32 v154, v154, v164, v163
	v_div_fixup_f32 v153, v154, v153, 1.0
	v_fma_f32 v154, -v155, v165, 1.0
	v_fmac_f32_e32 v165, v154, v165
	v_div_scale_f32 v154, vcc, 1.0, v152, 1.0
	v_mul_f32_e32 v163, v154, v165
	v_fma_f32 v164, -v155, v163, v154
	v_fmac_f32_e32 v163, v164, v165
	v_fma_f32 v154, -v155, v163, v154
	v_div_fmas_f32 v154, v154, v165, v163
	v_div_fixup_f32 v152, v154, v152, 1.0
	v_lshlrev_b32_e32 v154, 16, v124
	v_and_b32_e32 v155, 0xffff0000, v124
	v_lshlrev_b32_e32 v164, 16, v126
	v_and_b32_e32 v165, 0xffff0000, v126
	v_lshlrev_b32_e32 v126, 16, v127
	v_and_b32_e32 v127, 0xffff0000, v127
	v_lshlrev_b32_e32 v124, 16, v125
	v_and_b32_e32 v125, 0xffff0000, v125
	v_pk_fma_f32 v[116:117], v[116:117], v[120:121], v[154:155]
	v_pk_fma_f32 v[120:121], v[114:115], v[152:153], v[126:127]
	v_pk_fma_f32 v[114:115], v[112:113], v[122:123], v[164:165]
	v_cvt_pk_bf16_f32 v112, v116, v117
	v_pk_fma_f32 v[118:119], v[118:119], v[150:151], v[124:125]
	s_nop 0
	v_cvt_pk_bf16_f32 v113, v118, v119
	v_cvt_pk_bf16_f32 v114, v114, v115
	v_cvt_pk_bf16_f32 v115, v120, v121
	buffer_store_dwordx4 v[112:115], v147, s[20:23], 0 offen offset:256 sc1
	s_nop 1
	v_or_b32_e32 v112, 16, v162
	v_mad_i64_i32 v[114:115], s[6:7], v112, s73, 0
	v_lshl_add_u64 v[112:113], v[114:115], 1, s[36:37]
	v_lshl_add_u64 v[112:113], v[112:113], 0, v[148:149]
	v_add_co_u32_e32 v116, vcc, s74, v112
	s_nop 1
	v_addc_co_u32_e32 v117, vcc, 0, v113, vcc
	s_waitcnt vmcnt(10)
	v_mov_b32_e32 v118, v232
	v_mov_b32_e32 v119, v233
	v_mov_b32_e32 v120, v234
	v_mov_b32_e32 v121, v235
	v_mov_b32_e32 v122, v236
	v_mov_b32_e32 v123, v237
	v_mov_b32_e32 v124, v238
	v_mov_b32_e32 v125, v239
	v_add_u32_e32 v202, 0x67300, v201
	global_load_dwordx4 v[232:235], v202, s[36:37]
	v_add_u32_e32 v202, 0x66100, v201
	global_load_dwordx4 v[236:239], v202, s[36:37]
	v_lshlrev_b32_e32 v115, 16, v118
	v_lshlrev_b32_e32 v127, 16, v119
	v_and_b32_e32 v147, 0xffff0000, v119
	v_lshlrev_b32_e32 v119, 16, v120
	v_mul_f32_e32 v115, 0xbfb8aa3b, v115
	v_and_b32_e32 v126, 0xffff0000, v118
	v_exp_f32_e32 v118, v115
	v_mul_f32_e32 v115, 0xbfb8aa3b, v119
	v_and_b32_e32 v150, 0xffff0000, v120
	v_exp_f32_e32 v120, v115
	v_mul_f32_e32 v115, 0xbfb8aa3b, v126
	v_exp_f32_e32 v119, v115
	v_mul_f32_e32 v115, 0xbfb8aa3b, v150
	v_lshlrev_b32_e32 v151, 16, v121
	v_and_b32_e32 v152, 0xffff0000, v121
	v_exp_f32_e32 v121, v115
	v_mul_f32_e32 v115, 0xbfb8aa3b, v127
	v_exp_f32_e32 v126, v115
	v_mul_f32_e32 v115, 0xbfb8aa3b, v147
	v_pk_add_f32 v[118:119], v[118:119], 1.0 op_sel_hi:[1,0]
	v_exp_f32_e32 v127, v115
	v_div_scale_f32 v115, s[6:7], v119, v119, 1.0
	v_rcp_f32_e32 v147, v115
	v_mul_f32_e32 v150, 0xbfb8aa3b, v151
	v_pk_add_f32 v[126:127], v[126:127], 1.0 op_sel_hi:[1,0]
	v_pk_add_f32 v[120:121], v[120:121], 1.0 op_sel_hi:[1,0]
	v_fma_f32 v151, -v115, v147, 1.0
	v_fmac_f32_e32 v147, v151, v147
	v_div_scale_f32 v151, vcc, 1.0, v119, 1.0
	v_mul_f32_e32 v153, v151, v147
	v_fma_f32 v154, -v115, v153, v151
	v_fmac_f32_e32 v153, v154, v147
	v_fma_f32 v115, -v115, v153, v151
	v_div_scale_f32 v151, s[6:7], v118, v118, 1.0
	v_rcp_f32_e32 v154, v151
; __device__ __forceinline__ u32x4 pack8(const f32x4 v0, const f32x4 v1) { u32x4 w; w.x = pk2(v0[0], v0[1]); w.y = pk2(v0[2], v0[3]); w.z = pk2(v1[0], v1[1]); w.w = pk2(v1[2], v1[3]); return w; }
; __device__ __forceinline__ void unpack8(const u32x4 w, f32x4& v0, f32x4& v1) { v0 = (f32x4){bflo(w.x), bfhi(w.x), bflo(w.y), bfhi(w.y)}; v1 = (f32x4){bflo(w.z), bfhi(w.z), bflo(w.w), bfhi(w.w)}; }
; __device__ __forceinline__ float sigmoidf_(float x) { return 1.0f / (1.0f + __expf(-x)); }
;     __device__ __forceinline__ void operator()(const f32x4 (&acc)[2][2][4][2], const Unit& u, int wr, int wc, int fr, int fq) const {
;     ...
;                 const int row = row0 + ai * 128 + m * 16;
;                 const bf16_t* rowp = z + (size_t)row * DIN + col0;
; #pragma unroll
;                 for (int bj = 0; bj < 2; ++bj) {
;                     const u32x4 gw = *(const u32x4*)(rowp + O_GA + bj * 128);
;                     f32x4 g0, g1; unpack8(gw, g0, g1);
;                     f32x4 v0, v1;
; #pragma unroll
;                     for (int j = 0; j < 4; ++j) { v0[j] = sigmoidf_(g0[j]) * acc[ai][bj][m][0][j]; v1[j] = sigmoidf_(g1[j]) * acc[ai][bj][m][1][j]; }
;                     const u32x4 mw = *(const u32x4*)(rowp + bj * 128); f32x4 m0, m1; unpack8(mw, m0, m1); v0 += m0; v1 += m1;
;                     __builtin_amdgcn_raw_buffer_store_b128(pack8(v0, v1), rsrc, (unsigned)(((size_t)row * DIN + col0 + bj * 128) * 2), 0, 16  ); }
	v_div_fmas_f32 v115, v115, v147, v153
	v_div_fixup_f32 v119, v115, v119, 1.0
	v_exp_f32_e32 v150, v150
	v_fma_f32 v115, -v151, v154, 1.0
	v_fmac_f32_e32 v154, v115, v154
	v_div_scale_f32 v115, vcc, 1.0, v118, 1.0
	v_mul_f32_e32 v147, v115, v154
	v_fma_f32 v153, -v151, v147, v115
	v_fmac_f32_e32 v147, v153, v154
	v_fma_f32 v115, -v151, v147, v115
	v_div_scale_f32 v151, s[6:7], v127, v127, 1.0
	v_rcp_f32_e32 v153, v151
	v_div_fmas_f32 v115, v115, v154, v147
	v_div_fixup_f32 v118, v115, v118, 1.0
	v_and_b32_e32 v155, 0xffff0000, v124
	v_fma_f32 v115, -v151, v153, 1.0
	v_fmac_f32_e32 v153, v115, v153
	v_div_scale_f32 v115, vcc, 1.0, v127, 1.0
	v_mul_f32_e32 v147, v115, v153
	v_fma_f32 v154, -v151, v147, v115
	v_fmac_f32_e32 v147, v154, v153
	v_fma_f32 v115, -v151, v147, v115
	v_div_scale_f32 v151, s[6:7], v126, v126, 1.0
	v_rcp_f32_e32 v154, v151
	v_div_fmas_f32 v115, v115, v153, v147
	v_div_fixup_f32 v127, v115, v127, 1.0
	v_fma_f32 v115, -v151, v154, 1.0
	v_fmac_f32_e32 v154, v115, v154
	v_div_scale_f32 v115, vcc, 1.0, v126, 1.0
	v_mul_f32_e32 v147, v115, v154
	v_fma_f32 v153, -v151, v147, v115
	v_fmac_f32_e32 v147, v153, v154
	v_fma_f32 v115, -v151, v147, v115
	v_mul_f32_e32 v151, 0xbfb8aa3b, v152
	v_div_scale_f32 v152, s[6:7], v121, v121, 1.0
	v_rcp_f32_e32 v153, v152
	v_div_fmas_f32 v115, v115, v154, v147
	v_div_fixup_f32 v126, v115, v126, 1.0
	v_exp_f32_e32 v151, v151
	v_fma_f32 v115, -v152, v153, 1.0
	v_fmac_f32_e32 v153, v115, v153
	v_div_scale_f32 v115, vcc, 1.0, v121, 1.0
	v_mul_f32_e32 v147, v115, v153
	v_fma_f32 v154, -v152, v147, v115
	v_fmac_f32_e32 v147, v154, v153
	v_fma_f32 v115, -v152, v147, v115
	v_div_scale_f32 v152, s[6:7], v120, v120, 1.0
	v_rcp_f32_e32 v154, v152
	v_div_fmas_f32 v115, v115, v153, v147
	v_div_fixup_f32 v121, v115, v121, 1.0
	v_pk_add_f32 v[150:151], v[150:151], 1.0 op_sel_hi:[1,0]
	v_fma_f32 v115, -v152, v154, 1.0
	v_fmac_f32_e32 v154, v115, v154
	v_div_scale_f32 v115, vcc, 1.0, v120, 1.0
	v_mul_f32_e32 v147, v115, v154
	v_fma_f32 v153, -v152, v147, v115
	v_fmac_f32_e32 v147, v153, v154
	v_fma_f32 v115, -v152, v147, v115
	v_div_scale_f32 v152, s[6:7], v151, v151, 1.0
	v_rcp_f32_e32 v153, v152
	v_div_fmas_f32 v115, v115, v154, v147
	v_div_fixup_f32 v120, v115, v120, 1.0
	v_fma_f32 v115, -v152, v153, 1.0
	v_fmac_f32_e32 v153, v115, v153
	v_div_scale_f32 v115, vcc, 1.0, v151, 1.0
	v_mul_f32_e32 v147, v115, v153
	v_fma_f32 v154, -v152, v147, v115
	v_fmac_f32_e32 v147, v154, v153
	v_fma_f32 v115, -v152, v147, v115
	v_div_scale_f32 v152, s[6:7], v150, v150, 1.0
	v_rcp_f32_e32 v154, v152
	v_div_fmas_f32 v115, v115, v153, v147
	v_div_fixup_f32 v151, v115, v151, 1.0
	v_fma_f32 v115, -v152, v154, 1.0
	v_fmac_f32_e32 v154, v115, v154
	v_div_scale_f32 v115, vcc, 1.0, v150, 1.0
	v_mul_f32_e32 v147, v115, v154
	v_fma_f32 v153, -v152, v147, v115
	v_fmac_f32_e32 v147, v153, v154
	v_fma_f32 v115, -v152, v147, v115
	v_div_fmas_f32 v115, v115, v154, v147
	v_div_fixup_f32 v150, v115, v150, 1.0
	v_lshlrev_b32_e32 v152, 16, v122
	v_and_b32_e32 v153, 0xffff0000, v122
	v_lshlrev_b32_e32 v154, 16, v124
	v_lshlrev_b32_e32 v124, 16, v125
	v_and_b32_e32 v125, 0xffff0000, v125
	v_lshlrev_b32_e32 v122, 16, v123
	v_and_b32_e32 v123, 0xffff0000, v123
	v_pk_fma_f32 v[108:109], v[108:109], v[118:119], v[152:153]
	v_pk_fma_f32 v[118:119], v[106:107], v[150:151], v[124:125]
	v_pk_fma_f32 v[106:107], v[104:105], v[120:121], v[154:155]
	v_add_lshl_u32 v120, v146, v114, 1
	v_pk_fma_f32 v[110:111], v[110:111], v[126:127], v[122:123]
	v_cvt_pk_bf16_f32 v104, v108, v109
	s_nop 0
	v_cvt_pk_bf16_f32 v105, v110, v111
	v_cvt_pk_bf16_f32 v106, v106, v107
	v_cvt_pk_bf16_f32 v107, v118, v119
	buffer_store_dwordx4 v[104:107], v120, s[20:23], 0 offen sc1
	s_nop 0
	s_waitcnt vmcnt(11)
	v_mov_b32_e32 v104, v240
	v_mov_b32_e32 v105, v241
	v_mov_b32_e32 v106, v242
	v_mov_b32_e32 v107, v243
	v_mov_b32_e32 v108, v244
	v_mov_b32_e32 v109, v245
	v_mov_b32_e32 v110, v246
	v_mov_b32_e32 v111, v247
	v_add_u32_e32 v202, 0x111200, v201
	global_load_dwordx4 v[240:243], v202, s[36:37]
	v_add_u32_e32 v202, 0x110000, v201
	global_load_dwordx4 v[244:247], v202, s[36:37]
	v_lshlrev_b32_e32 v114, 16, v105
	v_and_b32_e32 v115, 0xffff0000, v105
	v_lshlrev_b32_e32 v105, 16, v106
	v_lshlrev_b32_e32 v112, 16, v104
	v_and_b32_e32 v113, 0xffff0000, v104
	v_mul_f32_e32 v105, 0xbfb8aa3b, v105
	v_and_b32_e32 v116, 0xffff0000, v106
	v_mul_f32_e32 v104, 0xbfb8aa3b, v112
	v_exp_f32_e32 v106, v105
	v_mul_f32_e32 v105, 0xbfb8aa3b, v113
	v_exp_f32_e32 v104, v104
	v_exp_f32_e32 v105, v105
	v_mul_f32_e32 v113, 0xbfb8aa3b, v115
	v_lshlrev_b32_e32 v117, 16, v107
	v_and_b32_e32 v118, 0xffff0000, v107
	v_pk_add_f32 v[104:105], v[104:105], 1.0 op_sel_hi:[1,0]
	v_mul_f32_e32 v107, 0xbfb8aa3b, v116
	v_div_scale_f32 v115, s[6:7], v105, v105, 1.0
	v_rcp_f32_e32 v116, v115
	v_mul_f32_e32 v112, 0xbfb8aa3b, v114
	v_mul_f32_e32 v114, 0xbfb8aa3b, v117
	v_exp_f32_e32 v112, v112
	v_fma_f32 v117, -v115, v116, 1.0
	v_fmac_f32_e32 v116, v117, v116
	v_div_scale_f32 v117, vcc, 1.0, v105, 1.0
	v_mul_f32_e32 v119, v117, v116
	v_fma_f32 v121, -v115, v119, v117
	v_fmac_f32_e32 v119, v121, v116
	v_fma_f32 v115, -v115, v119, v117
	v_div_scale_f32 v117, s[6:7], v104, v104, 1.0
	v_rcp_f32_e32 v121, v117
	v_div_fmas_f32 v115, v115, v116, v119
	v_exp_f32_e32 v113, v113
	v_div_fixup_f32 v105, v115, v105, 1.0
	v_fma_f32 v115, -v117, v121, 1.0
	v_fmac_f32_e32 v121, v115, v121
	v_div_scale_f32 v115, vcc, 1.0, v104, 1.0
	v_mul_f32_e32 v116, v115, v121
	v_fma_f32 v119, -v117, v116, v115
	v_pk_add_f32 v[112:113], v[112:113], 1.0 op_sel_hi:[1,0]
	v_fmac_f32_e32 v116, v119, v121
	v_fma_f32 v115, -v117, v116, v115
; __device__ __forceinline__ u32x4 pack8(const f32x4 v0, const f32x4 v1) { u32x4 w; w.x = pk2(v0[0], v0[1]); w.y = pk2(v0[2], v0[3]); w.z = pk2(v1[0], v1[1]); w.w = pk2(v1[2], v1[3]); return w; }
; __device__ __forceinline__ void unpack8(const u32x4 w, f32x4& v0, f32x4& v1) { v0 = (f32x4){bflo(w.x), bfhi(w.x), bflo(w.y), bfhi(w.y)}; v1 = (f32x4){bflo(w.z), bfhi(w.z), bflo(w.w), bfhi(w.w)}; }
; __device__ __forceinline__ float sigmoidf_(float x) { return 1.0f / (1.0f + __expf(-x)); }
;     __device__ __forceinline__ void operator()(const f32x4 (&acc)[2][2][4][2], const Unit& u, int wr, int wc, int fr, int fq) const {
;     ...
;                 const int row = row0 + ai * 128 + m * 16;
;                 const bf16_t* rowp = z + (size_t)row * DIN + col0;
; #pragma unroll
;                 for (int bj = 0; bj < 2; ++bj) {
;                     const u32x4 gw = *(const u32x4*)(rowp + O_GA + bj * 128);
;                     f32x4 g0, g1; unpack8(gw, g0, g1);
;                     f32x4 v0, v1;
; #pragma unroll
;                     for (int j = 0; j < 4; ++j) { v0[j] = sigmoidf_(g0[j]) * acc[ai][bj][m][0][j]; v1[j] = sigmoidf_(g1[j]) * acc[ai][bj][m][1][j]; }
;                     const u32x4 mw = *(const u32x4*)(rowp + bj * 128); f32x4 m0, m1; unpack8(mw, m0, m1); v0 += m0; v1 += m1;
;                     __builtin_amdgcn_raw_buffer_store_b128(pack8(v0, v1), rsrc, (unsigned)(((size_t)row * DIN + col0 + bj * 128) * 2), 0, 16  ); }
	v_div_scale_f32 v117, s[6:7], v113, v113, 1.0
	v_rcp_f32_e32 v119, v117
	v_div_fmas_f32 v115, v115, v121, v116
	v_div_fixup_f32 v104, v115, v104, 1.0
	v_exp_f32_e32 v107, v107
	v_fma_f32 v115, -v117, v119, 1.0
	v_fmac_f32_e32 v119, v115, v119
	v_div_scale_f32 v115, vcc, 1.0, v113, 1.0
	v_mul_f32_e32 v116, v115, v119
	v_fma_f32 v121, -v117, v116, v115
	v_fmac_f32_e32 v116, v121, v119
	v_fma_f32 v115, -v117, v116, v115
	v_div_scale_f32 v117, s[6:7], v112, v112, 1.0
	v_rcp_f32_e32 v121, v117
	v_div_fmas_f32 v115, v115, v119, v116
	v_div_fixup_f32 v113, v115, v113, 1.0
	v_pk_add_f32 v[106:107], v[106:107], 1.0 op_sel_hi:[1,0]
	v_fma_f32 v115, -v117, v121, 1.0
	v_fmac_f32_e32 v121, v115, v121
	v_div_scale_f32 v115, vcc, 1.0, v112, 1.0
	v_mul_f32_e32 v116, v115, v121
	v_fma_f32 v119, -v117, v116, v115
	v_fmac_f32_e32 v116, v119, v121
	v_fma_f32 v117, -v117, v116, v115
	v_mul_f32_e32 v115, 0xbfb8aa3b, v118
	v_div_scale_f32 v118, s[6:7], v107, v107, 1.0
	v_rcp_f32_e32 v119, v118
	v_div_fmas_f32 v116, v117, v121, v116
	v_div_fixup_f32 v112, v116, v112, 1.0
	v_exp_f32_e32 v114, v114
	v_fma_f32 v116, -v118, v119, 1.0
	v_fmac_f32_e32 v119, v116, v119
	v_div_scale_f32 v116, vcc, 1.0, v107, 1.0
	v_mul_f32_e32 v117, v116, v119
	v_fma_f32 v121, -v118, v117, v116
	v_fmac_f32_e32 v117, v121, v119
	v_fma_f32 v116, -v118, v117, v116
	v_div_scale_f32 v118, s[6:7], v106, v106, 1.0
	v_rcp_f32_e32 v121, v118
	v_div_fmas_f32 v116, v116, v119, v117
	v_exp_f32_e32 v115, v115
	v_div_fixup_f32 v107, v116, v107, 1.0
	v_fma_f32 v116, -v118, v121, 1.0
	v_fmac_f32_e32 v121, v116, v121
	v_div_scale_f32 v116, vcc, 1.0, v106, 1.0
	v_mul_f32_e32 v117, v116, v121
	v_fma_f32 v119, -v118, v117, v116
	v_pk_add_f32 v[114:115], v[114:115], 1.0 op_sel_hi:[1,0]
	v_fmac_f32_e32 v117, v119, v121
	v_fma_f32 v116, -v118, v117, v116
	v_div_scale_f32 v118, s[6:7], v115, v115, 1.0
	v_rcp_f32_e32 v119, v118
	v_div_fmas_f32 v116, v116, v121, v117
	v_div_fixup_f32 v106, v116, v106, 1.0
	v_fma_f32 v116, -v118, v119, 1.0
	v_fmac_f32_e32 v119, v116, v119
	v_div_scale_f32 v116, vcc, 1.0, v115, 1.0
	v_mul_f32_e32 v117, v116, v119
	v_fma_f32 v121, -v118, v117, v116
	v_fmac_f32_e32 v117, v121, v119
	v_fma_f32 v116, -v118, v117, v116
	v_div_scale_f32 v118, s[6:7], v114, v114, 1.0
	v_rcp_f32_e32 v121, v118
	v_div_fmas_f32 v116, v116, v119, v117
	v_div_fixup_f32 v115, v116, v115, 1.0
	v_fma_f32 v116, -v118, v121, 1.0
	v_fmac_f32_e32 v121, v116, v121
	v_div_scale_f32 v116, vcc, 1.0, v114, 1.0
	v_mul_f32_e32 v117, v116, v121
	v_fma_f32 v119, -v118, v117, v116
	v_fmac_f32_e32 v117, v119, v121
	v_fma_f32 v116, -v118, v117, v116
	v_div_fmas_f32 v116, v116, v121, v117
	v_div_fixup_f32 v114, v116, v114, 1.0
	v_lshlrev_b32_e32 v116, 16, v108
	v_and_b32_e32 v117, 0xffff0000, v108
	v_lshlrev_b32_e32 v118, 16, v110
	v_and_b32_e32 v119, 0xffff0000, v110
	v_lshlrev_b32_e32 v110, 16, v111
	v_and_b32_e32 v111, 0xffff0000, v111
	v_lshlrev_b32_e32 v108, 16, v109
	v_and_b32_e32 v109, 0xffff0000, v109
	v_pk_fma_f32 v[100:101], v[100:101], v[104:105], v[116:117]
	v_pk_fma_f32 v[104:105], v[98:99], v[114:115], v[110:111]
	v_pk_fma_f32 v[98:99], v[96:97], v[106:107], v[118:119]
	v_cvt_pk_bf16_f32 v96, v100, v101
	v_pk_fma_f32 v[102:103], v[102:103], v[112:113], v[108:109]
	s_nop 0
	v_cvt_pk_bf16_f32 v97, v102, v103
	v_cvt_pk_bf16_f32 v98, v98, v99
	v_cvt_pk_bf16_f32 v99, v104, v105
	buffer_store_dwordx4 v[96:99], v120, s[20:23], 0 offen offset:256 sc1
	s_nop 1
	v_or_b32_e32 v96, 32, v162
	v_mad_i64_i32 v[98:99], s[6:7], v96, s73, 0
	v_lshl_add_u64 v[96:97], v[98:99], 1, s[36:37]
	v_lshl_add_u64 v[96:97], v[96:97], 0, v[148:149]
	v_add_co_u32_e32 v100, vcc, s74, v96
	s_nop 1
	v_addc_co_u32_e32 v101, vcc, 0, v97, vcc
	s_waitcnt vmcnt(12)
	v_mov_b32_e32 v102, v248
	v_mov_b32_e32 v103, v249
	v_mov_b32_e32 v104, v250
	v_mov_b32_e32 v105, v251
	v_mov_b32_e32 v106, v252
	v_mov_b32_e32 v107, v253
	v_mov_b32_e32 v108, v254
	v_mov_b32_e32 v109, v255
	v_add_u32_e32 v202, 0x111300, v201
	global_load_dwordx4 v[248:251], v202, s[36:37]
	v_add_u32_e32 v202, 0x110100, v201
	global_load_dwordx4 v[252:255], v202, s[36:37]
	v_lshlrev_b32_e32 v99, 16, v102
	v_lshlrev_b32_e32 v111, 16, v103
	v_and_b32_e32 v112, 0xffff0000, v103
	v_lshlrev_b32_e32 v103, 16, v104
	v_mul_f32_e32 v99, 0xbfb8aa3b, v99
	v_and_b32_e32 v110, 0xffff0000, v102
	v_exp_f32_e32 v102, v99
	v_mul_f32_e32 v99, 0xbfb8aa3b, v103
	v_and_b32_e32 v113, 0xffff0000, v104
	v_exp_f32_e32 v104, v99
	v_mul_f32_e32 v99, 0xbfb8aa3b, v110
	v_exp_f32_e32 v103, v99
	v_mul_f32_e32 v99, 0xbfb8aa3b, v113
	v_lshlrev_b32_e32 v114, 16, v105
	v_and_b32_e32 v115, 0xffff0000, v105
	v_exp_f32_e32 v105, v99
	v_mul_f32_e32 v99, 0xbfb8aa3b, v111
	v_exp_f32_e32 v110, v99
	v_mul_f32_e32 v99, 0xbfb8aa3b, v112
	v_pk_add_f32 v[102:103], v[102:103], 1.0 op_sel_hi:[1,0]
	v_exp_f32_e32 v111, v99
	v_div_scale_f32 v99, s[6:7], v103, v103, 1.0
	v_rcp_f32_e32 v113, v99
	v_mul_f32_e32 v112, 0xbfb8aa3b, v114
	v_pk_add_f32 v[110:111], v[110:111], 1.0 op_sel_hi:[1,0]
	v_pk_add_f32 v[104:105], v[104:105], 1.0 op_sel_hi:[1,0]
	v_fma_f32 v114, -v99, v113, 1.0
	v_fmac_f32_e32 v113, v114, v113
	v_div_scale_f32 v114, vcc, 1.0, v103, 1.0
	v_mul_f32_e32 v116, v114, v113
	v_fma_f32 v117, -v99, v116, v114
	v_fmac_f32_e32 v116, v117, v113
	v_fma_f32 v99, -v99, v116, v114
	v_div_scale_f32 v114, s[6:7], v102, v102, 1.0
	v_rcp_f32_e32 v117, v114
	v_div_fmas_f32 v99, v99, v113, v116
	v_div_fixup_f32 v103, v99, v103, 1.0
	v_exp_f32_e32 v112, v112
	v_fma_f32 v99, -v114, v117, 1.0
	v_fmac_f32_e32 v117, v99, v117
	v_div_scale_f32 v99, vcc, 1.0, v102, 1.0
	v_mul_f32_e32 v113, v99, v117
	v_fma_f32 v116, -v114, v113, v99
; __device__ __forceinline__ float sigmoidf_(float x) { return 1.0f / (1.0f + __expf(-x)); }
; __device__ __forceinline__ u32x4 pack8(const f32x4 v0, const f32x4 v1) { u32x4 w; w.x = pk2(v0[0], v0[1]); w.y = pk2(v0[2], v0[3]); w.z = pk2(v1[0], v1[1]); w.w = pk2(v1[2], v1[3]); return w; }
; __device__ __forceinline__ void unpack8(const u32x4 w, f32x4& v0, f32x4& v1) { v0 = (f32x4){bflo(w.x), bfhi(w.x), bflo(w.y), bfhi(w.y)}; v1 = (f32x4){bflo(w.z), bfhi(w.z), bflo(w.w), bfhi(w.w)}; }
;     __device__ __forceinline__ void operator()(const f32x4 (&acc)[2][2][4][2], const Unit& u, int wr, int wc, int fr, int fq) const {
;         const __amdgpu_buffer_rsrc_t rsrc = __builtin_amdgcn_make_buffer_rsrc((void*)z, 0, T_ALL * DIN * 2, 0x00020000);
;         const int row0 = row_off + u.pm * 256 + wr * 64 + fr, col0 = u.pn * 256 + wc * 32 + 8 * fq;
; #pragma unroll
;         for (int ai = 0; ai < 2; ++ai)
; #pragma unroll
;             for (int m = 0; m < 4; ++m) {
;                 const int row = row0 + ai * 128 + m * 16;
;                 const bf16_t* rowp = z + (size_t)row * DIN + col0;
; #pragma unroll
;                 for (int bj = 0; bj < 2; ++bj) {
;                     const u32x4 gw = *(const u32x4*)(rowp + O_GA + bj * 128);
;                     f32x4 g0, g1; unpack8(gw, g0, g1);
;                     f32x4 v0, v1;
; #pragma unroll
;                     for (int j = 0; j < 4; ++j) { v0[j] = sigmoidf_(g0[j]) * acc[ai][bj][m][0][j]; v1[j] = sigmoidf_(g1[j]) * acc[ai][bj][m][1][j]; }
;                     const u32x4 mw = *(const u32x4*)(rowp + bj * 128); f32x4 m0, m1; unpack8(mw, m0, m1); v0 += m0; v1 += m1;
;                     __builtin_amdgcn_raw_buffer_store_b128(pack8(v0, v1), rsrc, (unsigned)(((size_t)row * DIN + col0 + bj * 128) * 2), 0, 16  ); }
	v_fmac_f32_e32 v113, v116, v117
	v_fma_f32 v99, -v114, v113, v99
	v_div_scale_f32 v114, s[6:7], v111, v111, 1.0
	v_rcp_f32_e32 v116, v114
	v_div_fmas_f32 v99, v99, v117, v113
	v_div_fixup_f32 v102, v99, v102, 1.0
	v_fma_f32 v99, -v114, v116, 1.0
	v_fmac_f32_e32 v116, v99, v116
	v_div_scale_f32 v99, vcc, 1.0, v111, 1.0
	v_mul_f32_e32 v113, v99, v116
	v_fma_f32 v117, -v114, v113, v99
	v_fmac_f32_e32 v113, v117, v116
	v_fma_f32 v99, -v114, v113, v99
	v_div_scale_f32 v114, s[6:7], v110, v110, 1.0
	v_rcp_f32_e32 v117, v114
	v_div_fmas_f32 v99, v99, v116, v113
	v_div_fixup_f32 v111, v99, v111, 1.0
	v_fma_f32 v99, -v114, v117, 1.0
	v_fmac_f32_e32 v117, v99, v117
	v_div_scale_f32 v99, vcc, 1.0, v110, 1.0
	v_mul_f32_e32 v116, v99, v117
	v_fma_f32 v113, -v114, v116, v99
	v_fmac_f32_e32 v116, v113, v117
	v_fma_f32 v99, -v114, v116, v99
	v_div_scale_f32 v114, s[6:7], v105, v105, 1.0
	v_mul_f32_e32 v113, 0xbfb8aa3b, v115
	v_rcp_f32_e32 v115, v114
	v_div_fmas_f32 v99, v99, v117, v116
	v_div_fixup_f32 v110, v99, v110, 1.0
	v_exp_f32_e32 v113, v113
	v_fma_f32 v99, -v114, v115, 1.0
	v_fmac_f32_e32 v115, v99, v115
	v_div_scale_f32 v99, vcc, 1.0, v105, 1.0
	v_mul_f32_e32 v116, v99, v115
	v_fma_f32 v117, -v114, v116, v99
	v_fmac_f32_e32 v116, v117, v115
	v_fma_f32 v99, -v114, v116, v99
	v_div_scale_f32 v114, s[6:7], v104, v104, 1.0
	v_rcp_f32_e32 v117, v114
	v_div_fmas_f32 v99, v99, v115, v116
	v_div_fixup_f32 v105, v99, v105, 1.0
	v_pk_add_f32 v[112:113], v[112:113], 1.0 op_sel_hi:[1,0]
	v_fma_f32 v99, -v114, v117, 1.0
	v_fmac_f32_e32 v117, v99, v117
	v_div_scale_f32 v99, vcc, 1.0, v104, 1.0
	v_mul_f32_e32 v115, v99, v117
	v_fma_f32 v116, -v114, v115, v99
	v_fmac_f32_e32 v115, v116, v117
	v_fma_f32 v99, -v114, v115, v99
	v_div_scale_f32 v114, s[6:7], v113, v113, 1.0
	v_rcp_f32_e32 v116, v114
	v_div_fmas_f32 v99, v99, v117, v115
	v_div_fixup_f32 v104, v99, v104, 1.0
	v_fma_f32 v99, -v114, v116, 1.0
	v_fmac_f32_e32 v116, v99, v116
	v_div_scale_f32 v99, vcc, 1.0, v113, 1.0
	v_mul_f32_e32 v115, v99, v116
	v_fma_f32 v117, -v114, v115, v99
	v_fmac_f32_e32 v115, v117, v116
	v_fma_f32 v99, -v114, v115, v99
	v_div_scale_f32 v114, s[6:7], v112, v112, 1.0
	v_rcp_f32_e32 v117, v114
	v_div_fmas_f32 v99, v99, v116, v115
	v_div_fixup_f32 v113, v99, v113, 1.0
	v_fma_f32 v99, -v114, v117, 1.0
	v_fmac_f32_e32 v117, v99, v117
	v_div_scale_f32 v99, vcc, 1.0, v112, 1.0
	v_mul_f32_e32 v115, v99, v117
	v_fma_f32 v116, -v114, v115, v99
	v_fmac_f32_e32 v115, v116, v117
	v_fma_f32 v99, -v114, v115, v99
	v_div_fmas_f32 v99, v99, v117, v115
	v_div_fixup_f32 v112, v99, v112, 1.0
	v_lshlrev_b32_e32 v114, 16, v106
	v_and_b32_e32 v115, 0xffff0000, v106
	v_lshlrev_b32_e32 v116, 16, v108
	v_and_b32_e32 v117, 0xffff0000, v108
	v_lshlrev_b32_e32 v108, 16, v109
	v_and_b32_e32 v109, 0xffff0000, v109
	v_lshlrev_b32_e32 v106, 16, v107
	v_and_b32_e32 v107, 0xffff0000, v107
	v_pk_fma_f32 v[92:93], v[92:93], v[102:103], v[114:115]
	v_pk_fma_f32 v[102:103], v[90:91], v[112:113], v[108:109]
	v_pk_fma_f32 v[90:91], v[88:89], v[104:105], v[116:117]
	v_add_lshl_u32 v104, v146, v98, 1
	v_pk_fma_f32 v[94:95], v[94:95], v[110:111], v[106:107]
	v_cvt_pk_bf16_f32 v88, v92, v93
	s_nop 0
	v_cvt_pk_bf16_f32 v89, v94, v95
	v_cvt_pk_bf16_f32 v90, v90, v91
	v_cvt_pk_bf16_f32 v91, v102, v103
	buffer_store_dwordx4 v[88:91], v104, s[20:23], 0 offen sc1
	s_nop 0
	s_waitcnt vmcnt(13)
	v_mov_b32_e32 v88, v204
	v_mov_b32_e32 v89, v205
	v_mov_b32_e32 v90, v206
	v_mov_b32_e32 v91, v207
	v_mov_b32_e32 v92, v208
	v_mov_b32_e32 v93, v209
	v_mov_b32_e32 v94, v210
	v_mov_b32_e32 v95, v211
	v_add_u32_e32 v202, 0x133200, v201
	global_load_dwordx4 v[204:207], v202, s[36:37]
	v_add_u32_e32 v202, 0x132000, v201
	global_load_dwordx4 v[208:211], v202, s[36:37]
	v_lshlrev_b32_e32 v98, 16, v89
	v_and_b32_e32 v99, 0xffff0000, v89
	v_lshlrev_b32_e32 v89, 16, v90
	v_lshlrev_b32_e32 v96, 16, v88
	v_and_b32_e32 v97, 0xffff0000, v88
	v_mul_f32_e32 v89, 0xbfb8aa3b, v89
	v_and_b32_e32 v100, 0xffff0000, v90
	v_mul_f32_e32 v88, 0xbfb8aa3b, v96
	v_exp_f32_e32 v90, v89
	v_mul_f32_e32 v89, 0xbfb8aa3b, v97
	v_exp_f32_e32 v88, v88
	v_exp_f32_e32 v89, v89
	v_mul_f32_e32 v97, 0xbfb8aa3b, v99
	v_lshlrev_b32_e32 v101, 16, v91
	v_and_b32_e32 v102, 0xffff0000, v91
	v_pk_add_f32 v[88:89], v[88:89], 1.0 op_sel_hi:[1,0]
	v_mul_f32_e32 v91, 0xbfb8aa3b, v100
	v_div_scale_f32 v99, s[6:7], v89, v89, 1.0
	v_rcp_f32_e32 v100, v99
	v_mul_f32_e32 v96, 0xbfb8aa3b, v98
	v_mul_f32_e32 v98, 0xbfb8aa3b, v101
	v_exp_f32_e32 v96, v96
	v_fma_f32 v101, -v99, v100, 1.0
	v_fmac_f32_e32 v100, v101, v100
	v_div_scale_f32 v101, vcc, 1.0, v89, 1.0
	v_mul_f32_e32 v103, v101, v100
	v_fma_f32 v105, -v99, v103, v101
	v_fmac_f32_e32 v103, v105, v100
	v_fma_f32 v99, -v99, v103, v101
	v_div_scale_f32 v101, s[6:7], v88, v88, 1.0
	v_rcp_f32_e32 v105, v101
	v_div_fmas_f32 v99, v99, v100, v103
	v_exp_f32_e32 v97, v97
	v_div_fixup_f32 v89, v99, v89, 1.0
	v_fma_f32 v99, -v101, v105, 1.0
	v_fmac_f32_e32 v105, v99, v105
	v_div_scale_f32 v99, vcc, 1.0, v88, 1.0
	v_mul_f32_e32 v100, v99, v105
	v_fma_f32 v103, -v101, v100, v99
	v_pk_add_f32 v[96:97], v[96:97], 1.0 op_sel_hi:[1,0]
	v_fmac_f32_e32 v100, v103, v105
	v_fma_f32 v99, -v101, v100, v99
	v_div_scale_f32 v101, s[6:7], v97, v97, 1.0
	v_rcp_f32_e32 v103, v101
	v_div_fmas_f32 v99, v99, v105, v100
	v_div_fixup_f32 v88, v99, v88, 1.0
	v_exp_f32_e32 v91, v91
	v_fma_f32 v99, -v101, v103, 1.0
	v_fmac_f32_e32 v103, v99, v103
	v_div_scale_f32 v99, vcc, 1.0, v97, 1.0
	v_mul_f32_e32 v100, v99, v103
	v_fma_f32 v105, -v101, v100, v99
	v_fmac_f32_e32 v100, v105, v103
	v_fma_f32 v99, -v101, v100, v99
	v_div_scale_f32 v101, s[6:7], v96, v96, 1.0
; __device__ __forceinline__ float sigmoidf_(float x) { return 1.0f / (1.0f + __expf(-x)); }
; __device__ __forceinline__ u32x4 pack8(const f32x4 v0, const f32x4 v1) { u32x4 w; w.x = pk2(v0[0], v0[1]); w.y = pk2(v0[2], v0[3]); w.z = pk2(v1[0], v1[1]); w.w = pk2(v1[2], v1[3]); return w; }
; __device__ __forceinline__ void unpack8(const u32x4 w, f32x4& v0, f32x4& v1) { v0 = (f32x4){bflo(w.x), bfhi(w.x), bflo(w.y), bfhi(w.y)}; v1 = (f32x4){bflo(w.z), bfhi(w.z), bflo(w.w), bfhi(w.w)}; }
;     __device__ __forceinline__ void operator()(const f32x4 (&acc)[2][2][4][2], const Unit& u, int wr, int wc, int fr, int fq) const {
;     ...
;         for (int ai = 0; ai < 2; ++ai)
; #pragma unroll
;             for (int m = 0; m < 4; ++m) {
;                 const int row = row0 + ai * 128 + m * 16;
;                 const bf16_t* rowp = z + (size_t)row * DIN + col0;
; #pragma unroll
;                 for (int bj = 0; bj < 2; ++bj) {
;                     const u32x4 gw = *(const u32x4*)(rowp + O_GA + bj * 128);
;                     f32x4 g0, g1; unpack8(gw, g0, g1);
;                     f32x4 v0, v1;
; #pragma unroll
;                     for (int j = 0; j < 4; ++j) { v0[j] = sigmoidf_(g0[j]) * acc[ai][bj][m][0][j]; v1[j] = sigmoidf_(g1[j]) * acc[ai][bj][m][1][j]; }
;                     const u32x4 mw = *(const u32x4*)(rowp + bj * 128); f32x4 m0, m1; unpack8(mw, m0, m1); v0 += m0; v1 += m1;
;                     __builtin_amdgcn_raw_buffer_store_b128(pack8(v0, v1), rsrc, (unsigned)(((size_t)row * DIN + col0 + bj * 128) * 2), 0, 16  ); }
	v_rcp_f32_e32 v105, v101
	v_div_fmas_f32 v99, v99, v103, v100
	v_div_fixup_f32 v97, v99, v97, 1.0
	v_pk_add_f32 v[90:91], v[90:91], 1.0 op_sel_hi:[1,0]
	v_fma_f32 v99, -v101, v105, 1.0
	v_fmac_f32_e32 v105, v99, v105
	v_div_scale_f32 v99, vcc, 1.0, v96, 1.0
	v_mul_f32_e32 v100, v99, v105
	v_fma_f32 v103, -v101, v100, v99
	v_fmac_f32_e32 v100, v103, v105
	v_fma_f32 v101, -v101, v100, v99
	v_mul_f32_e32 v99, 0xbfb8aa3b, v102
	v_div_scale_f32 v102, s[6:7], v91, v91, 1.0
	v_rcp_f32_e32 v103, v102
	v_div_fmas_f32 v100, v101, v105, v100
	v_div_fixup_f32 v96, v100, v96, 1.0
	v_exp_f32_e32 v98, v98
	v_fma_f32 v100, -v102, v103, 1.0
	v_fmac_f32_e32 v103, v100, v103
	v_div_scale_f32 v100, vcc, 1.0, v91, 1.0
	v_mul_f32_e32 v101, v100, v103
	v_fma_f32 v105, -v102, v101, v100
	v_fmac_f32_e32 v101, v105, v103
	v_fma_f32 v100, -v102, v101, v100
	v_div_scale_f32 v102, s[6:7], v90, v90, 1.0
	v_rcp_f32_e32 v105, v102
	v_div_fmas_f32 v100, v100, v103, v101
	v_exp_f32_e32 v99, v99
	v_div_fixup_f32 v91, v100, v91, 1.0
	v_fma_f32 v100, -v102, v105, 1.0
	v_fmac_f32_e32 v105, v100, v105
	v_div_scale_f32 v100, vcc, 1.0, v90, 1.0
	v_mul_f32_e32 v101, v100, v105
	v_fma_f32 v103, -v102, v101, v100
	v_pk_add_f32 v[98:99], v[98:99], 1.0 op_sel_hi:[1,0]
	v_fmac_f32_e32 v101, v103, v105
	v_fma_f32 v100, -v102, v101, v100
	v_div_scale_f32 v102, s[6:7], v99, v99, 1.0
	v_rcp_f32_e32 v103, v102
	v_div_fmas_f32 v100, v100, v105, v101
	v_div_fixup_f32 v90, v100, v90, 1.0
	v_fma_f32 v100, -v102, v103, 1.0
	v_fmac_f32_e32 v103, v100, v103
	v_div_scale_f32 v100, vcc, 1.0, v99, 1.0
	v_mul_f32_e32 v101, v100, v103
	v_fma_f32 v105, -v102, v101, v100
	v_fmac_f32_e32 v101, v105, v103
	v_fma_f32 v100, -v102, v101, v100
	v_div_scale_f32 v102, s[6:7], v98, v98, 1.0
	v_rcp_f32_e32 v105, v102
	v_div_fmas_f32 v100, v100, v103, v101
	v_div_fixup_f32 v99, v100, v99, 1.0
	v_fma_f32 v100, -v102, v105, 1.0
	v_fmac_f32_e32 v105, v100, v105
	v_div_scale_f32 v100, vcc, 1.0, v98, 1.0
	v_mul_f32_e32 v101, v100, v105
	v_fma_f32 v103, -v102, v101, v100
	v_fmac_f32_e32 v101, v103, v105
	v_fma_f32 v100, -v102, v101, v100
	v_div_fmas_f32 v100, v100, v105, v101
	v_div_fixup_f32 v98, v100, v98, 1.0
	v_lshlrev_b32_e32 v100, 16, v92
	v_and_b32_e32 v101, 0xffff0000, v92
	v_lshlrev_b32_e32 v102, 16, v94
	v_and_b32_e32 v103, 0xffff0000, v94
	v_lshlrev_b32_e32 v94, 16, v95
	v_and_b32_e32 v95, 0xffff0000, v95
	v_lshlrev_b32_e32 v92, 16, v93
	v_and_b32_e32 v93, 0xffff0000, v93
	v_pk_fma_f32 v[84:85], v[84:85], v[88:89], v[100:101]
	v_pk_fma_f32 v[88:89], v[82:83], v[98:99], v[94:95]
	v_pk_fma_f32 v[82:83], v[80:81], v[90:91], v[102:103]
	v_cvt_pk_bf16_f32 v80, v84, v85
	v_pk_fma_f32 v[86:87], v[86:87], v[96:97], v[92:93]
	s_nop 0
	v_cvt_pk_bf16_f32 v81, v86, v87
	v_cvt_pk_bf16_f32 v82, v82, v83
	v_cvt_pk_bf16_f32 v83, v88, v89
	buffer_store_dwordx4 v[80:83], v104, s[20:23], 0 offen offset:256 sc1
	s_nop 1
	v_or_b32_e32 v80, 48, v162
	v_mad_i64_i32 v[82:83], s[6:7], v80, s73, 0
	v_lshl_add_u64 v[80:81], v[82:83], 1, s[36:37]
	v_lshl_add_u64 v[80:81], v[80:81], 0, v[148:149]
	v_add_co_u32_e32 v84, vcc, s74, v80
	s_nop 1
	v_addc_co_u32_e32 v85, vcc, 0, v81, vcc
	s_waitcnt vmcnt(13)
	v_mov_b32_e32 v86, v212
	v_mov_b32_e32 v87, v213
	v_mov_b32_e32 v88, v214
	v_mov_b32_e32 v89, v215
	v_mov_b32_e32 v90, v216
	v_mov_b32_e32 v91, v217
	v_mov_b32_e32 v92, v218
	v_mov_b32_e32 v93, v219
	v_add_u32_e32 v202, 0x133300, v201
	global_load_dwordx4 v[212:215], v202, s[36:37]
	v_add_u32_e32 v202, 0x132100, v201
	global_load_dwordx4 v[216:219], v202, s[36:37]
	v_lshlrev_b32_e32 v83, 16, v86
	v_lshlrev_b32_e32 v95, 16, v87
	v_and_b32_e32 v96, 0xffff0000, v87
	v_lshlrev_b32_e32 v87, 16, v88
	v_mul_f32_e32 v83, 0xbfb8aa3b, v83
	v_and_b32_e32 v94, 0xffff0000, v86
	v_exp_f32_e32 v86, v83
	v_mul_f32_e32 v83, 0xbfb8aa3b, v87
	v_and_b32_e32 v97, 0xffff0000, v88
	v_exp_f32_e32 v88, v83
	v_mul_f32_e32 v83, 0xbfb8aa3b, v94
	v_exp_f32_e32 v87, v83
	v_mul_f32_e32 v83, 0xbfb8aa3b, v97
	v_lshlrev_b32_e32 v98, 16, v89
	v_and_b32_e32 v99, 0xffff0000, v89
	v_exp_f32_e32 v89, v83
	v_mul_f32_e32 v83, 0xbfb8aa3b, v95
	v_exp_f32_e32 v94, v83
	v_mul_f32_e32 v83, 0xbfb8aa3b, v96
	v_pk_add_f32 v[86:87], v[86:87], 1.0 op_sel_hi:[1,0]
	v_exp_f32_e32 v95, v83
	v_div_scale_f32 v83, s[6:7], v87, v87, 1.0
	v_rcp_f32_e32 v97, v83
	v_mul_f32_e32 v96, 0xbfb8aa3b, v98
	v_pk_add_f32 v[94:95], v[94:95], 1.0 op_sel_hi:[1,0]
	v_pk_add_f32 v[88:89], v[88:89], 1.0 op_sel_hi:[1,0]
	v_fma_f32 v98, -v83, v97, 1.0
	v_fmac_f32_e32 v97, v98, v97
	v_div_scale_f32 v98, vcc, 1.0, v87, 1.0
	v_mul_f32_e32 v100, v98, v97
	v_fma_f32 v101, -v83, v100, v98
	v_fmac_f32_e32 v100, v101, v97
	v_fma_f32 v83, -v83, v100, v98
	v_div_scale_f32 v98, s[6:7], v86, v86, 1.0
	v_rcp_f32_e32 v101, v98
	v_div_fmas_f32 v83, v83, v97, v100
	v_div_fixup_f32 v87, v83, v87, 1.0
	v_exp_f32_e32 v96, v96
	v_fma_f32 v83, -v98, v101, 1.0
	v_fmac_f32_e32 v101, v83, v101
	v_div_scale_f32 v83, vcc, 1.0, v86, 1.0
	v_mul_f32_e32 v97, v83, v101
	v_fma_f32 v100, -v98, v97, v83
	v_fmac_f32_e32 v97, v100, v101
	v_fma_f32 v83, -v98, v97, v83
	v_div_scale_f32 v98, s[6:7], v95, v95, 1.0
	v_rcp_f32_e32 v100, v98
	v_div_fmas_f32 v83, v83, v101, v97
	v_div_fixup_f32 v86, v83, v86, 1.0
	v_fma_f32 v83, -v98, v100, 1.0
	v_fmac_f32_e32 v100, v83, v100
	v_div_scale_f32 v83, vcc, 1.0, v95, 1.0
	v_mul_f32_e32 v97, v83, v100
	v_fma_f32 v101, -v98, v97, v83
	v_fmac_f32_e32 v97, v101, v100
	v_fma_f32 v83, -v98, v97, v83
	v_div_scale_f32 v98, s[6:7], v94, v94, 1.0
	v_rcp_f32_e32 v101, v98
	v_div_fmas_f32 v83, v83, v100, v97
	v_div_fixup_f32 v95, v83, v95, 1.0
	v_fma_f32 v83, -v98, v101, 1.0
	v_fmac_f32_e32 v101, v83, v101
; __device__ __forceinline__ float sigmoidf_(float x) { return 1.0f / (1.0f + __expf(-x)); }
; __device__ __forceinline__ u32x4 pack8(const f32x4 v0, const f32x4 v1) { u32x4 w; w.x = pk2(v0[0], v0[1]); w.y = pk2(v0[2], v0[3]); w.z = pk2(v1[0], v1[1]); w.w = pk2(v1[2], v1[3]); return w; }
; __device__ __forceinline__ void unpack8(const u32x4 w, f32x4& v0, f32x4& v1) { v0 = (f32x4){bflo(w.x), bfhi(w.x), bflo(w.y), bfhi(w.y)}; v1 = (f32x4){bflo(w.z), bfhi(w.z), bflo(w.w), bfhi(w.w)}; }
;     __device__ __forceinline__ void operator()(const f32x4 (&acc)[2][2][4][2], const Unit& u, int wr, int wc, int fr, int fq) const {
;     ...
;         for (int ai = 0; ai < 2; ++ai)
; #pragma unroll
;             for (int m = 0; m < 4; ++m) {
;                 const int row = row0 + ai * 128 + m * 16;
;                 const bf16_t* rowp = z + (size_t)row * DIN + col0;
; #pragma unroll
;                 for (int bj = 0; bj < 2; ++bj) {
;                     const u32x4 gw = *(const u32x4*)(rowp + O_GA + bj * 128);
;                     f32x4 g0, g1; unpack8(gw, g0, g1);
;                     f32x4 v0, v1;
; #pragma unroll
;                     for (int j = 0; j < 4; ++j) { v0[j] = sigmoidf_(g0[j]) * acc[ai][bj][m][0][j]; v1[j] = sigmoidf_(g1[j]) * acc[ai][bj][m][1][j]; }
;                     const u32x4 mw = *(const u32x4*)(rowp + bj * 128); f32x4 m0, m1; unpack8(mw, m0, m1); v0 += m0; v1 += m1;
;                     __builtin_amdgcn_raw_buffer_store_b128(pack8(v0, v1), rsrc, (unsigned)(((size_t)row * DIN + col0 + bj * 128) * 2), 0, 16  ); }
	v_div_scale_f32 v83, vcc, 1.0, v94, 1.0
	v_mul_f32_e32 v100, v83, v101
	v_fma_f32 v97, -v98, v100, v83
	v_fmac_f32_e32 v100, v97, v101
	v_fma_f32 v83, -v98, v100, v83
	v_div_scale_f32 v98, s[6:7], v89, v89, 1.0
	v_mul_f32_e32 v97, 0xbfb8aa3b, v99
	v_rcp_f32_e32 v99, v98
	v_div_fmas_f32 v83, v83, v101, v100
	v_div_fixup_f32 v94, v83, v94, 1.0
	v_exp_f32_e32 v97, v97
	v_fma_f32 v83, -v98, v99, 1.0
	v_fmac_f32_e32 v99, v83, v99
	v_div_scale_f32 v83, vcc, 1.0, v89, 1.0
	v_mul_f32_e32 v100, v83, v99
	v_fma_f32 v101, -v98, v100, v83
	v_fmac_f32_e32 v100, v101, v99
	v_fma_f32 v83, -v98, v100, v83
	v_div_scale_f32 v98, s[6:7], v88, v88, 1.0
	v_rcp_f32_e32 v101, v98
	v_div_fmas_f32 v83, v83, v99, v100
	v_div_fixup_f32 v89, v83, v89, 1.0
	v_pk_add_f32 v[96:97], v[96:97], 1.0 op_sel_hi:[1,0]
	v_fma_f32 v83, -v98, v101, 1.0
	v_fmac_f32_e32 v101, v83, v101
	v_div_scale_f32 v83, vcc, 1.0, v88, 1.0
	v_mul_f32_e32 v99, v83, v101
	v_fma_f32 v100, -v98, v99, v83
	v_fmac_f32_e32 v99, v100, v101
	v_fma_f32 v83, -v98, v99, v83
	v_div_scale_f32 v98, s[6:7], v97, v97, 1.0
	v_rcp_f32_e32 v100, v98
	v_div_fmas_f32 v83, v83, v101, v99
	v_div_fixup_f32 v88, v83, v88, 1.0
	v_fma_f32 v83, -v98, v100, 1.0
	v_fmac_f32_e32 v100, v83, v100
	v_div_scale_f32 v83, vcc, 1.0, v97, 1.0
	v_mul_f32_e32 v99, v83, v100
	v_fma_f32 v101, -v98, v99, v83
	v_fmac_f32_e32 v99, v101, v100
	v_fma_f32 v83, -v98, v99, v83
	v_div_scale_f32 v98, s[6:7], v96, v96, 1.0
	v_rcp_f32_e32 v101, v98
	v_div_fmas_f32 v83, v83, v100, v99
	v_div_fixup_f32 v97, v83, v97, 1.0
	v_fma_f32 v83, -v98, v101, 1.0
	v_fmac_f32_e32 v101, v83, v101
	v_div_scale_f32 v83, vcc, 1.0, v96, 1.0
	v_mul_f32_e32 v99, v83, v101
	v_fma_f32 v100, -v98, v99, v83
	v_fmac_f32_e32 v99, v100, v101
	v_fma_f32 v83, -v98, v99, v83
	v_div_fmas_f32 v83, v83, v101, v99
	v_div_fixup_f32 v96, v83, v96, 1.0
	v_lshlrev_b32_e32 v98, 16, v90
	v_and_b32_e32 v99, 0xffff0000, v90
	v_lshlrev_b32_e32 v100, 16, v92
	v_and_b32_e32 v101, 0xffff0000, v92
	v_lshlrev_b32_e32 v92, 16, v93
	v_and_b32_e32 v93, 0xffff0000, v93
	v_lshlrev_b32_e32 v90, 16, v91
	v_and_b32_e32 v91, 0xffff0000, v91
	v_pk_fma_f32 v[76:77], v[76:77], v[86:87], v[98:99]
	v_pk_fma_f32 v[86:87], v[74:75], v[96:97], v[92:93]
	v_pk_fma_f32 v[74:75], v[72:73], v[88:89], v[100:101]
	v_add_lshl_u32 v88, v146, v82, 1
	v_pk_fma_f32 v[78:79], v[78:79], v[94:95], v[90:91]
	v_cvt_pk_bf16_f32 v72, v76, v77
	s_nop 0
	v_cvt_pk_bf16_f32 v73, v78, v79
	v_cvt_pk_bf16_f32 v74, v74, v75
	v_cvt_pk_bf16_f32 v75, v86, v87
	buffer_store_dwordx4 v[72:75], v88, s[20:23], 0 offen sc1
	s_nop 0
	s_waitcnt vmcnt(13)
	v_mov_b32_e32 v72, v232
	v_mov_b32_e32 v73, v233
	v_mov_b32_e32 v74, v234
	v_mov_b32_e32 v75, v235
	v_mov_b32_e32 v76, v236
	v_mov_b32_e32 v77, v237
	v_mov_b32_e32 v78, v238
	v_mov_b32_e32 v79, v239
	v_add_u32_e32 v202, 0x155200, v201
	global_load_dwordx4 v[232:235], v202, s[36:37]
	v_add_u32_e32 v202, 0x154000, v201
	global_load_dwordx4 v[236:239], v202, s[36:37]
	v_lshlrev_b32_e32 v82, 16, v73
	v_and_b32_e32 v83, 0xffff0000, v73
	v_lshlrev_b32_e32 v73, 16, v74
	v_lshlrev_b32_e32 v80, 16, v72
	v_and_b32_e32 v81, 0xffff0000, v72
	v_mul_f32_e32 v73, 0xbfb8aa3b, v73
	v_and_b32_e32 v84, 0xffff0000, v74
	v_mul_f32_e32 v72, 0xbfb8aa3b, v80
	v_exp_f32_e32 v74, v73
	v_mul_f32_e32 v73, 0xbfb8aa3b, v81
	v_exp_f32_e32 v72, v72
	v_exp_f32_e32 v73, v73
	v_mul_f32_e32 v81, 0xbfb8aa3b, v83
	v_lshlrev_b32_e32 v85, 16, v75
	v_and_b32_e32 v86, 0xffff0000, v75
	v_pk_add_f32 v[72:73], v[72:73], 1.0 op_sel_hi:[1,0]
	v_mul_f32_e32 v75, 0xbfb8aa3b, v84
	v_div_scale_f32 v83, s[6:7], v73, v73, 1.0
	v_rcp_f32_e32 v84, v83
	v_mul_f32_e32 v80, 0xbfb8aa3b, v82
	v_mul_f32_e32 v82, 0xbfb8aa3b, v85
	v_exp_f32_e32 v80, v80
	v_fma_f32 v85, -v83, v84, 1.0
	v_fmac_f32_e32 v84, v85, v84
	v_div_scale_f32 v85, vcc, 1.0, v73, 1.0
	v_mul_f32_e32 v87, v85, v84
	v_fma_f32 v89, -v83, v87, v85
	v_fmac_f32_e32 v87, v89, v84
	v_fma_f32 v83, -v83, v87, v85
	v_div_scale_f32 v85, s[6:7], v72, v72, 1.0
	v_rcp_f32_e32 v89, v85
	v_div_fmas_f32 v83, v83, v84, v87
	v_exp_f32_e32 v81, v81
	v_div_fixup_f32 v73, v83, v73, 1.0
	v_fma_f32 v83, -v85, v89, 1.0
	v_fmac_f32_e32 v89, v83, v89
	v_div_scale_f32 v83, vcc, 1.0, v72, 1.0
	v_mul_f32_e32 v84, v83, v89
	v_fma_f32 v87, -v85, v84, v83
	v_pk_add_f32 v[80:81], v[80:81], 1.0 op_sel_hi:[1,0]
	v_fmac_f32_e32 v84, v87, v89
	v_fma_f32 v83, -v85, v84, v83
	v_div_scale_f32 v85, s[6:7], v81, v81, 1.0
	v_rcp_f32_e32 v87, v85
	v_div_fmas_f32 v83, v83, v89, v84
	v_div_fixup_f32 v72, v83, v72, 1.0
	v_exp_f32_e32 v75, v75
	v_fma_f32 v83, -v85, v87, 1.0
	v_fmac_f32_e32 v87, v83, v87
	v_div_scale_f32 v83, vcc, 1.0, v81, 1.0
	v_mul_f32_e32 v84, v83, v87
	v_fma_f32 v89, -v85, v84, v83
	v_fmac_f32_e32 v84, v89, v87
	v_fma_f32 v83, -v85, v84, v83
	v_div_scale_f32 v85, s[6:7], v80, v80, 1.0
	v_rcp_f32_e32 v89, v85
	v_div_fmas_f32 v83, v83, v87, v84
	v_div_fixup_f32 v81, v83, v81, 1.0
	v_pk_add_f32 v[74:75], v[74:75], 1.0 op_sel_hi:[1,0]
	v_fma_f32 v83, -v85, v89, 1.0
	v_fmac_f32_e32 v89, v83, v89
	v_div_scale_f32 v83, vcc, 1.0, v80, 1.0
	v_mul_f32_e32 v84, v83, v89
	v_fma_f32 v87, -v85, v84, v83
	v_fmac_f32_e32 v84, v87, v89
	v_fma_f32 v85, -v85, v84, v83
	v_mul_f32_e32 v83, 0xbfb8aa3b, v86
	v_div_scale_f32 v86, s[6:7], v75, v75, 1.0
	v_rcp_f32_e32 v87, v86
	v_div_fmas_f32 v84, v85, v89, v84
	v_div_fixup_f32 v80, v84, v80, 1.0
	v_exp_f32_e32 v82, v82
	v_fma_f32 v84, -v86, v87, 1.0
	v_fmac_f32_e32 v87, v84, v87
	v_div_scale_f32 v84, vcc, 1.0, v75, 1.0
	v_mul_f32_e32 v85, v84, v87
	v_fma_f32 v89, -v86, v85, v84
	v_fmac_f32_e32 v85, v89, v87
	v_fma_f32 v84, -v86, v85, v84
	v_div_scale_f32 v86, s[6:7], v74, v74, 1.0
; __device__ __forceinline__ float sigmoidf_(float x) { return 1.0f / (1.0f + __expf(-x)); }
; __device__ __forceinline__ u32x4 pack8(const f32x4 v0, const f32x4 v1) { u32x4 w; w.x = pk2(v0[0], v0[1]); w.y = pk2(v0[2], v0[3]); w.z = pk2(v1[0], v1[1]); w.w = pk2(v1[2], v1[3]); return w; }
; __device__ __forceinline__ void unpack8(const u32x4 w, f32x4& v0, f32x4& v1) { v0 = (f32x4){bflo(w.x), bfhi(w.x), bflo(w.y), bfhi(w.y)}; v1 = (f32x4){bflo(w.z), bfhi(w.z), bflo(w.w), bfhi(w.w)}; }
;     __device__ __forceinline__ void operator()(const f32x4 (&acc)[2][2][4][2], const Unit& u, int wr, int wc, int fr, int fq) const {
;     ...
;         for (int ai = 0; ai < 2; ++ai)
; #pragma unroll
;             for (int m = 0; m < 4; ++m) {
;                 const int row = row0 + ai * 128 + m * 16;
;                 const bf16_t* rowp = z + (size_t)row * DIN + col0;
; #pragma unroll
;                 for (int bj = 0; bj < 2; ++bj) {
;                     const u32x4 gw = *(const u32x4*)(rowp + O_GA + bj * 128);
;                     f32x4 g0, g1; unpack8(gw, g0, g1);
;                     f32x4 v0, v1;
; #pragma unroll
;                     for (int j = 0; j < 4; ++j) { v0[j] = sigmoidf_(g0[j]) * acc[ai][bj][m][0][j]; v1[j] = sigmoidf_(g1[j]) * acc[ai][bj][m][1][j]; }
;                     const u32x4 mw = *(const u32x4*)(rowp + bj * 128); f32x4 m0, m1; unpack8(mw, m0, m1); v0 += m0; v1 += m1;
;                     __builtin_amdgcn_raw_buffer_store_b128(pack8(v0, v1), rsrc, (unsigned)(((size_t)row * DIN + col0 + bj * 128) * 2), 0, 16  ); }
	v_rcp_f32_e32 v89, v86
	v_div_fmas_f32 v84, v84, v87, v85
	v_exp_f32_e32 v83, v83
	v_div_fixup_f32 v75, v84, v75, 1.0
	v_fma_f32 v84, -v86, v89, 1.0
	v_fmac_f32_e32 v89, v84, v89
	v_div_scale_f32 v84, vcc, 1.0, v74, 1.0
	v_mul_f32_e32 v85, v84, v89
	v_fma_f32 v87, -v86, v85, v84
	v_pk_add_f32 v[82:83], v[82:83], 1.0 op_sel_hi:[1,0]
	v_fmac_f32_e32 v85, v87, v89
	v_fma_f32 v84, -v86, v85, v84
	v_div_scale_f32 v86, s[6:7], v83, v83, 1.0
	v_rcp_f32_e32 v87, v86
	v_div_fmas_f32 v84, v84, v89, v85
	v_div_fixup_f32 v74, v84, v74, 1.0
	v_fma_f32 v84, -v86, v87, 1.0
	v_fmac_f32_e32 v87, v84, v87
	v_div_scale_f32 v84, vcc, 1.0, v83, 1.0
	v_mul_f32_e32 v85, v84, v87
	v_fma_f32 v89, -v86, v85, v84
	v_fmac_f32_e32 v85, v89, v87
	v_fma_f32 v84, -v86, v85, v84
	v_div_scale_f32 v86, s[6:7], v82, v82, 1.0
	v_rcp_f32_e32 v89, v86
	v_div_fmas_f32 v84, v84, v87, v85
	v_div_fixup_f32 v83, v84, v83, 1.0
	v_fma_f32 v84, -v86, v89, 1.0
	v_fmac_f32_e32 v89, v84, v89
	v_div_scale_f32 v84, vcc, 1.0, v82, 1.0
	v_mul_f32_e32 v85, v84, v89
	v_fma_f32 v87, -v86, v85, v84
	v_fmac_f32_e32 v85, v87, v89
	v_fma_f32 v84, -v86, v85, v84
	v_div_fmas_f32 v84, v84, v89, v85
	v_div_fixup_f32 v82, v84, v82, 1.0
	v_lshlrev_b32_e32 v84, 16, v76
	v_and_b32_e32 v85, 0xffff0000, v76
	v_lshlrev_b32_e32 v86, 16, v78
	v_and_b32_e32 v87, 0xffff0000, v78
	v_lshlrev_b32_e32 v78, 16, v79
	v_and_b32_e32 v79, 0xffff0000, v79
	v_lshlrev_b32_e32 v76, 16, v77
	v_and_b32_e32 v77, 0xffff0000, v77
	v_pk_fma_f32 v[68:69], v[68:69], v[72:73], v[84:85]
	v_pk_fma_f32 v[72:73], v[66:67], v[82:83], v[78:79]
	v_pk_fma_f32 v[66:67], v[64:65], v[74:75], v[86:87]
	v_cvt_pk_bf16_f32 v64, v68, v69
	v_pk_fma_f32 v[70:71], v[70:71], v[80:81], v[76:77]
	s_nop 0
	v_cvt_pk_bf16_f32 v65, v70, v71
	v_cvt_pk_bf16_f32 v66, v66, v67
	v_cvt_pk_bf16_f32 v67, v72, v73
	buffer_store_dwordx4 v[64:67], v88, s[20:23], 0 offen offset:256 sc1
	s_nop 1
	v_add_u32_e32 v64, 0x80, v162
	v_mad_i64_i32 v[66:67], s[6:7], v64, s73, 0
	v_lshl_add_u64 v[64:65], v[66:67], 1, s[36:37]
	v_lshl_add_u64 v[64:65], v[64:65], 0, v[148:149]
	v_add_co_u32_e32 v68, vcc, s74, v64
	s_nop 1
	v_addc_co_u32_e32 v69, vcc, 0, v65, vcc
	s_waitcnt vmcnt(13)
	v_mov_b32_e32 v70, v240
	v_mov_b32_e32 v71, v241
	v_mov_b32_e32 v72, v242
	v_mov_b32_e32 v73, v243
	v_mov_b32_e32 v74, v244
	v_mov_b32_e32 v75, v245
	v_mov_b32_e32 v76, v246
	v_mov_b32_e32 v77, v247
	v_add_u32_e32 v202, 0x155300, v201
	global_load_dwordx4 v[240:243], v202, s[36:37]
	v_add_u32_e32 v202, 0x154100, v201
	global_load_dwordx4 v[244:247], v202, s[36:37]
	v_lshlrev_b32_e32 v67, 16, v70
	v_lshlrev_b32_e32 v79, 16, v71
	v_and_b32_e32 v80, 0xffff0000, v71
	v_lshlrev_b32_e32 v71, 16, v72
	v_mul_f32_e32 v67, 0xbfb8aa3b, v67
	v_and_b32_e32 v78, 0xffff0000, v70
	v_exp_f32_e32 v70, v67
	v_mul_f32_e32 v67, 0xbfb8aa3b, v71
	v_and_b32_e32 v81, 0xffff0000, v72
	v_exp_f32_e32 v72, v67
	v_mul_f32_e32 v67, 0xbfb8aa3b, v78
	v_exp_f32_e32 v71, v67
	v_mul_f32_e32 v67, 0xbfb8aa3b, v81
	v_lshlrev_b32_e32 v82, 16, v73
	v_and_b32_e32 v83, 0xffff0000, v73
	v_exp_f32_e32 v73, v67
	v_mul_f32_e32 v67, 0xbfb8aa3b, v79
	v_exp_f32_e32 v78, v67
	v_mul_f32_e32 v67, 0xbfb8aa3b, v80
	v_pk_add_f32 v[70:71], v[70:71], 1.0 op_sel_hi:[1,0]
	v_exp_f32_e32 v79, v67
	v_div_scale_f32 v67, s[6:7], v71, v71, 1.0
	v_rcp_f32_e32 v81, v67
	v_mul_f32_e32 v80, 0xbfb8aa3b, v82
	v_pk_add_f32 v[78:79], v[78:79], 1.0 op_sel_hi:[1,0]
	v_pk_add_f32 v[72:73], v[72:73], 1.0 op_sel_hi:[1,0]
	v_fma_f32 v82, -v67, v81, 1.0
	v_fmac_f32_e32 v81, v82, v81
	v_div_scale_f32 v82, vcc, 1.0, v71, 1.0
	v_mul_f32_e32 v84, v82, v81
	v_fma_f32 v85, -v67, v84, v82
	v_fmac_f32_e32 v84, v85, v81
	v_fma_f32 v67, -v67, v84, v82
	v_div_scale_f32 v82, s[6:7], v70, v70, 1.0
	v_rcp_f32_e32 v85, v82
	v_div_fmas_f32 v67, v67, v81, v84
	v_div_fixup_f32 v71, v67, v71, 1.0
	v_exp_f32_e32 v80, v80
	v_fma_f32 v67, -v82, v85, 1.0
	v_fmac_f32_e32 v85, v67, v85
	v_div_scale_f32 v67, vcc, 1.0, v70, 1.0
	v_mul_f32_e32 v81, v67, v85
	v_fma_f32 v84, -v82, v81, v67
	v_fmac_f32_e32 v81, v84, v85
	v_fma_f32 v67, -v82, v81, v67
	v_div_scale_f32 v82, s[6:7], v79, v79, 1.0
	v_rcp_f32_e32 v84, v82
	v_div_fmas_f32 v67, v67, v85, v81
	v_div_fixup_f32 v70, v67, v70, 1.0
	v_fma_f32 v67, -v82, v84, 1.0
	v_fmac_f32_e32 v84, v67, v84
	v_div_scale_f32 v67, vcc, 1.0, v79, 1.0
	v_mul_f32_e32 v81, v67, v84
	v_fma_f32 v85, -v82, v81, v67
	v_fmac_f32_e32 v81, v85, v84
	v_fma_f32 v67, -v82, v81, v67
	v_div_scale_f32 v82, s[6:7], v78, v78, 1.0
	v_rcp_f32_e32 v85, v82
	v_div_fmas_f32 v67, v67, v84, v81
	v_div_fixup_f32 v79, v67, v79, 1.0
	v_fma_f32 v67, -v82, v85, 1.0
	v_fmac_f32_e32 v85, v67, v85
	v_div_scale_f32 v67, vcc, 1.0, v78, 1.0
	v_mul_f32_e32 v84, v67, v85
	v_fma_f32 v81, -v82, v84, v67
	v_fmac_f32_e32 v84, v81, v85
	v_fma_f32 v67, -v82, v84, v67
	v_div_scale_f32 v82, s[6:7], v73, v73, 1.0
	v_mul_f32_e32 v81, 0xbfb8aa3b, v83
	v_rcp_f32_e32 v83, v82
	v_div_fmas_f32 v67, v67, v85, v84
	v_div_fixup_f32 v78, v67, v78, 1.0
	v_exp_f32_e32 v81, v81
	v_fma_f32 v67, -v82, v83, 1.0
	v_fmac_f32_e32 v83, v67, v83
	v_div_scale_f32 v67, vcc, 1.0, v73, 1.0
	v_mul_f32_e32 v84, v67, v83
	v_fma_f32 v85, -v82, v84, v67
	v_fmac_f32_e32 v84, v85, v83
	v_fma_f32 v67, -v82, v84, v67
	v_div_scale_f32 v82, s[6:7], v72, v72, 1.0
	v_rcp_f32_e32 v85, v82
	v_div_fmas_f32 v67, v67, v83, v84
	v_div_fixup_f32 v73, v67, v73, 1.0
	v_pk_add_f32 v[80:81], v[80:81], 1.0 op_sel_hi:[1,0]
	v_fma_f32 v67, -v82, v85, 1.0
	v_fmac_f32_e32 v85, v67, v85
	v_div_scale_f32 v67, vcc, 1.0, v72, 1.0
	v_mul_f32_e32 v83, v67, v85
	v_fma_f32 v84, -v82, v83, v67
	v_fmac_f32_e32 v83, v84, v85
	v_fma_f32 v67, -v82, v83, v67
	v_div_scale_f32 v82, s[6:7], v81, v81, 1.0
; __device__ __forceinline__ float sigmoidf_(float x) { return 1.0f / (1.0f + __expf(-x)); }
; __device__ __forceinline__ u32x4 pack8(const f32x4 v0, const f32x4 v1) { u32x4 w; w.x = pk2(v0[0], v0[1]); w.y = pk2(v0[2], v0[3]); w.z = pk2(v1[0], v1[1]); w.w = pk2(v1[2], v1[3]); return w; }
; __device__ __forceinline__ void unpack8(const u32x4 w, f32x4& v0, f32x4& v1) { v0 = (f32x4){bflo(w.x), bfhi(w.x), bflo(w.y), bfhi(w.y)}; v1 = (f32x4){bflo(w.z), bfhi(w.z), bflo(w.w), bfhi(w.w)}; }
;     __device__ __forceinline__ void operator()(const f32x4 (&acc)[2][2][4][2], const Unit& u, int wr, int wc, int fr, int fq) const {
;     ...
;         for (int ai = 0; ai < 2; ++ai)
; #pragma unroll
;             for (int m = 0; m < 4; ++m) {
;                 const int row = row0 + ai * 128 + m * 16;
;                 const bf16_t* rowp = z + (size_t)row * DIN + col0;
; #pragma unroll
;                 for (int bj = 0; bj < 2; ++bj) {
;                     const u32x4 gw = *(const u32x4*)(rowp + O_GA + bj * 128);
;                     f32x4 g0, g1; unpack8(gw, g0, g1);
;                     f32x4 v0, v1;
; #pragma unroll
;                     for (int j = 0; j < 4; ++j) { v0[j] = sigmoidf_(g0[j]) * acc[ai][bj][m][0][j]; v1[j] = sigmoidf_(g1[j]) * acc[ai][bj][m][1][j]; }
;                     const u32x4 mw = *(const u32x4*)(rowp + bj * 128); f32x4 m0, m1; unpack8(mw, m0, m1); v0 += m0; v1 += m1;
;                     __builtin_amdgcn_raw_buffer_store_b128(pack8(v0, v1), rsrc, (unsigned)(((size_t)row * DIN + col0 + bj * 128) * 2), 0, 16  ); }
	v_rcp_f32_e32 v84, v82
	v_div_fmas_f32 v67, v67, v85, v83
	v_div_fixup_f32 v72, v67, v72, 1.0
	v_fma_f32 v67, -v82, v84, 1.0
	v_fmac_f32_e32 v84, v67, v84
	v_div_scale_f32 v67, vcc, 1.0, v81, 1.0
	v_mul_f32_e32 v83, v67, v84
	v_fma_f32 v85, -v82, v83, v67
	v_fmac_f32_e32 v83, v85, v84
	v_fma_f32 v67, -v82, v83, v67
	v_div_scale_f32 v82, s[6:7], v80, v80, 1.0
	v_rcp_f32_e32 v85, v82
	v_div_fmas_f32 v67, v67, v84, v83
	v_div_fixup_f32 v81, v67, v81, 1.0
	v_fma_f32 v67, -v82, v85, 1.0
	v_fmac_f32_e32 v85, v67, v85
	v_div_scale_f32 v67, vcc, 1.0, v80, 1.0
	v_mul_f32_e32 v83, v67, v85
	v_fma_f32 v84, -v82, v83, v67
	v_fmac_f32_e32 v83, v84, v85
	v_fma_f32 v67, -v82, v83, v67
	v_div_fmas_f32 v67, v67, v85, v83
	v_div_fixup_f32 v80, v67, v80, 1.0
	v_lshlrev_b32_e32 v82, 16, v74
	v_and_b32_e32 v83, 0xffff0000, v74
	v_lshlrev_b32_e32 v84, 16, v76
	v_and_b32_e32 v85, 0xffff0000, v76
	v_lshlrev_b32_e32 v76, 16, v77
	v_and_b32_e32 v77, 0xffff0000, v77
	v_lshlrev_b32_e32 v74, 16, v75
	v_and_b32_e32 v75, 0xffff0000, v75
	v_pk_fma_f32 v[60:61], v[60:61], v[70:71], v[82:83]
	v_pk_fma_f32 v[70:71], v[58:59], v[80:81], v[76:77]
	v_pk_fma_f32 v[58:59], v[56:57], v[72:73], v[84:85]
	v_add_lshl_u32 v72, v146, v66, 1
	v_pk_fma_f32 v[62:63], v[62:63], v[78:79], v[74:75]
	v_cvt_pk_bf16_f32 v56, v60, v61
	s_nop 0
	v_cvt_pk_bf16_f32 v57, v62, v63
	v_cvt_pk_bf16_f32 v58, v58, v59
	v_cvt_pk_bf16_f32 v59, v70, v71
	buffer_store_dwordx4 v[56:59], v72, s[20:23], 0 offen sc1
	s_nop 0
	s_waitcnt vmcnt(13)
	v_mov_b32_e32 v56, v248
	v_mov_b32_e32 v57, v249
	v_mov_b32_e32 v58, v250
	v_mov_b32_e32 v59, v251
	v_mov_b32_e32 v60, v252
	v_mov_b32_e32 v61, v253
	v_mov_b32_e32 v62, v254
	v_mov_b32_e32 v63, v255
	v_add_u32_e32 v202, 0x177200, v201
	global_load_dwordx4 v[248:251], v202, s[36:37]
	v_add_u32_e32 v202, 0x176000, v201
	global_load_dwordx4 v[252:255], v202, s[36:37]
	v_lshlrev_b32_e32 v66, 16, v57
	v_and_b32_e32 v67, 0xffff0000, v57
	v_lshlrev_b32_e32 v57, 16, v58
	v_lshlrev_b32_e32 v64, 16, v56
	v_and_b32_e32 v65, 0xffff0000, v56
	v_mul_f32_e32 v57, 0xbfb8aa3b, v57
	v_and_b32_e32 v68, 0xffff0000, v58
	v_mul_f32_e32 v56, 0xbfb8aa3b, v64
	v_exp_f32_e32 v58, v57
	v_mul_f32_e32 v57, 0xbfb8aa3b, v65
	v_exp_f32_e32 v56, v56
	v_exp_f32_e32 v57, v57
	v_mul_f32_e32 v65, 0xbfb8aa3b, v67
	v_lshlrev_b32_e32 v69, 16, v59
	v_and_b32_e32 v70, 0xffff0000, v59
	v_pk_add_f32 v[56:57], v[56:57], 1.0 op_sel_hi:[1,0]
	v_mul_f32_e32 v59, 0xbfb8aa3b, v68
	v_div_scale_f32 v67, s[6:7], v57, v57, 1.0
	v_rcp_f32_e32 v68, v67
	v_mul_f32_e32 v64, 0xbfb8aa3b, v66
	v_mul_f32_e32 v66, 0xbfb8aa3b, v69
	v_exp_f32_e32 v64, v64
	v_fma_f32 v69, -v67, v68, 1.0
	v_fmac_f32_e32 v68, v69, v68
	v_div_scale_f32 v69, vcc, 1.0, v57, 1.0
	v_mul_f32_e32 v71, v69, v68
	v_fma_f32 v73, -v67, v71, v69
	v_fmac_f32_e32 v71, v73, v68
	v_fma_f32 v67, -v67, v71, v69
	v_div_scale_f32 v69, s[6:7], v56, v56, 1.0
	v_rcp_f32_e32 v73, v69
	v_div_fmas_f32 v67, v67, v68, v71
	v_exp_f32_e32 v65, v65
	v_div_fixup_f32 v57, v67, v57, 1.0
	v_fma_f32 v67, -v69, v73, 1.0
	v_fmac_f32_e32 v73, v67, v73
	v_div_scale_f32 v67, vcc, 1.0, v56, 1.0
	v_mul_f32_e32 v68, v67, v73
	v_fma_f32 v71, -v69, v68, v67
	v_pk_add_f32 v[64:65], v[64:65], 1.0 op_sel_hi:[1,0]
	v_fmac_f32_e32 v68, v71, v73
	v_fma_f32 v67, -v69, v68, v67
	v_div_scale_f32 v69, s[6:7], v65, v65, 1.0
	v_rcp_f32_e32 v71, v69
	v_div_fmas_f32 v67, v67, v73, v68
	v_div_fixup_f32 v56, v67, v56, 1.0
	v_exp_f32_e32 v59, v59
	v_fma_f32 v67, -v69, v71, 1.0
	v_fmac_f32_e32 v71, v67, v71
	v_div_scale_f32 v67, vcc, 1.0, v65, 1.0
	v_mul_f32_e32 v68, v67, v71
	v_fma_f32 v73, -v69, v68, v67
	v_fmac_f32_e32 v68, v73, v71
	v_fma_f32 v67, -v69, v68, v67
	v_div_scale_f32 v69, s[6:7], v64, v64, 1.0
	v_rcp_f32_e32 v73, v69
	v_div_fmas_f32 v67, v67, v71, v68
	v_div_fixup_f32 v65, v67, v65, 1.0
	v_pk_add_f32 v[58:59], v[58:59], 1.0 op_sel_hi:[1,0]
	v_fma_f32 v67, -v69, v73, 1.0
	v_fmac_f32_e32 v73, v67, v73
	v_div_scale_f32 v67, vcc, 1.0, v64, 1.0
	v_mul_f32_e32 v68, v67, v73
	v_fma_f32 v71, -v69, v68, v67
	v_fmac_f32_e32 v68, v71, v73
	v_fma_f32 v69, -v69, v68, v67
	v_mul_f32_e32 v67, 0xbfb8aa3b, v70
	v_div_scale_f32 v70, s[6:7], v59, v59, 1.0
	v_rcp_f32_e32 v71, v70
	v_div_fmas_f32 v68, v69, v73, v68
	v_div_fixup_f32 v64, v68, v64, 1.0
	v_exp_f32_e32 v66, v66
	v_fma_f32 v68, -v70, v71, 1.0
	v_fmac_f32_e32 v71, v68, v71
	v_div_scale_f32 v68, vcc, 1.0, v59, 1.0
	v_mul_f32_e32 v69, v68, v71
	v_fma_f32 v73, -v70, v69, v68
	v_fmac_f32_e32 v69, v73, v71
	v_fma_f32 v68, -v70, v69, v68
	v_div_scale_f32 v70, s[6:7], v58, v58, 1.0
	v_rcp_f32_e32 v73, v70
	v_div_fmas_f32 v68, v68, v71, v69
	v_exp_f32_e32 v67, v67
	v_div_fixup_f32 v59, v68, v59, 1.0
	v_fma_f32 v68, -v70, v73, 1.0
	v_fmac_f32_e32 v73, v68, v73
	v_div_scale_f32 v68, vcc, 1.0, v58, 1.0
	v_mul_f32_e32 v69, v68, v73
	v_fma_f32 v71, -v70, v69, v68
	v_pk_add_f32 v[66:67], v[66:67], 1.0 op_sel_hi:[1,0]
	v_fmac_f32_e32 v69, v71, v73
	v_fma_f32 v68, -v70, v69, v68
	v_div_scale_f32 v70, s[6:7], v67, v67, 1.0
	v_rcp_f32_e32 v71, v70
	v_div_fmas_f32 v68, v68, v73, v69
	v_div_fixup_f32 v58, v68, v58, 1.0
	v_fma_f32 v68, -v70, v71, 1.0
	v_fmac_f32_e32 v71, v68, v71
	v_div_scale_f32 v68, vcc, 1.0, v67, 1.0
	v_mul_f32_e32 v69, v68, v71
	v_fma_f32 v73, -v70, v69, v68
	v_fmac_f32_e32 v69, v73, v71
	v_fma_f32 v68, -v70, v69, v68
	v_div_scale_f32 v70, s[6:7], v66, v66, 1.0
	v_rcp_f32_e32 v73, v70
	v_div_fmas_f32 v68, v68, v71, v69
	v_div_fixup_f32 v67, v68, v67, 1.0
	v_fma_f32 v68, -v70, v73, 1.0
	v_fmac_f32_e32 v73, v68, v73
	v_div_scale_f32 v68, vcc, 1.0, v66, 1.0
	v_mul_f32_e32 v69, v68, v73
	v_fma_f32 v71, -v70, v69, v68
	v_fmac_f32_e32 v69, v71, v73
	v_fma_f32 v68, -v70, v69, v68
	v_div_fmas_f32 v68, v68, v73, v69
	v_div_fixup_f32 v66, v68, v66, 1.0
	v_lshlrev_b32_e32 v68, 16, v60
	v_and_b32_e32 v69, 0xffff0000, v60
	v_lshlrev_b32_e32 v70, 16, v62
	v_and_b32_e32 v71, 0xffff0000, v62
	v_lshlrev_b32_e32 v62, 16, v63
	v_and_b32_e32 v63, 0xffff0000, v63
	v_lshlrev_b32_e32 v60, 16, v61
	v_and_b32_e32 v61, 0xffff0000, v61
	v_pk_fma_f32 v[52:53], v[52:53], v[56:57], v[68:69]
	v_pk_fma_f32 v[56:57], v[50:51], v[66:67], v[62:63]
	v_pk_fma_f32 v[50:51], v[48:49], v[58:59], v[70:71]
	v_cvt_pk_bf16_f32 v48, v52, v53
	v_pk_fma_f32 v[54:55], v[54:55], v[64:65], v[60:61]
	s_nop 0
	v_cvt_pk_bf16_f32 v49, v54, v55
	v_cvt_pk_bf16_f32 v50, v50, v51
	v_cvt_pk_bf16_f32 v51, v56, v57
	buffer_store_dwordx4 v[48:51], v72, s[20:23], 0 offen offset:256 sc1
	s_nop 1
	v_add_u32_e32 v48, 0x90, v162
	v_mad_i64_i32 v[50:51], s[6:7], v48, s73, 0
	v_lshl_add_u64 v[48:49], v[50:51], 1, s[36:37]
	v_lshl_add_u64 v[48:49], v[48:49], 0, v[148:149]
	v_add_co_u32_e32 v52, vcc, s74, v48
	s_nop 1
	v_addc_co_u32_e32 v53, vcc, 0, v49, vcc
	s_waitcnt vmcnt(13)
; __device__ __forceinline__ float sigmoidf_(float x) { return 1.0f / (1.0f + __expf(-x)); }
; __device__ __forceinline__ u32x4 pack8(const f32x4 v0, const f32x4 v1) { u32x4 w; w.x = pk2(v0[0], v0[1]); w.y = pk2(v0[2], v0[3]); w.z = pk2(v1[0], v1[1]); w.w = pk2(v1[2], v1[3]); return w; }
; __device__ __forceinline__ void unpack8(const u32x4 w, f32x4& v0, f32x4& v1) { v0 = (f32x4){bflo(w.x), bfhi(w.x), bflo(w.y), bfhi(w.y)}; v1 = (f32x4){bflo(w.z), bfhi(w.z), bflo(w.w), bfhi(w.w)}; }
;     __device__ __forceinline__ void operator()(const f32x4 (&acc)[2][2][4][2], const Unit& u, int wr, int wc, int fr, int fq) const {
;     ...
;         for (int ai = 0; ai < 2; ++ai)
; #pragma unroll
;             for (int m = 0; m < 4; ++m) {
;                 const int row = row0 + ai * 128 + m * 16;
;                 const bf16_t* rowp = z + (size_t)row * DIN + col0;
; #pragma unroll
;                 for (int bj = 0; bj < 2; ++bj) {
;                     const u32x4 gw = *(const u32x4*)(rowp + O_GA + bj * 128);
;                     f32x4 g0, g1; unpack8(gw, g0, g1);
;                     f32x4 v0, v1;
; #pragma unroll
;                     for (int j = 0; j < 4; ++j) { v0[j] = sigmoidf_(g0[j]) * acc[ai][bj][m][0][j]; v1[j] = sigmoidf_(g1[j]) * acc[ai][bj][m][1][j]; }
;                     const u32x4 mw = *(const u32x4*)(rowp + bj * 128); f32x4 m0, m1; unpack8(mw, m0, m1); v0 += m0; v1 += m1;
;                     __builtin_amdgcn_raw_buffer_store_b128(pack8(v0, v1), rsrc, (unsigned)(((size_t)row * DIN + col0 + bj * 128) * 2), 0, 16  ); }
	v_mov_b32_e32 v54, v204
	v_mov_b32_e32 v55, v205
	v_mov_b32_e32 v56, v206
	v_mov_b32_e32 v57, v207
	v_mov_b32_e32 v58, v208
	v_mov_b32_e32 v59, v209
	v_mov_b32_e32 v60, v210
	v_mov_b32_e32 v61, v211
	v_add_u32_e32 v202, 0x177300, v201
	global_load_dwordx4 v[204:207], v202, s[36:37]
	v_add_u32_e32 v202, 0x176100, v201
	global_load_dwordx4 v[208:211], v202, s[36:37]
	v_lshlrev_b32_e32 v51, 16, v54
	v_lshlrev_b32_e32 v63, 16, v55
	v_and_b32_e32 v64, 0xffff0000, v55
	v_lshlrev_b32_e32 v55, 16, v56
	v_mul_f32_e32 v51, 0xbfb8aa3b, v51
	v_and_b32_e32 v62, 0xffff0000, v54
	v_exp_f32_e32 v54, v51
	v_mul_f32_e32 v51, 0xbfb8aa3b, v55
	v_and_b32_e32 v65, 0xffff0000, v56
	v_exp_f32_e32 v56, v51
	v_mul_f32_e32 v51, 0xbfb8aa3b, v62
	v_exp_f32_e32 v55, v51
	v_mul_f32_e32 v51, 0xbfb8aa3b, v65
	v_lshlrev_b32_e32 v66, 16, v57
	v_and_b32_e32 v67, 0xffff0000, v57
	v_exp_f32_e32 v57, v51
	v_mul_f32_e32 v51, 0xbfb8aa3b, v63
	v_exp_f32_e32 v62, v51
	v_mul_f32_e32 v51, 0xbfb8aa3b, v64
	v_pk_add_f32 v[54:55], v[54:55], 1.0 op_sel_hi:[1,0]
	v_exp_f32_e32 v63, v51
	v_div_scale_f32 v51, s[6:7], v55, v55, 1.0
	v_rcp_f32_e32 v65, v51
	v_mul_f32_e32 v64, 0xbfb8aa3b, v66
	v_pk_add_f32 v[62:63], v[62:63], 1.0 op_sel_hi:[1,0]
	v_pk_add_f32 v[56:57], v[56:57], 1.0 op_sel_hi:[1,0]
	v_fma_f32 v66, -v51, v65, 1.0
	v_fmac_f32_e32 v65, v66, v65
	v_div_scale_f32 v66, vcc, 1.0, v55, 1.0
	v_mul_f32_e32 v68, v66, v65
	v_fma_f32 v69, -v51, v68, v66
	v_fmac_f32_e32 v68, v69, v65
	v_fma_f32 v51, -v51, v68, v66
	v_div_scale_f32 v66, s[6:7], v54, v54, 1.0
	v_rcp_f32_e32 v69, v66
	v_div_fmas_f32 v51, v51, v65, v68
	v_div_fixup_f32 v55, v51, v55, 1.0
	v_exp_f32_e32 v64, v64
	v_fma_f32 v51, -v66, v69, 1.0
	v_fmac_f32_e32 v69, v51, v69
	v_div_scale_f32 v51, vcc, 1.0, v54, 1.0
	v_mul_f32_e32 v65, v51, v69
	v_fma_f32 v68, -v66, v65, v51
	v_fmac_f32_e32 v65, v68, v69
	v_fma_f32 v51, -v66, v65, v51
	v_div_scale_f32 v66, s[6:7], v63, v63, 1.0
	v_rcp_f32_e32 v68, v66
	v_div_fmas_f32 v51, v51, v69, v65
	v_div_fixup_f32 v54, v51, v54, 1.0
	v_fma_f32 v51, -v66, v68, 1.0
	v_fmac_f32_e32 v68, v51, v68
	v_div_scale_f32 v51, vcc, 1.0, v63, 1.0
	v_mul_f32_e32 v65, v51, v68
	v_fma_f32 v69, -v66, v65, v51
	v_fmac_f32_e32 v65, v69, v68
	v_fma_f32 v51, -v66, v65, v51
	v_div_scale_f32 v66, s[6:7], v62, v62, 1.0
	v_rcp_f32_e32 v69, v66
	v_div_fmas_f32 v51, v51, v68, v65
	v_div_fixup_f32 v63, v51, v63, 1.0
	v_fma_f32 v51, -v66, v69, 1.0
	v_fmac_f32_e32 v69, v51, v69
	v_div_scale_f32 v51, vcc, 1.0, v62, 1.0
	v_mul_f32_e32 v68, v51, v69
	v_fma_f32 v65, -v66, v68, v51
	v_fmac_f32_e32 v68, v65, v69
	v_fma_f32 v51, -v66, v68, v51
	v_div_scale_f32 v66, s[6:7], v57, v57, 1.0
	v_mul_f32_e32 v65, 0xbfb8aa3b, v67
	v_rcp_f32_e32 v67, v66
	v_div_fmas_f32 v51, v51, v69, v68
	v_div_fixup_f32 v62, v51, v62, 1.0
	v_exp_f32_e32 v65, v65
	v_fma_f32 v51, -v66, v67, 1.0
	v_fmac_f32_e32 v67, v51, v67
	v_div_scale_f32 v51, vcc, 1.0, v57, 1.0
	v_mul_f32_e32 v68, v51, v67
	v_fma_f32 v69, -v66, v68, v51
	v_fmac_f32_e32 v68, v69, v67
	v_fma_f32 v51, -v66, v68, v51
	v_div_scale_f32 v66, s[6:7], v56, v56, 1.0
	v_rcp_f32_e32 v69, v66
	v_div_fmas_f32 v51, v51, v67, v68
	v_div_fixup_f32 v57, v51, v57, 1.0
	v_pk_add_f32 v[64:65], v[64:65], 1.0 op_sel_hi:[1,0]
	v_fma_f32 v51, -v66, v69, 1.0
	v_fmac_f32_e32 v69, v51, v69
	v_div_scale_f32 v51, vcc, 1.0, v56, 1.0
	v_mul_f32_e32 v67, v51, v69
	v_fma_f32 v68, -v66, v67, v51
	v_fmac_f32_e32 v67, v68, v69
	v_fma_f32 v51, -v66, v67, v51
	v_div_scale_f32 v66, s[6:7], v65, v65, 1.0
	v_rcp_f32_e32 v68, v66
	v_div_fmas_f32 v51, v51, v69, v67
	v_div_fixup_f32 v56, v51, v56, 1.0
	v_fma_f32 v51, -v66, v68, 1.0
	v_fmac_f32_e32 v68, v51, v68
	v_div_scale_f32 v51, vcc, 1.0, v65, 1.0
	v_mul_f32_e32 v67, v51, v68
	v_fma_f32 v69, -v66, v67, v51
	v_fmac_f32_e32 v67, v69, v68
	v_fma_f32 v51, -v66, v67, v51
	v_div_scale_f32 v66, s[6:7], v64, v64, 1.0
	v_rcp_f32_e32 v69, v66
	v_div_fmas_f32 v51, v51, v68, v67
	v_div_fixup_f32 v65, v51, v65, 1.0
	v_fma_f32 v51, -v66, v69, 1.0
	v_fmac_f32_e32 v69, v51, v69
	v_div_scale_f32 v51, vcc, 1.0, v64, 1.0
	v_mul_f32_e32 v67, v51, v69
	v_fma_f32 v68, -v66, v67, v51
	v_fmac_f32_e32 v67, v68, v69
	v_fma_f32 v51, -v66, v67, v51
	v_div_fmas_f32 v51, v51, v69, v67
	v_div_fixup_f32 v64, v51, v64, 1.0
	v_lshlrev_b32_e32 v66, 16, v58
	v_and_b32_e32 v67, 0xffff0000, v58
	v_lshlrev_b32_e32 v68, 16, v60
	v_and_b32_e32 v69, 0xffff0000, v60
	v_lshlrev_b32_e32 v60, 16, v61
	v_and_b32_e32 v61, 0xffff0000, v61
	v_lshlrev_b32_e32 v58, 16, v59
	v_and_b32_e32 v59, 0xffff0000, v59
	v_pk_fma_f32 v[44:45], v[44:45], v[54:55], v[66:67]
	v_pk_fma_f32 v[54:55], v[42:43], v[64:65], v[60:61]
	v_pk_fma_f32 v[42:43], v[40:41], v[56:57], v[68:69]
	v_add_lshl_u32 v56, v146, v50, 1
	v_pk_fma_f32 v[46:47], v[46:47], v[62:63], v[58:59]
	v_cvt_pk_bf16_f32 v40, v44, v45
	s_nop 0
	v_cvt_pk_bf16_f32 v41, v46, v47
	v_cvt_pk_bf16_f32 v42, v42, v43
	v_cvt_pk_bf16_f32 v43, v54, v55
	buffer_store_dwordx4 v[40:43], v56, s[20:23], 0 offen sc1
	s_nop 0
	s_waitcnt vmcnt(13)
; __device__ __forceinline__ float sigmoidf_(float x) { return 1.0f / (1.0f + __expf(-x)); }
; __device__ __forceinline__ u32x4 pack8(const f32x4 v0, const f32x4 v1) { u32x4 w; w.x = pk2(v0[0], v0[1]); w.y = pk2(v0[2], v0[3]); w.z = pk2(v1[0], v1[1]); w.w = pk2(v1[2], v1[3]); return w; }
; __device__ __forceinline__ void unpack8(const u32x4 w, f32x4& v0, f32x4& v1) { v0 = (f32x4){bflo(w.x), bfhi(w.x), bflo(w.y), bfhi(w.y)}; v1 = (f32x4){bflo(w.z), bfhi(w.z), bflo(w.w), bfhi(w.w)}; }
;     __device__ __forceinline__ void operator()(const f32x4 (&acc)[2][2][4][2], const Unit& u, int wr, int wc, int fr, int fq) const {
;     ...
;         for (int ai = 0; ai < 2; ++ai)
; #pragma unroll
;             for (int m = 0; m < 4; ++m) {
;                 const int row = row0 + ai * 128 + m * 16;
;                 const bf16_t* rowp = z + (size_t)row * DIN + col0;
; #pragma unroll
;                 for (int bj = 0; bj < 2; ++bj) {
;                     const u32x4 gw = *(const u32x4*)(rowp + O_GA + bj * 128);
;                     f32x4 g0, g1; unpack8(gw, g0, g1);
;                     f32x4 v0, v1;
; #pragma unroll
;                     for (int j = 0; j < 4; ++j) { v0[j] = sigmoidf_(g0[j]) * acc[ai][bj][m][0][j]; v1[j] = sigmoidf_(g1[j]) * acc[ai][bj][m][1][j]; }
;                     const u32x4 mw = *(const u32x4*)(rowp + bj * 128); f32x4 m0, m1; unpack8(mw, m0, m1); v0 += m0; v1 += m1;
;                     __builtin_amdgcn_raw_buffer_store_b128(pack8(v0, v1), rsrc, (unsigned)(((size_t)row * DIN + col0 + bj * 128) * 2), 0, 16  ); }
	v_mov_b32_e32 v40, v212
	v_mov_b32_e32 v41, v213
	v_mov_b32_e32 v42, v214
	v_mov_b32_e32 v43, v215
	v_mov_b32_e32 v44, v216
	v_mov_b32_e32 v45, v217
	v_mov_b32_e32 v46, v218
	v_mov_b32_e32 v47, v219
	v_lshlrev_b32_e32 v50, 16, v41
	v_and_b32_e32 v51, 0xffff0000, v41
	v_lshlrev_b32_e32 v41, 16, v42
	v_lshlrev_b32_e32 v48, 16, v40
	v_and_b32_e32 v49, 0xffff0000, v40
	v_mul_f32_e32 v41, 0xbfb8aa3b, v41
	v_and_b32_e32 v52, 0xffff0000, v42
	v_mul_f32_e32 v40, 0xbfb8aa3b, v48
	v_exp_f32_e32 v42, v41
	v_mul_f32_e32 v41, 0xbfb8aa3b, v49
	v_exp_f32_e32 v40, v40
	v_exp_f32_e32 v41, v41
	v_mul_f32_e32 v49, 0xbfb8aa3b, v51
	v_lshlrev_b32_e32 v53, 16, v43
	v_and_b32_e32 v54, 0xffff0000, v43
	v_pk_add_f32 v[40:41], v[40:41], 1.0 op_sel_hi:[1,0]
	v_mul_f32_e32 v43, 0xbfb8aa3b, v52
	v_div_scale_f32 v51, s[6:7], v41, v41, 1.0
	v_rcp_f32_e32 v52, v51
	v_mul_f32_e32 v48, 0xbfb8aa3b, v50
	v_mul_f32_e32 v50, 0xbfb8aa3b, v53
	v_exp_f32_e32 v48, v48
	v_fma_f32 v53, -v51, v52, 1.0
	v_fmac_f32_e32 v52, v53, v52
	v_div_scale_f32 v53, vcc, 1.0, v41, 1.0
	v_mul_f32_e32 v55, v53, v52
	v_fma_f32 v57, -v51, v55, v53
	v_fmac_f32_e32 v55, v57, v52
	v_fma_f32 v51, -v51, v55, v53
	v_div_scale_f32 v53, s[6:7], v40, v40, 1.0
	v_rcp_f32_e32 v57, v53
	v_div_fmas_f32 v51, v51, v52, v55
	v_exp_f32_e32 v49, v49
	v_div_fixup_f32 v41, v51, v41, 1.0
	v_fma_f32 v51, -v53, v57, 1.0
	v_fmac_f32_e32 v57, v51, v57
	v_div_scale_f32 v51, vcc, 1.0, v40, 1.0
	v_mul_f32_e32 v52, v51, v57
	v_fma_f32 v55, -v53, v52, v51
	v_pk_add_f32 v[48:49], v[48:49], 1.0 op_sel_hi:[1,0]
	v_fmac_f32_e32 v52, v55, v57
	v_fma_f32 v51, -v53, v52, v51
	v_div_scale_f32 v53, s[6:7], v49, v49, 1.0
	v_rcp_f32_e32 v55, v53
	v_div_fmas_f32 v51, v51, v57, v52
	v_div_fixup_f32 v40, v51, v40, 1.0
	v_exp_f32_e32 v43, v43
	v_fma_f32 v51, -v53, v55, 1.0
	v_fmac_f32_e32 v55, v51, v55
	v_div_scale_f32 v51, vcc, 1.0, v49, 1.0
	v_mul_f32_e32 v52, v51, v55
	v_fma_f32 v57, -v53, v52, v51
	v_fmac_f32_e32 v52, v57, v55
	v_fma_f32 v51, -v53, v52, v51
	v_div_scale_f32 v53, s[6:7], v48, v48, 1.0
	v_rcp_f32_e32 v57, v53
	v_div_fmas_f32 v51, v51, v55, v52
	v_div_fixup_f32 v49, v51, v49, 1.0
	v_pk_add_f32 v[42:43], v[42:43], 1.0 op_sel_hi:[1,0]
	v_fma_f32 v51, -v53, v57, 1.0
	v_fmac_f32_e32 v57, v51, v57
	v_div_scale_f32 v51, vcc, 1.0, v48, 1.0
	v_mul_f32_e32 v52, v51, v57
	v_fma_f32 v55, -v53, v52, v51
	v_fmac_f32_e32 v52, v55, v57
	v_fma_f32 v53, -v53, v52, v51
	v_mul_f32_e32 v51, 0xbfb8aa3b, v54
	v_div_scale_f32 v54, s[6:7], v43, v43, 1.0
	v_rcp_f32_e32 v55, v54
	v_div_fmas_f32 v52, v53, v57, v52
	v_div_fixup_f32 v48, v52, v48, 1.0
	v_exp_f32_e32 v50, v50
	v_fma_f32 v52, -v54, v55, 1.0
	v_fmac_f32_e32 v55, v52, v55
	v_div_scale_f32 v52, vcc, 1.0, v43, 1.0
	v_mul_f32_e32 v53, v52, v55
	v_fma_f32 v57, -v54, v53, v52
	v_fmac_f32_e32 v53, v57, v55
	v_fma_f32 v52, -v54, v53, v52
	v_div_scale_f32 v54, s[6:7], v42, v42, 1.0
	v_rcp_f32_e32 v57, v54
	v_div_fmas_f32 v52, v52, v55, v53
	v_exp_f32_e32 v51, v51
	v_div_fixup_f32 v43, v52, v43, 1.0
	v_fma_f32 v52, -v54, v57, 1.0
	v_fmac_f32_e32 v57, v52, v57
	v_div_scale_f32 v52, vcc, 1.0, v42, 1.0
	v_mul_f32_e32 v53, v52, v57
	v_fma_f32 v55, -v54, v53, v52
	v_pk_add_f32 v[50:51], v[50:51], 1.0 op_sel_hi:[1,0]
	v_fmac_f32_e32 v53, v55, v57
	v_fma_f32 v52, -v54, v53, v52
	v_div_scale_f32 v54, s[6:7], v51, v51, 1.0
	v_rcp_f32_e32 v55, v54
	v_div_fmas_f32 v52, v52, v57, v53
	v_div_fixup_f32 v42, v52, v42, 1.0
	v_fma_f32 v52, -v54, v55, 1.0
	v_fmac_f32_e32 v55, v52, v55
	v_div_scale_f32 v52, vcc, 1.0, v51, 1.0
	v_mul_f32_e32 v53, v52, v55
	v_fma_f32 v57, -v54, v53, v52
	v_fmac_f32_e32 v53, v57, v55
	v_fma_f32 v52, -v54, v53, v52
	v_div_scale_f32 v54, s[6:7], v50, v50, 1.0
	v_rcp_f32_e32 v57, v54
	v_div_fmas_f32 v52, v52, v55, v53
	v_div_fixup_f32 v51, v52, v51, 1.0
	v_fma_f32 v52, -v54, v57, 1.0
	v_fmac_f32_e32 v57, v52, v57
	v_div_scale_f32 v52, vcc, 1.0, v50, 1.0
	v_mul_f32_e32 v53, v52, v57
	v_fma_f32 v55, -v54, v53, v52
	v_fmac_f32_e32 v53, v55, v57
	v_fma_f32 v52, -v54, v53, v52
	v_div_fmas_f32 v52, v52, v57, v53
	v_div_fixup_f32 v50, v52, v50, 1.0
	v_lshlrev_b32_e32 v52, 16, v44
	v_and_b32_e32 v53, 0xffff0000, v44
	v_lshlrev_b32_e32 v54, 16, v46
	v_and_b32_e32 v55, 0xffff0000, v46
	v_lshlrev_b32_e32 v46, 16, v47
	v_and_b32_e32 v47, 0xffff0000, v47
	v_lshlrev_b32_e32 v44, 16, v45
	v_and_b32_e32 v45, 0xffff0000, v45
	v_pk_fma_f32 v[36:37], v[36:37], v[40:41], v[52:53]
	v_pk_fma_f32 v[40:41], v[34:35], v[50:51], v[46:47]
	v_pk_fma_f32 v[34:35], v[32:33], v[42:43], v[54:55]
	v_cvt_pk_bf16_f32 v32, v36, v37
	v_pk_fma_f32 v[38:39], v[38:39], v[48:49], v[44:45]
	s_nop 0
	v_cvt_pk_bf16_f32 v33, v38, v39
	v_cvt_pk_bf16_f32 v34, v34, v35
	v_cvt_pk_bf16_f32 v35, v40, v41
	buffer_store_dwordx4 v[32:35], v56, s[20:23], 0 offen offset:256 sc1
	s_nop 1
	v_add_u32_e32 v32, 0xa0, v162
	v_mad_i64_i32 v[34:35], s[6:7], v32, s73, 0
	v_lshl_add_u64 v[32:33], v[34:35], 1, s[36:37]
	v_lshl_add_u64 v[32:33], v[32:33], 0, v[148:149]
	v_add_co_u32_e32 v36, vcc, s74, v32
	s_nop 1
	v_addc_co_u32_e32 v37, vcc, 0, v33, vcc
	s_waitcnt vmcnt(11)
; __device__ __forceinline__ float sigmoidf_(float x) { return 1.0f / (1.0f + __expf(-x)); }
; __device__ __forceinline__ u32x4 pack8(const f32x4 v0, const f32x4 v1) { u32x4 w; w.x = pk2(v0[0], v0[1]); w.y = pk2(v0[2], v0[3]); w.z = pk2(v1[0], v1[1]); w.w = pk2(v1[2], v1[3]); return w; }
; __device__ __forceinline__ void unpack8(const u32x4 w, f32x4& v0, f32x4& v1) { v0 = (f32x4){bflo(w.x), bfhi(w.x), bflo(w.y), bfhi(w.y)}; v1 = (f32x4){bflo(w.z), bfhi(w.z), bflo(w.w), bfhi(w.w)}; }
;     __device__ __forceinline__ void operator()(const f32x4 (&acc)[2][2][4][2], const Unit& u, int wr, int wc, int fr, int fq) const {
;     ...
;         for (int ai = 0; ai < 2; ++ai)
; #pragma unroll
;             for (int m = 0; m < 4; ++m) {
;                 const int row = row0 + ai * 128 + m * 16;
;                 const bf16_t* rowp = z + (size_t)row * DIN + col0;
; #pragma unroll
;                 for (int bj = 0; bj < 2; ++bj) {
;                     const u32x4 gw = *(const u32x4*)(rowp + O_GA + bj * 128);
;                     f32x4 g0, g1; unpack8(gw, g0, g1);
;                     f32x4 v0, v1;
; #pragma unroll
;                     for (int j = 0; j < 4; ++j) { v0[j] = sigmoidf_(g0[j]) * acc[ai][bj][m][0][j]; v1[j] = sigmoidf_(g1[j]) * acc[ai][bj][m][1][j]; }
;                     const u32x4 mw = *(const u32x4*)(rowp + bj * 128); f32x4 m0, m1; unpack8(mw, m0, m1); v0 += m0; v1 += m1;
;                     __builtin_amdgcn_raw_buffer_store_b128(pack8(v0, v1), rsrc, (unsigned)(((size_t)row * DIN + col0 + bj * 128) * 2), 0, 16  ); }
	v_mov_b32_e32 v38, v232
	v_mov_b32_e32 v39, v233
	v_mov_b32_e32 v40, v234
	v_mov_b32_e32 v41, v235
	v_mov_b32_e32 v42, v236
	v_mov_b32_e32 v43, v237
	v_mov_b32_e32 v44, v238
	v_mov_b32_e32 v45, v239
	v_lshlrev_b32_e32 v35, 16, v38
	v_lshlrev_b32_e32 v47, 16, v39
	v_and_b32_e32 v48, 0xffff0000, v39
	v_lshlrev_b32_e32 v39, 16, v40
	v_mul_f32_e32 v35, 0xbfb8aa3b, v35
	v_and_b32_e32 v46, 0xffff0000, v38
	v_exp_f32_e32 v38, v35
	v_mul_f32_e32 v35, 0xbfb8aa3b, v39
	v_and_b32_e32 v49, 0xffff0000, v40
	v_exp_f32_e32 v40, v35
	v_mul_f32_e32 v35, 0xbfb8aa3b, v46
	v_exp_f32_e32 v39, v35
	v_mul_f32_e32 v35, 0xbfb8aa3b, v49
	v_lshlrev_b32_e32 v50, 16, v41
	v_and_b32_e32 v51, 0xffff0000, v41
	v_exp_f32_e32 v41, v35
	v_mul_f32_e32 v35, 0xbfb8aa3b, v47
	v_exp_f32_e32 v46, v35
	v_mul_f32_e32 v35, 0xbfb8aa3b, v48
	v_pk_add_f32 v[38:39], v[38:39], 1.0 op_sel_hi:[1,0]
	v_exp_f32_e32 v47, v35
	v_div_scale_f32 v35, s[6:7], v39, v39, 1.0
	v_rcp_f32_e32 v49, v35
	v_mul_f32_e32 v48, 0xbfb8aa3b, v50
	v_pk_add_f32 v[46:47], v[46:47], 1.0 op_sel_hi:[1,0]
	v_pk_add_f32 v[40:41], v[40:41], 1.0 op_sel_hi:[1,0]
	v_fma_f32 v50, -v35, v49, 1.0
	v_fmac_f32_e32 v49, v50, v49
	v_div_scale_f32 v50, vcc, 1.0, v39, 1.0
	v_mul_f32_e32 v52, v50, v49
	v_fma_f32 v53, -v35, v52, v50
	v_fmac_f32_e32 v52, v53, v49
	v_fma_f32 v35, -v35, v52, v50
	v_div_scale_f32 v50, s[6:7], v38, v38, 1.0
	v_rcp_f32_e32 v53, v50
	v_div_fmas_f32 v35, v35, v49, v52
	v_div_fixup_f32 v39, v35, v39, 1.0
	v_exp_f32_e32 v48, v48
	v_fma_f32 v35, -v50, v53, 1.0
	v_fmac_f32_e32 v53, v35, v53
	v_div_scale_f32 v35, vcc, 1.0, v38, 1.0
	v_mul_f32_e32 v49, v35, v53
	v_fma_f32 v52, -v50, v49, v35
	v_fmac_f32_e32 v49, v52, v53
	v_fma_f32 v35, -v50, v49, v35
	v_div_scale_f32 v50, s[6:7], v47, v47, 1.0
	v_rcp_f32_e32 v52, v50
	v_div_fmas_f32 v35, v35, v53, v49
	v_div_fixup_f32 v38, v35, v38, 1.0
	v_fma_f32 v35, -v50, v52, 1.0
	v_fmac_f32_e32 v52, v35, v52
	v_div_scale_f32 v35, vcc, 1.0, v47, 1.0
	v_mul_f32_e32 v49, v35, v52
	v_fma_f32 v53, -v50, v49, v35
	v_fmac_f32_e32 v49, v53, v52
	v_fma_f32 v35, -v50, v49, v35
	v_div_scale_f32 v50, s[6:7], v46, v46, 1.0
	v_rcp_f32_e32 v53, v50
	v_div_fmas_f32 v35, v35, v52, v49
	v_div_fixup_f32 v47, v35, v47, 1.0
	v_fma_f32 v35, -v50, v53, 1.0
	v_fmac_f32_e32 v53, v35, v53
	v_div_scale_f32 v35, vcc, 1.0, v46, 1.0
	v_mul_f32_e32 v52, v35, v53
	v_fma_f32 v49, -v50, v52, v35
	v_fmac_f32_e32 v52, v49, v53
	v_fma_f32 v35, -v50, v52, v35
	v_div_scale_f32 v50, s[6:7], v41, v41, 1.0
	v_mul_f32_e32 v49, 0xbfb8aa3b, v51
	v_rcp_f32_e32 v51, v50
	v_div_fmas_f32 v35, v35, v53, v52
	v_div_fixup_f32 v46, v35, v46, 1.0
	v_exp_f32_e32 v49, v49
	v_fma_f32 v35, -v50, v51, 1.0
	v_fmac_f32_e32 v51, v35, v51
	v_div_scale_f32 v35, vcc, 1.0, v41, 1.0
	v_mul_f32_e32 v52, v35, v51
	v_fma_f32 v53, -v50, v52, v35
	v_fmac_f32_e32 v52, v53, v51
	v_fma_f32 v35, -v50, v52, v35
	v_div_scale_f32 v50, s[6:7], v40, v40, 1.0
	v_rcp_f32_e32 v53, v50
	v_div_fmas_f32 v35, v35, v51, v52
	v_div_fixup_f32 v41, v35, v41, 1.0
	v_pk_add_f32 v[48:49], v[48:49], 1.0 op_sel_hi:[1,0]
	v_fma_f32 v35, -v50, v53, 1.0
	v_fmac_f32_e32 v53, v35, v53
	v_div_scale_f32 v35, vcc, 1.0, v40, 1.0
	v_mul_f32_e32 v51, v35, v53
	v_fma_f32 v52, -v50, v51, v35
	v_fmac_f32_e32 v51, v52, v53
	v_fma_f32 v35, -v50, v51, v35
	v_div_scale_f32 v50, s[6:7], v49, v49, 1.0
	v_rcp_f32_e32 v52, v50
	v_div_fmas_f32 v35, v35, v53, v51
	v_div_fixup_f32 v40, v35, v40, 1.0
	v_fma_f32 v35, -v50, v52, 1.0
	v_fmac_f32_e32 v52, v35, v52
	v_div_scale_f32 v35, vcc, 1.0, v49, 1.0
	v_mul_f32_e32 v51, v35, v52
	v_fma_f32 v53, -v50, v51, v35
	v_fmac_f32_e32 v51, v53, v52
	v_fma_f32 v35, -v50, v51, v35
	v_div_scale_f32 v50, s[6:7], v48, v48, 1.0
	v_rcp_f32_e32 v53, v50
	v_div_fmas_f32 v35, v35, v52, v51
	v_div_fixup_f32 v49, v35, v49, 1.0
	v_fma_f32 v35, -v50, v53, 1.0
	v_fmac_f32_e32 v53, v35, v53
	v_div_scale_f32 v35, vcc, 1.0, v48, 1.0
	v_mul_f32_e32 v51, v35, v53
	v_fma_f32 v52, -v50, v51, v35
	v_fmac_f32_e32 v51, v52, v53
	v_fma_f32 v35, -v50, v51, v35
	v_div_fmas_f32 v35, v35, v53, v51
	v_div_fixup_f32 v48, v35, v48, 1.0
	v_lshlrev_b32_e32 v50, 16, v42
	v_and_b32_e32 v51, 0xffff0000, v42
	v_lshlrev_b32_e32 v52, 16, v44
	v_and_b32_e32 v53, 0xffff0000, v44
	v_lshlrev_b32_e32 v44, 16, v45
	v_and_b32_e32 v45, 0xffff0000, v45
	v_lshlrev_b32_e32 v42, 16, v43
	v_and_b32_e32 v43, 0xffff0000, v43
	v_pk_fma_f32 v[28:29], v[28:29], v[38:39], v[50:51]
	v_pk_fma_f32 v[38:39], v[26:27], v[48:49], v[44:45]
	v_pk_fma_f32 v[26:27], v[24:25], v[40:41], v[52:53]
	v_add_lshl_u32 v40, v146, v34, 1
	v_pk_fma_f32 v[30:31], v[30:31], v[46:47], v[42:43]
	v_cvt_pk_bf16_f32 v24, v28, v29
	s_nop 0
	v_cvt_pk_bf16_f32 v25, v30, v31
	v_cvt_pk_bf16_f32 v26, v26, v27
	v_cvt_pk_bf16_f32 v27, v38, v39
	buffer_store_dwordx4 v[24:27], v40, s[20:23], 0 offen sc1
	s_nop 0
	s_waitcnt vmcnt(9)
; __device__ __forceinline__ float sigmoidf_(float x) { return 1.0f / (1.0f + __expf(-x)); }
; __device__ __forceinline__ u32x4 pack8(const f32x4 v0, const f32x4 v1) { u32x4 w; w.x = pk2(v0[0], v0[1]); w.y = pk2(v0[2], v0[3]); w.z = pk2(v1[0], v1[1]); w.w = pk2(v1[2], v1[3]); return w; }
; __device__ __forceinline__ void unpack8(const u32x4 w, f32x4& v0, f32x4& v1) { v0 = (f32x4){bflo(w.x), bfhi(w.x), bflo(w.y), bfhi(w.y)}; v1 = (f32x4){bflo(w.z), bfhi(w.z), bflo(w.w), bfhi(w.w)}; }
;     __device__ __forceinline__ void operator()(const f32x4 (&acc)[2][2][4][2], const Unit& u, int wr, int wc, int fr, int fq) const {
;     ...
;         for (int ai = 0; ai < 2; ++ai)
; #pragma unroll
;             for (int m = 0; m < 4; ++m) {
;                 const int row = row0 + ai * 128 + m * 16;
;                 const bf16_t* rowp = z + (size_t)row * DIN + col0;
; #pragma unroll
;                 for (int bj = 0; bj < 2; ++bj) {
;                     const u32x4 gw = *(const u32x4*)(rowp + O_GA + bj * 128);
;                     f32x4 g0, g1; unpack8(gw, g0, g1);
;                     f32x4 v0, v1;
; #pragma unroll
;                     for (int j = 0; j < 4; ++j) { v0[j] = sigmoidf_(g0[j]) * acc[ai][bj][m][0][j]; v1[j] = sigmoidf_(g1[j]) * acc[ai][bj][m][1][j]; }
;                     const u32x4 mw = *(const u32x4*)(rowp + bj * 128); f32x4 m0, m1; unpack8(mw, m0, m1); v0 += m0; v1 += m1;
;                     __builtin_amdgcn_raw_buffer_store_b128(pack8(v0, v1), rsrc, (unsigned)(((size_t)row * DIN + col0 + bj * 128) * 2), 0, 16  ); }
	v_mov_b32_e32 v24, v240
	v_mov_b32_e32 v25, v241
	v_mov_b32_e32 v26, v242
	v_mov_b32_e32 v27, v243
	v_mov_b32_e32 v28, v244
	v_mov_b32_e32 v29, v245
	v_mov_b32_e32 v30, v246
	v_mov_b32_e32 v31, v247
	v_lshlrev_b32_e32 v34, 16, v25
	v_and_b32_e32 v35, 0xffff0000, v25
	v_lshlrev_b32_e32 v25, 16, v26
	v_lshlrev_b32_e32 v32, 16, v24
	v_and_b32_e32 v33, 0xffff0000, v24
	v_mul_f32_e32 v25, 0xbfb8aa3b, v25
	v_and_b32_e32 v36, 0xffff0000, v26
	v_mul_f32_e32 v24, 0xbfb8aa3b, v32
	v_exp_f32_e32 v26, v25
	v_mul_f32_e32 v25, 0xbfb8aa3b, v33
	v_exp_f32_e32 v24, v24
	v_exp_f32_e32 v25, v25
	v_mul_f32_e32 v33, 0xbfb8aa3b, v35
	v_lshlrev_b32_e32 v37, 16, v27
	v_and_b32_e32 v38, 0xffff0000, v27
	v_pk_add_f32 v[24:25], v[24:25], 1.0 op_sel_hi:[1,0]
	v_mul_f32_e32 v27, 0xbfb8aa3b, v36
	v_div_scale_f32 v35, s[6:7], v25, v25, 1.0
	v_rcp_f32_e32 v36, v35
	v_mul_f32_e32 v32, 0xbfb8aa3b, v34
	v_mul_f32_e32 v34, 0xbfb8aa3b, v37
	v_exp_f32_e32 v32, v32
	v_fma_f32 v37, -v35, v36, 1.0
	v_fmac_f32_e32 v36, v37, v36
	v_div_scale_f32 v37, vcc, 1.0, v25, 1.0
	v_mul_f32_e32 v39, v37, v36
	v_fma_f32 v41, -v35, v39, v37
	v_fmac_f32_e32 v39, v41, v36
	v_fma_f32 v35, -v35, v39, v37
	v_div_scale_f32 v37, s[6:7], v24, v24, 1.0
	v_rcp_f32_e32 v41, v37
	v_div_fmas_f32 v35, v35, v36, v39
	v_exp_f32_e32 v33, v33
	v_div_fixup_f32 v25, v35, v25, 1.0
	v_fma_f32 v35, -v37, v41, 1.0
	v_fmac_f32_e32 v41, v35, v41
	v_div_scale_f32 v35, vcc, 1.0, v24, 1.0
	v_mul_f32_e32 v36, v35, v41
	v_fma_f32 v39, -v37, v36, v35
	v_pk_add_f32 v[32:33], v[32:33], 1.0 op_sel_hi:[1,0]
	v_fmac_f32_e32 v36, v39, v41
	v_fma_f32 v35, -v37, v36, v35
	v_div_scale_f32 v37, s[6:7], v33, v33, 1.0
	v_rcp_f32_e32 v39, v37
	v_div_fmas_f32 v35, v35, v41, v36
	v_div_fixup_f32 v24, v35, v24, 1.0
	v_exp_f32_e32 v27, v27
	v_fma_f32 v35, -v37, v39, 1.0
	v_fmac_f32_e32 v39, v35, v39
	v_div_scale_f32 v35, vcc, 1.0, v33, 1.0
	v_mul_f32_e32 v36, v35, v39
	v_fma_f32 v41, -v37, v36, v35
	v_fmac_f32_e32 v36, v41, v39
	v_fma_f32 v35, -v37, v36, v35
	v_div_scale_f32 v37, s[6:7], v32, v32, 1.0
	v_rcp_f32_e32 v41, v37
	v_div_fmas_f32 v35, v35, v39, v36
	v_div_fixup_f32 v33, v35, v33, 1.0
	v_pk_add_f32 v[26:27], v[26:27], 1.0 op_sel_hi:[1,0]
	v_fma_f32 v35, -v37, v41, 1.0
	v_fmac_f32_e32 v41, v35, v41
	v_div_scale_f32 v35, vcc, 1.0, v32, 1.0
	v_mul_f32_e32 v36, v35, v41
	v_fma_f32 v39, -v37, v36, v35
	v_fmac_f32_e32 v36, v39, v41
	v_fma_f32 v37, -v37, v36, v35
	v_mul_f32_e32 v35, 0xbfb8aa3b, v38
	v_div_scale_f32 v38, s[6:7], v27, v27, 1.0
	v_rcp_f32_e32 v39, v38
	v_div_fmas_f32 v36, v37, v41, v36
	v_div_fixup_f32 v32, v36, v32, 1.0
	v_exp_f32_e32 v34, v34
	v_fma_f32 v36, -v38, v39, 1.0
	v_fmac_f32_e32 v39, v36, v39
	v_div_scale_f32 v36, vcc, 1.0, v27, 1.0
	v_mul_f32_e32 v37, v36, v39
	v_fma_f32 v41, -v38, v37, v36
	v_fmac_f32_e32 v37, v41, v39
	v_fma_f32 v36, -v38, v37, v36
	v_div_scale_f32 v38, s[6:7], v26, v26, 1.0
	v_rcp_f32_e32 v41, v38
	v_div_fmas_f32 v36, v36, v39, v37
	v_exp_f32_e32 v35, v35
	v_div_fixup_f32 v27, v36, v27, 1.0
	v_fma_f32 v36, -v38, v41, 1.0
	v_fmac_f32_e32 v41, v36, v41
	v_div_scale_f32 v36, vcc, 1.0, v26, 1.0
	v_mul_f32_e32 v37, v36, v41
	v_fma_f32 v39, -v38, v37, v36
	v_pk_add_f32 v[34:35], v[34:35], 1.0 op_sel_hi:[1,0]
	v_fmac_f32_e32 v37, v39, v41
	v_fma_f32 v36, -v38, v37, v36
	v_div_scale_f32 v38, s[6:7], v35, v35, 1.0
	v_rcp_f32_e32 v39, v38
	v_div_fmas_f32 v36, v36, v41, v37
	v_div_fixup_f32 v26, v36, v26, 1.0
	v_fma_f32 v36, -v38, v39, 1.0
	v_fmac_f32_e32 v39, v36, v39
	v_div_scale_f32 v36, vcc, 1.0, v35, 1.0
	v_mul_f32_e32 v37, v36, v39
	v_fma_f32 v41, -v38, v37, v36
	v_fmac_f32_e32 v37, v41, v39
	v_fma_f32 v36, -v38, v37, v36
	v_div_scale_f32 v38, s[6:7], v34, v34, 1.0
	v_rcp_f32_e32 v41, v38
	v_div_fmas_f32 v36, v36, v39, v37
	v_div_fixup_f32 v35, v36, v35, 1.0
	v_fma_f32 v36, -v38, v41, 1.0
	v_fmac_f32_e32 v41, v36, v41
	v_div_scale_f32 v36, vcc, 1.0, v34, 1.0
	v_mul_f32_e32 v37, v36, v41
	v_fma_f32 v39, -v38, v37, v36
	v_fmac_f32_e32 v37, v39, v41
	v_fma_f32 v36, -v38, v37, v36
	v_div_fmas_f32 v36, v36, v41, v37
	v_div_fixup_f32 v34, v36, v34, 1.0
	v_lshlrev_b32_e32 v36, 16, v28
	v_and_b32_e32 v37, 0xffff0000, v28
	v_lshlrev_b32_e32 v38, 16, v30
	v_and_b32_e32 v39, 0xffff0000, v30
	v_lshlrev_b32_e32 v30, 16, v31
	v_and_b32_e32 v31, 0xffff0000, v31
	v_lshlrev_b32_e32 v28, 16, v29
	v_and_b32_e32 v29, 0xffff0000, v29
	v_pk_fma_f32 v[20:21], v[20:21], v[24:25], v[36:37]
	v_pk_fma_f32 v[24:25], v[18:19], v[34:35], v[30:31]
	v_pk_fma_f32 v[18:19], v[16:17], v[26:27], v[38:39]
	v_cvt_pk_bf16_f32 v16, v20, v21
	v_pk_fma_f32 v[22:23], v[22:23], v[32:33], v[28:29]
	s_nop 0
	v_cvt_pk_bf16_f32 v17, v22, v23
	v_cvt_pk_bf16_f32 v18, v18, v19
	v_cvt_pk_bf16_f32 v19, v24, v25
	buffer_store_dwordx4 v[16:19], v40, s[20:23], 0 offen offset:256 sc1
	s_nop 1
	v_add_u32_e32 v16, 0xb0, v162
	v_mad_i64_i32 v[18:19], s[6:7], v16, s73, 0
	v_lshl_add_u64 v[16:17], v[18:19], 1, s[36:37]
	v_lshl_add_u64 v[16:17], v[16:17], 0, v[148:149]
	v_add_co_u32_e32 v20, vcc, s74, v16
	s_nop 1
	v_addc_co_u32_e32 v21, vcc, 0, v17, vcc
	s_waitcnt vmcnt(7)
; __device__ __forceinline__ float sigmoidf_(float x) { return 1.0f / (1.0f + __expf(-x)); }
; __device__ __forceinline__ u32x4 pack8(const f32x4 v0, const f32x4 v1) { u32x4 w; w.x = pk2(v0[0], v0[1]); w.y = pk2(v0[2], v0[3]); w.z = pk2(v1[0], v1[1]); w.w = pk2(v1[2], v1[3]); return w; }
; __device__ __forceinline__ void unpack8(const u32x4 w, f32x4& v0, f32x4& v1) { v0 = (f32x4){bflo(w.x), bfhi(w.x), bflo(w.y), bfhi(w.y)}; v1 = (f32x4){bflo(w.z), bfhi(w.z), bflo(w.w), bfhi(w.w)}; }
;     __device__ __forceinline__ void operator()(const f32x4 (&acc)[2][2][4][2], const Unit& u, int wr, int wc, int fr, int fq) const {
;     ...
;         for (int ai = 0; ai < 2; ++ai)
; #pragma unroll
;             for (int m = 0; m < 4; ++m) {
;                 const int row = row0 + ai * 128 + m * 16;
;                 const bf16_t* rowp = z + (size_t)row * DIN + col0;
; #pragma unroll
;                 for (int bj = 0; bj < 2; ++bj) {
;                     const u32x4 gw = *(const u32x4*)(rowp + O_GA + bj * 128);
;                     f32x4 g0, g1; unpack8(gw, g0, g1);
;                     f32x4 v0, v1;
; #pragma unroll
;                     for (int j = 0; j < 4; ++j) { v0[j] = sigmoidf_(g0[j]) * acc[ai][bj][m][0][j]; v1[j] = sigmoidf_(g1[j]) * acc[ai][bj][m][1][j]; }
;                     const u32x4 mw = *(const u32x4*)(rowp + bj * 128); f32x4 m0, m1; unpack8(mw, m0, m1); v0 += m0; v1 += m1;
;                     __builtin_amdgcn_raw_buffer_store_b128(pack8(v0, v1), rsrc, (unsigned)(((size_t)row * DIN + col0 + bj * 128) * 2), 0, 16  ); }
	v_mov_b32_e32 v22, v248
	v_mov_b32_e32 v23, v249
	v_mov_b32_e32 v24, v250
	v_mov_b32_e32 v25, v251
	v_mov_b32_e32 v26, v252
	v_mov_b32_e32 v27, v253
	v_mov_b32_e32 v28, v254
	v_mov_b32_e32 v29, v255
	v_lshlrev_b32_e32 v19, 16, v22
	v_lshlrev_b32_e32 v31, 16, v23
	v_and_b32_e32 v32, 0xffff0000, v23
	v_lshlrev_b32_e32 v23, 16, v24
	v_mul_f32_e32 v19, 0xbfb8aa3b, v19
	v_and_b32_e32 v30, 0xffff0000, v22
	v_exp_f32_e32 v22, v19
	v_mul_f32_e32 v19, 0xbfb8aa3b, v23
	v_and_b32_e32 v33, 0xffff0000, v24
	v_exp_f32_e32 v24, v19
	v_mul_f32_e32 v19, 0xbfb8aa3b, v30
	v_exp_f32_e32 v23, v19
	v_mul_f32_e32 v19, 0xbfb8aa3b, v33
	v_lshlrev_b32_e32 v34, 16, v25
	v_and_b32_e32 v35, 0xffff0000, v25
	v_exp_f32_e32 v25, v19
	v_mul_f32_e32 v19, 0xbfb8aa3b, v31
	v_exp_f32_e32 v30, v19
	v_mul_f32_e32 v19, 0xbfb8aa3b, v32
	v_pk_add_f32 v[22:23], v[22:23], 1.0 op_sel_hi:[1,0]
	v_exp_f32_e32 v31, v19
	v_div_scale_f32 v19, s[6:7], v23, v23, 1.0
	v_rcp_f32_e32 v33, v19
	v_mul_f32_e32 v32, 0xbfb8aa3b, v34
	v_pk_add_f32 v[30:31], v[30:31], 1.0 op_sel_hi:[1,0]
	v_pk_add_f32 v[24:25], v[24:25], 1.0 op_sel_hi:[1,0]
	v_fma_f32 v34, -v19, v33, 1.0
	v_fmac_f32_e32 v33, v34, v33
	v_div_scale_f32 v34, vcc, 1.0, v23, 1.0
	v_mul_f32_e32 v36, v34, v33
	v_fma_f32 v37, -v19, v36, v34
	v_fmac_f32_e32 v36, v37, v33
	v_fma_f32 v19, -v19, v36, v34
	v_div_scale_f32 v34, s[6:7], v22, v22, 1.0
	v_rcp_f32_e32 v37, v34
	v_div_fmas_f32 v19, v19, v33, v36
	v_div_fixup_f32 v23, v19, v23, 1.0
	v_exp_f32_e32 v32, v32
	v_fma_f32 v19, -v34, v37, 1.0
	v_fmac_f32_e32 v37, v19, v37
	v_div_scale_f32 v19, vcc, 1.0, v22, 1.0
	v_mul_f32_e32 v33, v19, v37
	v_fma_f32 v36, -v34, v33, v19
	v_fmac_f32_e32 v33, v36, v37
	v_fma_f32 v19, -v34, v33, v19
	v_div_scale_f32 v34, s[6:7], v31, v31, 1.0
	v_rcp_f32_e32 v36, v34
	v_div_fmas_f32 v19, v19, v37, v33
	v_div_fixup_f32 v22, v19, v22, 1.0
	v_fma_f32 v19, -v34, v36, 1.0
	v_fmac_f32_e32 v36, v19, v36
	v_div_scale_f32 v19, vcc, 1.0, v31, 1.0
	v_mul_f32_e32 v33, v19, v36
	v_fma_f32 v37, -v34, v33, v19
	v_fmac_f32_e32 v33, v37, v36
	v_fma_f32 v19, -v34, v33, v19
	v_div_scale_f32 v34, s[6:7], v30, v30, 1.0
	v_rcp_f32_e32 v37, v34
	v_div_fmas_f32 v19, v19, v36, v33
	v_div_fixup_f32 v31, v19, v31, 1.0
	v_fma_f32 v19, -v34, v37, 1.0
	v_fmac_f32_e32 v37, v19, v37
	v_div_scale_f32 v19, vcc, 1.0, v30, 1.0
	v_mul_f32_e32 v36, v19, v37
	v_fma_f32 v33, -v34, v36, v19
	v_fmac_f32_e32 v36, v33, v37
	v_fma_f32 v19, -v34, v36, v19
	v_div_scale_f32 v34, s[6:7], v25, v25, 1.0
	v_mul_f32_e32 v33, 0xbfb8aa3b, v35
	v_rcp_f32_e32 v35, v34
	v_div_fmas_f32 v19, v19, v37, v36
	v_div_fixup_f32 v30, v19, v30, 1.0
	v_exp_f32_e32 v33, v33
	v_fma_f32 v19, -v34, v35, 1.0
	v_fmac_f32_e32 v35, v19, v35
	v_div_scale_f32 v19, vcc, 1.0, v25, 1.0
	v_mul_f32_e32 v36, v19, v35
	v_fma_f32 v37, -v34, v36, v19
	v_fmac_f32_e32 v36, v37, v35
	v_fma_f32 v19, -v34, v36, v19
	v_div_scale_f32 v34, s[6:7], v24, v24, 1.0
	v_rcp_f32_e32 v37, v34
	v_div_fmas_f32 v19, v19, v35, v36
	v_div_fixup_f32 v25, v19, v25, 1.0
	v_pk_add_f32 v[32:33], v[32:33], 1.0 op_sel_hi:[1,0]
	v_fma_f32 v19, -v34, v37, 1.0
	v_fmac_f32_e32 v37, v19, v37
	v_div_scale_f32 v19, vcc, 1.0, v24, 1.0
	v_mul_f32_e32 v35, v19, v37
	v_fma_f32 v36, -v34, v35, v19
	v_fmac_f32_e32 v35, v36, v37
	v_fma_f32 v19, -v34, v35, v19
	v_div_scale_f32 v34, s[6:7], v33, v33, 1.0
	v_rcp_f32_e32 v36, v34
	v_div_fmas_f32 v19, v19, v37, v35
	v_div_fixup_f32 v24, v19, v24, 1.0
	v_fma_f32 v19, -v34, v36, 1.0
	v_fmac_f32_e32 v36, v19, v36
	v_div_scale_f32 v19, vcc, 1.0, v33, 1.0
	v_mul_f32_e32 v35, v19, v36
	v_fma_f32 v37, -v34, v35, v19
	v_fmac_f32_e32 v35, v37, v36
	v_fma_f32 v19, -v34, v35, v19
	v_div_scale_f32 v34, s[6:7], v32, v32, 1.0
	v_rcp_f32_e32 v37, v34
	v_div_fmas_f32 v19, v19, v36, v35
	v_div_fixup_f32 v33, v19, v33, 1.0
	v_fma_f32 v19, -v34, v37, 1.0
	v_fmac_f32_e32 v37, v19, v37
	v_div_scale_f32 v19, vcc, 1.0, v32, 1.0
	v_mul_f32_e32 v35, v19, v37
	v_fma_f32 v36, -v34, v35, v19
	v_fmac_f32_e32 v35, v36, v37
	v_fma_f32 v19, -v34, v35, v19
	v_div_fmas_f32 v19, v19, v37, v35
	v_div_fixup_f32 v32, v19, v32, 1.0
	v_lshlrev_b32_e32 v34, 16, v26
	v_and_b32_e32 v35, 0xffff0000, v26
	v_lshlrev_b32_e32 v36, 16, v28
	v_and_b32_e32 v37, 0xffff0000, v28
	v_lshlrev_b32_e32 v28, 16, v29
	v_and_b32_e32 v29, 0xffff0000, v29
	v_lshlrev_b32_e32 v26, 16, v27
	v_and_b32_e32 v27, 0xffff0000, v27
	v_pk_fma_f32 v[12:13], v[12:13], v[22:23], v[34:35]
	v_pk_fma_f32 v[22:23], v[10:11], v[32:33], v[28:29]
	v_pk_fma_f32 v[10:11], v[8:9], v[24:25], v[36:37]
	v_add_lshl_u32 v24, v146, v18, 1
	v_pk_fma_f32 v[14:15], v[14:15], v[30:31], v[26:27]
	v_cvt_pk_bf16_f32 v8, v12, v13
	s_nop 0
	v_cvt_pk_bf16_f32 v9, v14, v15
	v_cvt_pk_bf16_f32 v10, v10, v11
	v_cvt_pk_bf16_f32 v11, v22, v23
	buffer_store_dwordx4 v[8:11], v24, s[20:23], 0 offen sc1
	s_nop 0
	s_waitcnt vmcnt(5)
; __device__ __forceinline__ float sigmoidf_(float x) { return 1.0f / (1.0f + __expf(-x)); }
; __device__ __forceinline__ u32x4 pack8(const f32x4 v0, const f32x4 v1) { u32x4 w; w.x = pk2(v0[0], v0[1]); w.y = pk2(v0[2], v0[3]); w.z = pk2(v1[0], v1[1]); w.w = pk2(v1[2], v1[3]); return w; }
; __device__ __forceinline__ void unpack8(const u32x4 w, f32x4& v0, f32x4& v1) { v0 = (f32x4){bflo(w.x), bfhi(w.x), bflo(w.y), bfhi(w.y)}; v1 = (f32x4){bflo(w.z), bfhi(w.z), bflo(w.w), bfhi(w.w)}; }
;     __device__ __forceinline__ void operator()(const f32x4 (&acc)[2][2][4][2], const Unit& u, int wr, int wc, int fr, int fq) const {
;     ...
;         for (int ai = 0; ai < 2; ++ai)
; #pragma unroll
;             for (int m = 0; m < 4; ++m) {
;                 const int row = row0 + ai * 128 + m * 16;
;                 const bf16_t* rowp = z + (size_t)row * DIN + col0;
; #pragma unroll
;                 for (int bj = 0; bj < 2; ++bj) {
;                     const u32x4 gw = *(const u32x4*)(rowp + O_GA + bj * 128);
;                     f32x4 g0, g1; unpack8(gw, g0, g1);
;                     f32x4 v0, v1;
; #pragma unroll
;                     for (int j = 0; j < 4; ++j) { v0[j] = sigmoidf_(g0[j]) * acc[ai][bj][m][0][j]; v1[j] = sigmoidf_(g1[j]) * acc[ai][bj][m][1][j]; }
;                     const u32x4 mw = *(const u32x4*)(rowp + bj * 128); f32x4 m0, m1; unpack8(mw, m0, m1); v0 += m0; v1 += m1;
;                     __builtin_amdgcn_raw_buffer_store_b128(pack8(v0, v1), rsrc, (unsigned)(((size_t)row * DIN + col0 + bj * 128) * 2), 0, 16  ); }
;             }
;         asm volatile("s_waitcnt vmcnt(0)" ::: "memory");
;         if (fr == 0 && fq == 0) (void)__hip_atomic_fetch_add(ready + 64 * (pm_off + u.pm), 1u, __ATOMIC_RELAXED, __HIP_MEMORY_SCOPE_AGENT);
;     }
	v_mov_b32_e32 v8, v204
	v_mov_b32_e32 v9, v205
	v_mov_b32_e32 v10, v206
	v_mov_b32_e32 v11, v207
	v_mov_b32_e32 v12, v208
	v_mov_b32_e32 v13, v209
	v_mov_b32_e32 v14, v210
	v_mov_b32_e32 v15, v211
	v_lshlrev_b32_e32 v18, 16, v9
	v_and_b32_e32 v19, 0xffff0000, v9
	v_lshlrev_b32_e32 v9, 16, v10
	v_lshlrev_b32_e32 v16, 16, v8
	v_and_b32_e32 v17, 0xffff0000, v8
	v_mul_f32_e32 v9, 0xbfb8aa3b, v9
	v_and_b32_e32 v20, 0xffff0000, v10
	v_mul_f32_e32 v8, 0xbfb8aa3b, v16
	v_exp_f32_e32 v10, v9
	v_mul_f32_e32 v9, 0xbfb8aa3b, v17
	v_exp_f32_e32 v8, v8
	v_exp_f32_e32 v9, v9
	v_mul_f32_e32 v17, 0xbfb8aa3b, v19
	v_lshlrev_b32_e32 v21, 16, v11
	v_and_b32_e32 v22, 0xffff0000, v11
	v_pk_add_f32 v[8:9], v[8:9], 1.0 op_sel_hi:[1,0]
	v_mul_f32_e32 v11, 0xbfb8aa3b, v20
	v_div_scale_f32 v19, s[6:7], v9, v9, 1.0
	v_rcp_f32_e32 v20, v19
	v_mul_f32_e32 v16, 0xbfb8aa3b, v18
	v_mul_f32_e32 v18, 0xbfb8aa3b, v21
	v_exp_f32_e32 v16, v16
	v_fma_f32 v21, -v19, v20, 1.0
	v_fmac_f32_e32 v20, v21, v20
	v_div_scale_f32 v21, vcc, 1.0, v9, 1.0
	v_mul_f32_e32 v23, v21, v20
	v_fma_f32 v25, -v19, v23, v21
	v_fmac_f32_e32 v23, v25, v20
	v_fma_f32 v19, -v19, v23, v21
	v_div_scale_f32 v21, s[6:7], v8, v8, 1.0
	v_rcp_f32_e32 v25, v21
	v_div_fmas_f32 v19, v19, v20, v23
	v_exp_f32_e32 v17, v17
	v_div_fixup_f32 v9, v19, v9, 1.0
	v_fma_f32 v19, -v21, v25, 1.0
	v_fmac_f32_e32 v25, v19, v25
	v_div_scale_f32 v19, vcc, 1.0, v8, 1.0
	v_mul_f32_e32 v20, v19, v25
	v_fma_f32 v23, -v21, v20, v19
	v_pk_add_f32 v[16:17], v[16:17], 1.0 op_sel_hi:[1,0]
	v_fmac_f32_e32 v20, v23, v25
	v_fma_f32 v19, -v21, v20, v19
	v_div_scale_f32 v21, s[6:7], v17, v17, 1.0
	v_rcp_f32_e32 v23, v21
	v_div_fmas_f32 v19, v19, v25, v20
	v_div_fixup_f32 v8, v19, v8, 1.0
	v_exp_f32_e32 v11, v11
	v_fma_f32 v19, -v21, v23, 1.0
	v_fmac_f32_e32 v23, v19, v23
	v_div_scale_f32 v19, vcc, 1.0, v17, 1.0
	v_mul_f32_e32 v20, v19, v23
	v_fma_f32 v25, -v21, v20, v19
	v_fmac_f32_e32 v20, v25, v23
	v_fma_f32 v19, -v21, v20, v19
	v_div_scale_f32 v21, s[6:7], v16, v16, 1.0
	v_rcp_f32_e32 v25, v21
	v_div_fmas_f32 v19, v19, v23, v20
	v_div_fixup_f32 v17, v19, v17, 1.0
	v_pk_add_f32 v[10:11], v[10:11], 1.0 op_sel_hi:[1,0]
	v_fma_f32 v19, -v21, v25, 1.0
	v_fmac_f32_e32 v25, v19, v25
	v_div_scale_f32 v19, vcc, 1.0, v16, 1.0
	v_mul_f32_e32 v20, v19, v25
	v_fma_f32 v23, -v21, v20, v19
	v_fmac_f32_e32 v20, v23, v25
	v_fma_f32 v21, -v21, v20, v19
	v_mul_f32_e32 v19, 0xbfb8aa3b, v22
	v_div_scale_f32 v22, s[6:7], v11, v11, 1.0
	v_rcp_f32_e32 v23, v22
	v_div_fmas_f32 v20, v21, v25, v20
	v_div_fixup_f32 v16, v20, v16, 1.0
	v_exp_f32_e32 v18, v18
	v_fma_f32 v20, -v22, v23, 1.0
	v_fmac_f32_e32 v23, v20, v23
	v_div_scale_f32 v20, vcc, 1.0, v11, 1.0
	v_mul_f32_e32 v21, v20, v23
	v_fma_f32 v25, -v22, v21, v20
	v_fmac_f32_e32 v21, v25, v23
	v_fma_f32 v20, -v22, v21, v20
	v_div_scale_f32 v22, s[6:7], v10, v10, 1.0
	v_rcp_f32_e32 v25, v22
	v_div_fmas_f32 v20, v20, v23, v21
	v_exp_f32_e32 v19, v19
	v_div_fixup_f32 v11, v20, v11, 1.0
	v_fma_f32 v20, -v22, v25, 1.0
	v_fmac_f32_e32 v25, v20, v25
	v_div_scale_f32 v20, vcc, 1.0, v10, 1.0
	v_mul_f32_e32 v21, v20, v25
	v_fma_f32 v23, -v22, v21, v20
	v_pk_add_f32 v[18:19], v[18:19], 1.0 op_sel_hi:[1,0]
	v_fmac_f32_e32 v21, v23, v25
	v_fma_f32 v20, -v22, v21, v20
	v_div_scale_f32 v22, s[6:7], v19, v19, 1.0
	v_rcp_f32_e32 v23, v22
	v_div_fmas_f32 v20, v20, v25, v21
	v_div_fixup_f32 v10, v20, v10, 1.0
	v_fma_f32 v20, -v22, v23, 1.0
	v_fmac_f32_e32 v23, v20, v23
	v_div_scale_f32 v20, vcc, 1.0, v19, 1.0
	v_mul_f32_e32 v21, v20, v23
	v_fma_f32 v25, -v22, v21, v20
	v_fmac_f32_e32 v21, v25, v23
	v_fma_f32 v20, -v22, v21, v20
	v_div_scale_f32 v22, s[6:7], v18, v18, 1.0
	v_rcp_f32_e32 v25, v22
	v_div_fmas_f32 v20, v20, v23, v21
	v_div_fixup_f32 v19, v20, v19, 1.0
	v_fma_f32 v20, -v22, v25, 1.0
	v_fmac_f32_e32 v25, v20, v25
	v_div_scale_f32 v20, vcc, 1.0, v18, 1.0
	v_mul_f32_e32 v21, v20, v25
	v_fma_f32 v23, -v22, v21, v20
	v_fmac_f32_e32 v21, v23, v25
	v_fma_f32 v20, -v22, v21, v20
	v_div_fmas_f32 v20, v20, v25, v21
	v_div_fixup_f32 v18, v20, v18, 1.0
	v_lshlrev_b32_e32 v20, 16, v12
	v_and_b32_e32 v21, 0xffff0000, v12
	v_lshlrev_b32_e32 v22, 16, v14
	v_and_b32_e32 v23, 0xffff0000, v14
	v_lshlrev_b32_e32 v14, 16, v15
	v_and_b32_e32 v15, 0xffff0000, v15
	v_lshlrev_b32_e32 v12, 16, v13
	v_and_b32_e32 v13, 0xffff0000, v13
	v_pk_fma_f32 v[4:5], v[4:5], v[8:9], v[20:21]
	v_pk_fma_f32 v[8:9], v[2:3], v[18:19], v[14:15]
	v_pk_fma_f32 v[2:3], v[0:1], v[10:11], v[22:23]
	v_pk_fma_f32 v[6:7], v[6:7], v[16:17], v[12:13]
	v_cvt_pk_bf16_f32 v0, v4, v5
	s_nop 0
	v_cvt_pk_bf16_f32 v1, v6, v7
	v_cvt_pk_bf16_f32 v2, v2, v3
	v_cvt_pk_bf16_f32 v3, v8, v9
	buffer_store_dwordx4 v[0:3], v24, s[20:23], 0 offen offset:256 sc1
	s_waitcnt vmcnt(0)
	s_and_saveexec_b64 s[12:13], s[8:9]
	s_cbranch_execz .LBB0_1833
	s_mov_b64 s[14:15], exec
	v_mbcnt_lo_u32_b32 v0, s14, 0
	v_mbcnt_hi_u32_b32 v0, s15, v0
	v_cmp_eq_u32_e32 vcc, 0, v0
	s_and_b64 s[6:7], exec, vcc
	s_mov_b64 exec, s[6:7]
	s_cbranch_execz .LBB0_1833
	s_lshl_b32 s6, s75, 6
	s_ashr_i32 s7, s6, 31
	s_lshl_b64 s[6:7], s[6:7], 2
	s_add_u32 s6, s28, s6
	s_addc_u32 s7, s29, s7
	s_bcnt1_i32_b64 s14, s[14:15]
	v_mov_b32_e32 v0, s14
	global_atomic_add v131, v0, s[6:7]
	s_branch .LBB0_1833

; #define PG8_STAGE(bufoff, gbase, voff) do { _Pragma("unroll") for (int _i = 0; _i < 2; ++_i) \
;         __builtin_amdgcn_global_load_lds((const unsigned*)((const char*)(gbase) + (voff)[_i]), (LAS unsigned*)(lds + (bufoff) + ldsw + _i * 8192), 16, 0, 0); } while (0)
; #define PG8_LDA(dst, b, h) do { _Pragma("unroll") for (int m = 0; m < 4; ++m) _Pragma("unroll") for (int k = 0; k < 2; ++k) dst[m][k] = *(const LAS bf16x8*)(lds + PG8_SA(b, h) + aoff + m * 2048 + k * 1024); } while (0)
; #define PG8_LDB(dst, b, h) do { _Pragma("unroll") for (int n = 0; n < 2; ++n) _Pragma("unroll") for (int k = 0; k < 2; ++k) dst[n][k] = *(const LAS bf16x8*)(lds + PG8_SB(b, h) + boff + n * 2048 + k * 1024); } while (0)
; #define PG8_MMA(ai, bj, At, Bt) do { __builtin_amdgcn_s_setprio(1); _Pragma("unroll") for (int m = 0; m < 4; ++m) _Pragma("unroll") for (int n = 0; n < 2; ++n) _Pragma("unroll") for (int k = 0; k < 2; ++k) \
;         acc[ai][bj][m][n] = __builtin_amdgcn_mfma_f32_16x16x32_bf16(Bt[n][k], At[m][k], acc[ai][bj][m][n], 0, 0, 0); __builtin_amdgcn_s_setprio(0); } while (0)
; #define PG8_WAIT_V(n) asm volatile("s_waitcnt vmcnt(" #n ")" ::: "memory")
; #define PG8_WAIT_L(n) asm volatile("s_waitcnt lgkmcnt(" #n ")" ::: "memory")
; #define PG8_BAR __builtin_amdgcn_s_barrier()
; #define PG8_SCHED __builtin_amdgcn_sched_barrier(0)
;     ...
;             PG8_LDB(B0, 0, 0); PG8_SCHED; PG8_LDA(At, 0, 0); PG8_STAGE(PG8_SA(1, 1), a1 + hA, voffA);
;             PG8_WAIT_L(8); PG8_BAR; PG8_WAIT_L(0); PG8_MMA(0, 0, At, B0); PG8_BAR; PG8_SCHED;
;             PG8_LDB(B1, 0, 1); PG8_STAGE(PG8_SB(0, 0), b2, voffB);
;             PG8_BAR; PG8_WAIT_L(0); PG8_MMA(0, 1, At, B1); PG8_BAR;
;             PG8_LDA(At, 0, 1); PG8_STAGE(PG8_SA(0, 0), a2, voffA);
;             PG8_BAR; PG8_WAIT_L(0); PG8_MMA(1, 0, At, B0); PG8_BAR; PG8_SCHED;
;             PG8_STAGE(PG8_SB(0, 1), b2 + hB, voffB);
;             PG8_WAIT_V(6); PG8_BAR; PG8_MMA(1, 1, At, B1); PG8_BAR;
;             PG8_LDB(B0, 1, 0); PG8_SCHED; PG8_LDA(At, 1, 0); PG8_STAGE(PG8_SA(0, 1), a2 + hA, voffA);
;             PG8_WAIT_L(8); PG8_BAR; PG8_WAIT_L(0); PG8_MMA(0, 0, At, B0); PG8_BAR; PG8_SCHED;
.LBB0_1864:
	ds_read_b128 v[140:143], v155
	ds_read_b128 v[146:149], v155 offset:1024
	ds_read_b128 v[158:161], v155 offset:2048
	ds_read_b128 v[162:165], v155 offset:3072
	s_add_u32 s12, s10, 0xfffe0080
	s_addc_u32 s13, s11, -1
	s_cmp_eq_u32 s45, 4
	s_cselect_b32 s15, s7, s13
	s_cselect_b32 s14, s16, s12
	s_cselect_b32 s13, s17, s44
	s_cselect_b32 s12, s33, s37
	v_lshl_add_u64 v[150:151], s[10:11], 0, v[138:139]
	s_add_i32 m0, s62, 0xc000
	ds_read_b128 v[170:173], v156
	ds_read_b128 v[174:177], v156 offset:1024
	ds_read_b128 v[178:181], v156 offset:2048
	ds_read_b128 v[182:185], v156 offset:3072
	ds_read_b128 v[186:189], v156 offset:4096
	ds_read_b128 v[190:193], v156 offset:5120
	ds_read_b128 v[194:197], v156 offset:6144
	ds_read_b128 v[198:201], v156 offset:7168
	global_load_lds_dwordx4 v[150:151], off
	v_lshl_add_u64 v[150:151], s[10:11], 0, v[136:137]
	s_add_i32 m0, s62, 0xe000
	s_nop 0
	global_load_lds_dwordx4 v[150:151], off
	s_waitcnt lgkmcnt(8)
	s_barrier
	s_waitcnt lgkmcnt(0)
	s_setprio 1
	s_waitcnt lgkmcnt(0)
	v_mfma_f32_16x16x32_bf16 v[124:127], v[140:143], v[170:173], v[124:127]
	v_mfma_f32_16x16x32_bf16 v[120:123], v[158:161], v[170:173], v[120:123]
	v_mfma_f32_16x16x32_bf16 v[108:111], v[140:143], v[178:181], v[108:111]
	v_mfma_f32_16x16x32_bf16 v[104:107], v[158:161], v[178:181], v[104:107]
	v_mfma_f32_16x16x32_bf16 v[92:95], v[140:143], v[186:189], v[92:95]
	v_mfma_f32_16x16x32_bf16 v[88:91], v[158:161], v[186:189], v[88:91]
	v_mfma_f32_16x16x32_bf16 v[76:79], v[140:143], v[194:197], v[76:79]
	v_mfma_f32_16x16x32_bf16 v[72:75], v[158:161], v[194:197], v[72:75]
	v_mfma_f32_16x16x32_bf16 v[124:127], v[146:149], v[174:177], v[124:127]
	v_mfma_f32_16x16x32_bf16 v[120:123], v[162:165], v[174:177], v[120:123]
	v_mfma_f32_16x16x32_bf16 v[108:111], v[146:149], v[182:185], v[108:111]
	v_mfma_f32_16x16x32_bf16 v[104:107], v[162:165], v[182:185], v[104:107]
	v_mfma_f32_16x16x32_bf16 v[92:95], v[146:149], v[190:193], v[92:95]
	v_mfma_f32_16x16x32_bf16 v[88:91], v[162:165], v[190:193], v[88:91]
	v_mfma_f32_16x16x32_bf16 v[76:79], v[146:149], v[198:201], v[76:79]
	v_mfma_f32_16x16x32_bf16 v[72:75], v[162:165], v[198:201], v[72:75]
	s_setprio 0
	s_barrier
	s_add_i32 s53, s71, s61
	v_lshl_add_u64 v[150:151], s[12:13], 0, v[130:131]
	s_mov_b32 m0, s53
	ds_read_b128 v[202:205], v157
	ds_read_b128 v[206:209], v157 offset:1024
	ds_read_b128 v[210:213], v157 offset:2048
	ds_read_b128 v[214:217], v157 offset:3072
	global_load_lds_dwordx4 v[150:151], off
	v_lshl_add_u64 v[218:219], s[12:13], 0, v[134:135]
	s_add_i32 m0, s53, 0x2000
	s_nop 0
	global_load_lds_dwordx4 v[218:219], off
	s_barrier
	s_waitcnt lgkmcnt(0)
	s_setprio 1
	s_waitcnt lgkmcnt(0)
	v_mfma_f32_16x16x32_bf16 v[116:119], v[202:205], v[170:173], v[116:119]
	v_mfma_f32_16x16x32_bf16 v[112:115], v[210:213], v[170:173], v[112:115]
	v_mfma_f32_16x16x32_bf16 v[100:103], v[202:205], v[178:181], v[100:103]
	v_mfma_f32_16x16x32_bf16 v[96:99], v[210:213], v[178:181], v[96:99]
	v_mfma_f32_16x16x32_bf16 v[84:87], v[202:205], v[186:189], v[84:87]
	v_mfma_f32_16x16x32_bf16 v[80:83], v[210:213], v[186:189], v[80:83]
	v_mfma_f32_16x16x32_bf16 v[68:71], v[202:205], v[194:197], v[68:71]
	v_mfma_f32_16x16x32_bf16 v[64:67], v[210:213], v[194:197], v[64:67]
	v_mfma_f32_16x16x32_bf16 v[116:119], v[206:209], v[174:177], v[116:119]
	v_mfma_f32_16x16x32_bf16 v[112:115], v[214:217], v[174:177], v[112:115]
	v_mfma_f32_16x16x32_bf16 v[100:103], v[206:209], v[182:185], v[100:103]
	v_mfma_f32_16x16x32_bf16 v[96:99], v[214:217], v[182:185], v[96:99]
	v_mfma_f32_16x16x32_bf16 v[84:87], v[206:209], v[190:193], v[84:87]
	v_mfma_f32_16x16x32_bf16 v[80:83], v[214:217], v[190:193], v[80:83]
	v_mfma_f32_16x16x32_bf16 v[68:71], v[206:209], v[198:201], v[68:71]
	v_mfma_f32_16x16x32_bf16 v[64:67], v[214:217], v[198:201], v[64:67]
	s_setprio 0
	s_mov_b32 m0, s62
	v_lshl_add_u64 v[220:221], s[14:15], 0, v[128:129]
	s_barrier
	ds_read_b128 v[170:173], v156 offset:16384
	ds_read_b128 v[174:177], v156 offset:17408
	ds_read_b128 v[178:181], v156 offset:18432
	ds_read_b128 v[182:185], v156 offset:19456
	ds_read_b128 v[186:189], v156 offset:20480
	ds_read_b128 v[190:193], v156 offset:21504
	ds_read_b128 v[194:197], v156 offset:22528
	ds_read_b128 v[198:201], v156 offset:23552
	global_load_lds_dwordx4 v[220:221], off
	v_lshl_add_u64 v[222:223], s[14:15], 0, v[132:133]
	s_mov_b32 m0, s63
	s_nop 0
	global_load_lds_dwordx4 v[222:223], off
	s_barrier
	s_waitcnt lgkmcnt(0)
	s_setprio 1
	s_waitcnt lgkmcnt(0)
	v_mfma_f32_16x16x32_bf16 v[60:63], v[140:143], v[170:173], v[60:63]
	v_mfma_f32_16x16x32_bf16 v[56:59], v[158:161], v[170:173], v[56:59]
	v_mfma_f32_16x16x32_bf16 v[44:47], v[140:143], v[178:181], v[44:47]
	v_mfma_f32_16x16x32_bf16 v[40:43], v[158:161], v[178:181], v[40:43]
	v_mfma_f32_16x16x32_bf16 v[28:31], v[140:143], v[186:189], v[28:31]
	v_mfma_f32_16x16x32_bf16 v[24:27], v[158:161], v[186:189], v[24:27]
	v_mfma_f32_16x16x32_bf16 v[12:15], v[140:143], v[194:197], v[12:15]
	v_mfma_f32_16x16x32_bf16 v[8:11], v[158:161], v[194:197], v[8:11]
	v_mfma_f32_16x16x32_bf16 v[60:63], v[146:149], v[174:177], v[60:63]
	v_mfma_f32_16x16x32_bf16 v[56:59], v[162:165], v[174:177], v[56:59]
	v_mfma_f32_16x16x32_bf16 v[44:47], v[146:149], v[182:185], v[44:47]
	v_mfma_f32_16x16x32_bf16 v[40:43], v[162:165], v[182:185], v[40:43]
	v_mfma_f32_16x16x32_bf16 v[28:31], v[146:149], v[190:193], v[28:31]
	v_mfma_f32_16x16x32_bf16 v[24:27], v[162:165], v[190:193], v[24:27]
	v_mfma_f32_16x16x32_bf16 v[12:15], v[146:149], v[198:201], v[12:15]
	v_mfma_f32_16x16x32_bf16 v[8:11], v[162:165], v[198:201], v[8:11]
	s_setprio 0
	s_barrier
; #define PG8_STAGE(bufoff, gbase, voff) do { _Pragma("unroll") for (int _i = 0; _i < 2; ++_i) \
;         __builtin_amdgcn_global_load_lds((const unsigned*)((const char*)(gbase) + (voff)[_i]), (LAS unsigned*)(lds + (bufoff) + ldsw + _i * 8192), 16, 0, 0); } while (0)
; #define PG8_LDA(dst, b, h) do { _Pragma("unroll") for (int m = 0; m < 4; ++m) _Pragma("unroll") for (int k = 0; k < 2; ++k) dst[m][k] = *(const LAS bf16x8*)(lds + PG8_SA(b, h) + aoff + m * 2048 + k * 1024); } while (0)
; #define PG8_LDB(dst, b, h) do { _Pragma("unroll") for (int n = 0; n < 2; ++n) _Pragma("unroll") for (int k = 0; k < 2; ++k) dst[n][k] = *(const LAS bf16x8*)(lds + PG8_SB(b, h) + boff + n * 2048 + k * 1024); } while (0)
; #define PG8_MMA(ai, bj, At, Bt) do { __builtin_amdgcn_s_setprio(1); _Pragma("unroll") for (int m = 0; m < 4; ++m) _Pragma("unroll") for (int n = 0; n < 2; ++n) _Pragma("unroll") for (int k = 0; k < 2; ++k) \
;         acc[ai][bj][m][n] = __builtin_amdgcn_mfma_f32_16x16x32_bf16(Bt[n][k], At[m][k], acc[ai][bj][m][n], 0, 0, 0); __builtin_amdgcn_s_setprio(0); } while (0)
; #define PG8_WAIT_V(n) asm volatile("s_waitcnt vmcnt(" #n ")" ::: "memory")
; #define PG8_WAIT_L(n) asm volatile("s_waitcnt lgkmcnt(" #n ")" ::: "memory")
; #define PG8_BAR __builtin_amdgcn_s_barrier()
; #define PG8_SCHED __builtin_amdgcn_sched_barrier(0)
;     ...
;             PG8_STAGE(PG8_SB(0, 1), b2 + hB, voffB);
;             PG8_WAIT_V(6); PG8_BAR; PG8_MMA(1, 1, At, B1); PG8_BAR;
;             PG8_LDB(B0, 1, 0); PG8_SCHED; PG8_LDA(At, 1, 0); PG8_STAGE(PG8_SA(0, 1), a2 + hA, voffA);
;             PG8_WAIT_L(8); PG8_BAR; PG8_WAIT_L(0); PG8_MMA(0, 0, At, B0); PG8_BAR; PG8_SCHED;
;             PG8_LDB(B1, 1, 1); PG8_STAGE(PG8_SB(1, 0), b3, voffB);
;             PG8_BAR; PG8_WAIT_L(0); PG8_MMA(0, 1, At, B1); PG8_BAR;
;             PG8_LDA(At, 1, 1); PG8_STAGE(PG8_SA(1, 0), a3, voffA);
;             PG8_BAR; PG8_WAIT_L(0); PG8_MMA(1, 0, At, B0); PG8_BAR; PG8_SCHED;
	s_add_u32 s76, s12, 0x20000
	s_addc_u32 s77, s13, 0
	s_add_i32 s53, s72, s61
	v_lshl_add_u64 v[140:141], s[76:77], 0, v[130:131]
	s_mov_b32 m0, s53
	s_nop 0
	global_load_lds_dwordx4 v[140:141], off
	v_lshl_add_u64 v[140:141], s[76:77], 0, v[134:135]
	s_add_i32 m0, s53, 0x2000
	s_nop 0
	global_load_lds_dwordx4 v[140:141], off
	s_waitcnt vmcnt(6)
	s_barrier
	s_setprio 1
	v_mfma_f32_16x16x32_bf16 v[52:55], v[202:205], v[170:173], v[52:55]
	v_mfma_f32_16x16x32_bf16 v[48:51], v[210:213], v[170:173], v[48:51]
	v_mfma_f32_16x16x32_bf16 v[36:39], v[202:205], v[178:181], v[36:39]
	v_mfma_f32_16x16x32_bf16 v[32:35], v[210:213], v[178:181], v[32:35]
	v_mfma_f32_16x16x32_bf16 v[20:23], v[202:205], v[186:189], v[20:23]
	v_mfma_f32_16x16x32_bf16 v[16:19], v[210:213], v[186:189], v[16:19]
	v_mfma_f32_16x16x32_bf16 v[4:7], v[202:205], v[194:197], v[4:7]
	v_mfma_f32_16x16x32_bf16 v[0:3], v[210:213], v[194:197], v[0:3]
	v_mfma_f32_16x16x32_bf16 v[52:55], v[206:209], v[174:177], v[52:55]
	v_mfma_f32_16x16x32_bf16 v[48:51], v[214:217], v[174:177], v[48:51]
	v_mfma_f32_16x16x32_bf16 v[36:39], v[206:209], v[182:185], v[36:39]
	v_mfma_f32_16x16x32_bf16 v[32:35], v[214:217], v[182:185], v[32:35]
	v_mfma_f32_16x16x32_bf16 v[20:23], v[206:209], v[190:193], v[20:23]
	v_mfma_f32_16x16x32_bf16 v[16:19], v[214:217], v[190:193], v[16:19]
	v_mfma_f32_16x16x32_bf16 v[4:7], v[206:209], v[198:201], v[4:7]
	v_mfma_f32_16x16x32_bf16 v[0:3], v[214:217], v[198:201], v[0:3]
	s_setprio 0
	s_add_i32 s53, 0, 0x18000
	v_add_u32_e32 v162, s53, v153
	s_barrier
	ds_read_b128 v[140:143], v162
	ds_read_b128 v[146:149], v162 offset:1024
	ds_read_b128 v[158:161], v162 offset:2048
	ds_read_b128 v[162:165], v162 offset:3072
	s_add_u32 s14, s14, 0x20000
	s_addc_u32 s15, s15, 0
	s_mov_b32 m0, s64
	v_lshl_add_u64 v[202:203], s[14:15], 0, v[128:129]
	ds_read_b128 v[170:173], v156 offset:32768
	ds_read_b128 v[174:177], v156 offset:33792
	ds_read_b128 v[178:181], v156 offset:34816
	ds_read_b128 v[182:185], v156 offset:35840
	ds_read_b128 v[186:189], v156 offset:36864
	ds_read_b128 v[190:193], v156 offset:37888
	ds_read_b128 v[194:197], v156 offset:38912
	ds_read_b128 v[198:201], v156 offset:39936
	global_load_lds_dwordx4 v[202:203], off
	v_lshl_add_u64 v[202:203], s[14:15], 0, v[132:133]
	s_mov_b32 m0, s65
	s_nop 0
	global_load_lds_dwordx4 v[202:203], off
	s_waitcnt lgkmcnt(8)
	s_barrier
	s_waitcnt lgkmcnt(0)
	s_setprio 1
	s_waitcnt lgkmcnt(0)
	v_mfma_f32_16x16x32_bf16 v[124:127], v[140:143], v[170:173], v[124:127]
	v_mfma_f32_16x16x32_bf16 v[120:123], v[158:161], v[170:173], v[120:123]
	v_mfma_f32_16x16x32_bf16 v[108:111], v[140:143], v[178:181], v[108:111]
	v_mfma_f32_16x16x32_bf16 v[104:107], v[158:161], v[178:181], v[104:107]
	v_mfma_f32_16x16x32_bf16 v[92:95], v[140:143], v[186:189], v[92:95]
	v_mfma_f32_16x16x32_bf16 v[88:91], v[158:161], v[186:189], v[88:91]
	v_mfma_f32_16x16x32_bf16 v[76:79], v[140:143], v[194:197], v[76:79]
	v_mfma_f32_16x16x32_bf16 v[72:75], v[158:161], v[194:197], v[72:75]
	v_mfma_f32_16x16x32_bf16 v[124:127], v[146:149], v[174:177], v[124:127]
	v_mfma_f32_16x16x32_bf16 v[120:123], v[162:165], v[174:177], v[120:123]
	v_mfma_f32_16x16x32_bf16 v[108:111], v[146:149], v[182:185], v[108:111]
	v_mfma_f32_16x16x32_bf16 v[104:107], v[162:165], v[182:185], v[104:107]
	v_mfma_f32_16x16x32_bf16 v[92:95], v[146:149], v[190:193], v[92:95]
	v_mfma_f32_16x16x32_bf16 v[88:91], v[162:165], v[190:193], v[88:91]
	v_mfma_f32_16x16x32_bf16 v[76:79], v[146:149], v[198:201], v[76:79]
	v_mfma_f32_16x16x32_bf16 v[72:75], v[162:165], v[198:201], v[72:75]
	s_setprio 0
	s_barrier
	s_add_i32 s14, 0, 0x1c000
	s_add_i32 s15, s53, s61
	v_add_u32_e32 v169, s14, v153
	v_lshl_add_u64 v[150:151], v[150:151], 0, s[38:39]
	s_mov_b32 m0, s15
	ds_read_b128 v[202:205], v169
	ds_read_b128 v[206:209], v169 offset:1024
	ds_read_b128 v[210:213], v169 offset:2048
	ds_read_b128 v[214:217], v169 offset:3072
	global_load_lds_dwordx4 v[150:151], off
	v_lshl_add_u64 v[150:151], v[218:219], 0, s[38:39]
	s_add_i32 m0, s15, 0x2000
	s_nop 0
	global_load_lds_dwordx4 v[150:151], off
	s_barrier
	s_waitcnt lgkmcnt(0)
	s_setprio 1
	s_waitcnt lgkmcnt(0)
	v_mfma_f32_16x16x32_bf16 v[116:119], v[202:205], v[170:173], v[116:119]
	v_mfma_f32_16x16x32_bf16 v[112:115], v[210:213], v[170:173], v[112:115]
	v_mfma_f32_16x16x32_bf16 v[100:103], v[202:205], v[178:181], v[100:103]
	v_mfma_f32_16x16x32_bf16 v[96:99], v[210:213], v[178:181], v[96:99]
	v_mfma_f32_16x16x32_bf16 v[84:87], v[202:205], v[186:189], v[84:87]
	v_mfma_f32_16x16x32_bf16 v[80:83], v[210:213], v[186:189], v[80:83]
	v_mfma_f32_16x16x32_bf16 v[68:71], v[202:205], v[194:197], v[68:71]
	v_mfma_f32_16x16x32_bf16 v[64:67], v[210:213], v[194:197], v[64:67]
	v_mfma_f32_16x16x32_bf16 v[116:119], v[206:209], v[174:177], v[116:119]
	v_mfma_f32_16x16x32_bf16 v[112:115], v[214:217], v[174:177], v[112:115]
	v_mfma_f32_16x16x32_bf16 v[100:103], v[206:209], v[182:185], v[100:103]
	v_mfma_f32_16x16x32_bf16 v[96:99], v[214:217], v[182:185], v[96:99]
	v_mfma_f32_16x16x32_bf16 v[84:87], v[206:209], v[190:193], v[84:87]
	v_mfma_f32_16x16x32_bf16 v[80:83], v[214:217], v[190:193], v[80:83]
	v_mfma_f32_16x16x32_bf16 v[68:71], v[206:209], v[198:201], v[68:71]
	v_mfma_f32_16x16x32_bf16 v[64:67], v[214:217], v[198:201], v[64:67]
	s_setprio 0
	s_mov_b32 m0, s67
	v_lshl_add_u64 v[150:151], v[220:221], 0, s[38:39]
	s_barrier
	ds_read_b128 v[170:173], v156 offset:49152
	ds_read_b128 v[174:177], v156 offset:50176
	ds_read_b128 v[178:181], v156 offset:51200
	ds_read_b128 v[182:185], v156 offset:52224
	ds_read_b128 v[186:189], v156 offset:53248
	ds_read_b128 v[190:193], v156 offset:54272
	ds_read_b128 v[194:197], v156 offset:55296
	ds_read_b128 v[198:201], v156 offset:56320
	global_load_lds_dwordx4 v[150:151], off
	v_lshl_add_u64 v[150:151], v[222:223], 0, s[38:39]
	s_mov_b32 m0, s68
	s_nop 0
	global_load_lds_dwordx4 v[150:151], off
	s_barrier
; __device__ __forceinline__ float sigmoidf_(float x) { return 1.0f / (1.0f + __expf(-x)); }
; #define PG8_STAGE(bufoff, gbase, voff) do { _Pragma("unroll") for (int _i = 0; _i < 2; ++_i) \
;         __builtin_amdgcn_global_load_lds((const unsigned*)((const char*)(gbase) + (voff)[_i]), (LAS unsigned*)(lds + (bufoff) + ldsw + _i * 8192), 16, 0, 0); } while (0)
; #define PG8_LDA(dst, b, h) do { _Pragma("unroll") for (int m = 0; m < 4; ++m) _Pragma("unroll") for (int k = 0; k < 2; ++k) dst[m][k] = *(const LAS bf16x8*)(lds + PG8_SA(b, h) + aoff + m * 2048 + k * 1024); } while (0)
; #define PG8_WAIT_V(n) asm volatile("s_waitcnt vmcnt(" #n ")" ::: "memory")
; #define PG8_WAIT_L(n) asm volatile("s_waitcnt lgkmcnt(" #n ")" ::: "memory")
; #define PG8_BAR __builtin_amdgcn_s_barrier()
;     ...
;             PG8_LDA(At, 1, 1); PG8_STAGE(PG8_SA(1, 0), a3, voffA);
;             PG8_BAR; PG8_WAIT_L(0); PG8_MMA(1, 0, At, B0); PG8_BAR; PG8_SCHED;
;             PG8_STAGE(PG8_SB(1, 1), b3 + hB, voffB);
;             PG8_WAIT_V(6); PG8_BAR; PG8_MMA(1, 1, At, B1); PG8_BAR;
;         }
;     __device__ __forceinline__ void operator()(const f32x4 (&acc)[2][2][4][2], const Unit& u, int wr, int wc, int fr, int fq) const {
;         const __amdgpu_buffer_rsrc_t rsrc = __builtin_amdgcn_make_buffer_rsrc((void*)z, 0, T_ALL * DIN * 2, 0x00020000);
;         const int row0 = row_off + u.pm * 256 + wr * 64 + fr, col0 = u.pn * 256 + wc * 32 + 8 * fq;
; #pragma unroll
;         for (int ai = 0; ai < 2; ++ai)
; #pragma unroll
;             for (int m = 0; m < 4; ++m) {
;                 const int row = row0 + ai * 128 + m * 16;
;                 const bf16_t* rowp = z + (size_t)row * DIN + col0;
; #pragma unroll
;                 for (int bj = 0; bj < 2; ++bj) {
;                     const u32x4 gw = *(const u32x4*)(rowp + O_GA + bj * 128);
;                     f32x4 g0, g1; unpack8(gw, g0, g1);
;                     f32x4 v0, v1;
; #pragma unroll
;                     for (int j = 0; j < 4; ++j) { v0[j] = sigmoidf_(g0[j]) * acc[ai][bj][m][0][j]; v1[j] = sigmoidf_(g1[j]) * acc[ai][bj][m][1][j]; }
;                     const u32x4 mw = *(const u32x4*)(rowp + bj * 128); f32x4 m0, m1; unpack8(mw, m0, m1); v0 += m0; v1 += m1;
;                     __builtin_amdgcn_raw_buffer_store_b128(pack8(v0, v1), rsrc, (unsigned)(((size_t)row * DIN + col0 + bj * 128) * 2), 0, 16  ); }
	s_waitcnt lgkmcnt(0)
	s_setprio 1
	s_waitcnt lgkmcnt(0)
	v_mfma_f32_16x16x32_bf16 v[60:63], v[140:143], v[170:173], v[60:63]
	v_mfma_f32_16x16x32_bf16 v[56:59], v[158:161], v[170:173], v[56:59]
	v_mfma_f32_16x16x32_bf16 v[44:47], v[140:143], v[178:181], v[44:47]
	v_mfma_f32_16x16x32_bf16 v[40:43], v[158:161], v[178:181], v[40:43]
	v_mfma_f32_16x16x32_bf16 v[28:31], v[140:143], v[186:189], v[28:31]
	v_mfma_f32_16x16x32_bf16 v[24:27], v[158:161], v[186:189], v[24:27]
	v_mfma_f32_16x16x32_bf16 v[12:15], v[140:143], v[194:197], v[12:15]
	v_mfma_f32_16x16x32_bf16 v[8:11], v[158:161], v[194:197], v[8:11]
	v_mfma_f32_16x16x32_bf16 v[60:63], v[146:149], v[174:177], v[60:63]
	v_mfma_f32_16x16x32_bf16 v[56:59], v[162:165], v[174:177], v[56:59]
	v_mfma_f32_16x16x32_bf16 v[44:47], v[146:149], v[182:185], v[44:47]
	v_mfma_f32_16x16x32_bf16 v[40:43], v[162:165], v[182:185], v[40:43]
	v_mfma_f32_16x16x32_bf16 v[28:31], v[146:149], v[190:193], v[28:31]
	v_mfma_f32_16x16x32_bf16 v[24:27], v[162:165], v[190:193], v[24:27]
	v_mfma_f32_16x16x32_bf16 v[12:15], v[146:149], v[198:201], v[12:15]
	v_mfma_f32_16x16x32_bf16 v[8:11], v[162:165], v[198:201], v[8:11]
	s_setprio 0
	s_barrier
	s_add_u32 s12, s12, 0x20080
	s_addc_u32 s13, s13, 0
	s_add_i32 s14, s14, s61
	v_lshl_add_u64 v[140:141], s[12:13], 0, v[130:131]
	s_mov_b32 m0, s14
	s_nop 0
	global_load_lds_dwordx4 v[140:141], off
	v_lshl_add_u64 v[140:141], s[12:13], 0, v[134:135]
	s_add_i32 m0, s14, 0x2000
	s_nop 0
	global_load_lds_dwordx4 v[140:141], off
	s_waitcnt vmcnt(6)
	s_barrier
	s_setprio 1
	v_mfma_f32_16x16x32_bf16 v[52:55], v[202:205], v[170:173], v[52:55]
	v_mfma_f32_16x16x32_bf16 v[48:51], v[210:213], v[170:173], v[48:51]
	v_mfma_f32_16x16x32_bf16 v[36:39], v[202:205], v[178:181], v[36:39]
	v_mfma_f32_16x16x32_bf16 v[32:35], v[210:213], v[178:181], v[32:35]
	v_mfma_f32_16x16x32_bf16 v[20:23], v[202:205], v[186:189], v[20:23]
	v_mfma_f32_16x16x32_bf16 v[16:19], v[210:213], v[186:189], v[16:19]
	v_mfma_f32_16x16x32_bf16 v[4:7], v[202:205], v[194:197], v[4:7]
	v_mfma_f32_16x16x32_bf16 v[0:3], v[210:213], v[194:197], v[0:3]
	v_mfma_f32_16x16x32_bf16 v[52:55], v[206:209], v[174:177], v[52:55]
	v_mfma_f32_16x16x32_bf16 v[48:51], v[214:217], v[174:177], v[48:51]
	v_mfma_f32_16x16x32_bf16 v[36:39], v[206:209], v[182:185], v[36:39]
	v_mfma_f32_16x16x32_bf16 v[32:35], v[214:217], v[182:185], v[32:35]
	v_mfma_f32_16x16x32_bf16 v[20:23], v[206:209], v[190:193], v[20:23]
	v_mfma_f32_16x16x32_bf16 v[16:19], v[214:217], v[190:193], v[16:19]
	v_mfma_f32_16x16x32_bf16 v[4:7], v[206:209], v[198:201], v[4:7]
	v_mfma_f32_16x16x32_bf16 v[0:3], v[214:217], v[198:201], v[0:3]
	s_setprio 0
	s_add_i32 s45, s45, 2
	s_add_u32 s37, s37, 0x100
	s_addc_u32 s44, s44, 0
	s_add_u32 s10, s10, 0x100
	s_addc_u32 s11, s11, 0
	s_cmp_gt_u32 s45, 5
	s_barrier
	s_cbranch_scc0 .LBB0_1864
	v_lshl_add_u32 v158, s75, 8, v152
	v_lshl_or_b32 v140, s6, 8, v154
	v_add_u32_e32 v142, 0x4000, v158
	v_ashrrev_i32_e32 v141, 31, v140
	v_mad_i64_i32 v[150:151], s[6:7], v142, s73, 0
	v_lshl_add_u64 v[146:147], v[150:151], 1, s[34:35]
	v_lshlrev_b64 v[142:143], 1, v[140:141]
	v_lshl_add_u64 v[146:147], v[146:147], 0, v[142:143]
	v_add_co_u32_e32 v148, vcc, 0x1000, v146
	s_nop 1
	v_addc_co_u32_e32 v149, vcc, 0, v147, vcc
	v_subrev_u32_e32 v197, s34, v146
	v_add_u32_e32 v198, 0x1200, v197
	global_load_dwordx4 v[200:203], v198, s[34:35]
	v_add_u32_e32 v198, 0x0, v197
	global_load_dwordx4 v[204:207], v198, s[34:35]
	v_add_u32_e32 v198, 0x1300, v197
	global_load_dwordx4 v[208:211], v198, s[34:35]
	v_add_u32_e32 v198, 0x100, v197
	global_load_dwordx4 v[212:215], v198, s[34:35]
	v_add_u32_e32 v198, 0x23200, v197
	global_load_dwordx4 v[232:235], v198, s[34:35]
	v_add_u32_e32 v198, 0x22000, v197
	global_load_dwordx4 v[236:239], v198, s[34:35]
	v_add_u32_e32 v198, 0x23300, v197
	global_load_dwordx4 v[240:243], v198, s[34:35]
	v_add_u32_e32 v198, 0x22100, v197
	global_load_dwordx4 v[244:247], v198, s[34:35]
	v_add_u32_e32 v198, 0x45200, v197
	global_load_dwordx4 v[248:251], v198, s[34:35]
	v_add_u32_e32 v198, 0x44000, v197
	global_load_dwordx4 v[252:255], v198, s[34:35]
	s_waitcnt vmcnt(8)
	v_mov_b32_e32 v160, v200
	v_mov_b32_e32 v161, v201
	v_mov_b32_e32 v162, v202
	v_mov_b32_e32 v163, v203
	v_mov_b32_e32 v170, v204
	v_mov_b32_e32 v171, v205
	v_mov_b32_e32 v172, v206
	v_mov_b32_e32 v173, v207
	v_add_u32_e32 v198, 0x45300, v197
	global_load_dwordx4 v[200:203], v198, s[34:35]
	v_add_u32_e32 v198, 0x44100, v197
	global_load_dwordx4 v[204:207], v198, s[34:35]
	v_lshlrev_b32_e32 v141, 16, v160
	v_and_b32_e32 v151, 0xffff0000, v160
	v_lshlrev_b32_e32 v159, 16, v161
	v_and_b32_e32 v160, 0xffff0000, v161
	v_lshlrev_b32_e32 v161, 16, v162
	v_and_b32_e32 v162, 0xffff0000, v162
	v_mul_f32_e32 v141, 0xbfb8aa3b, v141
	v_mul_f32_e32 v161, 0xbfb8aa3b, v161
	v_mul_f32_e32 v151, 0xbfb8aa3b, v151
	v_mul_f32_e32 v169, 0xbfb8aa3b, v162
	v_mul_f32_e32 v165, 0xbfb8aa3b, v160
	v_exp_f32_e32 v160, v141
	v_exp_f32_e32 v162, v161
	v_exp_f32_e32 v161, v151
	v_lshlrev_b32_e32 v164, 16, v163
	v_mul_f32_e32 v159, 0xbfb8aa3b, v159
	v_mul_f32_e32 v174, 0xbfb8aa3b, v164
	v_exp_f32_e32 v164, v159
	v_exp_f32_e32 v165, v165
	v_and_b32_e32 v163, 0xffff0000, v163
	v_mul_f32_e32 v163, 0xbfb8aa3b, v163
	v_pk_add_f32 v[160:161], v[160:161], 1.0 op_sel_hi:[1,0]
	v_exp_f32_e32 v175, v163
	v_exp_f32_e32 v163, v169
	v_div_scale_f32 v141, s[6:7], v161, v161, 1.0
	v_pk_add_f32 v[164:165], v[164:165], 1.0 op_sel_hi:[1,0]
	v_div_scale_f32 v159, s[6:7], v160, v160, 1.0
	v_rcp_f32_e32 v182, v141
	v_div_scale_f32 v176, s[6:7], v165, v165, 1.0
	v_rcp_f32_e32 v183, v159
	v_div_scale_f32 v178, s[6:7], v164, v164, 1.0
; __device__ __forceinline__ float sigmoidf_(float x) { return 1.0f / (1.0f + __expf(-x)); }
; __device__ __forceinline__ u32x4 pack8(const f32x4 v0, const f32x4 v1) { u32x4 w; w.x = pk2(v0[0], v0[1]); w.y = pk2(v0[2], v0[3]); w.z = pk2(v1[0], v1[1]); w.w = pk2(v1[2], v1[3]); return w; }
; __device__ __forceinline__ void unpack8(const u32x4 w, f32x4& v0, f32x4& v1) { v0 = (f32x4){bflo(w.x), bfhi(w.x), bflo(w.y), bfhi(w.y)}; v1 = (f32x4){bflo(w.z), bfhi(w.z), bflo(w.w), bfhi(w.w)}; }
;     __device__ __forceinline__ void operator()(const f32x4 (&acc)[2][2][4][2], const Unit& u, int wr, int wc, int fr, int fq) const {
;     ...
;         for (int ai = 0; ai < 2; ++ai)
; #pragma unroll
;             for (int m = 0; m < 4; ++m) {
;                 const int row = row0 + ai * 128 + m * 16;
;                 const bf16_t* rowp = z + (size_t)row * DIN + col0;
; #pragma unroll
;                 for (int bj = 0; bj < 2; ++bj) {
;                     const u32x4 gw = *(const u32x4*)(rowp + O_GA + bj * 128);
;                     f32x4 g0, g1; unpack8(gw, g0, g1);
;                     f32x4 v0, v1;
; #pragma unroll
;                     for (int j = 0; j < 4; ++j) { v0[j] = sigmoidf_(g0[j]) * acc[ai][bj][m][0][j]; v1[j] = sigmoidf_(g1[j]) * acc[ai][bj][m][1][j]; }
;                     const u32x4 mw = *(const u32x4*)(rowp + bj * 128); f32x4 m0, m1; unpack8(mw, m0, m1); v0 += m0; v1 += m1;
;                     __builtin_amdgcn_raw_buffer_store_b128(pack8(v0, v1), rsrc, (unsigned)(((size_t)row * DIN + col0 + bj * 128) * 2), 0, 16  ); }
	v_rcp_f32_e32 v184, v176
	v_pk_add_f32 v[162:163], v[162:163], 1.0 op_sel_hi:[1,0]
	v_rcp_f32_e32 v185, v178
	v_div_scale_f32 v180, s[6:7], v163, v163, 1.0
	v_fma_f32 v187, -v141, v182, 1.0
	v_div_scale_f32 v151, vcc, 1.0, v161, 1.0
	v_rcp_f32_e32 v186, v180
	v_fma_f32 v188, -v159, v183, 1.0
	v_fmac_f32_e32 v182, v187, v182
	v_div_scale_f32 v169, s[10:11], 1.0, v160, 1.0
	v_fma_f32 v189, -v176, v184, 1.0
	v_fmac_f32_e32 v183, v188, v183
	v_mul_f32_e32 v187, v151, v182
	v_div_scale_f32 v177, s[12:13], 1.0, v165, 1.0
	v_fma_f32 v190, -v178, v185, 1.0
	v_fmac_f32_e32 v184, v189, v184
	v_mul_f32_e32 v188, v169, v183
	v_fma_f32 v192, -v141, v187, v151
	v_div_scale_f32 v179, s[14:15], 1.0, v164, 1.0
	v_fmac_f32_e32 v185, v190, v185
	v_mul_f32_e32 v189, v177, v184
	v_fma_f32 v193, -v159, v188, v169
	v_fmac_f32_e32 v187, v192, v182
	v_fma_f32 v191, -v180, v186, 1.0
	v_mul_f32_e32 v190, v179, v185
	v_fma_f32 v194, -v176, v189, v177
	v_fmac_f32_e32 v188, v193, v183
	v_fma_f32 v141, -v141, v187, v151
	v_div_scale_f32 v181, s[16:17], 1.0, v163, 1.0
	v_fmac_f32_e32 v186, v191, v186
	v_fma_f32 v195, -v178, v190, v179
	v_fmac_f32_e32 v189, v194, v184
	v_fma_f32 v151, -v159, v188, v169
	v_div_fmas_f32 v141, v141, v182, v187
	s_mov_b64 vcc, s[10:11]
	v_mul_f32_e32 v191, v181, v186
	v_fmac_f32_e32 v190, v195, v185
	v_fma_f32 v159, -v176, v189, v177
	v_div_fixup_f32 v161, v141, v161, 1.0
	v_div_fmas_f32 v141, v151, v183, v188
	s_mov_b64 vcc, s[12:13]
	v_div_scale_f32 v151, s[6:7], v162, v162, 1.0
	v_fma_f32 v196, -v180, v191, v181
	v_fma_f32 v169, -v178, v190, v179
	v_div_fixup_f32 v160, v141, v160, 1.0
	v_div_fmas_f32 v141, v159, v184, v189
	s_mov_b64 vcc, s[14:15]
	v_rcp_f32_e32 v159, v151
	v_fmac_f32_e32 v191, v196, v186
	v_div_fixup_f32 v165, v141, v165, 1.0
	v_div_fmas_f32 v141, v169, v185, v190
	v_div_fixup_f32 v164, v141, v164, 1.0
	v_fma_f32 v141, -v180, v191, v181
	s_mov_b64 vcc, s[16:17]
	v_div_fmas_f32 v141, v141, v186, v191
	v_exp_f32_e32 v174, v174
	v_div_fixup_f32 v163, v141, v163, 1.0
	v_fma_f32 v141, -v151, v159, 1.0
	v_fmac_f32_e32 v159, v141, v159
	v_div_scale_f32 v141, vcc, 1.0, v162, 1.0
	v_mul_f32_e32 v169, v141, v159
	v_fma_f32 v176, -v151, v169, v141
	v_pk_add_f32 v[174:175], v[174:175], 1.0 op_sel_hi:[1,0]
	v_fmac_f32_e32 v169, v176, v159
	v_fma_f32 v141, -v151, v169, v141
	v_div_scale_f32 v151, s[6:7], v175, v175, 1.0
	v_rcp_f32_e32 v176, v151
	v_div_fmas_f32 v141, v141, v159, v169
	v_div_fixup_f32 v162, v141, v162, 1.0
	v_and_b32_e32 v177, 0xffff0000, v170
	v_fma_f32 v141, -v151, v176, 1.0
	v_fmac_f32_e32 v176, v141, v176
	v_div_scale_f32 v141, vcc, 1.0, v175, 1.0
	v_mul_f32_e32 v159, v141, v176
	v_fma_f32 v169, -v151, v159, v141
	v_fmac_f32_e32 v159, v169, v176
	v_fma_f32 v141, -v151, v159, v141
	v_div_scale_f32 v151, s[6:7], v174, v174, 1.0
	v_rcp_f32_e32 v169, v151
	v_div_fmas_f32 v141, v141, v176, v159
	v_div_fixup_f32 v175, v141, v175, 1.0
	v_lshlrev_b32_e32 v178, 16, v172
	v_fma_f32 v141, -v151, v169, 1.0
	v_fmac_f32_e32 v169, v141, v169
	v_div_scale_f32 v141, vcc, 1.0, v174, 1.0
	v_mul_f32_e32 v159, v141, v169
	v_fma_f32 v176, -v151, v159, v141
	v_fmac_f32_e32 v159, v176, v169
	v_fma_f32 v141, -v151, v159, v141
	v_div_fmas_f32 v141, v141, v169, v159
	v_div_fixup_f32 v174, v141, v174, 1.0
	v_lshlrev_b32_e32 v176, 16, v170
	v_and_b32_e32 v179, 0xffff0000, v172
	v_lshlrev_b32_e32 v172, 16, v173
	v_and_b32_e32 v173, 0xffff0000, v173
	v_lshlrev_b32_e32 v170, 16, v171
	v_and_b32_e32 v171, 0xffff0000, v171
	v_pk_fma_f32 v[124:125], v[124:125], v[160:161], v[176:177]
	v_pk_fma_f32 v[160:161], v[122:123], v[174:175], v[172:173]
	v_pk_fma_f32 v[122:123], v[120:121], v[162:163], v[178:179]
	v_add_lshl_u32 v141, v140, v150, 1
	v_pk_fma_f32 v[126:127], v[126:127], v[164:165], v[170:171]
	v_cvt_pk_bf16_f32 v120, v124, v125
	s_nop 0
	v_cvt_pk_bf16_f32 v121, v126, v127
	v_cvt_pk_bf16_f32 v122, v122, v123
	v_cvt_pk_bf16_f32 v123, v160, v161
	buffer_store_dwordx4 v[120:123], v141, s[20:23], 0 offen sc1
	s_nop 0
	s_waitcnt vmcnt(9)
	v_mov_b32_e32 v120, v208
	v_mov_b32_e32 v121, v209
	v_mov_b32_e32 v122, v210
	v_mov_b32_e32 v123, v211
	v_mov_b32_e32 v124, v212
	v_mov_b32_e32 v125, v213
	v_mov_b32_e32 v126, v214
	v_mov_b32_e32 v127, v215
	v_add_u32_e32 v198, 0x67200, v197
	global_load_dwordx4 v[208:211], v198, s[34:35]
	v_add_u32_e32 v198, 0x66000, v197
	global_load_dwordx4 v[212:215], v198, s[34:35]
	v_lshlrev_b32_e32 v146, 16, v120
	v_and_b32_e32 v120, 0xffff0000, v120
	v_lshlrev_b32_e32 v147, 16, v121
	v_and_b32_e32 v121, 0xffff0000, v121
	v_lshlrev_b32_e32 v148, 16, v122
	v_and_b32_e32 v122, 0xffff0000, v122
	v_lshlrev_b32_e32 v149, 16, v123
	v_and_b32_e32 v150, 0xffff0000, v123
	v_mul_f32_e32 v123, 0xbfb8aa3b, v146
	v_mul_f32_e32 v146, 0xbfb8aa3b, v148
	v_mul_f32_e32 v148, 0xbfb8aa3b, v120
	v_mul_f32_e32 v147, 0xbfb8aa3b, v147
	v_mul_f32_e32 v121, 0xbfb8aa3b, v121
	v_mul_f32_e32 v151, 0xbfb8aa3b, v122
	v_exp_f32_e32 v120, v123
	v_exp_f32_e32 v122, v146
	v_exp_f32_e32 v146, v147
	v_exp_f32_e32 v147, v121
	v_exp_f32_e32 v121, v148
	v_mul_f32_e32 v149, 0xbfb8aa3b, v149
	v_exp_f32_e32 v148, v149
	v_exp_f32_e32 v123, v151
	v_pk_add_f32 v[120:121], v[120:121], 1.0 op_sel_hi:[1,0]
	v_pk_add_f32 v[146:147], v[146:147], 1.0 op_sel_hi:[1,0]
	v_div_scale_f32 v149, s[6:7], v121, v121, 1.0
	v_rcp_f32_e32 v159, v149
	v_div_scale_f32 v151, vcc, 1.0, v121, 1.0
	v_div_scale_f32 v160, s[6:7], v120, v120, 1.0
	v_fma_f32 v162, -v149, v159, 1.0
	v_fmac_f32_e32 v159, v162, v159
	v_mul_f32_e32 v162, v151, v159
	v_rcp_f32_e32 v161, v160
	v_fma_f32 v163, -v149, v162, v151
	v_fmac_f32_e32 v162, v163, v159
	v_fma_f32 v149, -v149, v162, v151
	v_div_fmas_f32 v149, v149, v159, v162
; __device__ __forceinline__ float sigmoidf_(float x) { return 1.0f / (1.0f + __expf(-x)); }
; __device__ __forceinline__ u32x4 pack8(const f32x4 v0, const f32x4 v1) { u32x4 w; w.x = pk2(v0[0], v0[1]); w.y = pk2(v0[2], v0[3]); w.z = pk2(v1[0], v1[1]); w.w = pk2(v1[2], v1[3]); return w; }
; __device__ __forceinline__ void unpack8(const u32x4 w, f32x4& v0, f32x4& v1) { v0 = (f32x4){bflo(w.x), bfhi(w.x), bflo(w.y), bfhi(w.y)}; v1 = (f32x4){bflo(w.z), bfhi(w.z), bflo(w.w), bfhi(w.w)}; }
;     __device__ __forceinline__ void operator()(const f32x4 (&acc)[2][2][4][2], const Unit& u, int wr, int wc, int fr, int fq) const {
;     ...
;         for (int ai = 0; ai < 2; ++ai)
; #pragma unroll
;             for (int m = 0; m < 4; ++m) {
;                 const int row = row0 + ai * 128 + m * 16;
;                 const bf16_t* rowp = z + (size_t)row * DIN + col0;
; #pragma unroll
;                 for (int bj = 0; bj < 2; ++bj) {
;                     const u32x4 gw = *(const u32x4*)(rowp + O_GA + bj * 128);
;                     f32x4 g0, g1; unpack8(gw, g0, g1);
;                     f32x4 v0, v1;
; #pragma unroll
;                     for (int j = 0; j < 4; ++j) { v0[j] = sigmoidf_(g0[j]) * acc[ai][bj][m][0][j]; v1[j] = sigmoidf_(g1[j]) * acc[ai][bj][m][1][j]; }
;                     const u32x4 mw = *(const u32x4*)(rowp + bj * 128); f32x4 m0, m1; unpack8(mw, m0, m1); v0 += m0; v1 += m1;
;                     __builtin_amdgcn_raw_buffer_store_b128(pack8(v0, v1), rsrc, (unsigned)(((size_t)row * DIN + col0 + bj * 128) * 2), 0, 16  ); }
	v_div_fixup_f32 v121, v149, v121, 1.0
	v_fma_f32 v149, -v160, v161, 1.0
	v_fmac_f32_e32 v161, v149, v161
	v_div_scale_f32 v149, vcc, 1.0, v120, 1.0
	v_mul_f32_e32 v151, v149, v161
	v_fma_f32 v159, -v160, v151, v149
	v_fmac_f32_e32 v151, v159, v161
	v_div_scale_f32 v159, s[6:7], v147, v147, 1.0
	v_fma_f32 v149, -v160, v151, v149
	v_rcp_f32_e32 v160, v159
	v_div_fmas_f32 v149, v149, v161, v151
	v_div_fixup_f32 v120, v149, v120, 1.0
	v_pk_add_f32 v[122:123], v[122:123], 1.0 op_sel_hi:[1,0]
	v_fma_f32 v149, -v159, v160, 1.0
	v_fmac_f32_e32 v160, v149, v160
	v_div_scale_f32 v149, vcc, 1.0, v147, 1.0
	v_mul_f32_e32 v151, v149, v160
	v_fma_f32 v161, -v159, v151, v149
	v_fmac_f32_e32 v151, v161, v160
	v_fma_f32 v149, -v159, v151, v149
	v_div_scale_f32 v159, s[6:7], v146, v146, 1.0
	v_rcp_f32_e32 v161, v159
	v_div_fmas_f32 v149, v149, v160, v151
	v_div_fixup_f32 v147, v149, v147, 1.0
	v_fma_f32 v149, -v159, v161, 1.0
	v_fmac_f32_e32 v161, v149, v161
	v_div_scale_f32 v149, vcc, 1.0, v146, 1.0
	v_mul_f32_e32 v151, v149, v161
	v_fma_f32 v160, -v159, v151, v149
	v_fmac_f32_e32 v151, v160, v161
	v_fma_f32 v159, -v159, v151, v149
	v_mul_f32_e32 v149, 0xbfb8aa3b, v150
	v_div_scale_f32 v150, s[6:7], v123, v123, 1.0
	v_rcp_f32_e32 v160, v150
	v_div_fmas_f32 v151, v159, v161, v151
	v_div_fixup_f32 v146, v151, v146, 1.0
	v_exp_f32_e32 v149, v149
	v_fma_f32 v151, -v150, v160, 1.0
	v_fmac_f32_e32 v160, v151, v160
	v_div_scale_f32 v151, vcc, 1.0, v123, 1.0
	v_mul_f32_e32 v159, v151, v160
	v_fma_f32 v161, -v150, v159, v151
	v_fmac_f32_e32 v159, v161, v160
	v_fma_f32 v150, -v150, v159, v151
	v_div_scale_f32 v151, s[6:7], v122, v122, 1.0
	v_rcp_f32_e32 v161, v151
	v_div_fmas_f32 v150, v150, v160, v159
	v_div_fixup_f32 v123, v150, v123, 1.0
	v_pk_add_f32 v[148:149], v[148:149], 1.0 op_sel_hi:[1,0]
	v_fma_f32 v150, -v151, v161, 1.0
	v_fmac_f32_e32 v161, v150, v161
	v_div_scale_f32 v150, vcc, 1.0, v122, 1.0
	v_mul_f32_e32 v159, v150, v161
	v_fma_f32 v160, -v151, v159, v150
	v_fmac_f32_e32 v159, v160, v161
	v_fma_f32 v150, -v151, v159, v150
	v_div_scale_f32 v151, s[6:7], v149, v149, 1.0
	v_rcp_f32_e32 v160, v151
	v_div_fmas_f32 v150, v150, v161, v159
	v_div_fixup_f32 v122, v150, v122, 1.0
	v_fma_f32 v150, -v151, v160, 1.0
	v_fmac_f32_e32 v160, v150, v160
	v_div_scale_f32 v150, vcc, 1.0, v149, 1.0
	v_mul_f32_e32 v159, v150, v160
	v_fma_f32 v161, -v151, v159, v150
	v_fmac_f32_e32 v159, v161, v160
	v_fma_f32 v150, -v151, v159, v150
	v_div_scale_f32 v151, s[6:7], v148, v148, 1.0
	v_rcp_f32_e32 v161, v151
	v_div_fmas_f32 v150, v150, v160, v159
	v_div_fixup_f32 v149, v150, v149, 1.0
	v_fma_f32 v150, -v151, v161, 1.0
	v_fmac_f32_e32 v161, v150, v161
	v_div_scale_f32 v150, vcc, 1.0, v148, 1.0
	v_mul_f32_e32 v159, v150, v161
	v_fma_f32 v160, -v151, v159, v150
	v_fmac_f32_e32 v159, v160, v161
	v_fma_f32 v150, -v151, v159, v150
	v_div_fmas_f32 v150, v150, v161, v159
	v_div_fixup_f32 v148, v150, v148, 1.0
	v_lshlrev_b32_e32 v150, 16, v124
	v_and_b32_e32 v151, 0xffff0000, v124
	v_lshlrev_b32_e32 v160, 16, v126
	v_and_b32_e32 v161, 0xffff0000, v126
	v_lshlrev_b32_e32 v126, 16, v127
	v_and_b32_e32 v127, 0xffff0000, v127
	v_lshlrev_b32_e32 v124, 16, v125
	v_and_b32_e32 v125, 0xffff0000, v125
	v_pk_fma_f32 v[116:117], v[116:117], v[120:121], v[150:151]
	v_pk_fma_f32 v[120:121], v[114:115], v[148:149], v[126:127]
	v_pk_fma_f32 v[114:115], v[112:113], v[122:123], v[160:161]
	v_cvt_pk_bf16_f32 v112, v116, v117
	v_pk_fma_f32 v[118:119], v[118:119], v[146:147], v[124:125]
	s_nop 0
	v_cvt_pk_bf16_f32 v113, v118, v119
	v_cvt_pk_bf16_f32 v114, v114, v115
	v_cvt_pk_bf16_f32 v115, v120, v121
	buffer_store_dwordx4 v[112:115], v141, s[20:23], 0 offen offset:256 sc1
	s_nop 1
	v_add_u32_e32 v112, 0x4010, v158
	v_mad_i64_i32 v[114:115], s[6:7], v112, s73, 0
	v_lshl_add_u64 v[112:113], v[114:115], 1, s[34:35]
	v_lshl_add_u64 v[112:113], v[112:113], 0, v[142:143]
	v_add_co_u32_e32 v116, vcc, s74, v112
	s_nop 1
	v_addc_co_u32_e32 v117, vcc, 0, v113, vcc
	s_waitcnt vmcnt(10)
	v_mov_b32_e32 v118, v232
	v_mov_b32_e32 v119, v233
	v_mov_b32_e32 v120, v234
	v_mov_b32_e32 v121, v235
	v_mov_b32_e32 v122, v236
	v_mov_b32_e32 v123, v237
	v_mov_b32_e32 v124, v238
	v_mov_b32_e32 v125, v239
	v_add_u32_e32 v198, 0x67300, v197
	global_load_dwordx4 v[232:235], v198, s[34:35]
	v_add_u32_e32 v198, 0x66100, v197
	global_load_dwordx4 v[236:239], v198, s[34:35]
	v_lshlrev_b32_e32 v115, 16, v118
	v_lshlrev_b32_e32 v127, 16, v119
	v_and_b32_e32 v141, 0xffff0000, v119
	v_lshlrev_b32_e32 v119, 16, v120
	v_mul_f32_e32 v115, 0xbfb8aa3b, v115
	v_and_b32_e32 v126, 0xffff0000, v118
	v_exp_f32_e32 v118, v115
	v_mul_f32_e32 v115, 0xbfb8aa3b, v119
	v_and_b32_e32 v146, 0xffff0000, v120
	v_exp_f32_e32 v120, v115
	v_mul_f32_e32 v115, 0xbfb8aa3b, v126
	v_exp_f32_e32 v119, v115
	v_mul_f32_e32 v115, 0xbfb8aa3b, v146
	v_lshlrev_b32_e32 v147, 16, v121
	v_and_b32_e32 v148, 0xffff0000, v121
	v_exp_f32_e32 v121, v115
	v_mul_f32_e32 v115, 0xbfb8aa3b, v127
	v_exp_f32_e32 v126, v115
	v_mul_f32_e32 v115, 0xbfb8aa3b, v141
	v_pk_add_f32 v[118:119], v[118:119], 1.0 op_sel_hi:[1,0]
	v_exp_f32_e32 v127, v115
	v_div_scale_f32 v115, s[6:7], v119, v119, 1.0
	v_rcp_f32_e32 v141, v115
	v_mul_f32_e32 v146, 0xbfb8aa3b, v147
	v_pk_add_f32 v[126:127], v[126:127], 1.0 op_sel_hi:[1,0]
	v_pk_add_f32 v[120:121], v[120:121], 1.0 op_sel_hi:[1,0]
	v_fma_f32 v147, -v115, v141, 1.0
	v_fmac_f32_e32 v141, v147, v141
	v_div_scale_f32 v147, vcc, 1.0, v119, 1.0
	v_mul_f32_e32 v149, v147, v141
	v_fma_f32 v150, -v115, v149, v147
	v_fmac_f32_e32 v149, v150, v141
	v_fma_f32 v115, -v115, v149, v147
	v_div_scale_f32 v147, s[6:7], v118, v118, 1.0
	v_rcp_f32_e32 v150, v147
; __device__ __forceinline__ float sigmoidf_(float x) { return 1.0f / (1.0f + __expf(-x)); }
; __device__ __forceinline__ u32x4 pack8(const f32x4 v0, const f32x4 v1) { u32x4 w; w.x = pk2(v0[0], v0[1]); w.y = pk2(v0[2], v0[3]); w.z = pk2(v1[0], v1[1]); w.w = pk2(v1[2], v1[3]); return w; }
; __device__ __forceinline__ void unpack8(const u32x4 w, f32x4& v0, f32x4& v1) { v0 = (f32x4){bflo(w.x), bfhi(w.x), bflo(w.y), bfhi(w.y)}; v1 = (f32x4){bflo(w.z), bfhi(w.z), bflo(w.w), bfhi(w.w)}; }
;     __device__ __forceinline__ void operator()(const f32x4 (&acc)[2][2][4][2], const Unit& u, int wr, int wc, int fr, int fq) const {
;     ...
;         for (int ai = 0; ai < 2; ++ai)
; #pragma unroll
;             for (int m = 0; m < 4; ++m) {
;                 const int row = row0 + ai * 128 + m * 16;
;                 const bf16_t* rowp = z + (size_t)row * DIN + col0;
; #pragma unroll
;                 for (int bj = 0; bj < 2; ++bj) {
;                     const u32x4 gw = *(const u32x4*)(rowp + O_GA + bj * 128);
;                     f32x4 g0, g1; unpack8(gw, g0, g1);
;                     f32x4 v0, v1;
; #pragma unroll
;                     for (int j = 0; j < 4; ++j) { v0[j] = sigmoidf_(g0[j]) * acc[ai][bj][m][0][j]; v1[j] = sigmoidf_(g1[j]) * acc[ai][bj][m][1][j]; }
;                     const u32x4 mw = *(const u32x4*)(rowp + bj * 128); f32x4 m0, m1; unpack8(mw, m0, m1); v0 += m0; v1 += m1;
;                     __builtin_amdgcn_raw_buffer_store_b128(pack8(v0, v1), rsrc, (unsigned)(((size_t)row * DIN + col0 + bj * 128) * 2), 0, 16  ); }
	v_div_fmas_f32 v115, v115, v141, v149
	v_div_fixup_f32 v119, v115, v119, 1.0
	v_exp_f32_e32 v146, v146
	v_fma_f32 v115, -v147, v150, 1.0
	v_fmac_f32_e32 v150, v115, v150
	v_div_scale_f32 v115, vcc, 1.0, v118, 1.0
	v_mul_f32_e32 v141, v115, v150
	v_fma_f32 v149, -v147, v141, v115
	v_fmac_f32_e32 v141, v149, v150
	v_fma_f32 v115, -v147, v141, v115
	v_div_scale_f32 v147, s[6:7], v127, v127, 1.0
	v_rcp_f32_e32 v149, v147
	v_div_fmas_f32 v115, v115, v150, v141
	v_div_fixup_f32 v118, v115, v118, 1.0
	v_and_b32_e32 v151, 0xffff0000, v124
	v_fma_f32 v115, -v147, v149, 1.0
	v_fmac_f32_e32 v149, v115, v149
	v_div_scale_f32 v115, vcc, 1.0, v127, 1.0
	v_mul_f32_e32 v141, v115, v149
	v_fma_f32 v150, -v147, v141, v115
	v_fmac_f32_e32 v141, v150, v149
	v_fma_f32 v115, -v147, v141, v115
	v_div_scale_f32 v147, s[6:7], v126, v126, 1.0
	v_rcp_f32_e32 v150, v147
	v_div_fmas_f32 v115, v115, v149, v141
	v_div_fixup_f32 v127, v115, v127, 1.0
	v_fma_f32 v115, -v147, v150, 1.0
	v_fmac_f32_e32 v150, v115, v150
	v_div_scale_f32 v115, vcc, 1.0, v126, 1.0
	v_mul_f32_e32 v141, v115, v150
	v_fma_f32 v149, -v147, v141, v115
	v_fmac_f32_e32 v141, v149, v150
	v_fma_f32 v115, -v147, v141, v115
	v_mul_f32_e32 v147, 0xbfb8aa3b, v148
	v_div_scale_f32 v148, s[6:7], v121, v121, 1.0
	v_rcp_f32_e32 v149, v148
	v_div_fmas_f32 v115, v115, v150, v141
	v_div_fixup_f32 v126, v115, v126, 1.0
	v_exp_f32_e32 v147, v147
	v_fma_f32 v115, -v148, v149, 1.0
	v_fmac_f32_e32 v149, v115, v149
	v_div_scale_f32 v115, vcc, 1.0, v121, 1.0
	v_mul_f32_e32 v141, v115, v149
	v_fma_f32 v150, -v148, v141, v115
	v_fmac_f32_e32 v141, v150, v149
	v_fma_f32 v115, -v148, v141, v115
	v_div_scale_f32 v148, s[6:7], v120, v120, 1.0
	v_rcp_f32_e32 v150, v148
	v_div_fmas_f32 v115, v115, v149, v141
	v_div_fixup_f32 v121, v115, v121, 1.0
	v_pk_add_f32 v[146:147], v[146:147], 1.0 op_sel_hi:[1,0]
	v_fma_f32 v115, -v148, v150, 1.0
	v_fmac_f32_e32 v150, v115, v150
	v_div_scale_f32 v115, vcc, 1.0, v120, 1.0
	v_mul_f32_e32 v141, v115, v150
	v_fma_f32 v149, -v148, v141, v115
	v_fmac_f32_e32 v141, v149, v150
	v_fma_f32 v115, -v148, v141, v115
	v_div_scale_f32 v148, s[6:7], v147, v147, 1.0
	v_rcp_f32_e32 v149, v148
	v_div_fmas_f32 v115, v115, v150, v141
	v_div_fixup_f32 v120, v115, v120, 1.0
	v_fma_f32 v115, -v148, v149, 1.0
	v_fmac_f32_e32 v149, v115, v149
	v_div_scale_f32 v115, vcc, 1.0, v147, 1.0
	v_mul_f32_e32 v141, v115, v149
	v_fma_f32 v150, -v148, v141, v115
	v_fmac_f32_e32 v141, v150, v149
	v_fma_f32 v115, -v148, v141, v115
	v_div_scale_f32 v148, s[6:7], v146, v146, 1.0
	v_rcp_f32_e32 v150, v148
	v_div_fmas_f32 v115, v115, v149, v141
	v_div_fixup_f32 v147, v115, v147, 1.0
	v_fma_f32 v115, -v148, v150, 1.0
	v_fmac_f32_e32 v150, v115, v150
	v_div_scale_f32 v115, vcc, 1.0, v146, 1.0
	v_mul_f32_e32 v141, v115, v150
	v_fma_f32 v149, -v148, v141, v115
	v_fmac_f32_e32 v141, v149, v150
	v_fma_f32 v115, -v148, v141, v115
	v_div_fmas_f32 v115, v115, v150, v141
	v_div_fixup_f32 v146, v115, v146, 1.0
	v_lshlrev_b32_e32 v148, 16, v122
	v_and_b32_e32 v149, 0xffff0000, v122
	v_lshlrev_b32_e32 v150, 16, v124
	v_lshlrev_b32_e32 v124, 16, v125
	v_and_b32_e32 v125, 0xffff0000, v125
	v_lshlrev_b32_e32 v122, 16, v123
	v_and_b32_e32 v123, 0xffff0000, v123
	v_pk_fma_f32 v[108:109], v[108:109], v[118:119], v[148:149]
	v_pk_fma_f32 v[118:119], v[106:107], v[146:147], v[124:125]
	v_pk_fma_f32 v[106:107], v[104:105], v[120:121], v[150:151]
	v_add_lshl_u32 v120, v140, v114, 1
	v_pk_fma_f32 v[110:111], v[110:111], v[126:127], v[122:123]
	v_cvt_pk_bf16_f32 v104, v108, v109
	s_nop 0
	v_cvt_pk_bf16_f32 v105, v110, v111
	v_cvt_pk_bf16_f32 v106, v106, v107
	v_cvt_pk_bf16_f32 v107, v118, v119
	buffer_store_dwordx4 v[104:107], v120, s[20:23], 0 offen sc1
	s_nop 0
	s_waitcnt vmcnt(11)
	v_mov_b32_e32 v104, v240
	v_mov_b32_e32 v105, v241
	v_mov_b32_e32 v106, v242
	v_mov_b32_e32 v107, v243
	v_mov_b32_e32 v108, v244
	v_mov_b32_e32 v109, v245
	v_mov_b32_e32 v110, v246
	v_mov_b32_e32 v111, v247
	v_add_u32_e32 v198, 0x111200, v197
	global_load_dwordx4 v[240:243], v198, s[34:35]
	v_add_u32_e32 v198, 0x110000, v197
	global_load_dwordx4 v[244:247], v198, s[34:35]
	v_lshlrev_b32_e32 v114, 16, v105
	v_and_b32_e32 v115, 0xffff0000, v105
	v_lshlrev_b32_e32 v105, 16, v106
	v_lshlrev_b32_e32 v112, 16, v104
	v_and_b32_e32 v113, 0xffff0000, v104
	v_mul_f32_e32 v105, 0xbfb8aa3b, v105
	v_and_b32_e32 v116, 0xffff0000, v106
	v_mul_f32_e32 v104, 0xbfb8aa3b, v112
	v_exp_f32_e32 v106, v105
	v_mul_f32_e32 v105, 0xbfb8aa3b, v113
	v_exp_f32_e32 v104, v104
	v_exp_f32_e32 v105, v105
	v_mul_f32_e32 v113, 0xbfb8aa3b, v115
	v_lshlrev_b32_e32 v117, 16, v107
	v_and_b32_e32 v118, 0xffff0000, v107
	v_pk_add_f32 v[104:105], v[104:105], 1.0 op_sel_hi:[1,0]
	v_mul_f32_e32 v107, 0xbfb8aa3b, v116
	v_div_scale_f32 v115, s[6:7], v105, v105, 1.0
	v_rcp_f32_e32 v116, v115
	v_mul_f32_e32 v112, 0xbfb8aa3b, v114
	v_mul_f32_e32 v114, 0xbfb8aa3b, v117
	v_exp_f32_e32 v112, v112
	v_fma_f32 v117, -v115, v116, 1.0
	v_fmac_f32_e32 v116, v117, v116
	v_div_scale_f32 v117, vcc, 1.0, v105, 1.0
	v_mul_f32_e32 v119, v117, v116
	v_fma_f32 v121, -v115, v119, v117
	v_fmac_f32_e32 v119, v121, v116
	v_fma_f32 v115, -v115, v119, v117
	v_div_scale_f32 v117, s[6:7], v104, v104, 1.0
	v_rcp_f32_e32 v121, v117
	v_div_fmas_f32 v115, v115, v116, v119
	v_exp_f32_e32 v113, v113
	v_div_fixup_f32 v105, v115, v105, 1.0
	v_fma_f32 v115, -v117, v121, 1.0
	v_fmac_f32_e32 v121, v115, v121
	v_div_scale_f32 v115, vcc, 1.0, v104, 1.0
	v_mul_f32_e32 v116, v115, v121
	v_fma_f32 v119, -v117, v116, v115
	v_pk_add_f32 v[112:113], v[112:113], 1.0 op_sel_hi:[1,0]
	v_fmac_f32_e32 v116, v119, v121
	v_fma_f32 v115, -v117, v116, v115
; __device__ __forceinline__ float sigmoidf_(float x) { return 1.0f / (1.0f + __expf(-x)); }
; __device__ __forceinline__ u32x4 pack8(const f32x4 v0, const f32x4 v1) { u32x4 w; w.x = pk2(v0[0], v0[1]); w.y = pk2(v0[2], v0[3]); w.z = pk2(v1[0], v1[1]); w.w = pk2(v1[2], v1[3]); return w; }
; __device__ __forceinline__ void unpack8(const u32x4 w, f32x4& v0, f32x4& v1) { v0 = (f32x4){bflo(w.x), bfhi(w.x), bflo(w.y), bfhi(w.y)}; v1 = (f32x4){bflo(w.z), bfhi(w.z), bflo(w.w), bfhi(w.w)}; }
;     __device__ __forceinline__ void operator()(const f32x4 (&acc)[2][2][4][2], const Unit& u, int wr, int wc, int fr, int fq) const {
;     ...
;         for (int ai = 0; ai < 2; ++ai)
; #pragma unroll
;             for (int m = 0; m < 4; ++m) {
;                 const int row = row0 + ai * 128 + m * 16;
;                 const bf16_t* rowp = z + (size_t)row * DIN + col0;
; #pragma unroll
;                 for (int bj = 0; bj < 2; ++bj) {
;                     const u32x4 gw = *(const u32x4*)(rowp + O_GA + bj * 128);
;                     f32x4 g0, g1; unpack8(gw, g0, g1);
;                     f32x4 v0, v1;
; #pragma unroll
;                     for (int j = 0; j < 4; ++j) { v0[j] = sigmoidf_(g0[j]) * acc[ai][bj][m][0][j]; v1[j] = sigmoidf_(g1[j]) * acc[ai][bj][m][1][j]; }
;                     const u32x4 mw = *(const u32x4*)(rowp + bj * 128); f32x4 m0, m1; unpack8(mw, m0, m1); v0 += m0; v1 += m1;
;                     __builtin_amdgcn_raw_buffer_store_b128(pack8(v0, v1), rsrc, (unsigned)(((size_t)row * DIN + col0 + bj * 128) * 2), 0, 16  ); }
	v_div_scale_f32 v117, s[6:7], v113, v113, 1.0
	v_rcp_f32_e32 v119, v117
	v_div_fmas_f32 v115, v115, v121, v116
	v_div_fixup_f32 v104, v115, v104, 1.0
	v_exp_f32_e32 v107, v107
	v_fma_f32 v115, -v117, v119, 1.0
	v_fmac_f32_e32 v119, v115, v119
	v_div_scale_f32 v115, vcc, 1.0, v113, 1.0
	v_mul_f32_e32 v116, v115, v119
	v_fma_f32 v121, -v117, v116, v115
	v_fmac_f32_e32 v116, v121, v119
	v_fma_f32 v115, -v117, v116, v115
	v_div_scale_f32 v117, s[6:7], v112, v112, 1.0
	v_rcp_f32_e32 v121, v117
	v_div_fmas_f32 v115, v115, v119, v116
	v_div_fixup_f32 v113, v115, v113, 1.0
	v_pk_add_f32 v[106:107], v[106:107], 1.0 op_sel_hi:[1,0]
	v_fma_f32 v115, -v117, v121, 1.0
	v_fmac_f32_e32 v121, v115, v121
	v_div_scale_f32 v115, vcc, 1.0, v112, 1.0
	v_mul_f32_e32 v116, v115, v121
	v_fma_f32 v119, -v117, v116, v115
	v_fmac_f32_e32 v116, v119, v121
	v_fma_f32 v117, -v117, v116, v115
	v_mul_f32_e32 v115, 0xbfb8aa3b, v118
	v_div_scale_f32 v118, s[6:7], v107, v107, 1.0
	v_rcp_f32_e32 v119, v118
	v_div_fmas_f32 v116, v117, v121, v116
	v_div_fixup_f32 v112, v116, v112, 1.0
	v_exp_f32_e32 v114, v114
	v_fma_f32 v116, -v118, v119, 1.0
	v_fmac_f32_e32 v119, v116, v119
	v_div_scale_f32 v116, vcc, 1.0, v107, 1.0
	v_mul_f32_e32 v117, v116, v119
	v_fma_f32 v121, -v118, v117, v116
	v_fmac_f32_e32 v117, v121, v119
	v_fma_f32 v116, -v118, v117, v116
	v_div_scale_f32 v118, s[6:7], v106, v106, 1.0
	v_rcp_f32_e32 v121, v118
	v_div_fmas_f32 v116, v116, v119, v117
	v_exp_f32_e32 v115, v115
	v_div_fixup_f32 v107, v116, v107, 1.0
	v_fma_f32 v116, -v118, v121, 1.0
	v_fmac_f32_e32 v121, v116, v121
	v_div_scale_f32 v116, vcc, 1.0, v106, 1.0
	v_mul_f32_e32 v117, v116, v121
	v_fma_f32 v119, -v118, v117, v116
	v_pk_add_f32 v[114:115], v[114:115], 1.0 op_sel_hi:[1,0]
	v_fmac_f32_e32 v117, v119, v121
	v_fma_f32 v116, -v118, v117, v116
	v_div_scale_f32 v118, s[6:7], v115, v115, 1.0
	v_rcp_f32_e32 v119, v118
	v_div_fmas_f32 v116, v116, v121, v117
	v_div_fixup_f32 v106, v116, v106, 1.0
	v_fma_f32 v116, -v118, v119, 1.0
	v_fmac_f32_e32 v119, v116, v119
	v_div_scale_f32 v116, vcc, 1.0, v115, 1.0
	v_mul_f32_e32 v117, v116, v119
	v_fma_f32 v121, -v118, v117, v116
	v_fmac_f32_e32 v117, v121, v119
	v_fma_f32 v116, -v118, v117, v116
	v_div_scale_f32 v118, s[6:7], v114, v114, 1.0
	v_rcp_f32_e32 v121, v118
	v_div_fmas_f32 v116, v116, v119, v117
	v_div_fixup_f32 v115, v116, v115, 1.0
	v_fma_f32 v116, -v118, v121, 1.0
	v_fmac_f32_e32 v121, v116, v121
	v_div_scale_f32 v116, vcc, 1.0, v114, 1.0
	v_mul_f32_e32 v117, v116, v121
	v_fma_f32 v119, -v118, v117, v116
	v_fmac_f32_e32 v117, v119, v121
	v_fma_f32 v116, -v118, v117, v116
	v_div_fmas_f32 v116, v116, v121, v117
	v_div_fixup_f32 v114, v116, v114, 1.0
	v_lshlrev_b32_e32 v116, 16, v108
	v_and_b32_e32 v117, 0xffff0000, v108
	v_lshlrev_b32_e32 v118, 16, v110
	v_and_b32_e32 v119, 0xffff0000, v110
	v_lshlrev_b32_e32 v110, 16, v111
	v_and_b32_e32 v111, 0xffff0000, v111
	v_lshlrev_b32_e32 v108, 16, v109
	v_and_b32_e32 v109, 0xffff0000, v109
	v_pk_fma_f32 v[100:101], v[100:101], v[104:105], v[116:117]
	v_pk_fma_f32 v[104:105], v[98:99], v[114:115], v[110:111]
	v_pk_fma_f32 v[98:99], v[96:97], v[106:107], v[118:119]
	v_cvt_pk_bf16_f32 v96, v100, v101
	v_pk_fma_f32 v[102:103], v[102:103], v[112:113], v[108:109]
	s_nop 0
	v_cvt_pk_bf16_f32 v97, v102, v103
	v_cvt_pk_bf16_f32 v98, v98, v99
	v_cvt_pk_bf16_f32 v99, v104, v105
	buffer_store_dwordx4 v[96:99], v120, s[20:23], 0 offen offset:256 sc1
	s_nop 1
	v_add_u32_e32 v96, 0x4020, v158
	v_mad_i64_i32 v[98:99], s[6:7], v96, s73, 0
	v_lshl_add_u64 v[96:97], v[98:99], 1, s[34:35]
	v_lshl_add_u64 v[96:97], v[96:97], 0, v[142:143]
	v_add_co_u32_e32 v100, vcc, s74, v96
	s_nop 1
	v_addc_co_u32_e32 v101, vcc, 0, v97, vcc
	s_waitcnt vmcnt(12)
	v_mov_b32_e32 v102, v248
	v_mov_b32_e32 v103, v249
	v_mov_b32_e32 v104, v250
	v_mov_b32_e32 v105, v251
	v_mov_b32_e32 v106, v252
	v_mov_b32_e32 v107, v253
	v_mov_b32_e32 v108, v254
	v_mov_b32_e32 v109, v255
	v_add_u32_e32 v198, 0x111300, v197
	global_load_dwordx4 v[248:251], v198, s[34:35]
	v_add_u32_e32 v198, 0x110100, v197
	global_load_dwordx4 v[252:255], v198, s[34:35]
	v_lshlrev_b32_e32 v99, 16, v102
	v_lshlrev_b32_e32 v111, 16, v103
	v_and_b32_e32 v112, 0xffff0000, v103
	v_lshlrev_b32_e32 v103, 16, v104
	v_mul_f32_e32 v99, 0xbfb8aa3b, v99
	v_and_b32_e32 v110, 0xffff0000, v102
	v_exp_f32_e32 v102, v99
	v_mul_f32_e32 v99, 0xbfb8aa3b, v103
	v_and_b32_e32 v113, 0xffff0000, v104
	v_exp_f32_e32 v104, v99
	v_mul_f32_e32 v99, 0xbfb8aa3b, v110
	v_exp_f32_e32 v103, v99
	v_mul_f32_e32 v99, 0xbfb8aa3b, v113
	v_lshlrev_b32_e32 v114, 16, v105
	v_and_b32_e32 v115, 0xffff0000, v105
	v_exp_f32_e32 v105, v99
	v_mul_f32_e32 v99, 0xbfb8aa3b, v111
	v_exp_f32_e32 v110, v99
	v_mul_f32_e32 v99, 0xbfb8aa3b, v112
	v_pk_add_f32 v[102:103], v[102:103], 1.0 op_sel_hi:[1,0]
	v_exp_f32_e32 v111, v99
	v_div_scale_f32 v99, s[6:7], v103, v103, 1.0
	v_rcp_f32_e32 v113, v99
	v_mul_f32_e32 v112, 0xbfb8aa3b, v114
	v_pk_add_f32 v[110:111], v[110:111], 1.0 op_sel_hi:[1,0]
	v_pk_add_f32 v[104:105], v[104:105], 1.0 op_sel_hi:[1,0]
	v_fma_f32 v114, -v99, v113, 1.0
	v_fmac_f32_e32 v113, v114, v113
	v_div_scale_f32 v114, vcc, 1.0, v103, 1.0
	v_mul_f32_e32 v116, v114, v113
	v_fma_f32 v117, -v99, v116, v114
	v_fmac_f32_e32 v116, v117, v113
	v_fma_f32 v99, -v99, v116, v114
	v_div_scale_f32 v114, s[6:7], v102, v102, 1.0
	v_rcp_f32_e32 v117, v114
	v_div_fmas_f32 v99, v99, v113, v116
	v_div_fixup_f32 v103, v99, v103, 1.0
	v_exp_f32_e32 v112, v112
	v_fma_f32 v99, -v114, v117, 1.0
	v_fmac_f32_e32 v117, v99, v117
	v_div_scale_f32 v99, vcc, 1.0, v102, 1.0
	v_mul_f32_e32 v113, v99, v117
	v_fma_f32 v116, -v114, v113, v99
; __device__ __forceinline__ float sigmoidf_(float x) { return 1.0f / (1.0f + __expf(-x)); }
; __device__ __forceinline__ u32x4 pack8(const f32x4 v0, const f32x4 v1) { u32x4 w; w.x = pk2(v0[0], v0[1]); w.y = pk2(v0[2], v0[3]); w.z = pk2(v1[0], v1[1]); w.w = pk2(v1[2], v1[3]); return w; }
; __device__ __forceinline__ void unpack8(const u32x4 w, f32x4& v0, f32x4& v1) { v0 = (f32x4){bflo(w.x), bfhi(w.x), bflo(w.y), bfhi(w.y)}; v1 = (f32x4){bflo(w.z), bfhi(w.z), bflo(w.w), bfhi(w.w)}; }
;     __device__ __forceinline__ void operator()(const f32x4 (&acc)[2][2][4][2], const Unit& u, int wr, int wc, int fr, int fq) const {
;     ...
;         for (int ai = 0; ai < 2; ++ai)
; #pragma unroll
;             for (int m = 0; m < 4; ++m) {
;                 const int row = row0 + ai * 128 + m * 16;
;                 const bf16_t* rowp = z + (size_t)row * DIN + col0;
; #pragma unroll
;                 for (int bj = 0; bj < 2; ++bj) {
;                     const u32x4 gw = *(const u32x4*)(rowp + O_GA + bj * 128);
;                     f32x4 g0, g1; unpack8(gw, g0, g1);
;                     f32x4 v0, v1;
; #pragma unroll
;                     for (int j = 0; j < 4; ++j) { v0[j] = sigmoidf_(g0[j]) * acc[ai][bj][m][0][j]; v1[j] = sigmoidf_(g1[j]) * acc[ai][bj][m][1][j]; }
;                     const u32x4 mw = *(const u32x4*)(rowp + bj * 128); f32x4 m0, m1; unpack8(mw, m0, m1); v0 += m0; v1 += m1;
;                     __builtin_amdgcn_raw_buffer_store_b128(pack8(v0, v1), rsrc, (unsigned)(((size_t)row * DIN + col0 + bj * 128) * 2), 0, 16  ); }
	v_fmac_f32_e32 v113, v116, v117
	v_fma_f32 v99, -v114, v113, v99
	v_div_scale_f32 v114, s[6:7], v111, v111, 1.0
	v_rcp_f32_e32 v116, v114
	v_div_fmas_f32 v99, v99, v117, v113
	v_div_fixup_f32 v102, v99, v102, 1.0
	v_fma_f32 v99, -v114, v116, 1.0
	v_fmac_f32_e32 v116, v99, v116
	v_div_scale_f32 v99, vcc, 1.0, v111, 1.0
	v_mul_f32_e32 v113, v99, v116
	v_fma_f32 v117, -v114, v113, v99
	v_fmac_f32_e32 v113, v117, v116
	v_fma_f32 v99, -v114, v113, v99
	v_div_scale_f32 v114, s[6:7], v110, v110, 1.0
	v_rcp_f32_e32 v117, v114
	v_div_fmas_f32 v99, v99, v116, v113
	v_div_fixup_f32 v111, v99, v111, 1.0
	v_fma_f32 v99, -v114, v117, 1.0
	v_fmac_f32_e32 v117, v99, v117
	v_div_scale_f32 v99, vcc, 1.0, v110, 1.0
	v_mul_f32_e32 v116, v99, v117
	v_fma_f32 v113, -v114, v116, v99
	v_fmac_f32_e32 v116, v113, v117
	v_fma_f32 v99, -v114, v116, v99
	v_div_scale_f32 v114, s[6:7], v105, v105, 1.0
	v_mul_f32_e32 v113, 0xbfb8aa3b, v115
	v_rcp_f32_e32 v115, v114
	v_div_fmas_f32 v99, v99, v117, v116
	v_div_fixup_f32 v110, v99, v110, 1.0
	v_exp_f32_e32 v113, v113
	v_fma_f32 v99, -v114, v115, 1.0
	v_fmac_f32_e32 v115, v99, v115
	v_div_scale_f32 v99, vcc, 1.0, v105, 1.0
	v_mul_f32_e32 v116, v99, v115
	v_fma_f32 v117, -v114, v116, v99
	v_fmac_f32_e32 v116, v117, v115
	v_fma_f32 v99, -v114, v116, v99
	v_div_scale_f32 v114, s[6:7], v104, v104, 1.0
	v_rcp_f32_e32 v117, v114
	v_div_fmas_f32 v99, v99, v115, v116
	v_div_fixup_f32 v105, v99, v105, 1.0
	v_pk_add_f32 v[112:113], v[112:113], 1.0 op_sel_hi:[1,0]
	v_fma_f32 v99, -v114, v117, 1.0
	v_fmac_f32_e32 v117, v99, v117
	v_div_scale_f32 v99, vcc, 1.0, v104, 1.0
	v_mul_f32_e32 v115, v99, v117
	v_fma_f32 v116, -v114, v115, v99
	v_fmac_f32_e32 v115, v116, v117
	v_fma_f32 v99, -v114, v115, v99
	v_div_scale_f32 v114, s[6:7], v113, v113, 1.0
	v_rcp_f32_e32 v116, v114
	v_div_fmas_f32 v99, v99, v117, v115
	v_div_fixup_f32 v104, v99, v104, 1.0
	v_fma_f32 v99, -v114, v116, 1.0
	v_fmac_f32_e32 v116, v99, v116
	v_div_scale_f32 v99, vcc, 1.0, v113, 1.0
	v_mul_f32_e32 v115, v99, v116
	v_fma_f32 v117, -v114, v115, v99
	v_fmac_f32_e32 v115, v117, v116
	v_fma_f32 v99, -v114, v115, v99
	v_div_scale_f32 v114, s[6:7], v112, v112, 1.0
	v_rcp_f32_e32 v117, v114
	v_div_fmas_f32 v99, v99, v116, v115
	v_div_fixup_f32 v113, v99, v113, 1.0
	v_fma_f32 v99, -v114, v117, 1.0
	v_fmac_f32_e32 v117, v99, v117
	v_div_scale_f32 v99, vcc, 1.0, v112, 1.0
	v_mul_f32_e32 v115, v99, v117
	v_fma_f32 v116, -v114, v115, v99
	v_fmac_f32_e32 v115, v116, v117
	v_fma_f32 v99, -v114, v115, v99
	v_div_fmas_f32 v99, v99, v117, v115
	v_div_fixup_f32 v112, v99, v112, 1.0
	v_lshlrev_b32_e32 v114, 16, v106
	v_and_b32_e32 v115, 0xffff0000, v106
	v_lshlrev_b32_e32 v116, 16, v108
	v_and_b32_e32 v117, 0xffff0000, v108
	v_lshlrev_b32_e32 v108, 16, v109
	v_and_b32_e32 v109, 0xffff0000, v109
	v_lshlrev_b32_e32 v106, 16, v107
	v_and_b32_e32 v107, 0xffff0000, v107
	v_pk_fma_f32 v[92:93], v[92:93], v[102:103], v[114:115]
	v_pk_fma_f32 v[102:103], v[90:91], v[112:113], v[108:109]
	v_pk_fma_f32 v[90:91], v[88:89], v[104:105], v[116:117]
	v_add_lshl_u32 v104, v140, v98, 1
	v_pk_fma_f32 v[94:95], v[94:95], v[110:111], v[106:107]
	v_cvt_pk_bf16_f32 v88, v92, v93
	s_nop 0
	v_cvt_pk_bf16_f32 v89, v94, v95
	v_cvt_pk_bf16_f32 v90, v90, v91
	v_cvt_pk_bf16_f32 v91, v102, v103
	buffer_store_dwordx4 v[88:91], v104, s[20:23], 0 offen sc1
	s_nop 0
	s_waitcnt vmcnt(13)
	v_mov_b32_e32 v88, v200
	v_mov_b32_e32 v89, v201
	v_mov_b32_e32 v90, v202
	v_mov_b32_e32 v91, v203
	v_mov_b32_e32 v92, v204
	v_mov_b32_e32 v93, v205
	v_mov_b32_e32 v94, v206
	v_mov_b32_e32 v95, v207
	v_add_u32_e32 v198, 0x133200, v197
	global_load_dwordx4 v[200:203], v198, s[34:35]
	v_add_u32_e32 v198, 0x132000, v197
	global_load_dwordx4 v[204:207], v198, s[34:35]
	v_lshlrev_b32_e32 v98, 16, v89
	v_and_b32_e32 v99, 0xffff0000, v89
	v_lshlrev_b32_e32 v89, 16, v90
	v_lshlrev_b32_e32 v96, 16, v88
	v_and_b32_e32 v97, 0xffff0000, v88
	v_mul_f32_e32 v89, 0xbfb8aa3b, v89
	v_and_b32_e32 v100, 0xffff0000, v90
	v_mul_f32_e32 v88, 0xbfb8aa3b, v96
	v_exp_f32_e32 v90, v89
	v_mul_f32_e32 v89, 0xbfb8aa3b, v97
	v_exp_f32_e32 v88, v88
	v_exp_f32_e32 v89, v89
	v_mul_f32_e32 v97, 0xbfb8aa3b, v99
	v_lshlrev_b32_e32 v101, 16, v91
	v_and_b32_e32 v102, 0xffff0000, v91
	v_pk_add_f32 v[88:89], v[88:89], 1.0 op_sel_hi:[1,0]
	v_mul_f32_e32 v91, 0xbfb8aa3b, v100
	v_div_scale_f32 v99, s[6:7], v89, v89, 1.0
	v_rcp_f32_e32 v100, v99
	v_mul_f32_e32 v96, 0xbfb8aa3b, v98
	v_mul_f32_e32 v98, 0xbfb8aa3b, v101
	v_exp_f32_e32 v96, v96
	v_fma_f32 v101, -v99, v100, 1.0
	v_fmac_f32_e32 v100, v101, v100
	v_div_scale_f32 v101, vcc, 1.0, v89, 1.0
	v_mul_f32_e32 v103, v101, v100
	v_fma_f32 v105, -v99, v103, v101
	v_fmac_f32_e32 v103, v105, v100
	v_fma_f32 v99, -v99, v103, v101
	v_div_scale_f32 v101, s[6:7], v88, v88, 1.0
	v_rcp_f32_e32 v105, v101
	v_div_fmas_f32 v99, v99, v100, v103
	v_exp_f32_e32 v97, v97
	v_div_fixup_f32 v89, v99, v89, 1.0
	v_fma_f32 v99, -v101, v105, 1.0
	v_fmac_f32_e32 v105, v99, v105
	v_div_scale_f32 v99, vcc, 1.0, v88, 1.0
	v_mul_f32_e32 v100, v99, v105
	v_fma_f32 v103, -v101, v100, v99
	v_pk_add_f32 v[96:97], v[96:97], 1.0 op_sel_hi:[1,0]
	v_fmac_f32_e32 v100, v103, v105
	v_fma_f32 v99, -v101, v100, v99
	v_div_scale_f32 v101, s[6:7], v97, v97, 1.0
	v_rcp_f32_e32 v103, v101
	v_div_fmas_f32 v99, v99, v105, v100
	v_div_fixup_f32 v88, v99, v88, 1.0
	v_exp_f32_e32 v91, v91
	v_fma_f32 v99, -v101, v103, 1.0
	v_fmac_f32_e32 v103, v99, v103
	v_div_scale_f32 v99, vcc, 1.0, v97, 1.0
	v_mul_f32_e32 v100, v99, v103
	v_fma_f32 v105, -v101, v100, v99
	v_fmac_f32_e32 v100, v105, v103
	v_fma_f32 v99, -v101, v100, v99
	v_div_scale_f32 v101, s[6:7], v96, v96, 1.0
; __device__ __forceinline__ float sigmoidf_(float x) { return 1.0f / (1.0f + __expf(-x)); }
; __device__ __forceinline__ u32x4 pack8(const f32x4 v0, const f32x4 v1) { u32x4 w; w.x = pk2(v0[0], v0[1]); w.y = pk2(v0[2], v0[3]); w.z = pk2(v1[0], v1[1]); w.w = pk2(v1[2], v1[3]); return w; }
; __device__ __forceinline__ void unpack8(const u32x4 w, f32x4& v0, f32x4& v1) { v0 = (f32x4){bflo(w.x), bfhi(w.x), bflo(w.y), bfhi(w.y)}; v1 = (f32x4){bflo(w.z), bfhi(w.z), bflo(w.w), bfhi(w.w)}; }
;     __device__ __forceinline__ void operator()(const f32x4 (&acc)[2][2][4][2], const Unit& u, int wr, int wc, int fr, int fq) const {
;     ...
;         for (int ai = 0; ai < 2; ++ai)
; #pragma unroll
;             for (int m = 0; m < 4; ++m) {
;                 const int row = row0 + ai * 128 + m * 16;
;                 const bf16_t* rowp = z + (size_t)row * DIN + col0;
; #pragma unroll
;                 for (int bj = 0; bj < 2; ++bj) {
;                     const u32x4 gw = *(const u32x4*)(rowp + O_GA + bj * 128);
;                     f32x4 g0, g1; unpack8(gw, g0, g1);
;                     f32x4 v0, v1;
; #pragma unroll
;                     for (int j = 0; j < 4; ++j) { v0[j] = sigmoidf_(g0[j]) * acc[ai][bj][m][0][j]; v1[j] = sigmoidf_(g1[j]) * acc[ai][bj][m][1][j]; }
;                     const u32x4 mw = *(const u32x4*)(rowp + bj * 128); f32x4 m0, m1; unpack8(mw, m0, m1); v0 += m0; v1 += m1;
;                     __builtin_amdgcn_raw_buffer_store_b128(pack8(v0, v1), rsrc, (unsigned)(((size_t)row * DIN + col0 + bj * 128) * 2), 0, 16  ); }
	v_rcp_f32_e32 v105, v101
	v_div_fmas_f32 v99, v99, v103, v100
	v_div_fixup_f32 v97, v99, v97, 1.0
	v_pk_add_f32 v[90:91], v[90:91], 1.0 op_sel_hi:[1,0]
	v_fma_f32 v99, -v101, v105, 1.0
	v_fmac_f32_e32 v105, v99, v105
	v_div_scale_f32 v99, vcc, 1.0, v96, 1.0
	v_mul_f32_e32 v100, v99, v105
	v_fma_f32 v103, -v101, v100, v99
	v_fmac_f32_e32 v100, v103, v105
	v_fma_f32 v101, -v101, v100, v99
	v_mul_f32_e32 v99, 0xbfb8aa3b, v102
	v_div_scale_f32 v102, s[6:7], v91, v91, 1.0
	v_rcp_f32_e32 v103, v102
	v_div_fmas_f32 v100, v101, v105, v100
	v_div_fixup_f32 v96, v100, v96, 1.0
	v_exp_f32_e32 v98, v98
	v_fma_f32 v100, -v102, v103, 1.0
	v_fmac_f32_e32 v103, v100, v103
	v_div_scale_f32 v100, vcc, 1.0, v91, 1.0
	v_mul_f32_e32 v101, v100, v103
	v_fma_f32 v105, -v102, v101, v100
	v_fmac_f32_e32 v101, v105, v103
	v_fma_f32 v100, -v102, v101, v100
	v_div_scale_f32 v102, s[6:7], v90, v90, 1.0
	v_rcp_f32_e32 v105, v102
	v_div_fmas_f32 v100, v100, v103, v101
	v_exp_f32_e32 v99, v99
	v_div_fixup_f32 v91, v100, v91, 1.0
	v_fma_f32 v100, -v102, v105, 1.0
	v_fmac_f32_e32 v105, v100, v105
	v_div_scale_f32 v100, vcc, 1.0, v90, 1.0
	v_mul_f32_e32 v101, v100, v105
	v_fma_f32 v103, -v102, v101, v100
	v_pk_add_f32 v[98:99], v[98:99], 1.0 op_sel_hi:[1,0]
	v_fmac_f32_e32 v101, v103, v105
	v_fma_f32 v100, -v102, v101, v100
	v_div_scale_f32 v102, s[6:7], v99, v99, 1.0
	v_rcp_f32_e32 v103, v102
	v_div_fmas_f32 v100, v100, v105, v101
	v_div_fixup_f32 v90, v100, v90, 1.0
	v_fma_f32 v100, -v102, v103, 1.0
	v_fmac_f32_e32 v103, v100, v103
	v_div_scale_f32 v100, vcc, 1.0, v99, 1.0
	v_mul_f32_e32 v101, v100, v103
	v_fma_f32 v105, -v102, v101, v100
	v_fmac_f32_e32 v101, v105, v103
	v_fma_f32 v100, -v102, v101, v100
	v_div_scale_f32 v102, s[6:7], v98, v98, 1.0
	v_rcp_f32_e32 v105, v102
	v_div_fmas_f32 v100, v100, v103, v101
	v_div_fixup_f32 v99, v100, v99, 1.0
	v_fma_f32 v100, -v102, v105, 1.0
	v_fmac_f32_e32 v105, v100, v105
	v_div_scale_f32 v100, vcc, 1.0, v98, 1.0
	v_mul_f32_e32 v101, v100, v105
	v_fma_f32 v103, -v102, v101, v100
	v_fmac_f32_e32 v101, v103, v105
	v_fma_f32 v100, -v102, v101, v100
	v_div_fmas_f32 v100, v100, v105, v101
	v_div_fixup_f32 v98, v100, v98, 1.0
	v_lshlrev_b32_e32 v100, 16, v92
	v_and_b32_e32 v101, 0xffff0000, v92
	v_lshlrev_b32_e32 v102, 16, v94
	v_and_b32_e32 v103, 0xffff0000, v94
	v_lshlrev_b32_e32 v94, 16, v95
	v_and_b32_e32 v95, 0xffff0000, v95
	v_lshlrev_b32_e32 v92, 16, v93
	v_and_b32_e32 v93, 0xffff0000, v93
	v_pk_fma_f32 v[84:85], v[84:85], v[88:89], v[100:101]
	v_pk_fma_f32 v[88:89], v[82:83], v[98:99], v[94:95]
	v_pk_fma_f32 v[82:83], v[80:81], v[90:91], v[102:103]
	v_cvt_pk_bf16_f32 v80, v84, v85
	v_pk_fma_f32 v[86:87], v[86:87], v[96:97], v[92:93]
	s_nop 0
	v_cvt_pk_bf16_f32 v81, v86, v87
	v_cvt_pk_bf16_f32 v82, v82, v83
	v_cvt_pk_bf16_f32 v83, v88, v89
	buffer_store_dwordx4 v[80:83], v104, s[20:23], 0 offen offset:256 sc1
	s_nop 1
	v_add_u32_e32 v80, 0x4030, v158
	v_mad_i64_i32 v[82:83], s[6:7], v80, s73, 0
	v_lshl_add_u64 v[80:81], v[82:83], 1, s[34:35]
	v_lshl_add_u64 v[80:81], v[80:81], 0, v[142:143]
	v_add_co_u32_e32 v84, vcc, s74, v80
	s_nop 1
	v_addc_co_u32_e32 v85, vcc, 0, v81, vcc
	s_waitcnt vmcnt(13)
	v_mov_b32_e32 v86, v208
	v_mov_b32_e32 v87, v209
	v_mov_b32_e32 v88, v210
	v_mov_b32_e32 v89, v211
	v_mov_b32_e32 v90, v212
	v_mov_b32_e32 v91, v213
	v_mov_b32_e32 v92, v214
	v_mov_b32_e32 v93, v215
	v_add_u32_e32 v198, 0x133300, v197
	global_load_dwordx4 v[208:211], v198, s[34:35]
	v_add_u32_e32 v198, 0x132100, v197
	global_load_dwordx4 v[212:215], v198, s[34:35]
	v_lshlrev_b32_e32 v83, 16, v86
	v_lshlrev_b32_e32 v95, 16, v87
	v_and_b32_e32 v96, 0xffff0000, v87
	v_lshlrev_b32_e32 v87, 16, v88
	v_mul_f32_e32 v83, 0xbfb8aa3b, v83
	v_and_b32_e32 v94, 0xffff0000, v86
	v_exp_f32_e32 v86, v83
	v_mul_f32_e32 v83, 0xbfb8aa3b, v87
	v_and_b32_e32 v97, 0xffff0000, v88
	v_exp_f32_e32 v88, v83
	v_mul_f32_e32 v83, 0xbfb8aa3b, v94
	v_exp_f32_e32 v87, v83
	v_mul_f32_e32 v83, 0xbfb8aa3b, v97
	v_lshlrev_b32_e32 v98, 16, v89
	v_and_b32_e32 v99, 0xffff0000, v89
	v_exp_f32_e32 v89, v83
	v_mul_f32_e32 v83, 0xbfb8aa3b, v95
	v_exp_f32_e32 v94, v83
	v_mul_f32_e32 v83, 0xbfb8aa3b, v96
	v_pk_add_f32 v[86:87], v[86:87], 1.0 op_sel_hi:[1,0]
	v_exp_f32_e32 v95, v83
	v_div_scale_f32 v83, s[6:7], v87, v87, 1.0
	v_rcp_f32_e32 v97, v83
	v_mul_f32_e32 v96, 0xbfb8aa3b, v98
	v_pk_add_f32 v[94:95], v[94:95], 1.0 op_sel_hi:[1,0]
	v_pk_add_f32 v[88:89], v[88:89], 1.0 op_sel_hi:[1,0]
	v_fma_f32 v98, -v83, v97, 1.0
	v_fmac_f32_e32 v97, v98, v97
	v_div_scale_f32 v98, vcc, 1.0, v87, 1.0
	v_mul_f32_e32 v100, v98, v97
	v_fma_f32 v101, -v83, v100, v98
	v_fmac_f32_e32 v100, v101, v97
	v_fma_f32 v83, -v83, v100, v98
	v_div_scale_f32 v98, s[6:7], v86, v86, 1.0
	v_rcp_f32_e32 v101, v98
	v_div_fmas_f32 v83, v83, v97, v100
	v_div_fixup_f32 v87, v83, v87, 1.0
	v_exp_f32_e32 v96, v96
	v_fma_f32 v83, -v98, v101, 1.0
	v_fmac_f32_e32 v101, v83, v101
	v_div_scale_f32 v83, vcc, 1.0, v86, 1.0
	v_mul_f32_e32 v97, v83, v101
	v_fma_f32 v100, -v98, v97, v83
	v_fmac_f32_e32 v97, v100, v101
	v_fma_f32 v83, -v98, v97, v83
	v_div_scale_f32 v98, s[6:7], v95, v95, 1.0
	v_rcp_f32_e32 v100, v98
	v_div_fmas_f32 v83, v83, v101, v97
	v_div_fixup_f32 v86, v83, v86, 1.0
	v_fma_f32 v83, -v98, v100, 1.0
	v_fmac_f32_e32 v100, v83, v100
	v_div_scale_f32 v83, vcc, 1.0, v95, 1.0
	v_mul_f32_e32 v97, v83, v100
	v_fma_f32 v101, -v98, v97, v83
	v_fmac_f32_e32 v97, v101, v100
	v_fma_f32 v83, -v98, v97, v83
	v_div_scale_f32 v98, s[6:7], v94, v94, 1.0
	v_rcp_f32_e32 v101, v98
	v_div_fmas_f32 v83, v83, v100, v97
	v_div_fixup_f32 v95, v83, v95, 1.0
	v_fma_f32 v83, -v98, v101, 1.0
	v_fmac_f32_e32 v101, v83, v101
; __device__ __forceinline__ float sigmoidf_(float x) { return 1.0f / (1.0f + __expf(-x)); }
; __device__ __forceinline__ u32x4 pack8(const f32x4 v0, const f32x4 v1) { u32x4 w; w.x = pk2(v0[0], v0[1]); w.y = pk2(v0[2], v0[3]); w.z = pk2(v1[0], v1[1]); w.w = pk2(v1[2], v1[3]); return w; }
; __device__ __forceinline__ void unpack8(const u32x4 w, f32x4& v0, f32x4& v1) { v0 = (f32x4){bflo(w.x), bfhi(w.x), bflo(w.y), bfhi(w.y)}; v1 = (f32x4){bflo(w.z), bfhi(w.z), bflo(w.w), bfhi(w.w)}; }
;     __device__ __forceinline__ void operator()(const f32x4 (&acc)[2][2][4][2], const Unit& u, int wr, int wc, int fr, int fq) const {
;     ...
;         for (int ai = 0; ai < 2; ++ai)
; #pragma unroll
;             for (int m = 0; m < 4; ++m) {
;                 const int row = row0 + ai * 128 + m * 16;
;                 const bf16_t* rowp = z + (size_t)row * DIN + col0;
; #pragma unroll
;                 for (int bj = 0; bj < 2; ++bj) {
;                     const u32x4 gw = *(const u32x4*)(rowp + O_GA + bj * 128);
;                     f32x4 g0, g1; unpack8(gw, g0, g1);
;                     f32x4 v0, v1;
; #pragma unroll
;                     for (int j = 0; j < 4; ++j) { v0[j] = sigmoidf_(g0[j]) * acc[ai][bj][m][0][j]; v1[j] = sigmoidf_(g1[j]) * acc[ai][bj][m][1][j]; }
;                     const u32x4 mw = *(const u32x4*)(rowp + bj * 128); f32x4 m0, m1; unpack8(mw, m0, m1); v0 += m0; v1 += m1;
;                     __builtin_amdgcn_raw_buffer_store_b128(pack8(v0, v1), rsrc, (unsigned)(((size_t)row * DIN + col0 + bj * 128) * 2), 0, 16  ); }
	v_div_scale_f32 v83, vcc, 1.0, v94, 1.0
	v_mul_f32_e32 v100, v83, v101
	v_fma_f32 v97, -v98, v100, v83
	v_fmac_f32_e32 v100, v97, v101
	v_fma_f32 v83, -v98, v100, v83
	v_div_scale_f32 v98, s[6:7], v89, v89, 1.0
	v_mul_f32_e32 v97, 0xbfb8aa3b, v99
	v_rcp_f32_e32 v99, v98
	v_div_fmas_f32 v83, v83, v101, v100
	v_div_fixup_f32 v94, v83, v94, 1.0
	v_exp_f32_e32 v97, v97
	v_fma_f32 v83, -v98, v99, 1.0
	v_fmac_f32_e32 v99, v83, v99
	v_div_scale_f32 v83, vcc, 1.0, v89, 1.0
	v_mul_f32_e32 v100, v83, v99
	v_fma_f32 v101, -v98, v100, v83
	v_fmac_f32_e32 v100, v101, v99
	v_fma_f32 v83, -v98, v100, v83
	v_div_scale_f32 v98, s[6:7], v88, v88, 1.0
	v_rcp_f32_e32 v101, v98
	v_div_fmas_f32 v83, v83, v99, v100
	v_div_fixup_f32 v89, v83, v89, 1.0
	v_pk_add_f32 v[96:97], v[96:97], 1.0 op_sel_hi:[1,0]
	v_fma_f32 v83, -v98, v101, 1.0
	v_fmac_f32_e32 v101, v83, v101
	v_div_scale_f32 v83, vcc, 1.0, v88, 1.0
	v_mul_f32_e32 v99, v83, v101
	v_fma_f32 v100, -v98, v99, v83
	v_fmac_f32_e32 v99, v100, v101
	v_fma_f32 v83, -v98, v99, v83
	v_div_scale_f32 v98, s[6:7], v97, v97, 1.0
	v_rcp_f32_e32 v100, v98
	v_div_fmas_f32 v83, v83, v101, v99
	v_div_fixup_f32 v88, v83, v88, 1.0
	v_fma_f32 v83, -v98, v100, 1.0
	v_fmac_f32_e32 v100, v83, v100
	v_div_scale_f32 v83, vcc, 1.0, v97, 1.0
	v_mul_f32_e32 v99, v83, v100
	v_fma_f32 v101, -v98, v99, v83
	v_fmac_f32_e32 v99, v101, v100
	v_fma_f32 v83, -v98, v99, v83
	v_div_scale_f32 v98, s[6:7], v96, v96, 1.0
	v_rcp_f32_e32 v101, v98
	v_div_fmas_f32 v83, v83, v100, v99
	v_div_fixup_f32 v97, v83, v97, 1.0
	v_fma_f32 v83, -v98, v101, 1.0
	v_fmac_f32_e32 v101, v83, v101
	v_div_scale_f32 v83, vcc, 1.0, v96, 1.0
	v_mul_f32_e32 v99, v83, v101
	v_fma_f32 v100, -v98, v99, v83
	v_fmac_f32_e32 v99, v100, v101
	v_fma_f32 v83, -v98, v99, v83
	v_div_fmas_f32 v83, v83, v101, v99
	v_div_fixup_f32 v96, v83, v96, 1.0
	v_lshlrev_b32_e32 v98, 16, v90
	v_and_b32_e32 v99, 0xffff0000, v90
	v_lshlrev_b32_e32 v100, 16, v92
	v_and_b32_e32 v101, 0xffff0000, v92
	v_lshlrev_b32_e32 v92, 16, v93
	v_and_b32_e32 v93, 0xffff0000, v93
	v_lshlrev_b32_e32 v90, 16, v91
	v_and_b32_e32 v91, 0xffff0000, v91
	v_pk_fma_f32 v[76:77], v[76:77], v[86:87], v[98:99]
	v_pk_fma_f32 v[86:87], v[74:75], v[96:97], v[92:93]
	v_pk_fma_f32 v[74:75], v[72:73], v[88:89], v[100:101]
	v_add_lshl_u32 v88, v140, v82, 1
	v_pk_fma_f32 v[78:79], v[78:79], v[94:95], v[90:91]
	v_cvt_pk_bf16_f32 v72, v76, v77
	s_nop 0
	v_cvt_pk_bf16_f32 v73, v78, v79
	v_cvt_pk_bf16_f32 v74, v74, v75
	v_cvt_pk_bf16_f32 v75, v86, v87
	buffer_store_dwordx4 v[72:75], v88, s[20:23], 0 offen sc1
	s_nop 0
	s_waitcnt vmcnt(13)
	v_mov_b32_e32 v72, v232
	v_mov_b32_e32 v73, v233
	v_mov_b32_e32 v74, v234
	v_mov_b32_e32 v75, v235
	v_mov_b32_e32 v76, v236
	v_mov_b32_e32 v77, v237
	v_mov_b32_e32 v78, v238
	v_mov_b32_e32 v79, v239
	v_add_u32_e32 v198, 0x155200, v197
	global_load_dwordx4 v[232:235], v198, s[34:35]
	v_add_u32_e32 v198, 0x154000, v197
	global_load_dwordx4 v[236:239], v198, s[34:35]
	v_lshlrev_b32_e32 v82, 16, v73
	v_and_b32_e32 v83, 0xffff0000, v73
	v_lshlrev_b32_e32 v73, 16, v74
	v_lshlrev_b32_e32 v80, 16, v72
	v_and_b32_e32 v81, 0xffff0000, v72
	v_mul_f32_e32 v73, 0xbfb8aa3b, v73
	v_and_b32_e32 v84, 0xffff0000, v74
	v_mul_f32_e32 v72, 0xbfb8aa3b, v80
	v_exp_f32_e32 v74, v73
	v_mul_f32_e32 v73, 0xbfb8aa3b, v81
	v_exp_f32_e32 v72, v72
	v_exp_f32_e32 v73, v73
	v_mul_f32_e32 v81, 0xbfb8aa3b, v83
	v_lshlrev_b32_e32 v85, 16, v75
	v_and_b32_e32 v86, 0xffff0000, v75
	v_pk_add_f32 v[72:73], v[72:73], 1.0 op_sel_hi:[1,0]
	v_mul_f32_e32 v75, 0xbfb8aa3b, v84
	v_div_scale_f32 v83, s[6:7], v73, v73, 1.0
	v_rcp_f32_e32 v84, v83
	v_mul_f32_e32 v80, 0xbfb8aa3b, v82
	v_mul_f32_e32 v82, 0xbfb8aa3b, v85
	v_exp_f32_e32 v80, v80
	v_fma_f32 v85, -v83, v84, 1.0
	v_fmac_f32_e32 v84, v85, v84
	v_div_scale_f32 v85, vcc, 1.0, v73, 1.0
	v_mul_f32_e32 v87, v85, v84
	v_fma_f32 v89, -v83, v87, v85
	v_fmac_f32_e32 v87, v89, v84
	v_fma_f32 v83, -v83, v87, v85
	v_div_scale_f32 v85, s[6:7], v72, v72, 1.0
	v_rcp_f32_e32 v89, v85
	v_div_fmas_f32 v83, v83, v84, v87
	v_exp_f32_e32 v81, v81
	v_div_fixup_f32 v73, v83, v73, 1.0
	v_fma_f32 v83, -v85, v89, 1.0
	v_fmac_f32_e32 v89, v83, v89
	v_div_scale_f32 v83, vcc, 1.0, v72, 1.0
	v_mul_f32_e32 v84, v83, v89
	v_fma_f32 v87, -v85, v84, v83
	v_pk_add_f32 v[80:81], v[80:81], 1.0 op_sel_hi:[1,0]
	v_fmac_f32_e32 v84, v87, v89
	v_fma_f32 v83, -v85, v84, v83
	v_div_scale_f32 v85, s[6:7], v81, v81, 1.0
	v_rcp_f32_e32 v87, v85
	v_div_fmas_f32 v83, v83, v89, v84
	v_div_fixup_f32 v72, v83, v72, 1.0
	v_exp_f32_e32 v75, v75
	v_fma_f32 v83, -v85, v87, 1.0
	v_fmac_f32_e32 v87, v83, v87
	v_div_scale_f32 v83, vcc, 1.0, v81, 1.0
	v_mul_f32_e32 v84, v83, v87
	v_fma_f32 v89, -v85, v84, v83
	v_fmac_f32_e32 v84, v89, v87
	v_fma_f32 v83, -v85, v84, v83
	v_div_scale_f32 v85, s[6:7], v80, v80, 1.0
	v_rcp_f32_e32 v89, v85
	v_div_fmas_f32 v83, v83, v87, v84
	v_div_fixup_f32 v81, v83, v81, 1.0
	v_pk_add_f32 v[74:75], v[74:75], 1.0 op_sel_hi:[1,0]
	v_fma_f32 v83, -v85, v89, 1.0
	v_fmac_f32_e32 v89, v83, v89
	v_div_scale_f32 v83, vcc, 1.0, v80, 1.0
	v_mul_f32_e32 v84, v83, v89
	v_fma_f32 v87, -v85, v84, v83
	v_fmac_f32_e32 v84, v87, v89
	v_fma_f32 v85, -v85, v84, v83
	v_mul_f32_e32 v83, 0xbfb8aa3b, v86
	v_div_scale_f32 v86, s[6:7], v75, v75, 1.0
	v_rcp_f32_e32 v87, v86
	v_div_fmas_f32 v84, v85, v89, v84
	v_div_fixup_f32 v80, v84, v80, 1.0
	v_exp_f32_e32 v82, v82
	v_fma_f32 v84, -v86, v87, 1.0
	v_fmac_f32_e32 v87, v84, v87
	v_div_scale_f32 v84, vcc, 1.0, v75, 1.0
	v_mul_f32_e32 v85, v84, v87
	v_fma_f32 v89, -v86, v85, v84
	v_fmac_f32_e32 v85, v89, v87
	v_fma_f32 v84, -v86, v85, v84
	v_div_scale_f32 v86, s[6:7], v74, v74, 1.0
; __device__ __forceinline__ u32x4 pack8(const f32x4 v0, const f32x4 v1) { u32x4 w; w.x = pk2(v0[0], v0[1]); w.y = pk2(v0[2], v0[3]); w.z = pk2(v1[0], v1[1]); w.w = pk2(v1[2], v1[3]); return w; }
; __device__ __forceinline__ void unpack8(const u32x4 w, f32x4& v0, f32x4& v1) { v0 = (f32x4){bflo(w.x), bfhi(w.x), bflo(w.y), bfhi(w.y)}; v1 = (f32x4){bflo(w.z), bfhi(w.z), bflo(w.w), bfhi(w.w)}; }
; __device__ __forceinline__ float sigmoidf_(float x) { return 1.0f / (1.0f + __expf(-x)); }
;     __device__ __forceinline__ void operator()(const f32x4 (&acc)[2][2][4][2], const Unit& u, int wr, int wc, int fr, int fq) const {
;     ...
;                 const int row = row0 + ai * 128 + m * 16;
;                 const bf16_t* rowp = z + (size_t)row * DIN + col0;
; #pragma unroll
;                 for (int bj = 0; bj < 2; ++bj) {
;                     const u32x4 gw = *(const u32x4*)(rowp + O_GA + bj * 128);
;                     f32x4 g0, g1; unpack8(gw, g0, g1);
;                     f32x4 v0, v1;
; #pragma unroll
;                     for (int j = 0; j < 4; ++j) { v0[j] = sigmoidf_(g0[j]) * acc[ai][bj][m][0][j]; v1[j] = sigmoidf_(g1[j]) * acc[ai][bj][m][1][j]; }
;                     const u32x4 mw = *(const u32x4*)(rowp + bj * 128); f32x4 m0, m1; unpack8(mw, m0, m1); v0 += m0; v1 += m1;
;                     __builtin_amdgcn_raw_buffer_store_b128(pack8(v0, v1), rsrc, (unsigned)(((size_t)row * DIN + col0 + bj * 128) * 2), 0, 16  ); }
	v_rcp_f32_e32 v89, v86
	v_div_fmas_f32 v84, v84, v87, v85
	v_exp_f32_e32 v83, v83
	v_div_fixup_f32 v75, v84, v75, 1.0
	v_fma_f32 v84, -v86, v89, 1.0
	v_fmac_f32_e32 v89, v84, v89
	v_div_scale_f32 v84, vcc, 1.0, v74, 1.0
	v_mul_f32_e32 v85, v84, v89
	v_fma_f32 v87, -v86, v85, v84
	v_pk_add_f32 v[82:83], v[82:83], 1.0 op_sel_hi:[1,0]
	v_fmac_f32_e32 v85, v87, v89
	v_fma_f32 v84, -v86, v85, v84
	v_div_scale_f32 v86, s[6:7], v83, v83, 1.0
	v_rcp_f32_e32 v87, v86
	v_div_fmas_f32 v84, v84, v89, v85
	v_div_fixup_f32 v74, v84, v74, 1.0
	v_fma_f32 v84, -v86, v87, 1.0
	v_fmac_f32_e32 v87, v84, v87
	v_div_scale_f32 v84, vcc, 1.0, v83, 1.0
	v_mul_f32_e32 v85, v84, v87
	v_fma_f32 v89, -v86, v85, v84
	v_fmac_f32_e32 v85, v89, v87
	v_fma_f32 v84, -v86, v85, v84
	v_div_scale_f32 v86, s[6:7], v82, v82, 1.0
	v_rcp_f32_e32 v89, v86
	v_div_fmas_f32 v84, v84, v87, v85
	v_div_fixup_f32 v83, v84, v83, 1.0
	v_fma_f32 v84, -v86, v89, 1.0
	v_fmac_f32_e32 v89, v84, v89
	v_div_scale_f32 v84, vcc, 1.0, v82, 1.0
	v_mul_f32_e32 v85, v84, v89
	v_fma_f32 v87, -v86, v85, v84
	v_fmac_f32_e32 v85, v87, v89
	v_fma_f32 v84, -v86, v85, v84
	v_div_fmas_f32 v84, v84, v89, v85
	v_div_fixup_f32 v82, v84, v82, 1.0
	v_lshlrev_b32_e32 v84, 16, v76
	v_and_b32_e32 v85, 0xffff0000, v76
	v_lshlrev_b32_e32 v86, 16, v78
	v_and_b32_e32 v87, 0xffff0000, v78
	v_lshlrev_b32_e32 v78, 16, v79
	v_and_b32_e32 v79, 0xffff0000, v79
	v_lshlrev_b32_e32 v76, 16, v77
	v_and_b32_e32 v77, 0xffff0000, v77
	v_pk_fma_f32 v[68:69], v[68:69], v[72:73], v[84:85]
	v_pk_fma_f32 v[72:73], v[66:67], v[82:83], v[78:79]
	v_pk_fma_f32 v[66:67], v[64:65], v[74:75], v[86:87]
	v_cvt_pk_bf16_f32 v64, v68, v69
	v_pk_fma_f32 v[70:71], v[70:71], v[80:81], v[76:77]
	s_nop 0
	v_cvt_pk_bf16_f32 v65, v70, v71
	v_cvt_pk_bf16_f32 v66, v66, v67
	v_cvt_pk_bf16_f32 v67, v72, v73
	buffer_store_dwordx4 v[64:67], v88, s[20:23], 0 offen offset:256 sc1
	s_nop 1
	v_add_u32_e32 v64, 0x4080, v158
	v_mad_i64_i32 v[66:67], s[6:7], v64, s73, 0
	v_lshl_add_u64 v[64:65], v[66:67], 1, s[34:35]
	v_lshl_add_u64 v[64:65], v[64:65], 0, v[142:143]
	v_add_co_u32_e32 v68, vcc, s74, v64
	s_nop 1
	v_addc_co_u32_e32 v69, vcc, 0, v65, vcc
	s_waitcnt vmcnt(13)
	v_mov_b32_e32 v70, v240
	v_mov_b32_e32 v71, v241
	v_mov_b32_e32 v72, v242
	v_mov_b32_e32 v73, v243
	v_mov_b32_e32 v74, v244
	v_mov_b32_e32 v75, v245
	v_mov_b32_e32 v76, v246
	v_mov_b32_e32 v77, v247
	v_add_u32_e32 v198, 0x155300, v197
	global_load_dwordx4 v[240:243], v198, s[34:35]
	v_add_u32_e32 v198, 0x154100, v197
	global_load_dwordx4 v[244:247], v198, s[34:35]
	v_lshlrev_b32_e32 v67, 16, v70
	v_lshlrev_b32_e32 v79, 16, v71
	v_and_b32_e32 v80, 0xffff0000, v71
	v_lshlrev_b32_e32 v71, 16, v72
	v_mul_f32_e32 v67, 0xbfb8aa3b, v67
	v_and_b32_e32 v78, 0xffff0000, v70
	v_exp_f32_e32 v70, v67
	v_mul_f32_e32 v67, 0xbfb8aa3b, v71
	v_and_b32_e32 v81, 0xffff0000, v72
	v_exp_f32_e32 v72, v67
	v_mul_f32_e32 v67, 0xbfb8aa3b, v78
	v_exp_f32_e32 v71, v67
	v_mul_f32_e32 v67, 0xbfb8aa3b, v81
	v_lshlrev_b32_e32 v82, 16, v73
	v_and_b32_e32 v83, 0xffff0000, v73
	v_exp_f32_e32 v73, v67
	v_mul_f32_e32 v67, 0xbfb8aa3b, v79
	v_exp_f32_e32 v78, v67
	v_mul_f32_e32 v67, 0xbfb8aa3b, v80
	v_pk_add_f32 v[70:71], v[70:71], 1.0 op_sel_hi:[1,0]
	v_exp_f32_e32 v79, v67
	v_div_scale_f32 v67, s[6:7], v71, v71, 1.0
	v_rcp_f32_e32 v81, v67
	v_mul_f32_e32 v80, 0xbfb8aa3b, v82
	v_pk_add_f32 v[78:79], v[78:79], 1.0 op_sel_hi:[1,0]
	v_pk_add_f32 v[72:73], v[72:73], 1.0 op_sel_hi:[1,0]
	v_fma_f32 v82, -v67, v81, 1.0
	v_fmac_f32_e32 v81, v82, v81
	v_div_scale_f32 v82, vcc, 1.0, v71, 1.0
	v_mul_f32_e32 v84, v82, v81
	v_fma_f32 v85, -v67, v84, v82
	v_fmac_f32_e32 v84, v85, v81
	v_fma_f32 v67, -v67, v84, v82
	v_div_scale_f32 v82, s[6:7], v70, v70, 1.0
	v_rcp_f32_e32 v85, v82
	v_div_fmas_f32 v67, v67, v81, v84
	v_div_fixup_f32 v71, v67, v71, 1.0
	v_exp_f32_e32 v80, v80
	v_fma_f32 v67, -v82, v85, 1.0
	v_fmac_f32_e32 v85, v67, v85
	v_div_scale_f32 v67, vcc, 1.0, v70, 1.0
	v_mul_f32_e32 v81, v67, v85
	v_fma_f32 v84, -v82, v81, v67
	v_fmac_f32_e32 v81, v84, v85
	v_fma_f32 v67, -v82, v81, v67
	v_div_scale_f32 v82, s[6:7], v79, v79, 1.0
	v_rcp_f32_e32 v84, v82
	v_div_fmas_f32 v67, v67, v85, v81
	v_div_fixup_f32 v70, v67, v70, 1.0
	v_fma_f32 v67, -v82, v84, 1.0
	v_fmac_f32_e32 v84, v67, v84
	v_div_scale_f32 v67, vcc, 1.0, v79, 1.0
	v_mul_f32_e32 v81, v67, v84
	v_fma_f32 v85, -v82, v81, v67
	v_fmac_f32_e32 v81, v85, v84
	v_fma_f32 v67, -v82, v81, v67
	v_div_scale_f32 v82, s[6:7], v78, v78, 1.0
	v_rcp_f32_e32 v85, v82
	v_div_fmas_f32 v67, v67, v84, v81
	v_div_fixup_f32 v79, v67, v79, 1.0
	v_fma_f32 v67, -v82, v85, 1.0
	v_fmac_f32_e32 v85, v67, v85
	v_div_scale_f32 v67, vcc, 1.0, v78, 1.0
	v_mul_f32_e32 v84, v67, v85
	v_fma_f32 v81, -v82, v84, v67
	v_fmac_f32_e32 v84, v81, v85
	v_fma_f32 v67, -v82, v84, v67
	v_div_scale_f32 v82, s[6:7], v73, v73, 1.0
	v_mul_f32_e32 v81, 0xbfb8aa3b, v83
	v_rcp_f32_e32 v83, v82
	v_div_fmas_f32 v67, v67, v85, v84
	v_div_fixup_f32 v78, v67, v78, 1.0
	v_exp_f32_e32 v81, v81
	v_fma_f32 v67, -v82, v83, 1.0
	v_fmac_f32_e32 v83, v67, v83
	v_div_scale_f32 v67, vcc, 1.0, v73, 1.0
	v_mul_f32_e32 v84, v67, v83
	v_fma_f32 v85, -v82, v84, v67
	v_fmac_f32_e32 v84, v85, v83
	v_fma_f32 v67, -v82, v84, v67
	v_div_scale_f32 v82, s[6:7], v72, v72, 1.0
	v_rcp_f32_e32 v85, v82
	v_div_fmas_f32 v67, v67, v83, v84
	v_div_fixup_f32 v73, v67, v73, 1.0
	v_pk_add_f32 v[80:81], v[80:81], 1.0 op_sel_hi:[1,0]
	v_fma_f32 v67, -v82, v85, 1.0
	v_fmac_f32_e32 v85, v67, v85
	v_div_scale_f32 v67, vcc, 1.0, v72, 1.0
	v_mul_f32_e32 v83, v67, v85
	v_fma_f32 v84, -v82, v83, v67
	v_fmac_f32_e32 v83, v84, v85
	v_fma_f32 v67, -v82, v83, v67
	v_div_scale_f32 v82, s[6:7], v81, v81, 1.0
; __device__ __forceinline__ u32x4 pack8(const f32x4 v0, const f32x4 v1) { u32x4 w; w.x = pk2(v0[0], v0[1]); w.y = pk2(v0[2], v0[3]); w.z = pk2(v1[0], v1[1]); w.w = pk2(v1[2], v1[3]); return w; }
; __device__ __forceinline__ void unpack8(const u32x4 w, f32x4& v0, f32x4& v1) { v0 = (f32x4){bflo(w.x), bfhi(w.x), bflo(w.y), bfhi(w.y)}; v1 = (f32x4){bflo(w.z), bfhi(w.z), bflo(w.w), bfhi(w.w)}; }
; __device__ __forceinline__ float sigmoidf_(float x) { return 1.0f / (1.0f + __expf(-x)); }
;     __device__ __forceinline__ void operator()(const f32x4 (&acc)[2][2][4][2], const Unit& u, int wr, int wc, int fr, int fq) const {
;     ...
;                 const int row = row0 + ai * 128 + m * 16;
;                 const bf16_t* rowp = z + (size_t)row * DIN + col0;
; #pragma unroll
;                 for (int bj = 0; bj < 2; ++bj) {
;                     const u32x4 gw = *(const u32x4*)(rowp + O_GA + bj * 128);
;                     f32x4 g0, g1; unpack8(gw, g0, g1);
;                     f32x4 v0, v1;
; #pragma unroll
;                     for (int j = 0; j < 4; ++j) { v0[j] = sigmoidf_(g0[j]) * acc[ai][bj][m][0][j]; v1[j] = sigmoidf_(g1[j]) * acc[ai][bj][m][1][j]; }
;                     const u32x4 mw = *(const u32x4*)(rowp + bj * 128); f32x4 m0, m1; unpack8(mw, m0, m1); v0 += m0; v1 += m1;
;                     __builtin_amdgcn_raw_buffer_store_b128(pack8(v0, v1), rsrc, (unsigned)(((size_t)row * DIN + col0 + bj * 128) * 2), 0, 16  ); }
	v_rcp_f32_e32 v84, v82
	v_div_fmas_f32 v67, v67, v85, v83
	v_div_fixup_f32 v72, v67, v72, 1.0
	v_fma_f32 v67, -v82, v84, 1.0
	v_fmac_f32_e32 v84, v67, v84
	v_div_scale_f32 v67, vcc, 1.0, v81, 1.0
	v_mul_f32_e32 v83, v67, v84
	v_fma_f32 v85, -v82, v83, v67
	v_fmac_f32_e32 v83, v85, v84
	v_fma_f32 v67, -v82, v83, v67
	v_div_scale_f32 v82, s[6:7], v80, v80, 1.0
	v_rcp_f32_e32 v85, v82
	v_div_fmas_f32 v67, v67, v84, v83
	v_div_fixup_f32 v81, v67, v81, 1.0
	v_fma_f32 v67, -v82, v85, 1.0
	v_fmac_f32_e32 v85, v67, v85
	v_div_scale_f32 v67, vcc, 1.0, v80, 1.0
	v_mul_f32_e32 v83, v67, v85
	v_fma_f32 v84, -v82, v83, v67
	v_fmac_f32_e32 v83, v84, v85
	v_fma_f32 v67, -v82, v83, v67
	v_div_fmas_f32 v67, v67, v85, v83
	v_div_fixup_f32 v80, v67, v80, 1.0
	v_lshlrev_b32_e32 v82, 16, v74
	v_and_b32_e32 v83, 0xffff0000, v74
	v_lshlrev_b32_e32 v84, 16, v76
	v_and_b32_e32 v85, 0xffff0000, v76
	v_lshlrev_b32_e32 v76, 16, v77
	v_and_b32_e32 v77, 0xffff0000, v77
	v_lshlrev_b32_e32 v74, 16, v75
	v_and_b32_e32 v75, 0xffff0000, v75
	v_pk_fma_f32 v[60:61], v[60:61], v[70:71], v[82:83]
	v_pk_fma_f32 v[70:71], v[58:59], v[80:81], v[76:77]
	v_pk_fma_f32 v[58:59], v[56:57], v[72:73], v[84:85]
	v_add_lshl_u32 v72, v140, v66, 1
	v_pk_fma_f32 v[62:63], v[62:63], v[78:79], v[74:75]
	v_cvt_pk_bf16_f32 v56, v60, v61
	s_nop 0
	v_cvt_pk_bf16_f32 v57, v62, v63
	v_cvt_pk_bf16_f32 v58, v58, v59
	v_cvt_pk_bf16_f32 v59, v70, v71
	buffer_store_dwordx4 v[56:59], v72, s[20:23], 0 offen sc1
	s_nop 0
	s_waitcnt vmcnt(13)
	v_mov_b32_e32 v56, v248
	v_mov_b32_e32 v57, v249
	v_mov_b32_e32 v58, v250
	v_mov_b32_e32 v59, v251
	v_mov_b32_e32 v60, v252
	v_mov_b32_e32 v61, v253
	v_mov_b32_e32 v62, v254
	v_mov_b32_e32 v63, v255
	v_add_u32_e32 v198, 0x177200, v197
	global_load_dwordx4 v[248:251], v198, s[34:35]
	v_add_u32_e32 v198, 0x176000, v197
	global_load_dwordx4 v[252:255], v198, s[34:35]
	v_lshlrev_b32_e32 v66, 16, v57
	v_and_b32_e32 v67, 0xffff0000, v57
	v_lshlrev_b32_e32 v57, 16, v58
	v_lshlrev_b32_e32 v64, 16, v56
	v_and_b32_e32 v65, 0xffff0000, v56
	v_mul_f32_e32 v57, 0xbfb8aa3b, v57
	v_and_b32_e32 v68, 0xffff0000, v58
	v_mul_f32_e32 v56, 0xbfb8aa3b, v64
	v_exp_f32_e32 v58, v57
	v_mul_f32_e32 v57, 0xbfb8aa3b, v65
	v_exp_f32_e32 v56, v56
	v_exp_f32_e32 v57, v57
	v_mul_f32_e32 v65, 0xbfb8aa3b, v67
	v_lshlrev_b32_e32 v69, 16, v59
	v_and_b32_e32 v70, 0xffff0000, v59
	v_pk_add_f32 v[56:57], v[56:57], 1.0 op_sel_hi:[1,0]
	v_mul_f32_e32 v59, 0xbfb8aa3b, v68
	v_div_scale_f32 v67, s[6:7], v57, v57, 1.0
	v_rcp_f32_e32 v68, v67
	v_mul_f32_e32 v64, 0xbfb8aa3b, v66
	v_mul_f32_e32 v66, 0xbfb8aa3b, v69
	v_exp_f32_e32 v64, v64
	v_fma_f32 v69, -v67, v68, 1.0
	v_fmac_f32_e32 v68, v69, v68
	v_div_scale_f32 v69, vcc, 1.0, v57, 1.0
	v_mul_f32_e32 v71, v69, v68
	v_fma_f32 v73, -v67, v71, v69
	v_fmac_f32_e32 v71, v73, v68
	v_fma_f32 v67, -v67, v71, v69
	v_div_scale_f32 v69, s[6:7], v56, v56, 1.0
	v_rcp_f32_e32 v73, v69
	v_div_fmas_f32 v67, v67, v68, v71
	v_exp_f32_e32 v65, v65
	v_div_fixup_f32 v57, v67, v57, 1.0
	v_fma_f32 v67, -v69, v73, 1.0
	v_fmac_f32_e32 v73, v67, v73
	v_div_scale_f32 v67, vcc, 1.0, v56, 1.0
	v_mul_f32_e32 v68, v67, v73
	v_fma_f32 v71, -v69, v68, v67
	v_pk_add_f32 v[64:65], v[64:65], 1.0 op_sel_hi:[1,0]
	v_fmac_f32_e32 v68, v71, v73
	v_fma_f32 v67, -v69, v68, v67
	v_div_scale_f32 v69, s[6:7], v65, v65, 1.0
	v_rcp_f32_e32 v71, v69
	v_div_fmas_f32 v67, v67, v73, v68
	v_div_fixup_f32 v56, v67, v56, 1.0
	v_exp_f32_e32 v59, v59
	v_fma_f32 v67, -v69, v71, 1.0
	v_fmac_f32_e32 v71, v67, v71
	v_div_scale_f32 v67, vcc, 1.0, v65, 1.0
	v_mul_f32_e32 v68, v67, v71
	v_fma_f32 v73, -v69, v68, v67
	v_fmac_f32_e32 v68, v73, v71
	v_fma_f32 v67, -v69, v68, v67
	v_div_scale_f32 v69, s[6:7], v64, v64, 1.0
	v_rcp_f32_e32 v73, v69
	v_div_fmas_f32 v67, v67, v71, v68
	v_div_fixup_f32 v65, v67, v65, 1.0
	v_pk_add_f32 v[58:59], v[58:59], 1.0 op_sel_hi:[1,0]
	v_fma_f32 v67, -v69, v73, 1.0
	v_fmac_f32_e32 v73, v67, v73
	v_div_scale_f32 v67, vcc, 1.0, v64, 1.0
	v_mul_f32_e32 v68, v67, v73
	v_fma_f32 v71, -v69, v68, v67
	v_fmac_f32_e32 v68, v71, v73
	v_fma_f32 v69, -v69, v68, v67
	v_mul_f32_e32 v67, 0xbfb8aa3b, v70
	v_div_scale_f32 v70, s[6:7], v59, v59, 1.0
	v_rcp_f32_e32 v71, v70
	v_div_fmas_f32 v68, v69, v73, v68
	v_div_fixup_f32 v64, v68, v64, 1.0
	v_exp_f32_e32 v66, v66
	v_fma_f32 v68, -v70, v71, 1.0
	v_fmac_f32_e32 v71, v68, v71
	v_div_scale_f32 v68, vcc, 1.0, v59, 1.0
	v_mul_f32_e32 v69, v68, v71
	v_fma_f32 v73, -v70, v69, v68
	v_fmac_f32_e32 v69, v73, v71
	v_fma_f32 v68, -v70, v69, v68
	v_div_scale_f32 v70, s[6:7], v58, v58, 1.0
	v_rcp_f32_e32 v73, v70
	v_div_fmas_f32 v68, v68, v71, v69
	v_exp_f32_e32 v67, v67
	v_div_fixup_f32 v59, v68, v59, 1.0
	v_fma_f32 v68, -v70, v73, 1.0
	v_fmac_f32_e32 v73, v68, v73
	v_div_scale_f32 v68, vcc, 1.0, v58, 1.0
	v_mul_f32_e32 v69, v68, v73
	v_fma_f32 v71, -v70, v69, v68
	v_pk_add_f32 v[66:67], v[66:67], 1.0 op_sel_hi:[1,0]
	v_fmac_f32_e32 v69, v71, v73
	v_fma_f32 v68, -v70, v69, v68
	v_div_scale_f32 v70, s[6:7], v67, v67, 1.0
	v_rcp_f32_e32 v71, v70
	v_div_fmas_f32 v68, v68, v73, v69
	v_div_fixup_f32 v58, v68, v58, 1.0
	v_fma_f32 v68, -v70, v71, 1.0
	v_fmac_f32_e32 v71, v68, v71
	v_div_scale_f32 v68, vcc, 1.0, v67, 1.0
	v_mul_f32_e32 v69, v68, v71
	v_fma_f32 v73, -v70, v69, v68
	v_fmac_f32_e32 v69, v73, v71
	v_fma_f32 v68, -v70, v69, v68
	v_div_scale_f32 v70, s[6:7], v66, v66, 1.0
	v_rcp_f32_e32 v73, v70
	v_div_fmas_f32 v68, v68, v71, v69
	v_div_fixup_f32 v67, v68, v67, 1.0
	v_fma_f32 v68, -v70, v73, 1.0
	v_fmac_f32_e32 v73, v68, v73
	v_div_scale_f32 v68, vcc, 1.0, v66, 1.0
	v_mul_f32_e32 v69, v68, v73
	v_fma_f32 v71, -v70, v69, v68
	v_fmac_f32_e32 v69, v71, v73
	v_fma_f32 v68, -v70, v69, v68
	v_div_fmas_f32 v68, v68, v73, v69
	v_div_fixup_f32 v66, v68, v66, 1.0
	v_lshlrev_b32_e32 v68, 16, v60
	v_and_b32_e32 v69, 0xffff0000, v60
	v_lshlrev_b32_e32 v70, 16, v62
	v_and_b32_e32 v71, 0xffff0000, v62
	v_lshlrev_b32_e32 v62, 16, v63
	v_and_b32_e32 v63, 0xffff0000, v63
	v_lshlrev_b32_e32 v60, 16, v61
	v_and_b32_e32 v61, 0xffff0000, v61
	v_pk_fma_f32 v[52:53], v[52:53], v[56:57], v[68:69]
	v_pk_fma_f32 v[56:57], v[50:51], v[66:67], v[62:63]
	v_pk_fma_f32 v[50:51], v[48:49], v[58:59], v[70:71]
	v_cvt_pk_bf16_f32 v48, v52, v53
	v_pk_fma_f32 v[54:55], v[54:55], v[64:65], v[60:61]
	s_nop 0
	v_cvt_pk_bf16_f32 v49, v54, v55
	v_cvt_pk_bf16_f32 v50, v50, v51
	v_cvt_pk_bf16_f32 v51, v56, v57
	buffer_store_dwordx4 v[48:51], v72, s[20:23], 0 offen offset:256 sc1
	s_nop 1
	v_add_u32_e32 v48, 0x4090, v158
	v_mad_i64_i32 v[50:51], s[6:7], v48, s73, 0
	v_lshl_add_u64 v[48:49], v[50:51], 1, s[34:35]
	v_lshl_add_u64 v[48:49], v[48:49], 0, v[142:143]
	v_add_co_u32_e32 v52, vcc, s74, v48
	s_nop 1
	v_addc_co_u32_e32 v53, vcc, 0, v49, vcc
	s_waitcnt vmcnt(13)
; __device__ __forceinline__ u32x4 pack8(const f32x4 v0, const f32x4 v1) { u32x4 w; w.x = pk2(v0[0], v0[1]); w.y = pk2(v0[2], v0[3]); w.z = pk2(v1[0], v1[1]); w.w = pk2(v1[2], v1[3]); return w; }
; __device__ __forceinline__ void unpack8(const u32x4 w, f32x4& v0, f32x4& v1) { v0 = (f32x4){bflo(w.x), bfhi(w.x), bflo(w.y), bfhi(w.y)}; v1 = (f32x4){bflo(w.z), bfhi(w.z), bflo(w.w), bfhi(w.w)}; }
; __device__ __forceinline__ float sigmoidf_(float x) { return 1.0f / (1.0f + __expf(-x)); }
;     __device__ __forceinline__ void operator()(const f32x4 (&acc)[2][2][4][2], const Unit& u, int wr, int wc, int fr, int fq) const {
;     ...
;                 const int row = row0 + ai * 128 + m * 16;
;                 const bf16_t* rowp = z + (size_t)row * DIN + col0;
; #pragma unroll
;                 for (int bj = 0; bj < 2; ++bj) {
;                     const u32x4 gw = *(const u32x4*)(rowp + O_GA + bj * 128);
;                     f32x4 g0, g1; unpack8(gw, g0, g1);
;                     f32x4 v0, v1;
; #pragma unroll
;                     for (int j = 0; j < 4; ++j) { v0[j] = sigmoidf_(g0[j]) * acc[ai][bj][m][0][j]; v1[j] = sigmoidf_(g1[j]) * acc[ai][bj][m][1][j]; }
;                     const u32x4 mw = *(const u32x4*)(rowp + bj * 128); f32x4 m0, m1; unpack8(mw, m0, m1); v0 += m0; v1 += m1;
;                     __builtin_amdgcn_raw_buffer_store_b128(pack8(v0, v1), rsrc, (unsigned)(((size_t)row * DIN + col0 + bj * 128) * 2), 0, 16  ); }
	v_mov_b32_e32 v54, v200
	v_mov_b32_e32 v55, v201
	v_mov_b32_e32 v56, v202
	v_mov_b32_e32 v57, v203
	v_mov_b32_e32 v58, v204
	v_mov_b32_e32 v59, v205
	v_mov_b32_e32 v60, v206
	v_mov_b32_e32 v61, v207
	v_add_u32_e32 v198, 0x177300, v197
	global_load_dwordx4 v[200:203], v198, s[34:35]
	v_add_u32_e32 v198, 0x176100, v197
	global_load_dwordx4 v[204:207], v198, s[34:35]
	v_lshlrev_b32_e32 v51, 16, v54
	v_lshlrev_b32_e32 v63, 16, v55
	v_and_b32_e32 v64, 0xffff0000, v55
	v_lshlrev_b32_e32 v55, 16, v56
	v_mul_f32_e32 v51, 0xbfb8aa3b, v51
	v_and_b32_e32 v62, 0xffff0000, v54
	v_exp_f32_e32 v54, v51
	v_mul_f32_e32 v51, 0xbfb8aa3b, v55
	v_and_b32_e32 v65, 0xffff0000, v56
	v_exp_f32_e32 v56, v51
	v_mul_f32_e32 v51, 0xbfb8aa3b, v62
	v_exp_f32_e32 v55, v51
	v_mul_f32_e32 v51, 0xbfb8aa3b, v65
	v_lshlrev_b32_e32 v66, 16, v57
	v_and_b32_e32 v67, 0xffff0000, v57
	v_exp_f32_e32 v57, v51
	v_mul_f32_e32 v51, 0xbfb8aa3b, v63
	v_exp_f32_e32 v62, v51
	v_mul_f32_e32 v51, 0xbfb8aa3b, v64
	v_pk_add_f32 v[54:55], v[54:55], 1.0 op_sel_hi:[1,0]
	v_exp_f32_e32 v63, v51
	v_div_scale_f32 v51, s[6:7], v55, v55, 1.0
	v_rcp_f32_e32 v65, v51
	v_mul_f32_e32 v64, 0xbfb8aa3b, v66
	v_pk_add_f32 v[62:63], v[62:63], 1.0 op_sel_hi:[1,0]
	v_pk_add_f32 v[56:57], v[56:57], 1.0 op_sel_hi:[1,0]
	v_fma_f32 v66, -v51, v65, 1.0
	v_fmac_f32_e32 v65, v66, v65
	v_div_scale_f32 v66, vcc, 1.0, v55, 1.0
	v_mul_f32_e32 v68, v66, v65
	v_fma_f32 v69, -v51, v68, v66
	v_fmac_f32_e32 v68, v69, v65
	v_fma_f32 v51, -v51, v68, v66
	v_div_scale_f32 v66, s[6:7], v54, v54, 1.0
	v_rcp_f32_e32 v69, v66
	v_div_fmas_f32 v51, v51, v65, v68
	v_div_fixup_f32 v55, v51, v55, 1.0
	v_exp_f32_e32 v64, v64
	v_fma_f32 v51, -v66, v69, 1.0
	v_fmac_f32_e32 v69, v51, v69
	v_div_scale_f32 v51, vcc, 1.0, v54, 1.0
	v_mul_f32_e32 v65, v51, v69
	v_fma_f32 v68, -v66, v65, v51
	v_fmac_f32_e32 v65, v68, v69
	v_fma_f32 v51, -v66, v65, v51
	v_div_scale_f32 v66, s[6:7], v63, v63, 1.0
	v_rcp_f32_e32 v68, v66
	v_div_fmas_f32 v51, v51, v69, v65
	v_div_fixup_f32 v54, v51, v54, 1.0
	v_fma_f32 v51, -v66, v68, 1.0
	v_fmac_f32_e32 v68, v51, v68
	v_div_scale_f32 v51, vcc, 1.0, v63, 1.0
	v_mul_f32_e32 v65, v51, v68
	v_fma_f32 v69, -v66, v65, v51
	v_fmac_f32_e32 v65, v69, v68
	v_fma_f32 v51, -v66, v65, v51
	v_div_scale_f32 v66, s[6:7], v62, v62, 1.0
	v_rcp_f32_e32 v69, v66
	v_div_fmas_f32 v51, v51, v68, v65
	v_div_fixup_f32 v63, v51, v63, 1.0
	v_fma_f32 v51, -v66, v69, 1.0
	v_fmac_f32_e32 v69, v51, v69
	v_div_scale_f32 v51, vcc, 1.0, v62, 1.0
	v_mul_f32_e32 v68, v51, v69
	v_fma_f32 v65, -v66, v68, v51
	v_fmac_f32_e32 v68, v65, v69
	v_fma_f32 v51, -v66, v68, v51
	v_div_scale_f32 v66, s[6:7], v57, v57, 1.0
	v_mul_f32_e32 v65, 0xbfb8aa3b, v67
	v_rcp_f32_e32 v67, v66
	v_div_fmas_f32 v51, v51, v69, v68
	v_div_fixup_f32 v62, v51, v62, 1.0
	v_exp_f32_e32 v65, v65
	v_fma_f32 v51, -v66, v67, 1.0
	v_fmac_f32_e32 v67, v51, v67
	v_div_scale_f32 v51, vcc, 1.0, v57, 1.0
	v_mul_f32_e32 v68, v51, v67
	v_fma_f32 v69, -v66, v68, v51
	v_fmac_f32_e32 v68, v69, v67
	v_fma_f32 v51, -v66, v68, v51
	v_div_scale_f32 v66, s[6:7], v56, v56, 1.0
	v_rcp_f32_e32 v69, v66
	v_div_fmas_f32 v51, v51, v67, v68
	v_div_fixup_f32 v57, v51, v57, 1.0
	v_pk_add_f32 v[64:65], v[64:65], 1.0 op_sel_hi:[1,0]
	v_fma_f32 v51, -v66, v69, 1.0
	v_fmac_f32_e32 v69, v51, v69
	v_div_scale_f32 v51, vcc, 1.0, v56, 1.0
	v_mul_f32_e32 v67, v51, v69
	v_fma_f32 v68, -v66, v67, v51
	v_fmac_f32_e32 v67, v68, v69
	v_fma_f32 v51, -v66, v67, v51
	v_div_scale_f32 v66, s[6:7], v65, v65, 1.0
	v_rcp_f32_e32 v68, v66
	v_div_fmas_f32 v51, v51, v69, v67
	v_div_fixup_f32 v56, v51, v56, 1.0
	v_fma_f32 v51, -v66, v68, 1.0
	v_fmac_f32_e32 v68, v51, v68
	v_div_scale_f32 v51, vcc, 1.0, v65, 1.0
	v_mul_f32_e32 v67, v51, v68
	v_fma_f32 v69, -v66, v67, v51
	v_fmac_f32_e32 v67, v69, v68
	v_fma_f32 v51, -v66, v67, v51
	v_div_scale_f32 v66, s[6:7], v64, v64, 1.0
	v_rcp_f32_e32 v69, v66
	v_div_fmas_f32 v51, v51, v68, v67
	v_div_fixup_f32 v65, v51, v65, 1.0
	v_fma_f32 v51, -v66, v69, 1.0
	v_fmac_f32_e32 v69, v51, v69
	v_div_scale_f32 v51, vcc, 1.0, v64, 1.0
	v_mul_f32_e32 v67, v51, v69
	v_fma_f32 v68, -v66, v67, v51
	v_fmac_f32_e32 v67, v68, v69
	v_fma_f32 v51, -v66, v67, v51
	v_div_fmas_f32 v51, v51, v69, v67
	v_div_fixup_f32 v64, v51, v64, 1.0
	v_lshlrev_b32_e32 v66, 16, v58
	v_and_b32_e32 v67, 0xffff0000, v58
	v_lshlrev_b32_e32 v68, 16, v60
	v_and_b32_e32 v69, 0xffff0000, v60
	v_lshlrev_b32_e32 v60, 16, v61
	v_and_b32_e32 v61, 0xffff0000, v61
	v_lshlrev_b32_e32 v58, 16, v59
	v_and_b32_e32 v59, 0xffff0000, v59
	v_pk_fma_f32 v[44:45], v[44:45], v[54:55], v[66:67]
	v_pk_fma_f32 v[54:55], v[42:43], v[64:65], v[60:61]
	v_pk_fma_f32 v[42:43], v[40:41], v[56:57], v[68:69]
	v_add_lshl_u32 v56, v140, v50, 1
	v_pk_fma_f32 v[46:47], v[46:47], v[62:63], v[58:59]
	v_cvt_pk_bf16_f32 v40, v44, v45
	s_nop 0
	v_cvt_pk_bf16_f32 v41, v46, v47
	v_cvt_pk_bf16_f32 v42, v42, v43
	v_cvt_pk_bf16_f32 v43, v54, v55
	buffer_store_dwordx4 v[40:43], v56, s[20:23], 0 offen sc1
	s_nop 0
	s_waitcnt vmcnt(13)
; __device__ __forceinline__ u32x4 pack8(const f32x4 v0, const f32x4 v1) { u32x4 w; w.x = pk2(v0[0], v0[1]); w.y = pk2(v0[2], v0[3]); w.z = pk2(v1[0], v1[1]); w.w = pk2(v1[2], v1[3]); return w; }
; __device__ __forceinline__ void unpack8(const u32x4 w, f32x4& v0, f32x4& v1) { v0 = (f32x4){bflo(w.x), bfhi(w.x), bflo(w.y), bfhi(w.y)}; v1 = (f32x4){bflo(w.z), bfhi(w.z), bflo(w.w), bfhi(w.w)}; }
; __device__ __forceinline__ float sigmoidf_(float x) { return 1.0f / (1.0f + __expf(-x)); }
;     __device__ __forceinline__ void operator()(const f32x4 (&acc)[2][2][4][2], const Unit& u, int wr, int wc, int fr, int fq) const {
;     ...
;                 const int row = row0 + ai * 128 + m * 16;
;                 const bf16_t* rowp = z + (size_t)row * DIN + col0;
; #pragma unroll
;                 for (int bj = 0; bj < 2; ++bj) {
;                     const u32x4 gw = *(const u32x4*)(rowp + O_GA + bj * 128);
;                     f32x4 g0, g1; unpack8(gw, g0, g1);
;                     f32x4 v0, v1;
; #pragma unroll
;                     for (int j = 0; j < 4; ++j) { v0[j] = sigmoidf_(g0[j]) * acc[ai][bj][m][0][j]; v1[j] = sigmoidf_(g1[j]) * acc[ai][bj][m][1][j]; }
;                     const u32x4 mw = *(const u32x4*)(rowp + bj * 128); f32x4 m0, m1; unpack8(mw, m0, m1); v0 += m0; v1 += m1;
;                     __builtin_amdgcn_raw_buffer_store_b128(pack8(v0, v1), rsrc, (unsigned)(((size_t)row * DIN + col0 + bj * 128) * 2), 0, 16  ); }
	v_mov_b32_e32 v40, v208
	v_mov_b32_e32 v41, v209
	v_mov_b32_e32 v42, v210
	v_mov_b32_e32 v43, v211
	v_mov_b32_e32 v44, v212
	v_mov_b32_e32 v45, v213
	v_mov_b32_e32 v46, v214
	v_mov_b32_e32 v47, v215
	v_lshlrev_b32_e32 v50, 16, v41
	v_and_b32_e32 v51, 0xffff0000, v41
	v_lshlrev_b32_e32 v41, 16, v42
	v_lshlrev_b32_e32 v48, 16, v40
	v_and_b32_e32 v49, 0xffff0000, v40
	v_mul_f32_e32 v41, 0xbfb8aa3b, v41
	v_and_b32_e32 v52, 0xffff0000, v42
	v_mul_f32_e32 v40, 0xbfb8aa3b, v48
	v_exp_f32_e32 v42, v41
	v_mul_f32_e32 v41, 0xbfb8aa3b, v49
	v_exp_f32_e32 v40, v40
	v_exp_f32_e32 v41, v41
	v_mul_f32_e32 v49, 0xbfb8aa3b, v51
	v_lshlrev_b32_e32 v53, 16, v43
	v_and_b32_e32 v54, 0xffff0000, v43
	v_pk_add_f32 v[40:41], v[40:41], 1.0 op_sel_hi:[1,0]
	v_mul_f32_e32 v43, 0xbfb8aa3b, v52
	v_div_scale_f32 v51, s[6:7], v41, v41, 1.0
	v_rcp_f32_e32 v52, v51
	v_mul_f32_e32 v48, 0xbfb8aa3b, v50
	v_mul_f32_e32 v50, 0xbfb8aa3b, v53
	v_exp_f32_e32 v48, v48
	v_fma_f32 v53, -v51, v52, 1.0
	v_fmac_f32_e32 v52, v53, v52
	v_div_scale_f32 v53, vcc, 1.0, v41, 1.0
	v_mul_f32_e32 v55, v53, v52
	v_fma_f32 v57, -v51, v55, v53
	v_fmac_f32_e32 v55, v57, v52
	v_fma_f32 v51, -v51, v55, v53
	v_div_scale_f32 v53, s[6:7], v40, v40, 1.0
	v_rcp_f32_e32 v57, v53
	v_div_fmas_f32 v51, v51, v52, v55
	v_exp_f32_e32 v49, v49
	v_div_fixup_f32 v41, v51, v41, 1.0
	v_fma_f32 v51, -v53, v57, 1.0
	v_fmac_f32_e32 v57, v51, v57
	v_div_scale_f32 v51, vcc, 1.0, v40, 1.0
	v_mul_f32_e32 v52, v51, v57
	v_fma_f32 v55, -v53, v52, v51
	v_pk_add_f32 v[48:49], v[48:49], 1.0 op_sel_hi:[1,0]
	v_fmac_f32_e32 v52, v55, v57
	v_fma_f32 v51, -v53, v52, v51
	v_div_scale_f32 v53, s[6:7], v49, v49, 1.0
	v_rcp_f32_e32 v55, v53
	v_div_fmas_f32 v51, v51, v57, v52
	v_div_fixup_f32 v40, v51, v40, 1.0
	v_exp_f32_e32 v43, v43
	v_fma_f32 v51, -v53, v55, 1.0
	v_fmac_f32_e32 v55, v51, v55
	v_div_scale_f32 v51, vcc, 1.0, v49, 1.0
	v_mul_f32_e32 v52, v51, v55
	v_fma_f32 v57, -v53, v52, v51
	v_fmac_f32_e32 v52, v57, v55
	v_fma_f32 v51, -v53, v52, v51
	v_div_scale_f32 v53, s[6:7], v48, v48, 1.0
	v_rcp_f32_e32 v57, v53
	v_div_fmas_f32 v51, v51, v55, v52
	v_div_fixup_f32 v49, v51, v49, 1.0
	v_pk_add_f32 v[42:43], v[42:43], 1.0 op_sel_hi:[1,0]
	v_fma_f32 v51, -v53, v57, 1.0
	v_fmac_f32_e32 v57, v51, v57
	v_div_scale_f32 v51, vcc, 1.0, v48, 1.0
	v_mul_f32_e32 v52, v51, v57
	v_fma_f32 v55, -v53, v52, v51
	v_fmac_f32_e32 v52, v55, v57
	v_fma_f32 v53, -v53, v52, v51
	v_mul_f32_e32 v51, 0xbfb8aa3b, v54
	v_div_scale_f32 v54, s[6:7], v43, v43, 1.0
	v_rcp_f32_e32 v55, v54
	v_div_fmas_f32 v52, v53, v57, v52
	v_div_fixup_f32 v48, v52, v48, 1.0
	v_exp_f32_e32 v50, v50
	v_fma_f32 v52, -v54, v55, 1.0
	v_fmac_f32_e32 v55, v52, v55
	v_div_scale_f32 v52, vcc, 1.0, v43, 1.0
	v_mul_f32_e32 v53, v52, v55
	v_fma_f32 v57, -v54, v53, v52
	v_fmac_f32_e32 v53, v57, v55
	v_fma_f32 v52, -v54, v53, v52
	v_div_scale_f32 v54, s[6:7], v42, v42, 1.0
	v_rcp_f32_e32 v57, v54
	v_div_fmas_f32 v52, v52, v55, v53
	v_exp_f32_e32 v51, v51
	v_div_fixup_f32 v43, v52, v43, 1.0
	v_fma_f32 v52, -v54, v57, 1.0
	v_fmac_f32_e32 v57, v52, v57
	v_div_scale_f32 v52, vcc, 1.0, v42, 1.0
	v_mul_f32_e32 v53, v52, v57
	v_fma_f32 v55, -v54, v53, v52
	v_pk_add_f32 v[50:51], v[50:51], 1.0 op_sel_hi:[1,0]
	v_fmac_f32_e32 v53, v55, v57
	v_fma_f32 v52, -v54, v53, v52
	v_div_scale_f32 v54, s[6:7], v51, v51, 1.0
	v_rcp_f32_e32 v55, v54
	v_div_fmas_f32 v52, v52, v57, v53
	v_div_fixup_f32 v42, v52, v42, 1.0
	v_fma_f32 v52, -v54, v55, 1.0
	v_fmac_f32_e32 v55, v52, v55
	v_div_scale_f32 v52, vcc, 1.0, v51, 1.0
	v_mul_f32_e32 v53, v52, v55
	v_fma_f32 v57, -v54, v53, v52
	v_fmac_f32_e32 v53, v57, v55
	v_fma_f32 v52, -v54, v53, v52
	v_div_scale_f32 v54, s[6:7], v50, v50, 1.0
	v_rcp_f32_e32 v57, v54
	v_div_fmas_f32 v52, v52, v55, v53
	v_div_fixup_f32 v51, v52, v51, 1.0
	v_fma_f32 v52, -v54, v57, 1.0
	v_fmac_f32_e32 v57, v52, v57
	v_div_scale_f32 v52, vcc, 1.0, v50, 1.0
	v_mul_f32_e32 v53, v52, v57
	v_fma_f32 v55, -v54, v53, v52
	v_fmac_f32_e32 v53, v55, v57
	v_fma_f32 v52, -v54, v53, v52
	v_div_fmas_f32 v52, v52, v57, v53
	v_div_fixup_f32 v50, v52, v50, 1.0
	v_lshlrev_b32_e32 v52, 16, v44
	v_and_b32_e32 v53, 0xffff0000, v44
	v_lshlrev_b32_e32 v54, 16, v46
	v_and_b32_e32 v55, 0xffff0000, v46
	v_lshlrev_b32_e32 v46, 16, v47
	v_and_b32_e32 v47, 0xffff0000, v47
	v_lshlrev_b32_e32 v44, 16, v45
	v_and_b32_e32 v45, 0xffff0000, v45
	v_pk_fma_f32 v[36:37], v[36:37], v[40:41], v[52:53]
	v_pk_fma_f32 v[40:41], v[34:35], v[50:51], v[46:47]
	v_pk_fma_f32 v[34:35], v[32:33], v[42:43], v[54:55]
	v_cvt_pk_bf16_f32 v32, v36, v37
	v_pk_fma_f32 v[38:39], v[38:39], v[48:49], v[44:45]
	s_nop 0
	v_cvt_pk_bf16_f32 v33, v38, v39
	v_cvt_pk_bf16_f32 v34, v34, v35
	v_cvt_pk_bf16_f32 v35, v40, v41
	buffer_store_dwordx4 v[32:35], v56, s[20:23], 0 offen offset:256 sc1
	s_nop 1
	v_add_u32_e32 v32, 0x40a0, v158
	v_mad_i64_i32 v[34:35], s[6:7], v32, s73, 0
	v_lshl_add_u64 v[32:33], v[34:35], 1, s[34:35]
	v_lshl_add_u64 v[32:33], v[32:33], 0, v[142:143]
	v_add_co_u32_e32 v36, vcc, s74, v32
	s_nop 1
	v_addc_co_u32_e32 v37, vcc, 0, v33, vcc
	s_waitcnt vmcnt(11)
; __device__ __forceinline__ u32x4 pack8(const f32x4 v0, const f32x4 v1) { u32x4 w; w.x = pk2(v0[0], v0[1]); w.y = pk2(v0[2], v0[3]); w.z = pk2(v1[0], v1[1]); w.w = pk2(v1[2], v1[3]); return w; }
; __device__ __forceinline__ void unpack8(const u32x4 w, f32x4& v0, f32x4& v1) { v0 = (f32x4){bflo(w.x), bfhi(w.x), bflo(w.y), bfhi(w.y)}; v1 = (f32x4){bflo(w.z), bfhi(w.z), bflo(w.w), bfhi(w.w)}; }
; __device__ __forceinline__ float sigmoidf_(float x) { return 1.0f / (1.0f + __expf(-x)); }
;     __device__ __forceinline__ void operator()(const f32x4 (&acc)[2][2][4][2], const Unit& u, int wr, int wc, int fr, int fq) const {
;     ...
;                 const int row = row0 + ai * 128 + m * 16;
;                 const bf16_t* rowp = z + (size_t)row * DIN + col0;
; #pragma unroll
;                 for (int bj = 0; bj < 2; ++bj) {
;                     const u32x4 gw = *(const u32x4*)(rowp + O_GA + bj * 128);
;                     f32x4 g0, g1; unpack8(gw, g0, g1);
;                     f32x4 v0, v1;
; #pragma unroll
;                     for (int j = 0; j < 4; ++j) { v0[j] = sigmoidf_(g0[j]) * acc[ai][bj][m][0][j]; v1[j] = sigmoidf_(g1[j]) * acc[ai][bj][m][1][j]; }
;                     const u32x4 mw = *(const u32x4*)(rowp + bj * 128); f32x4 m0, m1; unpack8(mw, m0, m1); v0 += m0; v1 += m1;
;                     __builtin_amdgcn_raw_buffer_store_b128(pack8(v0, v1), rsrc, (unsigned)(((size_t)row * DIN + col0 + bj * 128) * 2), 0, 16  ); }
	v_mov_b32_e32 v38, v232
	v_mov_b32_e32 v39, v233
	v_mov_b32_e32 v40, v234
	v_mov_b32_e32 v41, v235
	v_mov_b32_e32 v42, v236
	v_mov_b32_e32 v43, v237
	v_mov_b32_e32 v44, v238
	v_mov_b32_e32 v45, v239
	v_lshlrev_b32_e32 v35, 16, v38
	v_lshlrev_b32_e32 v47, 16, v39
	v_and_b32_e32 v48, 0xffff0000, v39
	v_lshlrev_b32_e32 v39, 16, v40
	v_mul_f32_e32 v35, 0xbfb8aa3b, v35
	v_and_b32_e32 v46, 0xffff0000, v38
	v_exp_f32_e32 v38, v35
	v_mul_f32_e32 v35, 0xbfb8aa3b, v39
	v_and_b32_e32 v49, 0xffff0000, v40
	v_exp_f32_e32 v40, v35
	v_mul_f32_e32 v35, 0xbfb8aa3b, v46
	v_exp_f32_e32 v39, v35
	v_mul_f32_e32 v35, 0xbfb8aa3b, v49
	v_lshlrev_b32_e32 v50, 16, v41
	v_and_b32_e32 v51, 0xffff0000, v41
	v_exp_f32_e32 v41, v35
	v_mul_f32_e32 v35, 0xbfb8aa3b, v47
	v_exp_f32_e32 v46, v35
	v_mul_f32_e32 v35, 0xbfb8aa3b, v48
	v_pk_add_f32 v[38:39], v[38:39], 1.0 op_sel_hi:[1,0]
	v_exp_f32_e32 v47, v35
	v_div_scale_f32 v35, s[6:7], v39, v39, 1.0
	v_rcp_f32_e32 v49, v35
	v_mul_f32_e32 v48, 0xbfb8aa3b, v50
	v_pk_add_f32 v[46:47], v[46:47], 1.0 op_sel_hi:[1,0]
	v_pk_add_f32 v[40:41], v[40:41], 1.0 op_sel_hi:[1,0]
	v_fma_f32 v50, -v35, v49, 1.0
	v_fmac_f32_e32 v49, v50, v49
	v_div_scale_f32 v50, vcc, 1.0, v39, 1.0
	v_mul_f32_e32 v52, v50, v49
	v_fma_f32 v53, -v35, v52, v50
	v_fmac_f32_e32 v52, v53, v49
	v_fma_f32 v35, -v35, v52, v50
	v_div_scale_f32 v50, s[6:7], v38, v38, 1.0
	v_rcp_f32_e32 v53, v50
	v_div_fmas_f32 v35, v35, v49, v52
	v_div_fixup_f32 v39, v35, v39, 1.0
	v_exp_f32_e32 v48, v48
	v_fma_f32 v35, -v50, v53, 1.0
	v_fmac_f32_e32 v53, v35, v53
	v_div_scale_f32 v35, vcc, 1.0, v38, 1.0
	v_mul_f32_e32 v49, v35, v53
	v_fma_f32 v52, -v50, v49, v35
	v_fmac_f32_e32 v49, v52, v53
	v_fma_f32 v35, -v50, v49, v35
	v_div_scale_f32 v50, s[6:7], v47, v47, 1.0
	v_rcp_f32_e32 v52, v50
	v_div_fmas_f32 v35, v35, v53, v49
	v_div_fixup_f32 v38, v35, v38, 1.0
	v_fma_f32 v35, -v50, v52, 1.0
	v_fmac_f32_e32 v52, v35, v52
	v_div_scale_f32 v35, vcc, 1.0, v47, 1.0
	v_mul_f32_e32 v49, v35, v52
	v_fma_f32 v53, -v50, v49, v35
	v_fmac_f32_e32 v49, v53, v52
	v_fma_f32 v35, -v50, v49, v35
	v_div_scale_f32 v50, s[6:7], v46, v46, 1.0
	v_rcp_f32_e32 v53, v50
	v_div_fmas_f32 v35, v35, v52, v49
	v_div_fixup_f32 v47, v35, v47, 1.0
	v_fma_f32 v35, -v50, v53, 1.0
	v_fmac_f32_e32 v53, v35, v53
	v_div_scale_f32 v35, vcc, 1.0, v46, 1.0
	v_mul_f32_e32 v52, v35, v53
	v_fma_f32 v49, -v50, v52, v35
	v_fmac_f32_e32 v52, v49, v53
	v_fma_f32 v35, -v50, v52, v35
	v_div_scale_f32 v50, s[6:7], v41, v41, 1.0
	v_mul_f32_e32 v49, 0xbfb8aa3b, v51
	v_rcp_f32_e32 v51, v50
	v_div_fmas_f32 v35, v35, v53, v52
	v_div_fixup_f32 v46, v35, v46, 1.0
	v_exp_f32_e32 v49, v49
	v_fma_f32 v35, -v50, v51, 1.0
	v_fmac_f32_e32 v51, v35, v51
	v_div_scale_f32 v35, vcc, 1.0, v41, 1.0
	v_mul_f32_e32 v52, v35, v51
	v_fma_f32 v53, -v50, v52, v35
	v_fmac_f32_e32 v52, v53, v51
	v_fma_f32 v35, -v50, v52, v35
	v_div_scale_f32 v50, s[6:7], v40, v40, 1.0
	v_rcp_f32_e32 v53, v50
	v_div_fmas_f32 v35, v35, v51, v52
	v_div_fixup_f32 v41, v35, v41, 1.0
	v_pk_add_f32 v[48:49], v[48:49], 1.0 op_sel_hi:[1,0]
	v_fma_f32 v35, -v50, v53, 1.0
	v_fmac_f32_e32 v53, v35, v53
	v_div_scale_f32 v35, vcc, 1.0, v40, 1.0
	v_mul_f32_e32 v51, v35, v53
	v_fma_f32 v52, -v50, v51, v35
	v_fmac_f32_e32 v51, v52, v53
	v_fma_f32 v35, -v50, v51, v35
	v_div_scale_f32 v50, s[6:7], v49, v49, 1.0
	v_rcp_f32_e32 v52, v50
	v_div_fmas_f32 v35, v35, v53, v51
	v_div_fixup_f32 v40, v35, v40, 1.0
	v_fma_f32 v35, -v50, v52, 1.0
	v_fmac_f32_e32 v52, v35, v52
	v_div_scale_f32 v35, vcc, 1.0, v49, 1.0
	v_mul_f32_e32 v51, v35, v52
	v_fma_f32 v53, -v50, v51, v35
	v_fmac_f32_e32 v51, v53, v52
	v_fma_f32 v35, -v50, v51, v35
	v_div_scale_f32 v50, s[6:7], v48, v48, 1.0
	v_rcp_f32_e32 v53, v50
	v_div_fmas_f32 v35, v35, v52, v51
	v_div_fixup_f32 v49, v35, v49, 1.0
	v_fma_f32 v35, -v50, v53, 1.0
	v_fmac_f32_e32 v53, v35, v53
	v_div_scale_f32 v35, vcc, 1.0, v48, 1.0
	v_mul_f32_e32 v51, v35, v53
	v_fma_f32 v52, -v50, v51, v35
	v_fmac_f32_e32 v51, v52, v53
	v_fma_f32 v35, -v50, v51, v35
	v_div_fmas_f32 v35, v35, v53, v51
	v_div_fixup_f32 v48, v35, v48, 1.0
	v_lshlrev_b32_e32 v50, 16, v42
	v_and_b32_e32 v51, 0xffff0000, v42
	v_lshlrev_b32_e32 v52, 16, v44
	v_and_b32_e32 v53, 0xffff0000, v44
	v_lshlrev_b32_e32 v44, 16, v45
	v_and_b32_e32 v45, 0xffff0000, v45
	v_lshlrev_b32_e32 v42, 16, v43
	v_and_b32_e32 v43, 0xffff0000, v43
	v_pk_fma_f32 v[28:29], v[28:29], v[38:39], v[50:51]
	v_pk_fma_f32 v[38:39], v[26:27], v[48:49], v[44:45]
	v_pk_fma_f32 v[26:27], v[24:25], v[40:41], v[52:53]
	v_add_lshl_u32 v40, v140, v34, 1
	v_pk_fma_f32 v[30:31], v[30:31], v[46:47], v[42:43]
	v_cvt_pk_bf16_f32 v24, v28, v29
	s_nop 0
	v_cvt_pk_bf16_f32 v25, v30, v31
	v_cvt_pk_bf16_f32 v26, v26, v27
	v_cvt_pk_bf16_f32 v27, v38, v39
	buffer_store_dwordx4 v[24:27], v40, s[20:23], 0 offen sc1
	s_nop 0
	s_waitcnt vmcnt(9)
; __device__ __forceinline__ u32x4 pack8(const f32x4 v0, const f32x4 v1) { u32x4 w; w.x = pk2(v0[0], v0[1]); w.y = pk2(v0[2], v0[3]); w.z = pk2(v1[0], v1[1]); w.w = pk2(v1[2], v1[3]); return w; }
; __device__ __forceinline__ void unpack8(const u32x4 w, f32x4& v0, f32x4& v1) { v0 = (f32x4){bflo(w.x), bfhi(w.x), bflo(w.y), bfhi(w.y)}; v1 = (f32x4){bflo(w.z), bfhi(w.z), bflo(w.w), bfhi(w.w)}; }
; __device__ __forceinline__ float sigmoidf_(float x) { return 1.0f / (1.0f + __expf(-x)); }
;     __device__ __forceinline__ void operator()(const f32x4 (&acc)[2][2][4][2], const Unit& u, int wr, int wc, int fr, int fq) const {
;     ...
;                 const int row = row0 + ai * 128 + m * 16;
;                 const bf16_t* rowp = z + (size_t)row * DIN + col0;
; #pragma unroll
;                 for (int bj = 0; bj < 2; ++bj) {
;                     const u32x4 gw = *(const u32x4*)(rowp + O_GA + bj * 128);
;                     f32x4 g0, g1; unpack8(gw, g0, g1);
;                     f32x4 v0, v1;
; #pragma unroll
;                     for (int j = 0; j < 4; ++j) { v0[j] = sigmoidf_(g0[j]) * acc[ai][bj][m][0][j]; v1[j] = sigmoidf_(g1[j]) * acc[ai][bj][m][1][j]; }
;                     const u32x4 mw = *(const u32x4*)(rowp + bj * 128); f32x4 m0, m1; unpack8(mw, m0, m1); v0 += m0; v1 += m1;
;                     __builtin_amdgcn_raw_buffer_store_b128(pack8(v0, v1), rsrc, (unsigned)(((size_t)row * DIN + col0 + bj * 128) * 2), 0, 16  ); }
	v_mov_b32_e32 v24, v240
	v_mov_b32_e32 v25, v241
	v_mov_b32_e32 v26, v242
	v_mov_b32_e32 v27, v243
	v_mov_b32_e32 v28, v244
	v_mov_b32_e32 v29, v245
	v_mov_b32_e32 v30, v246
	v_mov_b32_e32 v31, v247
	v_lshlrev_b32_e32 v34, 16, v25
	v_and_b32_e32 v35, 0xffff0000, v25
	v_lshlrev_b32_e32 v25, 16, v26
	v_lshlrev_b32_e32 v32, 16, v24
	v_and_b32_e32 v33, 0xffff0000, v24
	v_mul_f32_e32 v25, 0xbfb8aa3b, v25
	v_and_b32_e32 v36, 0xffff0000, v26
	v_mul_f32_e32 v24, 0xbfb8aa3b, v32
	v_exp_f32_e32 v26, v25
	v_mul_f32_e32 v25, 0xbfb8aa3b, v33
	v_exp_f32_e32 v24, v24
	v_exp_f32_e32 v25, v25
	v_mul_f32_e32 v33, 0xbfb8aa3b, v35
	v_lshlrev_b32_e32 v37, 16, v27
	v_and_b32_e32 v38, 0xffff0000, v27
	v_pk_add_f32 v[24:25], v[24:25], 1.0 op_sel_hi:[1,0]
	v_mul_f32_e32 v27, 0xbfb8aa3b, v36
	v_div_scale_f32 v35, s[6:7], v25, v25, 1.0
	v_rcp_f32_e32 v36, v35
	v_mul_f32_e32 v32, 0xbfb8aa3b, v34
	v_mul_f32_e32 v34, 0xbfb8aa3b, v37
	v_exp_f32_e32 v32, v32
	v_fma_f32 v37, -v35, v36, 1.0
	v_fmac_f32_e32 v36, v37, v36
	v_div_scale_f32 v37, vcc, 1.0, v25, 1.0
	v_mul_f32_e32 v39, v37, v36
	v_fma_f32 v41, -v35, v39, v37
	v_fmac_f32_e32 v39, v41, v36
	v_fma_f32 v35, -v35, v39, v37
	v_div_scale_f32 v37, s[6:7], v24, v24, 1.0
	v_rcp_f32_e32 v41, v37
	v_div_fmas_f32 v35, v35, v36, v39
	v_exp_f32_e32 v33, v33
	v_div_fixup_f32 v25, v35, v25, 1.0
	v_fma_f32 v35, -v37, v41, 1.0
	v_fmac_f32_e32 v41, v35, v41
	v_div_scale_f32 v35, vcc, 1.0, v24, 1.0
	v_mul_f32_e32 v36, v35, v41
	v_fma_f32 v39, -v37, v36, v35
	v_pk_add_f32 v[32:33], v[32:33], 1.0 op_sel_hi:[1,0]
	v_fmac_f32_e32 v36, v39, v41
	v_fma_f32 v35, -v37, v36, v35
	v_div_scale_f32 v37, s[6:7], v33, v33, 1.0
	v_rcp_f32_e32 v39, v37
	v_div_fmas_f32 v35, v35, v41, v36
	v_div_fixup_f32 v24, v35, v24, 1.0
	v_exp_f32_e32 v27, v27
	v_fma_f32 v35, -v37, v39, 1.0
	v_fmac_f32_e32 v39, v35, v39
	v_div_scale_f32 v35, vcc, 1.0, v33, 1.0
	v_mul_f32_e32 v36, v35, v39
	v_fma_f32 v41, -v37, v36, v35
	v_fmac_f32_e32 v36, v41, v39
	v_fma_f32 v35, -v37, v36, v35
	v_div_scale_f32 v37, s[6:7], v32, v32, 1.0
	v_rcp_f32_e32 v41, v37
	v_div_fmas_f32 v35, v35, v39, v36
	v_div_fixup_f32 v33, v35, v33, 1.0
	v_pk_add_f32 v[26:27], v[26:27], 1.0 op_sel_hi:[1,0]
	v_fma_f32 v35, -v37, v41, 1.0
	v_fmac_f32_e32 v41, v35, v41
	v_div_scale_f32 v35, vcc, 1.0, v32, 1.0
	v_mul_f32_e32 v36, v35, v41
	v_fma_f32 v39, -v37, v36, v35
	v_fmac_f32_e32 v36, v39, v41
	v_fma_f32 v37, -v37, v36, v35
	v_mul_f32_e32 v35, 0xbfb8aa3b, v38
	v_div_scale_f32 v38, s[6:7], v27, v27, 1.0
	v_rcp_f32_e32 v39, v38
	v_div_fmas_f32 v36, v37, v41, v36
	v_div_fixup_f32 v32, v36, v32, 1.0
	v_exp_f32_e32 v34, v34
	v_fma_f32 v36, -v38, v39, 1.0
	v_fmac_f32_e32 v39, v36, v39
	v_div_scale_f32 v36, vcc, 1.0, v27, 1.0
	v_mul_f32_e32 v37, v36, v39
	v_fma_f32 v41, -v38, v37, v36
	v_fmac_f32_e32 v37, v41, v39
	v_fma_f32 v36, -v38, v37, v36
	v_div_scale_f32 v38, s[6:7], v26, v26, 1.0
	v_rcp_f32_e32 v41, v38
	v_div_fmas_f32 v36, v36, v39, v37
	v_exp_f32_e32 v35, v35
	v_div_fixup_f32 v27, v36, v27, 1.0
	v_fma_f32 v36, -v38, v41, 1.0
	v_fmac_f32_e32 v41, v36, v41
	v_div_scale_f32 v36, vcc, 1.0, v26, 1.0
	v_mul_f32_e32 v37, v36, v41
	v_fma_f32 v39, -v38, v37, v36
	v_pk_add_f32 v[34:35], v[34:35], 1.0 op_sel_hi:[1,0]
	v_fmac_f32_e32 v37, v39, v41
	v_fma_f32 v36, -v38, v37, v36
	v_div_scale_f32 v38, s[6:7], v35, v35, 1.0
	v_rcp_f32_e32 v39, v38
	v_div_fmas_f32 v36, v36, v41, v37
	v_div_fixup_f32 v26, v36, v26, 1.0
	v_fma_f32 v36, -v38, v39, 1.0
	v_fmac_f32_e32 v39, v36, v39
	v_div_scale_f32 v36, vcc, 1.0, v35, 1.0
	v_mul_f32_e32 v37, v36, v39
	v_fma_f32 v41, -v38, v37, v36
	v_fmac_f32_e32 v37, v41, v39
	v_fma_f32 v36, -v38, v37, v36
	v_div_scale_f32 v38, s[6:7], v34, v34, 1.0
	v_rcp_f32_e32 v41, v38
	v_div_fmas_f32 v36, v36, v39, v37
	v_div_fixup_f32 v35, v36, v35, 1.0
	v_fma_f32 v36, -v38, v41, 1.0
	v_fmac_f32_e32 v41, v36, v41
	v_div_scale_f32 v36, vcc, 1.0, v34, 1.0
	v_mul_f32_e32 v37, v36, v41
	v_fma_f32 v39, -v38, v37, v36
	v_fmac_f32_e32 v37, v39, v41
	v_fma_f32 v36, -v38, v37, v36
	v_div_fmas_f32 v36, v36, v41, v37
	v_div_fixup_f32 v34, v36, v34, 1.0
	v_lshlrev_b32_e32 v36, 16, v28
	v_and_b32_e32 v37, 0xffff0000, v28
	v_lshlrev_b32_e32 v38, 16, v30
	v_and_b32_e32 v39, 0xffff0000, v30
	v_lshlrev_b32_e32 v30, 16, v31
	v_and_b32_e32 v31, 0xffff0000, v31
	v_lshlrev_b32_e32 v28, 16, v29
	v_and_b32_e32 v29, 0xffff0000, v29
	v_pk_fma_f32 v[20:21], v[20:21], v[24:25], v[36:37]
	v_pk_fma_f32 v[24:25], v[18:19], v[34:35], v[30:31]
	v_pk_fma_f32 v[18:19], v[16:17], v[26:27], v[38:39]
	v_cvt_pk_bf16_f32 v16, v20, v21
	v_pk_fma_f32 v[22:23], v[22:23], v[32:33], v[28:29]
	s_nop 0
	v_cvt_pk_bf16_f32 v17, v22, v23
	v_cvt_pk_bf16_f32 v18, v18, v19
	v_cvt_pk_bf16_f32 v19, v24, v25
	buffer_store_dwordx4 v[16:19], v40, s[20:23], 0 offen offset:256 sc1
	s_nop 1
	v_add_u32_e32 v16, 0x40b0, v158
	v_mad_i64_i32 v[18:19], s[6:7], v16, s73, 0
	v_lshl_add_u64 v[16:17], v[18:19], 1, s[34:35]
	v_lshl_add_u64 v[16:17], v[16:17], 0, v[142:143]
	v_add_co_u32_e32 v20, vcc, s74, v16
	s_nop 1
	v_addc_co_u32_e32 v21, vcc, 0, v17, vcc
	s_waitcnt vmcnt(7)
; __device__ __forceinline__ u32x4 pack8(const f32x4 v0, const f32x4 v1) { u32x4 w; w.x = pk2(v0[0], v0[1]); w.y = pk2(v0[2], v0[3]); w.z = pk2(v1[0], v1[1]); w.w = pk2(v1[2], v1[3]); return w; }
; __device__ __forceinline__ void unpack8(const u32x4 w, f32x4& v0, f32x4& v1) { v0 = (f32x4){bflo(w.x), bfhi(w.x), bflo(w.y), bfhi(w.y)}; v1 = (f32x4){bflo(w.z), bfhi(w.z), bflo(w.w), bfhi(w.w)}; }
; __device__ __forceinline__ float sigmoidf_(float x) { return 1.0f / (1.0f + __expf(-x)); }
;     __device__ __forceinline__ void operator()(const f32x4 (&acc)[2][2][4][2], const Unit& u, int wr, int wc, int fr, int fq) const {
;     ...
;                 const int row = row0 + ai * 128 + m * 16;
;                 const bf16_t* rowp = z + (size_t)row * DIN + col0;
; #pragma unroll
;                 for (int bj = 0; bj < 2; ++bj) {
;                     const u32x4 gw = *(const u32x4*)(rowp + O_GA + bj * 128);
;                     f32x4 g0, g1; unpack8(gw, g0, g1);
;                     f32x4 v0, v1;
; #pragma unroll
;                     for (int j = 0; j < 4; ++j) { v0[j] = sigmoidf_(g0[j]) * acc[ai][bj][m][0][j]; v1[j] = sigmoidf_(g1[j]) * acc[ai][bj][m][1][j]; }
;                     const u32x4 mw = *(const u32x4*)(rowp + bj * 128); f32x4 m0, m1; unpack8(mw, m0, m1); v0 += m0; v1 += m1;
;                     __builtin_amdgcn_raw_buffer_store_b128(pack8(v0, v1), rsrc, (unsigned)(((size_t)row * DIN + col0 + bj * 128) * 2), 0, 16  ); }
	v_mov_b32_e32 v22, v248
	v_mov_b32_e32 v23, v249
	v_mov_b32_e32 v24, v250
	v_mov_b32_e32 v25, v251
	v_mov_b32_e32 v26, v252
	v_mov_b32_e32 v27, v253
	v_mov_b32_e32 v28, v254
	v_mov_b32_e32 v29, v255
	v_lshlrev_b32_e32 v19, 16, v22
	v_lshlrev_b32_e32 v31, 16, v23
	v_and_b32_e32 v32, 0xffff0000, v23
	v_lshlrev_b32_e32 v23, 16, v24
	v_mul_f32_e32 v19, 0xbfb8aa3b, v19
	v_and_b32_e32 v30, 0xffff0000, v22
	v_exp_f32_e32 v22, v19
	v_mul_f32_e32 v19, 0xbfb8aa3b, v23
	v_and_b32_e32 v33, 0xffff0000, v24
	v_exp_f32_e32 v24, v19
	v_mul_f32_e32 v19, 0xbfb8aa3b, v30
	v_exp_f32_e32 v23, v19
	v_mul_f32_e32 v19, 0xbfb8aa3b, v33
	v_lshlrev_b32_e32 v34, 16, v25
	v_and_b32_e32 v35, 0xffff0000, v25
	v_exp_f32_e32 v25, v19
	v_mul_f32_e32 v19, 0xbfb8aa3b, v31
	v_exp_f32_e32 v30, v19
	v_mul_f32_e32 v19, 0xbfb8aa3b, v32
	v_pk_add_f32 v[22:23], v[22:23], 1.0 op_sel_hi:[1,0]
	v_exp_f32_e32 v31, v19
	v_div_scale_f32 v19, s[6:7], v23, v23, 1.0
	v_rcp_f32_e32 v33, v19
	v_mul_f32_e32 v32, 0xbfb8aa3b, v34
	v_pk_add_f32 v[30:31], v[30:31], 1.0 op_sel_hi:[1,0]
	v_pk_add_f32 v[24:25], v[24:25], 1.0 op_sel_hi:[1,0]
	v_fma_f32 v34, -v19, v33, 1.0
	v_fmac_f32_e32 v33, v34, v33
	v_div_scale_f32 v34, vcc, 1.0, v23, 1.0
	v_mul_f32_e32 v36, v34, v33
	v_fma_f32 v37, -v19, v36, v34
	v_fmac_f32_e32 v36, v37, v33
	v_fma_f32 v19, -v19, v36, v34
	v_div_scale_f32 v34, s[6:7], v22, v22, 1.0
	v_rcp_f32_e32 v37, v34
	v_div_fmas_f32 v19, v19, v33, v36
	v_div_fixup_f32 v23, v19, v23, 1.0
	v_exp_f32_e32 v32, v32
	v_fma_f32 v19, -v34, v37, 1.0
	v_fmac_f32_e32 v37, v19, v37
	v_div_scale_f32 v19, vcc, 1.0, v22, 1.0
	v_mul_f32_e32 v33, v19, v37
	v_fma_f32 v36, -v34, v33, v19
	v_fmac_f32_e32 v33, v36, v37
	v_fma_f32 v19, -v34, v33, v19
	v_div_scale_f32 v34, s[6:7], v31, v31, 1.0
	v_rcp_f32_e32 v36, v34
	v_div_fmas_f32 v19, v19, v37, v33
	v_div_fixup_f32 v22, v19, v22, 1.0
	v_fma_f32 v19, -v34, v36, 1.0
	v_fmac_f32_e32 v36, v19, v36
	v_div_scale_f32 v19, vcc, 1.0, v31, 1.0
	v_mul_f32_e32 v33, v19, v36
	v_fma_f32 v37, -v34, v33, v19
	v_fmac_f32_e32 v33, v37, v36
	v_fma_f32 v19, -v34, v33, v19
	v_div_scale_f32 v34, s[6:7], v30, v30, 1.0
	v_rcp_f32_e32 v37, v34
	v_div_fmas_f32 v19, v19, v36, v33
	v_div_fixup_f32 v31, v19, v31, 1.0
	v_fma_f32 v19, -v34, v37, 1.0
	v_fmac_f32_e32 v37, v19, v37
	v_div_scale_f32 v19, vcc, 1.0, v30, 1.0
	v_mul_f32_e32 v36, v19, v37
	v_fma_f32 v33, -v34, v36, v19
	v_fmac_f32_e32 v36, v33, v37
	v_fma_f32 v19, -v34, v36, v19
	v_div_scale_f32 v34, s[6:7], v25, v25, 1.0
	v_mul_f32_e32 v33, 0xbfb8aa3b, v35
	v_rcp_f32_e32 v35, v34
	v_div_fmas_f32 v19, v19, v37, v36
	v_div_fixup_f32 v30, v19, v30, 1.0
	v_exp_f32_e32 v33, v33
	v_fma_f32 v19, -v34, v35, 1.0
	v_fmac_f32_e32 v35, v19, v35
	v_div_scale_f32 v19, vcc, 1.0, v25, 1.0
	v_mul_f32_e32 v36, v19, v35
	v_fma_f32 v37, -v34, v36, v19
	v_fmac_f32_e32 v36, v37, v35
	v_fma_f32 v19, -v34, v36, v19
	v_div_scale_f32 v34, s[6:7], v24, v24, 1.0
	v_rcp_f32_e32 v37, v34
	v_div_fmas_f32 v19, v19, v35, v36
	v_div_fixup_f32 v25, v19, v25, 1.0
	v_pk_add_f32 v[32:33], v[32:33], 1.0 op_sel_hi:[1,0]
	v_fma_f32 v19, -v34, v37, 1.0
	v_fmac_f32_e32 v37, v19, v37
	v_div_scale_f32 v19, vcc, 1.0, v24, 1.0
	v_mul_f32_e32 v35, v19, v37
	v_fma_f32 v36, -v34, v35, v19
	v_fmac_f32_e32 v35, v36, v37
	v_fma_f32 v19, -v34, v35, v19
	v_div_scale_f32 v34, s[6:7], v33, v33, 1.0
	v_rcp_f32_e32 v36, v34
	v_div_fmas_f32 v19, v19, v37, v35
	v_div_fixup_f32 v24, v19, v24, 1.0
	v_fma_f32 v19, -v34, v36, 1.0
	v_fmac_f32_e32 v36, v19, v36
	v_div_scale_f32 v19, vcc, 1.0, v33, 1.0
	v_mul_f32_e32 v35, v19, v36
	v_fma_f32 v37, -v34, v35, v19
	v_fmac_f32_e32 v35, v37, v36
	v_fma_f32 v19, -v34, v35, v19
	v_div_scale_f32 v34, s[6:7], v32, v32, 1.0
	v_rcp_f32_e32 v37, v34
	v_div_fmas_f32 v19, v19, v36, v35
	v_div_fixup_f32 v33, v19, v33, 1.0
	v_fma_f32 v19, -v34, v37, 1.0
	v_fmac_f32_e32 v37, v19, v37
	v_div_scale_f32 v19, vcc, 1.0, v32, 1.0
	v_mul_f32_e32 v35, v19, v37
	v_fma_f32 v36, -v34, v35, v19
	v_fmac_f32_e32 v35, v36, v37
	v_fma_f32 v19, -v34, v35, v19
	v_div_fmas_f32 v19, v19, v37, v35
	v_div_fixup_f32 v32, v19, v32, 1.0
	v_lshlrev_b32_e32 v34, 16, v26
	v_and_b32_e32 v35, 0xffff0000, v26
	v_lshlrev_b32_e32 v36, 16, v28
	v_and_b32_e32 v37, 0xffff0000, v28
	v_lshlrev_b32_e32 v28, 16, v29
	v_and_b32_e32 v29, 0xffff0000, v29
	v_lshlrev_b32_e32 v26, 16, v27
	v_and_b32_e32 v27, 0xffff0000, v27
	v_pk_fma_f32 v[12:13], v[12:13], v[22:23], v[34:35]
	v_pk_fma_f32 v[22:23], v[10:11], v[32:33], v[28:29]
	v_pk_fma_f32 v[10:11], v[8:9], v[24:25], v[36:37]
	v_add_lshl_u32 v24, v140, v18, 1
	v_pk_fma_f32 v[14:15], v[14:15], v[30:31], v[26:27]
	v_cvt_pk_bf16_f32 v8, v12, v13
	s_nop 0
	v_cvt_pk_bf16_f32 v9, v14, v15
	v_cvt_pk_bf16_f32 v10, v10, v11
	v_cvt_pk_bf16_f32 v11, v22, v23
	buffer_store_dwordx4 v[8:11], v24, s[20:23], 0 offen sc1
	s_nop 0
	s_waitcnt vmcnt(5)
; __device__ __forceinline__ float sigmoidf_(float x) { return 1.0f / (1.0f + __expf(-x)); }
; __device__ __forceinline__ u32x4 pack8(const f32x4 v0, const f32x4 v1) { u32x4 w; w.x = pk2(v0[0], v0[1]); w.y = pk2(v0[2], v0[3]); w.z = pk2(v1[0], v1[1]); w.w = pk2(v1[2], v1[3]); return w; }
; __device__ __forceinline__ void unpack8(const u32x4 w, f32x4& v0, f32x4& v1) { v0 = (f32x4){bflo(w.x), bfhi(w.x), bflo(w.y), bfhi(w.y)}; v1 = (f32x4){bflo(w.z), bfhi(w.z), bflo(w.w), bfhi(w.w)}; }
;     __device__ __forceinline__ void operator()(const f32x4 (&acc)[2][2][4][2], const Unit& u, int wr, int wc, int fr, int fq) const {
;     ...
;                 const int row = row0 + ai * 128 + m * 16;
;                 const bf16_t* rowp = z + (size_t)row * DIN + col0;
; #pragma unroll
;                 for (int bj = 0; bj < 2; ++bj) {
;                     const u32x4 gw = *(const u32x4*)(rowp + O_GA + bj * 128);
;                     f32x4 g0, g1; unpack8(gw, g0, g1);
;                     f32x4 v0, v1;
; #pragma unroll
;                     for (int j = 0; j < 4; ++j) { v0[j] = sigmoidf_(g0[j]) * acc[ai][bj][m][0][j]; v1[j] = sigmoidf_(g1[j]) * acc[ai][bj][m][1][j]; }
;                     const u32x4 mw = *(const u32x4*)(rowp + bj * 128); f32x4 m0, m1; unpack8(mw, m0, m1); v0 += m0; v1 += m1;
;                     __builtin_amdgcn_raw_buffer_store_b128(pack8(v0, v1), rsrc, (unsigned)(((size_t)row * DIN + col0 + bj * 128) * 2), 0, 16  ); }
;             }
;         asm volatile("s_waitcnt vmcnt(0)" ::: "memory");
;         if (fr == 0 && fq == 0) (void)__hip_atomic_fetch_add(ready + 64 * (pm_off + u.pm), 1u, __ATOMIC_RELAXED, __HIP_MEMORY_SCOPE_AGENT);
	v_mov_b32_e32 v8, v200
	v_mov_b32_e32 v9, v201
	v_mov_b32_e32 v10, v202
	v_mov_b32_e32 v11, v203
	v_mov_b32_e32 v12, v204
	v_mov_b32_e32 v13, v205
	v_mov_b32_e32 v14, v206
	v_mov_b32_e32 v15, v207
	v_lshlrev_b32_e32 v18, 16, v9
	v_and_b32_e32 v19, 0xffff0000, v9
	v_lshlrev_b32_e32 v9, 16, v10
	v_lshlrev_b32_e32 v16, 16, v8
	v_and_b32_e32 v17, 0xffff0000, v8
	v_mul_f32_e32 v9, 0xbfb8aa3b, v9
	v_and_b32_e32 v20, 0xffff0000, v10
	v_mul_f32_e32 v8, 0xbfb8aa3b, v16
	v_exp_f32_e32 v10, v9
	v_mul_f32_e32 v9, 0xbfb8aa3b, v17
	v_exp_f32_e32 v8, v8
	v_exp_f32_e32 v9, v9
	v_mul_f32_e32 v17, 0xbfb8aa3b, v19
	v_lshlrev_b32_e32 v21, 16, v11
	v_and_b32_e32 v22, 0xffff0000, v11
	v_pk_add_f32 v[8:9], v[8:9], 1.0 op_sel_hi:[1,0]
	v_mul_f32_e32 v11, 0xbfb8aa3b, v20
	v_div_scale_f32 v19, s[6:7], v9, v9, 1.0
	v_rcp_f32_e32 v20, v19
	v_mul_f32_e32 v16, 0xbfb8aa3b, v18
	v_mul_f32_e32 v18, 0xbfb8aa3b, v21
	v_exp_f32_e32 v16, v16
	v_fma_f32 v21, -v19, v20, 1.0
	v_fmac_f32_e32 v20, v21, v20
	v_div_scale_f32 v21, vcc, 1.0, v9, 1.0
	v_mul_f32_e32 v23, v21, v20
	v_fma_f32 v25, -v19, v23, v21
	v_fmac_f32_e32 v23, v25, v20
	v_fma_f32 v19, -v19, v23, v21
	v_div_scale_f32 v21, s[6:7], v8, v8, 1.0
	v_rcp_f32_e32 v25, v21
	v_div_fmas_f32 v19, v19, v20, v23
	v_exp_f32_e32 v17, v17
	v_div_fixup_f32 v9, v19, v9, 1.0
	v_fma_f32 v19, -v21, v25, 1.0
	v_fmac_f32_e32 v25, v19, v25
	v_div_scale_f32 v19, vcc, 1.0, v8, 1.0
	v_mul_f32_e32 v20, v19, v25
	v_fma_f32 v23, -v21, v20, v19
	v_pk_add_f32 v[16:17], v[16:17], 1.0 op_sel_hi:[1,0]
	v_fmac_f32_e32 v20, v23, v25
	v_fma_f32 v19, -v21, v20, v19
	v_div_scale_f32 v21, s[6:7], v17, v17, 1.0
	v_rcp_f32_e32 v23, v21
	v_div_fmas_f32 v19, v19, v25, v20
	v_div_fixup_f32 v8, v19, v8, 1.0
	v_exp_f32_e32 v11, v11
	v_fma_f32 v19, -v21, v23, 1.0
	v_fmac_f32_e32 v23, v19, v23
	v_div_scale_f32 v19, vcc, 1.0, v17, 1.0
	v_mul_f32_e32 v20, v19, v23
	v_fma_f32 v25, -v21, v20, v19
	v_fmac_f32_e32 v20, v25, v23
	v_fma_f32 v19, -v21, v20, v19
	v_div_scale_f32 v21, s[6:7], v16, v16, 1.0
	v_rcp_f32_e32 v25, v21
	v_div_fmas_f32 v19, v19, v23, v20
	v_div_fixup_f32 v17, v19, v17, 1.0
	v_pk_add_f32 v[10:11], v[10:11], 1.0 op_sel_hi:[1,0]
	v_fma_f32 v19, -v21, v25, 1.0
	v_fmac_f32_e32 v25, v19, v25
	v_div_scale_f32 v19, vcc, 1.0, v16, 1.0
	v_mul_f32_e32 v20, v19, v25
	v_fma_f32 v23, -v21, v20, v19
	v_fmac_f32_e32 v20, v23, v25
	v_fma_f32 v21, -v21, v20, v19
	v_mul_f32_e32 v19, 0xbfb8aa3b, v22
	v_div_scale_f32 v22, s[6:7], v11, v11, 1.0
	v_rcp_f32_e32 v23, v22
	v_div_fmas_f32 v20, v21, v25, v20
	v_div_fixup_f32 v16, v20, v16, 1.0
	v_exp_f32_e32 v18, v18
	v_fma_f32 v20, -v22, v23, 1.0
	v_fmac_f32_e32 v23, v20, v23
	v_div_scale_f32 v20, vcc, 1.0, v11, 1.0
	v_mul_f32_e32 v21, v20, v23
	v_fma_f32 v25, -v22, v21, v20
	v_fmac_f32_e32 v21, v25, v23
	v_fma_f32 v20, -v22, v21, v20
	v_div_scale_f32 v22, s[6:7], v10, v10, 1.0
	v_rcp_f32_e32 v25, v22
	v_div_fmas_f32 v20, v20, v23, v21
	v_exp_f32_e32 v19, v19
	v_div_fixup_f32 v11, v20, v11, 1.0
	v_fma_f32 v20, -v22, v25, 1.0
	v_fmac_f32_e32 v25, v20, v25
	v_div_scale_f32 v20, vcc, 1.0, v10, 1.0
	v_mul_f32_e32 v21, v20, v25
	v_fma_f32 v23, -v22, v21, v20
	v_pk_add_f32 v[18:19], v[18:19], 1.0 op_sel_hi:[1,0]
	v_fmac_f32_e32 v21, v23, v25
	v_fma_f32 v20, -v22, v21, v20
	v_div_scale_f32 v22, s[6:7], v19, v19, 1.0
	v_rcp_f32_e32 v23, v22
	v_div_fmas_f32 v20, v20, v25, v21
	v_div_fixup_f32 v10, v20, v10, 1.0
	v_fma_f32 v20, -v22, v23, 1.0
	v_fmac_f32_e32 v23, v20, v23
	v_div_scale_f32 v20, vcc, 1.0, v19, 1.0
	v_mul_f32_e32 v21, v20, v23
	v_fma_f32 v25, -v22, v21, v20
	v_fmac_f32_e32 v21, v25, v23
	v_fma_f32 v20, -v22, v21, v20
	v_div_scale_f32 v22, s[6:7], v18, v18, 1.0
	v_rcp_f32_e32 v25, v22
	v_div_fmas_f32 v20, v20, v23, v21
	v_div_fixup_f32 v19, v20, v19, 1.0
	v_fma_f32 v20, -v22, v25, 1.0
	v_fmac_f32_e32 v25, v20, v25
	v_div_scale_f32 v20, vcc, 1.0, v18, 1.0
	v_mul_f32_e32 v21, v20, v25
	v_fma_f32 v23, -v22, v21, v20
	v_fmac_f32_e32 v21, v23, v25
	v_fma_f32 v20, -v22, v21, v20
	v_div_fmas_f32 v20, v20, v25, v21
	v_div_fixup_f32 v18, v20, v18, 1.0
	v_lshlrev_b32_e32 v20, 16, v12
	v_and_b32_e32 v21, 0xffff0000, v12
	v_lshlrev_b32_e32 v22, 16, v14
	v_and_b32_e32 v23, 0xffff0000, v14
	v_lshlrev_b32_e32 v14, 16, v15
	v_and_b32_e32 v15, 0xffff0000, v15
	v_lshlrev_b32_e32 v12, 16, v13
	v_and_b32_e32 v13, 0xffff0000, v13
	v_pk_fma_f32 v[4:5], v[4:5], v[8:9], v[20:21]
	v_pk_fma_f32 v[8:9], v[2:3], v[18:19], v[14:15]
	v_pk_fma_f32 v[2:3], v[0:1], v[10:11], v[22:23]
	v_pk_fma_f32 v[6:7], v[6:7], v[16:17], v[12:13]
	v_cvt_pk_bf16_f32 v0, v4, v5
	s_nop 0
	v_cvt_pk_bf16_f32 v1, v6, v7
	v_cvt_pk_bf16_f32 v2, v2, v3
	v_cvt_pk_bf16_f32 v3, v8, v9
	buffer_store_dwordx4 v[0:3], v24, s[20:23], 0 offen offset:256 sc1
	s_waitcnt vmcnt(0)
	s_and_saveexec_b64 s[10:11], s[8:9]
	s_cbranch_execz .LBB0_1856
	s_mov_b64 s[12:13], exec
	v_mbcnt_lo_u32_b32 v0, s12, 0
	v_mbcnt_hi_u32_b32 v0, s13, v0
	v_cmp_eq_u32_e32 vcc, 0, v0
	s_and_b64 s[6:7], exec, vcc
	s_mov_b64 exec, s[6:7]
	s_cbranch_execz .LBB0_1856
	s_lshl_b32 s6, s75, 6
	s_addk_i32 s6, 0x1000
	s_ashr_i32 s7, s6, 31
	s_lshl_b64 s[6:7], s[6:7], 2
	s_add_u32 s6, s28, s6
	s_addc_u32 s7, s29, s7
	s_bcnt1_i32_b64 s12, s[12:13]
	v_mov_b32_e32 v0, s12
	global_atomic_add v131, v0, s[6:7]
	s_branch .LBB0_1856

; #define PG8_STAGE(bufoff, gbase, voff) do { _Pragma("unroll") for (int _i = 0; _i < 2; ++_i) \
;         __builtin_amdgcn_global_load_lds((const unsigned*)((const char*)(gbase) + (voff)[_i]), (LAS unsigned*)(lds + (bufoff) + ldsw + _i * 8192), 16, 0, 0); } while (0)
; #define PG8_LDA(dst, b, h) do { _Pragma("unroll") for (int m = 0; m < 4; ++m) _Pragma("unroll") for (int k = 0; k < 2; ++k) dst[m][k] = *(const LAS bf16x8*)(lds + PG8_SA(b, h) + aoff + m * 2048 + k * 1024); } while (0)
; #define PG8_LDB(dst, b, h) do { _Pragma("unroll") for (int n = 0; n < 2; ++n) _Pragma("unroll") for (int k = 0; k < 2; ++k) dst[n][k] = *(const LAS bf16x8*)(lds + PG8_SB(b, h) + boff + n * 2048 + k * 1024); } while (0)
; #define PG8_MMA(ai, bj, At, Bt) do { __builtin_amdgcn_s_setprio(1); _Pragma("unroll") for (int m = 0; m < 4; ++m) _Pragma("unroll") for (int n = 0; n < 2; ++n) _Pragma("unroll") for (int k = 0; k < 2; ++k) \
;         acc[ai][bj][m][n] = __builtin_amdgcn_mfma_f32_16x16x32_bf16(Bt[n][k], At[m][k], acc[ai][bj][m][n], 0, 0, 0); __builtin_amdgcn_s_setprio(0); } while (0)
; #define PG8_WAIT_V(n) asm volatile("s_waitcnt vmcnt(" #n ")" ::: "memory")
; #define PG8_WAIT_L(n) asm volatile("s_waitcnt lgkmcnt(" #n ")" ::: "memory")
; #define PG8_BAR __builtin_amdgcn_s_barrier()
; #define PG8_SCHED __builtin_amdgcn_sched_barrier(0)
;     ...
;             PG8_LDB(B0, 0, 0); PG8_SCHED; PG8_LDA(At, 0, 0); PG8_STAGE(PG8_SA(1, 1), a1 + hA, voffA);
;             PG8_WAIT_L(8); PG8_BAR; PG8_WAIT_L(0); PG8_MMA(0, 0, At, B0); PG8_BAR; PG8_SCHED;
;             PG8_LDB(B1, 0, 1); PG8_STAGE(PG8_SB(0, 0), b2, voffB);
;             PG8_BAR; PG8_WAIT_L(0); PG8_MMA(0, 1, At, B1); PG8_BAR;
;             PG8_LDA(At, 0, 1); PG8_STAGE(PG8_SA(0, 0), a2, voffA);
;             PG8_BAR; PG8_WAIT_L(0); PG8_MMA(1, 0, At, B0); PG8_BAR; PG8_SCHED;
;             PG8_STAGE(PG8_SB(0, 1), b2 + hB, voffB);
;             PG8_WAIT_V(6); PG8_BAR; PG8_MMA(1, 1, At, B1); PG8_BAR;
.LBB0_2099:
	ds_read_b128 v[156:159], v151
	ds_read_b128 v[160:163], v151 offset:1024
	ds_read_b128 v[170:173], v151 offset:2048
	ds_read_b128 v[174:177], v151 offset:3072
	s_add_u32 s38, s36, 0xfffc0080
	s_addc_u32 s39, s37, -1
	s_cmp_eq_u32 s71, 12
	s_cselect_b32 s41, s25, s39
	s_cselect_b32 s40, s44, s38
	s_cselect_b32 s39, s35, s70
	s_cselect_b32 s38, s45, s69
	v_lshl_add_u64 v[146:147], s[36:37], 0, v[138:139]
	s_add_i32 m0, s53, 0xc000
	ds_read_b128 v[178:181], v152
	ds_read_b128 v[182:185], v152 offset:1024
	ds_read_b128 v[186:189], v152 offset:2048
	ds_read_b128 v[190:193], v152 offset:3072
	ds_read_b128 v[194:197], v152 offset:4096
	ds_read_b128 v[198:201], v152 offset:5120
	ds_read_b128 v[202:205], v152 offset:6144
	ds_read_b128 v[206:209], v152 offset:7168
	global_load_lds_dwordx4 v[146:147], off
	v_lshl_add_u64 v[146:147], s[36:37], 0, v[136:137]
	s_add_i32 m0, s53, 0xe000
	s_nop 0
	global_load_lds_dwordx4 v[146:147], off
	s_waitcnt lgkmcnt(8)
	s_barrier
	s_waitcnt lgkmcnt(0)
	s_setprio 1
	s_waitcnt lgkmcnt(0)
	v_mfma_f32_16x16x32_bf16 v[124:127], v[156:159], v[178:181], v[124:127]
	v_mfma_f32_16x16x32_bf16 v[120:123], v[170:173], v[178:181], v[120:123]
	v_mfma_f32_16x16x32_bf16 v[108:111], v[156:159], v[186:189], v[108:111]
	v_mfma_f32_16x16x32_bf16 v[104:107], v[170:173], v[186:189], v[104:107]
	v_mfma_f32_16x16x32_bf16 v[92:95], v[156:159], v[194:197], v[92:95]
	v_mfma_f32_16x16x32_bf16 v[88:91], v[170:173], v[194:197], v[88:91]
	v_mfma_f32_16x16x32_bf16 v[76:79], v[156:159], v[202:205], v[76:79]
	v_mfma_f32_16x16x32_bf16 v[72:75], v[170:173], v[202:205], v[72:75]
	v_mfma_f32_16x16x32_bf16 v[124:127], v[160:163], v[182:185], v[124:127]
	v_mfma_f32_16x16x32_bf16 v[120:123], v[174:177], v[182:185], v[120:123]
	v_mfma_f32_16x16x32_bf16 v[108:111], v[160:163], v[190:193], v[108:111]
	v_mfma_f32_16x16x32_bf16 v[104:107], v[174:177], v[190:193], v[104:107]
	v_mfma_f32_16x16x32_bf16 v[92:95], v[160:163], v[198:201], v[92:95]
	v_mfma_f32_16x16x32_bf16 v[88:91], v[174:177], v[198:201], v[88:91]
	v_mfma_f32_16x16x32_bf16 v[76:79], v[160:163], v[206:209], v[76:79]
	v_mfma_f32_16x16x32_bf16 v[72:75], v[174:177], v[206:209], v[72:75]
	s_setprio 0
	s_barrier
	s_add_i32 s72, s61, s52
	v_lshl_add_u64 v[146:147], s[38:39], 0, v[130:131]
	s_mov_b32 m0, s72
	ds_read_b128 v[210:213], v153
	ds_read_b128 v[214:217], v153 offset:1024
	ds_read_b128 v[218:221], v153 offset:2048
	ds_read_b128 v[222:225], v153 offset:3072
	global_load_lds_dwordx4 v[146:147], off
	v_lshl_add_u64 v[164:165], s[38:39], 0, v[134:135]
	s_add_i32 m0, s72, 0x2000
	s_nop 0
	global_load_lds_dwordx4 v[164:165], off
	s_barrier
	s_waitcnt lgkmcnt(0)
	s_setprio 1
	s_waitcnt lgkmcnt(0)
	v_mfma_f32_16x16x32_bf16 v[116:119], v[210:213], v[178:181], v[116:119]
	v_mfma_f32_16x16x32_bf16 v[112:115], v[218:221], v[178:181], v[112:115]
	v_mfma_f32_16x16x32_bf16 v[100:103], v[210:213], v[186:189], v[100:103]
	v_mfma_f32_16x16x32_bf16 v[96:99], v[218:221], v[186:189], v[96:99]
	v_mfma_f32_16x16x32_bf16 v[84:87], v[210:213], v[194:197], v[84:87]
	v_mfma_f32_16x16x32_bf16 v[80:83], v[218:221], v[194:197], v[80:83]
	v_mfma_f32_16x16x32_bf16 v[68:71], v[210:213], v[202:205], v[68:71]
	v_mfma_f32_16x16x32_bf16 v[64:67], v[218:221], v[202:205], v[64:67]
	v_mfma_f32_16x16x32_bf16 v[116:119], v[214:217], v[182:185], v[116:119]
	v_mfma_f32_16x16x32_bf16 v[112:115], v[222:225], v[182:185], v[112:115]
	v_mfma_f32_16x16x32_bf16 v[100:103], v[214:217], v[190:193], v[100:103]
	v_mfma_f32_16x16x32_bf16 v[96:99], v[222:225], v[190:193], v[96:99]
	v_mfma_f32_16x16x32_bf16 v[84:87], v[214:217], v[198:201], v[84:87]
	v_mfma_f32_16x16x32_bf16 v[80:83], v[222:225], v[198:201], v[80:83]
	v_mfma_f32_16x16x32_bf16 v[68:71], v[214:217], v[206:209], v[68:71]
	v_mfma_f32_16x16x32_bf16 v[64:67], v[222:225], v[206:209], v[64:67]
	s_setprio 0
	s_mov_b32 m0, s53
	v_lshl_add_u64 v[226:227], s[40:41], 0, v[128:129]
	s_barrier
	ds_read_b128 v[178:181], v152 offset:16384
	ds_read_b128 v[182:185], v152 offset:17408
	ds_read_b128 v[186:189], v152 offset:18432
	ds_read_b128 v[190:193], v152 offset:19456
	ds_read_b128 v[194:197], v152 offset:20480
	ds_read_b128 v[198:201], v152 offset:21504
	ds_read_b128 v[202:205], v152 offset:22528
	ds_read_b128 v[206:209], v152 offset:23552
	global_load_lds_dwordx4 v[226:227], off
	v_lshl_add_u64 v[228:229], s[40:41], 0, v[132:133]
	s_mov_b32 m0, s54
	s_nop 0
	global_load_lds_dwordx4 v[228:229], off
	s_barrier
	s_waitcnt lgkmcnt(0)
	s_setprio 1
	s_waitcnt lgkmcnt(0)
	v_mfma_f32_16x16x32_bf16 v[60:63], v[156:159], v[178:181], v[60:63]
	v_mfma_f32_16x16x32_bf16 v[56:59], v[170:173], v[178:181], v[56:59]
	v_mfma_f32_16x16x32_bf16 v[44:47], v[156:159], v[186:189], v[44:47]
	v_mfma_f32_16x16x32_bf16 v[40:43], v[170:173], v[186:189], v[40:43]
	v_mfma_f32_16x16x32_bf16 v[28:31], v[156:159], v[194:197], v[28:31]
	v_mfma_f32_16x16x32_bf16 v[24:27], v[170:173], v[194:197], v[24:27]
	v_mfma_f32_16x16x32_bf16 v[12:15], v[156:159], v[202:205], v[12:15]
	v_mfma_f32_16x16x32_bf16 v[8:11], v[170:173], v[202:205], v[8:11]
	v_mfma_f32_16x16x32_bf16 v[60:63], v[160:163], v[182:185], v[60:63]
	v_mfma_f32_16x16x32_bf16 v[56:59], v[174:177], v[182:185], v[56:59]
	v_mfma_f32_16x16x32_bf16 v[44:47], v[160:163], v[190:193], v[44:47]
	v_mfma_f32_16x16x32_bf16 v[40:43], v[174:177], v[190:193], v[40:43]
	v_mfma_f32_16x16x32_bf16 v[28:31], v[160:163], v[198:201], v[28:31]
	v_mfma_f32_16x16x32_bf16 v[24:27], v[174:177], v[198:201], v[24:27]
	v_mfma_f32_16x16x32_bf16 v[12:15], v[160:163], v[206:209], v[12:15]
	v_mfma_f32_16x16x32_bf16 v[8:11], v[174:177], v[206:209], v[8:11]
	s_setprio 0
	s_barrier
; #define PG8_STAGE(bufoff, gbase, voff) do { _Pragma("unroll") for (int _i = 0; _i < 2; ++_i) \
;         __builtin_amdgcn_global_load_lds((const unsigned*)((const char*)(gbase) + (voff)[_i]), (LAS unsigned*)(lds + (bufoff) + ldsw + _i * 8192), 16, 0, 0); } while (0)
; #define PG8_LDA(dst, b, h) do { _Pragma("unroll") for (int m = 0; m < 4; ++m) _Pragma("unroll") for (int k = 0; k < 2; ++k) dst[m][k] = *(const LAS bf16x8*)(lds + PG8_SA(b, h) + aoff + m * 2048 + k * 1024); } while (0)
; #define PG8_LDB(dst, b, h) do { _Pragma("unroll") for (int n = 0; n < 2; ++n) _Pragma("unroll") for (int k = 0; k < 2; ++k) dst[n][k] = *(const LAS bf16x8*)(lds + PG8_SB(b, h) + boff + n * 2048 + k * 1024); } while (0)
; #define PG8_MMA(ai, bj, At, Bt) do { __builtin_amdgcn_s_setprio(1); _Pragma("unroll") for (int m = 0; m < 4; ++m) _Pragma("unroll") for (int n = 0; n < 2; ++n) _Pragma("unroll") for (int k = 0; k < 2; ++k) \
;         acc[ai][bj][m][n] = __builtin_amdgcn_mfma_f32_16x16x32_bf16(Bt[n][k], At[m][k], acc[ai][bj][m][n], 0, 0, 0); __builtin_amdgcn_s_setprio(0); } while (0)
; #define PG8_WAIT_V(n) asm volatile("s_waitcnt vmcnt(" #n ")" ::: "memory")
; #define PG8_WAIT_L(n) asm volatile("s_waitcnt lgkmcnt(" #n ")" ::: "memory")
; #define PG8_BAR __builtin_amdgcn_s_barrier()
; #define PG8_SCHED __builtin_amdgcn_sched_barrier(0)
;     ...
;             PG8_STAGE(PG8_SB(0, 1), b2 + hB, voffB);
;             PG8_WAIT_V(6); PG8_BAR; PG8_MMA(1, 1, At, B1); PG8_BAR;
;             PG8_LDB(B0, 1, 0); PG8_SCHED; PG8_LDA(At, 1, 0); PG8_STAGE(PG8_SA(0, 1), a2 + hA, voffA);
;             PG8_WAIT_L(8); PG8_BAR; PG8_WAIT_L(0); PG8_MMA(0, 0, At, B0); PG8_BAR; PG8_SCHED;
;             PG8_LDB(B1, 1, 1); PG8_STAGE(PG8_SB(1, 0), b3, voffB);
;             PG8_BAR; PG8_WAIT_L(0); PG8_MMA(0, 1, At, B1); PG8_BAR;
;             PG8_LDA(At, 1, 1); PG8_STAGE(PG8_SA(1, 0), a3, voffA);
;             PG8_BAR; PG8_WAIT_L(0); PG8_MMA(1, 0, At, B0); PG8_BAR; PG8_SCHED;
	s_add_u32 s72, s38, 0x40000
	s_addc_u32 s73, s39, 0
	s_add_i32 s74, s62, s52
	v_lshl_add_u64 v[156:157], s[72:73], 0, v[130:131]
	s_mov_b32 m0, s74
	s_nop 0
	global_load_lds_dwordx4 v[156:157], off
	v_lshl_add_u64 v[156:157], s[72:73], 0, v[134:135]
	s_add_i32 m0, s74, 0x2000
	s_nop 0
	global_load_lds_dwordx4 v[156:157], off
	s_waitcnt vmcnt(6)
	s_barrier
	s_setprio 1
	v_mfma_f32_16x16x32_bf16 v[52:55], v[210:213], v[178:181], v[52:55]
	v_mfma_f32_16x16x32_bf16 v[48:51], v[218:221], v[178:181], v[48:51]
	v_mfma_f32_16x16x32_bf16 v[36:39], v[210:213], v[186:189], v[36:39]
	v_mfma_f32_16x16x32_bf16 v[32:35], v[218:221], v[186:189], v[32:35]
	v_mfma_f32_16x16x32_bf16 v[20:23], v[210:213], v[194:197], v[20:23]
	v_mfma_f32_16x16x32_bf16 v[16:19], v[218:221], v[194:197], v[16:19]
	v_mfma_f32_16x16x32_bf16 v[4:7], v[210:213], v[202:205], v[4:7]
	v_mfma_f32_16x16x32_bf16 v[0:3], v[218:221], v[202:205], v[0:3]
	v_mfma_f32_16x16x32_bf16 v[52:55], v[214:217], v[182:185], v[52:55]
	v_mfma_f32_16x16x32_bf16 v[48:51], v[222:225], v[182:185], v[48:51]
	v_mfma_f32_16x16x32_bf16 v[36:39], v[214:217], v[190:193], v[36:39]
	v_mfma_f32_16x16x32_bf16 v[32:35], v[222:225], v[190:193], v[32:35]
	v_mfma_f32_16x16x32_bf16 v[20:23], v[214:217], v[198:201], v[20:23]
	v_mfma_f32_16x16x32_bf16 v[16:19], v[222:225], v[198:201], v[16:19]
	v_mfma_f32_16x16x32_bf16 v[4:7], v[214:217], v[206:209], v[4:7]
	v_mfma_f32_16x16x32_bf16 v[0:3], v[222:225], v[206:209], v[0:3]
	s_setprio 0
	s_add_i32 s72, 0, 0x18000
	v_add_u32_e32 v155, s72, v149
	s_barrier
	ds_read_b128 v[156:159], v155
	ds_read_b128 v[160:163], v155 offset:1024
	ds_read_b128 v[170:173], v155 offset:2048
	ds_read_b128 v[174:177], v155 offset:3072
	s_add_u32 s40, s40, 0x40000
	s_addc_u32 s41, s41, 0
	s_mov_b32 m0, s55
	v_lshl_add_u64 v[210:211], s[40:41], 0, v[128:129]
	ds_read_b128 v[178:181], v152 offset:32768
	ds_read_b128 v[182:185], v152 offset:33792
	ds_read_b128 v[186:189], v152 offset:34816
	ds_read_b128 v[190:193], v152 offset:35840
	ds_read_b128 v[194:197], v152 offset:36864
	ds_read_b128 v[198:201], v152 offset:37888
	ds_read_b128 v[202:205], v152 offset:38912
	ds_read_b128 v[206:209], v152 offset:39936
	global_load_lds_dwordx4 v[210:211], off
	v_lshl_add_u64 v[210:211], s[40:41], 0, v[132:133]
	s_mov_b32 m0, s56
	s_nop 0
	global_load_lds_dwordx4 v[210:211], off
	s_waitcnt lgkmcnt(8)
	s_barrier
	s_waitcnt lgkmcnt(0)
	s_setprio 1
	s_waitcnt lgkmcnt(0)
	v_mfma_f32_16x16x32_bf16 v[124:127], v[156:159], v[178:181], v[124:127]
	v_mfma_f32_16x16x32_bf16 v[120:123], v[170:173], v[178:181], v[120:123]
	v_mfma_f32_16x16x32_bf16 v[108:111], v[156:159], v[186:189], v[108:111]
	v_mfma_f32_16x16x32_bf16 v[104:107], v[170:173], v[186:189], v[104:107]
	v_mfma_f32_16x16x32_bf16 v[92:95], v[156:159], v[194:197], v[92:95]
	v_mfma_f32_16x16x32_bf16 v[88:91], v[170:173], v[194:197], v[88:91]
	v_mfma_f32_16x16x32_bf16 v[76:79], v[156:159], v[202:205], v[76:79]
	v_mfma_f32_16x16x32_bf16 v[72:75], v[170:173], v[202:205], v[72:75]
	v_mfma_f32_16x16x32_bf16 v[124:127], v[160:163], v[182:185], v[124:127]
	v_mfma_f32_16x16x32_bf16 v[120:123], v[174:177], v[182:185], v[120:123]
	v_mfma_f32_16x16x32_bf16 v[108:111], v[160:163], v[190:193], v[108:111]
	v_mfma_f32_16x16x32_bf16 v[104:107], v[174:177], v[190:193], v[104:107]
	v_mfma_f32_16x16x32_bf16 v[92:95], v[160:163], v[198:201], v[92:95]
	v_mfma_f32_16x16x32_bf16 v[88:91], v[174:177], v[198:201], v[88:91]
	v_mfma_f32_16x16x32_bf16 v[76:79], v[160:163], v[206:209], v[76:79]
	v_mfma_f32_16x16x32_bf16 v[72:75], v[174:177], v[206:209], v[72:75]
	s_setprio 0
	s_barrier
	s_add_i32 s40, 0, 0x1c000
	s_add_i32 s41, s72, s52
	v_add_u32_e32 v155, s40, v149
	v_lshl_add_u64 v[146:147], v[146:147], 0, s[26:27]
	s_mov_b32 m0, s41
	ds_read_b128 v[210:213], v155
	ds_read_b128 v[214:217], v155 offset:1024
	ds_read_b128 v[218:221], v155 offset:2048
	ds_read_b128 v[222:225], v155 offset:3072
	global_load_lds_dwordx4 v[146:147], off
	v_lshl_add_u64 v[146:147], v[164:165], 0, s[26:27]
	s_add_i32 m0, s41, 0x2000
	s_nop 0
	global_load_lds_dwordx4 v[146:147], off
	s_barrier
	s_waitcnt lgkmcnt(0)
	s_setprio 1
	s_waitcnt lgkmcnt(0)
	v_mfma_f32_16x16x32_bf16 v[116:119], v[210:213], v[178:181], v[116:119]
	v_mfma_f32_16x16x32_bf16 v[112:115], v[218:221], v[178:181], v[112:115]
	v_mfma_f32_16x16x32_bf16 v[100:103], v[210:213], v[186:189], v[100:103]
	v_mfma_f32_16x16x32_bf16 v[96:99], v[218:221], v[186:189], v[96:99]
	v_mfma_f32_16x16x32_bf16 v[84:87], v[210:213], v[194:197], v[84:87]
	v_mfma_f32_16x16x32_bf16 v[80:83], v[218:221], v[194:197], v[80:83]
	v_mfma_f32_16x16x32_bf16 v[68:71], v[210:213], v[202:205], v[68:71]
	v_mfma_f32_16x16x32_bf16 v[64:67], v[218:221], v[202:205], v[64:67]
	v_mfma_f32_16x16x32_bf16 v[116:119], v[214:217], v[182:185], v[116:119]
	v_mfma_f32_16x16x32_bf16 v[112:115], v[222:225], v[182:185], v[112:115]
	v_mfma_f32_16x16x32_bf16 v[100:103], v[214:217], v[190:193], v[100:103]
	v_mfma_f32_16x16x32_bf16 v[96:99], v[222:225], v[190:193], v[96:99]
	v_mfma_f32_16x16x32_bf16 v[84:87], v[214:217], v[198:201], v[84:87]
	v_mfma_f32_16x16x32_bf16 v[80:83], v[222:225], v[198:201], v[80:83]
	v_mfma_f32_16x16x32_bf16 v[68:71], v[214:217], v[206:209], v[68:71]
	v_mfma_f32_16x16x32_bf16 v[64:67], v[222:225], v[206:209], v[64:67]
	s_setprio 0
	s_mov_b32 m0, s58
	v_lshl_add_u64 v[146:147], v[226:227], 0, s[26:27]
	s_barrier
	ds_read_b128 v[178:181], v152 offset:49152
	ds_read_b128 v[182:185], v152 offset:50176
	ds_read_b128 v[186:189], v152 offset:51200
	ds_read_b128 v[190:193], v152 offset:52224
	ds_read_b128 v[194:197], v152 offset:53248
	ds_read_b128 v[198:201], v152 offset:54272
	ds_read_b128 v[202:205], v152 offset:55296
	ds_read_b128 v[206:209], v152 offset:56320
	global_load_lds_dwordx4 v[146:147], off
	v_lshl_add_u64 v[146:147], v[228:229], 0, s[26:27]
	s_mov_b32 m0, s59
	s_nop 0
	global_load_lds_dwordx4 v[146:147], off
	s_barrier
; #define PG8_STAGE(bufoff, gbase, voff) do { _Pragma("unroll") for (int _i = 0; _i < 2; ++_i) \
;         __builtin_amdgcn_global_load_lds((const unsigned*)((const char*)(gbase) + (voff)[_i]), (LAS unsigned*)(lds + (bufoff) + ldsw + _i * 8192), 16, 0, 0); } while (0)
; #define PG8_LDA(dst, b, h) do { _Pragma("unroll") for (int m = 0; m < 4; ++m) _Pragma("unroll") for (int k = 0; k < 2; ++k) dst[m][k] = *(const LAS bf16x8*)(lds + PG8_SA(b, h) + aoff + m * 2048 + k * 1024); } while (0)
; #define PG8_LDB(dst, b, h) do { _Pragma("unroll") for (int n = 0; n < 2; ++n) _Pragma("unroll") for (int k = 0; k < 2; ++k) dst[n][k] = *(const LAS bf16x8*)(lds + PG8_SB(b, h) + boff + n * 2048 + k * 1024); } while (0)
; #define PG8_MMA(ai, bj, At, Bt) do { __builtin_amdgcn_s_setprio(1); _Pragma("unroll") for (int m = 0; m < 4; ++m) _Pragma("unroll") for (int n = 0; n < 2; ++n) _Pragma("unroll") for (int k = 0; k < 2; ++k) \
;         acc[ai][bj][m][n] = __builtin_amdgcn_mfma_f32_16x16x32_bf16(Bt[n][k], At[m][k], acc[ai][bj][m][n], 0, 0, 0); __builtin_amdgcn_s_setprio(0); } while (0)
; #define PG8_WAIT_V(n) asm volatile("s_waitcnt vmcnt(" #n ")" ::: "memory")
; #define PG8_WAIT_L(n) asm volatile("s_waitcnt lgkmcnt(" #n ")" ::: "memory")
; #define PG8_BAR __builtin_amdgcn_s_barrier()
; #define PG8_SCHED __builtin_amdgcn_sched_barrier(0)
;     ...
;             PG8_WAIT_L(8); PG8_BAR; PG8_WAIT_L(0); PG8_MMA(0, 0, At, B0); PG8_BAR; PG8_SCHED;
;             PG8_LDB(B1, 1, 1); PG8_STAGE(PG8_SB(1, 0), b3, voffB);
;             PG8_BAR; PG8_WAIT_L(0); PG8_MMA(0, 1, At, B1); PG8_BAR;
;             PG8_LDA(At, 1, 1); PG8_STAGE(PG8_SA(1, 0), a3, voffA);
;             PG8_BAR; PG8_WAIT_L(0); PG8_MMA(1, 0, At, B0); PG8_BAR; PG8_SCHED;
;             PG8_STAGE(PG8_SB(1, 1), b3 + hB, voffB);
;             PG8_WAIT_V(6); PG8_BAR; PG8_MMA(1, 1, At, B1); PG8_BAR;
; __device__ __forceinline__ float row_rstd(const float* ssq, int row) {
;     const f32x4* p = (const f32x4*)(ssq + (size_t)row * 16);
;     const f32x4 a = p[0], b = p[1], c = p[2], d = p[3];
;     const float s = ((a[0] + a[1]) + (a[2] + a[3])) + ((b[0] + b[1]) + (b[2] + b[3])) + ((c[0] + c[1]) + (c[2] + c[3])) + ((d[0] + d[1]) + (d[2] + d[3]));
;     return rsqrtf(s * (1.0f / 1024.0f) + 1e-6f);
	s_waitcnt lgkmcnt(0)
	s_setprio 1
	s_waitcnt lgkmcnt(0)
	v_mfma_f32_16x16x32_bf16 v[60:63], v[156:159], v[178:181], v[60:63]
	v_mfma_f32_16x16x32_bf16 v[56:59], v[170:173], v[178:181], v[56:59]
	v_mfma_f32_16x16x32_bf16 v[44:47], v[156:159], v[186:189], v[44:47]
	v_mfma_f32_16x16x32_bf16 v[40:43], v[170:173], v[186:189], v[40:43]
	v_mfma_f32_16x16x32_bf16 v[28:31], v[156:159], v[194:197], v[28:31]
	v_mfma_f32_16x16x32_bf16 v[24:27], v[170:173], v[194:197], v[24:27]
	v_mfma_f32_16x16x32_bf16 v[12:15], v[156:159], v[202:205], v[12:15]
	v_mfma_f32_16x16x32_bf16 v[8:11], v[170:173], v[202:205], v[8:11]
	v_mfma_f32_16x16x32_bf16 v[60:63], v[160:163], v[182:185], v[60:63]
	v_mfma_f32_16x16x32_bf16 v[56:59], v[174:177], v[182:185], v[56:59]
	v_mfma_f32_16x16x32_bf16 v[44:47], v[160:163], v[190:193], v[44:47]
	v_mfma_f32_16x16x32_bf16 v[40:43], v[174:177], v[190:193], v[40:43]
	v_mfma_f32_16x16x32_bf16 v[28:31], v[160:163], v[198:201], v[28:31]
	v_mfma_f32_16x16x32_bf16 v[24:27], v[174:177], v[198:201], v[24:27]
	v_mfma_f32_16x16x32_bf16 v[12:15], v[160:163], v[206:209], v[12:15]
	v_mfma_f32_16x16x32_bf16 v[8:11], v[174:177], v[206:209], v[8:11]
	s_setprio 0
	s_barrier
	s_add_u32 s38, s38, 0x40080
	s_addc_u32 s39, s39, 0
	s_add_i32 s40, s40, s52
	v_lshl_add_u64 v[146:147], s[38:39], 0, v[130:131]
	s_mov_b32 m0, s40
	s_nop 0
	global_load_lds_dwordx4 v[146:147], off
	v_lshl_add_u64 v[146:147], s[38:39], 0, v[134:135]
	s_add_i32 m0, s40, 0x2000
	s_nop 0
	global_load_lds_dwordx4 v[146:147], off
	s_waitcnt vmcnt(6)
	s_barrier
	s_setprio 1
	v_mfma_f32_16x16x32_bf16 v[52:55], v[210:213], v[178:181], v[52:55]
	v_mfma_f32_16x16x32_bf16 v[48:51], v[218:221], v[178:181], v[48:51]
	v_mfma_f32_16x16x32_bf16 v[36:39], v[210:213], v[186:189], v[36:39]
	v_mfma_f32_16x16x32_bf16 v[32:35], v[218:221], v[186:189], v[32:35]
	v_mfma_f32_16x16x32_bf16 v[20:23], v[210:213], v[194:197], v[20:23]
	v_mfma_f32_16x16x32_bf16 v[16:19], v[218:221], v[194:197], v[16:19]
	v_mfma_f32_16x16x32_bf16 v[4:7], v[210:213], v[202:205], v[4:7]
	v_mfma_f32_16x16x32_bf16 v[0:3], v[218:221], v[202:205], v[0:3]
	v_mfma_f32_16x16x32_bf16 v[52:55], v[214:217], v[182:185], v[52:55]
	v_mfma_f32_16x16x32_bf16 v[48:51], v[222:225], v[182:185], v[48:51]
	v_mfma_f32_16x16x32_bf16 v[36:39], v[214:217], v[190:193], v[36:39]
	v_mfma_f32_16x16x32_bf16 v[32:35], v[222:225], v[190:193], v[32:35]
	v_mfma_f32_16x16x32_bf16 v[20:23], v[214:217], v[198:201], v[20:23]
	v_mfma_f32_16x16x32_bf16 v[16:19], v[222:225], v[198:201], v[16:19]
	v_mfma_f32_16x16x32_bf16 v[4:7], v[214:217], v[206:209], v[4:7]
	v_mfma_f32_16x16x32_bf16 v[0:3], v[222:225], v[206:209], v[0:3]
	s_setprio 0
	s_add_i32 s71, s71, 2
	s_add_u32 s69, s69, 0x100
	s_addc_u32 s70, s70, 0
	s_add_u32 s36, s36, 0x100
	s_addc_u32 s37, s37, 0
	s_cmp_gt_u32 s71, 13
	s_barrier
	s_cbranch_scc0 .LBB0_2099
	v_lshl_add_u32 v146, s68, 8, v148
	v_ashrrev_i32_e32 v147, 31, v146
	v_lshlrev_b64 v[156:157], 6, v[146:147]
	v_lshl_add_u64 v[164:165], s[22:23], 0, v[156:157]
	v_subrev_u32_e32 v180, s22, v164
	v_add_u32_e32 v181, 0x0, v180
	global_load_dwordx4 v[182:185], v181, s[22:23]
	v_add_u32_e32 v181, 0x10, v180
	global_load_dwordx4 v[186:189], v181, s[22:23]
	v_add_u32_e32 v181, 0x20, v180
	global_load_dwordx4 v[190:193], v181, s[22:23]
	v_add_u32_e32 v181, 0x30, v180
	global_load_dwordx4 v[194:197], v181, s[22:23]
	v_add_u32_e32 v181, 0x400, v180
	global_load_dwordx4 v[198:201], v181, s[22:23]
	v_add_u32_e32 v181, 0x410, v180
	global_load_dwordx4 v[202:205], v181, s[22:23]
	v_add_u32_e32 v181, 0x420, v180
	global_load_dwordx4 v[206:209], v181, s[22:23]
	v_add_u32_e32 v181, 0x430, v180
	global_load_dwordx4 v[210:213], v181, s[22:23]
	v_add_u32_e32 v181, 0x800, v180
	global_load_dwordx4 v[214:217], v181, s[22:23]
	v_add_u32_e32 v181, 0x810, v180
	global_load_dwordx4 v[218:221], v181, s[22:23]
	v_add_u32_e32 v181, 0x820, v180
	global_load_dwordx4 v[222:225], v181, s[22:23]
	v_add_u32_e32 v181, 0x830, v180
	global_load_dwordx4 v[232:235], v181, s[22:23]
	v_add_u32_e32 v181, 0xc00, v180
	global_load_dwordx4 v[236:239], v181, s[22:23]
	v_add_u32_e32 v181, 0xc10, v180
	global_load_dwordx4 v[240:243], v181, s[22:23]
	v_add_u32_e32 v181, 0xc20, v180
	global_load_dwordx4 v[244:247], v181, s[22:23]
	v_add_u32_e32 v181, 0xc30, v180
	global_load_dwordx4 v[248:251], v181, s[22:23]
	v_or_b32_e32 v164, 16, v146
	v_lshl_or_b32 v147, s33, 9, v150
	v_ashrrev_i32_e32 v165, 31, v164
	v_lshl_add_u32 v155, v146, 13, v147
	s_waitcnt vmcnt(12)
; __device__ __forceinline__ u32x4 pack8(const f32x4 v0, const f32x4 v1) { u32x4 w; w.x = pk2(v0[0], v0[1]); w.y = pk2(v0[2], v0[3]); w.z = pk2(v1[0], v1[1]); w.w = pk2(v1[2], v1[3]); return w; }
; __device__ __forceinline__ float row_rstd(const float* ssq, int row) {
;     const f32x4* p = (const f32x4*)(ssq + (size_t)row * 16);
;     const f32x4 a = p[0], b = p[1], c = p[2], d = p[3];
;     const float s = ((a[0] + a[1]) + (a[2] + a[3])) + ((b[0] + b[1]) + (b[2] + b[3])) + ((c[0] + c[1]) + (c[2] + c[3])) + ((d[0] + d[1]) + (d[2] + d[3]));
;     return rsqrtf(s * (1.0f / 1024.0f) + 1e-6f);
;     __device__ __forceinline__ void operator()(const f32x4 (&acc)[2][2][4][2], const Unit& u, int wr, int wc, int fr, int fq) const {
;     ...
;         const int row0 = row_off + u.pm * 256 + wr * 64 + fr, col0 = u.pn * 256 + wc * 32 + 8 * fq;
; #pragma unroll
;         for (int ai = 0; ai < 2; ++ai)
; #pragma unroll
;             for (int m = 0; m < 4; ++m) {
;                 const int row = row0 + ai * 128 + m * 16; const float rs = row_rstd(ssq, row);
; #pragma unroll
;                 for (int bj = 0; bj < 2; ++bj) { f32x4 v0 = acc[ai][bj][m][0] * rs, v1 = acc[ai][bj][m][1] * rs;
; #pragma unroll
;                     for (int j = 0; j < 4; ++j) { const float a = fmaxf(v0[j], 0.f), b = fmaxf(v1[j], 0.f); v0[j] = a * a; v1[j] = b * b; }
;                     __builtin_amdgcn_raw_buffer_store_b128(pack8(v0, v1), rsrc, (unsigned)(((size_t)row * DFF + col0 + bj * 128) * 2), 0, 16  ); }
	v_mov_b32_e32 v156, v182
	v_mov_b32_e32 v157, v183
	v_mov_b32_e32 v158, v184
	v_mov_b32_e32 v159, v185
	v_mov_b32_e32 v160, v186
	v_mov_b32_e32 v161, v187
	v_mov_b32_e32 v162, v188
	v_mov_b32_e32 v163, v189
	v_mov_b32_e32 v170, v190
	v_mov_b32_e32 v171, v191
	v_mov_b32_e32 v172, v192
	v_mov_b32_e32 v173, v193
	v_mov_b32_e32 v174, v194
	v_mov_b32_e32 v175, v195
	v_mov_b32_e32 v176, v196
	v_mov_b32_e32 v177, v197
	v_add_u32_e32 v181, 0x2000, v180
	global_load_dwordx4 v[182:185], v181, s[22:23]
	v_add_u32_e32 v181, 0x2010, v180
	global_load_dwordx4 v[186:189], v181, s[22:23]
	v_add_u32_e32 v181, 0x2020, v180
	global_load_dwordx4 v[190:193], v181, s[22:23]
	v_add_u32_e32 v181, 0x2030, v180
	global_load_dwordx4 v[194:197], v181, s[22:23]
	v_mov_b32_e32 v178, v157
	v_mov_b32_e32 v179, v158
	v_mov_b32_e32 v157, v159
	v_mov_b32_e32 v158, v161
	v_mov_b32_e32 v159, v162
	v_mov_b32_e32 v161, v163
	v_pk_add_f32 v[156:157], v[178:179], v[156:157]
	v_pk_add_f32 v[158:159], v[158:159], v[160:161]
	v_pk_add_f32 v[156:157], v[156:157], v[156:157] op_sel:[0,1] op_sel_hi:[1,0]
	v_pk_add_f32 v[158:159], v[158:159], v[158:159] op_sel:[0,1] op_sel_hi:[1,0]
	v_add_f32_e32 v162, v170, v171
	v_add_f32_e32 v170, v172, v173
	v_mov_b32_e32 v163, v176
	v_mov_b32_e32 v171, v177
	v_mov_b32_e32 v157, v174
	v_mov_b32_e32 v159, v175
	v_pk_add_f32 v[160:161], v[162:163], v[170:171]
	v_pk_add_f32 v[156:157], v[156:157], v[158:159]
	s_nop 0
	v_pk_add_f32 v[156:157], v[156:157], v[160:161]
	s_nop 0
	v_add_f32_e32 v156, v156, v157
	v_fmamk_f32 v156, v156, 0x3a800000, v154
	v_mul_f32_e32 v157, 0x4b800000, v156
	v_cmp_gt_f32_e32 vcc, s63, v156
	s_nop 1
	v_cndmask_b32_e32 v156, v156, v157, vcc
	v_rsq_f32_e32 v158, v156
	v_lshlrev_b64 v[156:157], 6, v[164:165]
	v_lshl_add_u64 v[156:157], s[22:23], 0, v[156:157]
	v_mul_f32_e32 v159, 0x45800000, v158
	v_cndmask_b32_e32 v158, v158, v159, vcc
	v_pk_mul_f32 v[126:127], v[126:127], v[158:159] op_sel_hi:[1,0]
	v_pk_mul_f32 v[124:125], v[124:125], v[158:159] op_sel_hi:[1,0]
	v_pk_mul_f32 v[122:123], v[122:123], v[158:159] op_sel_hi:[1,0]
	v_pk_mul_f32 v[120:121], v[120:121], v[158:159] op_sel_hi:[1,0]
	v_pk_mul_f32 v[114:115], v[114:115], v[158:159] op_sel_hi:[1,0]
	v_pk_mul_f32 v[112:113], v[112:113], v[158:159] op_sel_hi:[1,0]
	v_pk_mul_f32 v[118:119], v[118:119], v[158:159] op_sel_hi:[1,0]
	v_pk_mul_f32 v[116:117], v[116:117], v[158:159] op_sel_hi:[1,0]
	v_max_f32_e32 v124, 0, v124
	v_max_f32_e32 v120, 0, v120
	v_max_f32_e32 v125, 0, v125
	v_max_f32_e32 v121, 0, v121
	v_max_f32_e32 v126, 0, v126
	v_max_f32_e32 v122, 0, v122
	v_max_f32_e32 v127, 0, v127
	v_max_f32_e32 v123, 0, v123
	v_max_f32_e32 v112, 0, v112
	v_max_f32_e32 v113, 0, v113
	v_max_f32_e32 v114, 0, v114
	v_max_f32_e32 v115, 0, v115
	v_max_f32_e32 v116, 0, v116
	v_max_f32_e32 v117, 0, v117
	v_max_f32_e32 v118, 0, v118
	v_max_f32_e32 v119, 0, v119
	v_mul_f32_e32 v124, v124, v124
	v_mul_f32_e32 v120, v120, v120
	v_mul_f32_e32 v125, v125, v125
	v_mul_f32_e32 v121, v121, v121
	v_mul_f32_e32 v126, v126, v126
	v_mul_f32_e32 v122, v122, v122
	v_mul_f32_e32 v127, v127, v127
	v_mul_f32_e32 v123, v123, v123
	v_mul_f32_e32 v158, v112, v112
	v_mul_f32_e32 v159, v113, v113
	v_mul_f32_e32 v160, v114, v114
	v_mul_f32_e32 v161, v115, v115
	v_cvt_pk_bf16_f32 v112, v124, v125
	v_cvt_pk_bf16_f32 v113, v126, v127
	v_cvt_pk_bf16_f32 v114, v120, v121
	v_cvt_pk_bf16_f32 v115, v122, v123
	v_mul_f32_e32 v116, v116, v116
	v_mul_f32_e32 v117, v117, v117
	v_mul_f32_e32 v118, v118, v118
	v_mul_f32_e32 v119, v119, v119
	buffer_store_dwordx4 v[112:115], v155, s[12:15], 0 offen sc1
	s_nop 1
	v_cvt_pk_bf16_f32 v112, v116, v117
	v_cvt_pk_bf16_f32 v113, v118, v119
	v_cvt_pk_bf16_f32 v114, v158, v159
	v_cvt_pk_bf16_f32 v115, v160, v161
	buffer_store_dwordx4 v[112:115], v155, s[12:15], 0 offen offset:256 sc1
	s_nop 0
	v_or_b32_e32 v156, 32, v146
	v_ashrrev_i32_e32 v157, 31, v156
	v_lshl_add_u32 v155, v164, 13, v147
	s_waitcnt vmcnt(14)
	v_mov_b32_e32 v112, v198
	v_mov_b32_e32 v113, v199
	v_mov_b32_e32 v114, v200
	v_mov_b32_e32 v115, v201
	v_mov_b32_e32 v116, v202
	v_mov_b32_e32 v117, v203
	v_mov_b32_e32 v118, v204
	v_mov_b32_e32 v119, v205
	v_mov_b32_e32 v120, v206
	v_mov_b32_e32 v121, v207
	v_mov_b32_e32 v122, v208
	v_mov_b32_e32 v123, v209
	v_mov_b32_e32 v124, v210
	v_mov_b32_e32 v125, v211
	v_mov_b32_e32 v126, v212
	v_mov_b32_e32 v127, v213
	v_add_u32_e32 v181, 0x2400, v180
	global_load_dwordx4 v[198:201], v181, s[22:23]
	v_add_u32_e32 v181, 0x2410, v180
	global_load_dwordx4 v[202:205], v181, s[22:23]
	v_add_u32_e32 v181, 0x2420, v180
	global_load_dwordx4 v[206:209], v181, s[22:23]
	v_add_u32_e32 v181, 0x2430, v180
	global_load_dwordx4 v[210:213], v181, s[22:23]
	v_mov_b32_e32 v158, v113
	v_mov_b32_e32 v159, v114
	v_mov_b32_e32 v113, v115
	v_mov_b32_e32 v114, v117
	v_mov_b32_e32 v115, v118
	v_mov_b32_e32 v117, v119
	v_pk_add_f32 v[112:113], v[158:159], v[112:113]
	v_pk_add_f32 v[114:115], v[114:115], v[116:117]
	v_pk_add_f32 v[112:113], v[112:113], v[112:113] op_sel:[0,1] op_sel_hi:[1,0]
	v_pk_add_f32 v[114:115], v[114:115], v[114:115] op_sel:[0,1] op_sel_hi:[1,0]
	v_add_f32_e32 v118, v120, v121
	v_add_f32_e32 v120, v122, v123
	v_mov_b32_e32 v119, v126
	v_mov_b32_e32 v121, v127
	v_mov_b32_e32 v113, v124
	v_mov_b32_e32 v115, v125
	v_pk_add_f32 v[116:117], v[118:119], v[120:121]
	v_pk_add_f32 v[112:113], v[112:113], v[114:115]
	s_nop 0
	v_pk_add_f32 v[112:113], v[112:113], v[116:117]
	s_nop 0
	v_add_f32_e32 v112, v112, v113
	v_fmamk_f32 v112, v112, 0x3a800000, v154
	v_mul_f32_e32 v113, 0x4b800000, v112
	v_cmp_gt_f32_e32 vcc, s63, v112
	s_nop 1
	v_cndmask_b32_e32 v112, v112, v113, vcc
	v_rsq_f32_e32 v114, v112
; __device__ __forceinline__ u32x4 pack8(const f32x4 v0, const f32x4 v1) { u32x4 w; w.x = pk2(v0[0], v0[1]); w.y = pk2(v0[2], v0[3]); w.z = pk2(v1[0], v1[1]); w.w = pk2(v1[2], v1[3]); return w; }
; __device__ __forceinline__ float row_rstd(const float* ssq, int row) {
;     const f32x4* p = (const f32x4*)(ssq + (size_t)row * 16);
;     const f32x4 a = p[0], b = p[1], c = p[2], d = p[3];
;     const float s = ((a[0] + a[1]) + (a[2] + a[3])) + ((b[0] + b[1]) + (b[2] + b[3])) + ((c[0] + c[1]) + (c[2] + c[3])) + ((d[0] + d[1]) + (d[2] + d[3]));
;     return rsqrtf(s * (1.0f / 1024.0f) + 1e-6f);
;     __device__ __forceinline__ void operator()(const f32x4 (&acc)[2][2][4][2], const Unit& u, int wr, int wc, int fr, int fq) const {
;     ...
;         const int row0 = row_off + u.pm * 256 + wr * 64 + fr, col0 = u.pn * 256 + wc * 32 + 8 * fq;
; #pragma unroll
;         for (int ai = 0; ai < 2; ++ai)
; #pragma unroll
;             for (int m = 0; m < 4; ++m) {
;                 const int row = row0 + ai * 128 + m * 16; const float rs = row_rstd(ssq, row);
; #pragma unroll
;                 for (int bj = 0; bj < 2; ++bj) { f32x4 v0 = acc[ai][bj][m][0] * rs, v1 = acc[ai][bj][m][1] * rs;
; #pragma unroll
;                     for (int j = 0; j < 4; ++j) { const float a = fmaxf(v0[j], 0.f), b = fmaxf(v1[j], 0.f); v0[j] = a * a; v1[j] = b * b; }
;                     __builtin_amdgcn_raw_buffer_store_b128(pack8(v0, v1), rsrc, (unsigned)(((size_t)row * DFF + col0 + bj * 128) * 2), 0, 16  ); }
	v_lshlrev_b64 v[112:113], 6, v[156:157]
	v_lshl_add_u64 v[112:113], s[22:23], 0, v[112:113]
	v_mul_f32_e32 v115, 0x45800000, v114
	v_cndmask_b32_e32 v114, v114, v115, vcc
	v_pk_mul_f32 v[110:111], v[110:111], v[114:115] op_sel_hi:[1,0]
	v_pk_mul_f32 v[108:109], v[108:109], v[114:115] op_sel_hi:[1,0]
	v_pk_mul_f32 v[106:107], v[106:107], v[114:115] op_sel_hi:[1,0]
	v_pk_mul_f32 v[104:105], v[104:105], v[114:115] op_sel_hi:[1,0]
	v_pk_mul_f32 v[98:99], v[98:99], v[114:115] op_sel_hi:[1,0]
	v_pk_mul_f32 v[96:97], v[96:97], v[114:115] op_sel_hi:[1,0]
	v_pk_mul_f32 v[102:103], v[102:103], v[114:115] op_sel_hi:[1,0]
	v_pk_mul_f32 v[100:101], v[100:101], v[114:115] op_sel_hi:[1,0]
	v_max_f32_e32 v108, 0, v108
	v_max_f32_e32 v104, 0, v104
	v_max_f32_e32 v109, 0, v109
	v_max_f32_e32 v105, 0, v105
	v_max_f32_e32 v110, 0, v110
	v_max_f32_e32 v106, 0, v106
	v_max_f32_e32 v111, 0, v111
	v_max_f32_e32 v107, 0, v107
	v_max_f32_e32 v96, 0, v96
	v_max_f32_e32 v97, 0, v97
	v_max_f32_e32 v98, 0, v98
	v_max_f32_e32 v99, 0, v99
	v_max_f32_e32 v100, 0, v100
	v_max_f32_e32 v101, 0, v101
	v_max_f32_e32 v102, 0, v102
	v_max_f32_e32 v103, 0, v103
	v_mul_f32_e32 v108, v108, v108
	v_mul_f32_e32 v104, v104, v104
	v_mul_f32_e32 v109, v109, v109
	v_mul_f32_e32 v105, v105, v105
	v_mul_f32_e32 v110, v110, v110
	v_mul_f32_e32 v106, v106, v106
	v_mul_f32_e32 v111, v111, v111
	v_mul_f32_e32 v107, v107, v107
	v_mul_f32_e32 v114, v96, v96
	v_mul_f32_e32 v115, v97, v97
	v_mul_f32_e32 v116, v98, v98
	v_mul_f32_e32 v117, v99, v99
	v_cvt_pk_bf16_f32 v96, v108, v109
	v_cvt_pk_bf16_f32 v97, v110, v111
	v_cvt_pk_bf16_f32 v98, v104, v105
	v_cvt_pk_bf16_f32 v99, v106, v107
	v_mul_f32_e32 v100, v100, v100
	v_mul_f32_e32 v101, v101, v101
	v_mul_f32_e32 v102, v102, v102
	v_mul_f32_e32 v103, v103, v103
	buffer_store_dwordx4 v[96:99], v155, s[12:15], 0 offen sc1
	s_nop 1
	v_cvt_pk_bf16_f32 v96, v100, v101
	v_cvt_pk_bf16_f32 v97, v102, v103
	v_cvt_pk_bf16_f32 v98, v114, v115
	v_cvt_pk_bf16_f32 v99, v116, v117
	buffer_store_dwordx4 v[96:99], v155, s[12:15], 0 offen offset:256 sc1
	s_nop 0
	v_or_b32_e32 v112, 48, v146
	v_ashrrev_i32_e32 v113, 31, v112
	v_lshl_add_u32 v116, v156, 13, v147
	s_waitcnt vmcnt(16)
	v_mov_b32_e32 v96, v214
	v_mov_b32_e32 v97, v215
	v_mov_b32_e32 v98, v216
	v_mov_b32_e32 v99, v217
	v_mov_b32_e32 v100, v218
	v_mov_b32_e32 v101, v219
	v_mov_b32_e32 v102, v220
	v_mov_b32_e32 v103, v221
	v_mov_b32_e32 v104, v222
	v_mov_b32_e32 v105, v223
	v_mov_b32_e32 v106, v224
	v_mov_b32_e32 v107, v225
	v_mov_b32_e32 v108, v232
	v_mov_b32_e32 v109, v233
	v_mov_b32_e32 v110, v234
	v_mov_b32_e32 v111, v235
	v_add_u32_e32 v181, 0x2800, v180
	global_load_dwordx4 v[214:217], v181, s[22:23]
	v_add_u32_e32 v181, 0x2810, v180
	global_load_dwordx4 v[218:221], v181, s[22:23]
	v_add_u32_e32 v181, 0x2820, v180
	global_load_dwordx4 v[222:225], v181, s[22:23]
	v_add_u32_e32 v181, 0x2830, v180
	global_load_dwordx4 v[232:235], v181, s[22:23]
	v_mov_b32_e32 v114, v97
	v_mov_b32_e32 v115, v98
	v_mov_b32_e32 v97, v99
	v_mov_b32_e32 v98, v101
	v_mov_b32_e32 v99, v102
	v_mov_b32_e32 v101, v103
	v_pk_add_f32 v[96:97], v[114:115], v[96:97]
	v_pk_add_f32 v[98:99], v[98:99], v[100:101]
	v_pk_add_f32 v[96:97], v[96:97], v[96:97] op_sel:[0,1] op_sel_hi:[1,0]
	v_pk_add_f32 v[98:99], v[98:99], v[98:99] op_sel:[0,1] op_sel_hi:[1,0]
	v_add_f32_e32 v102, v104, v105
	v_add_f32_e32 v104, v106, v107
	v_mov_b32_e32 v103, v110
	v_mov_b32_e32 v105, v111
	v_mov_b32_e32 v97, v108
	v_mov_b32_e32 v99, v109
	v_pk_add_f32 v[100:101], v[102:103], v[104:105]
	v_pk_add_f32 v[96:97], v[96:97], v[98:99]
	s_nop 0
	v_pk_add_f32 v[96:97], v[96:97], v[100:101]
	s_nop 0
	v_add_f32_e32 v96, v96, v97
	v_fmamk_f32 v96, v96, 0x3a800000, v154
	v_mul_f32_e32 v97, 0x4b800000, v96
	v_cmp_gt_f32_e32 vcc, s63, v96
	s_nop 1
	v_cndmask_b32_e32 v96, v96, v97, vcc
	v_rsq_f32_e32 v98, v96
	v_lshlrev_b64 v[96:97], 6, v[112:113]
	v_lshl_add_u64 v[96:97], s[22:23], 0, v[96:97]
	v_mul_f32_e32 v99, 0x45800000, v98
	v_cndmask_b32_e32 v98, v98, v99, vcc
	v_pk_mul_f32 v[94:95], v[94:95], v[98:99] op_sel_hi:[1,0]
	v_pk_mul_f32 v[92:93], v[92:93], v[98:99] op_sel_hi:[1,0]
	v_pk_mul_f32 v[90:91], v[90:91], v[98:99] op_sel_hi:[1,0]
	v_pk_mul_f32 v[88:89], v[88:89], v[98:99] op_sel_hi:[1,0]
	v_pk_mul_f32 v[82:83], v[82:83], v[98:99] op_sel_hi:[1,0]
	v_pk_mul_f32 v[80:81], v[80:81], v[98:99] op_sel_hi:[1,0]
	v_pk_mul_f32 v[86:87], v[86:87], v[98:99] op_sel_hi:[1,0]
	v_pk_mul_f32 v[84:85], v[84:85], v[98:99] op_sel_hi:[1,0]
	v_max_f32_e32 v92, 0, v92
	v_max_f32_e32 v88, 0, v88
	v_max_f32_e32 v93, 0, v93
	v_max_f32_e32 v89, 0, v89
	v_max_f32_e32 v94, 0, v94
	v_max_f32_e32 v90, 0, v90
	v_max_f32_e32 v95, 0, v95
	v_max_f32_e32 v91, 0, v91
	v_max_f32_e32 v80, 0, v80
	v_max_f32_e32 v81, 0, v81
	v_max_f32_e32 v82, 0, v82
	v_max_f32_e32 v83, 0, v83
	v_max_f32_e32 v84, 0, v84
	v_max_f32_e32 v85, 0, v85
	v_max_f32_e32 v86, 0, v86
	v_max_f32_e32 v87, 0, v87
	v_mul_f32_e32 v92, v92, v92
	v_mul_f32_e32 v88, v88, v88
	v_mul_f32_e32 v93, v93, v93
	v_mul_f32_e32 v89, v89, v89
	v_mul_f32_e32 v94, v94, v94
	v_mul_f32_e32 v90, v90, v90
	v_mul_f32_e32 v95, v95, v95
	v_mul_f32_e32 v91, v91, v91
	v_mul_f32_e32 v98, v80, v80
	v_mul_f32_e32 v99, v81, v81
	v_mul_f32_e32 v100, v82, v82
	v_mul_f32_e32 v101, v83, v83
	v_cvt_pk_bf16_f32 v80, v92, v93
	v_cvt_pk_bf16_f32 v81, v94, v95
	v_cvt_pk_bf16_f32 v82, v88, v89
	v_cvt_pk_bf16_f32 v83, v90, v91
	v_mul_f32_e32 v84, v84, v84
	v_mul_f32_e32 v85, v85, v85
	v_mul_f32_e32 v86, v86, v86
	v_mul_f32_e32 v87, v87, v87
	buffer_store_dwordx4 v[80:83], v116, s[12:15], 0 offen sc1
	s_nop 1
	v_cvt_pk_bf16_f32 v80, v84, v85
	v_cvt_pk_bf16_f32 v81, v86, v87
	v_cvt_pk_bf16_f32 v82, v98, v99
	v_cvt_pk_bf16_f32 v83, v100, v101
	buffer_store_dwordx4 v[80:83], v116, s[12:15], 0 offen offset:256 sc1
	s_nop 0
	v_add_u32_e32 v96, 0x80, v146
	v_ashrrev_i32_e32 v97, 31, v96
	v_lshl_add_u32 v100, v112, 13, v147
	s_waitcnt vmcnt(18)
; __device__ __forceinline__ u32x4 pack8(const f32x4 v0, const f32x4 v1) { u32x4 w; w.x = pk2(v0[0], v0[1]); w.y = pk2(v0[2], v0[3]); w.z = pk2(v1[0], v1[1]); w.w = pk2(v1[2], v1[3]); return w; }
; __device__ __forceinline__ float row_rstd(const float* ssq, int row) {
;     const f32x4* p = (const f32x4*)(ssq + (size_t)row * 16);
;     const f32x4 a = p[0], b = p[1], c = p[2], d = p[3];
;     const float s = ((a[0] + a[1]) + (a[2] + a[3])) + ((b[0] + b[1]) + (b[2] + b[3])) + ((c[0] + c[1]) + (c[2] + c[3])) + ((d[0] + d[1]) + (d[2] + d[3]));
;     return rsqrtf(s * (1.0f / 1024.0f) + 1e-6f);
;     __device__ __forceinline__ void operator()(const f32x4 (&acc)[2][2][4][2], const Unit& u, int wr, int wc, int fr, int fq) const {
;     ...
;         const int row0 = row_off + u.pm * 256 + wr * 64 + fr, col0 = u.pn * 256 + wc * 32 + 8 * fq;
; #pragma unroll
;         for (int ai = 0; ai < 2; ++ai)
; #pragma unroll
;             for (int m = 0; m < 4; ++m) {
;                 const int row = row0 + ai * 128 + m * 16; const float rs = row_rstd(ssq, row);
; #pragma unroll
;                 for (int bj = 0; bj < 2; ++bj) { f32x4 v0 = acc[ai][bj][m][0] * rs, v1 = acc[ai][bj][m][1] * rs;
; #pragma unroll
;                     for (int j = 0; j < 4; ++j) { const float a = fmaxf(v0[j], 0.f), b = fmaxf(v1[j], 0.f); v0[j] = a * a; v1[j] = b * b; }
;                     __builtin_amdgcn_raw_buffer_store_b128(pack8(v0, v1), rsrc, (unsigned)(((size_t)row * DFF + col0 + bj * 128) * 2), 0, 16  ); }
	v_mov_b32_e32 v80, v236
	v_mov_b32_e32 v81, v237
	v_mov_b32_e32 v82, v238
	v_mov_b32_e32 v83, v239
	v_mov_b32_e32 v84, v240
	v_mov_b32_e32 v85, v241
	v_mov_b32_e32 v86, v242
	v_mov_b32_e32 v87, v243
	v_mov_b32_e32 v88, v244
	v_mov_b32_e32 v89, v245
	v_mov_b32_e32 v90, v246
	v_mov_b32_e32 v91, v247
	v_mov_b32_e32 v92, v248
	v_mov_b32_e32 v93, v249
	v_mov_b32_e32 v94, v250
	v_mov_b32_e32 v95, v251
	v_add_u32_e32 v181, 0x2c00, v180
	global_load_dwordx4 v[236:239], v181, s[22:23]
	v_add_u32_e32 v181, 0x2c10, v180
	global_load_dwordx4 v[240:243], v181, s[22:23]
	v_add_u32_e32 v181, 0x2c20, v180
	global_load_dwordx4 v[244:247], v181, s[22:23]
	v_add_u32_e32 v181, 0x2c30, v180
	global_load_dwordx4 v[248:251], v181, s[22:23]
	v_mov_b32_e32 v98, v81
	v_mov_b32_e32 v99, v82
	v_mov_b32_e32 v81, v83
	v_mov_b32_e32 v82, v85
	v_mov_b32_e32 v83, v86
	v_mov_b32_e32 v85, v87
	v_pk_add_f32 v[80:81], v[98:99], v[80:81]
	v_pk_add_f32 v[82:83], v[82:83], v[84:85]
	v_pk_add_f32 v[80:81], v[80:81], v[80:81] op_sel:[0,1] op_sel_hi:[1,0]
	v_pk_add_f32 v[82:83], v[82:83], v[82:83] op_sel:[0,1] op_sel_hi:[1,0]
	v_add_f32_e32 v86, v88, v89
	v_add_f32_e32 v88, v90, v91
	v_mov_b32_e32 v87, v94
	v_mov_b32_e32 v89, v95
	v_mov_b32_e32 v81, v92
	v_mov_b32_e32 v83, v93
	v_pk_add_f32 v[84:85], v[86:87], v[88:89]
	v_pk_add_f32 v[80:81], v[80:81], v[82:83]
	s_nop 0
	v_pk_add_f32 v[80:81], v[80:81], v[84:85]
	s_nop 0
	v_add_f32_e32 v80, v80, v81
	v_fmamk_f32 v80, v80, 0x3a800000, v154
	v_mul_f32_e32 v81, 0x4b800000, v80
	v_cmp_gt_f32_e32 vcc, s63, v80
	s_nop 1
	v_cndmask_b32_e32 v80, v80, v81, vcc
	v_rsq_f32_e32 v82, v80
	v_lshlrev_b64 v[80:81], 6, v[96:97]
	v_lshl_add_u64 v[80:81], s[22:23], 0, v[80:81]
	v_mul_f32_e32 v83, 0x45800000, v82
	v_cndmask_b32_e32 v82, v82, v83, vcc
	v_pk_mul_f32 v[78:79], v[78:79], v[82:83] op_sel_hi:[1,0]
	v_pk_mul_f32 v[76:77], v[76:77], v[82:83] op_sel_hi:[1,0]
	v_pk_mul_f32 v[74:75], v[74:75], v[82:83] op_sel_hi:[1,0]
	v_pk_mul_f32 v[72:73], v[72:73], v[82:83] op_sel_hi:[1,0]
	v_pk_mul_f32 v[66:67], v[66:67], v[82:83] op_sel_hi:[1,0]
	v_pk_mul_f32 v[64:65], v[64:65], v[82:83] op_sel_hi:[1,0]
	v_pk_mul_f32 v[70:71], v[70:71], v[82:83] op_sel_hi:[1,0]
	v_pk_mul_f32 v[68:69], v[68:69], v[82:83] op_sel_hi:[1,0]
	v_max_f32_e32 v76, 0, v76
	v_max_f32_e32 v72, 0, v72
	v_max_f32_e32 v77, 0, v77
	v_max_f32_e32 v73, 0, v73
	v_max_f32_e32 v78, 0, v78
	v_max_f32_e32 v74, 0, v74
	v_max_f32_e32 v79, 0, v79
	v_max_f32_e32 v75, 0, v75
	v_max_f32_e32 v64, 0, v64
	v_max_f32_e32 v65, 0, v65
	v_max_f32_e32 v66, 0, v66
	v_max_f32_e32 v67, 0, v67
	v_max_f32_e32 v68, 0, v68
	v_max_f32_e32 v69, 0, v69
	v_max_f32_e32 v70, 0, v70
	v_max_f32_e32 v71, 0, v71
	v_mul_f32_e32 v76, v76, v76
	v_mul_f32_e32 v72, v72, v72
	v_mul_f32_e32 v77, v77, v77
	v_mul_f32_e32 v73, v73, v73
	v_mul_f32_e32 v78, v78, v78
	v_mul_f32_e32 v74, v74, v74
	v_mul_f32_e32 v79, v79, v79
	v_mul_f32_e32 v75, v75, v75
	v_mul_f32_e32 v82, v64, v64
	v_mul_f32_e32 v83, v65, v65
	v_mul_f32_e32 v84, v66, v66
	v_mul_f32_e32 v85, v67, v67
	v_cvt_pk_bf16_f32 v64, v76, v77
	v_cvt_pk_bf16_f32 v65, v78, v79
	v_cvt_pk_bf16_f32 v66, v72, v73
	v_cvt_pk_bf16_f32 v67, v74, v75
	v_mul_f32_e32 v68, v68, v68
	v_mul_f32_e32 v69, v69, v69
	v_mul_f32_e32 v70, v70, v70
	v_mul_f32_e32 v71, v71, v71
	buffer_store_dwordx4 v[64:67], v100, s[12:15], 0 offen sc1
	s_nop 1
	v_cvt_pk_bf16_f32 v64, v68, v69
	v_cvt_pk_bf16_f32 v65, v70, v71
	v_cvt_pk_bf16_f32 v66, v82, v83
	v_cvt_pk_bf16_f32 v67, v84, v85
	buffer_store_dwordx4 v[64:67], v100, s[12:15], 0 offen offset:256 sc1
	s_nop 0
	v_add_u32_e32 v80, 0x90, v146
	v_ashrrev_i32_e32 v81, 31, v80
	v_lshl_add_u32 v84, v96, 13, v147
	s_waitcnt vmcnt(20)
	v_mov_b32_e32 v64, v182
	v_mov_b32_e32 v65, v183
	v_mov_b32_e32 v66, v184
	v_mov_b32_e32 v67, v185
	v_mov_b32_e32 v68, v186
	v_mov_b32_e32 v69, v187
	v_mov_b32_e32 v70, v188
	v_mov_b32_e32 v71, v189
	v_mov_b32_e32 v72, v190
	v_mov_b32_e32 v73, v191
	v_mov_b32_e32 v74, v192
	v_mov_b32_e32 v75, v193
	v_mov_b32_e32 v76, v194
	v_mov_b32_e32 v77, v195
	v_mov_b32_e32 v78, v196
	v_mov_b32_e32 v79, v197
	v_mov_b32_e32 v82, v65
	v_mov_b32_e32 v83, v66
	v_mov_b32_e32 v65, v67
	v_mov_b32_e32 v66, v69
	v_mov_b32_e32 v67, v70
	v_mov_b32_e32 v69, v71
	v_pk_add_f32 v[64:65], v[82:83], v[64:65]
	v_pk_add_f32 v[66:67], v[66:67], v[68:69]
	v_pk_add_f32 v[64:65], v[64:65], v[64:65] op_sel:[0,1] op_sel_hi:[1,0]
	v_pk_add_f32 v[66:67], v[66:67], v[66:67] op_sel:[0,1] op_sel_hi:[1,0]
	v_add_f32_e32 v70, v72, v73
	v_add_f32_e32 v72, v74, v75
	v_mov_b32_e32 v71, v78
	v_mov_b32_e32 v73, v79
	v_mov_b32_e32 v65, v76
	v_mov_b32_e32 v67, v77
	v_pk_add_f32 v[68:69], v[70:71], v[72:73]
	v_pk_add_f32 v[64:65], v[64:65], v[66:67]
	s_nop 0
	v_pk_add_f32 v[64:65], v[64:65], v[68:69]
	s_nop 0
	v_add_f32_e32 v64, v64, v65
	v_fmamk_f32 v64, v64, 0x3a800000, v154
	v_mul_f32_e32 v65, 0x4b800000, v64
	v_cmp_gt_f32_e32 vcc, s63, v64
	s_nop 1
	v_cndmask_b32_e32 v64, v64, v65, vcc
	v_rsq_f32_e32 v66, v64
	v_lshlrev_b64 v[64:65], 6, v[80:81]
	v_lshl_add_u64 v[64:65], s[22:23], 0, v[64:65]
	v_mul_f32_e32 v67, 0x45800000, v66
	v_cndmask_b32_e32 v66, v66, v67, vcc
	v_pk_mul_f32 v[62:63], v[62:63], v[66:67] op_sel_hi:[1,0]
	v_pk_mul_f32 v[60:61], v[60:61], v[66:67] op_sel_hi:[1,0]
	v_pk_mul_f32 v[58:59], v[58:59], v[66:67] op_sel_hi:[1,0]
	v_pk_mul_f32 v[56:57], v[56:57], v[66:67] op_sel_hi:[1,0]
	v_pk_mul_f32 v[50:51], v[50:51], v[66:67] op_sel_hi:[1,0]
	v_pk_mul_f32 v[48:49], v[48:49], v[66:67] op_sel_hi:[1,0]
	v_pk_mul_f32 v[54:55], v[54:55], v[66:67] op_sel_hi:[1,0]
	v_pk_mul_f32 v[52:53], v[52:53], v[66:67] op_sel_hi:[1,0]
	v_max_f32_e32 v60, 0, v60
	v_max_f32_e32 v56, 0, v56
	v_max_f32_e32 v61, 0, v61
	v_max_f32_e32 v57, 0, v57
	v_max_f32_e32 v62, 0, v62
	v_max_f32_e32 v58, 0, v58
	v_max_f32_e32 v63, 0, v63
	v_max_f32_e32 v59, 0, v59
	v_max_f32_e32 v48, 0, v48
	v_max_f32_e32 v49, 0, v49
	v_max_f32_e32 v50, 0, v50
	v_max_f32_e32 v51, 0, v51
	v_max_f32_e32 v52, 0, v52
	v_max_f32_e32 v53, 0, v53
	v_max_f32_e32 v54, 0, v54
	v_max_f32_e32 v55, 0, v55
	v_mul_f32_e32 v60, v60, v60
	v_mul_f32_e32 v56, v56, v56
	v_mul_f32_e32 v61, v61, v61
	v_mul_f32_e32 v57, v57, v57
	v_mul_f32_e32 v62, v62, v62
	v_mul_f32_e32 v58, v58, v58
	v_mul_f32_e32 v63, v63, v63
	v_mul_f32_e32 v59, v59, v59
	v_mul_f32_e32 v66, v48, v48
	v_mul_f32_e32 v67, v49, v49
	v_mul_f32_e32 v68, v50, v50
	v_mul_f32_e32 v69, v51, v51
	v_cvt_pk_bf16_f32 v48, v60, v61
	v_cvt_pk_bf16_f32 v49, v62, v63
	v_cvt_pk_bf16_f32 v50, v56, v57
	v_cvt_pk_bf16_f32 v51, v58, v59
	v_mul_f32_e32 v52, v52, v52
	v_mul_f32_e32 v53, v53, v53
	v_mul_f32_e32 v54, v54, v54
	v_mul_f32_e32 v55, v55, v55
	buffer_store_dwordx4 v[48:51], v84, s[12:15], 0 offen sc1
	s_nop 1
	v_cvt_pk_bf16_f32 v48, v52, v53
	v_cvt_pk_bf16_f32 v49, v54, v55
	v_cvt_pk_bf16_f32 v50, v66, v67
	v_cvt_pk_bf16_f32 v51, v68, v69
	buffer_store_dwordx4 v[48:51], v84, s[12:15], 0 offen offset:256 sc1
	s_nop 0
	v_add_u32_e32 v64, 0xa0, v146
	v_ashrrev_i32_e32 v65, 31, v64
	v_lshl_add_u32 v68, v80, 13, v147
	s_waitcnt vmcnt(16)
; __device__ __forceinline__ u32x4 pack8(const f32x4 v0, const f32x4 v1) { u32x4 w; w.x = pk2(v0[0], v0[1]); w.y = pk2(v0[2], v0[3]); w.z = pk2(v1[0], v1[1]); w.w = pk2(v1[2], v1[3]); return w; }
; __device__ __forceinline__ float row_rstd(const float* ssq, int row) {
;     const f32x4* p = (const f32x4*)(ssq + (size_t)row * 16);
;     const f32x4 a = p[0], b = p[1], c = p[2], d = p[3];
;     const float s = ((a[0] + a[1]) + (a[2] + a[3])) + ((b[0] + b[1]) + (b[2] + b[3])) + ((c[0] + c[1]) + (c[2] + c[3])) + ((d[0] + d[1]) + (d[2] + d[3]));
;     return rsqrtf(s * (1.0f / 1024.0f) + 1e-6f);
;     __device__ __forceinline__ void operator()(const f32x4 (&acc)[2][2][4][2], const Unit& u, int wr, int wc, int fr, int fq) const {
;     ...
;         const int row0 = row_off + u.pm * 256 + wr * 64 + fr, col0 = u.pn * 256 + wc * 32 + 8 * fq;
; #pragma unroll
;         for (int ai = 0; ai < 2; ++ai)
; #pragma unroll
;             for (int m = 0; m < 4; ++m) {
;                 const int row = row0 + ai * 128 + m * 16; const float rs = row_rstd(ssq, row);
; #pragma unroll
;                 for (int bj = 0; bj < 2; ++bj) { f32x4 v0 = acc[ai][bj][m][0] * rs, v1 = acc[ai][bj][m][1] * rs;
; #pragma unroll
;                     for (int j = 0; j < 4; ++j) { const float a = fmaxf(v0[j], 0.f), b = fmaxf(v1[j], 0.f); v0[j] = a * a; v1[j] = b * b; }
;                     __builtin_amdgcn_raw_buffer_store_b128(pack8(v0, v1), rsrc, (unsigned)(((size_t)row * DFF + col0 + bj * 128) * 2), 0, 16  ); }
	v_mov_b32_e32 v48, v198
	v_mov_b32_e32 v49, v199
	v_mov_b32_e32 v50, v200
	v_mov_b32_e32 v51, v201
	v_mov_b32_e32 v52, v202
	v_mov_b32_e32 v53, v203
	v_mov_b32_e32 v54, v204
	v_mov_b32_e32 v55, v205
	v_mov_b32_e32 v56, v206
	v_mov_b32_e32 v57, v207
	v_mov_b32_e32 v58, v208
	v_mov_b32_e32 v59, v209
	v_mov_b32_e32 v60, v210
	v_mov_b32_e32 v61, v211
	v_mov_b32_e32 v62, v212
	v_mov_b32_e32 v63, v213
	v_mov_b32_e32 v66, v49
	v_mov_b32_e32 v67, v50
	v_mov_b32_e32 v49, v51
	v_mov_b32_e32 v50, v53
	v_mov_b32_e32 v51, v54
	v_mov_b32_e32 v53, v55
	v_pk_add_f32 v[48:49], v[66:67], v[48:49]
	v_pk_add_f32 v[50:51], v[50:51], v[52:53]
	v_pk_add_f32 v[48:49], v[48:49], v[48:49] op_sel:[0,1] op_sel_hi:[1,0]
	v_pk_add_f32 v[50:51], v[50:51], v[50:51] op_sel:[0,1] op_sel_hi:[1,0]
	v_add_f32_e32 v54, v56, v57
	v_add_f32_e32 v56, v58, v59
	v_mov_b32_e32 v55, v62
	v_mov_b32_e32 v57, v63
	v_mov_b32_e32 v49, v60
	v_mov_b32_e32 v51, v61
	v_pk_add_f32 v[52:53], v[54:55], v[56:57]
	v_pk_add_f32 v[48:49], v[48:49], v[50:51]
	s_nop 0
	v_pk_add_f32 v[48:49], v[48:49], v[52:53]
	s_nop 0
	v_add_f32_e32 v48, v48, v49
	v_fmamk_f32 v48, v48, 0x3a800000, v154
	v_mul_f32_e32 v49, 0x4b800000, v48
	v_cmp_gt_f32_e32 vcc, s63, v48
	s_nop 1
	v_cndmask_b32_e32 v48, v48, v49, vcc
	v_rsq_f32_e32 v50, v48
	v_lshlrev_b64 v[48:49], 6, v[64:65]
	v_lshl_add_u64 v[48:49], s[22:23], 0, v[48:49]
	v_mul_f32_e32 v51, 0x45800000, v50
	v_cndmask_b32_e32 v50, v50, v51, vcc
	v_pk_mul_f32 v[46:47], v[46:47], v[50:51] op_sel_hi:[1,0]
	v_pk_mul_f32 v[44:45], v[44:45], v[50:51] op_sel_hi:[1,0]
	v_pk_mul_f32 v[42:43], v[42:43], v[50:51] op_sel_hi:[1,0]
	v_pk_mul_f32 v[40:41], v[40:41], v[50:51] op_sel_hi:[1,0]
	v_pk_mul_f32 v[34:35], v[34:35], v[50:51] op_sel_hi:[1,0]
	v_pk_mul_f32 v[32:33], v[32:33], v[50:51] op_sel_hi:[1,0]
	v_pk_mul_f32 v[38:39], v[38:39], v[50:51] op_sel_hi:[1,0]
	v_pk_mul_f32 v[36:37], v[36:37], v[50:51] op_sel_hi:[1,0]
	v_max_f32_e32 v44, 0, v44
	v_max_f32_e32 v40, 0, v40
	v_max_f32_e32 v45, 0, v45
	v_max_f32_e32 v41, 0, v41
	v_max_f32_e32 v46, 0, v46
	v_max_f32_e32 v42, 0, v42
	v_max_f32_e32 v47, 0, v47
	v_max_f32_e32 v43, 0, v43
	v_max_f32_e32 v32, 0, v32
	v_max_f32_e32 v33, 0, v33
	v_max_f32_e32 v34, 0, v34
	v_max_f32_e32 v35, 0, v35
	v_max_f32_e32 v36, 0, v36
	v_max_f32_e32 v37, 0, v37
	v_max_f32_e32 v38, 0, v38
	v_max_f32_e32 v39, 0, v39
	v_mul_f32_e32 v44, v44, v44
	v_mul_f32_e32 v40, v40, v40
	v_mul_f32_e32 v45, v45, v45
	v_mul_f32_e32 v41, v41, v41
	v_mul_f32_e32 v46, v46, v46
	v_mul_f32_e32 v42, v42, v42
	v_mul_f32_e32 v47, v47, v47
	v_mul_f32_e32 v43, v43, v43
	v_mul_f32_e32 v50, v32, v32
	v_mul_f32_e32 v51, v33, v33
	v_mul_f32_e32 v52, v34, v34
	v_mul_f32_e32 v53, v35, v35
	v_cvt_pk_bf16_f32 v32, v44, v45
	v_cvt_pk_bf16_f32 v33, v46, v47
	v_cvt_pk_bf16_f32 v34, v40, v41
	v_cvt_pk_bf16_f32 v35, v42, v43
	v_mul_f32_e32 v36, v36, v36
	v_mul_f32_e32 v37, v37, v37
	v_mul_f32_e32 v38, v38, v38
	v_mul_f32_e32 v39, v39, v39
	buffer_store_dwordx4 v[32:35], v68, s[12:15], 0 offen sc1
	s_nop 1
	v_cvt_pk_bf16_f32 v32, v36, v37
	v_cvt_pk_bf16_f32 v33, v38, v39
	v_cvt_pk_bf16_f32 v34, v50, v51
	v_cvt_pk_bf16_f32 v35, v52, v53
	buffer_store_dwordx4 v[32:35], v68, s[12:15], 0 offen offset:256 sc1
	s_nop 0
	v_add_u32_e32 v48, 0xb0, v146
	v_ashrrev_i32_e32 v49, 31, v48
	v_lshl_add_u32 v52, v64, 13, v147
	s_waitcnt vmcnt(12)
	v_mov_b32_e32 v32, v214
	v_mov_b32_e32 v33, v215
	v_mov_b32_e32 v34, v216
	v_mov_b32_e32 v35, v217
	v_mov_b32_e32 v36, v218
	v_mov_b32_e32 v37, v219
	v_mov_b32_e32 v38, v220
	v_mov_b32_e32 v39, v221
	v_mov_b32_e32 v40, v222
	v_mov_b32_e32 v41, v223
	v_mov_b32_e32 v42, v224
	v_mov_b32_e32 v43, v225
	v_mov_b32_e32 v44, v232
	v_mov_b32_e32 v45, v233
	v_mov_b32_e32 v46, v234
	v_mov_b32_e32 v47, v235
	v_mov_b32_e32 v50, v33
	v_mov_b32_e32 v51, v34
	v_mov_b32_e32 v33, v35
	v_mov_b32_e32 v34, v37
	v_mov_b32_e32 v35, v38
	v_mov_b32_e32 v37, v39
	v_pk_add_f32 v[32:33], v[50:51], v[32:33]
	v_pk_add_f32 v[34:35], v[34:35], v[36:37]
	v_pk_add_f32 v[32:33], v[32:33], v[32:33] op_sel:[0,1] op_sel_hi:[1,0]
	v_pk_add_f32 v[34:35], v[34:35], v[34:35] op_sel:[0,1] op_sel_hi:[1,0]
	v_add_f32_e32 v38, v40, v41
	v_add_f32_e32 v40, v42, v43
	v_mov_b32_e32 v39, v46
	v_mov_b32_e32 v41, v47
	v_mov_b32_e32 v33, v44
	v_mov_b32_e32 v35, v45
	v_pk_add_f32 v[36:37], v[38:39], v[40:41]
	v_pk_add_f32 v[32:33], v[32:33], v[34:35]
	s_nop 0
	v_pk_add_f32 v[32:33], v[32:33], v[36:37]
	s_nop 0
	v_add_f32_e32 v32, v32, v33
	v_fmamk_f32 v32, v32, 0x3a800000, v154
	v_mul_f32_e32 v33, 0x4b800000, v32
	v_cmp_gt_f32_e32 vcc, s63, v32
	s_nop 1
	v_cndmask_b32_e32 v32, v32, v33, vcc
	v_rsq_f32_e32 v34, v32
	v_lshlrev_b64 v[32:33], 6, v[48:49]
	v_lshl_add_u64 v[32:33], s[22:23], 0, v[32:33]
	v_mul_f32_e32 v35, 0x45800000, v34
	v_cndmask_b32_e32 v34, v34, v35, vcc
	v_pk_mul_f32 v[30:31], v[30:31], v[34:35] op_sel_hi:[1,0]
	v_pk_mul_f32 v[28:29], v[28:29], v[34:35] op_sel_hi:[1,0]
	v_pk_mul_f32 v[26:27], v[26:27], v[34:35] op_sel_hi:[1,0]
	v_pk_mul_f32 v[24:25], v[24:25], v[34:35] op_sel_hi:[1,0]
	v_pk_mul_f32 v[18:19], v[18:19], v[34:35] op_sel_hi:[1,0]
	v_pk_mul_f32 v[16:17], v[16:17], v[34:35] op_sel_hi:[1,0]
	v_pk_mul_f32 v[22:23], v[22:23], v[34:35] op_sel_hi:[1,0]
	v_pk_mul_f32 v[20:21], v[20:21], v[34:35] op_sel_hi:[1,0]
	v_max_f32_e32 v28, 0, v28
	v_max_f32_e32 v24, 0, v24
	v_max_f32_e32 v29, 0, v29
	v_max_f32_e32 v25, 0, v25
	v_max_f32_e32 v30, 0, v30
	v_max_f32_e32 v26, 0, v26
	v_max_f32_e32 v31, 0, v31
	v_max_f32_e32 v27, 0, v27
	v_max_f32_e32 v16, 0, v16
	v_max_f32_e32 v17, 0, v17
	v_max_f32_e32 v18, 0, v18
	v_max_f32_e32 v19, 0, v19
	v_max_f32_e32 v20, 0, v20
	v_max_f32_e32 v21, 0, v21
	v_max_f32_e32 v22, 0, v22
	v_max_f32_e32 v23, 0, v23
	v_mul_f32_e32 v28, v28, v28
	v_mul_f32_e32 v24, v24, v24
	v_mul_f32_e32 v29, v29, v29
	v_mul_f32_e32 v25, v25, v25
	v_mul_f32_e32 v30, v30, v30
	v_mul_f32_e32 v26, v26, v26
	v_mul_f32_e32 v31, v31, v31
	v_mul_f32_e32 v27, v27, v27
	v_mul_f32_e32 v34, v16, v16
	v_mul_f32_e32 v35, v17, v17
	v_mul_f32_e32 v36, v18, v18
	v_mul_f32_e32 v37, v19, v19
	v_cvt_pk_bf16_f32 v16, v28, v29
	v_cvt_pk_bf16_f32 v17, v30, v31
	v_cvt_pk_bf16_f32 v18, v24, v25
	v_cvt_pk_bf16_f32 v19, v26, v27
	v_mul_f32_e32 v20, v20, v20
	v_mul_f32_e32 v21, v21, v21
	v_mul_f32_e32 v22, v22, v22
	v_mul_f32_e32 v23, v23, v23
	buffer_store_dwordx4 v[16:19], v52, s[12:15], 0 offen sc1
	s_nop 1
	v_cvt_pk_bf16_f32 v16, v20, v21
	v_cvt_pk_bf16_f32 v17, v22, v23
	v_cvt_pk_bf16_f32 v18, v34, v35
	v_cvt_pk_bf16_f32 v19, v36, v37
	buffer_store_dwordx4 v[16:19], v52, s[12:15], 0 offen offset:256 sc1
	s_nop 0
	s_waitcnt vmcnt(8)
; __device__ __forceinline__ u32x4 pack8(const f32x4 v0, const f32x4 v1) { u32x4 w; w.x = pk2(v0[0], v0[1]); w.y = pk2(v0[2], v0[3]); w.z = pk2(v1[0], v1[1]); w.w = pk2(v1[2], v1[3]); return w; }
; __device__ __forceinline__ float row_rstd(const float* ssq, int row) {
;     const f32x4* p = (const f32x4*)(ssq + (size_t)row * 16);
;     const f32x4 a = p[0], b = p[1], c = p[2], d = p[3];
;     const float s = ((a[0] + a[1]) + (a[2] + a[3])) + ((b[0] + b[1]) + (b[2] + b[3])) + ((c[0] + c[1]) + (c[2] + c[3])) + ((d[0] + d[1]) + (d[2] + d[3]));
;     return rsqrtf(s * (1.0f / 1024.0f) + 1e-6f);
;     __device__ __forceinline__ void operator()(const f32x4 (&acc)[2][2][4][2], const Unit& u, int wr, int wc, int fr, int fq) const {
;     ...
;         const int row0 = row_off + u.pm * 256 + wr * 64 + fr, col0 = u.pn * 256 + wc * 32 + 8 * fq;
; #pragma unroll
;         for (int ai = 0; ai < 2; ++ai)
; #pragma unroll
;             for (int m = 0; m < 4; ++m) {
;                 const int row = row0 + ai * 128 + m * 16; const float rs = row_rstd(ssq, row);
; #pragma unroll
;                 for (int bj = 0; bj < 2; ++bj) { f32x4 v0 = acc[ai][bj][m][0] * rs, v1 = acc[ai][bj][m][1] * rs;
; #pragma unroll
;                     for (int j = 0; j < 4; ++j) { const float a = fmaxf(v0[j], 0.f), b = fmaxf(v1[j], 0.f); v0[j] = a * a; v1[j] = b * b; }
;                     __builtin_amdgcn_raw_buffer_store_b128(pack8(v0, v1), rsrc, (unsigned)(((size_t)row * DFF + col0 + bj * 128) * 2), 0, 16  ); }
;             }
;         asm volatile("s_waitcnt vmcnt(0)" ::: "memory");
;         if (fr == 0 && fq == 0) (void)__hip_atomic_fetch_add(ready + 64 * (pm_off + u.pm), 1u, __ATOMIC_RELAXED, __HIP_MEMORY_SCOPE_AGENT);
	v_mov_b32_e32 v16, v236
	v_mov_b32_e32 v17, v237
	v_mov_b32_e32 v18, v238
	v_mov_b32_e32 v19, v239
	v_mov_b32_e32 v20, v240
	v_mov_b32_e32 v21, v241
	v_mov_b32_e32 v22, v242
	v_mov_b32_e32 v23, v243
	v_mov_b32_e32 v24, v244
	v_mov_b32_e32 v25, v245
	v_mov_b32_e32 v26, v246
	v_mov_b32_e32 v27, v247
	v_mov_b32_e32 v28, v248
	v_mov_b32_e32 v29, v249
	v_mov_b32_e32 v30, v250
	v_mov_b32_e32 v31, v251
	v_mov_b32_e32 v32, v17
	v_mov_b32_e32 v33, v18
	v_mov_b32_e32 v17, v19
	v_mov_b32_e32 v18, v21
	v_mov_b32_e32 v19, v22
	v_mov_b32_e32 v21, v23
	v_pk_add_f32 v[16:17], v[32:33], v[16:17]
	v_pk_add_f32 v[18:19], v[18:19], v[20:21]
	v_pk_add_f32 v[16:17], v[16:17], v[16:17] op_sel:[0,1] op_sel_hi:[1,0]
	v_pk_add_f32 v[18:19], v[18:19], v[18:19] op_sel:[0,1] op_sel_hi:[1,0]
	v_add_f32_e32 v22, v24, v25
	v_add_f32_e32 v24, v26, v27
	v_mov_b32_e32 v23, v30
	v_mov_b32_e32 v25, v31
	v_mov_b32_e32 v17, v28
	v_mov_b32_e32 v19, v29
	v_pk_add_f32 v[20:21], v[22:23], v[24:25]
	v_pk_add_f32 v[16:17], v[16:17], v[18:19]
	s_nop 0
	v_pk_add_f32 v[16:17], v[16:17], v[20:21]
	s_nop 0
	v_add_f32_e32 v16, v16, v17
	v_fmamk_f32 v16, v16, 0x3a800000, v154
	v_mul_f32_e32 v17, 0x4b800000, v16
	v_cmp_gt_f32_e32 vcc, s63, v16
	s_nop 1
	v_cndmask_b32_e32 v16, v16, v17, vcc
	v_rsq_f32_e32 v16, v16
	v_lshl_add_u32 v17, v48, 13, v147
	v_mul_f32_e32 v18, 0x45800000, v16
	v_cndmask_b32_e32 v16, v16, v18, vcc
	v_pk_mul_f32 v[14:15], v[14:15], v[16:17] op_sel_hi:[1,0]
	v_pk_mul_f32 v[12:13], v[12:13], v[16:17] op_sel_hi:[1,0]
	v_pk_mul_f32 v[10:11], v[10:11], v[16:17] op_sel_hi:[1,0]
	v_pk_mul_f32 v[8:9], v[8:9], v[16:17] op_sel_hi:[1,0]
	v_pk_mul_f32 v[2:3], v[2:3], v[16:17] op_sel_hi:[1,0]
	v_pk_mul_f32 v[0:1], v[0:1], v[16:17] op_sel_hi:[1,0]
	v_pk_mul_f32 v[6:7], v[6:7], v[16:17] op_sel_hi:[1,0]
	v_pk_mul_f32 v[4:5], v[4:5], v[16:17] op_sel_hi:[1,0]
	v_max_f32_e32 v12, 0, v12
	v_max_f32_e32 v8, 0, v8
	v_max_f32_e32 v13, 0, v13
	v_max_f32_e32 v9, 0, v9
	v_max_f32_e32 v14, 0, v14
	v_max_f32_e32 v10, 0, v10
	v_max_f32_e32 v15, 0, v15
	v_max_f32_e32 v11, 0, v11
	v_max_f32_e32 v0, 0, v0
	v_max_f32_e32 v1, 0, v1
	v_max_f32_e32 v2, 0, v2
	v_max_f32_e32 v3, 0, v3
	v_max_f32_e32 v4, 0, v4
	v_max_f32_e32 v5, 0, v5
	v_max_f32_e32 v6, 0, v6
	v_max_f32_e32 v7, 0, v7
	v_mul_f32_e32 v12, v12, v12
	v_mul_f32_e32 v8, v8, v8
	v_mul_f32_e32 v13, v13, v13
	v_mul_f32_e32 v9, v9, v9
	v_mul_f32_e32 v14, v14, v14
	v_mul_f32_e32 v10, v10, v10
	v_mul_f32_e32 v15, v15, v15
	v_mul_f32_e32 v11, v11, v11
	v_mul_f32_e32 v16, v0, v0
	v_mul_f32_e32 v18, v1, v1
	v_mul_f32_e32 v19, v2, v2
	v_mul_f32_e32 v20, v3, v3
	v_cvt_pk_bf16_f32 v0, v12, v13
	v_cvt_pk_bf16_f32 v1, v14, v15
	v_cvt_pk_bf16_f32 v2, v8, v9
	v_cvt_pk_bf16_f32 v3, v10, v11
	v_mul_f32_e32 v4, v4, v4
	v_mul_f32_e32 v5, v5, v5
	v_mul_f32_e32 v6, v6, v6
	v_mul_f32_e32 v7, v7, v7
	buffer_store_dwordx4 v[0:3], v17, s[12:15], 0 offen sc1
	s_nop 1
	v_cvt_pk_bf16_f32 v0, v4, v5
	v_cvt_pk_bf16_f32 v1, v6, v7
	v_cvt_pk_bf16_f32 v2, v16, v18
	v_cvt_pk_bf16_f32 v3, v19, v20
	buffer_store_dwordx4 v[0:3], v17, s[12:15], 0 offen offset:256 sc1
	s_waitcnt vmcnt(0)
	s_and_saveexec_b64 s[36:37], s[6:7]
	s_cbranch_execz .LBB0_2091
	s_mov_b64 s[38:39], exec
	v_mbcnt_lo_u32_b32 v0, s38, 0
	v_mbcnt_hi_u32_b32 v0, s39, v0
	v_cmp_eq_u32_e32 vcc, 0, v0
	s_and_b64 s[40:41], exec, vcc
	s_mov_b64 exec, s[40:41]
	s_cbranch_execz .LBB0_2091
	s_lshl_b32 s40, s68, 6
	s_ashr_i32 s41, s40, 31
	s_lshl_b64 s[40:41], s[40:41], 2
	s_add_u32 s40, s66, s40
	s_addc_u32 s41, s67, s41
	s_bcnt1_i32_b64 s25, s[38:39]
	v_mov_b32_e32 v0, s25
	global_atomic_add v131, v0, s[40:41]
	s_branch .LBB0_2091

; #define PG8_STAGE(bufoff, gbase, voff) do { _Pragma("unroll") for (int _i = 0; _i < 2; ++_i) \
;         __builtin_amdgcn_global_load_lds((const unsigned*)((const char*)(gbase) + (voff)[_i]), (LAS unsigned*)(lds + (bufoff) + ldsw + _i * 8192), 16, 0, 0); } while (0)
; #define PG8_LDA(dst, b, h) do { _Pragma("unroll") for (int m = 0; m < 4; ++m) _Pragma("unroll") for (int k = 0; k < 2; ++k) dst[m][k] = *(const LAS bf16x8*)(lds + PG8_SA(b, h) + aoff + m * 2048 + k * 1024); } while (0)
; #define PG8_LDB(dst, b, h) do { _Pragma("unroll") for (int n = 0; n < 2; ++n) _Pragma("unroll") for (int k = 0; k < 2; ++k) dst[n][k] = *(const LAS bf16x8*)(lds + PG8_SB(b, h) + boff + n * 2048 + k * 1024); } while (0)
; #define PG8_MMA(ai, bj, At, Bt) do { __builtin_amdgcn_s_setprio(1); _Pragma("unroll") for (int m = 0; m < 4; ++m) _Pragma("unroll") for (int n = 0; n < 2; ++n) _Pragma("unroll") for (int k = 0; k < 2; ++k) \
;         acc[ai][bj][m][n] = __builtin_amdgcn_mfma_f32_16x16x32_bf16(Bt[n][k], At[m][k], acc[ai][bj][m][n], 0, 0, 0); __builtin_amdgcn_s_setprio(0); } while (0)
; #define PG8_WAIT_V(n) asm volatile("s_waitcnt vmcnt(" #n ")" ::: "memory")
; #define PG8_WAIT_L(n) asm volatile("s_waitcnt lgkmcnt(" #n ")" ::: "memory")
; #define PG8_BAR __builtin_amdgcn_s_barrier()
; #define PG8_SCHED __builtin_amdgcn_sched_barrier(0)
;     ...
;             PG8_LDB(B0, 0, 0); PG8_SCHED; PG8_LDA(At, 0, 0); PG8_STAGE(PG8_SA(1, 1), a1 + hA, voffA);
;             PG8_WAIT_L(8); PG8_BAR; PG8_WAIT_L(0); PG8_MMA(0, 0, At, B0); PG8_BAR; PG8_SCHED;
;             PG8_LDB(B1, 0, 1); PG8_STAGE(PG8_SB(0, 0), b2, voffB);
;             PG8_BAR; PG8_WAIT_L(0); PG8_MMA(0, 1, At, B1); PG8_BAR;
;             PG8_LDA(At, 0, 1); PG8_STAGE(PG8_SA(0, 0), a2, voffA);
;             PG8_BAR; PG8_WAIT_L(0); PG8_MMA(1, 0, At, B0); PG8_BAR; PG8_SCHED;
;             PG8_STAGE(PG8_SB(0, 1), b2 + hB, voffB);
;             PG8_WAIT_V(6); PG8_BAR; PG8_MMA(1, 1, At, B1); PG8_BAR;
.LBB0_2122:
	ds_read_b128 v[150:153], v143
	ds_read_b128 v[154:157], v143 offset:1024
	ds_read_b128 v[158:161], v143 offset:2048
	ds_read_b128 v[162:165], v143 offset:3072
	s_add_u32 s36, s34, 0xfffc0080
	s_addc_u32 s37, s35, -1
	s_cmp_eq_u32 s71, 12
	s_cselect_b32 s39, s21, s37
	s_cselect_b32 s38, s44, s36
	s_cselect_b32 s37, s29, s70
	s_cselect_b32 s36, s45, s69
	v_lshl_add_u64 v[202:203], s[34:35], 0, v[138:139]
	s_add_i32 m0, s53, 0xc000
	ds_read_b128 v[170:173], v146
	ds_read_b128 v[174:177], v146 offset:1024
	ds_read_b128 v[178:181], v146 offset:2048
	ds_read_b128 v[182:185], v146 offset:3072
	ds_read_b128 v[186:189], v146 offset:4096
	ds_read_b128 v[190:193], v146 offset:5120
	ds_read_b128 v[194:197], v146 offset:6144
	ds_read_b128 v[198:201], v146 offset:7168
	global_load_lds_dwordx4 v[202:203], off
	v_lshl_add_u64 v[202:203], s[34:35], 0, v[136:137]
	s_add_i32 m0, s53, 0xe000
	s_nop 0
	global_load_lds_dwordx4 v[202:203], off
	s_waitcnt lgkmcnt(8)
	s_barrier
	s_waitcnt lgkmcnt(0)
	s_setprio 1
	s_waitcnt lgkmcnt(0)
	v_mfma_f32_16x16x32_bf16 v[124:127], v[150:153], v[170:173], v[124:127]
	v_mfma_f32_16x16x32_bf16 v[120:123], v[158:161], v[170:173], v[120:123]
	v_mfma_f32_16x16x32_bf16 v[108:111], v[150:153], v[178:181], v[108:111]
	v_mfma_f32_16x16x32_bf16 v[104:107], v[158:161], v[178:181], v[104:107]
	v_mfma_f32_16x16x32_bf16 v[92:95], v[150:153], v[186:189], v[92:95]
	v_mfma_f32_16x16x32_bf16 v[88:91], v[158:161], v[186:189], v[88:91]
	v_mfma_f32_16x16x32_bf16 v[76:79], v[150:153], v[194:197], v[76:79]
	v_mfma_f32_16x16x32_bf16 v[72:75], v[158:161], v[194:197], v[72:75]
	v_mfma_f32_16x16x32_bf16 v[124:127], v[154:157], v[174:177], v[124:127]
	v_mfma_f32_16x16x32_bf16 v[120:123], v[162:165], v[174:177], v[120:123]
	v_mfma_f32_16x16x32_bf16 v[108:111], v[154:157], v[182:185], v[108:111]
	v_mfma_f32_16x16x32_bf16 v[104:107], v[162:165], v[182:185], v[104:107]
	v_mfma_f32_16x16x32_bf16 v[92:95], v[154:157], v[190:193], v[92:95]
	v_mfma_f32_16x16x32_bf16 v[88:91], v[162:165], v[190:193], v[88:91]
	v_mfma_f32_16x16x32_bf16 v[76:79], v[154:157], v[198:201], v[76:79]
	v_mfma_f32_16x16x32_bf16 v[72:75], v[162:165], v[198:201], v[72:75]
	s_setprio 0
	s_barrier
	s_add_i32 s72, s61, s52
	v_lshl_add_u64 v[218:219], s[36:37], 0, v[130:131]
	s_mov_b32 m0, s72
	ds_read_b128 v[202:205], v147
	ds_read_b128 v[206:209], v147 offset:1024
	ds_read_b128 v[210:213], v147 offset:2048
	ds_read_b128 v[214:217], v147 offset:3072
	global_load_lds_dwordx4 v[218:219], off
	v_lshl_add_u64 v[220:221], s[36:37], 0, v[134:135]
	s_add_i32 m0, s72, 0x2000
	s_nop 0
	global_load_lds_dwordx4 v[220:221], off
	s_barrier
	s_waitcnt lgkmcnt(0)
	s_setprio 1
	s_waitcnt lgkmcnt(0)
	v_mfma_f32_16x16x32_bf16 v[116:119], v[202:205], v[170:173], v[116:119]
	v_mfma_f32_16x16x32_bf16 v[112:115], v[210:213], v[170:173], v[112:115]
	v_mfma_f32_16x16x32_bf16 v[100:103], v[202:205], v[178:181], v[100:103]
	v_mfma_f32_16x16x32_bf16 v[96:99], v[210:213], v[178:181], v[96:99]
	v_mfma_f32_16x16x32_bf16 v[84:87], v[202:205], v[186:189], v[84:87]
	v_mfma_f32_16x16x32_bf16 v[80:83], v[210:213], v[186:189], v[80:83]
	v_mfma_f32_16x16x32_bf16 v[68:71], v[202:205], v[194:197], v[68:71]
	v_mfma_f32_16x16x32_bf16 v[64:67], v[210:213], v[194:197], v[64:67]
	v_mfma_f32_16x16x32_bf16 v[116:119], v[206:209], v[174:177], v[116:119]
	v_mfma_f32_16x16x32_bf16 v[112:115], v[214:217], v[174:177], v[112:115]
	v_mfma_f32_16x16x32_bf16 v[100:103], v[206:209], v[182:185], v[100:103]
	v_mfma_f32_16x16x32_bf16 v[96:99], v[214:217], v[182:185], v[96:99]
	v_mfma_f32_16x16x32_bf16 v[84:87], v[206:209], v[190:193], v[84:87]
	v_mfma_f32_16x16x32_bf16 v[80:83], v[214:217], v[190:193], v[80:83]
	v_mfma_f32_16x16x32_bf16 v[68:71], v[206:209], v[198:201], v[68:71]
	v_mfma_f32_16x16x32_bf16 v[64:67], v[214:217], v[198:201], v[64:67]
	s_setprio 0
	s_mov_b32 m0, s53
	v_lshl_add_u64 v[222:223], s[38:39], 0, v[128:129]
	s_barrier
	ds_read_b128 v[170:173], v146 offset:16384
	ds_read_b128 v[174:177], v146 offset:17408
	ds_read_b128 v[178:181], v146 offset:18432
	ds_read_b128 v[182:185], v146 offset:19456
	ds_read_b128 v[186:189], v146 offset:20480
	ds_read_b128 v[190:193], v146 offset:21504
	ds_read_b128 v[194:197], v146 offset:22528
	ds_read_b128 v[198:201], v146 offset:23552
	global_load_lds_dwordx4 v[222:223], off
	v_lshl_add_u64 v[224:225], s[38:39], 0, v[132:133]
	s_mov_b32 m0, s54
	s_nop 0
	global_load_lds_dwordx4 v[224:225], off
	s_barrier
	s_waitcnt lgkmcnt(0)
	s_setprio 1
	s_waitcnt lgkmcnt(0)
	v_mfma_f32_16x16x32_bf16 v[60:63], v[150:153], v[170:173], v[60:63]
	v_mfma_f32_16x16x32_bf16 v[56:59], v[158:161], v[170:173], v[56:59]
	v_mfma_f32_16x16x32_bf16 v[44:47], v[150:153], v[178:181], v[44:47]
	v_mfma_f32_16x16x32_bf16 v[40:43], v[158:161], v[178:181], v[40:43]
	v_mfma_f32_16x16x32_bf16 v[28:31], v[150:153], v[186:189], v[28:31]
	v_mfma_f32_16x16x32_bf16 v[24:27], v[158:161], v[186:189], v[24:27]
	v_mfma_f32_16x16x32_bf16 v[12:15], v[150:153], v[194:197], v[12:15]
	v_mfma_f32_16x16x32_bf16 v[8:11], v[158:161], v[194:197], v[8:11]
	v_mfma_f32_16x16x32_bf16 v[60:63], v[154:157], v[174:177], v[60:63]
	v_mfma_f32_16x16x32_bf16 v[56:59], v[162:165], v[174:177], v[56:59]
	v_mfma_f32_16x16x32_bf16 v[44:47], v[154:157], v[182:185], v[44:47]
	v_mfma_f32_16x16x32_bf16 v[40:43], v[162:165], v[182:185], v[40:43]
	v_mfma_f32_16x16x32_bf16 v[28:31], v[154:157], v[190:193], v[28:31]
	v_mfma_f32_16x16x32_bf16 v[24:27], v[162:165], v[190:193], v[24:27]
	v_mfma_f32_16x16x32_bf16 v[12:15], v[154:157], v[198:201], v[12:15]
	v_mfma_f32_16x16x32_bf16 v[8:11], v[162:165], v[198:201], v[8:11]
	s_setprio 0
	s_barrier
; #define PG8_STAGE(bufoff, gbase, voff) do { _Pragma("unroll") for (int _i = 0; _i < 2; ++_i) \
;         __builtin_amdgcn_global_load_lds((const unsigned*)((const char*)(gbase) + (voff)[_i]), (LAS unsigned*)(lds + (bufoff) + ldsw + _i * 8192), 16, 0, 0); } while (0)
; #define PG8_LDA(dst, b, h) do { _Pragma("unroll") for (int m = 0; m < 4; ++m) _Pragma("unroll") for (int k = 0; k < 2; ++k) dst[m][k] = *(const LAS bf16x8*)(lds + PG8_SA(b, h) + aoff + m * 2048 + k * 1024); } while (0)
; #define PG8_LDB(dst, b, h) do { _Pragma("unroll") for (int n = 0; n < 2; ++n) _Pragma("unroll") for (int k = 0; k < 2; ++k) dst[n][k] = *(const LAS bf16x8*)(lds + PG8_SB(b, h) + boff + n * 2048 + k * 1024); } while (0)
; #define PG8_MMA(ai, bj, At, Bt) do { __builtin_amdgcn_s_setprio(1); _Pragma("unroll") for (int m = 0; m < 4; ++m) _Pragma("unroll") for (int n = 0; n < 2; ++n) _Pragma("unroll") for (int k = 0; k < 2; ++k) \
;         acc[ai][bj][m][n] = __builtin_amdgcn_mfma_f32_16x16x32_bf16(Bt[n][k], At[m][k], acc[ai][bj][m][n], 0, 0, 0); __builtin_amdgcn_s_setprio(0); } while (0)
; #define PG8_WAIT_V(n) asm volatile("s_waitcnt vmcnt(" #n ")" ::: "memory")
; #define PG8_WAIT_L(n) asm volatile("s_waitcnt lgkmcnt(" #n ")" ::: "memory")
; #define PG8_BAR __builtin_amdgcn_s_barrier()
; #define PG8_SCHED __builtin_amdgcn_sched_barrier(0)
;     ...
;             PG8_STAGE(PG8_SB(0, 1), b2 + hB, voffB);
;             PG8_WAIT_V(6); PG8_BAR; PG8_MMA(1, 1, At, B1); PG8_BAR;
;             PG8_LDB(B0, 1, 0); PG8_SCHED; PG8_LDA(At, 1, 0); PG8_STAGE(PG8_SA(0, 1), a2 + hA, voffA);
;             PG8_WAIT_L(8); PG8_BAR; PG8_WAIT_L(0); PG8_MMA(0, 0, At, B0); PG8_BAR; PG8_SCHED;
;             PG8_LDB(B1, 1, 1); PG8_STAGE(PG8_SB(1, 0), b3, voffB);
;             PG8_BAR; PG8_WAIT_L(0); PG8_MMA(0, 1, At, B1); PG8_BAR;
;             PG8_LDA(At, 1, 1); PG8_STAGE(PG8_SA(1, 0), a3, voffA);
;             PG8_BAR; PG8_WAIT_L(0); PG8_MMA(1, 0, At, B0); PG8_BAR; PG8_SCHED;
	s_add_u32 s72, s36, 0x40000
	s_addc_u32 s73, s37, 0
	s_add_i32 s74, s62, s52
	v_lshl_add_u64 v[150:151], s[72:73], 0, v[130:131]
	s_mov_b32 m0, s74
	s_nop 0
	global_load_lds_dwordx4 v[150:151], off
	v_lshl_add_u64 v[150:151], s[72:73], 0, v[134:135]
	s_add_i32 m0, s74, 0x2000
	s_nop 0
	global_load_lds_dwordx4 v[150:151], off
	s_waitcnt vmcnt(6)
	s_barrier
	s_setprio 1
	v_mfma_f32_16x16x32_bf16 v[52:55], v[202:205], v[170:173], v[52:55]
	v_mfma_f32_16x16x32_bf16 v[48:51], v[210:213], v[170:173], v[48:51]
	v_mfma_f32_16x16x32_bf16 v[36:39], v[202:205], v[178:181], v[36:39]
	v_mfma_f32_16x16x32_bf16 v[32:35], v[210:213], v[178:181], v[32:35]
	v_mfma_f32_16x16x32_bf16 v[20:23], v[202:205], v[186:189], v[20:23]
	v_mfma_f32_16x16x32_bf16 v[16:19], v[210:213], v[186:189], v[16:19]
	v_mfma_f32_16x16x32_bf16 v[4:7], v[202:205], v[194:197], v[4:7]
	v_mfma_f32_16x16x32_bf16 v[0:3], v[210:213], v[194:197], v[0:3]
	v_mfma_f32_16x16x32_bf16 v[52:55], v[206:209], v[174:177], v[52:55]
	v_mfma_f32_16x16x32_bf16 v[48:51], v[214:217], v[174:177], v[48:51]
	v_mfma_f32_16x16x32_bf16 v[36:39], v[206:209], v[182:185], v[36:39]
	v_mfma_f32_16x16x32_bf16 v[32:35], v[214:217], v[182:185], v[32:35]
	v_mfma_f32_16x16x32_bf16 v[20:23], v[206:209], v[190:193], v[20:23]
	v_mfma_f32_16x16x32_bf16 v[16:19], v[214:217], v[190:193], v[16:19]
	v_mfma_f32_16x16x32_bf16 v[4:7], v[206:209], v[198:201], v[4:7]
	v_mfma_f32_16x16x32_bf16 v[0:3], v[214:217], v[198:201], v[0:3]
	s_setprio 0
	s_add_i32 s72, 0, 0x18000
	v_add_u32_e32 v149, s72, v141
	s_barrier
	ds_read_b128 v[150:153], v149
	ds_read_b128 v[154:157], v149 offset:1024
	ds_read_b128 v[158:161], v149 offset:2048
	ds_read_b128 v[162:165], v149 offset:3072
	s_add_u32 s38, s38, 0x40000
	s_addc_u32 s39, s39, 0
	s_mov_b32 m0, s55
	v_lshl_add_u64 v[202:203], s[38:39], 0, v[128:129]
	ds_read_b128 v[170:173], v146 offset:32768
	ds_read_b128 v[174:177], v146 offset:33792
	ds_read_b128 v[178:181], v146 offset:34816
	ds_read_b128 v[182:185], v146 offset:35840
	ds_read_b128 v[186:189], v146 offset:36864
	ds_read_b128 v[190:193], v146 offset:37888
	ds_read_b128 v[194:197], v146 offset:38912
	ds_read_b128 v[198:201], v146 offset:39936
	global_load_lds_dwordx4 v[202:203], off
	v_lshl_add_u64 v[202:203], s[38:39], 0, v[132:133]
	s_mov_b32 m0, s56
	s_nop 0
	global_load_lds_dwordx4 v[202:203], off
	s_waitcnt lgkmcnt(8)
	s_barrier
	s_waitcnt lgkmcnt(0)
	s_setprio 1
	s_waitcnt lgkmcnt(0)
	v_mfma_f32_16x16x32_bf16 v[124:127], v[150:153], v[170:173], v[124:127]
	v_mfma_f32_16x16x32_bf16 v[120:123], v[158:161], v[170:173], v[120:123]
	v_mfma_f32_16x16x32_bf16 v[108:111], v[150:153], v[178:181], v[108:111]
	v_mfma_f32_16x16x32_bf16 v[104:107], v[158:161], v[178:181], v[104:107]
	v_mfma_f32_16x16x32_bf16 v[92:95], v[150:153], v[186:189], v[92:95]
	v_mfma_f32_16x16x32_bf16 v[88:91], v[158:161], v[186:189], v[88:91]
	v_mfma_f32_16x16x32_bf16 v[76:79], v[150:153], v[194:197], v[76:79]
	v_mfma_f32_16x16x32_bf16 v[72:75], v[158:161], v[194:197], v[72:75]
	v_mfma_f32_16x16x32_bf16 v[124:127], v[154:157], v[174:177], v[124:127]
	v_mfma_f32_16x16x32_bf16 v[120:123], v[162:165], v[174:177], v[120:123]
	v_mfma_f32_16x16x32_bf16 v[108:111], v[154:157], v[182:185], v[108:111]
	v_mfma_f32_16x16x32_bf16 v[104:107], v[162:165], v[182:185], v[104:107]
	v_mfma_f32_16x16x32_bf16 v[92:95], v[154:157], v[190:193], v[92:95]
	v_mfma_f32_16x16x32_bf16 v[88:91], v[162:165], v[190:193], v[88:91]
	v_mfma_f32_16x16x32_bf16 v[76:79], v[154:157], v[198:201], v[76:79]
	v_mfma_f32_16x16x32_bf16 v[72:75], v[162:165], v[198:201], v[72:75]
	s_setprio 0
	s_barrier
	s_add_i32 s38, 0, 0x1c000
	s_add_i32 s39, s72, s52
	v_add_u32_e32 v149, s38, v141
	v_lshl_add_u64 v[218:219], v[218:219], 0, s[22:23]
	s_mov_b32 m0, s39
	ds_read_b128 v[202:205], v149
	ds_read_b128 v[206:209], v149 offset:1024
	ds_read_b128 v[210:213], v149 offset:2048
	ds_read_b128 v[214:217], v149 offset:3072
	global_load_lds_dwordx4 v[218:219], off
	v_lshl_add_u64 v[218:219], v[220:221], 0, s[22:23]
	s_add_i32 m0, s39, 0x2000
	s_nop 0
	global_load_lds_dwordx4 v[218:219], off
	s_barrier
	s_waitcnt lgkmcnt(0)
	s_setprio 1
	s_waitcnt lgkmcnt(0)
	v_mfma_f32_16x16x32_bf16 v[116:119], v[202:205], v[170:173], v[116:119]
	v_mfma_f32_16x16x32_bf16 v[112:115], v[210:213], v[170:173], v[112:115]
	v_mfma_f32_16x16x32_bf16 v[100:103], v[202:205], v[178:181], v[100:103]
	v_mfma_f32_16x16x32_bf16 v[96:99], v[210:213], v[178:181], v[96:99]
	v_mfma_f32_16x16x32_bf16 v[84:87], v[202:205], v[186:189], v[84:87]
	v_mfma_f32_16x16x32_bf16 v[80:83], v[210:213], v[186:189], v[80:83]
	v_mfma_f32_16x16x32_bf16 v[68:71], v[202:205], v[194:197], v[68:71]
	v_mfma_f32_16x16x32_bf16 v[64:67], v[210:213], v[194:197], v[64:67]
	v_mfma_f32_16x16x32_bf16 v[116:119], v[206:209], v[174:177], v[116:119]
	v_mfma_f32_16x16x32_bf16 v[112:115], v[214:217], v[174:177], v[112:115]
	v_mfma_f32_16x16x32_bf16 v[100:103], v[206:209], v[182:185], v[100:103]
	v_mfma_f32_16x16x32_bf16 v[96:99], v[214:217], v[182:185], v[96:99]
	v_mfma_f32_16x16x32_bf16 v[84:87], v[206:209], v[190:193], v[84:87]
	v_mfma_f32_16x16x32_bf16 v[80:83], v[214:217], v[190:193], v[80:83]
	v_mfma_f32_16x16x32_bf16 v[68:71], v[206:209], v[198:201], v[68:71]
	v_mfma_f32_16x16x32_bf16 v[64:67], v[214:217], v[198:201], v[64:67]
	s_setprio 0
	s_mov_b32 m0, s58
	v_lshl_add_u64 v[218:219], v[222:223], 0, s[22:23]
	s_barrier
	ds_read_b128 v[170:173], v146 offset:49152
	ds_read_b128 v[174:177], v146 offset:50176
	ds_read_b128 v[178:181], v146 offset:51200
	ds_read_b128 v[182:185], v146 offset:52224
	ds_read_b128 v[186:189], v146 offset:53248
	ds_read_b128 v[190:193], v146 offset:54272
	ds_read_b128 v[194:197], v146 offset:55296
	ds_read_b128 v[198:201], v146 offset:56320
	global_load_lds_dwordx4 v[218:219], off
	v_lshl_add_u64 v[218:219], v[224:225], 0, s[22:23]
	s_mov_b32 m0, s59
	s_nop 0
	global_load_lds_dwordx4 v[218:219], off
	s_barrier
; #define PG8_STAGE(bufoff, gbase, voff) do { _Pragma("unroll") for (int _i = 0; _i < 2; ++_i) \
;         __builtin_amdgcn_global_load_lds((const unsigned*)((const char*)(gbase) + (voff)[_i]), (LAS unsigned*)(lds + (bufoff) + ldsw + _i * 8192), 16, 0, 0); } while (0)
; #define PG8_LDA(dst, b, h) do { _Pragma("unroll") for (int m = 0; m < 4; ++m) _Pragma("unroll") for (int k = 0; k < 2; ++k) dst[m][k] = *(const LAS bf16x8*)(lds + PG8_SA(b, h) + aoff + m * 2048 + k * 1024); } while (0)
; #define PG8_LDB(dst, b, h) do { _Pragma("unroll") for (int n = 0; n < 2; ++n) _Pragma("unroll") for (int k = 0; k < 2; ++k) dst[n][k] = *(const LAS bf16x8*)(lds + PG8_SB(b, h) + boff + n * 2048 + k * 1024); } while (0)
; #define PG8_MMA(ai, bj, At, Bt) do { __builtin_amdgcn_s_setprio(1); _Pragma("unroll") for (int m = 0; m < 4; ++m) _Pragma("unroll") for (int n = 0; n < 2; ++n) _Pragma("unroll") for (int k = 0; k < 2; ++k) \
;         acc[ai][bj][m][n] = __builtin_amdgcn_mfma_f32_16x16x32_bf16(Bt[n][k], At[m][k], acc[ai][bj][m][n], 0, 0, 0); __builtin_amdgcn_s_setprio(0); } while (0)
; #define PG8_WAIT_V(n) asm volatile("s_waitcnt vmcnt(" #n ")" ::: "memory")
; #define PG8_WAIT_L(n) asm volatile("s_waitcnt lgkmcnt(" #n ")" ::: "memory")
; #define PG8_BAR __builtin_amdgcn_s_barrier()
; #define PG8_SCHED __builtin_amdgcn_sched_barrier(0)
;     ...
;             PG8_WAIT_L(8); PG8_BAR; PG8_WAIT_L(0); PG8_MMA(0, 0, At, B0); PG8_BAR; PG8_SCHED;
;             PG8_LDB(B1, 1, 1); PG8_STAGE(PG8_SB(1, 0), b3, voffB);
;             PG8_BAR; PG8_WAIT_L(0); PG8_MMA(0, 1, At, B1); PG8_BAR;
;             PG8_LDA(At, 1, 1); PG8_STAGE(PG8_SA(1, 0), a3, voffA);
;             PG8_BAR; PG8_WAIT_L(0); PG8_MMA(1, 0, At, B0); PG8_BAR; PG8_SCHED;
;             PG8_STAGE(PG8_SB(1, 1), b3 + hB, voffB);
;             PG8_WAIT_V(6); PG8_BAR; PG8_MMA(1, 1, At, B1); PG8_BAR;
; __device__ __forceinline__ float row_rstd(const float* ssq, int row) {
;     const f32x4* p = (const f32x4*)(ssq + (size_t)row * 16);
;     const f32x4 a = p[0], b = p[1], c = p[2], d = p[3];
;     const float s = ((a[0] + a[1]) + (a[2] + a[3])) + ((b[0] + b[1]) + (b[2] + b[3])) + ((c[0] + c[1]) + (c[2] + c[3])) + ((d[0] + d[1]) + (d[2] + d[3]));
;     return rsqrtf(s * (1.0f / 1024.0f) + 1e-6f);
	s_waitcnt lgkmcnt(0)
	s_setprio 1
	s_waitcnt lgkmcnt(0)
	v_mfma_f32_16x16x32_bf16 v[60:63], v[150:153], v[170:173], v[60:63]
	v_mfma_f32_16x16x32_bf16 v[56:59], v[158:161], v[170:173], v[56:59]
	v_mfma_f32_16x16x32_bf16 v[44:47], v[150:153], v[178:181], v[44:47]
	v_mfma_f32_16x16x32_bf16 v[40:43], v[158:161], v[178:181], v[40:43]
	v_mfma_f32_16x16x32_bf16 v[28:31], v[150:153], v[186:189], v[28:31]
	v_mfma_f32_16x16x32_bf16 v[24:27], v[158:161], v[186:189], v[24:27]
	v_mfma_f32_16x16x32_bf16 v[12:15], v[150:153], v[194:197], v[12:15]
	v_mfma_f32_16x16x32_bf16 v[8:11], v[158:161], v[194:197], v[8:11]
	v_mfma_f32_16x16x32_bf16 v[60:63], v[154:157], v[174:177], v[60:63]
	v_mfma_f32_16x16x32_bf16 v[56:59], v[162:165], v[174:177], v[56:59]
	v_mfma_f32_16x16x32_bf16 v[44:47], v[154:157], v[182:185], v[44:47]
	v_mfma_f32_16x16x32_bf16 v[40:43], v[162:165], v[182:185], v[40:43]
	v_mfma_f32_16x16x32_bf16 v[28:31], v[154:157], v[190:193], v[28:31]
	v_mfma_f32_16x16x32_bf16 v[24:27], v[162:165], v[190:193], v[24:27]
	v_mfma_f32_16x16x32_bf16 v[12:15], v[154:157], v[198:201], v[12:15]
	v_mfma_f32_16x16x32_bf16 v[8:11], v[162:165], v[198:201], v[8:11]
	s_setprio 0
	s_barrier
	s_add_u32 s36, s36, 0x40080
	s_addc_u32 s37, s37, 0
	s_add_i32 s38, s38, s52
	v_lshl_add_u64 v[150:151], s[36:37], 0, v[130:131]
	s_mov_b32 m0, s38
	s_nop 0
	global_load_lds_dwordx4 v[150:151], off
	v_lshl_add_u64 v[150:151], s[36:37], 0, v[134:135]
	s_add_i32 m0, s38, 0x2000
	s_nop 0
	global_load_lds_dwordx4 v[150:151], off
	s_waitcnt vmcnt(6)
	s_barrier
	s_setprio 1
	v_mfma_f32_16x16x32_bf16 v[52:55], v[202:205], v[170:173], v[52:55]
	v_mfma_f32_16x16x32_bf16 v[48:51], v[210:213], v[170:173], v[48:51]
	v_mfma_f32_16x16x32_bf16 v[36:39], v[202:205], v[178:181], v[36:39]
	v_mfma_f32_16x16x32_bf16 v[32:35], v[210:213], v[178:181], v[32:35]
	v_mfma_f32_16x16x32_bf16 v[20:23], v[202:205], v[186:189], v[20:23]
	v_mfma_f32_16x16x32_bf16 v[16:19], v[210:213], v[186:189], v[16:19]
	v_mfma_f32_16x16x32_bf16 v[4:7], v[202:205], v[194:197], v[4:7]
	v_mfma_f32_16x16x32_bf16 v[0:3], v[210:213], v[194:197], v[0:3]
	v_mfma_f32_16x16x32_bf16 v[52:55], v[206:209], v[174:177], v[52:55]
	v_mfma_f32_16x16x32_bf16 v[48:51], v[214:217], v[174:177], v[48:51]
	v_mfma_f32_16x16x32_bf16 v[36:39], v[206:209], v[182:185], v[36:39]
	v_mfma_f32_16x16x32_bf16 v[32:35], v[214:217], v[182:185], v[32:35]
	v_mfma_f32_16x16x32_bf16 v[20:23], v[206:209], v[190:193], v[20:23]
	v_mfma_f32_16x16x32_bf16 v[16:19], v[214:217], v[190:193], v[16:19]
	v_mfma_f32_16x16x32_bf16 v[4:7], v[206:209], v[198:201], v[4:7]
	v_mfma_f32_16x16x32_bf16 v[0:3], v[214:217], v[198:201], v[0:3]
	s_setprio 0
	s_add_i32 s71, s71, 2
	s_add_u32 s69, s69, 0x100
	s_addc_u32 s70, s70, 0
	s_add_u32 s34, s34, 0x100
	s_addc_u32 s35, s35, 0
	s_cmp_gt_u32 s71, 13
	s_barrier
	s_cbranch_scc0 .LBB0_2122
	v_lshl_add_u32 v150, s68, 8, v140
	v_add_u32_e32 v164, 0x4000, v150
	v_ashrrev_i32_e32 v165, 31, v164
	v_lshlrev_b64 v[152:153], 6, v[164:165]
	v_lshl_add_u64 v[170:171], s[14:15], 0, v[152:153]
	v_subrev_u32_e32 v176, s14, v170
	v_add_u32_e32 v177, 0x0, v176
	global_load_dwordx4 v[178:181], v177, s[14:15]
	v_add_u32_e32 v177, 0x10, v176
	global_load_dwordx4 v[182:185], v177, s[14:15]
	v_add_u32_e32 v177, 0x20, v176
	global_load_dwordx4 v[186:189], v177, s[14:15]
	v_add_u32_e32 v177, 0x30, v176
	global_load_dwordx4 v[190:193], v177, s[14:15]
	v_add_u32_e32 v177, 0x400, v176
	global_load_dwordx4 v[194:197], v177, s[14:15]
	v_add_u32_e32 v177, 0x410, v176
	global_load_dwordx4 v[198:201], v177, s[14:15]
	v_add_u32_e32 v177, 0x420, v176
	global_load_dwordx4 v[202:205], v177, s[14:15]
	v_add_u32_e32 v177, 0x430, v176
	global_load_dwordx4 v[206:209], v177, s[14:15]
	v_add_u32_e32 v177, 0x800, v176
	global_load_dwordx4 v[210:213], v177, s[14:15]
	v_add_u32_e32 v177, 0x810, v176
	global_load_dwordx4 v[214:217], v177, s[14:15]
	v_add_u32_e32 v177, 0x820, v176
	global_load_dwordx4 v[232:235], v177, s[14:15]
	v_add_u32_e32 v177, 0x830, v176
	global_load_dwordx4 v[236:239], v177, s[14:15]
	v_add_u32_e32 v177, 0xc00, v176
	global_load_dwordx4 v[240:243], v177, s[14:15]
	v_add_u32_e32 v177, 0xc10, v176
	global_load_dwordx4 v[244:247], v177, s[14:15]
	v_add_u32_e32 v177, 0xc20, v176
	global_load_dwordx4 v[248:251], v177, s[14:15]
	v_add_u32_e32 v177, 0xc30, v176
	global_load_dwordx4 v[252:255], v177, s[14:15]
	s_nop 0
	v_lshl_or_b32 v149, s33, 9, v142
	v_lshl_add_u32 v151, v164, 13, v149
	v_add_u32_e32 v174, 0x4010, v150
	v_ashrrev_i32_e32 v175, 31, v174
	s_waitcnt vmcnt(12)
; __device__ __forceinline__ u32x4 pack8(const f32x4 v0, const f32x4 v1) { u32x4 w; w.x = pk2(v0[0], v0[1]); w.y = pk2(v0[2], v0[3]); w.z = pk2(v1[0], v1[1]); w.w = pk2(v1[2], v1[3]); return w; }
; __device__ __forceinline__ float row_rstd(const float* ssq, int row) {
;     const f32x4* p = (const f32x4*)(ssq + (size_t)row * 16);
;     const f32x4 a = p[0], b = p[1], c = p[2], d = p[3];
;     const float s = ((a[0] + a[1]) + (a[2] + a[3])) + ((b[0] + b[1]) + (b[2] + b[3])) + ((c[0] + c[1]) + (c[2] + c[3])) + ((d[0] + d[1]) + (d[2] + d[3]));
;     return rsqrtf(s * (1.0f / 1024.0f) + 1e-6f);
;     __device__ __forceinline__ void operator()(const f32x4 (&acc)[2][2][4][2], const Unit& u, int wr, int wc, int fr, int fq) const {
;     ...
;         const int row0 = row_off + u.pm * 256 + wr * 64 + fr, col0 = u.pn * 256 + wc * 32 + 8 * fq;
; #pragma unroll
;         for (int ai = 0; ai < 2; ++ai)
; #pragma unroll
;             for (int m = 0; m < 4; ++m) {
;                 const int row = row0 + ai * 128 + m * 16; const float rs = row_rstd(ssq, row);
; #pragma unroll
;                 for (int bj = 0; bj < 2; ++bj) { f32x4 v0 = acc[ai][bj][m][0] * rs, v1 = acc[ai][bj][m][1] * rs;
; #pragma unroll
;                     for (int j = 0; j < 4; ++j) { const float a = fmaxf(v0[j], 0.f), b = fmaxf(v1[j], 0.f); v0[j] = a * a; v1[j] = b * b; }
;                     __builtin_amdgcn_raw_buffer_store_b128(pack8(v0, v1), rsrc, (unsigned)(((size_t)row * DFF + col0 + bj * 128) * 2), 0, 16  ); }
	v_mov_b32_e32 v152, v178
	v_mov_b32_e32 v153, v179
	v_mov_b32_e32 v154, v180
	v_mov_b32_e32 v155, v181
	v_mov_b32_e32 v156, v182
	v_mov_b32_e32 v157, v183
	v_mov_b32_e32 v158, v184
	v_mov_b32_e32 v159, v185
	v_mov_b32_e32 v160, v186
	v_mov_b32_e32 v161, v187
	v_mov_b32_e32 v162, v188
	v_mov_b32_e32 v163, v189
	v_mov_b32_e32 v170, v190
	v_mov_b32_e32 v171, v191
	v_mov_b32_e32 v172, v192
	v_mov_b32_e32 v173, v193
	v_add_u32_e32 v177, 0x2000, v176
	global_load_dwordx4 v[178:181], v177, s[14:15]
	v_add_u32_e32 v177, 0x2010, v176
	global_load_dwordx4 v[182:185], v177, s[14:15]
	v_add_u32_e32 v177, 0x2020, v176
	global_load_dwordx4 v[186:189], v177, s[14:15]
	v_add_u32_e32 v177, 0x2030, v176
	global_load_dwordx4 v[190:193], v177, s[14:15]
	v_mov_b32_e32 v164, v153
	v_mov_b32_e32 v165, v154
	v_mov_b32_e32 v153, v155
	v_mov_b32_e32 v154, v157
	v_mov_b32_e32 v155, v158
	v_mov_b32_e32 v157, v159
	v_pk_add_f32 v[152:153], v[164:165], v[152:153]
	v_pk_add_f32 v[154:155], v[154:155], v[156:157]
	v_pk_add_f32 v[152:153], v[152:153], v[152:153] op_sel:[0,1] op_sel_hi:[1,0]
	v_pk_add_f32 v[154:155], v[154:155], v[154:155] op_sel:[0,1] op_sel_hi:[1,0]
	v_add_f32_e32 v158, v160, v161
	v_add_f32_e32 v160, v162, v163
	v_mov_b32_e32 v159, v172
	v_mov_b32_e32 v161, v173
	v_mov_b32_e32 v153, v170
	v_mov_b32_e32 v155, v171
	v_pk_add_f32 v[156:157], v[158:159], v[160:161]
	v_pk_add_f32 v[152:153], v[152:153], v[154:155]
	s_nop 0
	v_pk_add_f32 v[152:153], v[152:153], v[156:157]
	s_nop 0
	v_add_f32_e32 v152, v152, v153
	v_fmamk_f32 v152, v152, 0x3a800000, v148
	v_mul_f32_e32 v153, 0x4b800000, v152
	v_cmp_gt_f32_e32 vcc, s63, v152
	s_nop 1
	v_cndmask_b32_e32 v152, v152, v153, vcc
	v_rsq_f32_e32 v154, v152
	v_lshlrev_b64 v[152:153], 6, v[174:175]
	v_lshl_add_u64 v[152:153], s[14:15], 0, v[152:153]
	v_mul_f32_e32 v155, 0x45800000, v154
	v_cndmask_b32_e32 v154, v154, v155, vcc
	v_pk_mul_f32 v[126:127], v[126:127], v[154:155] op_sel_hi:[1,0]
	v_pk_mul_f32 v[124:125], v[124:125], v[154:155] op_sel_hi:[1,0]
	v_pk_mul_f32 v[122:123], v[122:123], v[154:155] op_sel_hi:[1,0]
	v_pk_mul_f32 v[120:121], v[120:121], v[154:155] op_sel_hi:[1,0]
	v_pk_mul_f32 v[114:115], v[114:115], v[154:155] op_sel_hi:[1,0]
	v_pk_mul_f32 v[112:113], v[112:113], v[154:155] op_sel_hi:[1,0]
	v_pk_mul_f32 v[118:119], v[118:119], v[154:155] op_sel_hi:[1,0]
	v_pk_mul_f32 v[116:117], v[116:117], v[154:155] op_sel_hi:[1,0]
	v_max_f32_e32 v124, 0, v124
	v_max_f32_e32 v120, 0, v120
	v_max_f32_e32 v125, 0, v125
	v_max_f32_e32 v121, 0, v121
	v_max_f32_e32 v126, 0, v126
	v_max_f32_e32 v122, 0, v122
	v_max_f32_e32 v127, 0, v127
	v_max_f32_e32 v123, 0, v123
	v_max_f32_e32 v112, 0, v112
	v_max_f32_e32 v113, 0, v113
	v_max_f32_e32 v114, 0, v114
	v_max_f32_e32 v115, 0, v115
	v_max_f32_e32 v116, 0, v116
	v_max_f32_e32 v117, 0, v117
	v_max_f32_e32 v118, 0, v118
	v_max_f32_e32 v119, 0, v119
	v_mul_f32_e32 v124, v124, v124
	v_mul_f32_e32 v120, v120, v120
	v_mul_f32_e32 v125, v125, v125
	v_mul_f32_e32 v121, v121, v121
	v_mul_f32_e32 v126, v126, v126
	v_mul_f32_e32 v122, v122, v122
	v_mul_f32_e32 v127, v127, v127
	v_mul_f32_e32 v123, v123, v123
	v_mul_f32_e32 v154, v112, v112
	v_mul_f32_e32 v155, v113, v113
	v_mul_f32_e32 v156, v114, v114
	v_mul_f32_e32 v157, v115, v115
	v_cvt_pk_bf16_f32 v112, v124, v125
	v_cvt_pk_bf16_f32 v113, v126, v127
	v_cvt_pk_bf16_f32 v114, v120, v121
	v_cvt_pk_bf16_f32 v115, v122, v123
	v_mul_f32_e32 v116, v116, v116
	v_mul_f32_e32 v117, v117, v117
	v_mul_f32_e32 v118, v118, v118
	v_mul_f32_e32 v119, v119, v119
	buffer_store_dwordx4 v[112:115], v151, s[8:11], 0 offen sc1
	s_nop 1
	v_cvt_pk_bf16_f32 v112, v116, v117
	v_cvt_pk_bf16_f32 v113, v118, v119
	v_cvt_pk_bf16_f32 v114, v154, v155
	v_cvt_pk_bf16_f32 v115, v156, v157
	buffer_store_dwordx4 v[112:115], v151, s[8:11], 0 offen offset:256 sc1
	s_nop 0
	v_add_u32_e32 v152, 0x4020, v150
	v_ashrrev_i32_e32 v153, 31, v152
	v_lshl_add_u32 v151, v174, 13, v149
	s_waitcnt vmcnt(14)
	v_mov_b32_e32 v112, v194
	v_mov_b32_e32 v113, v195
	v_mov_b32_e32 v114, v196
	v_mov_b32_e32 v115, v197
	v_mov_b32_e32 v116, v198
	v_mov_b32_e32 v117, v199
	v_mov_b32_e32 v118, v200
	v_mov_b32_e32 v119, v201
	v_mov_b32_e32 v120, v202
	v_mov_b32_e32 v121, v203
	v_mov_b32_e32 v122, v204
	v_mov_b32_e32 v123, v205
	v_mov_b32_e32 v124, v206
	v_mov_b32_e32 v125, v207
	v_mov_b32_e32 v126, v208
	v_mov_b32_e32 v127, v209
	v_add_u32_e32 v177, 0x2400, v176
	global_load_dwordx4 v[194:197], v177, s[14:15]
	v_add_u32_e32 v177, 0x2410, v176
	global_load_dwordx4 v[198:201], v177, s[14:15]
	v_add_u32_e32 v177, 0x2420, v176
	global_load_dwordx4 v[202:205], v177, s[14:15]
	v_add_u32_e32 v177, 0x2430, v176
	global_load_dwordx4 v[206:209], v177, s[14:15]
	v_mov_b32_e32 v154, v113
	v_mov_b32_e32 v155, v114
	v_mov_b32_e32 v113, v115
	v_mov_b32_e32 v114, v117
	v_mov_b32_e32 v115, v118
	v_mov_b32_e32 v117, v119
	v_pk_add_f32 v[112:113], v[154:155], v[112:113]
	v_pk_add_f32 v[114:115], v[114:115], v[116:117]
	v_pk_add_f32 v[112:113], v[112:113], v[112:113] op_sel:[0,1] op_sel_hi:[1,0]
	v_pk_add_f32 v[114:115], v[114:115], v[114:115] op_sel:[0,1] op_sel_hi:[1,0]
	v_add_f32_e32 v118, v120, v121
	v_add_f32_e32 v120, v122, v123
	v_mov_b32_e32 v119, v126
	v_mov_b32_e32 v121, v127
	v_mov_b32_e32 v113, v124
	v_mov_b32_e32 v115, v125
	v_pk_add_f32 v[116:117], v[118:119], v[120:121]
	v_pk_add_f32 v[112:113], v[112:113], v[114:115]
	s_nop 0
	v_pk_add_f32 v[112:113], v[112:113], v[116:117]
	s_nop 0
	v_add_f32_e32 v112, v112, v113
	v_fmamk_f32 v112, v112, 0x3a800000, v148
	v_mul_f32_e32 v113, 0x4b800000, v112
	v_cmp_gt_f32_e32 vcc, s63, v112
	s_nop 1
	v_cndmask_b32_e32 v112, v112, v113, vcc
	v_rsq_f32_e32 v114, v112
; __device__ __forceinline__ u32x4 pack8(const f32x4 v0, const f32x4 v1) { u32x4 w; w.x = pk2(v0[0], v0[1]); w.y = pk2(v0[2], v0[3]); w.z = pk2(v1[0], v1[1]); w.w = pk2(v1[2], v1[3]); return w; }
; __device__ __forceinline__ float row_rstd(const float* ssq, int row) {
;     const f32x4* p = (const f32x4*)(ssq + (size_t)row * 16);
;     const f32x4 a = p[0], b = p[1], c = p[2], d = p[3];
;     const float s = ((a[0] + a[1]) + (a[2] + a[3])) + ((b[0] + b[1]) + (b[2] + b[3])) + ((c[0] + c[1]) + (c[2] + c[3])) + ((d[0] + d[1]) + (d[2] + d[3]));
;     return rsqrtf(s * (1.0f / 1024.0f) + 1e-6f);
;     __device__ __forceinline__ void operator()(const f32x4 (&acc)[2][2][4][2], const Unit& u, int wr, int wc, int fr, int fq) const {
;     ...
;         const int row0 = row_off + u.pm * 256 + wr * 64 + fr, col0 = u.pn * 256 + wc * 32 + 8 * fq;
; #pragma unroll
;         for (int ai = 0; ai < 2; ++ai)
; #pragma unroll
;             for (int m = 0; m < 4; ++m) {
;                 const int row = row0 + ai * 128 + m * 16; const float rs = row_rstd(ssq, row);
; #pragma unroll
;                 for (int bj = 0; bj < 2; ++bj) { f32x4 v0 = acc[ai][bj][m][0] * rs, v1 = acc[ai][bj][m][1] * rs;
; #pragma unroll
;                     for (int j = 0; j < 4; ++j) { const float a = fmaxf(v0[j], 0.f), b = fmaxf(v1[j], 0.f); v0[j] = a * a; v1[j] = b * b; }
;                     __builtin_amdgcn_raw_buffer_store_b128(pack8(v0, v1), rsrc, (unsigned)(((size_t)row * DFF + col0 + bj * 128) * 2), 0, 16  ); }
	v_lshlrev_b64 v[112:113], 6, v[152:153]
	v_lshl_add_u64 v[112:113], s[14:15], 0, v[112:113]
	v_mul_f32_e32 v115, 0x45800000, v114
	v_cndmask_b32_e32 v114, v114, v115, vcc
	v_pk_mul_f32 v[110:111], v[110:111], v[114:115] op_sel_hi:[1,0]
	v_pk_mul_f32 v[108:109], v[108:109], v[114:115] op_sel_hi:[1,0]
	v_pk_mul_f32 v[106:107], v[106:107], v[114:115] op_sel_hi:[1,0]
	v_pk_mul_f32 v[104:105], v[104:105], v[114:115] op_sel_hi:[1,0]
	v_pk_mul_f32 v[98:99], v[98:99], v[114:115] op_sel_hi:[1,0]
	v_pk_mul_f32 v[96:97], v[96:97], v[114:115] op_sel_hi:[1,0]
	v_pk_mul_f32 v[102:103], v[102:103], v[114:115] op_sel_hi:[1,0]
	v_pk_mul_f32 v[100:101], v[100:101], v[114:115] op_sel_hi:[1,0]
	v_max_f32_e32 v108, 0, v108
	v_max_f32_e32 v104, 0, v104
	v_max_f32_e32 v109, 0, v109
	v_max_f32_e32 v105, 0, v105
	v_max_f32_e32 v110, 0, v110
	v_max_f32_e32 v106, 0, v106
	v_max_f32_e32 v111, 0, v111
	v_max_f32_e32 v107, 0, v107
	v_max_f32_e32 v96, 0, v96
	v_max_f32_e32 v97, 0, v97
	v_max_f32_e32 v98, 0, v98
	v_max_f32_e32 v99, 0, v99
	v_max_f32_e32 v100, 0, v100
	v_max_f32_e32 v101, 0, v101
	v_max_f32_e32 v102, 0, v102
	v_max_f32_e32 v103, 0, v103
	v_mul_f32_e32 v108, v108, v108
	v_mul_f32_e32 v104, v104, v104
	v_mul_f32_e32 v109, v109, v109
	v_mul_f32_e32 v105, v105, v105
	v_mul_f32_e32 v110, v110, v110
	v_mul_f32_e32 v106, v106, v106
	v_mul_f32_e32 v111, v111, v111
	v_mul_f32_e32 v107, v107, v107
	v_mul_f32_e32 v114, v96, v96
	v_mul_f32_e32 v115, v97, v97
	v_mul_f32_e32 v116, v98, v98
	v_mul_f32_e32 v117, v99, v99
	v_cvt_pk_bf16_f32 v96, v108, v109
	v_cvt_pk_bf16_f32 v97, v110, v111
	v_cvt_pk_bf16_f32 v98, v104, v105
	v_cvt_pk_bf16_f32 v99, v106, v107
	v_mul_f32_e32 v100, v100, v100
	v_mul_f32_e32 v101, v101, v101
	v_mul_f32_e32 v102, v102, v102
	v_mul_f32_e32 v103, v103, v103
	buffer_store_dwordx4 v[96:99], v151, s[8:11], 0 offen sc1
	s_nop 1
	v_cvt_pk_bf16_f32 v96, v100, v101
	v_cvt_pk_bf16_f32 v97, v102, v103
	v_cvt_pk_bf16_f32 v98, v114, v115
	v_cvt_pk_bf16_f32 v99, v116, v117
	buffer_store_dwordx4 v[96:99], v151, s[8:11], 0 offen offset:256 sc1
	s_nop 0
	v_add_u32_e32 v112, 0x4030, v150
	v_ashrrev_i32_e32 v113, 31, v112
	v_lshl_add_u32 v116, v152, 13, v149
	s_waitcnt vmcnt(16)
	v_mov_b32_e32 v96, v210
	v_mov_b32_e32 v97, v211
	v_mov_b32_e32 v98, v212
	v_mov_b32_e32 v99, v213
	v_mov_b32_e32 v100, v214
	v_mov_b32_e32 v101, v215
	v_mov_b32_e32 v102, v216
	v_mov_b32_e32 v103, v217
	v_mov_b32_e32 v104, v232
	v_mov_b32_e32 v105, v233
	v_mov_b32_e32 v106, v234
	v_mov_b32_e32 v107, v235
	v_mov_b32_e32 v108, v236
	v_mov_b32_e32 v109, v237
	v_mov_b32_e32 v110, v238
	v_mov_b32_e32 v111, v239
	v_add_u32_e32 v177, 0x2800, v176
	global_load_dwordx4 v[210:213], v177, s[14:15]
	v_add_u32_e32 v177, 0x2810, v176
	global_load_dwordx4 v[214:217], v177, s[14:15]
	v_add_u32_e32 v177, 0x2820, v176
	global_load_dwordx4 v[232:235], v177, s[14:15]
	v_add_u32_e32 v177, 0x2830, v176
	global_load_dwordx4 v[236:239], v177, s[14:15]
	v_mov_b32_e32 v114, v97
	v_mov_b32_e32 v115, v98
	v_mov_b32_e32 v97, v99
	v_mov_b32_e32 v98, v101
	v_mov_b32_e32 v99, v102
	v_mov_b32_e32 v101, v103
	v_pk_add_f32 v[96:97], v[114:115], v[96:97]
	v_pk_add_f32 v[98:99], v[98:99], v[100:101]
	v_pk_add_f32 v[96:97], v[96:97], v[96:97] op_sel:[0,1] op_sel_hi:[1,0]
	v_pk_add_f32 v[98:99], v[98:99], v[98:99] op_sel:[0,1] op_sel_hi:[1,0]
	v_add_f32_e32 v102, v104, v105
	v_add_f32_e32 v104, v106, v107
	v_mov_b32_e32 v103, v110
	v_mov_b32_e32 v105, v111
	v_mov_b32_e32 v97, v108
	v_mov_b32_e32 v99, v109
	v_pk_add_f32 v[100:101], v[102:103], v[104:105]
	v_pk_add_f32 v[96:97], v[96:97], v[98:99]
	s_nop 0
	v_pk_add_f32 v[96:97], v[96:97], v[100:101]
	s_nop 0
	v_add_f32_e32 v96, v96, v97
	v_fmamk_f32 v96, v96, 0x3a800000, v148
	v_mul_f32_e32 v97, 0x4b800000, v96
	v_cmp_gt_f32_e32 vcc, s63, v96
	s_nop 1
	v_cndmask_b32_e32 v96, v96, v97, vcc
	v_rsq_f32_e32 v98, v96
	v_lshlrev_b64 v[96:97], 6, v[112:113]
	v_lshl_add_u64 v[96:97], s[14:15], 0, v[96:97]
	v_mul_f32_e32 v99, 0x45800000, v98
	v_cndmask_b32_e32 v98, v98, v99, vcc
	v_pk_mul_f32 v[94:95], v[94:95], v[98:99] op_sel_hi:[1,0]
	v_pk_mul_f32 v[92:93], v[92:93], v[98:99] op_sel_hi:[1,0]
	v_pk_mul_f32 v[90:91], v[90:91], v[98:99] op_sel_hi:[1,0]
	v_pk_mul_f32 v[88:89], v[88:89], v[98:99] op_sel_hi:[1,0]
	v_pk_mul_f32 v[82:83], v[82:83], v[98:99] op_sel_hi:[1,0]
	v_pk_mul_f32 v[80:81], v[80:81], v[98:99] op_sel_hi:[1,0]
	v_pk_mul_f32 v[86:87], v[86:87], v[98:99] op_sel_hi:[1,0]
	v_pk_mul_f32 v[84:85], v[84:85], v[98:99] op_sel_hi:[1,0]
	v_max_f32_e32 v92, 0, v92
	v_max_f32_e32 v88, 0, v88
	v_max_f32_e32 v93, 0, v93
	v_max_f32_e32 v89, 0, v89
	v_max_f32_e32 v94, 0, v94
	v_max_f32_e32 v90, 0, v90
	v_max_f32_e32 v95, 0, v95
	v_max_f32_e32 v91, 0, v91
	v_max_f32_e32 v80, 0, v80
	v_max_f32_e32 v81, 0, v81
	v_max_f32_e32 v82, 0, v82
	v_max_f32_e32 v83, 0, v83
	v_max_f32_e32 v84, 0, v84
	v_max_f32_e32 v85, 0, v85
	v_max_f32_e32 v86, 0, v86
	v_max_f32_e32 v87, 0, v87
	v_mul_f32_e32 v92, v92, v92
	v_mul_f32_e32 v88, v88, v88
	v_mul_f32_e32 v93, v93, v93
	v_mul_f32_e32 v89, v89, v89
	v_mul_f32_e32 v94, v94, v94
	v_mul_f32_e32 v90, v90, v90
	v_mul_f32_e32 v95, v95, v95
	v_mul_f32_e32 v91, v91, v91
	v_mul_f32_e32 v98, v80, v80
	v_mul_f32_e32 v99, v81, v81
	v_mul_f32_e32 v100, v82, v82
	v_mul_f32_e32 v101, v83, v83
	v_cvt_pk_bf16_f32 v80, v92, v93
	v_cvt_pk_bf16_f32 v81, v94, v95
	v_cvt_pk_bf16_f32 v82, v88, v89
	v_cvt_pk_bf16_f32 v83, v90, v91
	v_mul_f32_e32 v84, v84, v84
	v_mul_f32_e32 v85, v85, v85
	v_mul_f32_e32 v86, v86, v86
	v_mul_f32_e32 v87, v87, v87
	buffer_store_dwordx4 v[80:83], v116, s[8:11], 0 offen sc1
	s_nop 1
	v_cvt_pk_bf16_f32 v80, v84, v85
	v_cvt_pk_bf16_f32 v81, v86, v87
	v_cvt_pk_bf16_f32 v82, v98, v99
	v_cvt_pk_bf16_f32 v83, v100, v101
	buffer_store_dwordx4 v[80:83], v116, s[8:11], 0 offen offset:256 sc1
	s_nop 0
	v_add_u32_e32 v96, 0x4080, v150
	v_ashrrev_i32_e32 v97, 31, v96
	v_lshl_add_u32 v100, v112, 13, v149
	s_waitcnt vmcnt(18)
; __device__ __forceinline__ u32x4 pack8(const f32x4 v0, const f32x4 v1) { u32x4 w; w.x = pk2(v0[0], v0[1]); w.y = pk2(v0[2], v0[3]); w.z = pk2(v1[0], v1[1]); w.w = pk2(v1[2], v1[3]); return w; }
; __device__ __forceinline__ float row_rstd(const float* ssq, int row) {
;     const f32x4* p = (const f32x4*)(ssq + (size_t)row * 16);
;     const f32x4 a = p[0], b = p[1], c = p[2], d = p[3];
;     const float s = ((a[0] + a[1]) + (a[2] + a[3])) + ((b[0] + b[1]) + (b[2] + b[3])) + ((c[0] + c[1]) + (c[2] + c[3])) + ((d[0] + d[1]) + (d[2] + d[3]));
;     return rsqrtf(s * (1.0f / 1024.0f) + 1e-6f);
;     __device__ __forceinline__ void operator()(const f32x4 (&acc)[2][2][4][2], const Unit& u, int wr, int wc, int fr, int fq) const {
;     ...
;                 const int row = row0 + ai * 128 + m * 16; const float rs = row_rstd(ssq, row);
; #pragma unroll
;                 for (int bj = 0; bj < 2; ++bj) { f32x4 v0 = acc[ai][bj][m][0] * rs, v1 = acc[ai][bj][m][1] * rs;
; #pragma unroll
;                     for (int j = 0; j < 4; ++j) { const float a = fmaxf(v0[j], 0.f), b = fmaxf(v1[j], 0.f); v0[j] = a * a; v1[j] = b * b; }
;                     __builtin_amdgcn_raw_buffer_store_b128(pack8(v0, v1), rsrc, (unsigned)(((size_t)row * DFF + col0 + bj * 128) * 2), 0, 16  ); }
	v_mov_b32_e32 v80, v240
	v_mov_b32_e32 v81, v241
	v_mov_b32_e32 v82, v242
	v_mov_b32_e32 v83, v243
	v_mov_b32_e32 v84, v244
	v_mov_b32_e32 v85, v245
	v_mov_b32_e32 v86, v246
	v_mov_b32_e32 v87, v247
	v_mov_b32_e32 v88, v248
	v_mov_b32_e32 v89, v249
	v_mov_b32_e32 v90, v250
	v_mov_b32_e32 v91, v251
	v_mov_b32_e32 v92, v252
	v_mov_b32_e32 v93, v253
	v_mov_b32_e32 v94, v254
	v_mov_b32_e32 v95, v255
	v_add_u32_e32 v177, 0x2c00, v176
	global_load_dwordx4 v[240:243], v177, s[14:15]
	v_add_u32_e32 v177, 0x2c10, v176
	global_load_dwordx4 v[244:247], v177, s[14:15]
	v_add_u32_e32 v177, 0x2c20, v176
	global_load_dwordx4 v[248:251], v177, s[14:15]
	v_add_u32_e32 v177, 0x2c30, v176
	global_load_dwordx4 v[252:255], v177, s[14:15]
	v_mov_b32_e32 v98, v81
	v_mov_b32_e32 v99, v82
	v_mov_b32_e32 v81, v83
	v_mov_b32_e32 v82, v85
	v_mov_b32_e32 v83, v86
	v_mov_b32_e32 v85, v87
	v_pk_add_f32 v[80:81], v[98:99], v[80:81]
	v_pk_add_f32 v[82:83], v[82:83], v[84:85]
	v_pk_add_f32 v[80:81], v[80:81], v[80:81] op_sel:[0,1] op_sel_hi:[1,0]
	v_pk_add_f32 v[82:83], v[82:83], v[82:83] op_sel:[0,1] op_sel_hi:[1,0]
	v_add_f32_e32 v86, v88, v89
	v_add_f32_e32 v88, v90, v91
	v_mov_b32_e32 v87, v94
	v_mov_b32_e32 v89, v95
	v_mov_b32_e32 v81, v92
	v_mov_b32_e32 v83, v93
	v_pk_add_f32 v[84:85], v[86:87], v[88:89]
	v_pk_add_f32 v[80:81], v[80:81], v[82:83]
	s_nop 0
	v_pk_add_f32 v[80:81], v[80:81], v[84:85]
	s_nop 0
	v_add_f32_e32 v80, v80, v81
	v_fmamk_f32 v80, v80, 0x3a800000, v148
	v_mul_f32_e32 v81, 0x4b800000, v80
	v_cmp_gt_f32_e32 vcc, s63, v80
	s_nop 1
	v_cndmask_b32_e32 v80, v80, v81, vcc
	v_rsq_f32_e32 v82, v80
	v_lshlrev_b64 v[80:81], 6, v[96:97]
	v_lshl_add_u64 v[80:81], s[14:15], 0, v[80:81]
	v_mul_f32_e32 v83, 0x45800000, v82
	v_cndmask_b32_e32 v82, v82, v83, vcc
	v_pk_mul_f32 v[78:79], v[78:79], v[82:83] op_sel_hi:[1,0]
	v_pk_mul_f32 v[76:77], v[76:77], v[82:83] op_sel_hi:[1,0]
	v_pk_mul_f32 v[74:75], v[74:75], v[82:83] op_sel_hi:[1,0]
	v_pk_mul_f32 v[72:73], v[72:73], v[82:83] op_sel_hi:[1,0]
	v_pk_mul_f32 v[66:67], v[66:67], v[82:83] op_sel_hi:[1,0]
	v_pk_mul_f32 v[64:65], v[64:65], v[82:83] op_sel_hi:[1,0]
	v_pk_mul_f32 v[70:71], v[70:71], v[82:83] op_sel_hi:[1,0]
	v_pk_mul_f32 v[68:69], v[68:69], v[82:83] op_sel_hi:[1,0]
	v_max_f32_e32 v76, 0, v76
	v_max_f32_e32 v72, 0, v72
	v_max_f32_e32 v77, 0, v77
	v_max_f32_e32 v73, 0, v73
	v_max_f32_e32 v78, 0, v78
	v_max_f32_e32 v74, 0, v74
	v_max_f32_e32 v79, 0, v79
	v_max_f32_e32 v75, 0, v75
	v_max_f32_e32 v64, 0, v64
	v_max_f32_e32 v65, 0, v65
	v_max_f32_e32 v66, 0, v66
	v_max_f32_e32 v67, 0, v67
	v_max_f32_e32 v68, 0, v68
	v_max_f32_e32 v69, 0, v69
	v_max_f32_e32 v70, 0, v70
	v_max_f32_e32 v71, 0, v71
	v_mul_f32_e32 v76, v76, v76
	v_mul_f32_e32 v72, v72, v72
	v_mul_f32_e32 v77, v77, v77
	v_mul_f32_e32 v73, v73, v73
	v_mul_f32_e32 v78, v78, v78
	v_mul_f32_e32 v74, v74, v74
	v_mul_f32_e32 v79, v79, v79
	v_mul_f32_e32 v75, v75, v75
	v_mul_f32_e32 v82, v64, v64
	v_mul_f32_e32 v83, v65, v65
	v_mul_f32_e32 v84, v66, v66
	v_mul_f32_e32 v85, v67, v67
	v_cvt_pk_bf16_f32 v64, v76, v77
	v_cvt_pk_bf16_f32 v65, v78, v79
	v_cvt_pk_bf16_f32 v66, v72, v73
	v_cvt_pk_bf16_f32 v67, v74, v75
	v_mul_f32_e32 v68, v68, v68
	v_mul_f32_e32 v69, v69, v69
	v_mul_f32_e32 v70, v70, v70
	v_mul_f32_e32 v71, v71, v71
	buffer_store_dwordx4 v[64:67], v100, s[8:11], 0 offen sc1
	s_nop 1
	v_cvt_pk_bf16_f32 v64, v68, v69
	v_cvt_pk_bf16_f32 v65, v70, v71
	v_cvt_pk_bf16_f32 v66, v82, v83
	v_cvt_pk_bf16_f32 v67, v84, v85
	buffer_store_dwordx4 v[64:67], v100, s[8:11], 0 offen offset:256 sc1
	s_nop 0
	v_add_u32_e32 v80, 0x4090, v150
	v_ashrrev_i32_e32 v81, 31, v80
	v_lshl_add_u32 v84, v96, 13, v149
	s_waitcnt vmcnt(20)
	v_mov_b32_e32 v64, v178
	v_mov_b32_e32 v65, v179
	v_mov_b32_e32 v66, v180
	v_mov_b32_e32 v67, v181
	v_mov_b32_e32 v68, v182
	v_mov_b32_e32 v69, v183
	v_mov_b32_e32 v70, v184
	v_mov_b32_e32 v71, v185
	v_mov_b32_e32 v72, v186
	v_mov_b32_e32 v73, v187
	v_mov_b32_e32 v74, v188
	v_mov_b32_e32 v75, v189
	v_mov_b32_e32 v76, v190
	v_mov_b32_e32 v77, v191
	v_mov_b32_e32 v78, v192
	v_mov_b32_e32 v79, v193
	v_mov_b32_e32 v82, v65
	v_mov_b32_e32 v83, v66
	v_mov_b32_e32 v65, v67
	v_mov_b32_e32 v66, v69
	v_mov_b32_e32 v67, v70
	v_mov_b32_e32 v69, v71
	v_pk_add_f32 v[64:65], v[82:83], v[64:65]
	v_pk_add_f32 v[66:67], v[66:67], v[68:69]
	v_pk_add_f32 v[64:65], v[64:65], v[64:65] op_sel:[0,1] op_sel_hi:[1,0]
	v_pk_add_f32 v[66:67], v[66:67], v[66:67] op_sel:[0,1] op_sel_hi:[1,0]
	v_add_f32_e32 v70, v72, v73
	v_add_f32_e32 v72, v74, v75
	v_mov_b32_e32 v71, v78
	v_mov_b32_e32 v73, v79
	v_mov_b32_e32 v65, v76
	v_mov_b32_e32 v67, v77
	v_pk_add_f32 v[68:69], v[70:71], v[72:73]
	v_pk_add_f32 v[64:65], v[64:65], v[66:67]
	s_nop 0
	v_pk_add_f32 v[64:65], v[64:65], v[68:69]
	s_nop 0
	v_add_f32_e32 v64, v64, v65
	v_fmamk_f32 v64, v64, 0x3a800000, v148
	v_mul_f32_e32 v65, 0x4b800000, v64
	v_cmp_gt_f32_e32 vcc, s63, v64
	s_nop 1
	v_cndmask_b32_e32 v64, v64, v65, vcc
	v_rsq_f32_e32 v66, v64
	v_lshlrev_b64 v[64:65], 6, v[80:81]
	v_lshl_add_u64 v[64:65], s[14:15], 0, v[64:65]
	v_mul_f32_e32 v67, 0x45800000, v66
	v_cndmask_b32_e32 v66, v66, v67, vcc
	v_pk_mul_f32 v[62:63], v[62:63], v[66:67] op_sel_hi:[1,0]
	v_pk_mul_f32 v[60:61], v[60:61], v[66:67] op_sel_hi:[1,0]
	v_pk_mul_f32 v[58:59], v[58:59], v[66:67] op_sel_hi:[1,0]
	v_pk_mul_f32 v[56:57], v[56:57], v[66:67] op_sel_hi:[1,0]
	v_pk_mul_f32 v[50:51], v[50:51], v[66:67] op_sel_hi:[1,0]
	v_pk_mul_f32 v[48:49], v[48:49], v[66:67] op_sel_hi:[1,0]
	v_pk_mul_f32 v[54:55], v[54:55], v[66:67] op_sel_hi:[1,0]
	v_pk_mul_f32 v[52:53], v[52:53], v[66:67] op_sel_hi:[1,0]
	v_max_f32_e32 v60, 0, v60
	v_max_f32_e32 v56, 0, v56
	v_max_f32_e32 v61, 0, v61
	v_max_f32_e32 v57, 0, v57
	v_max_f32_e32 v62, 0, v62
	v_max_f32_e32 v58, 0, v58
	v_max_f32_e32 v63, 0, v63
	v_max_f32_e32 v59, 0, v59
	v_max_f32_e32 v48, 0, v48
	v_max_f32_e32 v49, 0, v49
	v_max_f32_e32 v50, 0, v50
	v_max_f32_e32 v51, 0, v51
	v_max_f32_e32 v52, 0, v52
	v_max_f32_e32 v53, 0, v53
	v_max_f32_e32 v54, 0, v54
	v_max_f32_e32 v55, 0, v55
	v_mul_f32_e32 v60, v60, v60
	v_mul_f32_e32 v56, v56, v56
	v_mul_f32_e32 v61, v61, v61
	v_mul_f32_e32 v57, v57, v57
	v_mul_f32_e32 v62, v62, v62
	v_mul_f32_e32 v58, v58, v58
	v_mul_f32_e32 v63, v63, v63
	v_mul_f32_e32 v59, v59, v59
	v_mul_f32_e32 v66, v48, v48
	v_mul_f32_e32 v67, v49, v49
	v_mul_f32_e32 v68, v50, v50
	v_mul_f32_e32 v69, v51, v51
	v_cvt_pk_bf16_f32 v48, v60, v61
	v_cvt_pk_bf16_f32 v49, v62, v63
	v_cvt_pk_bf16_f32 v50, v56, v57
	v_cvt_pk_bf16_f32 v51, v58, v59
	v_mul_f32_e32 v52, v52, v52
	v_mul_f32_e32 v53, v53, v53
	v_mul_f32_e32 v54, v54, v54
	v_mul_f32_e32 v55, v55, v55
	buffer_store_dwordx4 v[48:51], v84, s[8:11], 0 offen sc1
	s_nop 1
	v_cvt_pk_bf16_f32 v48, v52, v53
	v_cvt_pk_bf16_f32 v49, v54, v55
	v_cvt_pk_bf16_f32 v50, v66, v67
	v_cvt_pk_bf16_f32 v51, v68, v69
	buffer_store_dwordx4 v[48:51], v84, s[8:11], 0 offen offset:256 sc1
	s_nop 0
	v_add_u32_e32 v64, 0x40a0, v150
	v_ashrrev_i32_e32 v65, 31, v64
	v_lshl_add_u32 v68, v80, 13, v149
	s_waitcnt vmcnt(16)
; __device__ __forceinline__ u32x4 pack8(const f32x4 v0, const f32x4 v1) { u32x4 w; w.x = pk2(v0[0], v0[1]); w.y = pk2(v0[2], v0[3]); w.z = pk2(v1[0], v1[1]); w.w = pk2(v1[2], v1[3]); return w; }
; __device__ __forceinline__ float row_rstd(const float* ssq, int row) {
;     const f32x4* p = (const f32x4*)(ssq + (size_t)row * 16);
;     const f32x4 a = p[0], b = p[1], c = p[2], d = p[3];
;     const float s = ((a[0] + a[1]) + (a[2] + a[3])) + ((b[0] + b[1]) + (b[2] + b[3])) + ((c[0] + c[1]) + (c[2] + c[3])) + ((d[0] + d[1]) + (d[2] + d[3]));
;     return rsqrtf(s * (1.0f / 1024.0f) + 1e-6f);
;     __device__ __forceinline__ void operator()(const f32x4 (&acc)[2][2][4][2], const Unit& u, int wr, int wc, int fr, int fq) const {
;     ...
;                 const int row = row0 + ai * 128 + m * 16; const float rs = row_rstd(ssq, row);
; #pragma unroll
;                 for (int bj = 0; bj < 2; ++bj) { f32x4 v0 = acc[ai][bj][m][0] * rs, v1 = acc[ai][bj][m][1] * rs;
; #pragma unroll
;                     for (int j = 0; j < 4; ++j) { const float a = fmaxf(v0[j], 0.f), b = fmaxf(v1[j], 0.f); v0[j] = a * a; v1[j] = b * b; }
;                     __builtin_amdgcn_raw_buffer_store_b128(pack8(v0, v1), rsrc, (unsigned)(((size_t)row * DFF + col0 + bj * 128) * 2), 0, 16  ); }
	v_mov_b32_e32 v48, v194
	v_mov_b32_e32 v49, v195
	v_mov_b32_e32 v50, v196
	v_mov_b32_e32 v51, v197
	v_mov_b32_e32 v52, v198
	v_mov_b32_e32 v53, v199
	v_mov_b32_e32 v54, v200
	v_mov_b32_e32 v55, v201
	v_mov_b32_e32 v56, v202
	v_mov_b32_e32 v57, v203
	v_mov_b32_e32 v58, v204
	v_mov_b32_e32 v59, v205
	v_mov_b32_e32 v60, v206
	v_mov_b32_e32 v61, v207
	v_mov_b32_e32 v62, v208
	v_mov_b32_e32 v63, v209
	v_mov_b32_e32 v66, v49
	v_mov_b32_e32 v67, v50
	v_mov_b32_e32 v49, v51
	v_mov_b32_e32 v50, v53
	v_mov_b32_e32 v51, v54
	v_mov_b32_e32 v53, v55
	v_pk_add_f32 v[48:49], v[66:67], v[48:49]
	v_pk_add_f32 v[50:51], v[50:51], v[52:53]
	v_pk_add_f32 v[48:49], v[48:49], v[48:49] op_sel:[0,1] op_sel_hi:[1,0]
	v_pk_add_f32 v[50:51], v[50:51], v[50:51] op_sel:[0,1] op_sel_hi:[1,0]
	v_add_f32_e32 v54, v56, v57
	v_add_f32_e32 v56, v58, v59
	v_mov_b32_e32 v55, v62
	v_mov_b32_e32 v57, v63
	v_mov_b32_e32 v49, v60
	v_mov_b32_e32 v51, v61
	v_pk_add_f32 v[52:53], v[54:55], v[56:57]
	v_pk_add_f32 v[48:49], v[48:49], v[50:51]
	s_nop 0
	v_pk_add_f32 v[48:49], v[48:49], v[52:53]
	s_nop 0
	v_add_f32_e32 v48, v48, v49
	v_fmamk_f32 v48, v48, 0x3a800000, v148
	v_mul_f32_e32 v49, 0x4b800000, v48
	v_cmp_gt_f32_e32 vcc, s63, v48
	s_nop 1
	v_cndmask_b32_e32 v48, v48, v49, vcc
	v_rsq_f32_e32 v50, v48
	v_lshlrev_b64 v[48:49], 6, v[64:65]
	v_lshl_add_u64 v[48:49], s[14:15], 0, v[48:49]
	v_mul_f32_e32 v51, 0x45800000, v50
	v_cndmask_b32_e32 v50, v50, v51, vcc
	v_pk_mul_f32 v[46:47], v[46:47], v[50:51] op_sel_hi:[1,0]
	v_pk_mul_f32 v[44:45], v[44:45], v[50:51] op_sel_hi:[1,0]
	v_pk_mul_f32 v[42:43], v[42:43], v[50:51] op_sel_hi:[1,0]
	v_pk_mul_f32 v[40:41], v[40:41], v[50:51] op_sel_hi:[1,0]
	v_pk_mul_f32 v[34:35], v[34:35], v[50:51] op_sel_hi:[1,0]
	v_pk_mul_f32 v[32:33], v[32:33], v[50:51] op_sel_hi:[1,0]
	v_pk_mul_f32 v[38:39], v[38:39], v[50:51] op_sel_hi:[1,0]
	v_pk_mul_f32 v[36:37], v[36:37], v[50:51] op_sel_hi:[1,0]
	v_max_f32_e32 v44, 0, v44
	v_max_f32_e32 v40, 0, v40
	v_max_f32_e32 v45, 0, v45
	v_max_f32_e32 v41, 0, v41
	v_max_f32_e32 v46, 0, v46
	v_max_f32_e32 v42, 0, v42
	v_max_f32_e32 v47, 0, v47
	v_max_f32_e32 v43, 0, v43
	v_max_f32_e32 v32, 0, v32
	v_max_f32_e32 v33, 0, v33
	v_max_f32_e32 v34, 0, v34
	v_max_f32_e32 v35, 0, v35
	v_max_f32_e32 v36, 0, v36
	v_max_f32_e32 v37, 0, v37
	v_max_f32_e32 v38, 0, v38
	v_max_f32_e32 v39, 0, v39
	v_mul_f32_e32 v44, v44, v44
	v_mul_f32_e32 v40, v40, v40
	v_mul_f32_e32 v45, v45, v45
	v_mul_f32_e32 v41, v41, v41
	v_mul_f32_e32 v46, v46, v46
	v_mul_f32_e32 v42, v42, v42
	v_mul_f32_e32 v47, v47, v47
	v_mul_f32_e32 v43, v43, v43
	v_mul_f32_e32 v50, v32, v32
	v_mul_f32_e32 v51, v33, v33
	v_mul_f32_e32 v52, v34, v34
	v_mul_f32_e32 v53, v35, v35
	v_cvt_pk_bf16_f32 v32, v44, v45
	v_cvt_pk_bf16_f32 v33, v46, v47
	v_cvt_pk_bf16_f32 v34, v40, v41
	v_cvt_pk_bf16_f32 v35, v42, v43
	v_mul_f32_e32 v36, v36, v36
	v_mul_f32_e32 v37, v37, v37
	v_mul_f32_e32 v38, v38, v38
	v_mul_f32_e32 v39, v39, v39
	buffer_store_dwordx4 v[32:35], v68, s[8:11], 0 offen sc1
	s_nop 1
	v_cvt_pk_bf16_f32 v32, v36, v37
	v_cvt_pk_bf16_f32 v33, v38, v39
	v_cvt_pk_bf16_f32 v34, v50, v51
	v_cvt_pk_bf16_f32 v35, v52, v53
	buffer_store_dwordx4 v[32:35], v68, s[8:11], 0 offen offset:256 sc1
	s_nop 0
	v_add_u32_e32 v48, 0x40b0, v150
	v_ashrrev_i32_e32 v49, 31, v48
	v_lshl_add_u32 v52, v64, 13, v149
	s_waitcnt vmcnt(12)
	v_mov_b32_e32 v32, v210
	v_mov_b32_e32 v33, v211
	v_mov_b32_e32 v34, v212
	v_mov_b32_e32 v35, v213
	v_mov_b32_e32 v36, v214
	v_mov_b32_e32 v37, v215
	v_mov_b32_e32 v38, v216
	v_mov_b32_e32 v39, v217
	v_mov_b32_e32 v40, v232
	v_mov_b32_e32 v41, v233
	v_mov_b32_e32 v42, v234
	v_mov_b32_e32 v43, v235
	v_mov_b32_e32 v44, v236
	v_mov_b32_e32 v45, v237
	v_mov_b32_e32 v46, v238
	v_mov_b32_e32 v47, v239
	v_mov_b32_e32 v50, v33
	v_mov_b32_e32 v51, v34
	v_mov_b32_e32 v33, v35
	v_mov_b32_e32 v34, v37
	v_mov_b32_e32 v35, v38
	v_mov_b32_e32 v37, v39
	v_pk_add_f32 v[32:33], v[50:51], v[32:33]
	v_pk_add_f32 v[34:35], v[34:35], v[36:37]
	v_pk_add_f32 v[32:33], v[32:33], v[32:33] op_sel:[0,1] op_sel_hi:[1,0]
	v_pk_add_f32 v[34:35], v[34:35], v[34:35] op_sel:[0,1] op_sel_hi:[1,0]
	v_add_f32_e32 v38, v40, v41
	v_add_f32_e32 v40, v42, v43
	v_mov_b32_e32 v39, v46
	v_mov_b32_e32 v41, v47
	v_mov_b32_e32 v33, v44
	v_mov_b32_e32 v35, v45
	v_pk_add_f32 v[36:37], v[38:39], v[40:41]
	v_pk_add_f32 v[32:33], v[32:33], v[34:35]
	s_nop 0
	v_pk_add_f32 v[32:33], v[32:33], v[36:37]
	s_nop 0
	v_add_f32_e32 v32, v32, v33
	v_fmamk_f32 v32, v32, 0x3a800000, v148
	v_mul_f32_e32 v33, 0x4b800000, v32
	v_cmp_gt_f32_e32 vcc, s63, v32
	s_nop 1
	v_cndmask_b32_e32 v32, v32, v33, vcc
	v_rsq_f32_e32 v34, v32
	v_lshlrev_b64 v[32:33], 6, v[48:49]
	v_lshl_add_u64 v[32:33], s[14:15], 0, v[32:33]
	v_mul_f32_e32 v35, 0x45800000, v34
	v_cndmask_b32_e32 v34, v34, v35, vcc
	v_pk_mul_f32 v[30:31], v[30:31], v[34:35] op_sel_hi:[1,0]
	v_pk_mul_f32 v[28:29], v[28:29], v[34:35] op_sel_hi:[1,0]
	v_pk_mul_f32 v[26:27], v[26:27], v[34:35] op_sel_hi:[1,0]
	v_pk_mul_f32 v[24:25], v[24:25], v[34:35] op_sel_hi:[1,0]
	v_pk_mul_f32 v[18:19], v[18:19], v[34:35] op_sel_hi:[1,0]
	v_pk_mul_f32 v[16:17], v[16:17], v[34:35] op_sel_hi:[1,0]
	v_pk_mul_f32 v[22:23], v[22:23], v[34:35] op_sel_hi:[1,0]
	v_pk_mul_f32 v[20:21], v[20:21], v[34:35] op_sel_hi:[1,0]
	v_max_f32_e32 v28, 0, v28
	v_max_f32_e32 v24, 0, v24
	v_max_f32_e32 v29, 0, v29
	v_max_f32_e32 v25, 0, v25
	v_max_f32_e32 v30, 0, v30
	v_max_f32_e32 v26, 0, v26
	v_max_f32_e32 v31, 0, v31
	v_max_f32_e32 v27, 0, v27
	v_max_f32_e32 v16, 0, v16
	v_max_f32_e32 v17, 0, v17
	v_max_f32_e32 v18, 0, v18
	v_max_f32_e32 v19, 0, v19
	v_max_f32_e32 v20, 0, v20
	v_max_f32_e32 v21, 0, v21
	v_max_f32_e32 v22, 0, v22
	v_max_f32_e32 v23, 0, v23
	v_mul_f32_e32 v28, v28, v28
	v_mul_f32_e32 v24, v24, v24
	v_mul_f32_e32 v29, v29, v29
	v_mul_f32_e32 v25, v25, v25
	v_mul_f32_e32 v30, v30, v30
	v_mul_f32_e32 v26, v26, v26
	v_mul_f32_e32 v31, v31, v31
	v_mul_f32_e32 v27, v27, v27
	v_mul_f32_e32 v34, v16, v16
	v_mul_f32_e32 v35, v17, v17
	v_mul_f32_e32 v36, v18, v18
	v_mul_f32_e32 v37, v19, v19
	v_cvt_pk_bf16_f32 v16, v28, v29
	v_cvt_pk_bf16_f32 v17, v30, v31
	v_cvt_pk_bf16_f32 v18, v24, v25
	v_cvt_pk_bf16_f32 v19, v26, v27
	v_mul_f32_e32 v20, v20, v20
	v_mul_f32_e32 v21, v21, v21
	v_mul_f32_e32 v22, v22, v22
	v_mul_f32_e32 v23, v23, v23
	buffer_store_dwordx4 v[16:19], v52, s[8:11], 0 offen sc1
	s_nop 1
	v_cvt_pk_bf16_f32 v16, v20, v21
	v_cvt_pk_bf16_f32 v17, v22, v23
	v_cvt_pk_bf16_f32 v18, v34, v35
	v_cvt_pk_bf16_f32 v19, v36, v37
	buffer_store_dwordx4 v[16:19], v52, s[8:11], 0 offen offset:256 sc1
	s_nop 0
	s_waitcnt vmcnt(8)
; __device__ __forceinline__ u32x4 pack8(const f32x4 v0, const f32x4 v1) { u32x4 w; w.x = pk2(v0[0], v0[1]); w.y = pk2(v0[2], v0[3]); w.z = pk2(v1[0], v1[1]); w.w = pk2(v1[2], v1[3]); return w; }
; __device__ __forceinline__ float row_rstd(const float* ssq, int row) {
;     const f32x4* p = (const f32x4*)(ssq + (size_t)row * 16);
;     const f32x4 a = p[0], b = p[1], c = p[2], d = p[3];
;     const float s = ((a[0] + a[1]) + (a[2] + a[3])) + ((b[0] + b[1]) + (b[2] + b[3])) + ((c[0] + c[1]) + (c[2] + c[3])) + ((d[0] + d[1]) + (d[2] + d[3]));
;     return rsqrtf(s * (1.0f / 1024.0f) + 1e-6f);
;     __device__ __forceinline__ void operator()(const f32x4 (&acc)[2][2][4][2], const Unit& u, int wr, int wc, int fr, int fq) const {
;     ...
;                 const int row = row0 + ai * 128 + m * 16; const float rs = row_rstd(ssq, row);
; #pragma unroll
;                 for (int bj = 0; bj < 2; ++bj) { f32x4 v0 = acc[ai][bj][m][0] * rs, v1 = acc[ai][bj][m][1] * rs;
; #pragma unroll
;                     for (int j = 0; j < 4; ++j) { const float a = fmaxf(v0[j], 0.f), b = fmaxf(v1[j], 0.f); v0[j] = a * a; v1[j] = b * b; }
;                     __builtin_amdgcn_raw_buffer_store_b128(pack8(v0, v1), rsrc, (unsigned)(((size_t)row * DFF + col0 + bj * 128) * 2), 0, 16  ); }
;             }
;         asm volatile("s_waitcnt vmcnt(0)" ::: "memory");
;         if (fr == 0 && fq == 0) (void)__hip_atomic_fetch_add(ready + 64 * (pm_off + u.pm), 1u, __ATOMIC_RELAXED, __HIP_MEMORY_SCOPE_AGENT);
	v_mov_b32_e32 v16, v240
	v_mov_b32_e32 v17, v241
	v_mov_b32_e32 v18, v242
	v_mov_b32_e32 v19, v243
	v_mov_b32_e32 v20, v244
	v_mov_b32_e32 v21, v245
	v_mov_b32_e32 v22, v246
	v_mov_b32_e32 v23, v247
	v_mov_b32_e32 v24, v248
	v_mov_b32_e32 v25, v249
	v_mov_b32_e32 v26, v250
	v_mov_b32_e32 v27, v251
	v_mov_b32_e32 v28, v252
	v_mov_b32_e32 v29, v253
	v_mov_b32_e32 v30, v254
	v_mov_b32_e32 v31, v255
	v_mov_b32_e32 v32, v17
	v_mov_b32_e32 v33, v18
	v_mov_b32_e32 v17, v19
	v_mov_b32_e32 v18, v21
	v_mov_b32_e32 v19, v22
	v_mov_b32_e32 v21, v23
	v_pk_add_f32 v[16:17], v[32:33], v[16:17]
	v_pk_add_f32 v[18:19], v[18:19], v[20:21]
	v_pk_add_f32 v[16:17], v[16:17], v[16:17] op_sel:[0,1] op_sel_hi:[1,0]
	v_pk_add_f32 v[18:19], v[18:19], v[18:19] op_sel:[0,1] op_sel_hi:[1,0]
	v_add_f32_e32 v22, v24, v25
	v_add_f32_e32 v24, v26, v27
	v_mov_b32_e32 v23, v30
	v_mov_b32_e32 v25, v31
	v_mov_b32_e32 v17, v28
	v_mov_b32_e32 v19, v29
	v_pk_add_f32 v[20:21], v[22:23], v[24:25]
	v_pk_add_f32 v[16:17], v[16:17], v[18:19]
	s_nop 0
	v_pk_add_f32 v[16:17], v[16:17], v[20:21]
	s_nop 0
	v_add_f32_e32 v16, v16, v17
	v_fmamk_f32 v16, v16, 0x3a800000, v148
	v_mul_f32_e32 v17, 0x4b800000, v16
	v_cmp_gt_f32_e32 vcc, s63, v16
	s_nop 1
	v_cndmask_b32_e32 v16, v16, v17, vcc
	v_rsq_f32_e32 v16, v16
	v_lshl_add_u32 v17, v48, 13, v149
	v_mul_f32_e32 v18, 0x45800000, v16
	v_cndmask_b32_e32 v16, v16, v18, vcc
	v_pk_mul_f32 v[14:15], v[14:15], v[16:17] op_sel_hi:[1,0]
	v_pk_mul_f32 v[12:13], v[12:13], v[16:17] op_sel_hi:[1,0]
	v_pk_mul_f32 v[10:11], v[10:11], v[16:17] op_sel_hi:[1,0]
	v_pk_mul_f32 v[8:9], v[8:9], v[16:17] op_sel_hi:[1,0]
	v_pk_mul_f32 v[2:3], v[2:3], v[16:17] op_sel_hi:[1,0]
	v_pk_mul_f32 v[0:1], v[0:1], v[16:17] op_sel_hi:[1,0]
	v_pk_mul_f32 v[6:7], v[6:7], v[16:17] op_sel_hi:[1,0]
	v_pk_mul_f32 v[4:5], v[4:5], v[16:17] op_sel_hi:[1,0]
	v_max_f32_e32 v12, 0, v12
	v_max_f32_e32 v8, 0, v8
	v_max_f32_e32 v13, 0, v13
	v_max_f32_e32 v9, 0, v9
	v_max_f32_e32 v14, 0, v14
	v_max_f32_e32 v10, 0, v10
	v_max_f32_e32 v15, 0, v15
	v_max_f32_e32 v11, 0, v11
	v_max_f32_e32 v0, 0, v0
	v_max_f32_e32 v1, 0, v1
	v_max_f32_e32 v2, 0, v2
	v_max_f32_e32 v3, 0, v3
	v_max_f32_e32 v4, 0, v4
	v_max_f32_e32 v5, 0, v5
	v_max_f32_e32 v6, 0, v6
	v_max_f32_e32 v7, 0, v7
	v_mul_f32_e32 v12, v12, v12
	v_mul_f32_e32 v8, v8, v8
	v_mul_f32_e32 v13, v13, v13
	v_mul_f32_e32 v9, v9, v9
	v_mul_f32_e32 v14, v14, v14
	v_mul_f32_e32 v10, v10, v10
	v_mul_f32_e32 v15, v15, v15
	v_mul_f32_e32 v11, v11, v11
	v_mul_f32_e32 v16, v0, v0
	v_mul_f32_e32 v18, v1, v1
	v_mul_f32_e32 v19, v2, v2
	v_mul_f32_e32 v20, v3, v3
	v_cvt_pk_bf16_f32 v0, v12, v13
	v_cvt_pk_bf16_f32 v1, v14, v15
	v_cvt_pk_bf16_f32 v2, v8, v9
	v_cvt_pk_bf16_f32 v3, v10, v11
	v_mul_f32_e32 v4, v4, v4
	v_mul_f32_e32 v5, v5, v5
	v_mul_f32_e32 v6, v6, v6
	v_mul_f32_e32 v7, v7, v7
	buffer_store_dwordx4 v[0:3], v17, s[8:11], 0 offen sc1
	s_nop 1
	v_cvt_pk_bf16_f32 v0, v4, v5
	v_cvt_pk_bf16_f32 v1, v6, v7
	v_cvt_pk_bf16_f32 v2, v16, v18
	v_cvt_pk_bf16_f32 v3, v19, v20
	buffer_store_dwordx4 v[0:3], v17, s[8:11], 0 offen offset:256 sc1
	s_waitcnt vmcnt(0)
	s_and_saveexec_b64 s[34:35], s[6:7]
	s_cbranch_execz .LBB0_2114
	s_mov_b64 s[36:37], exec
	v_mbcnt_lo_u32_b32 v0, s36, 0
	v_mbcnt_hi_u32_b32 v0, s37, v0
	v_cmp_eq_u32_e32 vcc, 0, v0
	s_and_b64 s[38:39], exec, vcc
	s_mov_b64 exec, s[38:39]
	s_cbranch_execz .LBB0_2114
	s_lshl_b32 s21, s68, 6
	s_add_i32 s38, s21, 0x1000
	s_ashr_i32 s39, s38, 31
	s_lshl_b64 s[38:39], s[38:39], 2
	s_add_u32 s38, s66, s38
	s_addc_u32 s39, s67, s39
	s_bcnt1_i32_b64 s21, s[36:37]
	v_mov_b32_e32 v0, s21
	global_atomic_add v131, v0, s[38:39]
	s_branch .LBB0_2114
